# row scales stored as (u, v) pairs per expert by the quantise code; the U sweep gathers both with one dwordx2 per group
# speedup vs baseline: 1.0107x; 1.0107x over previous
; __device__ __forceinline__ void quantise_tables(const Args& A, int gw, int NGW, int row_lo, int row_hi) {
;     ...
;         for (int q = 0; q < 4; ++q) { const int r = row + q * NGW; rr[q] = r; const int rc = r < row_hi ? r : row;
;             const float* s = (rc < 16384 ? A.pu + (size_t)rc * 1024 : A.pv + (size_t)(rc - 16384) * 1024) + 16 * lane;
; #pragma unroll
;             for (int j = 0; j < 4; ++j) v[q][j] = *(const f32x4*)(s + 4 * j); }
; #pragma unroll
;         for (int q = 0; q < 4; ++q) {
;             float mx = 0.f;
; #pragma unroll
;             for (int j = 0; j < 4; ++j)
; #pragma unroll
;                 for (int e = 0; e < 4; ++e) mx = fmaxf(mx, fabsf(v[q][j][e]));
;             mx = xrow_max(mx);
;             mx = fmaxf(mx, __int_as_float(__builtin_amdgcn_mov_dpp(__float_as_int(mx), 0xB1, 0xF, 0xF, true)));
;             mx = fmaxf(mx, __int_as_float(__builtin_amdgcn_mov_dpp(__float_as_int(mx), 0x4E, 0xF, 0xF, true)));
;             mx = fmaxf(mx, __int_as_float(__builtin_amdgcn_mov_dpp(__float_as_int(mx), 0x141, 0xF, 0xF, true)));
;             mx = fmaxf(mx, __int_as_float(__builtin_amdgcn_mov_dpp(__float_as_int(mx), 0x140, 0xF, 0xF, true)));
;             const float sc = fmaxf(mx, 1e-30f) * (1.f / 256.f), inv = 1.f / sc;
;             u32x4 o4;
; #pragma unroll
;             for (int j = 0; j < 4; ++j) { int w0 = __builtin_amdgcn_cvt_pk_fp8_f32(v[q][j][0] * inv, v[q][j][1] * inv, 0, false); w0 = __builtin_amdgcn_cvt_pk_fp8_f32(v[q][j][2] * inv, v[q][j][3] * inv, w0, true); o4[j] = (unsigned)w0; }
;             if (rr[q] < row_hi) { *(u32x4*)(T8 + (size_t)rr[q] * 1024 + 16 * lane) = o4; if (lane == 0) SC[rr[q]] = sc; }
.LBB0_180:
	v_add_u32_e32 v60, s21, v62
	v_ashrrev_i32_e32 v61, 31, v60
	v_lshlrev_b64 v[0:1], 12, v[60:61]
	v_lshl_add_u64 v[0:1], v[52:53], 0, v[0:1]
	global_load_dwordx4 v[68:71], v[0:1], off
	global_load_dwordx4 v[72:75], v[0:1], off offset:16
	global_load_dwordx4 v[76:79], v[0:1], off offset:32
	global_load_dwordx4 v[80:83], v[0:1], off offset:48
	v_add_u32_e32 v58, v63, v62
	v_add_u32_e32 v56, s23, v62
	v_cmp_gt_i32_e64 s[8:9], s20, v58
	v_add_u32_e32 v54, s24, v62
	v_cmp_gt_i32_e64 s[6:7], s20, v56
	v_cndmask_b32_e64 v0, v60, v58, s[8:9]
	v_cmp_gt_i32_e64 s[4:5], s20, v54
	v_cndmask_b32_e64 v4, v60, v56, s[6:7]
	v_ashrrev_i32_e32 v1, 31, v0
	v_add_u32_e32 v2, 0xffffc000, v0
	v_cmp_gt_i32_e32 vcc, s20, v0
	v_cndmask_b32_e64 v8, v60, v54, s[4:5]
	v_ashrrev_i32_e32 v5, 31, v4
	v_add_u32_e32 v6, 0xffffc000, v4
	v_cndmask_b32_e32 v1, 0, v1, vcc
	v_cndmask_b32_e32 v0, v2, v0, vcc
	v_cndmask_b32_e32 v3, v64, v65, vcc
	v_cndmask_b32_e32 v2, v66, v67, vcc
	v_cmp_gt_i32_e32 vcc, s20, v4
	v_ashrrev_i32_e32 v9, 31, v8
	v_add_u32_e32 v10, 0xffffc000, v8
	v_cndmask_b32_e32 v5, 0, v5, vcc
	v_cndmask_b32_e32 v4, v6, v4, vcc
	v_cndmask_b32_e32 v7, v64, v65, vcc
	v_cndmask_b32_e32 v6, v66, v67, vcc
	v_cmp_gt_i32_e32 vcc, s20, v8
	v_lshlrev_b64 v[0:1], 12, v[0:1]
	v_lshlrev_b64 v[4:5], 12, v[4:5]
	v_cndmask_b32_e32 v9, 0, v9, vcc
	v_cndmask_b32_e32 v8, v10, v8, vcc
	v_cndmask_b32_e32 v11, v64, v65, vcc
	v_cndmask_b32_e32 v10, v66, v67, vcc
	v_lshlrev_b64 v[8:9], 12, v[8:9]
	v_lshl_add_u64 v[0:1], v[2:3], 0, v[0:1]
	v_lshl_add_u64 v[2:3], v[6:7], 0, v[4:5]
	v_lshl_add_u64 v[4:5], v[10:11], 0, v[8:9]
	v_lshl_add_u64 v[0:1], v[0:1], 0, v[48:49]
	v_lshl_add_u64 v[2:3], v[2:3], 0, v[48:49]
	v_lshl_add_u64 v[12:13], v[4:5], 0, v[48:49]
	global_load_dwordx4 v[32:35], v[0:1], off offset:48
	global_load_dwordx4 v[36:39], v[0:1], off offset:32
	global_load_dwordx4 v[40:43], v[0:1], off offset:16
	global_load_dwordx4 v[44:47], v[0:1], off
	global_load_dwordx4 v[16:19], v[2:3], off offset:48
	global_load_dwordx4 v[20:23], v[2:3], off offset:32
	global_load_dwordx4 v[24:27], v[2:3], off offset:16
	global_load_dwordx4 v[28:31], v[2:3], off
	s_nop 0
	global_load_dwordx4 v[0:3], v[12:13], off offset:48
	global_load_dwordx4 v[4:7], v[12:13], off offset:32
	global_load_dwordx4 v[8:11], v[12:13], off offset:16
	s_nop 0
	global_load_dwordx4 v[12:15], v[12:13], off
	v_mov_b32_e32 v84, 0
	v_mov_b32_e32 v85, 0
	v_mov_b32_e32 v86, 0
	v_mov_b32_e32 v87, 0
	s_waitcnt vmcnt(15)
	v_max3_f32 v55, |v68|, 0, |v69|
	v_max3_f32 v55, v55, |v70|, |v71|
	s_waitcnt vmcnt(14)
	v_max3_f32 v55, v55, |v72|, |v73|
	v_max3_f32 v55, v55, |v74|, |v75|
	s_waitcnt vmcnt(13)
	v_max3_f32 v55, v55, |v76|, |v77|
	v_max3_f32 v55, v55, |v78|, |v79|
	s_waitcnt vmcnt(12)
	v_max3_f32 v55, v55, |v80|, |v81|
	v_max3_f32 v55, v55, |v82|, |v83|
	v_mov_b32_e32 v57, v55
	s_nop 1
	v_permlane16_swap_b32_e32 v55, v57
	v_max_f32_e32 v57, v57, v57
	v_max_f32_e32 v55, v55, v55
	v_max_f32_e32 v55, v55, v57
	v_mov_b32_e32 v57, v55
	s_nop 1
	v_permlane32_swap_b32_e32 v55, v57
	v_max_f32_e32 v57, v57, v57
	v_max_f32_e32 v55, v55, v55
	v_max_f32_e32 v55, v55, v57
	s_nop 1
	v_mov_b32_dpp v57, v55 quad_perm:[1,0,3,2] row_mask:0xf bank_mask:0xf bound_ctrl:1
	v_max_f32_e32 v57, v57, v57
	v_max_f32_e32 v55, v55, v57
	s_nop 1
	v_mov_b32_dpp v57, v55 quad_perm:[2,3,0,1] row_mask:0xf bank_mask:0xf bound_ctrl:1
	v_max_f32_e32 v57, v57, v57
	v_max_f32_e32 v55, v55, v57
	s_nop 1
	v_mov_b32_dpp v57, v55 row_half_mirror row_mask:0xf bank_mask:0xf bound_ctrl:1
	v_max_f32_e32 v57, v57, v57
	v_max_f32_e32 v55, v55, v57
	s_nop 1
	v_mov_b32_dpp v57, v55 row_mirror row_mask:0xf bank_mask:0xf bound_ctrl:1
	v_max3_f32 v55, v55, v57, s25
	v_mul_f32_e32 v55, 0x3b800000, v55
	v_div_scale_f32 v57, s[16:17], v55, v55, 1.0
	v_rcp_f32_e32 v59, v57
	v_div_scale_f32 v88, vcc, 1.0, v55, 1.0
	v_fma_f32 v89, -v57, v59, 1.0
	v_fmac_f32_e32 v59, v89, v59
	v_mul_f32_e32 v89, v88, v59
	v_fma_f32 v90, -v57, v89, v88
	v_fmac_f32_e32 v89, v90, v59
	v_fma_f32 v57, -v57, v89, v88
	v_div_fmas_f32 v57, v57, v59, v89
	v_div_fixup_f32 v57, v57, v55, 1.0
	v_mul_f32_e32 v68, v68, v57
	v_mul_f32_e32 v69, v69, v57
	v_mul_f32_e32 v72, v72, v57
	v_mul_f32_e32 v73, v73, v57
	v_mul_f32_e32 v76, v76, v57
	v_mul_f32_e32 v77, v77, v57
	v_mul_f32_e32 v80, v80, v57
	v_mul_f32_e32 v81, v81, v57
	v_cvt_pk_fp8_f32 v84, v68, v69
	v_cvt_pk_fp8_f32 v85, v72, v73
	v_cvt_pk_fp8_f32 v86, v76, v77
	v_cvt_pk_fp8_f32 v87, v80, v81
	v_mul_f32_e32 v59, v70, v57
	v_mul_f32_e32 v70, v71, v57
	v_mul_f32_e32 v71, v74, v57
	v_mul_f32_e32 v74, v75, v57
	v_mul_f32_e32 v75, v78, v57
	v_mul_f32_e32 v78, v79, v57
	v_mul_f32_e32 v79, v82, v57
	v_mul_f32_e32 v57, v83, v57
	v_cvt_pk_fp8_f32 v84, v59, v70 op_sel:[0,0,1]
	v_cvt_pk_fp8_f32 v85, v71, v74 op_sel:[0,0,1]
	v_cvt_pk_fp8_f32 v86, v75, v78 op_sel:[0,0,1]
	v_cvt_pk_fp8_f32 v87, v79, v57 op_sel:[0,0,1]
	v_lshlrev_b64 v[68:69], 10, v[60:61]
	v_lshl_add_u64 v[68:69], v[50:51], 0, v[68:69]
	global_store_dwordx4 v[68:69], v[84:87], off
	s_and_saveexec_b64 s[16:17], s[0:1]
	s_cbranch_execz .LBB0_182
	v_lshl_add_u64 v[60:61], v[60:61], 3, s[12:13]
	global_store_dword v[60:61], v55, off
; __device__ __forceinline__ void quantise_tables(const Args& A, int gw, int NGW, int row_lo, int row_hi) {
;     ...
;         for (int q = 0; q < 4; ++q) {
;             float mx = 0.f;
; #pragma unroll
;             for (int j = 0; j < 4; ++j)
; #pragma unroll
;                 for (int e = 0; e < 4; ++e) mx = fmaxf(mx, fabsf(v[q][j][e]));
;             mx = xrow_max(mx);
;             mx = fmaxf(mx, __int_as_float(__builtin_amdgcn_mov_dpp(__float_as_int(mx), 0xB1, 0xF, 0xF, true)));
;             mx = fmaxf(mx, __int_as_float(__builtin_amdgcn_mov_dpp(__float_as_int(mx), 0x4E, 0xF, 0xF, true)));
;             mx = fmaxf(mx, __int_as_float(__builtin_amdgcn_mov_dpp(__float_as_int(mx), 0x141, 0xF, 0xF, true)));
;             mx = fmaxf(mx, __int_as_float(__builtin_amdgcn_mov_dpp(__float_as_int(mx), 0x140, 0xF, 0xF, true)));
;             const float sc = fmaxf(mx, 1e-30f) * (1.f / 256.f), inv = 1.f / sc;
;             u32x4 o4;
; #pragma unroll
;             for (int j = 0; j < 4; ++j) { int w0 = __builtin_amdgcn_cvt_pk_fp8_f32(v[q][j][0] * inv, v[q][j][1] * inv, 0, false); w0 = __builtin_amdgcn_cvt_pk_fp8_f32(v[q][j][2] * inv, v[q][j][3] * inv, w0, true); o4[j] = (unsigned)w0; }
;             if (rr[q] < row_hi) { *(u32x4*)(T8 + (size_t)rr[q] * 1024 + 16 * lane) = o4; if (lane == 0) SC[rr[q]] = sc; }
.LBB0_182:
	s_or_b64 exec, exec, s[16:17]
	s_waitcnt vmcnt(9)
	v_max3_f32 v55, |v44|, 0, |v45|
	v_max3_f32 v55, v55, |v46|, |v47|
	v_max3_f32 v55, v55, |v40|, |v41|
	v_max3_f32 v55, v55, |v42|, |v43|
	v_max3_f32 v55, v55, |v36|, |v37|
	v_max3_f32 v55, v55, |v38|, |v39|
	v_max3_f32 v55, v55, |v32|, |v33|
	v_max3_f32 v55, v55, |v34|, |v35|
	v_mov_b32_e32 v57, v55
	s_nop 1
	v_permlane16_swap_b32_e32 v55, v57
	v_max_f32_e32 v57, v57, v57
	v_max_f32_e32 v55, v55, v55
	v_max_f32_e32 v55, v55, v57
	v_mov_b32_e32 v57, v55
	s_nop 1
	v_permlane32_swap_b32_e32 v55, v57
	v_max_f32_e32 v57, v57, v57
	v_max_f32_e32 v55, v55, v55
	v_max_f32_e32 v55, v55, v57
	s_nop 1
	v_mov_b32_dpp v57, v55 quad_perm:[1,0,3,2] row_mask:0xf bank_mask:0xf bound_ctrl:1
	v_max_f32_e32 v57, v57, v57
	v_max_f32_e32 v55, v55, v57
	s_nop 1
	v_mov_b32_dpp v57, v55 quad_perm:[2,3,0,1] row_mask:0xf bank_mask:0xf bound_ctrl:1
	v_max_f32_e32 v57, v57, v57
	v_max_f32_e32 v55, v55, v57
	s_nop 1
	v_mov_b32_dpp v57, v55 row_half_mirror row_mask:0xf bank_mask:0xf bound_ctrl:1
	v_max_f32_e32 v57, v57, v57
	v_max_f32_e32 v55, v55, v57
	s_nop 1
	v_mov_b32_dpp v57, v55 row_mirror row_mask:0xf bank_mask:0xf bound_ctrl:1
	s_and_saveexec_b64 s[16:17], s[8:9]
	s_cbranch_execz .LBB0_185
	v_max3_f32 v55, v55, v57, s25
	v_mul_f32_e32 v55, 0x3b800000, v55
	v_div_scale_f32 v57, s[8:9], v55, v55, 1.0
	v_rcp_f32_e32 v59, v57
	v_div_scale_f32 v60, vcc, 1.0, v55, 1.0
	v_fma_f32 v61, -v57, v59, 1.0
	v_fmac_f32_e32 v59, v61, v59
	v_mul_f32_e32 v61, v60, v59
	v_fma_f32 v68, -v57, v61, v60
	v_fmac_f32_e32 v61, v68, v59
	v_fma_f32 v57, -v57, v61, v60
	v_div_fmas_f32 v57, v57, v59, v61
	v_div_fixup_f32 v57, v57, v55, 1.0
	v_mul_f32_e32 v59, v44, v57
	v_mul_f32_e32 v45, v45, v57
	v_mov_b32_e32 v44, 0
	v_cvt_pk_fp8_f32 v44, v59, v45
	v_mul_f32_e32 v46, v46, v57
	v_mul_f32_e32 v47, v47, v57
	v_mul_f32_e32 v40, v40, v57
	v_mul_f32_e32 v41, v41, v57
	v_mov_b32_e32 v45, 0
	v_cvt_pk_fp8_f32 v44, v46, v47 op_sel:[0,0,1]
	v_mul_f32_e32 v36, v36, v57
	v_mul_f32_e32 v37, v37, v57
	v_mov_b32_e32 v46, 0
	v_mul_f32_e32 v32, v32, v57
	v_mul_f32_e32 v33, v33, v57
	v_mov_b32_e32 v47, 0
	v_cvt_pk_fp8_f32 v45, v40, v41
	v_cvt_pk_fp8_f32 v46, v36, v37
	v_cvt_pk_fp8_f32 v47, v32, v33
	v_mul_f32_e32 v40, v42, v57
	v_mul_f32_e32 v41, v43, v57
	v_mul_f32_e32 v38, v38, v57
	v_mul_f32_e32 v39, v39, v57
	v_mul_f32_e32 v32, v34, v57
	v_mul_f32_e32 v33, v35, v57
	v_cvt_pk_fp8_f32 v45, v40, v41 op_sel:[0,0,1]
	v_cvt_pk_fp8_f32 v46, v38, v39 op_sel:[0,0,1]
	v_cvt_pk_fp8_f32 v47, v32, v33 op_sel:[0,0,1]
	v_ashrrev_i32_e32 v59, 31, v58
	v_lshlrev_b64 v[32:33], 10, v[58:59]
	v_lshl_add_u64 v[32:33], v[50:51], 0, v[32:33]
	global_store_dwordx4 v[32:33], v[44:47], off
	s_and_b64 exec, exec, s[0:1]
	s_cbranch_execz .LBB0_185
	v_lshl_add_u64 v[32:33], v[58:59], 3, s[12:13]
	global_store_dword v[32:33], v55, off
; __device__ __forceinline__ void quantise_tables(const Args& A, int gw, int NGW, int row_lo, int row_hi) {
;     ...
;         for (int q = 0; q < 4; ++q) {
;             float mx = 0.f;
; #pragma unroll
;             for (int j = 0; j < 4; ++j)
; #pragma unroll
;                 for (int e = 0; e < 4; ++e) mx = fmaxf(mx, fabsf(v[q][j][e]));
;             mx = xrow_max(mx);
;             mx = fmaxf(mx, __int_as_float(__builtin_amdgcn_mov_dpp(__float_as_int(mx), 0xB1, 0xF, 0xF, true)));
;             mx = fmaxf(mx, __int_as_float(__builtin_amdgcn_mov_dpp(__float_as_int(mx), 0x4E, 0xF, 0xF, true)));
;             mx = fmaxf(mx, __int_as_float(__builtin_amdgcn_mov_dpp(__float_as_int(mx), 0x141, 0xF, 0xF, true)));
;             mx = fmaxf(mx, __int_as_float(__builtin_amdgcn_mov_dpp(__float_as_int(mx), 0x140, 0xF, 0xF, true)));
;             const float sc = fmaxf(mx, 1e-30f) * (1.f / 256.f), inv = 1.f / sc;
;             u32x4 o4;
; #pragma unroll
;             for (int j = 0; j < 4; ++j) { int w0 = __builtin_amdgcn_cvt_pk_fp8_f32(v[q][j][0] * inv, v[q][j][1] * inv, 0, false); w0 = __builtin_amdgcn_cvt_pk_fp8_f32(v[q][j][2] * inv, v[q][j][3] * inv, w0, true); o4[j] = (unsigned)w0; }
;             if (rr[q] < row_hi) { *(u32x4*)(T8 + (size_t)rr[q] * 1024 + 16 * lane) = o4; if (lane == 0) SC[rr[q]] = sc; }
.LBB0_185:
	s_or_b64 exec, exec, s[16:17]
	s_waitcnt vmcnt(5)
	v_max3_f32 v32, |v28|, 0, |v29|
	v_max3_f32 v32, v32, |v30|, |v31|
	v_max3_f32 v32, v32, |v24|, |v25|
	v_max3_f32 v32, v32, |v26|, |v27|
	v_max3_f32 v32, v32, |v20|, |v21|
	v_max3_f32 v32, v32, |v22|, |v23|
	v_max3_f32 v32, v32, |v16|, |v17|
	v_max3_f32 v32, v32, |v18|, |v19|
	v_mov_b32_e32 v33, v32
	s_nop 1
	v_permlane16_swap_b32_e32 v32, v33
	v_max_f32_e32 v33, v33, v33
	v_max_f32_e32 v32, v32, v32
	v_max_f32_e32 v32, v32, v33
	v_mov_b32_e32 v33, v32
	s_nop 1
	v_permlane32_swap_b32_e32 v32, v33
	v_max_f32_e32 v33, v33, v33
	v_max_f32_e32 v32, v32, v32
	v_max_f32_e32 v32, v32, v33
	s_nop 1
	v_mov_b32_dpp v33, v32 quad_perm:[1,0,3,2] row_mask:0xf bank_mask:0xf bound_ctrl:1
	v_max_f32_e32 v33, v33, v33
	v_max_f32_e32 v32, v32, v33
	s_nop 1
	v_mov_b32_dpp v33, v32 quad_perm:[2,3,0,1] row_mask:0xf bank_mask:0xf bound_ctrl:1
	v_max_f32_e32 v33, v33, v33
	v_max_f32_e32 v32, v32, v33
	s_nop 1
	v_mov_b32_dpp v33, v32 row_half_mirror row_mask:0xf bank_mask:0xf bound_ctrl:1
	v_max_f32_e32 v33, v33, v33
	v_max_f32_e32 v32, v32, v33
	s_nop 1
	v_mov_b32_dpp v33, v32 row_mirror row_mask:0xf bank_mask:0xf bound_ctrl:1
	s_and_saveexec_b64 s[8:9], s[6:7]
	s_cbranch_execz .LBB0_188
	v_max3_f32 v32, v32, v33, s25
	v_mul_f32_e32 v32, 0x3b800000, v32
	v_div_scale_f32 v33, s[6:7], v32, v32, 1.0
	v_rcp_f32_e32 v34, v33
	v_div_scale_f32 v35, vcc, 1.0, v32, 1.0
	v_ashrrev_i32_e32 v57, 31, v56
	v_fma_f32 v36, -v33, v34, 1.0
	v_fmac_f32_e32 v34, v36, v34
	v_mul_f32_e32 v36, v35, v34
	v_fma_f32 v37, -v33, v36, v35
	v_fmac_f32_e32 v36, v37, v34
	v_fma_f32 v33, -v33, v36, v35
	v_div_fmas_f32 v33, v33, v34, v36
	v_div_fixup_f32 v33, v33, v32, 1.0
	v_mul_f32_e32 v34, v28, v33
	v_mul_f32_e32 v29, v29, v33
	v_mov_b32_e32 v28, 0
	v_cvt_pk_fp8_f32 v28, v34, v29
	v_mul_f32_e32 v30, v30, v33
	v_mul_f32_e32 v31, v31, v33
	v_mul_f32_e32 v24, v24, v33
	v_mul_f32_e32 v25, v25, v33
	v_mov_b32_e32 v29, 0
	v_cvt_pk_fp8_f32 v28, v30, v31 op_sel:[0,0,1]
	v_mul_f32_e32 v20, v20, v33
	v_mul_f32_e32 v21, v21, v33
	v_mov_b32_e32 v30, 0
	v_mul_f32_e32 v16, v16, v33
	v_mul_f32_e32 v17, v17, v33
	v_mov_b32_e32 v31, 0
	v_cvt_pk_fp8_f32 v29, v24, v25
	v_cvt_pk_fp8_f32 v30, v20, v21
	v_cvt_pk_fp8_f32 v31, v16, v17
	v_mul_f32_e32 v24, v26, v33
	v_mul_f32_e32 v25, v27, v33
	v_mul_f32_e32 v22, v22, v33
	v_mul_f32_e32 v23, v23, v33
	v_mul_f32_e32 v16, v18, v33
	v_mul_f32_e32 v17, v19, v33
	v_cvt_pk_fp8_f32 v29, v24, v25 op_sel:[0,0,1]
	v_cvt_pk_fp8_f32 v30, v22, v23 op_sel:[0,0,1]
	v_cvt_pk_fp8_f32 v31, v16, v17 op_sel:[0,0,1]
	v_lshlrev_b64 v[16:17], 10, v[56:57]
	v_lshl_add_u64 v[16:17], v[50:51], 0, v[16:17]
	global_store_dwordx4 v[16:17], v[28:31], off
	s_and_b64 exec, exec, s[0:1]
	s_cbranch_execz .LBB0_188
	v_lshl_add_u64 v[16:17], v[56:57], 3, s[12:13]
	global_store_dword v[16:17], v32, off
.LBB0_188:
	s_or_b64 exec, exec, s[8:9]
	s_waitcnt vmcnt(1)
	v_max3_f32 v16, |v12|, 0, |v13|
	v_max3_f32 v16, v16, |v14|, |v15|
	v_max3_f32 v16, v16, |v8|, |v9|
	v_max3_f32 v16, v16, |v10|, |v11|
	v_max3_f32 v16, v16, |v4|, |v5|
	v_max3_f32 v16, v16, |v6|, |v7|
	v_max3_f32 v16, v16, |v0|, |v1|
	v_max3_f32 v16, v16, |v2|, |v3|
	v_mov_b32_e32 v17, v16
	s_nop 1
	v_permlane16_swap_b32_e32 v16, v17
	v_max_f32_e32 v17, v17, v17
	v_max_f32_e32 v16, v16, v16
	v_max_f32_e32 v16, v16, v17
	v_mov_b32_e32 v17, v16
	s_nop 1
	v_permlane32_swap_b32_e32 v16, v17
	v_max_f32_e32 v17, v17, v17
	v_max_f32_e32 v16, v16, v16
	v_max_f32_e32 v16, v16, v17
	s_nop 1
	v_mov_b32_dpp v17, v16 quad_perm:[1,0,3,2] row_mask:0xf bank_mask:0xf bound_ctrl:1
	v_max_f32_e32 v17, v17, v17
	v_max_f32_e32 v16, v16, v17
	s_nop 1
	v_mov_b32_dpp v17, v16 quad_perm:[2,3,0,1] row_mask:0xf bank_mask:0xf bound_ctrl:1
	v_max_f32_e32 v17, v17, v17
	v_max_f32_e32 v16, v16, v17
	s_nop 1
	v_mov_b32_dpp v17, v16 row_half_mirror row_mask:0xf bank_mask:0xf bound_ctrl:1
	v_max_f32_e32 v17, v17, v17
	v_max_f32_e32 v16, v16, v17
	s_nop 1
	v_mov_b32_dpp v17, v16 row_mirror row_mask:0xf bank_mask:0xf bound_ctrl:1
	s_and_saveexec_b64 s[6:7], s[4:5]
	s_cbranch_execz .LBB0_179
	v_max3_f32 v16, v16, v17, s25
	v_mul_f32_e32 v16, 0x3b800000, v16
	v_div_scale_f32 v17, s[4:5], v16, v16, 1.0
	v_rcp_f32_e32 v18, v17
	v_div_scale_f32 v19, vcc, 1.0, v16, 1.0
	v_ashrrev_i32_e32 v55, 31, v54
	v_fma_f32 v20, -v17, v18, 1.0
	v_fmac_f32_e32 v18, v20, v18
	v_mul_f32_e32 v20, v19, v18
	v_fma_f32 v21, -v17, v20, v19
	v_fmac_f32_e32 v20, v21, v18
	v_fma_f32 v17, -v17, v20, v19
	v_div_fmas_f32 v17, v17, v18, v20
	v_div_fixup_f32 v17, v17, v16, 1.0
	v_mul_f32_e32 v18, v12, v17
	v_mul_f32_e32 v13, v13, v17
	v_mov_b32_e32 v12, 0
	v_cvt_pk_fp8_f32 v12, v18, v13
	v_mul_f32_e32 v14, v14, v17
	v_mul_f32_e32 v15, v15, v17
	v_mul_f32_e32 v8, v8, v17
	v_mul_f32_e32 v9, v9, v17
	v_mov_b32_e32 v13, 0
	v_cvt_pk_fp8_f32 v12, v14, v15 op_sel:[0,0,1]
	v_mul_f32_e32 v4, v4, v17
	v_mul_f32_e32 v5, v5, v17
	v_mov_b32_e32 v14, 0
	v_mul_f32_e32 v0, v0, v17
	v_mul_f32_e32 v1, v1, v17
	v_mov_b32_e32 v15, 0
	v_cvt_pk_fp8_f32 v13, v8, v9
	v_cvt_pk_fp8_f32 v14, v4, v5
	v_cvt_pk_fp8_f32 v15, v0, v1
	v_mul_f32_e32 v8, v10, v17
	v_mul_f32_e32 v9, v11, v17
	v_mul_f32_e32 v6, v6, v17
	v_mul_f32_e32 v7, v7, v17
	v_mul_f32_e32 v0, v2, v17
	v_mul_f32_e32 v1, v3, v17
	v_cvt_pk_fp8_f32 v13, v8, v9 op_sel:[0,0,1]
	v_cvt_pk_fp8_f32 v14, v6, v7 op_sel:[0,0,1]
	v_cvt_pk_fp8_f32 v15, v0, v1 op_sel:[0,0,1]
	v_lshlrev_b64 v[0:1], 10, v[54:55]
	v_lshl_add_u64 v[0:1], v[50:51], 0, v[0:1]
	global_store_dwordx4 v[0:1], v[12:15], off
	s_and_b64 exec, exec, s[0:1]
	s_cbranch_execz .LBB0_179
	v_lshl_add_u64 v[0:1], v[54:55], 3, s[12:13]
	global_store_dword v[0:1], v16, off
	s_branch .LBB0_179

; __device__ __forceinline__ void quantise_tables(const Args& A, int gw, int NGW, int row_lo, int row_hi) {
;     int tid_o = threadIdx.x; asm volatile("" : "+v"(tid_o)); const int lane = tid_o & 63;
;     unsigned char* T8 = A.ws + WS_T8; float* SC = (float*)(A.ws + WS_SC);
; #pragma unroll 1
;     for (int row = row_lo + gw; row < row_hi; row += 4 * NGW) {
;         f32x4 v[4][4]; int rr[4];
; #pragma unroll
;         for (int q = 0; q < 4; ++q) { const int r = row + q * NGW; rr[q] = r; const int rc = r < row_hi ? r : row;
;             const float* s = (rc < 16384 ? A.pu + (size_t)rc * 1024 : A.pv + (size_t)(rc - 16384) * 1024) + 16 * lane;
; #pragma unroll
;             for (int j = 0; j < 4; ++j) v[q][j] = *(const f32x4*)(s + 4 * j); }
.LBB0_344:
	s_or_b64 exec, exec, s[0:1]
	s_add_u32 s20, s50, 0x2fe0004
	s_movk_i32 s16, 0x4000
	v_mov_b32_e32 v0, v214
	s_addc_u32 s21, s51, 0
	v_cmp_gt_i32_e32 vcc, s16, v48
	s_and_saveexec_b64 s[10:11], vcc
	s_cbranch_execz .LBB0_358
	v_and_b32_e32 v2, 63, v0
	v_lshlrev_b32_e32 v50, 4, v2
	v_mov_b32_e32 v51, 0
	v_lshl_add_u64 v[0:1], s[50:51], 0, v[50:51]
	s_mov_b64 s[0:1], 0x1000000
	v_add_u32_e32 v54, 0x4000, v48
	v_lshl_add_u64 v[52:53], v[0:1], 0, s[0:1]
	v_cmp_eq_u32_e64 s[0:1], 0, v2
	s_lshl_b32 s17, s84, 4
	s_mul_i32 s22, s84, 24
	s_mov_b64 s[12:13], 0
	v_mov_b32_e32 v49, s45
	v_mov_b32_e32 v58, s43
	v_mov_b32_e32 v59, s44
	v_mov_b32_e32 v60, s42
	v_lshlrev_b32_e32 v50, 2, v50
	s_mov_b32 s23, 0x8000
	s_mov_b32 s24, 0xda24260
	s_movk_i32 s25, 0x7fff
	s_branch .LBB0_347

; __device__ __forceinline__ void quantise_tables(const Args& A, int gw, int NGW, int row_lo, int row_hi) {
;     ...
;     for (int row = row_lo + gw; row < row_hi; row += 4 * NGW) {
;         f32x4 v[4][4]; int rr[4];
; #pragma unroll
;         for (int q = 0; q < 4; ++q) { const int r = row + q * NGW; rr[q] = r; const int rc = r < row_hi ? r : row;
;             const float* s = (rc < 16384 ? A.pu + (size_t)rc * 1024 : A.pv + (size_t)(rc - 16384) * 1024) + 16 * lane;
; #pragma unroll
;             for (int j = 0; j < 4; ++j) v[q][j] = *(const f32x4*)(s + 4 * j); }
; #pragma unroll
;         for (int q = 0; q < 4; ++q) {
;             float mx = 0.f;
; #pragma unroll
;             for (int j = 0; j < 4; ++j)
; #pragma unroll
;                 for (int e = 0; e < 4; ++e) mx = fmaxf(mx, fabsf(v[q][j][e]));
;             mx = xrow_max(mx);
;             mx = fmaxf(mx, __int_as_float(__builtin_amdgcn_mov_dpp(__float_as_int(mx), 0xB1, 0xF, 0xF, true)));
;             mx = fmaxf(mx, __int_as_float(__builtin_amdgcn_mov_dpp(__float_as_int(mx), 0x4E, 0xF, 0xF, true)));
;             mx = fmaxf(mx, __int_as_float(__builtin_amdgcn_mov_dpp(__float_as_int(mx), 0x141, 0xF, 0xF, true)));
;             mx = fmaxf(mx, __int_as_float(__builtin_amdgcn_mov_dpp(__float_as_int(mx), 0x140, 0xF, 0xF, true)));
;             const float sc = fmaxf(mx, 1e-30f) * (1.f / 256.f), inv = 1.f / sc;
;             u32x4 o4;
; #pragma unroll
;             for (int j = 0; j < 4; ++j) { int w0 = __builtin_amdgcn_cvt_pk_fp8_f32(v[q][j][0] * inv, v[q][j][1] * inv, 0, false); w0 = __builtin_amdgcn_cvt_pk_fp8_f32(v[q][j][2] * inv, v[q][j][3] * inv, w0, true); o4[j] = (unsigned)w0; }
;             if (rr[q] < row_hi) { *(u32x4*)(T8 + (size_t)rr[q] * 1024 + 16 * lane) = o4; if (lane == 0) SC[rr[q]] = sc; }
.LBB0_347:
	v_add_u32_e32 v0, 0xffffc000, v54
	v_ashrrev_i32_e32 v55, 31, v54
	v_cmp_gt_i32_e32 vcc, s16, v54
	v_add_u32_e32 v56, v148, v54
	v_cmp_gt_i32_e64 s[8:9], s23, v56
	v_cndmask_b32_e32 v1, 0, v55, vcc
	v_cndmask_b32_e32 v0, v0, v54, vcc
	v_cndmask_b32_e32 v3, v49, v58, vcc
	v_cndmask_b32_e32 v2, v59, v60, vcc
	v_lshlrev_b64 v[0:1], 12, v[0:1]
	v_lshl_add_u64 v[0:1], v[2:3], 0, v[0:1]
	v_lshl_add_u64 v[0:1], v[0:1], 0, v[50:51]
	global_load_dwordx4 v[62:65], v[0:1], off
	global_load_dwordx4 v[66:69], v[0:1], off offset:16
	global_load_dwordx4 v[70:73], v[0:1], off offset:32
	global_load_dwordx4 v[74:77], v[0:1], off offset:48
	v_add_u32_e32 v1, v148, v56
	v_cndmask_b32_e64 v0, v54, v56, s[8:9]
	v_cmp_gt_i32_e64 s[6:7], s23, v1
	v_add_u32_e32 v61, v148, v1
	v_ashrrev_i32_e32 v2, 31, v0
	v_add_u32_e32 v3, 0xffffc000, v0
	v_cndmask_b32_e64 v4, v54, v1, s[6:7]
	v_cmp_gt_i32_e32 vcc, s16, v0
	v_cmp_gt_i32_e64 s[4:5], s23, v61
	v_ashrrev_i32_e32 v5, 31, v4
	v_cndmask_b32_e32 v1, 0, v2, vcc
	v_cndmask_b32_e32 v0, v3, v0, vcc
	v_cndmask_b32_e32 v3, v49, v58, vcc
	v_cndmask_b32_e32 v2, v59, v60, vcc
	v_add_u32_e32 v6, 0xffffc000, v4
	v_cndmask_b32_e64 v8, v54, v61, s[4:5]
	v_cmp_gt_i32_e32 vcc, s16, v4
	v_lshlrev_b64 v[0:1], 12, v[0:1]
	v_ashrrev_i32_e32 v9, 31, v8
	v_cndmask_b32_e32 v5, 0, v5, vcc
	v_cndmask_b32_e32 v4, v6, v4, vcc
	v_cndmask_b32_e32 v7, v49, v58, vcc
	v_cndmask_b32_e32 v6, v59, v60, vcc
	v_add_u32_e32 v10, 0xffffc000, v8
	v_cmp_gt_i32_e32 vcc, s16, v8
	v_lshl_add_u64 v[0:1], v[2:3], 0, v[0:1]
	v_lshlrev_b64 v[2:3], 12, v[4:5]
	v_cndmask_b32_e32 v5, 0, v9, vcc
	v_cndmask_b32_e32 v4, v10, v8, vcc
	v_cndmask_b32_e32 v9, v49, v58, vcc
	v_cndmask_b32_e32 v8, v59, v60, vcc
	v_lshl_add_u64 v[0:1], v[0:1], 0, v[50:51]
	v_lshl_add_u64 v[2:3], v[6:7], 0, v[2:3]
	v_lshlrev_b64 v[4:5], 12, v[4:5]
	global_load_dwordx4 v[32:35], v[0:1], off offset:48
	global_load_dwordx4 v[36:39], v[0:1], off offset:32
	global_load_dwordx4 v[40:43], v[0:1], off offset:16
	global_load_dwordx4 v[44:47], v[0:1], off
	v_lshl_add_u64 v[0:1], v[2:3], 0, v[50:51]
	v_lshl_add_u64 v[2:3], v[8:9], 0, v[4:5]
	v_lshl_add_u64 v[12:13], v[2:3], 0, v[50:51]
	global_load_dwordx4 v[16:19], v[0:1], off offset:48
	global_load_dwordx4 v[20:23], v[0:1], off offset:32
	global_load_dwordx4 v[24:27], v[0:1], off offset:16
	global_load_dwordx4 v[28:31], v[0:1], off
	s_nop 0
	global_load_dwordx4 v[0:3], v[12:13], off offset:48
	global_load_dwordx4 v[4:7], v[12:13], off offset:32
	global_load_dwordx4 v[8:11], v[12:13], off offset:16
	s_nop 0
	global_load_dwordx4 v[12:15], v[12:13], off
	v_mov_b32_e32 v78, 0
	v_mov_b32_e32 v79, 0
	s_waitcnt vmcnt(15)
	v_max3_f32 v57, |v62|, 0, |v63|
	v_max3_f32 v57, v57, |v64|, |v65|
	s_waitcnt vmcnt(14)
	v_max3_f32 v57, v57, |v66|, |v67|
	v_max3_f32 v57, v57, |v68|, |v69|
	s_waitcnt vmcnt(13)
	v_max3_f32 v57, v57, |v70|, |v71|
	v_max3_f32 v57, v57, |v72|, |v73|
	s_waitcnt vmcnt(12)
	v_max3_f32 v57, v57, |v74|, |v75|
	v_max3_f32 v57, v57, |v76|, |v77|
	v_mov_b32_e32 v80, v57
	s_nop 1
	v_permlane16_swap_b32_e32 v57, v80
	v_max_f32_e32 v80, v80, v80
	v_max_f32_e32 v57, v57, v57
	v_max_f32_e32 v57, v57, v80
	v_mov_b32_e32 v80, v57
	s_nop 1
	v_permlane32_swap_b32_e32 v57, v80
	v_max_f32_e32 v80, v80, v80
	v_max_f32_e32 v57, v57, v57
	v_max_f32_e32 v57, v57, v80
	s_nop 1
	v_mov_b32_dpp v80, v57 quad_perm:[1,0,3,2] row_mask:0xf bank_mask:0xf bound_ctrl:1
	v_max_f32_e32 v80, v80, v80
	v_max_f32_e32 v57, v57, v80
	s_nop 1
	v_mov_b32_dpp v80, v57 quad_perm:[2,3,0,1] row_mask:0xf bank_mask:0xf bound_ctrl:1
	v_max_f32_e32 v80, v80, v80
	v_max_f32_e32 v57, v57, v80
	s_nop 1
	v_mov_b32_dpp v80, v57 row_half_mirror row_mask:0xf bank_mask:0xf bound_ctrl:1
	v_max_f32_e32 v80, v80, v80
	v_max_f32_e32 v57, v57, v80
	s_nop 1
	v_mov_b32_dpp v80, v57 row_mirror row_mask:0xf bank_mask:0xf bound_ctrl:1
	v_max3_f32 v57, v57, v80, s24
	v_mul_f32_e32 v57, 0x3b800000, v57
	v_div_scale_f32 v81, s[14:15], v57, v57, 1.0
	v_rcp_f32_e32 v82, v81
	v_div_scale_f32 v83, vcc, 1.0, v57, 1.0
	v_mov_b32_e32 v80, 0
	v_fma_f32 v84, -v81, v82, 1.0
	v_fmac_f32_e32 v82, v84, v82
	v_mul_f32_e32 v84, v83, v82
	v_fma_f32 v85, -v81, v84, v83
	v_fmac_f32_e32 v84, v85, v82
	v_fma_f32 v81, -v81, v84, v83
	v_div_fmas_f32 v81, v81, v82, v84
	v_div_fixup_f32 v82, v81, v57, 1.0
	v_mul_f32_e32 v62, v62, v82
	v_mul_f32_e32 v63, v63, v82
	v_mul_f32_e32 v66, v66, v82
	v_mul_f32_e32 v67, v67, v82
	v_mul_f32_e32 v70, v70, v82
	v_mul_f32_e32 v71, v71, v82
	v_cvt_pk_fp8_f32 v78, v62, v63
	v_mul_f32_e32 v62, v74, v82
	v_mul_f32_e32 v63, v75, v82
	v_mov_b32_e32 v81, 0
	v_cvt_pk_fp8_f32 v79, v66, v67
	v_cvt_pk_fp8_f32 v80, v70, v71
	v_cvt_pk_fp8_f32 v81, v62, v63
	v_mul_f32_e32 v64, v64, v82
	v_mul_f32_e32 v65, v65, v82
	v_mul_f32_e32 v68, v68, v82
	v_mul_f32_e32 v69, v69, v82
	v_mul_f32_e32 v72, v72, v82
	v_mul_f32_e32 v73, v73, v82
	v_mul_f32_e32 v62, v76, v82
	v_mul_f32_e32 v63, v77, v82
	v_cvt_pk_fp8_f32 v78, v64, v65 op_sel:[0,0,1]
	v_cvt_pk_fp8_f32 v79, v68, v69 op_sel:[0,0,1]
	v_cvt_pk_fp8_f32 v80, v72, v73 op_sel:[0,0,1]
	v_cvt_pk_fp8_f32 v81, v62, v63 op_sel:[0,0,1]
	v_lshlrev_b64 v[62:63], 10, v[54:55]
	v_lshl_add_u64 v[62:63], v[52:53], 0, v[62:63]
	global_store_dwordx4 v[62:63], v[78:81], off
	s_and_saveexec_b64 s[14:15], s[0:1]
	s_cbranch_execz .LBB0_349
	v_lshl_add_u64 v[62:63], v[54:55], 3, s[20:21]
	global_store_dword v[62:63], v57, off
; __device__ __forceinline__ void quantise_tables(const Args& A, int gw, int NGW, int row_lo, int row_hi) {
;     ...
;         for (int q = 0; q < 4; ++q) {
;             float mx = 0.f;
; #pragma unroll
;             for (int j = 0; j < 4; ++j)
; #pragma unroll
;                 for (int e = 0; e < 4; ++e) mx = fmaxf(mx, fabsf(v[q][j][e]));
;             mx = xrow_max(mx);
;             mx = fmaxf(mx, __int_as_float(__builtin_amdgcn_mov_dpp(__float_as_int(mx), 0xB1, 0xF, 0xF, true)));
;             mx = fmaxf(mx, __int_as_float(__builtin_amdgcn_mov_dpp(__float_as_int(mx), 0x4E, 0xF, 0xF, true)));
;             mx = fmaxf(mx, __int_as_float(__builtin_amdgcn_mov_dpp(__float_as_int(mx), 0x141, 0xF, 0xF, true)));
;             mx = fmaxf(mx, __int_as_float(__builtin_amdgcn_mov_dpp(__float_as_int(mx), 0x140, 0xF, 0xF, true)));
;             const float sc = fmaxf(mx, 1e-30f) * (1.f / 256.f), inv = 1.f / sc;
;             u32x4 o4;
; #pragma unroll
;             for (int j = 0; j < 4; ++j) { int w0 = __builtin_amdgcn_cvt_pk_fp8_f32(v[q][j][0] * inv, v[q][j][1] * inv, 0, false); w0 = __builtin_amdgcn_cvt_pk_fp8_f32(v[q][j][2] * inv, v[q][j][3] * inv, w0, true); o4[j] = (unsigned)w0; }
;             if (rr[q] < row_hi) { *(u32x4*)(T8 + (size_t)rr[q] * 1024 + 16 * lane) = o4; if (lane == 0) SC[rr[q]] = sc; }
.LBB0_349:
	s_or_b64 exec, exec, s[14:15]
	s_waitcnt vmcnt(9)
	v_max3_f32 v55, |v44|, 0, |v45|
	v_max3_f32 v55, v55, |v46|, |v47|
	v_max3_f32 v55, v55, |v40|, |v41|
	v_max3_f32 v55, v55, |v42|, |v43|
	v_max3_f32 v55, v55, |v36|, |v37|
	v_max3_f32 v55, v55, |v38|, |v39|
	v_max3_f32 v55, v55, |v32|, |v33|
	v_max3_f32 v55, v55, |v34|, |v35|
	v_mov_b32_e32 v57, v55
	s_nop 1
	v_permlane16_swap_b32_e32 v55, v57
	v_max_f32_e32 v57, v57, v57
	v_max_f32_e32 v55, v55, v55
	v_max_f32_e32 v55, v55, v57
	v_mov_b32_e32 v57, v55
	s_nop 1
	v_permlane32_swap_b32_e32 v55, v57
	v_max_f32_e32 v57, v57, v57
	v_max_f32_e32 v55, v55, v55
	v_max_f32_e32 v55, v55, v57
	s_nop 1
	v_mov_b32_dpp v57, v55 quad_perm:[1,0,3,2] row_mask:0xf bank_mask:0xf bound_ctrl:1
	v_max_f32_e32 v57, v57, v57
	v_max_f32_e32 v55, v55, v57
	s_nop 1
	v_mov_b32_dpp v57, v55 quad_perm:[2,3,0,1] row_mask:0xf bank_mask:0xf bound_ctrl:1
	v_max_f32_e32 v57, v57, v57
	v_max_f32_e32 v55, v55, v57
	s_nop 1
	v_mov_b32_dpp v57, v55 row_half_mirror row_mask:0xf bank_mask:0xf bound_ctrl:1
	v_max_f32_e32 v57, v57, v57
	v_max_f32_e32 v55, v55, v57
	s_nop 1
	v_mov_b32_dpp v57, v55 row_mirror row_mask:0xf bank_mask:0xf bound_ctrl:1
	s_and_saveexec_b64 s[14:15], s[8:9]
	s_cbranch_execz .LBB0_352
	v_max3_f32 v55, v55, v57, s24
	v_mul_f32_e32 v55, 0x3b800000, v55
	v_div_scale_f32 v57, s[8:9], v55, v55, 1.0
	v_rcp_f32_e32 v62, v57
	v_div_scale_f32 v63, vcc, 1.0, v55, 1.0
	v_fma_f32 v64, -v57, v62, 1.0
	v_fmac_f32_e32 v62, v64, v62
	v_mul_f32_e32 v64, v63, v62
	v_fma_f32 v65, -v57, v64, v63
	v_fmac_f32_e32 v64, v65, v62
	v_fma_f32 v57, -v57, v64, v63
	v_div_fmas_f32 v57, v57, v62, v64
	v_div_fixup_f32 v57, v57, v55, 1.0
	v_mul_f32_e32 v62, v44, v57
	v_mul_f32_e32 v45, v45, v57
	v_mov_b32_e32 v44, 0
	v_cvt_pk_fp8_f32 v44, v62, v45
	v_mul_f32_e32 v46, v46, v57
	v_mul_f32_e32 v47, v47, v57
	v_mul_f32_e32 v40, v40, v57
	v_mul_f32_e32 v41, v41, v57
	v_mov_b32_e32 v45, 0
	v_cvt_pk_fp8_f32 v44, v46, v47 op_sel:[0,0,1]
	v_mul_f32_e32 v36, v36, v57
	v_mul_f32_e32 v37, v37, v57
	v_mov_b32_e32 v46, 0
	v_mul_f32_e32 v32, v32, v57
	v_mul_f32_e32 v33, v33, v57
	v_mov_b32_e32 v47, 0
	v_cvt_pk_fp8_f32 v45, v40, v41
	v_cvt_pk_fp8_f32 v46, v36, v37
	v_cvt_pk_fp8_f32 v47, v32, v33
	v_mul_f32_e32 v40, v42, v57
	v_mul_f32_e32 v41, v43, v57
	v_mul_f32_e32 v38, v38, v57
	v_mul_f32_e32 v39, v39, v57
	v_mul_f32_e32 v32, v34, v57
	v_mul_f32_e32 v33, v35, v57
	v_cvt_pk_fp8_f32 v45, v40, v41 op_sel:[0,0,1]
	v_cvt_pk_fp8_f32 v46, v38, v39 op_sel:[0,0,1]
	v_cvt_pk_fp8_f32 v47, v32, v33 op_sel:[0,0,1]
	v_ashrrev_i32_e32 v57, 31, v56
	v_lshlrev_b64 v[32:33], 10, v[56:57]
	v_lshl_add_u64 v[32:33], v[52:53], 0, v[32:33]
	global_store_dwordx4 v[32:33], v[44:47], off
	s_and_b64 exec, exec, s[0:1]
	s_cbranch_execz .LBB0_352
	v_lshl_add_u64 v[32:33], v[56:57], 3, s[20:21]
	global_store_dword v[32:33], v55, off
; __device__ __forceinline__ void quantise_tables(const Args& A, int gw, int NGW, int row_lo, int row_hi) {
;     ...
;         for (int q = 0; q < 4; ++q) {
;             float mx = 0.f;
; #pragma unroll
;             for (int j = 0; j < 4; ++j)
; #pragma unroll
;                 for (int e = 0; e < 4; ++e) mx = fmaxf(mx, fabsf(v[q][j][e]));
;             mx = xrow_max(mx);
;             mx = fmaxf(mx, __int_as_float(__builtin_amdgcn_mov_dpp(__float_as_int(mx), 0xB1, 0xF, 0xF, true)));
;             mx = fmaxf(mx, __int_as_float(__builtin_amdgcn_mov_dpp(__float_as_int(mx), 0x4E, 0xF, 0xF, true)));
;             mx = fmaxf(mx, __int_as_float(__builtin_amdgcn_mov_dpp(__float_as_int(mx), 0x141, 0xF, 0xF, true)));
;             mx = fmaxf(mx, __int_as_float(__builtin_amdgcn_mov_dpp(__float_as_int(mx), 0x140, 0xF, 0xF, true)));
;             const float sc = fmaxf(mx, 1e-30f) * (1.f / 256.f), inv = 1.f / sc;
;             u32x4 o4;
; #pragma unroll
;             for (int j = 0; j < 4; ++j) { int w0 = __builtin_amdgcn_cvt_pk_fp8_f32(v[q][j][0] * inv, v[q][j][1] * inv, 0, false); w0 = __builtin_amdgcn_cvt_pk_fp8_f32(v[q][j][2] * inv, v[q][j][3] * inv, w0, true); o4[j] = (unsigned)w0; }
;             if (rr[q] < row_hi) { *(u32x4*)(T8 + (size_t)rr[q] * 1024 + 16 * lane) = o4; if (lane == 0) SC[rr[q]] = sc; }
.LBB0_352:
	s_or_b64 exec, exec, s[14:15]
	s_waitcnt vmcnt(5)
	v_max3_f32 v32, |v28|, 0, |v29|
	v_max3_f32 v32, v32, |v30|, |v31|
	v_max3_f32 v32, v32, |v24|, |v25|
	v_max3_f32 v32, v32, |v26|, |v27|
	v_max3_f32 v32, v32, |v20|, |v21|
	v_max3_f32 v32, v32, |v22|, |v23|
	v_max3_f32 v32, v32, |v16|, |v17|
	v_max3_f32 v32, v32, |v18|, |v19|
	v_mov_b32_e32 v33, v32
	s_nop 1
	v_permlane16_swap_b32_e32 v32, v33
	v_max_f32_e32 v33, v33, v33
	v_max_f32_e32 v32, v32, v32
	v_max_f32_e32 v32, v32, v33
	v_mov_b32_e32 v33, v32
	s_nop 1
	v_permlane32_swap_b32_e32 v32, v33
	v_max_f32_e32 v33, v33, v33
	v_max_f32_e32 v32, v32, v32
	v_max_f32_e32 v32, v32, v33
	s_nop 1
	v_mov_b32_dpp v33, v32 quad_perm:[1,0,3,2] row_mask:0xf bank_mask:0xf bound_ctrl:1
	v_max_f32_e32 v33, v33, v33
	v_max_f32_e32 v32, v32, v33
	s_nop 1
	v_mov_b32_dpp v33, v32 quad_perm:[2,3,0,1] row_mask:0xf bank_mask:0xf bound_ctrl:1
	v_max_f32_e32 v33, v33, v33
	v_max_f32_e32 v32, v32, v33
	s_nop 1
	v_mov_b32_dpp v33, v32 row_half_mirror row_mask:0xf bank_mask:0xf bound_ctrl:1
	v_max_f32_e32 v33, v33, v33
	v_max_f32_e32 v32, v32, v33
	s_nop 1
	v_mov_b32_dpp v33, v32 row_mirror row_mask:0xf bank_mask:0xf bound_ctrl:1
	s_and_saveexec_b64 s[8:9], s[6:7]
	s_cbranch_execz .LBB0_355
	v_max3_f32 v32, v32, v33, s24
	v_mul_f32_e32 v34, 0x3b800000, v32
	v_div_scale_f32 v33, s[6:7], v34, v34, 1.0
	v_rcp_f32_e32 v35, v33
	v_add_u32_e32 v32, s17, v54
	v_fma_f32 v36, -v33, v35, 1.0
	v_fmac_f32_e32 v35, v36, v35
	v_div_scale_f32 v36, vcc, 1.0, v34, 1.0
	v_mul_f32_e32 v37, v36, v35
	v_fma_f32 v38, -v33, v37, v36
	v_fmac_f32_e32 v37, v38, v35
	v_fma_f32 v33, -v33, v37, v36
	v_div_fmas_f32 v33, v33, v35, v37
	v_div_fixup_f32 v33, v33, v34, 1.0
	v_mul_f32_e32 v35, v28, v33
	v_mul_f32_e32 v29, v29, v33
	v_mov_b32_e32 v28, 0
	v_cvt_pk_fp8_f32 v28, v35, v29
	v_mul_f32_e32 v30, v30, v33
	v_mul_f32_e32 v31, v31, v33
	v_mul_f32_e32 v24, v24, v33
	v_mul_f32_e32 v25, v25, v33
	v_mov_b32_e32 v29, 0
	v_cvt_pk_fp8_f32 v28, v30, v31 op_sel:[0,0,1]
	v_mul_f32_e32 v20, v20, v33
	v_mul_f32_e32 v21, v21, v33
	v_mov_b32_e32 v30, 0
	v_mul_f32_e32 v16, v16, v33
	v_mul_f32_e32 v17, v17, v33
	v_mov_b32_e32 v31, 0
	v_cvt_pk_fp8_f32 v29, v24, v25
	v_cvt_pk_fp8_f32 v30, v20, v21
	v_cvt_pk_fp8_f32 v31, v16, v17
	v_mul_f32_e32 v24, v26, v33
	v_mul_f32_e32 v25, v27, v33
	v_mul_f32_e32 v22, v22, v33
	v_mul_f32_e32 v23, v23, v33
	v_mul_f32_e32 v16, v18, v33
	v_mul_f32_e32 v17, v19, v33
	v_cvt_pk_fp8_f32 v29, v24, v25 op_sel:[0,0,1]
	v_cvt_pk_fp8_f32 v30, v22, v23 op_sel:[0,0,1]
	v_cvt_pk_fp8_f32 v31, v16, v17 op_sel:[0,0,1]
	v_ashrrev_i32_e32 v33, 31, v32
	v_lshlrev_b64 v[16:17], 10, v[32:33]
	v_lshl_add_u64 v[16:17], v[52:53], 0, v[16:17]
	global_store_dwordx4 v[16:17], v[28:31], off
	s_and_b64 exec, exec, s[0:1]
	s_cbranch_execz .LBB0_355
	v_lshl_add_u64 v[16:17], v[32:33], 3, s[20:21]
	global_store_dword v[16:17], v34, off
.LBB0_355:
	s_or_b64 exec, exec, s[8:9]
	s_waitcnt vmcnt(1)
	v_max3_f32 v16, |v12|, 0, |v13|
	v_max3_f32 v16, v16, |v14|, |v15|
	v_max3_f32 v16, v16, |v8|, |v9|
	v_max3_f32 v16, v16, |v10|, |v11|
	v_max3_f32 v16, v16, |v4|, |v5|
	v_max3_f32 v16, v16, |v6|, |v7|
	v_max3_f32 v16, v16, |v0|, |v1|
	v_max3_f32 v16, v16, |v2|, |v3|
	v_mov_b32_e32 v17, v16
	s_nop 1
	v_permlane16_swap_b32_e32 v16, v17
	v_max_f32_e32 v17, v17, v17
	v_max_f32_e32 v16, v16, v16
	v_max_f32_e32 v16, v16, v17
	v_mov_b32_e32 v17, v16
	s_nop 1
	v_permlane32_swap_b32_e32 v16, v17
	v_max_f32_e32 v17, v17, v17
	v_max_f32_e32 v16, v16, v16
	v_max_f32_e32 v16, v16, v17
	s_nop 1
	v_mov_b32_dpp v17, v16 quad_perm:[1,0,3,2] row_mask:0xf bank_mask:0xf bound_ctrl:1
	v_max_f32_e32 v17, v17, v17
	v_max_f32_e32 v16, v16, v17
	s_nop 1
	v_mov_b32_dpp v17, v16 quad_perm:[2,3,0,1] row_mask:0xf bank_mask:0xf bound_ctrl:1
	v_max_f32_e32 v17, v17, v17
	v_max_f32_e32 v16, v16, v17
	s_nop 1
	v_mov_b32_dpp v17, v16 row_half_mirror row_mask:0xf bank_mask:0xf bound_ctrl:1
	v_max_f32_e32 v17, v17, v17
	v_max_f32_e32 v16, v16, v17
	s_nop 1
	v_mov_b32_dpp v17, v16 row_mirror row_mask:0xf bank_mask:0xf bound_ctrl:1
	s_and_saveexec_b64 s[6:7], s[4:5]
	s_cbranch_execz .LBB0_346
	v_max3_f32 v16, v16, v17, s24
	v_mul_f32_e32 v18, 0x3b800000, v16
	v_div_scale_f32 v17, s[4:5], v18, v18, 1.0
	v_rcp_f32_e32 v19, v17
	v_add_u32_e32 v16, s22, v54
	v_fma_f32 v20, -v17, v19, 1.0
	v_fmac_f32_e32 v19, v20, v19
	v_div_scale_f32 v20, vcc, 1.0, v18, 1.0
	v_mul_f32_e32 v21, v20, v19
	v_fma_f32 v22, -v17, v21, v20
	v_fmac_f32_e32 v21, v22, v19
	v_fma_f32 v17, -v17, v21, v20
	v_div_fmas_f32 v17, v17, v19, v21
	v_div_fixup_f32 v17, v17, v18, 1.0
	v_mul_f32_e32 v19, v12, v17
	v_mul_f32_e32 v13, v13, v17
	v_mov_b32_e32 v12, 0
	v_cvt_pk_fp8_f32 v12, v19, v13
	v_mul_f32_e32 v14, v14, v17
	v_mul_f32_e32 v15, v15, v17
	v_mul_f32_e32 v8, v8, v17
	v_mul_f32_e32 v9, v9, v17
	v_mov_b32_e32 v13, 0
	v_cvt_pk_fp8_f32 v12, v14, v15 op_sel:[0,0,1]
	v_mul_f32_e32 v4, v4, v17
	v_mul_f32_e32 v5, v5, v17
	v_mov_b32_e32 v14, 0
	v_mul_f32_e32 v0, v0, v17
	v_mul_f32_e32 v1, v1, v17
	v_mov_b32_e32 v15, 0
	v_cvt_pk_fp8_f32 v13, v8, v9
	v_cvt_pk_fp8_f32 v14, v4, v5
	v_cvt_pk_fp8_f32 v15, v0, v1
	v_mul_f32_e32 v8, v10, v17
	v_mul_f32_e32 v9, v11, v17
	v_mul_f32_e32 v6, v6, v17
	v_mul_f32_e32 v7, v7, v17
	v_mul_f32_e32 v0, v2, v17
	v_mul_f32_e32 v1, v3, v17
	v_cvt_pk_fp8_f32 v13, v8, v9 op_sel:[0,0,1]
	v_cvt_pk_fp8_f32 v14, v6, v7 op_sel:[0,0,1]
	v_cvt_pk_fp8_f32 v15, v0, v1 op_sel:[0,0,1]
	v_ashrrev_i32_e32 v17, 31, v16
	v_lshlrev_b64 v[0:1], 10, v[16:17]
	v_lshl_add_u64 v[0:1], v[52:53], 0, v[0:1]
	global_store_dwordx4 v[0:1], v[12:15], off
	s_and_b64 exec, exec, s[0:1]
	s_cbranch_execz .LBB0_346
	v_lshl_add_u64 v[0:1], v[16:17], 3, s[20:21]
	global_store_dword v[0:1], v18, off
	s_branch .LBB0_346

; #define LAS __attribute__((address_space(3)))
; __device__ __forceinline__ unsigned f2key(float f) { const unsigned u = __float_as_uint(f); return (u & 0x80000000u) ? ~u : (u | 0x80000000u); }
; __device__ __forceinline__ void peer_tile(const Args& A, LAS unsigned char* lds, int tile) {
;     int tid_o = threadIdx.x; asm volatile("" : "+v"(tid_o)); const int tid = tid_o, lane = tid & 63, w = tid >> 6, g = lane >> 4, l15 = lane & 15;
;     const bf16_t* QRY = (const bf16_t*)(A.ws + WS_QRY);
;     const bf16_t* KEYS = (const bf16_t*)(A.ws + WS_KEYS);
;     const bf16_t* ACT = (const bf16_t*)(A.ws + WS_ACT);
;     const float* MOD = (const float*)(A.ws + WS_MOD);
;     LAS unsigned* idx = (LAS unsigned*)(lds + PE_IDX) + (w * 64 + lane) * 33;
;     LAS u32x2* SEL = (LAS u32x2*)(lds + PE_SEL);
;     {
;         const int tg = w & 3, hg = w >> 2, tl = 16 * tg + l15;
;         const size_t m = (size_t)tile * 64 + tl;
;         unsigned LA[4][2][16];
; #pragma unroll
;         for (int hh = 0; hh < 4; ++hh) {
;             const int h = 4 * hg + hh;
; #pragma unroll
;             for (int p = 0; p < 2; ++p) {
;                 const int hp = 2 * h + p;
;                 unsigned k0[16], k1[16];
;                 { const bf16_t* sp = QRY + m * 2048 + hp * 128 + 32 * g;
;                   const u32x4 s0 = *(const u32x4*)sp, s1 = *(const u32x4*)(sp + 8), s2 = *(const u32x4*)(sp + 16), s3 = *(const u32x4*)(sp + 24);
;                   const unsigned sw[16] = {s0.x, s0.y, s0.z, s0.w, s1.x, s1.y, s1.z, s1.w, s2.x, s2.y, s2.z, s2.w, s3.x, s3.y, s3.z, s3.w};
; #pragma unroll
;                   for (int i = 0; i < 16; ++i) {
;                       const float lo = (float)__builtin_bit_cast(_Float16, (unsigned short)(sw[i] & 0xffffu)), hi = (float)__builtin_bit_cast(_Float16, (unsigned short)(sw[i] >> 16));
;                       const unsigned klo = (f2key(lo) & ~127u) | (unsigned)(127 - (32 * g + 2 * i)), khi = (f2key(hi) & ~127u) | (unsigned)(127 - (32 * g + 2 * i + 1));
;                       if (i < 8) { k0[2 * i] = klo; k0[2 * i + 1] = khi; } else { k1[2 * (i - 8)] = klo; k1[2 * (i - 8) + 1] = khi; } } }
.LBB0_699:
	v_mov_b32_e32 v19, v214
	s_ashr_i32 s3, s2, 31
	v_ashrrev_i32_e32 v7, 6, v19
	v_and_b32_e32 v0, 15, v19
	v_lshlrev_b32_e32 v1, 4, v7
	v_and_or_b32 v13, v1, 48, v0
	s_lshl_b64 s[28:29], s[2:3], 6
	v_or_b32_e32 v0, s28, v13
	v_mov_b32_e32 v1, s29
	v_bfe_u32 v221, v19, 4, 2
	v_ashrrev_i32_e32 v11, 8, v19
	v_lshlrev_b64 v[0:1], 12, v[0:1]
	v_lshlrev_b32_e32 v2, 10, v11
	v_lshl_add_u64 v[0:1], s[54:55], 0, v[0:1]
	v_lshlrev_b32_e32 v112, 6, v221
	v_lshl_add_u64 v[0:1], v[0:1], 0, v[112:113]
	v_ashrrev_i32_e32 v3, 31, v2
	v_lshl_add_u64 v[4:5], v[2:3], 1, v[0:1]
	global_load_dwordx4 v[20:23], v[4:5], off
	global_load_dwordx4 v[24:27], v[4:5], off offset:16
	global_load_dwordx4 v[0:3], v[4:5], off offset:48
	global_load_dwordx4 v[28:31], v[4:5], off offset:32
	v_lshlrev_b32_e32 v15, 5, v221
	v_or_b32_e32 v8, 8, v15
	v_or_b32_e32 v14, 2, v15
	v_or_b32_e32 v12, 4, v15
	v_or_b32_e32 v10, 6, v15
	v_and_b32_e32 v9, 63, v19
	v_cmp_gt_u32_e64 s[0:1], 16, v9
	v_cmp_gt_u32_e64 s[4:5], 32, v9
	v_mul_lo_u32 v6, v19, s17
	s_mov_b32 s3, 8
	s_waitcnt vmcnt(3)
	v_cvt_f32_f16_sdwa v17, v20 dst_sel:DWORD dst_unused:UNUSED_PAD src0_sel:WORD_1
	v_cvt_f32_f16_e32 v16, v20
	v_cvt_f32_f16_sdwa v20, v21 dst_sel:DWORD dst_unused:UNUSED_PAD src0_sel:WORD_1
	v_cvt_f32_f16_e32 v18, v21
	v_cvt_f32_f16_e32 v21, v22
	v_cvt_f32_f16_sdwa v22, v22 dst_sel:DWORD dst_unused:UNUSED_PAD src0_sel:WORD_1
	v_not_b32_e32 v34, v17
	v_or_b32_e32 v35, 0x80000000, v17
	v_cmp_gt_i32_e32 vcc, 0, v17
	v_not_b32_e32 v36, v16
	v_or_b32_e32 v37, 0x80000000, v16
	v_cndmask_b32_e32 v17, v35, v34, vcc
	v_cmp_gt_i32_e32 vcc, 0, v16
	v_cvt_f32_f16_e32 v32, v23
	v_cvt_f32_f16_sdwa v23, v23 dst_sel:DWORD dst_unused:UNUSED_PAD src0_sel:WORD_1
	v_not_b32_e32 v38, v20
	v_or_b32_e32 v39, 0x80000000, v20
	v_cndmask_b32_e32 v16, v37, v36, vcc
	v_cmp_gt_i32_e32 vcc, 0, v20
	v_not_b32_e32 v40, v18
	v_or_b32_e32 v41, 0x80000000, v18
	v_cndmask_b32_e32 v20, v39, v38, vcc
	v_cmp_gt_i32_e32 vcc, 0, v18
	s_waitcnt vmcnt(2)
	v_cvt_f32_f16_e32 v33, v24
	v_cvt_f32_f16_sdwa v24, v24 dst_sel:DWORD dst_unused:UNUSED_PAD src0_sel:WORD_1
	v_not_b32_e32 v42, v22
	v_or_b32_e32 v43, 0x80000000, v22
	v_cndmask_b32_e32 v18, v41, v40, vcc
	v_cmp_gt_i32_e32 vcc, 0, v22
	v_not_b32_e32 v44, v21
	v_or_b32_e32 v45, 0x80000000, v21
	v_cndmask_b32_e32 v22, v43, v42, vcc
	v_cmp_gt_i32_e32 vcc, 0, v21
	v_not_b32_e32 v46, v23
	v_or_b32_e32 v47, 0x80000000, v23
	v_cndmask_b32_e32 v21, v45, v44, vcc
	v_cmp_gt_i32_e32 vcc, 0, v23
	v_not_b32_e32 v48, v32
	v_or_b32_e32 v49, 0x80000000, v32
	v_cndmask_b32_e32 v23, v47, v46, vcc
	v_cmp_gt_i32_e32 vcc, 0, v32
	v_and_b32_e32 v16, 0xffffff80, v16
	v_not_b32_e32 v50, v24
	v_or_b32_e32 v51, 0x80000000, v24
	v_cndmask_b32_e32 v32, v49, v48, vcc
	v_sub_u32_e32 v16, v16, v15
	v_cmp_gt_i32_e32 vcc, 0, v24
	v_add_u32_e32 v35, 0x7f, v16
	v_and_b32_e32 v17, 0xffffff80, v17
	v_cndmask_b32_e32 v16, v51, v50, vcc
	v_and_b32_e32 v16, 0xffffff80, v16
	v_sub_u32_e32 v17, v17, v15
	v_sub_u32_e32 v16, v16, v8
	v_add_u32_e32 v34, 0x7e, v17
	v_add_u32_e32 v41, 0x7e, v16
	v_not_b32_e32 v16, v33
	v_or_b32_e32 v17, 0x80000000, v33
	v_cmp_gt_i32_e32 vcc, 0, v33
	v_and_b32_e32 v20, 0xffffff80, v20
	v_and_b32_e32 v18, 0xffffff80, v18
	v_cndmask_b32_e32 v16, v17, v16, vcc
	v_cvt_f32_f16_sdwa v17, v25 dst_sel:DWORD dst_unused:UNUSED_PAD src0_sel:WORD_1
	v_and_b32_e32 v21, 0xffffff80, v21
	v_sub_u32_e32 v20, v20, v14
	v_sub_u32_e32 v18, v18, v14
	v_sub_u32_e32 v21, v21, v12
	v_add_u32_e32 v36, 0x7e, v20
	v_add_u32_e32 v37, 0x7f, v18
	v_add_u32_e32 v39, 0x7f, v21
	v_and_b32_e32 v16, 0xffffff80, v16
	v_cvt_f32_f16_e32 v18, v25
	v_not_b32_e32 v20, v17
	v_or_b32_e32 v21, 0x80000000, v17
	v_cmp_gt_i32_e32 vcc, 0, v17
	v_sub_u32_e32 v16, v16, v8
	v_add_u32_e32 v33, 0x7f, v16
	v_cndmask_b32_e32 v17, v21, v20, vcc
	v_or_b32_e32 v16, 10, v15
	v_and_b32_e32 v17, 0xffffff80, v17
	v_sub_u32_e32 v17, v17, v16
	v_add_u32_e32 v42, 0x7e, v17
	v_not_b32_e32 v17, v18
	v_or_b32_e32 v20, 0x80000000, v18
	v_cmp_gt_i32_e32 vcc, 0, v18
	v_cvt_f32_f16_sdwa v18, v26 dst_sel:DWORD dst_unused:UNUSED_PAD src0_sel:WORD_1
	v_and_b32_e32 v22, 0xffffff80, v22
	v_sub_u32_e32 v22, v22, v12
	v_cndmask_b32_e32 v17, v20, v17, vcc
	v_add_u32_e32 v38, 0x7e, v22
	v_and_b32_e32 v17, 0xffffff80, v17
	v_cvt_f32_f16_e32 v20, v26
	v_not_b32_e32 v21, v18
	v_or_b32_e32 v22, 0x80000000, v18
	v_cmp_gt_i32_e32 vcc, 0, v18
	v_sub_u32_e32 v17, v17, v16
	v_add_u32_e32 v43, 0x7f, v17
	v_cndmask_b32_e32 v18, v22, v21, vcc
	v_or_b32_e32 v17, 12, v15
	v_and_b32_e32 v18, 0xffffff80, v18
	v_sub_u32_e32 v18, v18, v17
	v_add_u32_e32 v44, 0x7e, v18
	v_not_b32_e32 v18, v20
	v_or_b32_e32 v21, 0x80000000, v20
	v_cmp_gt_i32_e32 vcc, 0, v20
	v_cvt_f32_f16_sdwa v20, v27 dst_sel:DWORD dst_unused:UNUSED_PAD src0_sel:WORD_1
	v_and_b32_e32 v23, 0xffffff80, v23
	v_sub_u32_e32 v23, v23, v10
	v_cndmask_b32_e32 v18, v21, v18, vcc
	v_add_u32_e32 v40, 0x7e, v23
	v_and_b32_e32 v18, 0xffffff80, v18
	v_cvt_f32_f16_e32 v21, v27
	v_not_b32_e32 v22, v20
	v_or_b32_e32 v23, 0x80000000, v20
	v_cmp_gt_i32_e32 vcc, 0, v20
	v_sub_u32_e32 v18, v18, v17
	v_add_u32_e32 v45, 0x7f, v18
	v_cndmask_b32_e32 v20, v23, v22, vcc
	v_or_b32_e32 v18, 14, v15
	v_and_b32_e32 v20, 0xffffff80, v20
	v_sub_u32_e32 v20, v20, v18
	v_add_u32_e32 v27, 0x7e, v20
	v_not_b32_e32 v20, v21
	v_or_b32_e32 v22, 0x80000000, v21
	v_cmp_gt_i32_e32 vcc, 0, v21
	s_waitcnt vmcnt(0)
; __device__ __forceinline__ unsigned f2key(float f) { const unsigned u = __float_as_uint(f); return (u & 0x80000000u) ? ~u : (u | 0x80000000u); }
; __device__ __forceinline__ void peer_tile(const Args& A, LAS unsigned char* lds, int tile) {
;     ...
;                   for (int i = 0; i < 16; ++i) {
;                       const float lo = (float)__builtin_bit_cast(_Float16, (unsigned short)(sw[i] & 0xffffu)), hi = (float)__builtin_bit_cast(_Float16, (unsigned short)(sw[i] >> 16));
;                       const unsigned klo = (f2key(lo) & ~127u) | (unsigned)(127 - (32 * g + 2 * i)), khi = (f2key(hi) & ~127u) | (unsigned)(127 - (32 * g + 2 * i + 1));
;                       if (i < 8) { k0[2 * i] = klo; k0[2 * i + 1] = khi; } else { k1[2 * (i - 8)] = klo; k1[2 * (i - 8) + 1] = khi; } } }
;                 sort16_desc(k0); sort16_desc(k1); merge16(k0, k1);
	v_cvt_f32_f16_sdwa v21, v28 dst_sel:DWORD dst_unused:UNUSED_PAD src0_sel:WORD_1
	v_and_b32_e32 v32, 0xffffff80, v32
	v_cndmask_b32_e32 v20, v22, v20, vcc
	v_and_b32_e32 v20, 0xffffff80, v20
	v_cvt_f32_f16_e32 v22, v28
	v_not_b32_e32 v23, v21
	v_or_b32_e32 v24, 0x80000000, v21
	v_cmp_gt_i32_e32 vcc, 0, v21
	v_sub_u32_e32 v20, v20, v18
	v_add_u32_e32 v46, 0x7f, v20
	v_cndmask_b32_e32 v21, v24, v23, vcc
	v_or_b32_e32 v20, 16, v15
	v_and_b32_e32 v21, 0xffffff80, v21
	v_sub_u32_e32 v21, v21, v20
	v_add_u32_e32 v47, 0x7e, v21
	v_not_b32_e32 v21, v22
	v_or_b32_e32 v23, 0x80000000, v22
	v_cmp_gt_i32_e32 vcc, 0, v22
	v_cvt_f32_f16_sdwa v22, v29 dst_sel:DWORD dst_unused:UNUSED_PAD src0_sel:WORD_1
	v_sub_u32_e32 v32, v32, v10
	v_cndmask_b32_e32 v21, v23, v21, vcc
	v_and_b32_e32 v21, 0xffffff80, v21
	v_cvt_f32_f16_e32 v23, v29
	v_not_b32_e32 v24, v22
	v_or_b32_e32 v25, 0x80000000, v22
	v_cmp_gt_i32_e32 vcc, 0, v22
	v_sub_u32_e32 v21, v21, v20
	v_add_u32_e32 v48, 0x7f, v21
	v_cndmask_b32_e32 v22, v25, v24, vcc
	v_or_b32_e32 v21, 18, v15
	v_and_b32_e32 v22, 0xffffff80, v22
	v_sub_u32_e32 v22, v22, v21
	v_add_u32_e32 v29, 0x7e, v22
	v_not_b32_e32 v22, v23
	v_or_b32_e32 v24, 0x80000000, v23
	v_cmp_gt_i32_e32 vcc, 0, v23
	v_cvt_f32_f16_sdwa v23, v30 dst_sel:DWORD dst_unused:UNUSED_PAD src0_sel:WORD_1
	v_add_u32_e32 v32, 0x7f, v32
	v_cndmask_b32_e32 v22, v24, v22, vcc
	v_and_b32_e32 v22, 0xffffff80, v22
	v_cvt_f32_f16_e32 v24, v30
	v_not_b32_e32 v25, v23
	v_or_b32_e32 v26, 0x80000000, v23
	v_cmp_gt_i32_e32 vcc, 0, v23
	v_sub_u32_e32 v22, v22, v21
	v_add_u32_e32 v49, 0x7f, v22
	v_cndmask_b32_e32 v23, v26, v25, vcc
	v_or_b32_e32 v22, 20, v15
	v_and_b32_e32 v23, 0xffffff80, v23
	v_sub_u32_e32 v23, v23, v22
	v_add_u32_e32 v30, 0x7e, v23
	v_not_b32_e32 v23, v24
	v_or_b32_e32 v25, 0x80000000, v24
	v_cmp_gt_i32_e32 vcc, 0, v24
	v_cvt_f32_f16_sdwa v24, v31 dst_sel:DWORD dst_unused:UNUSED_PAD src0_sel:WORD_1
	v_max_u32_e32 v64, v48, v47
	v_cndmask_b32_e32 v23, v25, v23, vcc
	v_and_b32_e32 v23, 0xffffff80, v23
	v_cvt_f32_f16_e32 v25, v31
	v_not_b32_e32 v26, v24
	v_or_b32_e32 v28, 0x80000000, v24
	v_cmp_gt_i32_e32 vcc, 0, v24
	v_sub_u32_e32 v23, v23, v22
	v_add_u32_e32 v50, 0x7f, v23
	v_cndmask_b32_e32 v24, v28, v26, vcc
	v_or_b32_e32 v23, 22, v15
	v_and_b32_e32 v24, 0xffffff80, v24
	v_sub_u32_e32 v24, v24, v23
	v_add_u32_e32 v31, 0x7e, v24
	v_not_b32_e32 v24, v25
	v_or_b32_e32 v26, 0x80000000, v25
	v_cmp_gt_i32_e32 vcc, 0, v25
	v_cvt_f32_f16_sdwa v25, v0 dst_sel:DWORD dst_unused:UNUSED_PAD src0_sel:WORD_1
	v_cvt_f32_f16_e32 v0, v0
	v_cndmask_b32_e32 v24, v26, v24, vcc
	v_and_b32_e32 v24, 0xffffff80, v24
	v_not_b32_e32 v26, v25
	v_or_b32_e32 v28, 0x80000000, v25
	v_cmp_gt_i32_e32 vcc, 0, v25
	v_sub_u32_e32 v24, v24, v23
	v_add_u32_e32 v51, 0x7f, v24
	v_cndmask_b32_e32 v25, v28, v26, vcc
	v_or_b32_e32 v24, 24, v15
	v_and_b32_e32 v25, 0xffffff80, v25
	v_sub_u32_e32 v25, v25, v24
	v_add_u32_e32 v52, 0x7e, v25
	v_not_b32_e32 v25, v0
	v_or_b32_e32 v26, 0x80000000, v0
	v_cmp_gt_i32_e32 vcc, 0, v0
	v_min_u32_e32 v47, v48, v47
	v_max_u32_e32 v48, v29, v49
	v_cndmask_b32_e32 v0, v26, v25, vcc
	v_cvt_f32_f16_sdwa v26, v1 dst_sel:DWORD dst_unused:UNUSED_PAD src0_sel:WORD_1
	v_cvt_f32_f16_e32 v1, v1
	v_or_b32_e32 v25, 26, v15
	v_and_b32_e32 v0, 0xffffff80, v0
	v_not_b32_e32 v28, v26
	v_or_b32_e32 v53, 0x80000000, v26
	v_cmp_gt_i32_e32 vcc, 0, v26
	v_sub_u32_e32 v0, v0, v24
	v_add_u32_e32 v0, 0x7f, v0
	v_cndmask_b32_e32 v26, v53, v28, vcc
	v_and_b32_e32 v26, 0xffffff80, v26
	v_sub_u32_e32 v26, v26, v25
	v_add_u32_e32 v53, 0x7e, v26
	v_not_b32_e32 v26, v1
	v_or_b32_e32 v28, 0x80000000, v1
	v_cmp_gt_i32_e32 vcc, 0, v1
	v_min_u32_e32 v29, v29, v49
	v_max_u32_e32 v49, v50, v30
	v_cndmask_b32_e32 v1, v28, v26, vcc
	v_cvt_f32_f16_sdwa v28, v2 dst_sel:DWORD dst_unused:UNUSED_PAD src0_sel:WORD_1
	v_cvt_f32_f16_e32 v2, v2
	v_or_b32_e32 v26, 28, v15
	v_and_b32_e32 v1, 0xffffff80, v1
	v_not_b32_e32 v54, v28
	v_or_b32_e32 v55, 0x80000000, v28
	v_cmp_gt_i32_e32 vcc, 0, v28
	v_sub_u32_e32 v1, v1, v25
	v_add_u32_e32 v1, 0x7f, v1
	v_cndmask_b32_e32 v28, v55, v54, vcc
	v_and_b32_e32 v28, 0xffffff80, v28
	v_sub_u32_e32 v28, v28, v26
	v_add_u32_e32 v54, 0x7e, v28
	v_not_b32_e32 v28, v2
	v_or_b32_e32 v55, 0x80000000, v2
	v_cmp_gt_i32_e32 vcc, 0, v2
	v_min_u32_e32 v30, v50, v30
	v_max_u32_e32 v50, v31, v51
	v_cndmask_b32_e32 v2, v55, v28, vcc
	v_cvt_f32_f16_e32 v55, v3
	v_cvt_f32_f16_sdwa v3, v3 dst_sel:DWORD dst_unused:UNUSED_PAD src0_sel:WORD_1
	v_and_b32_e32 v2, 0xffffff80, v2
	v_or_b32_e32 v28, 30, v15
	v_not_b32_e32 v56, v55
	v_or_b32_e32 v57, 0x80000000, v55
	v_cmp_gt_i32_e32 vcc, 0, v55
	v_sub_u32_e32 v2, v2, v26
	v_add_u32_e32 v2, 0x7f, v2
	v_cndmask_b32_e32 v55, v57, v56, vcc
	v_not_b32_e32 v56, v3
	v_or_b32_e32 v57, 0x80000000, v3
	v_cmp_gt_i32_e32 vcc, 0, v3
	v_and_b32_e32 v55, 0xffffff80, v55
	v_sub_u32_e32 v55, v55, v28
	v_cndmask_b32_e32 v3, v57, v56, vcc
	v_and_b32_e32 v3, 0xffffff80, v3
	v_sub_u32_e32 v3, v3, v28
	v_add_u32_e32 v55, 0x7f, v55
	v_add_u32_e32 v3, 0x7e, v3
	v_max_u32_e32 v56, v35, v34
	v_min_u32_e32 v34, v35, v34
	v_max_u32_e32 v35, v36, v37
	v_min_u32_e32 v36, v36, v37
	v_max_u32_e32 v37, v39, v38
	v_min_u32_e32 v38, v39, v38
	v_max_u32_e32 v39, v40, v32
	v_min_u32_e32 v32, v40, v32
	v_max_u32_e32 v40, v33, v41
	v_min_u32_e32 v33, v33, v41
	v_max_u32_e32 v41, v42, v43
	v_min_u32_e32 v42, v42, v43
	v_max_u32_e32 v43, v45, v44
	v_min_u32_e32 v44, v45, v44
	v_max_u32_e32 v45, v27, v46
	v_min_u32_e32 v27, v27, v46
	v_min_u32_e32 v31, v31, v51
	v_max_u32_e32 v51, v0, v52
	v_min_u32_e32 v0, v0, v52
	v_max_u32_e32 v52, v53, v1
	v_min_u32_e32 v1, v53, v1
	v_max_u32_e32 v53, v2, v54
; #define CE_DESC(a, b) do { const unsigned _mx = (a) > (b) ? (a) : (b), _mn = (a) > (b) ? (b) : (a); (a) = _mx; (b) = _mn; } while (0)
; __device__ __forceinline__ void sort16_desc(unsigned (&k)[16]) {
; #pragma unroll
;     for (int size = 2; size <= 16; size <<= 1)
; #pragma unroll
;         for (int stride = size >> 1; stride > 0; stride >>= 1)
; #pragma unroll
;             for (int i = 0; i < 16; ++i) { const int j = i ^ stride;
;                 if (j > i) { if ((i & size) == 0) CE_DESC(k[i], k[j]); else CE_DESC(k[j], k[i]); } }
; }
	v_min_u32_e32 v2, v2, v54
	v_max_u32_e32 v54, v3, v55
	v_min_u32_e32 v3, v3, v55
	v_max_u32_e32 v46, v56, v36
	v_min_u32_e32 v36, v56, v36
	v_max_u32_e32 v56, v34, v35
	v_min_u32_e32 v34, v34, v35
	v_max_u32_e32 v35, v32, v37
	v_min_u32_e32 v32, v32, v37
	v_max_u32_e32 v37, v39, v38
	v_min_u32_e32 v38, v39, v38
	v_max_u32_e32 v39, v40, v42
	v_min_u32_e32 v40, v40, v42
	v_max_u32_e32 v42, v33, v41
	v_min_u32_e32 v33, v33, v41
	v_max_u32_e32 v41, v27, v43
	v_min_u32_e32 v27, v27, v43
	v_max_u32_e32 v43, v45, v44
	v_min_u32_e32 v44, v45, v44
	v_max_u32_e32 v55, v64, v29
	v_min_u32_e32 v29, v64, v29
	v_max_u32_e32 v64, v47, v48
	v_min_u32_e32 v47, v47, v48
	v_max_u32_e32 v48, v31, v49
	v_min_u32_e32 v31, v31, v49
	v_max_u32_e32 v49, v50, v30
	v_min_u32_e32 v30, v50, v30
	v_max_u32_e32 v50, v51, v1
	v_min_u32_e32 v1, v51, v1
	v_max_u32_e32 v51, v0, v52
	v_min_u32_e32 v0, v0, v52
	v_max_u32_e32 v52, v3, v53
	v_min_u32_e32 v3, v3, v53
	v_max_u32_e32 v53, v54, v2
	v_min_u32_e32 v2, v54, v2
	v_max_u32_e32 v45, v46, v56
	v_min_u32_e32 v46, v46, v56
	v_max_u32_e32 v56, v36, v34
	v_min_u32_e32 v34, v36, v34
	v_max_u32_e32 v36, v38, v32
	v_min_u32_e32 v32, v38, v32
	v_max_u32_e32 v38, v37, v35
	v_min_u32_e32 v35, v37, v35
	v_max_u32_e32 v37, v39, v42
	v_min_u32_e32 v39, v39, v42
	v_max_u32_e32 v42, v40, v33
	v_min_u32_e32 v33, v40, v33
	v_max_u32_e32 v40, v44, v27
	v_min_u32_e32 v27, v44, v27
	v_max_u32_e32 v44, v43, v41
	v_min_u32_e32 v41, v43, v41
	v_max_u32_e32 v54, v55, v64
	v_min_u32_e32 v55, v55, v64
	v_max_u32_e32 v64, v29, v47
	v_min_u32_e32 v29, v29, v47
	v_max_u32_e32 v47, v30, v31
	v_min_u32_e32 v30, v30, v31
	v_max_u32_e32 v31, v49, v48
	v_min_u32_e32 v48, v49, v48
	v_max_u32_e32 v49, v50, v51
	v_min_u32_e32 v50, v50, v51
	v_max_u32_e32 v51, v1, v0
	v_min_u32_e32 v0, v1, v0
	v_max_u32_e32 v1, v2, v3
	v_min_u32_e32 v2, v2, v3
	v_max_u32_e32 v3, v53, v52
	v_min_u32_e32 v52, v53, v52
	v_max_u32_e32 v43, v45, v32
	v_min_u32_e32 v32, v45, v32
	v_max_u32_e32 v45, v46, v36
	v_min_u32_e32 v36, v46, v36
	v_max_u32_e32 v46, v56, v35
	v_min_u32_e32 v35, v56, v35
	v_max_u32_e32 v56, v34, v38
	v_min_u32_e32 v34, v34, v38
	v_max_u32_e32 v38, v27, v37
	v_min_u32_e32 v27, v27, v37
	v_max_u32_e32 v37, v40, v39
	v_min_u32_e32 v39, v40, v39
	v_max_u32_e32 v40, v41, v42
	v_min_u32_e32 v41, v41, v42
	v_max_u32_e32 v42, v44, v33
	v_min_u32_e32 v33, v44, v33
	v_max_u32_e32 v53, v54, v30
	v_min_u32_e32 v30, v54, v30
	v_max_u32_e32 v54, v55, v47
	v_min_u32_e32 v47, v55, v47
	v_max_u32_e32 v55, v64, v48
	v_min_u32_e32 v48, v64, v48
	v_max_u32_e32 v64, v29, v31
	v_min_u32_e32 v29, v29, v31
	v_max_u32_e32 v31, v2, v49
	v_min_u32_e32 v2, v2, v49
	v_max_u32_e32 v49, v1, v50
	v_min_u32_e32 v1, v1, v50
	v_max_u32_e32 v50, v52, v51
	v_min_u32_e32 v51, v52, v51
	v_max_u32_e32 v52, v3, v0
	v_min_u32_e32 v0, v3, v0
	v_max_u32_e32 v44, v43, v46
	v_min_u32_e32 v43, v43, v46
	v_max_u32_e32 v46, v45, v56
	v_min_u32_e32 v45, v45, v56
	v_max_u32_e32 v56, v32, v35
	v_min_u32_e32 v32, v32, v35
	v_max_u32_e32 v35, v36, v34
	v_min_u32_e32 v34, v36, v34
	v_max_u32_e32 v36, v41, v27
	v_min_u32_e32 v27, v41, v27
	v_max_u32_e32 v41, v33, v39
	v_min_u32_e32 v33, v33, v39
	v_max_u32_e32 v39, v40, v38
	v_min_u32_e32 v38, v40, v38
	v_max_u32_e32 v40, v42, v37
	v_min_u32_e32 v37, v42, v37
	v_max_u32_e32 v3, v53, v55
	v_min_u32_e32 v53, v53, v55
	v_max_u32_e32 v55, v54, v64
	v_min_u32_e32 v54, v54, v64
	v_max_u32_e32 v64, v30, v48
	v_min_u32_e32 v30, v30, v48
	v_max_u32_e32 v48, v47, v29
	v_min_u32_e32 v29, v47, v29
	v_max_u32_e32 v47, v51, v2
	v_min_u32_e32 v2, v51, v2
	v_max_u32_e32 v51, v0, v1
	v_min_u32_e32 v0, v0, v1
	v_max_u32_e32 v1, v50, v31
	v_min_u32_e32 v31, v50, v31
	v_max_u32_e32 v50, v52, v49
	v_min_u32_e32 v49, v52, v49
	v_max_u32_e32 v42, v44, v46
	v_min_u32_e32 v44, v44, v46
	v_max_u32_e32 v46, v43, v45
	v_min_u32_e32 v43, v43, v45
	v_max_u32_e32 v45, v56, v35
	v_min_u32_e32 v35, v56, v35
	v_max_u32_e32 v56, v32, v34
	v_min_u32_e32 v32, v32, v34
	v_max_u32_e32 v34, v33, v27
	v_min_u32_e32 v27, v33, v27
	v_max_u32_e32 v33, v41, v36
	v_min_u32_e32 v36, v41, v36
	v_max_u32_e32 v41, v37, v38
	v_min_u32_e32 v37, v37, v38
	v_max_u32_e32 v38, v40, v39
	v_min_u32_e32 v39, v40, v39
	v_max_u32_e32 v52, v3, v55
	v_min_u32_e32 v3, v3, v55
	v_max_u32_e32 v55, v53, v54
	v_min_u32_e32 v53, v53, v54
	v_max_u32_e32 v54, v64, v48
	v_min_u32_e32 v48, v64, v48
	v_max_u32_e32 v64, v30, v29
	v_min_u32_e32 v29, v30, v29
	v_max_u32_e32 v30, v0, v2
	v_min_u32_e32 v0, v0, v2
	v_max_u32_e32 v2, v51, v47
	v_min_u32_e32 v47, v51, v47
	v_max_u32_e32 v51, v49, v31
	v_min_u32_e32 v31, v49, v31
	v_max_u32_e32 v49, v50, v1
	v_min_u32_e32 v1, v50, v1
	v_max_u32_e32 v40, v42, v27
	v_min_u32_e32 v27, v42, v27
	v_max_u32_e32 v42, v44, v34
	v_min_u32_e32 v34, v44, v34
	v_max_u32_e32 v44, v46, v36
	v_min_u32_e32 v36, v46, v36
	v_max_u32_e32 v46, v43, v33
	v_min_u32_e32 v33, v43, v33
	v_max_u32_e32 v43, v45, v37
	v_min_u32_e32 v37, v45, v37
	v_max_u32_e32 v45, v35, v41
	v_min_u32_e32 v35, v35, v41
	v_max_u32_e32 v41, v56, v39
	v_min_u32_e32 v39, v56, v39
	v_max_u32_e32 v56, v32, v38
	v_min_u32_e32 v32, v32, v38
	v_max_u32_e32 v50, v52, v0
	v_min_u32_e32 v0, v52, v0
	v_max_u32_e32 v52, v3, v30
	v_min_u32_e32 v3, v3, v30
	v_max_u32_e32 v30, v55, v47
	v_min_u32_e32 v47, v55, v47
	v_max_u32_e32 v55, v53, v2
	v_min_u32_e32 v2, v53, v2
	v_max_u32_e32 v53, v54, v31
	v_min_u32_e32 v31, v54, v31
	v_max_u32_e32 v54, v48, v51
	v_min_u32_e32 v48, v48, v51
	v_max_u32_e32 v51, v64, v1
	v_min_u32_e32 v1, v64, v1
	v_max_u32_e32 v64, v29, v49
	v_min_u32_e32 v29, v29, v49
	v_max_u32_e32 v38, v40, v43
	v_min_u32_e32 v40, v40, v43
; #define CE_DESC(a, b) do { const unsigned _mx = (a) > (b) ? (a) : (b), _mn = (a) > (b) ? (b) : (a); (a) = _mx; (b) = _mn; } while (0)
; __device__ __forceinline__ void merge16(unsigned (&a)[16], const unsigned (&b)[16]) {
; #pragma unroll
;     for (int i = 0; i < 16; ++i) a[i] = a[i] > b[15 - i] ? a[i] : b[15 - i];
; #pragma unroll
;     for (int stride = 8; stride > 0; stride >>= 1)
; #pragma unroll
;         for (int i = 0; i < 16; ++i) { const int j = i ^ stride; if (j > i) CE_DESC(a[i], a[j]); }
; }
; __device__ __forceinline__ void peer_tile(const Args& A, LAS unsigned char* lds, int tile) {
;     ...
;                 for (int msk = 16; msk <= 32; msk <<= 1) {
; #pragma unroll
;                     for (int i = 0; i < 16; ++i) k1[i] = (unsigned)__shfl_xor((int)k0[i], msk);
;                     merge16(k0, k1); }
	v_max_u32_e32 v43, v42, v45
	v_min_u32_e32 v42, v42, v45
	v_max_u32_e32 v45, v44, v41
	v_min_u32_e32 v41, v44, v41
	v_max_u32_e32 v44, v46, v56
	v_min_u32_e32 v46, v46, v56
	v_max_u32_e32 v56, v27, v37
	v_min_u32_e32 v27, v27, v37
	v_max_u32_e32 v37, v34, v35
	v_min_u32_e32 v34, v34, v35
	v_max_u32_e32 v35, v36, v39
	v_min_u32_e32 v36, v36, v39
	v_max_u32_e32 v39, v33, v32
	v_min_u32_e32 v32, v33, v32
	v_max_u32_e32 v49, v50, v53
	v_min_u32_e32 v50, v50, v53
	v_max_u32_e32 v53, v52, v54
	v_min_u32_e32 v52, v52, v54
	v_max_u32_e32 v54, v30, v51
	v_min_u32_e32 v30, v30, v51
	v_max_u32_e32 v51, v55, v64
	v_min_u32_e32 v55, v55, v64
	v_max_u32_e32 v64, v0, v31
	v_min_u32_e32 v0, v0, v31
	v_max_u32_e32 v31, v3, v48
	v_min_u32_e32 v3, v3, v48
	v_max_u32_e32 v48, v47, v1
	v_min_u32_e32 v1, v47, v1
	v_max_u32_e32 v47, v2, v29
	v_min_u32_e32 v2, v2, v29
	v_max_u32_e32 v33, v38, v45
	v_min_u32_e32 v38, v38, v45
	v_max_u32_e32 v45, v43, v44
	v_min_u32_e32 v43, v43, v44
	v_max_u32_e32 v44, v40, v41
	v_min_u32_e32 v40, v40, v41
	v_max_u32_e32 v41, v42, v46
	v_min_u32_e32 v42, v42, v46
	v_max_u32_e32 v46, v56, v35
	v_min_u32_e32 v35, v56, v35
	v_max_u32_e32 v56, v37, v39
	v_min_u32_e32 v37, v37, v39
	v_max_u32_e32 v39, v27, v36
	v_min_u32_e32 v27, v27, v36
	v_max_u32_e32 v36, v34, v32
	v_min_u32_e32 v32, v34, v32
	v_max_u32_e32 v29, v49, v54
	v_min_u32_e32 v49, v49, v54
	v_max_u32_e32 v54, v53, v51
	v_min_u32_e32 v51, v53, v51
	v_max_u32_e32 v53, v50, v30
	v_min_u32_e32 v30, v50, v30
	v_max_u32_e32 v50, v52, v55
	v_min_u32_e32 v52, v52, v55
	v_max_u32_e32 v55, v64, v48
	v_min_u32_e32 v48, v64, v48
	v_max_u32_e32 v64, v31, v47
	v_min_u32_e32 v31, v31, v47
	v_max_u32_e32 v47, v0, v1
	v_min_u32_e32 v0, v0, v1
	v_max_u32_e32 v1, v3, v2
	v_min_u32_e32 v2, v3, v2
	v_min_u32_e32 v34, v33, v45
	v_min_u32_e32 v57, v38, v43
	v_min_u32_e32 v58, v44, v41
	v_min_u32_e32 v59, v40, v42
	v_min_u32_e32 v60, v46, v56
	v_min_u32_e32 v61, v35, v37
	v_min_u32_e32 v62, v39, v36
	v_min_u32_e32 v63, v27, v32
	v_min_u32_e32 v3, v29, v54
	v_min_u32_e32 v65, v49, v51
	v_min_u32_e32 v66, v53, v50
	v_min_u32_e32 v67, v30, v52
	v_min_u32_e32 v68, v55, v64
	v_min_u32_e32 v69, v48, v31
	v_min_u32_e32 v70, v47, v1
	v_min_u32_e32 v71, v0, v2
	v_max3_u32 v33, v33, v45, v71
	v_max3_u32 v0, v34, v0, v2
	v_max3_u32 v2, v38, v43, v70
	v_max3_u32 v1, v57, v47, v1
	v_max3_u32 v34, v44, v41, v69
	v_max3_u32 v31, v58, v48, v31
	v_max3_u32 v38, v40, v42, v68
	v_max3_u32 v40, v59, v55, v64
	v_max3_u32 v41, v46, v56, v67
	v_max3_u32 v30, v60, v30, v52
	v_max3_u32 v35, v35, v37, v66
	v_max3_u32 v37, v61, v53, v50
	v_max3_u32 v36, v39, v36, v65
	v_max3_u32 v39, v62, v49, v51
	v_max3_u32 v3, v27, v32, v3
	v_max3_u32 v27, v63, v29, v54
	v_max_u32_e32 v29, v33, v41
	v_min_u32_e32 v32, v33, v41
	v_max_u32_e32 v33, v0, v30
	v_min_u32_e32 v0, v0, v30
	v_max_u32_e32 v30, v2, v35
	v_min_u32_e32 v2, v2, v35
	v_max_u32_e32 v35, v1, v37
	v_min_u32_e32 v1, v1, v37
	v_max_u32_e32 v37, v34, v36
	v_min_u32_e32 v34, v34, v36
	v_max_u32_e32 v36, v31, v39
	v_min_u32_e32 v31, v31, v39
	v_max_u32_e32 v39, v38, v3
	v_min_u32_e32 v3, v38, v3
	v_max_u32_e32 v38, v40, v27
	v_min_u32_e32 v27, v40, v27
	v_max_u32_e32 v40, v29, v37
	v_min_u32_e32 v29, v29, v37
	v_max_u32_e32 v37, v33, v36
	v_min_u32_e32 v33, v33, v36
	v_max_u32_e32 v36, v30, v39
	v_min_u32_e32 v30, v30, v39
	v_max_u32_e32 v39, v35, v38
	v_min_u32_e32 v35, v35, v38
	v_max_u32_e32 v38, v32, v34
	v_min_u32_e32 v32, v32, v34
	v_max_u32_e32 v34, v0, v31
	v_min_u32_e32 v0, v0, v31
	v_max_u32_e32 v31, v2, v3
	v_min_u32_e32 v2, v2, v3
	v_max_u32_e32 v3, v1, v27
	v_min_u32_e32 v1, v1, v27
	v_max_u32_e32 v27, v40, v36
	v_min_u32_e32 v36, v40, v36
	v_max_u32_e32 v40, v37, v39
	v_min_u32_e32 v37, v37, v39
	v_max_u32_e32 v39, v29, v30
	v_min_u32_e32 v29, v29, v30
	v_max_u32_e32 v30, v33, v35
	v_min_u32_e32 v33, v33, v35
	v_max_u32_e32 v35, v38, v31
	v_min_u32_e32 v31, v38, v31
	v_max_u32_e32 v38, v34, v3
	v_min_u32_e32 v3, v34, v3
	v_max_u32_e32 v34, v32, v2
	v_min_u32_e32 v2, v32, v2
	v_max_u32_e32 v32, v0, v1
	v_min_u32_e32 v0, v0, v1
	v_cmp_lt_i32_e32 vcc, v217, v216
	v_max_u32_e32 v41, v36, v37
	v_min_u32_e32 v36, v36, v37
	v_max_u32_e32 v37, v39, v30
	v_min_u32_e32 v30, v39, v30
	v_max_u32_e32 v39, v29, v33
	v_min_u32_e32 v29, v29, v33
	v_max_u32_e32 v33, v35, v38
	v_min_u32_e32 v35, v35, v38
	v_max_u32_e32 v38, v31, v3
	v_min_u32_e32 v3, v31, v3
	v_max_u32_e32 v31, v34, v32
	v_min_u32_e32 v32, v34, v32
	v_max_u32_e32 v34, v2, v0
	v_min_u32_e32 v0, v2, v0
	v_cndmask_b32_e32 v2, v215, v217, vcc
	v_max_u32_e32 v1, v27, v40
	v_min_u32_e32 v40, v27, v40
	v_lshlrev_b32_e32 v27, 2, v2
	ds_bpermute_b32 v2, v27, v1
	ds_bpermute_b32 v42, v27, v40
	ds_bpermute_b32 v43, v27, v41
	ds_bpermute_b32 v44, v27, v36
	ds_bpermute_b32 v45, v27, v37
	ds_bpermute_b32 v46, v27, v30
	ds_bpermute_b32 v47, v27, v39
	ds_bpermute_b32 v48, v27, v29
	ds_bpermute_b32 v49, v27, v33
	ds_bpermute_b32 v50, v27, v35
	ds_bpermute_b32 v51, v27, v38
	ds_bpermute_b32 v52, v27, v0
	ds_bpermute_b32 v53, v27, v34
	ds_bpermute_b32 v54, v27, v32
	ds_bpermute_b32 v55, v27, v31
	ds_bpermute_b32 v56, v27, v3
	s_waitcnt lgkmcnt(4)
	v_max_u32_e32 v1, v1, v52
	s_waitcnt lgkmcnt(3)
	v_max_u32_e32 v40, v40, v53
	s_waitcnt lgkmcnt(2)
	v_max_u32_e32 v41, v41, v54
	s_waitcnt lgkmcnt(1)
	v_max_u32_e32 v36, v36, v55
	s_waitcnt lgkmcnt(0)
; __device__ __forceinline__ void peer_tile(const Args& A, LAS unsigned char* lds, int tile) {
;     ...
;                 { const bf16_t* sp = QRY + m * 2048 + hp * 128 + 32 * g;
;                   const u32x4 s0 = *(const u32x4*)sp, s1 = *(const u32x4*)(sp + 8), s2 = *(const u32x4*)(sp + 16), s3 = *(const u32x4*)(sp + 24);
;     ...
;                 for (int msk = 16; msk <= 32; msk <<= 1) {
; #pragma unroll
;                     for (int i = 0; i < 16; ++i) k1[i] = (unsigned)__shfl_xor((int)k0[i], msk);
;                     merge16(k0, k1); }
	v_max_u32_e32 v37, v37, v56
	v_max_u32_e32 v30, v30, v51
	v_max_u32_e32 v39, v39, v50
	v_max_u32_e32 v29, v29, v49
	v_max_u32_e32 v33, v33, v48
	v_max_u32_e32 v35, v35, v47
	v_max_u32_e32 v38, v38, v46
	v_max_u32_e32 v3, v3, v45
	v_max_u32_e32 v31, v31, v44
	v_max_u32_e32 v32, v32, v43
	v_max_u32_e32 v34, v34, v42
	v_max_u32_e32 v0, v0, v2
	v_max_u32_e32 v2, v1, v33
	v_min_u32_e32 v1, v1, v33
	v_max_u32_e32 v33, v40, v35
	v_min_u32_e32 v35, v40, v35
	v_max_u32_e32 v40, v41, v38
	v_min_u32_e32 v38, v41, v38
	v_max_u32_e32 v41, v36, v3
	v_min_u32_e32 v3, v36, v3
	v_max_u32_e32 v36, v37, v31
	v_min_u32_e32 v31, v37, v31
	v_max_u32_e32 v37, v30, v32
	v_min_u32_e32 v30, v30, v32
	v_max_u32_e32 v32, v39, v34
	v_min_u32_e32 v34, v39, v34
	v_max_u32_e32 v39, v29, v0
	v_min_u32_e32 v0, v29, v0
	v_max_u32_e32 v29, v2, v36
	v_min_u32_e32 v2, v2, v36
	v_max_u32_e32 v36, v33, v37
	v_min_u32_e32 v33, v33, v37
	v_max_u32_e32 v37, v40, v32
	v_min_u32_e32 v32, v40, v32
	v_max_u32_e32 v40, v41, v39
	v_min_u32_e32 v39, v41, v39
	v_max_u32_e32 v41, v1, v31
	v_min_u32_e32 v1, v1, v31
	v_max_u32_e32 v31, v35, v30
	v_min_u32_e32 v30, v35, v30
	v_max_u32_e32 v35, v38, v34
	v_min_u32_e32 v34, v38, v34
	v_max_u32_e32 v38, v3, v0
	v_min_u32_e32 v0, v3, v0
	v_max_u32_e32 v3, v29, v37
	v_min_u32_e32 v29, v29, v37
	v_max_u32_e32 v37, v36, v40
	v_min_u32_e32 v36, v36, v40
	v_max_u32_e32 v40, v2, v32
	v_min_u32_e32 v2, v2, v32
	v_max_u32_e32 v32, v33, v39
	v_min_u32_e32 v33, v33, v39
	v_max_u32_e32 v39, v41, v35
	v_min_u32_e32 v35, v41, v35
	v_max_u32_e32 v41, v31, v38
	v_min_u32_e32 v31, v31, v38
	v_max_u32_e32 v38, v1, v34
	v_min_u32_e32 v1, v1, v34
	v_max_u32_e32 v34, v30, v0
	v_min_u32_e32 v0, v30, v0
	v_cmp_lt_i32_e32 vcc, v218, v216
	v_max_u32_e32 v42, v40, v32
	v_min_u32_e32 v32, v40, v32
	v_max_u32_e32 v40, v2, v33
	v_min_u32_e32 v2, v2, v33
	v_max_u32_e32 v33, v39, v41
	v_min_u32_e32 v39, v39, v41
	v_max_u32_e32 v41, v35, v31
	v_min_u32_e32 v31, v35, v31
	v_max_u32_e32 v35, v38, v34
	v_min_u32_e32 v34, v38, v34
	v_max_u32_e32 v38, v1, v0
	v_min_u32_e32 v0, v1, v0
	v_cndmask_b32_e32 v1, v215, v218, vcc
	v_max_u32_e32 v30, v3, v37
	v_min_u32_e32 v3, v3, v37
	v_max_u32_e32 v37, v29, v36
	v_min_u32_e32 v36, v29, v36
	v_lshlrev_b32_e32 v29, 2, v1
	ds_bpermute_b32 v46, v29, v0
	ds_bpermute_b32 v1, v29, v30
	ds_bpermute_b32 v43, v29, v3
	ds_bpermute_b32 v44, v29, v37
	ds_bpermute_b32 v45, v29, v36
	s_waitcnt lgkmcnt(4)
	v_max_u32_e32 v30, v30, v46
	global_load_dwordx4 v[46:49], v[4:5], off offset:272
	global_load_dwordx4 v[50:53], v[4:5], off offset:256
	ds_bpermute_b32 v54, v29, v42
	ds_bpermute_b32 v55, v29, v32
	ds_bpermute_b32 v56, v29, v40
	ds_bpermute_b32 v57, v29, v2
	ds_bpermute_b32 v58, v29, v33
	ds_bpermute_b32 v59, v29, v39
	ds_bpermute_b32 v60, v29, v41
	ds_bpermute_b32 v61, v29, v31
	ds_bpermute_b32 v62, v29, v35
	ds_bpermute_b32 v63, v29, v38
	ds_bpermute_b32 v64, v29, v34
	s_waitcnt lgkmcnt(4)
	v_max_u32_e32 v32, v32, v60
	s_waitcnt lgkmcnt(3)
	v_max_u32_e32 v42, v42, v61
	s_waitcnt lgkmcnt(2)
	v_max_u32_e32 v36, v36, v62
	s_waitcnt lgkmcnt(1)
	v_max_u32_e32 v3, v3, v63
	s_waitcnt lgkmcnt(0)
	v_max_u32_e32 v37, v37, v64
	v_max_u32_e32 v40, v40, v59
	v_max_u32_e32 v2, v2, v58
	v_max_u32_e32 v33, v33, v57
	v_max_u32_e32 v39, v39, v56
	v_max_u32_e32 v41, v41, v55
	v_max_u32_e32 v31, v31, v54
	v_max_u32_e32 v35, v35, v45
	v_max_u32_e32 v34, v34, v44
	v_max_u32_e32 v38, v38, v43
	v_max_u32_e32 v0, v0, v1
	v_max_u32_e32 v1, v30, v33
	v_min_u32_e32 v30, v30, v33
	v_max_u32_e32 v33, v3, v39
	v_min_u32_e32 v3, v3, v39
	v_max_u32_e32 v39, v37, v41
	v_min_u32_e32 v37, v37, v41
	v_max_u32_e32 v41, v36, v31
	v_min_u32_e32 v31, v36, v31
	v_max_u32_e32 v36, v42, v35
	v_min_u32_e32 v35, v42, v35
	v_max_u32_e32 v42, v32, v34
	v_min_u32_e32 v32, v32, v34
	v_max_u32_e32 v34, v40, v38
	v_min_u32_e32 v38, v40, v38
	v_max_u32_e32 v40, v2, v0
	v_min_u32_e32 v0, v2, v0
	v_max_u32_e32 v2, v1, v36
	v_min_u32_e32 v1, v1, v36
	v_max_u32_e32 v36, v33, v42
	v_min_u32_e32 v33, v33, v42
	v_max_u32_e32 v42, v39, v34
	v_min_u32_e32 v34, v39, v34
	v_max_u32_e32 v39, v41, v40
	v_min_u32_e32 v40, v41, v40
	v_max_u32_e32 v41, v30, v35
	v_min_u32_e32 v30, v30, v35
	v_max_u32_e32 v35, v3, v32
	v_min_u32_e32 v3, v3, v32
	v_max_u32_e32 v32, v37, v38
	v_min_u32_e32 v37, v37, v38
	v_max_u32_e32 v38, v31, v0
	v_min_u32_e32 v0, v31, v0
	v_max_u32_e32 v31, v2, v42
	v_min_u32_e32 v2, v2, v42
	v_max_u32_e32 v42, v36, v39
	v_min_u32_e32 v36, v36, v39
	v_max_u32_e32 v39, v1, v34
	v_min_u32_e32 v1, v1, v34
	v_max_u32_e32 v34, v33, v40
	v_min_u32_e32 v33, v33, v40
	v_max_u32_e32 v54, v41, v32
	v_min_u32_e32 v32, v41, v32
	v_max_u32_e32 v55, v35, v38
	v_min_u32_e32 v56, v35, v38
	v_max_u32_e32 v57, v30, v37
	v_min_u32_e32 v30, v30, v37
	v_max_u32_e32 v58, v3, v0
	v_min_u32_e32 v0, v3, v0
	v_max_u32_e32 v45, v31, v42
	v_min_u32_e32 v44, v31, v42
	v_max_u32_e32 v43, v2, v36
	v_min_u32_e32 v42, v2, v36
	v_max_u32_e32 v41, v39, v34
	v_min_u32_e32 v40, v39, v34
	v_max_u32_e32 v39, v1, v33
	v_min_u32_e32 v38, v1, v33
	v_max_u32_e32 v37, v54, v55
	v_min_u32_e32 v36, v54, v55
	v_max_u32_e32 v35, v32, v56
	v_min_u32_e32 v34, v32, v56
	v_max_u32_e32 v33, v57, v58
	v_min_u32_e32 v32, v57, v58
	v_max_u32_e32 v31, v30, v0
	v_min_u32_e32 v30, v30, v0
	global_load_dwordx4 v[0:3], v[4:5], off offset:304
	global_load_dwordx4 v[54:57], v[4:5], off offset:288
	s_waitcnt vmcnt(2)
; __device__ __forceinline__ unsigned f2key(float f) { const unsigned u = __float_as_uint(f); return (u & 0x80000000u) ? ~u : (u | 0x80000000u); }
; __device__ __forceinline__ void peer_tile(const Args& A, LAS unsigned char* lds, int tile) {
;     ...
;                   for (int i = 0; i < 16; ++i) {
;                       const float lo = (float)__builtin_bit_cast(_Float16, (unsigned short)(sw[i] & 0xffffu)), hi = (float)__builtin_bit_cast(_Float16, (unsigned short)(sw[i] >> 16));
;                       const unsigned klo = (f2key(lo) & ~127u) | (unsigned)(127 - (32 * g + 2 * i)), khi = (f2key(hi) & ~127u) | (unsigned)(127 - (32 * g + 2 * i + 1));
;                       if (i < 8) { k0[2 * i] = klo; k0[2 * i + 1] = khi; } else { k1[2 * (i - 8)] = klo; k1[2 * (i - 8) + 1] = khi; } } }
	v_cvt_f32_f16_sdwa v58, v50 dst_sel:DWORD dst_unused:UNUSED_PAD src0_sel:WORD_1
	v_cvt_f32_f16_e32 v50, v50
	v_not_b32_e32 v59, v58
	v_or_b32_e32 v60, 0x80000000, v58
	v_cmp_gt_i32_e32 vcc, 0, v58
	s_nop 1
	v_cndmask_b32_e32 v58, v60, v59, vcc
	v_not_b32_e32 v59, v50
	v_or_b32_e32 v60, 0x80000000, v50
	v_cmp_gt_i32_e32 vcc, 0, v50
	v_and_b32_e32 v58, 0xffffff80, v58
	v_sub_u32_e32 v58, v58, v15
	v_cndmask_b32_e32 v50, v60, v59, vcc
	v_cvt_f32_f16_sdwa v59, v51 dst_sel:DWORD dst_unused:UNUSED_PAD src0_sel:WORD_1
	v_cvt_f32_f16_e32 v51, v51
	v_and_b32_e32 v50, 0xffffff80, v50
	v_sub_u32_e32 v50, v50, v15
	v_not_b32_e32 v60, v59
	v_or_b32_e32 v61, 0x80000000, v59
	v_cmp_gt_i32_e32 vcc, 0, v59
	v_add_u32_e32 v58, 0x7e, v58
	v_add_u32_e32 v50, 0x7f, v50
	v_cndmask_b32_e32 v59, v61, v60, vcc
	v_not_b32_e32 v60, v51
	v_or_b32_e32 v61, 0x80000000, v51
	v_cmp_gt_i32_e32 vcc, 0, v51
	v_and_b32_e32 v59, 0xffffff80, v59
	v_sub_u32_e32 v59, v59, v14
	v_cndmask_b32_e32 v51, v61, v60, vcc
	v_cvt_f32_f16_sdwa v60, v52 dst_sel:DWORD dst_unused:UNUSED_PAD src0_sel:WORD_1
	v_cvt_f32_f16_e32 v52, v52
	v_and_b32_e32 v51, 0xffffff80, v51
	v_sub_u32_e32 v51, v51, v14
	v_not_b32_e32 v61, v60
	v_or_b32_e32 v62, 0x80000000, v60
	v_cmp_gt_i32_e32 vcc, 0, v60
	v_add_u32_e32 v59, 0x7e, v59
	v_add_u32_e32 v51, 0x7f, v51
	v_cndmask_b32_e32 v60, v62, v61, vcc
	v_not_b32_e32 v61, v52
	v_or_b32_e32 v62, 0x80000000, v52
	v_cmp_gt_i32_e32 vcc, 0, v52
	v_and_b32_e32 v60, 0xffffff80, v60
	v_sub_u32_e32 v60, v60, v12
	v_cndmask_b32_e32 v52, v62, v61, vcc
	v_cvt_f32_f16_sdwa v61, v53 dst_sel:DWORD dst_unused:UNUSED_PAD src0_sel:WORD_1
	v_cvt_f32_f16_e32 v53, v53
	v_and_b32_e32 v52, 0xffffff80, v52
	v_sub_u32_e32 v52, v52, v12
	v_not_b32_e32 v62, v61
	v_or_b32_e32 v63, 0x80000000, v61
	v_cmp_gt_i32_e32 vcc, 0, v61
	v_add_u32_e32 v60, 0x7e, v60
	v_add_u32_e32 v52, 0x7f, v52
	v_cndmask_b32_e32 v61, v63, v62, vcc
	v_not_b32_e32 v62, v53
	v_or_b32_e32 v63, 0x80000000, v53
	v_cmp_gt_i32_e32 vcc, 0, v53
	v_and_b32_e32 v61, 0xffffff80, v61
	v_sub_u32_e32 v61, v61, v10
	v_cndmask_b32_e32 v53, v63, v62, vcc
	v_cvt_f32_f16_sdwa v62, v46 dst_sel:DWORD dst_unused:UNUSED_PAD src0_sel:WORD_1
	v_cvt_f32_f16_e32 v46, v46
	v_and_b32_e32 v53, 0xffffff80, v53
	v_sub_u32_e32 v53, v53, v10
	v_not_b32_e32 v63, v62
	v_or_b32_e32 v64, 0x80000000, v62
	v_cmp_gt_i32_e32 vcc, 0, v62
	v_add_u32_e32 v61, 0x7e, v61
	v_add_u32_e32 v53, 0x7f, v53
	v_cndmask_b32_e32 v62, v64, v63, vcc
	v_not_b32_e32 v63, v46
	v_or_b32_e32 v64, 0x80000000, v46
	v_cmp_gt_i32_e32 vcc, 0, v46
	v_and_b32_e32 v62, 0xffffff80, v62
	v_sub_u32_e32 v62, v62, v8
	v_cndmask_b32_e32 v46, v64, v63, vcc
	v_cvt_f32_f16_sdwa v63, v47 dst_sel:DWORD dst_unused:UNUSED_PAD src0_sel:WORD_1
	v_cvt_f32_f16_e32 v47, v47
	v_and_b32_e32 v46, 0xffffff80, v46
	v_sub_u32_e32 v46, v46, v8
	v_not_b32_e32 v64, v63
	v_or_b32_e32 v65, 0x80000000, v63
	v_cmp_gt_i32_e32 vcc, 0, v63
	v_add_u32_e32 v62, 0x7e, v62
	v_add_u32_e32 v46, 0x7f, v46
	v_cndmask_b32_e32 v63, v65, v64, vcc
	v_not_b32_e32 v64, v47
	v_or_b32_e32 v65, 0x80000000, v47
	v_cmp_gt_i32_e32 vcc, 0, v47
	v_and_b32_e32 v63, 0xffffff80, v63
	v_sub_u32_e32 v63, v63, v16
	v_cndmask_b32_e32 v47, v65, v64, vcc
	v_cvt_f32_f16_sdwa v64, v48 dst_sel:DWORD dst_unused:UNUSED_PAD src0_sel:WORD_1
	v_cvt_f32_f16_e32 v48, v48
	v_and_b32_e32 v47, 0xffffff80, v47
	v_sub_u32_e32 v47, v47, v16
	v_not_b32_e32 v65, v64
	v_or_b32_e32 v66, 0x80000000, v64
	v_cmp_gt_i32_e32 vcc, 0, v64
	v_add_u32_e32 v63, 0x7e, v63
	v_add_u32_e32 v47, 0x7f, v47
	v_cndmask_b32_e32 v64, v66, v65, vcc
	v_not_b32_e32 v65, v48
	v_or_b32_e32 v66, 0x80000000, v48
	v_cmp_gt_i32_e32 vcc, 0, v48
	v_and_b32_e32 v64, 0xffffff80, v64
	v_sub_u32_e32 v64, v64, v17
	v_cndmask_b32_e32 v48, v66, v65, vcc
	v_cvt_f32_f16_sdwa v65, v49 dst_sel:DWORD dst_unused:UNUSED_PAD src0_sel:WORD_1
	v_cvt_f32_f16_e32 v49, v49
	v_and_b32_e32 v48, 0xffffff80, v48
	v_sub_u32_e32 v48, v48, v17
	v_not_b32_e32 v66, v65
	v_or_b32_e32 v67, 0x80000000, v65
	v_cmp_gt_i32_e32 vcc, 0, v65
	v_add_u32_e32 v64, 0x7e, v64
	v_add_u32_e32 v48, 0x7f, v48
	v_cndmask_b32_e32 v65, v67, v66, vcc
	v_not_b32_e32 v66, v49
	v_or_b32_e32 v67, 0x80000000, v49
	v_cmp_gt_i32_e32 vcc, 0, v49
	v_and_b32_e32 v65, 0xffffff80, v65
	v_sub_u32_e32 v65, v65, v18
	v_cndmask_b32_e32 v49, v67, v66, vcc
	s_waitcnt vmcnt(0)
; __device__ __forceinline__ unsigned f2key(float f) { const unsigned u = __float_as_uint(f); return (u & 0x80000000u) ? ~u : (u | 0x80000000u); }
; __device__ __forceinline__ void peer_tile(const Args& A, LAS unsigned char* lds, int tile) {
;     ...
;                   for (int i = 0; i < 16; ++i) {
;                       const float lo = (float)__builtin_bit_cast(_Float16, (unsigned short)(sw[i] & 0xffffu)), hi = (float)__builtin_bit_cast(_Float16, (unsigned short)(sw[i] >> 16));
;                       const unsigned klo = (f2key(lo) & ~127u) | (unsigned)(127 - (32 * g + 2 * i)), khi = (f2key(hi) & ~127u) | (unsigned)(127 - (32 * g + 2 * i + 1));
;                       if (i < 8) { k0[2 * i] = klo; k0[2 * i + 1] = khi; } else { k1[2 * (i - 8)] = klo; k1[2 * (i - 8) + 1] = khi; } } }
;                 sort16_desc(k0); sort16_desc(k1); merge16(k0, k1);
	v_cvt_f32_f16_sdwa v66, v54 dst_sel:DWORD dst_unused:UNUSED_PAD src0_sel:WORD_1
	v_cvt_f32_f16_e32 v54, v54
	v_and_b32_e32 v49, 0xffffff80, v49
	v_sub_u32_e32 v49, v49, v18
	v_not_b32_e32 v67, v66
	v_or_b32_e32 v68, 0x80000000, v66
	v_cmp_gt_i32_e32 vcc, 0, v66
	v_add_u32_e32 v65, 0x7e, v65
	v_add_u32_e32 v49, 0x7f, v49
	v_cndmask_b32_e32 v66, v68, v67, vcc
	v_not_b32_e32 v67, v54
	v_or_b32_e32 v68, 0x80000000, v54
	v_cmp_gt_i32_e32 vcc, 0, v54
	v_and_b32_e32 v66, 0xffffff80, v66
	v_sub_u32_e32 v66, v66, v20
	v_cndmask_b32_e32 v54, v68, v67, vcc
	v_cvt_f32_f16_sdwa v67, v55 dst_sel:DWORD dst_unused:UNUSED_PAD src0_sel:WORD_1
	v_cvt_f32_f16_e32 v55, v55
	v_and_b32_e32 v54, 0xffffff80, v54
	v_sub_u32_e32 v54, v54, v20
	v_not_b32_e32 v68, v67
	v_or_b32_e32 v69, 0x80000000, v67
	v_cmp_gt_i32_e32 vcc, 0, v67
	v_add_u32_e32 v66, 0x7e, v66
	v_add_u32_e32 v54, 0x7f, v54
	v_cndmask_b32_e32 v67, v69, v68, vcc
	v_not_b32_e32 v68, v55
	v_or_b32_e32 v69, 0x80000000, v55
	v_cmp_gt_i32_e32 vcc, 0, v55
	v_and_b32_e32 v67, 0xffffff80, v67
	v_sub_u32_e32 v67, v67, v21
	v_cndmask_b32_e32 v55, v69, v68, vcc
	v_cvt_f32_f16_sdwa v68, v56 dst_sel:DWORD dst_unused:UNUSED_PAD src0_sel:WORD_1
	v_cvt_f32_f16_e32 v56, v56
	v_and_b32_e32 v55, 0xffffff80, v55
	v_sub_u32_e32 v55, v55, v21
	v_not_b32_e32 v69, v68
	v_or_b32_e32 v70, 0x80000000, v68
	v_cmp_gt_i32_e32 vcc, 0, v68
	v_add_u32_e32 v67, 0x7e, v67
	v_add_u32_e32 v55, 0x7f, v55
	v_cndmask_b32_e32 v68, v70, v69, vcc
	v_not_b32_e32 v69, v56
	v_or_b32_e32 v70, 0x80000000, v56
	v_cmp_gt_i32_e32 vcc, 0, v56
	v_and_b32_e32 v68, 0xffffff80, v68
	v_sub_u32_e32 v68, v68, v22
	v_cndmask_b32_e32 v56, v70, v69, vcc
	v_cvt_f32_f16_sdwa v69, v57 dst_sel:DWORD dst_unused:UNUSED_PAD src0_sel:WORD_1
	v_cvt_f32_f16_e32 v57, v57
	v_and_b32_e32 v56, 0xffffff80, v56
	v_sub_u32_e32 v56, v56, v22
	v_not_b32_e32 v70, v69
	v_or_b32_e32 v71, 0x80000000, v69
	v_cmp_gt_i32_e32 vcc, 0, v69
	v_add_u32_e32 v68, 0x7e, v68
	v_add_u32_e32 v56, 0x7f, v56
	v_cndmask_b32_e32 v69, v71, v70, vcc
	v_not_b32_e32 v70, v57
	v_or_b32_e32 v71, 0x80000000, v57
	v_cmp_gt_i32_e32 vcc, 0, v57
	v_and_b32_e32 v69, 0xffffff80, v69
	v_sub_u32_e32 v69, v69, v23
	v_cndmask_b32_e32 v57, v71, v70, vcc
	v_cvt_f32_f16_sdwa v70, v0 dst_sel:DWORD dst_unused:UNUSED_PAD src0_sel:WORD_1
	v_cvt_f32_f16_e32 v0, v0
	v_and_b32_e32 v57, 0xffffff80, v57
	v_sub_u32_e32 v57, v57, v23
	v_not_b32_e32 v71, v70
	v_or_b32_e32 v72, 0x80000000, v70
	v_cmp_gt_i32_e32 vcc, 0, v70
	v_add_u32_e32 v69, 0x7e, v69
	v_add_u32_e32 v57, 0x7f, v57
	v_cndmask_b32_e32 v70, v72, v71, vcc
	v_not_b32_e32 v71, v0
	v_or_b32_e32 v72, 0x80000000, v0
	v_cmp_gt_i32_e32 vcc, 0, v0
	v_and_b32_e32 v70, 0xffffff80, v70
	v_sub_u32_e32 v70, v70, v24
	v_cndmask_b32_e32 v0, v72, v71, vcc
	v_cvt_f32_f16_sdwa v71, v1 dst_sel:DWORD dst_unused:UNUSED_PAD src0_sel:WORD_1
	v_cvt_f32_f16_e32 v1, v1
	v_and_b32_e32 v0, 0xffffff80, v0
	v_sub_u32_e32 v0, v0, v24
	v_not_b32_e32 v72, v71
	v_or_b32_e32 v73, 0x80000000, v71
	v_cmp_gt_i32_e32 vcc, 0, v71
	v_add_u32_e32 v70, 0x7e, v70
	v_add_u32_e32 v0, 0x7f, v0
	v_cndmask_b32_e32 v71, v73, v72, vcc
	v_not_b32_e32 v72, v1
	v_or_b32_e32 v73, 0x80000000, v1
	v_cmp_gt_i32_e32 vcc, 0, v1
	v_and_b32_e32 v71, 0xffffff80, v71
	v_sub_u32_e32 v71, v71, v25
	v_cndmask_b32_e32 v1, v73, v72, vcc
	v_cvt_f32_f16_sdwa v72, v2 dst_sel:DWORD dst_unused:UNUSED_PAD src0_sel:WORD_1
	v_cvt_f32_f16_e32 v2, v2
	v_and_b32_e32 v1, 0xffffff80, v1
	v_sub_u32_e32 v1, v1, v25
	v_not_b32_e32 v73, v72
	v_or_b32_e32 v74, 0x80000000, v72
	v_cmp_gt_i32_e32 vcc, 0, v72
	v_add_u32_e32 v71, 0x7e, v71
	v_add_u32_e32 v1, 0x7f, v1
	v_cndmask_b32_e32 v72, v74, v73, vcc
	v_not_b32_e32 v73, v2
	v_or_b32_e32 v74, 0x80000000, v2
	v_cmp_gt_i32_e32 vcc, 0, v2
	v_and_b32_e32 v72, 0xffffff80, v72
	v_sub_u32_e32 v72, v72, v26
	v_cndmask_b32_e32 v2, v74, v73, vcc
	v_cvt_f32_f16_sdwa v73, v3 dst_sel:DWORD dst_unused:UNUSED_PAD src0_sel:WORD_1
	v_cvt_f32_f16_e32 v3, v3
	v_and_b32_e32 v2, 0xffffff80, v2
	v_sub_u32_e32 v2, v2, v26
	v_not_b32_e32 v74, v73
	v_or_b32_e32 v75, 0x80000000, v73
	v_cmp_gt_i32_e32 vcc, 0, v73
	v_add_u32_e32 v72, 0x7e, v72
	v_add_u32_e32 v2, 0x7f, v2
	v_cndmask_b32_e32 v73, v75, v74, vcc
	v_not_b32_e32 v74, v3
	v_or_b32_e32 v75, 0x80000000, v3
	v_cmp_gt_i32_e32 vcc, 0, v3
	v_and_b32_e32 v73, 0xffffff80, v73
	v_sub_u32_e32 v73, v73, v28
	v_cndmask_b32_e32 v3, v75, v74, vcc
	v_and_b32_e32 v3, 0xffffff80, v3
	v_sub_u32_e32 v3, v3, v28
	v_add_u32_e32 v73, 0x7e, v73
	v_add_u32_e32 v3, 0x7f, v3
	v_max_u32_e32 v74, v50, v58
	v_min_u32_e32 v50, v50, v58
	v_max_u32_e32 v58, v59, v51
	v_min_u32_e32 v51, v59, v51
	v_max_u32_e32 v59, v52, v60
	v_min_u32_e32 v52, v52, v60
	v_max_u32_e32 v60, v61, v53
	v_min_u32_e32 v53, v61, v53
	v_max_u32_e32 v61, v46, v62
	v_min_u32_e32 v46, v46, v62
	v_max_u32_e32 v62, v63, v47
	v_min_u32_e32 v47, v63, v47
	v_max_u32_e32 v63, v48, v64
	v_min_u32_e32 v48, v48, v64
	v_max_u32_e32 v64, v65, v49
	v_min_u32_e32 v49, v65, v49
	v_max_u32_e32 v82, v54, v66
	v_min_u32_e32 v54, v54, v66
	v_max_u32_e32 v66, v67, v55
	v_min_u32_e32 v55, v67, v55
	v_max_u32_e32 v67, v56, v68
	v_min_u32_e32 v56, v56, v68
	v_max_u32_e32 v68, v69, v57
	v_min_u32_e32 v57, v69, v57
	v_max_u32_e32 v69, v0, v70
	v_min_u32_e32 v0, v0, v70
	v_max_u32_e32 v70, v71, v1
	v_min_u32_e32 v1, v71, v1
	v_max_u32_e32 v71, v2, v72
	v_min_u32_e32 v2, v2, v72
	v_max_u32_e32 v72, v73, v3
	v_min_u32_e32 v3, v73, v3
	v_max_u32_e32 v65, v74, v51
	v_min_u32_e32 v51, v74, v51
	v_max_u32_e32 v74, v50, v58
	v_min_u32_e32 v50, v50, v58
	v_max_u32_e32 v58, v53, v59
	v_min_u32_e32 v53, v53, v59
	v_max_u32_e32 v59, v60, v52
	v_min_u32_e32 v52, v60, v52
; #define CE_DESC(a, b) do { const unsigned _mx = (a) > (b) ? (a) : (b), _mn = (a) > (b) ? (b) : (a); (a) = _mx; (b) = _mn; } while (0)
; __device__ __forceinline__ void sort16_desc(unsigned (&k)[16]) {
; #pragma unroll
;     for (int size = 2; size <= 16; size <<= 1)
; #pragma unroll
;         for (int stride = size >> 1; stride > 0; stride >>= 1)
; #pragma unroll
;             for (int i = 0; i < 16; ++i) { const int j = i ^ stride;
;                 if (j > i) { if ((i & size) == 0) CE_DESC(k[i], k[j]); else CE_DESC(k[j], k[i]); } }
; }
	v_max_u32_e32 v60, v61, v47
	v_min_u32_e32 v47, v61, v47
	v_max_u32_e32 v61, v46, v62
	v_min_u32_e32 v46, v46, v62
	v_max_u32_e32 v62, v49, v63
	v_min_u32_e32 v49, v49, v63
	v_max_u32_e32 v63, v64, v48
	v_min_u32_e32 v48, v64, v48
	v_max_u32_e32 v73, v82, v55
	v_min_u32_e32 v55, v82, v55
	v_max_u32_e32 v82, v54, v66
	v_min_u32_e32 v54, v54, v66
	v_max_u32_e32 v66, v57, v67
	v_min_u32_e32 v57, v57, v67
	v_max_u32_e32 v67, v68, v56
	v_min_u32_e32 v56, v68, v56
	v_max_u32_e32 v68, v69, v1
	v_min_u32_e32 v1, v69, v1
	v_max_u32_e32 v69, v0, v70
	v_min_u32_e32 v0, v0, v70
	v_max_u32_e32 v70, v3, v71
	v_min_u32_e32 v3, v3, v71
	v_max_u32_e32 v71, v72, v2
	v_min_u32_e32 v2, v72, v2
	v_max_u32_e32 v64, v65, v74
	v_min_u32_e32 v65, v65, v74
	v_max_u32_e32 v74, v51, v50
	v_min_u32_e32 v50, v51, v50
	v_max_u32_e32 v51, v52, v53
	v_min_u32_e32 v52, v52, v53
	v_max_u32_e32 v53, v59, v58
	v_min_u32_e32 v58, v59, v58
	v_max_u32_e32 v59, v60, v61
	v_min_u32_e32 v60, v60, v61
	v_max_u32_e32 v61, v47, v46
	v_min_u32_e32 v46, v47, v46
	v_max_u32_e32 v47, v48, v49
	v_min_u32_e32 v48, v48, v49
	v_max_u32_e32 v49, v63, v62
	v_min_u32_e32 v62, v63, v62
	v_max_u32_e32 v72, v73, v82
	v_min_u32_e32 v73, v73, v82
	v_max_u32_e32 v82, v55, v54
	v_min_u32_e32 v54, v55, v54
	v_max_u32_e32 v55, v56, v57
	v_min_u32_e32 v56, v56, v57
	v_max_u32_e32 v57, v67, v66
	v_min_u32_e32 v66, v67, v66
	v_max_u32_e32 v67, v68, v69
	v_min_u32_e32 v68, v68, v69
	v_max_u32_e32 v69, v1, v0
	v_min_u32_e32 v0, v1, v0
	v_max_u32_e32 v1, v2, v3
	v_min_u32_e32 v2, v2, v3
	v_max_u32_e32 v3, v71, v70
	v_min_u32_e32 v70, v71, v70
	v_max_u32_e32 v63, v64, v52
	v_min_u32_e32 v52, v64, v52
	v_max_u32_e32 v64, v65, v51
	v_min_u32_e32 v51, v65, v51
	v_max_u32_e32 v65, v74, v58
	v_min_u32_e32 v58, v74, v58
	v_max_u32_e32 v74, v50, v53
	v_min_u32_e32 v50, v50, v53
	v_max_u32_e32 v53, v48, v59
	v_min_u32_e32 v48, v48, v59
	v_max_u32_e32 v59, v47, v60
	v_min_u32_e32 v47, v47, v60
	v_max_u32_e32 v60, v62, v61
	v_min_u32_e32 v61, v62, v61
	v_max_u32_e32 v62, v49, v46
	v_min_u32_e32 v46, v49, v46
	v_max_u32_e32 v71, v72, v56
	v_min_u32_e32 v56, v72, v56
	v_max_u32_e32 v72, v73, v55
	v_min_u32_e32 v55, v73, v55
	v_max_u32_e32 v73, v82, v66
	v_min_u32_e32 v66, v82, v66
	v_max_u32_e32 v82, v54, v57
	v_min_u32_e32 v54, v54, v57
	v_max_u32_e32 v57, v2, v67
	v_min_u32_e32 v2, v2, v67
	v_max_u32_e32 v67, v1, v68
	v_min_u32_e32 v1, v1, v68
	v_max_u32_e32 v68, v70, v69
	v_min_u32_e32 v69, v70, v69
	v_max_u32_e32 v70, v3, v0
	v_min_u32_e32 v0, v3, v0
	v_max_u32_e32 v49, v63, v65
	v_min_u32_e32 v63, v63, v65
	v_max_u32_e32 v65, v64, v74
	v_min_u32_e32 v64, v64, v74
	v_max_u32_e32 v74, v52, v58
	v_min_u32_e32 v52, v52, v58
	v_max_u32_e32 v58, v51, v50
	v_min_u32_e32 v50, v51, v50
	v_max_u32_e32 v51, v61, v48
	v_min_u32_e32 v48, v61, v48
	v_max_u32_e32 v61, v46, v47
	v_min_u32_e32 v46, v46, v47
	v_max_u32_e32 v47, v60, v53
	v_min_u32_e32 v53, v60, v53
	v_max_u32_e32 v60, v62, v59
	v_min_u32_e32 v59, v62, v59
	v_max_u32_e32 v3, v71, v73
	v_min_u32_e32 v71, v71, v73
	v_max_u32_e32 v73, v72, v82
	v_min_u32_e32 v72, v72, v82
	v_max_u32_e32 v82, v56, v66
	v_min_u32_e32 v56, v56, v66
	v_max_u32_e32 v66, v55, v54
	v_min_u32_e32 v54, v55, v54
	v_max_u32_e32 v55, v69, v2
	v_min_u32_e32 v2, v69, v2
	v_max_u32_e32 v69, v0, v1
	v_min_u32_e32 v0, v0, v1
	v_max_u32_e32 v1, v68, v57
	v_min_u32_e32 v57, v68, v57
	v_max_u32_e32 v68, v70, v67
	v_min_u32_e32 v67, v70, v67
	v_max_u32_e32 v62, v49, v65
	v_min_u32_e32 v49, v49, v65
	v_max_u32_e32 v65, v63, v64
	v_min_u32_e32 v63, v63, v64
	v_max_u32_e32 v64, v74, v58
	v_min_u32_e32 v58, v74, v58
	v_max_u32_e32 v74, v52, v50
	v_min_u32_e32 v50, v52, v50
	v_max_u32_e32 v52, v46, v48
	v_min_u32_e32 v46, v46, v48
	v_max_u32_e32 v48, v61, v51
	v_min_u32_e32 v51, v61, v51
	v_max_u32_e32 v61, v59, v53
	v_min_u32_e32 v53, v59, v53
	v_max_u32_e32 v59, v60, v47
	v_min_u32_e32 v47, v60, v47
	v_max_u32_e32 v70, v3, v73
	v_min_u32_e32 v3, v3, v73
	v_max_u32_e32 v73, v71, v72
	v_min_u32_e32 v71, v71, v72
	v_max_u32_e32 v72, v82, v66
	v_min_u32_e32 v66, v82, v66
	v_max_u32_e32 v82, v56, v54
	v_min_u32_e32 v54, v56, v54
	v_max_u32_e32 v56, v0, v2
	v_min_u32_e32 v0, v0, v2
	v_max_u32_e32 v2, v69, v55
	v_min_u32_e32 v55, v69, v55
	v_max_u32_e32 v69, v67, v57
	v_min_u32_e32 v57, v67, v57
	v_max_u32_e32 v67, v68, v1
	v_min_u32_e32 v1, v68, v1
	v_max_u32_e32 v60, v62, v46
	v_min_u32_e32 v46, v62, v46
	v_max_u32_e32 v62, v49, v52
	v_min_u32_e32 v49, v49, v52
	v_max_u32_e32 v52, v65, v51
	v_min_u32_e32 v51, v65, v51
	v_max_u32_e32 v65, v63, v48
	v_min_u32_e32 v48, v63, v48
	v_max_u32_e32 v63, v64, v53
	v_min_u32_e32 v53, v64, v53
	v_max_u32_e32 v64, v58, v61
	v_min_u32_e32 v58, v58, v61
	v_max_u32_e32 v61, v74, v47
	v_min_u32_e32 v47, v74, v47
	v_max_u32_e32 v74, v50, v59
	v_min_u32_e32 v50, v50, v59
	v_max_u32_e32 v68, v70, v0
	v_min_u32_e32 v0, v70, v0
	v_max_u32_e32 v70, v3, v56
	v_min_u32_e32 v3, v3, v56
	v_max_u32_e32 v56, v73, v55
	v_min_u32_e32 v55, v73, v55
	v_max_u32_e32 v73, v71, v2
	v_min_u32_e32 v2, v71, v2
	v_max_u32_e32 v71, v72, v57
	v_min_u32_e32 v57, v72, v57
	v_max_u32_e32 v72, v66, v69
	v_min_u32_e32 v66, v66, v69
	v_max_u32_e32 v69, v82, v1
	v_min_u32_e32 v1, v82, v1
	v_max_u32_e32 v82, v54, v67
	v_min_u32_e32 v54, v54, v67
	v_max_u32_e32 v59, v60, v63
	v_min_u32_e32 v60, v60, v63
	v_max_u32_e32 v63, v62, v64
	v_min_u32_e32 v62, v62, v64
	v_max_u32_e32 v64, v52, v61
	v_min_u32_e32 v52, v52, v61
	v_max_u32_e32 v61, v65, v74
	v_min_u32_e32 v65, v65, v74
	v_max_u32_e32 v74, v46, v53
	v_min_u32_e32 v46, v46, v53
	v_max_u32_e32 v53, v49, v58
	v_min_u32_e32 v49, v49, v58
	v_max_u32_e32 v58, v51, v47
; #define CE_DESC(a, b) do { const unsigned _mx = (a) > (b) ? (a) : (b), _mn = (a) > (b) ? (b) : (a); (a) = _mx; (b) = _mn; } while (0)
; __device__ __forceinline__ void merge16(unsigned (&a)[16], const unsigned (&b)[16]) {
; #pragma unroll
;     for (int i = 0; i < 16; ++i) a[i] = a[i] > b[15 - i] ? a[i] : b[15 - i];
; #pragma unroll
;     for (int stride = 8; stride > 0; stride >>= 1)
; #pragma unroll
;         for (int i = 0; i < 16; ++i) { const int j = i ^ stride; if (j > i) CE_DESC(a[i], a[j]); }
; }
; __device__ __forceinline__ void peer_tile(const Args& A, LAS unsigned char* lds, int tile) {
;     ...
;                 for (int msk = 16; msk <= 32; msk <<= 1) {
; #pragma unroll
;                     for (int i = 0; i < 16; ++i) k1[i] = (unsigned)__shfl_xor((int)k0[i], msk);
;                     merge16(k0, k1); }
	v_min_u32_e32 v47, v51, v47
	v_max_u32_e32 v51, v48, v50
	v_min_u32_e32 v48, v48, v50
	v_max_u32_e32 v67, v68, v71
	v_min_u32_e32 v68, v68, v71
	v_max_u32_e32 v71, v70, v72
	v_min_u32_e32 v70, v70, v72
	v_max_u32_e32 v72, v56, v69
	v_min_u32_e32 v56, v56, v69
	v_max_u32_e32 v69, v73, v82
	v_min_u32_e32 v73, v73, v82
	v_max_u32_e32 v82, v0, v57
	v_min_u32_e32 v0, v0, v57
	v_max_u32_e32 v57, v3, v66
	v_min_u32_e32 v3, v3, v66
	v_max_u32_e32 v66, v55, v1
	v_min_u32_e32 v1, v55, v1
	v_max_u32_e32 v55, v2, v54
	v_min_u32_e32 v2, v2, v54
	v_max_u32_e32 v50, v59, v64
	v_min_u32_e32 v59, v59, v64
	v_max_u32_e32 v64, v63, v61
	v_min_u32_e32 v61, v63, v61
	v_max_u32_e32 v63, v60, v52
	v_min_u32_e32 v52, v60, v52
	v_max_u32_e32 v60, v62, v65
	v_min_u32_e32 v62, v62, v65
	v_max_u32_e32 v65, v74, v58
	v_min_u32_e32 v58, v74, v58
	v_max_u32_e32 v74, v53, v51
	v_min_u32_e32 v51, v53, v51
	v_max_u32_e32 v53, v46, v47
	v_min_u32_e32 v46, v46, v47
	v_max_u32_e32 v47, v49, v48
	v_min_u32_e32 v48, v49, v48
	v_max_u32_e32 v54, v67, v72
	v_min_u32_e32 v67, v67, v72
	v_max_u32_e32 v72, v71, v69
	v_min_u32_e32 v69, v71, v69
	v_max_u32_e32 v71, v68, v56
	v_min_u32_e32 v56, v68, v56
	v_max_u32_e32 v68, v70, v73
	v_min_u32_e32 v70, v70, v73
	v_max_u32_e32 v73, v82, v66
	v_min_u32_e32 v66, v82, v66
	v_max_u32_e32 v82, v57, v55
	v_min_u32_e32 v55, v57, v55
	v_max_u32_e32 v57, v0, v1
	v_min_u32_e32 v0, v0, v1
	v_max_u32_e32 v1, v3, v2
	v_min_u32_e32 v2, v3, v2
	v_min_u32_e32 v49, v50, v64
	v_min_u32_e32 v75, v59, v61
	v_min_u32_e32 v76, v63, v60
	v_min_u32_e32 v77, v52, v62
	v_min_u32_e32 v78, v65, v74
	v_min_u32_e32 v79, v58, v51
	v_min_u32_e32 v80, v53, v47
	v_min_u32_e32 v81, v46, v48
	v_min_u32_e32 v3, v54, v72
	v_min_u32_e32 v83, v67, v69
	v_min_u32_e32 v84, v71, v68
	v_min_u32_e32 v85, v56, v70
	v_min_u32_e32 v86, v73, v82
	v_min_u32_e32 v87, v66, v55
	v_min_u32_e32 v88, v57, v1
	v_min_u32_e32 v89, v0, v2
	v_max3_u32 v50, v50, v64, v89
	v_max3_u32 v0, v49, v0, v2
	v_max3_u32 v2, v59, v61, v88
	v_max3_u32 v1, v75, v57, v1
	v_max3_u32 v49, v63, v60, v87
	v_max3_u32 v55, v76, v66, v55
	v_max3_u32 v52, v52, v62, v86
	v_max3_u32 v57, v77, v73, v82
	v_max3_u32 v59, v65, v74, v85
	v_max3_u32 v56, v78, v56, v70
	v_max3_u32 v51, v58, v51, v84
	v_max3_u32 v58, v79, v71, v68
	v_max3_u32 v47, v53, v47, v83
	v_max3_u32 v53, v80, v67, v69
	v_max3_u32 v3, v46, v48, v3
	v_max3_u32 v46, v81, v54, v72
	v_max_u32_e32 v48, v50, v59
	v_min_u32_e32 v50, v50, v59
	v_max_u32_e32 v54, v0, v56
	v_min_u32_e32 v0, v0, v56
	v_max_u32_e32 v56, v2, v51
	v_min_u32_e32 v2, v2, v51
	v_max_u32_e32 v51, v1, v58
	v_min_u32_e32 v1, v1, v58
	v_max_u32_e32 v58, v49, v47
	v_min_u32_e32 v47, v49, v47
	v_max_u32_e32 v49, v55, v53
	v_min_u32_e32 v53, v55, v53
	v_max_u32_e32 v55, v52, v3
	v_min_u32_e32 v3, v52, v3
	v_max_u32_e32 v52, v57, v46
	v_min_u32_e32 v46, v57, v46
	v_max_u32_e32 v57, v48, v58
	v_min_u32_e32 v48, v48, v58
	v_max_u32_e32 v58, v54, v49
	v_min_u32_e32 v49, v54, v49
	v_max_u32_e32 v54, v56, v55
	v_min_u32_e32 v55, v56, v55
	v_max_u32_e32 v56, v51, v52
	v_min_u32_e32 v51, v51, v52
	v_max_u32_e32 v52, v50, v47
	v_min_u32_e32 v47, v50, v47
	v_max_u32_e32 v50, v0, v53
	v_min_u32_e32 v0, v0, v53
	v_max_u32_e32 v53, v2, v3
	v_min_u32_e32 v2, v2, v3
	v_max_u32_e32 v3, v1, v46
	v_min_u32_e32 v1, v1, v46
	v_max_u32_e32 v46, v57, v54
	v_min_u32_e32 v54, v57, v54
	v_max_u32_e32 v57, v58, v56
	v_min_u32_e32 v56, v58, v56
	v_max_u32_e32 v58, v48, v55
	v_min_u32_e32 v48, v48, v55
	v_max_u32_e32 v55, v49, v51
	v_min_u32_e32 v49, v49, v51
	v_max_u32_e32 v51, v52, v53
	v_min_u32_e32 v52, v52, v53
	v_max_u32_e32 v53, v50, v3
	v_min_u32_e32 v3, v50, v3
	v_max_u32_e32 v50, v47, v2
	v_min_u32_e32 v2, v47, v2
	v_max_u32_e32 v47, v0, v1
	v_min_u32_e32 v0, v0, v1
	v_max_u32_e32 v1, v46, v57
	v_min_u32_e32 v46, v46, v57
	v_max_u32_e32 v57, v54, v56
	v_min_u32_e32 v54, v54, v56
	v_max_u32_e32 v56, v58, v55
	v_min_u32_e32 v55, v58, v55
	v_max_u32_e32 v58, v48, v49
	v_min_u32_e32 v48, v48, v49
	v_max_u32_e32 v49, v51, v53
	v_min_u32_e32 v51, v51, v53
	v_max_u32_e32 v53, v52, v3
	v_min_u32_e32 v3, v52, v3
	v_max_u32_e32 v52, v50, v47
	v_min_u32_e32 v47, v50, v47
	v_max_u32_e32 v50, v2, v0
	v_min_u32_e32 v0, v2, v0
	ds_bpermute_b32 v2, v27, v1
	ds_bpermute_b32 v59, v27, v46
	ds_bpermute_b32 v60, v27, v57
	ds_bpermute_b32 v61, v27, v54
	ds_bpermute_b32 v62, v27, v56
	ds_bpermute_b32 v63, v27, v55
	ds_bpermute_b32 v64, v27, v58
	ds_bpermute_b32 v65, v27, v48
	ds_bpermute_b32 v66, v27, v49
	ds_bpermute_b32 v67, v27, v51
	ds_bpermute_b32 v68, v27, v53
	ds_bpermute_b32 v69, v27, v0
	ds_bpermute_b32 v70, v27, v50
	ds_bpermute_b32 v71, v27, v47
	ds_bpermute_b32 v72, v27, v52
	ds_bpermute_b32 v73, v27, v3
	s_waitcnt lgkmcnt(4)
	v_max_u32_e32 v1, v1, v69
	s_waitcnt lgkmcnt(3)
	v_max_u32_e32 v46, v46, v70
	s_waitcnt lgkmcnt(2)
	v_max_u32_e32 v57, v57, v71
	s_waitcnt lgkmcnt(1)
	v_max_u32_e32 v54, v54, v72
	s_waitcnt lgkmcnt(0)
; __device__ __forceinline__ void peer_tile(const Args& A, LAS unsigned char* lds, int tile) {
;     ...
;                 { const bf16_t* sp = QRY + m * 2048 + hp * 128 + 32 * g;
;                   const u32x4 s0 = *(const u32x4*)sp, s1 = *(const u32x4*)(sp + 8), s2 = *(const u32x4*)(sp + 16), s3 = *(const u32x4*)(sp + 24);
;     ...
;                 for (int msk = 16; msk <= 32; msk <<= 1) {
; #pragma unroll
;                     for (int i = 0; i < 16; ++i) k1[i] = (unsigned)__shfl_xor((int)k0[i], msk);
;                     merge16(k0, k1); }
	v_max_u32_e32 v56, v56, v73
	v_max_u32_e32 v55, v55, v68
	v_max_u32_e32 v58, v58, v67
	v_max_u32_e32 v48, v48, v66
	v_max_u32_e32 v49, v49, v65
	v_max_u32_e32 v51, v51, v64
	v_max_u32_e32 v53, v53, v63
	v_max_u32_e32 v3, v3, v62
	v_max_u32_e32 v52, v52, v61
	v_max_u32_e32 v47, v47, v60
	v_max_u32_e32 v50, v50, v59
	v_max_u32_e32 v0, v0, v2
	v_max_u32_e32 v2, v1, v49
	v_min_u32_e32 v1, v1, v49
	v_max_u32_e32 v49, v46, v51
	v_min_u32_e32 v46, v46, v51
	v_max_u32_e32 v51, v57, v53
	v_min_u32_e32 v53, v57, v53
	v_max_u32_e32 v57, v54, v3
	v_min_u32_e32 v3, v54, v3
	v_max_u32_e32 v54, v56, v52
	v_min_u32_e32 v52, v56, v52
	v_max_u32_e32 v56, v55, v47
	v_min_u32_e32 v47, v55, v47
	v_max_u32_e32 v55, v58, v50
	v_min_u32_e32 v50, v58, v50
	v_max_u32_e32 v58, v48, v0
	v_min_u32_e32 v0, v48, v0
	v_max_u32_e32 v48, v2, v54
	v_min_u32_e32 v2, v2, v54
	v_max_u32_e32 v54, v49, v56
	v_min_u32_e32 v49, v49, v56
	v_max_u32_e32 v56, v51, v55
	v_min_u32_e32 v51, v51, v55
	v_max_u32_e32 v55, v57, v58
	v_min_u32_e32 v57, v57, v58
	v_max_u32_e32 v58, v1, v52
	v_min_u32_e32 v1, v1, v52
	v_max_u32_e32 v52, v46, v47
	v_min_u32_e32 v46, v46, v47
	v_max_u32_e32 v47, v53, v50
	v_min_u32_e32 v50, v53, v50
	v_max_u32_e32 v53, v3, v0
	v_min_u32_e32 v0, v3, v0
	v_max_u32_e32 v3, v48, v56
	v_min_u32_e32 v48, v48, v56
	v_max_u32_e32 v56, v54, v55
	v_min_u32_e32 v54, v54, v55
	v_max_u32_e32 v55, v2, v51
	v_min_u32_e32 v2, v2, v51
	v_max_u32_e32 v51, v49, v57
	v_min_u32_e32 v49, v49, v57
	v_max_u32_e32 v57, v58, v47
	v_min_u32_e32 v47, v58, v47
	v_max_u32_e32 v58, v52, v53
	v_min_u32_e32 v52, v52, v53
	v_max_u32_e32 v53, v1, v50
	v_min_u32_e32 v1, v1, v50
	v_max_u32_e32 v50, v46, v0
	v_min_u32_e32 v0, v46, v0
	v_max_u32_e32 v46, v3, v56
	v_min_u32_e32 v3, v3, v56
	v_max_u32_e32 v56, v48, v54
	v_min_u32_e32 v48, v48, v54
	v_max_u32_e32 v54, v55, v51
	v_min_u32_e32 v51, v55, v51
	v_max_u32_e32 v55, v2, v49
	v_min_u32_e32 v2, v2, v49
	v_max_u32_e32 v49, v57, v58
	v_min_u32_e32 v57, v57, v58
	v_max_u32_e32 v58, v47, v52
	v_min_u32_e32 v47, v47, v52
	v_max_u32_e32 v52, v53, v50
	v_min_u32_e32 v50, v53, v50
	v_max_u32_e32 v53, v1, v0
	v_min_u32_e32 v0, v1, v0
	ds_bpermute_b32 v62, v29, v0
	ds_bpermute_b32 v1, v29, v46
	ds_bpermute_b32 v59, v29, v3
	ds_bpermute_b32 v60, v29, v56
	ds_bpermute_b32 v61, v29, v48
	s_waitcnt lgkmcnt(4)
	v_max_u32_e32 v46, v46, v62
	global_load_dwordx4 v[62:65], v[4:5], off offset:528
	global_load_dwordx4 v[66:69], v[4:5], off offset:512
	ds_bpermute_b32 v70, v29, v54
	ds_bpermute_b32 v71, v29, v51
	ds_bpermute_b32 v72, v29, v55
	ds_bpermute_b32 v73, v29, v2
	ds_bpermute_b32 v74, v29, v49
	ds_bpermute_b32 v75, v29, v57
	ds_bpermute_b32 v76, v29, v58
	ds_bpermute_b32 v77, v29, v47
	ds_bpermute_b32 v78, v29, v52
	ds_bpermute_b32 v79, v29, v53
	ds_bpermute_b32 v80, v29, v50
	s_waitcnt lgkmcnt(4)
	v_max_u32_e32 v51, v51, v76
	s_waitcnt lgkmcnt(3)
	v_max_u32_e32 v54, v54, v77
	s_waitcnt lgkmcnt(2)
	v_max_u32_e32 v48, v48, v78
	s_waitcnt lgkmcnt(1)
	v_max_u32_e32 v3, v3, v79
	s_waitcnt lgkmcnt(0)
	v_max_u32_e32 v56, v56, v80
	v_max_u32_e32 v55, v55, v75
	v_max_u32_e32 v2, v2, v74
	v_max_u32_e32 v49, v49, v73
	v_max_u32_e32 v57, v57, v72
	v_max_u32_e32 v58, v58, v71
	v_max_u32_e32 v47, v47, v70
	v_max_u32_e32 v52, v52, v61
	v_max_u32_e32 v50, v50, v60
	v_max_u32_e32 v53, v53, v59
	v_max_u32_e32 v0, v0, v1
	v_max_u32_e32 v1, v46, v49
	v_min_u32_e32 v46, v46, v49
	v_max_u32_e32 v49, v3, v57
	v_min_u32_e32 v3, v3, v57
	v_max_u32_e32 v57, v56, v58
	v_min_u32_e32 v56, v56, v58
	v_max_u32_e32 v58, v48, v47
	v_min_u32_e32 v47, v48, v47
	v_max_u32_e32 v48, v54, v52
	v_min_u32_e32 v52, v54, v52
	v_max_u32_e32 v54, v51, v50
	v_min_u32_e32 v50, v51, v50
	v_max_u32_e32 v51, v55, v53
	v_min_u32_e32 v53, v55, v53
	v_max_u32_e32 v55, v2, v0
	v_min_u32_e32 v0, v2, v0
	v_max_u32_e32 v2, v1, v48
	v_min_u32_e32 v1, v1, v48
	v_max_u32_e32 v48, v49, v54
	v_min_u32_e32 v49, v49, v54
	v_max_u32_e32 v54, v57, v51
	v_min_u32_e32 v51, v57, v51
	v_max_u32_e32 v57, v58, v55
	v_min_u32_e32 v55, v58, v55
	v_max_u32_e32 v58, v46, v52
	v_min_u32_e32 v46, v46, v52
	v_max_u32_e32 v52, v3, v50
	v_min_u32_e32 v3, v3, v50
	v_max_u32_e32 v50, v56, v53
	v_min_u32_e32 v53, v56, v53
	v_max_u32_e32 v56, v47, v0
	v_min_u32_e32 v0, v47, v0
	v_max_u32_e32 v47, v2, v54
	v_min_u32_e32 v2, v2, v54
	v_max_u32_e32 v54, v48, v57
	v_min_u32_e32 v48, v48, v57
	v_max_u32_e32 v70, v1, v51
	v_min_u32_e32 v1, v1, v51
	v_max_u32_e32 v51, v49, v55
	v_min_u32_e32 v49, v49, v55
	v_max_u32_e32 v71, v58, v50
	v_min_u32_e32 v50, v58, v50
	v_max_u32_e32 v72, v52, v56
	v_min_u32_e32 v73, v52, v56
	v_max_u32_e32 v74, v46, v53
	v_min_u32_e32 v46, v46, v53
	v_max_u32_e32 v75, v3, v0
	v_min_u32_e32 v0, v3, v0
	v_max_u32_e32 v61, v47, v54
	v_min_u32_e32 v60, v47, v54
	v_max_u32_e32 v59, v2, v48
	v_min_u32_e32 v58, v2, v48
	v_max_u32_e32 v57, v70, v51
	v_min_u32_e32 v56, v70, v51
	v_max_u32_e32 v55, v1, v49
	v_min_u32_e32 v54, v1, v49
	v_max_u32_e32 v53, v71, v72
	v_min_u32_e32 v52, v71, v72
	v_max_u32_e32 v51, v50, v73
	v_min_u32_e32 v50, v50, v73
	v_max_u32_e32 v47, v46, v0
	v_min_u32_e32 v46, v46, v0
	global_load_dwordx4 v[0:3], v[4:5], off offset:560
	global_load_dwordx4 v[70:73], v[4:5], off offset:544
	v_max_u32_e32 v49, v74, v75
	v_min_u32_e32 v48, v74, v75
	s_waitcnt vmcnt(2)
; __device__ __forceinline__ unsigned f2key(float f) { const unsigned u = __float_as_uint(f); return (u & 0x80000000u) ? ~u : (u | 0x80000000u); }
; __device__ __forceinline__ void peer_tile(const Args& A, LAS unsigned char* lds, int tile) {
;     ...
;                   for (int i = 0; i < 16; ++i) {
;                       const float lo = (float)__builtin_bit_cast(_Float16, (unsigned short)(sw[i] & 0xffffu)), hi = (float)__builtin_bit_cast(_Float16, (unsigned short)(sw[i] >> 16));
;                       const unsigned klo = (f2key(lo) & ~127u) | (unsigned)(127 - (32 * g + 2 * i)), khi = (f2key(hi) & ~127u) | (unsigned)(127 - (32 * g + 2 * i + 1));
;                       if (i < 8) { k0[2 * i] = klo; k0[2 * i + 1] = khi; } else { k1[2 * (i - 8)] = klo; k1[2 * (i - 8) + 1] = khi; } } }
	v_cvt_f32_f16_sdwa v74, v66 dst_sel:DWORD dst_unused:UNUSED_PAD src0_sel:WORD_1
	v_cvt_f32_f16_e32 v66, v66
	v_not_b32_e32 v75, v74
	v_or_b32_e32 v76, 0x80000000, v74
	v_cmp_gt_i32_e32 vcc, 0, v74
	s_nop 1
	v_cndmask_b32_e32 v74, v76, v75, vcc
	v_not_b32_e32 v75, v66
	v_or_b32_e32 v76, 0x80000000, v66
	v_cmp_gt_i32_e32 vcc, 0, v66
	v_and_b32_e32 v74, 0xffffff80, v74
	v_sub_u32_e32 v74, v74, v15
	v_cndmask_b32_e32 v66, v76, v75, vcc
	v_cvt_f32_f16_sdwa v75, v67 dst_sel:DWORD dst_unused:UNUSED_PAD src0_sel:WORD_1
	v_cvt_f32_f16_e32 v67, v67
	v_and_b32_e32 v66, 0xffffff80, v66
	v_sub_u32_e32 v66, v66, v15
	v_not_b32_e32 v76, v75
	v_or_b32_e32 v77, 0x80000000, v75
	v_cmp_gt_i32_e32 vcc, 0, v75
	v_add_u32_e32 v74, 0x7e, v74
	v_add_u32_e32 v66, 0x7f, v66
	v_cndmask_b32_e32 v75, v77, v76, vcc
	v_not_b32_e32 v76, v67
	v_or_b32_e32 v77, 0x80000000, v67
	v_cmp_gt_i32_e32 vcc, 0, v67
	v_and_b32_e32 v75, 0xffffff80, v75
	v_sub_u32_e32 v75, v75, v14
	v_cndmask_b32_e32 v67, v77, v76, vcc
	v_cvt_f32_f16_sdwa v76, v68 dst_sel:DWORD dst_unused:UNUSED_PAD src0_sel:WORD_1
	v_cvt_f32_f16_e32 v68, v68
	v_and_b32_e32 v67, 0xffffff80, v67
	v_sub_u32_e32 v67, v67, v14
	v_not_b32_e32 v77, v76
	v_or_b32_e32 v78, 0x80000000, v76
	v_cmp_gt_i32_e32 vcc, 0, v76
	v_add_u32_e32 v75, 0x7e, v75
	v_add_u32_e32 v67, 0x7f, v67
	v_cndmask_b32_e32 v76, v78, v77, vcc
	v_not_b32_e32 v77, v68
	v_or_b32_e32 v78, 0x80000000, v68
	v_cmp_gt_i32_e32 vcc, 0, v68
	v_and_b32_e32 v76, 0xffffff80, v76
	v_sub_u32_e32 v76, v76, v12
	v_cndmask_b32_e32 v68, v78, v77, vcc
	v_cvt_f32_f16_sdwa v77, v69 dst_sel:DWORD dst_unused:UNUSED_PAD src0_sel:WORD_1
	v_cvt_f32_f16_e32 v69, v69
	v_and_b32_e32 v68, 0xffffff80, v68
	v_sub_u32_e32 v68, v68, v12
	v_not_b32_e32 v78, v77
	v_or_b32_e32 v79, 0x80000000, v77
	v_cmp_gt_i32_e32 vcc, 0, v77
	v_add_u32_e32 v76, 0x7e, v76
	v_add_u32_e32 v68, 0x7f, v68
	v_cndmask_b32_e32 v77, v79, v78, vcc
	v_not_b32_e32 v78, v69
	v_or_b32_e32 v79, 0x80000000, v69
	v_cmp_gt_i32_e32 vcc, 0, v69
	v_and_b32_e32 v77, 0xffffff80, v77
	v_sub_u32_e32 v77, v77, v10
	v_cndmask_b32_e32 v69, v79, v78, vcc
	v_cvt_f32_f16_sdwa v78, v62 dst_sel:DWORD dst_unused:UNUSED_PAD src0_sel:WORD_1
	v_cvt_f32_f16_e32 v62, v62
	v_and_b32_e32 v69, 0xffffff80, v69
	v_sub_u32_e32 v69, v69, v10
	v_not_b32_e32 v79, v78
	v_or_b32_e32 v80, 0x80000000, v78
	v_cmp_gt_i32_e32 vcc, 0, v78
	v_add_u32_e32 v77, 0x7e, v77
	v_add_u32_e32 v69, 0x7f, v69
	v_cndmask_b32_e32 v78, v80, v79, vcc
	v_not_b32_e32 v79, v62
	v_or_b32_e32 v80, 0x80000000, v62
	v_cmp_gt_i32_e32 vcc, 0, v62
	v_and_b32_e32 v78, 0xffffff80, v78
	v_sub_u32_e32 v78, v78, v8
	v_cndmask_b32_e32 v62, v80, v79, vcc
	v_cvt_f32_f16_sdwa v79, v63 dst_sel:DWORD dst_unused:UNUSED_PAD src0_sel:WORD_1
	v_cvt_f32_f16_e32 v63, v63
	v_and_b32_e32 v62, 0xffffff80, v62
	v_sub_u32_e32 v62, v62, v8
	v_not_b32_e32 v80, v79
	v_or_b32_e32 v81, 0x80000000, v79
	v_cmp_gt_i32_e32 vcc, 0, v79
	v_add_u32_e32 v78, 0x7e, v78
	v_add_u32_e32 v62, 0x7f, v62
	v_cndmask_b32_e32 v79, v81, v80, vcc
	v_not_b32_e32 v80, v63
	v_or_b32_e32 v81, 0x80000000, v63
	v_cmp_gt_i32_e32 vcc, 0, v63
	v_and_b32_e32 v79, 0xffffff80, v79
	v_sub_u32_e32 v79, v79, v16
	v_cndmask_b32_e32 v63, v81, v80, vcc
	v_cvt_f32_f16_sdwa v80, v64 dst_sel:DWORD dst_unused:UNUSED_PAD src0_sel:WORD_1
	v_cvt_f32_f16_e32 v64, v64
	v_and_b32_e32 v63, 0xffffff80, v63
	v_sub_u32_e32 v63, v63, v16
	v_not_b32_e32 v81, v80
	v_or_b32_e32 v82, 0x80000000, v80
	v_cmp_gt_i32_e32 vcc, 0, v80
	v_add_u32_e32 v79, 0x7e, v79
	v_add_u32_e32 v63, 0x7f, v63
	v_cndmask_b32_e32 v80, v82, v81, vcc
	v_not_b32_e32 v81, v64
	v_or_b32_e32 v82, 0x80000000, v64
	v_cmp_gt_i32_e32 vcc, 0, v64
	v_and_b32_e32 v80, 0xffffff80, v80
	v_sub_u32_e32 v80, v80, v17
	v_cndmask_b32_e32 v64, v82, v81, vcc
	v_cvt_f32_f16_sdwa v81, v65 dst_sel:DWORD dst_unused:UNUSED_PAD src0_sel:WORD_1
	v_cvt_f32_f16_e32 v65, v65
	v_and_b32_e32 v64, 0xffffff80, v64
	v_sub_u32_e32 v64, v64, v17
	v_not_b32_e32 v82, v81
	v_or_b32_e32 v83, 0x80000000, v81
	v_cmp_gt_i32_e32 vcc, 0, v81
	v_add_u32_e32 v80, 0x7e, v80
	v_add_u32_e32 v64, 0x7f, v64
	v_cndmask_b32_e32 v81, v83, v82, vcc
	v_not_b32_e32 v82, v65
	v_or_b32_e32 v83, 0x80000000, v65
	v_cmp_gt_i32_e32 vcc, 0, v65
	v_and_b32_e32 v81, 0xffffff80, v81
	v_sub_u32_e32 v81, v81, v18
	v_cndmask_b32_e32 v65, v83, v82, vcc
	s_waitcnt vmcnt(0)
; __device__ __forceinline__ unsigned f2key(float f) { const unsigned u = __float_as_uint(f); return (u & 0x80000000u) ? ~u : (u | 0x80000000u); }
; __device__ __forceinline__ void peer_tile(const Args& A, LAS unsigned char* lds, int tile) {
;     ...
;                   for (int i = 0; i < 16; ++i) {
;                       const float lo = (float)__builtin_bit_cast(_Float16, (unsigned short)(sw[i] & 0xffffu)), hi = (float)__builtin_bit_cast(_Float16, (unsigned short)(sw[i] >> 16));
;                       const unsigned klo = (f2key(lo) & ~127u) | (unsigned)(127 - (32 * g + 2 * i)), khi = (f2key(hi) & ~127u) | (unsigned)(127 - (32 * g + 2 * i + 1));
;                       if (i < 8) { k0[2 * i] = klo; k0[2 * i + 1] = khi; } else { k1[2 * (i - 8)] = klo; k1[2 * (i - 8) + 1] = khi; } } }
;                 sort16_desc(k0); sort16_desc(k1); merge16(k0, k1);
	v_cvt_f32_f16_sdwa v82, v70 dst_sel:DWORD dst_unused:UNUSED_PAD src0_sel:WORD_1
	v_cvt_f32_f16_e32 v70, v70
	v_and_b32_e32 v65, 0xffffff80, v65
	v_sub_u32_e32 v65, v65, v18
	v_not_b32_e32 v83, v82
	v_or_b32_e32 v84, 0x80000000, v82
	v_cmp_gt_i32_e32 vcc, 0, v82
	v_add_u32_e32 v81, 0x7e, v81
	v_add_u32_e32 v65, 0x7f, v65
	v_cndmask_b32_e32 v82, v84, v83, vcc
	v_not_b32_e32 v83, v70
	v_or_b32_e32 v84, 0x80000000, v70
	v_cmp_gt_i32_e32 vcc, 0, v70
	v_and_b32_e32 v82, 0xffffff80, v82
	v_sub_u32_e32 v82, v82, v20
	v_cndmask_b32_e32 v70, v84, v83, vcc
	v_cvt_f32_f16_sdwa v83, v71 dst_sel:DWORD dst_unused:UNUSED_PAD src0_sel:WORD_1
	v_cvt_f32_f16_e32 v71, v71
	v_and_b32_e32 v70, 0xffffff80, v70
	v_sub_u32_e32 v70, v70, v20
	v_not_b32_e32 v84, v83
	v_or_b32_e32 v85, 0x80000000, v83
	v_cmp_gt_i32_e32 vcc, 0, v83
	v_add_u32_e32 v82, 0x7e, v82
	v_add_u32_e32 v70, 0x7f, v70
	v_cndmask_b32_e32 v83, v85, v84, vcc
	v_not_b32_e32 v84, v71
	v_or_b32_e32 v85, 0x80000000, v71
	v_cmp_gt_i32_e32 vcc, 0, v71
	v_and_b32_e32 v83, 0xffffff80, v83
	v_sub_u32_e32 v83, v83, v21
	v_cndmask_b32_e32 v71, v85, v84, vcc
	v_cvt_f32_f16_sdwa v84, v72 dst_sel:DWORD dst_unused:UNUSED_PAD src0_sel:WORD_1
	v_cvt_f32_f16_e32 v72, v72
	v_and_b32_e32 v71, 0xffffff80, v71
	v_sub_u32_e32 v71, v71, v21
	v_not_b32_e32 v85, v84
	v_or_b32_e32 v86, 0x80000000, v84
	v_cmp_gt_i32_e32 vcc, 0, v84
	v_add_u32_e32 v83, 0x7e, v83
	v_add_u32_e32 v71, 0x7f, v71
	v_cndmask_b32_e32 v84, v86, v85, vcc
	v_not_b32_e32 v85, v72
	v_or_b32_e32 v86, 0x80000000, v72
	v_cmp_gt_i32_e32 vcc, 0, v72
	v_and_b32_e32 v84, 0xffffff80, v84
	v_sub_u32_e32 v84, v84, v22
	v_cndmask_b32_e32 v72, v86, v85, vcc
	v_cvt_f32_f16_sdwa v85, v73 dst_sel:DWORD dst_unused:UNUSED_PAD src0_sel:WORD_1
	v_cvt_f32_f16_e32 v73, v73
	v_and_b32_e32 v72, 0xffffff80, v72
	v_sub_u32_e32 v72, v72, v22
	v_not_b32_e32 v86, v85
	v_or_b32_e32 v87, 0x80000000, v85
	v_cmp_gt_i32_e32 vcc, 0, v85
	v_add_u32_e32 v84, 0x7e, v84
	v_add_u32_e32 v72, 0x7f, v72
	v_cndmask_b32_e32 v85, v87, v86, vcc
	v_not_b32_e32 v86, v73
	v_or_b32_e32 v87, 0x80000000, v73
	v_cmp_gt_i32_e32 vcc, 0, v73
	v_and_b32_e32 v85, 0xffffff80, v85
	v_sub_u32_e32 v85, v85, v23
	v_cndmask_b32_e32 v73, v87, v86, vcc
	v_cvt_f32_f16_sdwa v86, v0 dst_sel:DWORD dst_unused:UNUSED_PAD src0_sel:WORD_1
	v_cvt_f32_f16_e32 v0, v0
	v_and_b32_e32 v73, 0xffffff80, v73
	v_sub_u32_e32 v73, v73, v23
	v_not_b32_e32 v87, v86
	v_or_b32_e32 v88, 0x80000000, v86
	v_cmp_gt_i32_e32 vcc, 0, v86
	v_add_u32_e32 v85, 0x7e, v85
	v_add_u32_e32 v73, 0x7f, v73
	v_cndmask_b32_e32 v86, v88, v87, vcc
	v_not_b32_e32 v87, v0
	v_or_b32_e32 v88, 0x80000000, v0
	v_cmp_gt_i32_e32 vcc, 0, v0
	v_and_b32_e32 v86, 0xffffff80, v86
	v_sub_u32_e32 v86, v86, v24
	v_cndmask_b32_e32 v0, v88, v87, vcc
	v_cvt_f32_f16_sdwa v87, v1 dst_sel:DWORD dst_unused:UNUSED_PAD src0_sel:WORD_1
	v_cvt_f32_f16_e32 v1, v1
	v_and_b32_e32 v0, 0xffffff80, v0
	v_sub_u32_e32 v0, v0, v24
	v_not_b32_e32 v88, v87
	v_or_b32_e32 v89, 0x80000000, v87
	v_cmp_gt_i32_e32 vcc, 0, v87
	v_add_u32_e32 v86, 0x7e, v86
	v_add_u32_e32 v0, 0x7f, v0
	v_cndmask_b32_e32 v87, v89, v88, vcc
	v_not_b32_e32 v88, v1
	v_or_b32_e32 v89, 0x80000000, v1
	v_cmp_gt_i32_e32 vcc, 0, v1
	v_and_b32_e32 v87, 0xffffff80, v87
	v_sub_u32_e32 v87, v87, v25
	v_cndmask_b32_e32 v1, v89, v88, vcc
	v_cvt_f32_f16_sdwa v88, v2 dst_sel:DWORD dst_unused:UNUSED_PAD src0_sel:WORD_1
	v_cvt_f32_f16_e32 v2, v2
	v_and_b32_e32 v1, 0xffffff80, v1
	v_sub_u32_e32 v1, v1, v25
	v_not_b32_e32 v89, v88
	v_or_b32_e32 v90, 0x80000000, v88
	v_cmp_gt_i32_e32 vcc, 0, v88
	v_add_u32_e32 v87, 0x7e, v87
	v_add_u32_e32 v1, 0x7f, v1
	v_cndmask_b32_e32 v88, v90, v89, vcc
	v_not_b32_e32 v89, v2
	v_or_b32_e32 v90, 0x80000000, v2
	v_cmp_gt_i32_e32 vcc, 0, v2
	v_and_b32_e32 v88, 0xffffff80, v88
	v_sub_u32_e32 v88, v88, v26
	v_cndmask_b32_e32 v2, v90, v89, vcc
	v_cvt_f32_f16_sdwa v89, v3 dst_sel:DWORD dst_unused:UNUSED_PAD src0_sel:WORD_1
	v_cvt_f32_f16_e32 v3, v3
	v_and_b32_e32 v2, 0xffffff80, v2
	v_sub_u32_e32 v2, v2, v26
	v_not_b32_e32 v90, v89
	v_or_b32_e32 v91, 0x80000000, v89
	v_cmp_gt_i32_e32 vcc, 0, v89
	v_add_u32_e32 v88, 0x7e, v88
	v_add_u32_e32 v2, 0x7f, v2
	v_cndmask_b32_e32 v89, v91, v90, vcc
	v_not_b32_e32 v90, v3
	v_or_b32_e32 v91, 0x80000000, v3
	v_cmp_gt_i32_e32 vcc, 0, v3
	v_and_b32_e32 v89, 0xffffff80, v89
	v_sub_u32_e32 v89, v89, v28
	v_cndmask_b32_e32 v3, v91, v90, vcc
	v_and_b32_e32 v3, 0xffffff80, v3
	v_sub_u32_e32 v3, v3, v28
	v_add_u32_e32 v89, 0x7e, v89
	v_add_u32_e32 v3, 0x7f, v3
	v_max_u32_e32 v90, v66, v74
	v_min_u32_e32 v66, v66, v74
	v_max_u32_e32 v74, v75, v67
	v_min_u32_e32 v67, v75, v67
	v_max_u32_e32 v75, v68, v76
	v_min_u32_e32 v68, v68, v76
	v_max_u32_e32 v76, v77, v69
	v_min_u32_e32 v69, v77, v69
	v_max_u32_e32 v77, v62, v78
	v_min_u32_e32 v62, v62, v78
	v_max_u32_e32 v78, v79, v63
	v_min_u32_e32 v63, v79, v63
	v_max_u32_e32 v79, v64, v80
	v_min_u32_e32 v64, v64, v80
	v_max_u32_e32 v80, v81, v65
	v_min_u32_e32 v65, v81, v65
	v_max_u32_e32 v98, v70, v82
	v_min_u32_e32 v70, v70, v82
	v_max_u32_e32 v82, v83, v71
	v_min_u32_e32 v71, v83, v71
	v_max_u32_e32 v83, v72, v84
	v_min_u32_e32 v72, v72, v84
	v_max_u32_e32 v84, v85, v73
	v_min_u32_e32 v73, v85, v73
	v_max_u32_e32 v85, v0, v86
	v_min_u32_e32 v0, v0, v86
	v_max_u32_e32 v86, v87, v1
	v_min_u32_e32 v1, v87, v1
	v_max_u32_e32 v87, v2, v88
	v_min_u32_e32 v2, v2, v88
	v_max_u32_e32 v88, v89, v3
	v_min_u32_e32 v3, v89, v3
	v_max_u32_e32 v81, v90, v67
	v_min_u32_e32 v67, v90, v67
	v_max_u32_e32 v90, v66, v74
	v_min_u32_e32 v66, v66, v74
	v_max_u32_e32 v74, v69, v75
	v_min_u32_e32 v69, v69, v75
	v_max_u32_e32 v75, v76, v68
	v_min_u32_e32 v68, v76, v68
; #define CE_DESC(a, b) do { const unsigned _mx = (a) > (b) ? (a) : (b), _mn = (a) > (b) ? (b) : (a); (a) = _mx; (b) = _mn; } while (0)
; __device__ __forceinline__ void sort16_desc(unsigned (&k)[16]) {
; #pragma unroll
;     for (int size = 2; size <= 16; size <<= 1)
; #pragma unroll
;         for (int stride = size >> 1; stride > 0; stride >>= 1)
; #pragma unroll
;             for (int i = 0; i < 16; ++i) { const int j = i ^ stride;
;                 if (j > i) { if ((i & size) == 0) CE_DESC(k[i], k[j]); else CE_DESC(k[j], k[i]); } }
; }
	v_max_u32_e32 v76, v77, v63
	v_min_u32_e32 v63, v77, v63
	v_max_u32_e32 v77, v62, v78
	v_min_u32_e32 v62, v62, v78
	v_max_u32_e32 v78, v65, v79
	v_min_u32_e32 v65, v65, v79
	v_max_u32_e32 v79, v80, v64
	v_min_u32_e32 v64, v80, v64
	v_max_u32_e32 v89, v98, v71
	v_min_u32_e32 v71, v98, v71
	v_max_u32_e32 v98, v70, v82
	v_min_u32_e32 v70, v70, v82
	v_max_u32_e32 v82, v73, v83
	v_min_u32_e32 v73, v73, v83
	v_max_u32_e32 v83, v84, v72
	v_min_u32_e32 v72, v84, v72
	v_max_u32_e32 v84, v85, v1
	v_min_u32_e32 v1, v85, v1
	v_max_u32_e32 v85, v0, v86
	v_min_u32_e32 v0, v0, v86
	v_max_u32_e32 v86, v3, v87
	v_min_u32_e32 v3, v3, v87
	v_max_u32_e32 v87, v88, v2
	v_min_u32_e32 v2, v88, v2
	v_max_u32_e32 v80, v81, v90
	v_min_u32_e32 v81, v81, v90
	v_max_u32_e32 v90, v67, v66
	v_min_u32_e32 v66, v67, v66
	v_max_u32_e32 v67, v68, v69
	v_min_u32_e32 v68, v68, v69
	v_max_u32_e32 v69, v75, v74
	v_min_u32_e32 v74, v75, v74
	v_max_u32_e32 v75, v76, v77
	v_min_u32_e32 v76, v76, v77
	v_max_u32_e32 v77, v63, v62
	v_min_u32_e32 v62, v63, v62
	v_max_u32_e32 v63, v64, v65
	v_min_u32_e32 v64, v64, v65
	v_max_u32_e32 v65, v79, v78
	v_min_u32_e32 v78, v79, v78
	v_max_u32_e32 v88, v89, v98
	v_min_u32_e32 v89, v89, v98
	v_max_u32_e32 v98, v71, v70
	v_min_u32_e32 v70, v71, v70
	v_max_u32_e32 v71, v72, v73
	v_min_u32_e32 v72, v72, v73
	v_max_u32_e32 v73, v83, v82
	v_min_u32_e32 v82, v83, v82
	v_max_u32_e32 v83, v84, v85
	v_min_u32_e32 v84, v84, v85
	v_max_u32_e32 v85, v1, v0
	v_min_u32_e32 v0, v1, v0
	v_max_u32_e32 v1, v2, v3
	v_min_u32_e32 v2, v2, v3
	v_max_u32_e32 v3, v87, v86
	v_min_u32_e32 v86, v87, v86
	v_max_u32_e32 v79, v80, v68
	v_min_u32_e32 v68, v80, v68
	v_max_u32_e32 v80, v81, v67
	v_min_u32_e32 v67, v81, v67
	v_max_u32_e32 v81, v90, v74
	v_min_u32_e32 v74, v90, v74
	v_max_u32_e32 v90, v66, v69
	v_min_u32_e32 v66, v66, v69
	v_max_u32_e32 v69, v64, v75
	v_min_u32_e32 v64, v64, v75
	v_max_u32_e32 v75, v63, v76
	v_min_u32_e32 v63, v63, v76
	v_max_u32_e32 v76, v78, v77
	v_min_u32_e32 v77, v78, v77
	v_max_u32_e32 v78, v65, v62
	v_min_u32_e32 v62, v65, v62
	v_max_u32_e32 v87, v88, v72
	v_min_u32_e32 v72, v88, v72
	v_max_u32_e32 v88, v89, v71
	v_min_u32_e32 v71, v89, v71
	v_max_u32_e32 v89, v98, v82
	v_min_u32_e32 v82, v98, v82
	v_max_u32_e32 v98, v70, v73
	v_min_u32_e32 v70, v70, v73
	v_max_u32_e32 v73, v2, v83
	v_min_u32_e32 v2, v2, v83
	v_max_u32_e32 v83, v1, v84
	v_min_u32_e32 v1, v1, v84
	v_max_u32_e32 v84, v86, v85
	v_min_u32_e32 v85, v86, v85
	v_max_u32_e32 v86, v3, v0
	v_min_u32_e32 v0, v3, v0
	v_max_u32_e32 v65, v79, v81
	v_min_u32_e32 v79, v79, v81
	v_max_u32_e32 v81, v80, v90
	v_min_u32_e32 v80, v80, v90
	v_max_u32_e32 v90, v68, v74
	v_min_u32_e32 v68, v68, v74
	v_max_u32_e32 v74, v67, v66
	v_min_u32_e32 v66, v67, v66
	v_max_u32_e32 v67, v77, v64
	v_min_u32_e32 v64, v77, v64
	v_max_u32_e32 v77, v62, v63
	v_min_u32_e32 v62, v62, v63
	v_max_u32_e32 v63, v76, v69
	v_min_u32_e32 v69, v76, v69
	v_max_u32_e32 v76, v78, v75
	v_min_u32_e32 v75, v78, v75
	v_max_u32_e32 v3, v87, v89
	v_min_u32_e32 v87, v87, v89
	v_max_u32_e32 v89, v88, v98
	v_min_u32_e32 v88, v88, v98
	v_max_u32_e32 v98, v72, v82
	v_min_u32_e32 v72, v72, v82
	v_max_u32_e32 v82, v71, v70
	v_min_u32_e32 v70, v71, v70
	v_max_u32_e32 v71, v85, v2
	v_min_u32_e32 v2, v85, v2
	v_max_u32_e32 v85, v0, v1
	v_min_u32_e32 v0, v0, v1
	v_max_u32_e32 v1, v84, v73
	v_min_u32_e32 v73, v84, v73
	v_max_u32_e32 v84, v86, v83
	v_min_u32_e32 v83, v86, v83
	v_max_u32_e32 v78, v65, v81
	v_min_u32_e32 v65, v65, v81
	v_max_u32_e32 v81, v79, v80
	v_min_u32_e32 v79, v79, v80
	v_max_u32_e32 v80, v90, v74
	v_min_u32_e32 v74, v90, v74
	v_max_u32_e32 v90, v68, v66
	v_min_u32_e32 v66, v68, v66
	v_max_u32_e32 v68, v62, v64
	v_min_u32_e32 v62, v62, v64
	v_max_u32_e32 v64, v77, v67
	v_min_u32_e32 v67, v77, v67
	v_max_u32_e32 v77, v75, v69
	v_min_u32_e32 v69, v75, v69
	v_max_u32_e32 v75, v76, v63
	v_min_u32_e32 v63, v76, v63
	v_max_u32_e32 v86, v3, v89
	v_min_u32_e32 v3, v3, v89
	v_max_u32_e32 v89, v87, v88
	v_min_u32_e32 v87, v87, v88
	v_max_u32_e32 v88, v98, v82
	v_min_u32_e32 v82, v98, v82
	v_max_u32_e32 v98, v72, v70
	v_min_u32_e32 v70, v72, v70
	v_max_u32_e32 v72, v0, v2
	v_min_u32_e32 v0, v0, v2
	v_max_u32_e32 v2, v85, v71
	v_min_u32_e32 v71, v85, v71
	v_max_u32_e32 v85, v83, v73
	v_min_u32_e32 v73, v83, v73
	v_max_u32_e32 v83, v84, v1
	v_min_u32_e32 v1, v84, v1
	v_max_u32_e32 v76, v78, v62
	v_min_u32_e32 v62, v78, v62
	v_max_u32_e32 v78, v65, v68
	v_min_u32_e32 v65, v65, v68
	v_max_u32_e32 v68, v81, v67
	v_min_u32_e32 v67, v81, v67
	v_max_u32_e32 v81, v79, v64
	v_min_u32_e32 v64, v79, v64
	v_max_u32_e32 v79, v80, v69
	v_min_u32_e32 v69, v80, v69
	v_max_u32_e32 v80, v74, v77
	v_min_u32_e32 v74, v74, v77
	v_max_u32_e32 v77, v90, v63
	v_min_u32_e32 v63, v90, v63
	v_max_u32_e32 v90, v66, v75
	v_min_u32_e32 v66, v66, v75
	v_max_u32_e32 v84, v86, v0
	v_min_u32_e32 v0, v86, v0
	v_max_u32_e32 v86, v3, v72
	v_min_u32_e32 v3, v3, v72
	v_max_u32_e32 v72, v89, v71
	v_min_u32_e32 v71, v89, v71
	v_max_u32_e32 v89, v87, v2
	v_min_u32_e32 v2, v87, v2
	v_max_u32_e32 v87, v88, v73
	v_min_u32_e32 v73, v88, v73
	v_max_u32_e32 v88, v82, v85
	v_min_u32_e32 v82, v82, v85
	v_max_u32_e32 v85, v98, v1
	v_min_u32_e32 v1, v98, v1
	v_max_u32_e32 v98, v70, v83
	v_min_u32_e32 v70, v70, v83
	v_max_u32_e32 v75, v76, v79
	v_min_u32_e32 v76, v76, v79
	v_max_u32_e32 v79, v78, v80
	v_min_u32_e32 v78, v78, v80
	v_max_u32_e32 v80, v68, v77
	v_min_u32_e32 v68, v68, v77
	v_max_u32_e32 v77, v81, v90
	v_min_u32_e32 v81, v81, v90
	v_max_u32_e32 v90, v62, v69
	v_min_u32_e32 v62, v62, v69
	v_max_u32_e32 v69, v65, v74
	v_min_u32_e32 v65, v65, v74
	v_max_u32_e32 v74, v67, v63
; #define CE_DESC(a, b) do { const unsigned _mx = (a) > (b) ? (a) : (b), _mn = (a) > (b) ? (b) : (a); (a) = _mx; (b) = _mn; } while (0)
; __device__ __forceinline__ void merge16(unsigned (&a)[16], const unsigned (&b)[16]) {
; #pragma unroll
;     for (int i = 0; i < 16; ++i) a[i] = a[i] > b[15 - i] ? a[i] : b[15 - i];
; #pragma unroll
;     for (int stride = 8; stride > 0; stride >>= 1)
; #pragma unroll
;         for (int i = 0; i < 16; ++i) { const int j = i ^ stride; if (j > i) CE_DESC(a[i], a[j]); }
; }
; __device__ __forceinline__ void peer_tile(const Args& A, LAS unsigned char* lds, int tile) {
;     ...
;                 for (int msk = 16; msk <= 32; msk <<= 1) {
; #pragma unroll
;                     for (int i = 0; i < 16; ++i) k1[i] = (unsigned)__shfl_xor((int)k0[i], msk);
;                     merge16(k0, k1); }
	v_min_u32_e32 v63, v67, v63
	v_max_u32_e32 v67, v64, v66
	v_min_u32_e32 v64, v64, v66
	v_max_u32_e32 v83, v84, v87
	v_min_u32_e32 v84, v84, v87
	v_max_u32_e32 v87, v86, v88
	v_min_u32_e32 v86, v86, v88
	v_max_u32_e32 v88, v72, v85
	v_min_u32_e32 v72, v72, v85
	v_max_u32_e32 v85, v89, v98
	v_min_u32_e32 v89, v89, v98
	v_max_u32_e32 v98, v0, v73
	v_min_u32_e32 v0, v0, v73
	v_max_u32_e32 v73, v3, v82
	v_min_u32_e32 v3, v3, v82
	v_max_u32_e32 v82, v71, v1
	v_min_u32_e32 v1, v71, v1
	v_max_u32_e32 v71, v2, v70
	v_min_u32_e32 v2, v2, v70
	v_max_u32_e32 v66, v75, v80
	v_min_u32_e32 v75, v75, v80
	v_max_u32_e32 v80, v79, v77
	v_min_u32_e32 v77, v79, v77
	v_max_u32_e32 v79, v76, v68
	v_min_u32_e32 v68, v76, v68
	v_max_u32_e32 v76, v78, v81
	v_min_u32_e32 v78, v78, v81
	v_max_u32_e32 v81, v90, v74
	v_min_u32_e32 v74, v90, v74
	v_max_u32_e32 v90, v69, v67
	v_min_u32_e32 v67, v69, v67
	v_max_u32_e32 v69, v62, v63
	v_min_u32_e32 v62, v62, v63
	v_max_u32_e32 v63, v65, v64
	v_min_u32_e32 v64, v65, v64
	v_max_u32_e32 v70, v83, v88
	v_min_u32_e32 v83, v83, v88
	v_max_u32_e32 v88, v87, v85
	v_min_u32_e32 v85, v87, v85
	v_max_u32_e32 v87, v84, v72
	v_min_u32_e32 v72, v84, v72
	v_max_u32_e32 v84, v86, v89
	v_min_u32_e32 v86, v86, v89
	v_max_u32_e32 v89, v98, v82
	v_min_u32_e32 v82, v98, v82
	v_max_u32_e32 v98, v73, v71
	v_min_u32_e32 v71, v73, v71
	v_max_u32_e32 v73, v0, v1
	v_min_u32_e32 v0, v0, v1
	v_max_u32_e32 v1, v3, v2
	v_min_u32_e32 v2, v3, v2
	v_min_u32_e32 v65, v66, v80
	v_min_u32_e32 v91, v75, v77
	v_min_u32_e32 v92, v79, v76
	v_min_u32_e32 v93, v68, v78
	v_min_u32_e32 v94, v81, v90
	v_min_u32_e32 v95, v74, v67
	v_min_u32_e32 v96, v69, v63
	v_min_u32_e32 v97, v62, v64
	v_min_u32_e32 v3, v70, v88
	v_min_u32_e32 v99, v83, v85
	v_min_u32_e32 v100, v87, v84
	v_min_u32_e32 v101, v72, v86
	v_min_u32_e32 v102, v89, v98
	v_min_u32_e32 v103, v82, v71
	v_min_u32_e32 v104, v73, v1
	v_min_u32_e32 v105, v0, v2
	v_max3_u32 v66, v66, v80, v105
	v_max3_u32 v0, v65, v0, v2
	v_max3_u32 v2, v75, v77, v104
	v_max3_u32 v1, v91, v73, v1
	v_max3_u32 v65, v79, v76, v103
	v_max3_u32 v71, v92, v82, v71
	v_max3_u32 v68, v68, v78, v102
	v_max3_u32 v73, v93, v89, v98
	v_max3_u32 v75, v81, v90, v101
	v_max3_u32 v72, v94, v72, v86
	v_max3_u32 v67, v74, v67, v100
	v_max3_u32 v74, v95, v87, v84
	v_max3_u32 v63, v69, v63, v99
	v_max3_u32 v69, v96, v83, v85
	v_max3_u32 v3, v62, v64, v3
	v_max3_u32 v62, v97, v70, v88
	v_max_u32_e32 v64, v66, v75
	v_min_u32_e32 v66, v66, v75
	v_max_u32_e32 v70, v0, v72
	v_min_u32_e32 v0, v0, v72
	v_max_u32_e32 v72, v2, v67
	v_min_u32_e32 v2, v2, v67
	v_max_u32_e32 v67, v1, v74
	v_min_u32_e32 v1, v1, v74
	v_max_u32_e32 v74, v65, v63
	v_min_u32_e32 v63, v65, v63
	v_max_u32_e32 v65, v71, v69
	v_min_u32_e32 v69, v71, v69
	v_max_u32_e32 v71, v68, v3
	v_min_u32_e32 v3, v68, v3
	v_max_u32_e32 v68, v73, v62
	v_min_u32_e32 v62, v73, v62
	v_max_u32_e32 v73, v64, v74
	v_min_u32_e32 v64, v64, v74
	v_max_u32_e32 v74, v70, v65
	v_min_u32_e32 v65, v70, v65
	v_max_u32_e32 v70, v72, v71
	v_min_u32_e32 v71, v72, v71
	v_max_u32_e32 v72, v67, v68
	v_min_u32_e32 v67, v67, v68
	v_max_u32_e32 v68, v66, v63
	v_min_u32_e32 v63, v66, v63
	v_max_u32_e32 v66, v0, v69
	v_min_u32_e32 v0, v0, v69
	v_max_u32_e32 v69, v2, v3
	v_min_u32_e32 v2, v2, v3
	v_max_u32_e32 v3, v1, v62
	v_min_u32_e32 v1, v1, v62
	v_max_u32_e32 v62, v73, v70
	v_min_u32_e32 v70, v73, v70
	v_max_u32_e32 v73, v74, v72
	v_min_u32_e32 v72, v74, v72
	v_max_u32_e32 v74, v64, v71
	v_min_u32_e32 v64, v64, v71
	v_max_u32_e32 v71, v65, v67
	v_min_u32_e32 v65, v65, v67
	v_max_u32_e32 v67, v68, v69
	v_min_u32_e32 v68, v68, v69
	v_max_u32_e32 v69, v66, v3
	v_min_u32_e32 v3, v66, v3
	v_max_u32_e32 v66, v63, v2
	v_min_u32_e32 v2, v63, v2
	v_max_u32_e32 v63, v0, v1
	v_min_u32_e32 v0, v0, v1
	v_max_u32_e32 v1, v62, v73
	v_min_u32_e32 v62, v62, v73
	v_max_u32_e32 v73, v70, v72
	v_min_u32_e32 v70, v70, v72
	v_max_u32_e32 v72, v74, v71
	v_min_u32_e32 v71, v74, v71
	v_max_u32_e32 v74, v64, v65
	v_min_u32_e32 v64, v64, v65
	v_max_u32_e32 v65, v67, v69
	v_min_u32_e32 v67, v67, v69
	v_max_u32_e32 v69, v68, v3
	v_min_u32_e32 v3, v68, v3
	v_max_u32_e32 v68, v66, v63
	v_min_u32_e32 v63, v66, v63
	v_max_u32_e32 v66, v2, v0
	v_min_u32_e32 v0, v2, v0
	ds_bpermute_b32 v2, v27, v1
	ds_bpermute_b32 v75, v27, v62
	ds_bpermute_b32 v76, v27, v73
	ds_bpermute_b32 v77, v27, v70
	ds_bpermute_b32 v78, v27, v72
	ds_bpermute_b32 v79, v27, v71
	ds_bpermute_b32 v80, v27, v74
	ds_bpermute_b32 v81, v27, v64
	ds_bpermute_b32 v82, v27, v65
	ds_bpermute_b32 v83, v27, v67
	ds_bpermute_b32 v84, v27, v69
	ds_bpermute_b32 v85, v27, v0
	ds_bpermute_b32 v86, v27, v66
	ds_bpermute_b32 v87, v27, v63
	ds_bpermute_b32 v88, v27, v68
	ds_bpermute_b32 v89, v27, v3
	s_waitcnt lgkmcnt(4)
	v_max_u32_e32 v1, v1, v85
	s_waitcnt lgkmcnt(3)
	v_max_u32_e32 v62, v62, v86
	s_waitcnt lgkmcnt(2)
	v_max_u32_e32 v73, v73, v87
	s_waitcnt lgkmcnt(1)
	v_max_u32_e32 v70, v70, v88
	s_waitcnt lgkmcnt(0)
; __device__ __forceinline__ void peer_tile(const Args& A, LAS unsigned char* lds, int tile) {
;     ...
;                 { const bf16_t* sp = QRY + m * 2048 + hp * 128 + 32 * g;
;                   const u32x4 s0 = *(const u32x4*)sp, s1 = *(const u32x4*)(sp + 8), s2 = *(const u32x4*)(sp + 16), s3 = *(const u32x4*)(sp + 24);
;     ...
;                 for (int msk = 16; msk <= 32; msk <<= 1) {
; #pragma unroll
;                     for (int i = 0; i < 16; ++i) k1[i] = (unsigned)__shfl_xor((int)k0[i], msk);
;                     merge16(k0, k1); }
	v_max_u32_e32 v72, v72, v89
	v_max_u32_e32 v71, v71, v84
	v_max_u32_e32 v74, v74, v83
	v_max_u32_e32 v64, v64, v82
	v_max_u32_e32 v65, v65, v81
	v_max_u32_e32 v67, v67, v80
	v_max_u32_e32 v69, v69, v79
	v_max_u32_e32 v3, v3, v78
	v_max_u32_e32 v68, v68, v77
	v_max_u32_e32 v63, v63, v76
	v_max_u32_e32 v66, v66, v75
	v_max_u32_e32 v0, v0, v2
	v_max_u32_e32 v2, v1, v65
	v_min_u32_e32 v1, v1, v65
	v_max_u32_e32 v65, v62, v67
	v_min_u32_e32 v62, v62, v67
	v_max_u32_e32 v67, v73, v69
	v_min_u32_e32 v69, v73, v69
	v_max_u32_e32 v73, v70, v3
	v_min_u32_e32 v3, v70, v3
	v_max_u32_e32 v70, v72, v68
	v_min_u32_e32 v68, v72, v68
	v_max_u32_e32 v72, v71, v63
	v_min_u32_e32 v63, v71, v63
	v_max_u32_e32 v71, v74, v66
	v_min_u32_e32 v66, v74, v66
	v_max_u32_e32 v74, v64, v0
	v_min_u32_e32 v0, v64, v0
	v_max_u32_e32 v64, v2, v70
	v_min_u32_e32 v2, v2, v70
	v_max_u32_e32 v70, v65, v72
	v_min_u32_e32 v65, v65, v72
	v_max_u32_e32 v72, v67, v71
	v_min_u32_e32 v67, v67, v71
	v_max_u32_e32 v71, v73, v74
	v_min_u32_e32 v73, v73, v74
	v_max_u32_e32 v74, v1, v68
	v_min_u32_e32 v1, v1, v68
	v_max_u32_e32 v68, v62, v63
	v_min_u32_e32 v62, v62, v63
	v_max_u32_e32 v63, v69, v66
	v_min_u32_e32 v66, v69, v66
	v_max_u32_e32 v69, v3, v0
	v_min_u32_e32 v0, v3, v0
	v_max_u32_e32 v3, v64, v72
	v_min_u32_e32 v64, v64, v72
	v_max_u32_e32 v72, v70, v71
	v_min_u32_e32 v70, v70, v71
	v_max_u32_e32 v71, v2, v67
	v_min_u32_e32 v2, v2, v67
	v_max_u32_e32 v67, v65, v73
	v_min_u32_e32 v65, v65, v73
	v_max_u32_e32 v73, v74, v63
	v_min_u32_e32 v63, v74, v63
	v_max_u32_e32 v74, v68, v69
	v_min_u32_e32 v68, v68, v69
	v_max_u32_e32 v69, v1, v66
	v_min_u32_e32 v1, v1, v66
	v_max_u32_e32 v66, v62, v0
	v_min_u32_e32 v0, v62, v0
	v_max_u32_e32 v62, v3, v72
	v_min_u32_e32 v3, v3, v72
	v_max_u32_e32 v72, v64, v70
	v_min_u32_e32 v64, v64, v70
	v_max_u32_e32 v70, v71, v67
	v_min_u32_e32 v67, v71, v67
	v_max_u32_e32 v71, v2, v65
	v_min_u32_e32 v2, v2, v65
	v_max_u32_e32 v65, v73, v74
	v_min_u32_e32 v73, v73, v74
	v_max_u32_e32 v74, v63, v68
	v_min_u32_e32 v63, v63, v68
	v_max_u32_e32 v68, v69, v66
	v_min_u32_e32 v66, v69, v66
	v_max_u32_e32 v69, v1, v0
	v_min_u32_e32 v0, v1, v0
	ds_bpermute_b32 v78, v29, v0
	ds_bpermute_b32 v1, v29, v62
	ds_bpermute_b32 v75, v29, v3
	ds_bpermute_b32 v76, v29, v72
	ds_bpermute_b32 v77, v29, v64
	s_waitcnt lgkmcnt(4)
	v_max_u32_e32 v62, v62, v78
	global_load_dwordx4 v[78:81], v[4:5], off offset:784
	global_load_dwordx4 v[82:85], v[4:5], off offset:768
	ds_bpermute_b32 v86, v29, v70
	ds_bpermute_b32 v87, v29, v67
	ds_bpermute_b32 v88, v29, v71
	ds_bpermute_b32 v89, v29, v2
	ds_bpermute_b32 v90, v29, v65
	ds_bpermute_b32 v91, v29, v73
	ds_bpermute_b32 v92, v29, v74
	ds_bpermute_b32 v93, v29, v63
	ds_bpermute_b32 v94, v29, v68
	ds_bpermute_b32 v95, v29, v69
	ds_bpermute_b32 v96, v29, v66
	s_waitcnt lgkmcnt(4)
	v_max_u32_e32 v67, v67, v92
	s_waitcnt lgkmcnt(3)
	v_max_u32_e32 v70, v70, v93
	s_waitcnt lgkmcnt(2)
	v_max_u32_e32 v64, v64, v94
	s_waitcnt lgkmcnt(1)
	v_max_u32_e32 v3, v3, v95
	s_waitcnt lgkmcnt(0)
	v_max_u32_e32 v72, v72, v96
	v_max_u32_e32 v71, v71, v91
	v_max_u32_e32 v2, v2, v90
	v_max_u32_e32 v65, v65, v89
	v_max_u32_e32 v73, v73, v88
	v_max_u32_e32 v74, v74, v87
	v_max_u32_e32 v63, v63, v86
	v_max_u32_e32 v68, v68, v77
	v_max_u32_e32 v66, v66, v76
	v_max_u32_e32 v69, v69, v75
	v_max_u32_e32 v0, v0, v1
	v_max_u32_e32 v1, v62, v65
	v_min_u32_e32 v62, v62, v65
	v_max_u32_e32 v65, v3, v73
	v_min_u32_e32 v3, v3, v73
	v_max_u32_e32 v73, v72, v74
	v_min_u32_e32 v72, v72, v74
	v_max_u32_e32 v74, v64, v63
	v_min_u32_e32 v63, v64, v63
	v_max_u32_e32 v64, v70, v68
	v_min_u32_e32 v68, v70, v68
	v_max_u32_e32 v70, v67, v66
	v_min_u32_e32 v66, v67, v66
	v_max_u32_e32 v67, v71, v69
	v_min_u32_e32 v69, v71, v69
	v_max_u32_e32 v71, v2, v0
	v_min_u32_e32 v0, v2, v0
	v_max_u32_e32 v2, v1, v64
	v_min_u32_e32 v1, v1, v64
	v_max_u32_e32 v64, v65, v70
	v_min_u32_e32 v65, v65, v70
	v_max_u32_e32 v70, v73, v67
	v_min_u32_e32 v67, v73, v67
	v_max_u32_e32 v73, v74, v71
	v_min_u32_e32 v71, v74, v71
	v_max_u32_e32 v74, v62, v68
	v_min_u32_e32 v62, v62, v68
	v_max_u32_e32 v68, v3, v66
	v_min_u32_e32 v3, v3, v66
	v_max_u32_e32 v66, v72, v69
	v_min_u32_e32 v69, v72, v69
	v_max_u32_e32 v72, v63, v0
	v_min_u32_e32 v0, v63, v0
	v_max_u32_e32 v63, v2, v70
	v_min_u32_e32 v2, v2, v70
	v_max_u32_e32 v70, v64, v73
	v_min_u32_e32 v64, v64, v73
	v_max_u32_e32 v86, v1, v67
	v_min_u32_e32 v1, v1, v67
	v_max_u32_e32 v67, v65, v71
	v_min_u32_e32 v65, v65, v71
	v_max_u32_e32 v87, v74, v66
	v_min_u32_e32 v66, v74, v66
	v_max_u32_e32 v88, v68, v72
	v_min_u32_e32 v89, v68, v72
	v_max_u32_e32 v90, v62, v69
	v_min_u32_e32 v62, v62, v69
	v_max_u32_e32 v91, v3, v0
	v_min_u32_e32 v0, v3, v0
	v_max_u32_e32 v77, v63, v70
	v_min_u32_e32 v76, v63, v70
	v_max_u32_e32 v75, v2, v64
	v_min_u32_e32 v74, v2, v64
	v_max_u32_e32 v73, v86, v67
	v_min_u32_e32 v72, v86, v67
	v_max_u32_e32 v71, v1, v65
	v_min_u32_e32 v70, v1, v65
	v_max_u32_e32 v69, v87, v88
	v_min_u32_e32 v68, v87, v88
	v_max_u32_e32 v67, v66, v89
	v_min_u32_e32 v66, v66, v89
	v_max_u32_e32 v63, v62, v0
	v_min_u32_e32 v62, v62, v0
	global_load_dwordx4 v[0:3], v[4:5], off offset:816
	global_load_dwordx4 v[86:89], v[4:5], off offset:800
	v_max_u32_e32 v65, v90, v91
	v_min_u32_e32 v64, v90, v91
	s_waitcnt vmcnt(2)
; __device__ __forceinline__ unsigned f2key(float f) { const unsigned u = __float_as_uint(f); return (u & 0x80000000u) ? ~u : (u | 0x80000000u); }
; __device__ __forceinline__ void peer_tile(const Args& A, LAS unsigned char* lds, int tile) {
;     ...
;                   for (int i = 0; i < 16; ++i) {
;                       const float lo = (float)__builtin_bit_cast(_Float16, (unsigned short)(sw[i] & 0xffffu)), hi = (float)__builtin_bit_cast(_Float16, (unsigned short)(sw[i] >> 16));
;                       const unsigned klo = (f2key(lo) & ~127u) | (unsigned)(127 - (32 * g + 2 * i)), khi = (f2key(hi) & ~127u) | (unsigned)(127 - (32 * g + 2 * i + 1));
;                       if (i < 8) { k0[2 * i] = klo; k0[2 * i + 1] = khi; } else { k1[2 * (i - 8)] = klo; k1[2 * (i - 8) + 1] = khi; } } }
;     ...
;                 for (int i = 0; i < 16; ++i) L2[p][i] = (g & 2) ? ((g & 1) ? LA[3][p][i] : LA[2][p][i]) : ((g & 1) ? LA[1][p][i] : LA[0][p][i]);
	v_cvt_f32_f16_sdwa v90, v82 dst_sel:DWORD dst_unused:UNUSED_PAD src0_sel:WORD_1
	v_cvt_f32_f16_e32 v82, v82
	v_cndmask_b32_e64 v38, v70, v38, s[0:1]
	v_cndmask_b32_e64 v37, v69, v37, s[0:1]
	v_not_b32_e32 v91, v90
	v_or_b32_e32 v92, 0x80000000, v90
	v_cmp_gt_i32_e32 vcc, 0, v90
	v_cndmask_b32_e64 v36, v68, v36, s[0:1]
	v_cndmask_b32_e64 v35, v67, v35, s[0:1]
	v_cndmask_b32_e32 v90, v92, v91, vcc
	v_not_b32_e32 v91, v82
	v_or_b32_e32 v92, 0x80000000, v82
	v_cmp_gt_i32_e32 vcc, 0, v82
	v_and_b32_e32 v90, 0xffffff80, v90
	v_sub_u32_e32 v90, v90, v15
	v_cndmask_b32_e32 v82, v92, v91, vcc
	v_cvt_f32_f16_sdwa v91, v83 dst_sel:DWORD dst_unused:UNUSED_PAD src0_sel:WORD_1
	v_cvt_f32_f16_e32 v83, v83
	v_and_b32_e32 v82, 0xffffff80, v82
	v_sub_u32_e32 v82, v82, v15
	v_not_b32_e32 v92, v91
	v_or_b32_e32 v93, 0x80000000, v91
	v_cmp_gt_i32_e32 vcc, 0, v91
	v_add_u32_e32 v90, 0x7e, v90
	v_add_u32_e32 v82, 0x7f, v82
	v_cndmask_b32_e32 v91, v93, v92, vcc
	v_not_b32_e32 v92, v83
	v_or_b32_e32 v93, 0x80000000, v83
	v_cmp_gt_i32_e32 vcc, 0, v83
	v_and_b32_e32 v91, 0xffffff80, v91
	v_sub_u32_e32 v91, v91, v14
	v_cndmask_b32_e32 v83, v93, v92, vcc
	v_cvt_f32_f16_sdwa v92, v84 dst_sel:DWORD dst_unused:UNUSED_PAD src0_sel:WORD_1
	v_cvt_f32_f16_e32 v84, v84
	v_and_b32_e32 v83, 0xffffff80, v83
	v_sub_u32_e32 v83, v83, v14
	v_not_b32_e32 v93, v92
	v_or_b32_e32 v94, 0x80000000, v92
	v_cmp_gt_i32_e32 vcc, 0, v92
	v_add_u32_e32 v91, 0x7e, v91
	v_add_u32_e32 v83, 0x7f, v83
	v_cndmask_b32_e32 v92, v94, v93, vcc
	v_not_b32_e32 v93, v84
	v_or_b32_e32 v94, 0x80000000, v84
	v_cmp_gt_i32_e32 vcc, 0, v84
	v_and_b32_e32 v92, 0xffffff80, v92
	v_sub_u32_e32 v92, v92, v12
	v_cndmask_b32_e32 v84, v94, v93, vcc
	v_cvt_f32_f16_sdwa v93, v85 dst_sel:DWORD dst_unused:UNUSED_PAD src0_sel:WORD_1
	v_cvt_f32_f16_e32 v85, v85
	v_and_b32_e32 v84, 0xffffff80, v84
	v_sub_u32_e32 v84, v84, v12
	v_not_b32_e32 v94, v93
	v_or_b32_e32 v95, 0x80000000, v93
	v_cmp_gt_i32_e32 vcc, 0, v93
	v_add_u32_e32 v92, 0x7e, v92
	v_add_u32_e32 v84, 0x7f, v84
	v_cndmask_b32_e32 v93, v95, v94, vcc
	v_not_b32_e32 v94, v85
	v_or_b32_e32 v95, 0x80000000, v85
	v_cmp_gt_i32_e32 vcc, 0, v85
	v_and_b32_e32 v93, 0xffffff80, v93
	v_sub_u32_e32 v93, v93, v10
	v_cndmask_b32_e32 v85, v95, v94, vcc
	v_cvt_f32_f16_sdwa v94, v78 dst_sel:DWORD dst_unused:UNUSED_PAD src0_sel:WORD_1
	v_cvt_f32_f16_e32 v78, v78
	v_and_b32_e32 v85, 0xffffff80, v85
	v_sub_u32_e32 v85, v85, v10
	v_not_b32_e32 v95, v94
	v_or_b32_e32 v96, 0x80000000, v94
	v_cmp_gt_i32_e32 vcc, 0, v94
	v_add_u32_e32 v93, 0x7e, v93
	v_add_u32_e32 v85, 0x7f, v85
	v_cndmask_b32_e32 v94, v96, v95, vcc
	v_not_b32_e32 v95, v78
	v_or_b32_e32 v96, 0x80000000, v78
	v_cmp_gt_i32_e32 vcc, 0, v78
	v_and_b32_e32 v94, 0xffffff80, v94
	v_sub_u32_e32 v94, v94, v8
	v_cndmask_b32_e32 v78, v96, v95, vcc
	v_cvt_f32_f16_sdwa v95, v79 dst_sel:DWORD dst_unused:UNUSED_PAD src0_sel:WORD_1
	v_cvt_f32_f16_e32 v79, v79
	v_and_b32_e32 v78, 0xffffff80, v78
	v_sub_u32_e32 v78, v78, v8
	v_not_b32_e32 v96, v95
	v_or_b32_e32 v97, 0x80000000, v95
	v_cmp_gt_i32_e32 vcc, 0, v95
	v_add_u32_e32 v94, 0x7e, v94
	v_add_u32_e32 v78, 0x7f, v78
	v_cndmask_b32_e32 v95, v97, v96, vcc
	v_not_b32_e32 v96, v79
	v_or_b32_e32 v97, 0x80000000, v79
	v_cmp_gt_i32_e32 vcc, 0, v79
	v_and_b32_e32 v95, 0xffffff80, v95
	v_sub_u32_e32 v95, v95, v16
	v_cndmask_b32_e32 v79, v97, v96, vcc
	v_cvt_f32_f16_sdwa v96, v80 dst_sel:DWORD dst_unused:UNUSED_PAD src0_sel:WORD_1
	v_cvt_f32_f16_e32 v80, v80
	v_and_b32_e32 v79, 0xffffff80, v79
	v_sub_u32_e32 v79, v79, v16
	v_not_b32_e32 v97, v96
	v_or_b32_e32 v98, 0x80000000, v96
	v_cmp_gt_i32_e32 vcc, 0, v96
	v_add_u32_e32 v95, 0x7e, v95
	v_add_u32_e32 v79, 0x7f, v79
	v_cndmask_b32_e32 v96, v98, v97, vcc
	v_not_b32_e32 v97, v80
	v_or_b32_e32 v98, 0x80000000, v80
	v_cmp_gt_i32_e32 vcc, 0, v80
	v_and_b32_e32 v96, 0xffffff80, v96
	v_sub_u32_e32 v96, v96, v17
	v_cndmask_b32_e32 v80, v98, v97, vcc
	v_cvt_f32_f16_sdwa v97, v81 dst_sel:DWORD dst_unused:UNUSED_PAD src0_sel:WORD_1
	v_cvt_f32_f16_e32 v81, v81
	v_and_b32_e32 v80, 0xffffff80, v80
	v_sub_u32_e32 v80, v80, v17
	v_not_b32_e32 v98, v97
	v_or_b32_e32 v99, 0x80000000, v97
	v_cmp_gt_i32_e32 vcc, 0, v97
	v_add_u32_e32 v96, 0x7e, v96
	v_add_u32_e32 v80, 0x7f, v80
	v_cndmask_b32_e32 v97, v99, v98, vcc
	v_not_b32_e32 v98, v81
	v_or_b32_e32 v99, 0x80000000, v81
	v_cmp_gt_i32_e32 vcc, 0, v81
	v_and_b32_e32 v97, 0xffffff80, v97
	v_sub_u32_e32 v97, v97, v18
	v_cndmask_b32_e32 v81, v99, v98, vcc
	s_waitcnt vmcnt(0)
; __device__ __forceinline__ unsigned f2key(float f) { const unsigned u = __float_as_uint(f); return (u & 0x80000000u) ? ~u : (u | 0x80000000u); }
; #define CE_DESC(a, b) do { const unsigned _mx = (a) > (b) ? (a) : (b), _mn = (a) > (b) ? (b) : (a); (a) = _mx; (b) = _mn; } while (0)
; __device__ __forceinline__ void sort16_desc(unsigned (&k)[16]) {
; #pragma unroll
;     for (int size = 2; size <= 16; size <<= 1)
; #pragma unroll
;         for (int stride = size >> 1; stride > 0; stride >>= 1)
; #pragma unroll
;             for (int i = 0; i < 16; ++i) { const int j = i ^ stride;
;                 if (j > i) { if ((i & size) == 0) CE_DESC(k[i], k[j]); else CE_DESC(k[j], k[i]); } }
; __device__ __forceinline__ void peer_tile(const Args& A, LAS unsigned char* lds, int tile) {
;     ...
;                   for (int i = 0; i < 16; ++i) {
;                       const float lo = (float)__builtin_bit_cast(_Float16, (unsigned short)(sw[i] & 0xffffu)), hi = (float)__builtin_bit_cast(_Float16, (unsigned short)(sw[i] >> 16));
;                       const unsigned klo = (f2key(lo) & ~127u) | (unsigned)(127 - (32 * g + 2 * i)), khi = (f2key(hi) & ~127u) | (unsigned)(127 - (32 * g + 2 * i + 1));
;                       if (i < 8) { k0[2 * i] = klo; k0[2 * i + 1] = khi; } else { k1[2 * (i - 8)] = klo; k1[2 * (i - 8) + 1] = khi; } } }
	v_cvt_f32_f16_sdwa v98, v86 dst_sel:DWORD dst_unused:UNUSED_PAD src0_sel:WORD_1
	v_cvt_f32_f16_e32 v86, v86
	v_and_b32_e32 v81, 0xffffff80, v81
	v_sub_u32_e32 v81, v81, v18
	v_not_b32_e32 v99, v98
	v_or_b32_e32 v100, 0x80000000, v98
	v_cmp_gt_i32_e32 vcc, 0, v98
	v_add_u32_e32 v97, 0x7e, v97
	v_add_u32_e32 v81, 0x7f, v81
	v_cndmask_b32_e32 v98, v100, v99, vcc
	v_not_b32_e32 v99, v86
	v_or_b32_e32 v100, 0x80000000, v86
	v_cmp_gt_i32_e32 vcc, 0, v86
	v_and_b32_e32 v98, 0xffffff80, v98
	v_sub_u32_e32 v98, v98, v20
	v_cndmask_b32_e32 v86, v100, v99, vcc
	v_cvt_f32_f16_sdwa v99, v87 dst_sel:DWORD dst_unused:UNUSED_PAD src0_sel:WORD_1
	v_cvt_f32_f16_e32 v87, v87
	v_and_b32_e32 v86, 0xffffff80, v86
	v_sub_u32_e32 v86, v86, v20
	v_not_b32_e32 v100, v99
	v_or_b32_e32 v101, 0x80000000, v99
	v_cmp_gt_i32_e32 vcc, 0, v99
	v_add_u32_e32 v98, 0x7e, v98
	v_add_u32_e32 v86, 0x7f, v86
	v_cndmask_b32_e32 v99, v101, v100, vcc
	v_not_b32_e32 v100, v87
	v_or_b32_e32 v101, 0x80000000, v87
	v_cmp_gt_i32_e32 vcc, 0, v87
	v_and_b32_e32 v99, 0xffffff80, v99
	v_sub_u32_e32 v99, v99, v21
	v_cndmask_b32_e32 v87, v101, v100, vcc
	v_cvt_f32_f16_sdwa v100, v88 dst_sel:DWORD dst_unused:UNUSED_PAD src0_sel:WORD_1
	v_cvt_f32_f16_e32 v88, v88
	v_and_b32_e32 v87, 0xffffff80, v87
	v_sub_u32_e32 v87, v87, v21
	v_not_b32_e32 v101, v100
	v_or_b32_e32 v102, 0x80000000, v100
	v_cmp_gt_i32_e32 vcc, 0, v100
	v_add_u32_e32 v99, 0x7e, v99
	v_add_u32_e32 v87, 0x7f, v87
	v_cndmask_b32_e32 v100, v102, v101, vcc
	v_not_b32_e32 v101, v88
	v_or_b32_e32 v102, 0x80000000, v88
	v_cmp_gt_i32_e32 vcc, 0, v88
	v_and_b32_e32 v100, 0xffffff80, v100
	v_sub_u32_e32 v100, v100, v22
	v_cndmask_b32_e32 v88, v102, v101, vcc
	v_cvt_f32_f16_sdwa v101, v89 dst_sel:DWORD dst_unused:UNUSED_PAD src0_sel:WORD_1
	v_cvt_f32_f16_e32 v89, v89
	v_and_b32_e32 v88, 0xffffff80, v88
	v_sub_u32_e32 v88, v88, v22
	v_not_b32_e32 v102, v101
	v_or_b32_e32 v103, 0x80000000, v101
	v_cmp_gt_i32_e32 vcc, 0, v101
	v_add_u32_e32 v100, 0x7e, v100
	v_add_u32_e32 v88, 0x7f, v88
	v_cndmask_b32_e32 v101, v103, v102, vcc
	v_not_b32_e32 v102, v89
	v_or_b32_e32 v103, 0x80000000, v89
	v_cmp_gt_i32_e32 vcc, 0, v89
	v_and_b32_e32 v101, 0xffffff80, v101
	v_sub_u32_e32 v101, v101, v23
	v_cndmask_b32_e32 v89, v103, v102, vcc
	v_cvt_f32_f16_sdwa v102, v0 dst_sel:DWORD dst_unused:UNUSED_PAD src0_sel:WORD_1
	v_cvt_f32_f16_e32 v0, v0
	v_and_b32_e32 v89, 0xffffff80, v89
	v_sub_u32_e32 v89, v89, v23
	v_not_b32_e32 v103, v102
	v_or_b32_e32 v104, 0x80000000, v102
	v_cmp_gt_i32_e32 vcc, 0, v102
	v_add_u32_e32 v101, 0x7e, v101
	v_add_u32_e32 v89, 0x7f, v89
	v_cndmask_b32_e32 v102, v104, v103, vcc
	v_not_b32_e32 v103, v0
	v_or_b32_e32 v104, 0x80000000, v0
	v_cmp_gt_i32_e32 vcc, 0, v0
	v_and_b32_e32 v102, 0xffffff80, v102
	v_sub_u32_e32 v102, v102, v24
	v_cndmask_b32_e32 v0, v104, v103, vcc
	v_cvt_f32_f16_sdwa v103, v1 dst_sel:DWORD dst_unused:UNUSED_PAD src0_sel:WORD_1
	v_cvt_f32_f16_e32 v1, v1
	v_and_b32_e32 v0, 0xffffff80, v0
	v_sub_u32_e32 v0, v0, v24
	v_not_b32_e32 v104, v103
	v_or_b32_e32 v105, 0x80000000, v103
	v_cmp_gt_i32_e32 vcc, 0, v103
	v_add_u32_e32 v102, 0x7e, v102
	v_add_u32_e32 v0, 0x7f, v0
	v_cndmask_b32_e32 v103, v105, v104, vcc
	v_not_b32_e32 v104, v1
	v_or_b32_e32 v105, 0x80000000, v1
	v_cmp_gt_i32_e32 vcc, 0, v1
	v_and_b32_e32 v103, 0xffffff80, v103
	v_sub_u32_e32 v103, v103, v25
	v_cndmask_b32_e32 v1, v105, v104, vcc
	v_cvt_f32_f16_sdwa v104, v2 dst_sel:DWORD dst_unused:UNUSED_PAD src0_sel:WORD_1
	v_cvt_f32_f16_e32 v2, v2
	v_and_b32_e32 v1, 0xffffff80, v1
	v_sub_u32_e32 v1, v1, v25
	v_not_b32_e32 v105, v104
	v_or_b32_e32 v106, 0x80000000, v104
	v_cmp_gt_i32_e32 vcc, 0, v104
	v_add_u32_e32 v103, 0x7e, v103
	v_add_u32_e32 v1, 0x7f, v1
	v_cndmask_b32_e32 v104, v106, v105, vcc
	v_not_b32_e32 v105, v2
	v_or_b32_e32 v106, 0x80000000, v2
	v_cmp_gt_i32_e32 vcc, 0, v2
	v_and_b32_e32 v104, 0xffffff80, v104
	v_sub_u32_e32 v104, v104, v26
	v_cndmask_b32_e32 v2, v106, v105, vcc
	v_cvt_f32_f16_sdwa v105, v3 dst_sel:DWORD dst_unused:UNUSED_PAD src0_sel:WORD_1
	v_cvt_f32_f16_e32 v3, v3
	v_and_b32_e32 v2, 0xffffff80, v2
	v_sub_u32_e32 v2, v2, v26
	v_not_b32_e32 v106, v105
	v_or_b32_e32 v107, 0x80000000, v105
	v_cmp_gt_i32_e32 vcc, 0, v105
	v_add_u32_e32 v104, 0x7e, v104
	v_add_u32_e32 v2, 0x7f, v2
	v_cndmask_b32_e32 v105, v107, v106, vcc
	v_not_b32_e32 v106, v3
	v_or_b32_e32 v107, 0x80000000, v3
	v_cmp_gt_i32_e32 vcc, 0, v3
	v_and_b32_e32 v105, 0xffffff80, v105
	v_sub_u32_e32 v105, v105, v28
	v_cndmask_b32_e32 v3, v107, v106, vcc
	v_and_b32_e32 v3, 0xffffff80, v3
	v_sub_u32_e32 v3, v3, v28
	v_add_u32_e32 v105, 0x7e, v105
	v_add_u32_e32 v3, 0x7f, v3
	v_max_u32_e32 v106, v82, v90
	v_min_u32_e32 v82, v82, v90
	v_max_u32_e32 v90, v91, v83
	v_min_u32_e32 v83, v91, v83
	v_max_u32_e32 v91, v84, v92
	v_min_u32_e32 v84, v84, v92
	v_max_u32_e32 v92, v93, v85
	v_min_u32_e32 v85, v93, v85
	v_max_u32_e32 v93, v78, v94
	v_min_u32_e32 v78, v78, v94
	v_max_u32_e32 v94, v95, v79
	v_min_u32_e32 v79, v95, v79
	v_max_u32_e32 v95, v80, v96
	v_min_u32_e32 v80, v80, v96
	v_max_u32_e32 v96, v97, v81
	v_min_u32_e32 v81, v97, v81
	v_max_u32_e32 v115, v86, v98
	v_min_u32_e32 v86, v86, v98
	v_max_u32_e32 v98, v99, v87
	v_min_u32_e32 v87, v99, v87
	v_max_u32_e32 v99, v88, v100
	v_min_u32_e32 v88, v88, v100
	v_max_u32_e32 v100, v101, v89
	v_min_u32_e32 v89, v101, v89
	v_max_u32_e32 v101, v0, v102
	v_min_u32_e32 v0, v0, v102
	v_max_u32_e32 v102, v103, v1
	v_min_u32_e32 v1, v103, v1
	v_max_u32_e32 v103, v2, v104
	v_min_u32_e32 v2, v2, v104
	v_max_u32_e32 v104, v105, v3
	v_min_u32_e32 v3, v105, v3
	v_max_u32_e32 v97, v106, v83
	v_min_u32_e32 v83, v106, v83
	v_max_u32_e32 v106, v82, v90
; #define CE_DESC(a, b) do { const unsigned _mx = (a) > (b) ? (a) : (b), _mn = (a) > (b) ? (b) : (a); (a) = _mx; (b) = _mn; } while (0)
; __device__ __forceinline__ void sort16_desc(unsigned (&k)[16]) {
; #pragma unroll
;     for (int size = 2; size <= 16; size <<= 1)
; #pragma unroll
;         for (int stride = size >> 1; stride > 0; stride >>= 1)
; #pragma unroll
;             for (int i = 0; i < 16; ++i) { const int j = i ^ stride;
;                 if (j > i) { if ((i & size) == 0) CE_DESC(k[i], k[j]); else CE_DESC(k[j], k[i]); } }
	v_min_u32_e32 v82, v82, v90
	v_max_u32_e32 v90, v85, v91
	v_min_u32_e32 v85, v85, v91
	v_max_u32_e32 v91, v92, v84
	v_min_u32_e32 v84, v92, v84
	v_max_u32_e32 v92, v93, v79
	v_min_u32_e32 v79, v93, v79
	v_max_u32_e32 v93, v78, v94
	v_min_u32_e32 v78, v78, v94
	v_max_u32_e32 v94, v81, v95
	v_min_u32_e32 v81, v81, v95
	v_max_u32_e32 v95, v96, v80
	v_min_u32_e32 v80, v96, v80
	v_max_u32_e32 v105, v115, v87
	v_min_u32_e32 v87, v115, v87
	v_max_u32_e32 v115, v86, v98
	v_min_u32_e32 v86, v86, v98
	v_max_u32_e32 v98, v89, v99
	v_min_u32_e32 v89, v89, v99
	v_max_u32_e32 v99, v100, v88
	v_min_u32_e32 v88, v100, v88
	v_max_u32_e32 v100, v101, v1
	v_min_u32_e32 v1, v101, v1
	v_max_u32_e32 v101, v0, v102
	v_min_u32_e32 v0, v0, v102
	v_max_u32_e32 v102, v3, v103
	v_min_u32_e32 v3, v3, v103
	v_max_u32_e32 v103, v104, v2
	v_min_u32_e32 v2, v104, v2
	v_max_u32_e32 v96, v97, v106
	v_min_u32_e32 v97, v97, v106
	v_max_u32_e32 v106, v83, v82
	v_min_u32_e32 v82, v83, v82
	v_max_u32_e32 v83, v84, v85
	v_min_u32_e32 v84, v84, v85
	v_max_u32_e32 v85, v91, v90
	v_min_u32_e32 v90, v91, v90
	v_max_u32_e32 v91, v92, v93
	v_min_u32_e32 v92, v92, v93
	v_max_u32_e32 v93, v79, v78
	v_min_u32_e32 v78, v79, v78
	v_max_u32_e32 v79, v80, v81
	v_min_u32_e32 v80, v80, v81
	v_max_u32_e32 v81, v95, v94
	v_min_u32_e32 v94, v95, v94
	v_max_u32_e32 v104, v105, v115
	v_min_u32_e32 v105, v105, v115
	v_max_u32_e32 v115, v87, v86
	v_min_u32_e32 v86, v87, v86
	v_max_u32_e32 v87, v88, v89
	v_min_u32_e32 v88, v88, v89
	v_max_u32_e32 v89, v99, v98
	v_min_u32_e32 v98, v99, v98
	v_max_u32_e32 v99, v100, v101
	v_min_u32_e32 v100, v100, v101
	v_max_u32_e32 v101, v1, v0
	v_min_u32_e32 v0, v1, v0
	v_max_u32_e32 v1, v2, v3
	v_min_u32_e32 v2, v2, v3
	v_max_u32_e32 v3, v103, v102
	v_min_u32_e32 v102, v103, v102
	v_max_u32_e32 v95, v96, v84
	v_min_u32_e32 v84, v96, v84
	v_max_u32_e32 v96, v97, v83
	v_min_u32_e32 v83, v97, v83
	v_max_u32_e32 v97, v106, v90
	v_min_u32_e32 v90, v106, v90
	v_max_u32_e32 v106, v82, v85
	v_min_u32_e32 v82, v82, v85
	v_max_u32_e32 v85, v80, v91
	v_min_u32_e32 v80, v80, v91
	v_max_u32_e32 v91, v79, v92
	v_min_u32_e32 v79, v79, v92
	v_max_u32_e32 v92, v94, v93
	v_min_u32_e32 v93, v94, v93
	v_max_u32_e32 v94, v81, v78
	v_min_u32_e32 v78, v81, v78
	v_max_u32_e32 v103, v104, v88
	v_min_u32_e32 v88, v104, v88
	v_max_u32_e32 v104, v105, v87
	v_min_u32_e32 v87, v105, v87
	v_max_u32_e32 v105, v115, v98
	v_min_u32_e32 v98, v115, v98
	v_max_u32_e32 v115, v86, v89
	v_min_u32_e32 v86, v86, v89
	v_max_u32_e32 v89, v2, v99
	v_min_u32_e32 v2, v2, v99
	v_max_u32_e32 v99, v1, v100
	v_min_u32_e32 v1, v1, v100
	v_max_u32_e32 v100, v102, v101
	v_min_u32_e32 v101, v102, v101
	v_max_u32_e32 v102, v3, v0
	v_min_u32_e32 v0, v3, v0
	v_max_u32_e32 v81, v95, v97
	v_min_u32_e32 v95, v95, v97
	v_max_u32_e32 v97, v96, v106
	v_min_u32_e32 v96, v96, v106
	v_max_u32_e32 v106, v84, v90
	v_min_u32_e32 v84, v84, v90
	v_max_u32_e32 v90, v83, v82
	v_min_u32_e32 v82, v83, v82
	v_max_u32_e32 v83, v93, v80
	v_min_u32_e32 v80, v93, v80
	v_max_u32_e32 v93, v78, v79
	v_min_u32_e32 v78, v78, v79
	v_max_u32_e32 v79, v92, v85
	v_min_u32_e32 v85, v92, v85
	v_max_u32_e32 v92, v94, v91
	v_min_u32_e32 v91, v94, v91
	v_max_u32_e32 v3, v103, v105
	v_min_u32_e32 v103, v103, v105
	v_max_u32_e32 v105, v104, v115
	v_min_u32_e32 v104, v104, v115
	v_max_u32_e32 v115, v88, v98
	v_min_u32_e32 v88, v88, v98
	v_max_u32_e32 v98, v87, v86
	v_min_u32_e32 v86, v87, v86
	v_max_u32_e32 v87, v101, v2
	v_min_u32_e32 v2, v101, v2
	v_max_u32_e32 v101, v0, v1
	v_min_u32_e32 v0, v0, v1
	v_max_u32_e32 v1, v100, v89
	v_min_u32_e32 v89, v100, v89
	v_max_u32_e32 v100, v102, v99
	v_min_u32_e32 v99, v102, v99
	v_max_u32_e32 v94, v81, v97
	v_min_u32_e32 v81, v81, v97
	v_max_u32_e32 v97, v95, v96
	v_min_u32_e32 v95, v95, v96
	v_max_u32_e32 v96, v106, v90
	v_min_u32_e32 v90, v106, v90
	v_max_u32_e32 v106, v84, v82
	v_min_u32_e32 v82, v84, v82
	v_max_u32_e32 v84, v78, v80
	v_min_u32_e32 v78, v78, v80
	v_max_u32_e32 v80, v93, v83
	v_min_u32_e32 v83, v93, v83
	v_max_u32_e32 v93, v91, v85
	v_min_u32_e32 v85, v91, v85
	v_max_u32_e32 v91, v92, v79
	v_min_u32_e32 v79, v92, v79
	v_max_u32_e32 v102, v3, v105
	v_min_u32_e32 v3, v3, v105
	v_max_u32_e32 v105, v103, v104
	v_min_u32_e32 v103, v103, v104
	v_max_u32_e32 v104, v115, v98
	v_min_u32_e32 v98, v115, v98
	v_max_u32_e32 v115, v88, v86
	v_min_u32_e32 v86, v88, v86
	v_max_u32_e32 v88, v0, v2
	v_min_u32_e32 v0, v0, v2
	v_max_u32_e32 v2, v101, v87
	v_min_u32_e32 v87, v101, v87
	v_max_u32_e32 v101, v99, v89
	v_min_u32_e32 v89, v99, v89
	v_max_u32_e32 v99, v100, v1
	v_min_u32_e32 v1, v100, v1
	v_max_u32_e32 v92, v94, v78
	v_min_u32_e32 v78, v94, v78
	v_max_u32_e32 v94, v81, v84
	v_min_u32_e32 v81, v81, v84
	v_max_u32_e32 v84, v97, v83
	v_min_u32_e32 v83, v97, v83
	v_max_u32_e32 v97, v95, v80
	v_min_u32_e32 v80, v95, v80
	v_max_u32_e32 v95, v96, v85
	v_min_u32_e32 v85, v96, v85
	v_max_u32_e32 v96, v90, v93
	v_min_u32_e32 v90, v90, v93
	v_max_u32_e32 v93, v106, v79
	v_min_u32_e32 v79, v106, v79
	v_max_u32_e32 v106, v82, v91
	v_min_u32_e32 v82, v82, v91
	v_max_u32_e32 v100, v102, v0
	v_min_u32_e32 v0, v102, v0
	v_max_u32_e32 v102, v3, v88
	v_min_u32_e32 v3, v3, v88
	v_max_u32_e32 v88, v105, v87
	v_min_u32_e32 v87, v105, v87
	v_max_u32_e32 v105, v103, v2
	v_min_u32_e32 v2, v103, v2
	v_max_u32_e32 v103, v104, v89
	v_min_u32_e32 v89, v104, v89
	v_max_u32_e32 v104, v98, v101
	v_min_u32_e32 v98, v98, v101
	v_max_u32_e32 v101, v115, v1
	v_min_u32_e32 v1, v115, v1
	v_max_u32_e32 v115, v86, v99
	v_min_u32_e32 v86, v86, v99
	v_max_u32_e32 v91, v92, v95
	v_min_u32_e32 v92, v92, v95
	v_max_u32_e32 v95, v94, v96
; #define CE_DESC(a, b) do { const unsigned _mx = (a) > (b) ? (a) : (b), _mn = (a) > (b) ? (b) : (a); (a) = _mx; (b) = _mn; } while (0)
; __device__ __forceinline__ void sort16_desc(unsigned (&k)[16]) {
; #pragma unroll
;     for (int size = 2; size <= 16; size <<= 1)
; #pragma unroll
;         for (int stride = size >> 1; stride > 0; stride >>= 1)
; #pragma unroll
;             for (int i = 0; i < 16; ++i) { const int j = i ^ stride;
;                 if (j > i) { if ((i & size) == 0) CE_DESC(k[i], k[j]); else CE_DESC(k[j], k[i]); } }
; }
; __device__ __forceinline__ void merge16(unsigned (&a)[16], const unsigned (&b)[16]) {
; #pragma unroll
;     for (int i = 0; i < 16; ++i) a[i] = a[i] > b[15 - i] ? a[i] : b[15 - i];
; #pragma unroll
;     for (int stride = 8; stride > 0; stride >>= 1)
; #pragma unroll
;         for (int i = 0; i < 16; ++i) { const int j = i ^ stride; if (j > i) CE_DESC(a[i], a[j]); }
; }
; __device__ __forceinline__ void peer_tile(const Args& A, LAS unsigned char* lds, int tile) {
;     ...
;                 for (int msk = 16; msk <= 32; msk <<= 1) {
; #pragma unroll
;                     for (int i = 0; i < 16; ++i) k1[i] = (unsigned)__shfl_xor((int)k0[i], msk);
;                     merge16(k0, k1); }
	v_min_u32_e32 v94, v94, v96
	v_max_u32_e32 v96, v84, v93
	v_min_u32_e32 v84, v84, v93
	v_max_u32_e32 v93, v97, v106
	v_min_u32_e32 v97, v97, v106
	v_max_u32_e32 v106, v78, v85
	v_min_u32_e32 v78, v78, v85
	v_max_u32_e32 v85, v81, v90
	v_min_u32_e32 v81, v81, v90
	v_max_u32_e32 v90, v83, v79
	v_min_u32_e32 v79, v83, v79
	v_max_u32_e32 v83, v80, v82
	v_min_u32_e32 v80, v80, v82
	v_max_u32_e32 v99, v100, v103
	v_min_u32_e32 v100, v100, v103
	v_max_u32_e32 v103, v102, v104
	v_min_u32_e32 v102, v102, v104
	v_max_u32_e32 v104, v88, v101
	v_min_u32_e32 v88, v88, v101
	v_max_u32_e32 v101, v105, v115
	v_min_u32_e32 v105, v105, v115
	v_max_u32_e32 v115, v0, v89
	v_min_u32_e32 v0, v0, v89
	v_max_u32_e32 v89, v3, v98
	v_min_u32_e32 v3, v3, v98
	v_max_u32_e32 v98, v87, v1
	v_min_u32_e32 v1, v87, v1
	v_max_u32_e32 v87, v2, v86
	v_min_u32_e32 v2, v2, v86
	v_max_u32_e32 v82, v91, v96
	v_min_u32_e32 v91, v91, v96
	v_max_u32_e32 v96, v95, v93
	v_min_u32_e32 v93, v95, v93
	v_max_u32_e32 v95, v92, v84
	v_min_u32_e32 v84, v92, v84
	v_max_u32_e32 v92, v94, v97
	v_min_u32_e32 v94, v94, v97
	v_max_u32_e32 v97, v106, v90
	v_min_u32_e32 v90, v106, v90
	v_max_u32_e32 v106, v85, v83
	v_min_u32_e32 v83, v85, v83
	v_max_u32_e32 v85, v78, v79
	v_min_u32_e32 v78, v78, v79
	v_max_u32_e32 v79, v81, v80
	v_min_u32_e32 v80, v81, v80
	v_max_u32_e32 v86, v99, v104
	v_min_u32_e32 v99, v99, v104
	v_max_u32_e32 v104, v103, v101
	v_min_u32_e32 v101, v103, v101
	v_max_u32_e32 v103, v100, v88
	v_min_u32_e32 v88, v100, v88
	v_max_u32_e32 v100, v102, v105
	v_min_u32_e32 v102, v102, v105
	v_max_u32_e32 v105, v115, v98
	v_min_u32_e32 v98, v115, v98
	v_max_u32_e32 v115, v89, v87
	v_min_u32_e32 v87, v89, v87
	v_max_u32_e32 v89, v0, v1
	v_min_u32_e32 v0, v0, v1
	v_max_u32_e32 v1, v3, v2
	v_min_u32_e32 v2, v3, v2
	v_min_u32_e32 v81, v82, v96
	v_min_u32_e32 v107, v91, v93
	v_min_u32_e32 v108, v95, v92
	v_min_u32_e32 v109, v84, v94
	v_min_u32_e32 v110, v97, v106
	v_min_u32_e32 v111, v90, v83
	v_min_u32_e32 v112, v85, v79
	v_min_u32_e32 v114, v78, v80
	v_min_u32_e32 v3, v86, v104
	v_min_u32_e32 v116, v99, v101
	v_min_u32_e32 v117, v103, v100
	v_min_u32_e32 v118, v88, v102
	v_min_u32_e32 v119, v105, v115
	v_min_u32_e32 v120, v98, v87
	v_min_u32_e32 v121, v89, v1
	v_min_u32_e32 v122, v0, v2
	v_max3_u32 v82, v82, v96, v122
	v_max3_u32 v0, v81, v0, v2
	v_max3_u32 v2, v91, v93, v121
	v_max3_u32 v1, v107, v89, v1
	v_max3_u32 v81, v95, v92, v120
	v_max3_u32 v87, v108, v98, v87
	v_max3_u32 v84, v84, v94, v119
	v_max3_u32 v89, v109, v105, v115
	v_max3_u32 v91, v97, v106, v118
	v_max3_u32 v88, v110, v88, v102
	v_max3_u32 v83, v90, v83, v117
	v_max3_u32 v90, v111, v103, v100
	v_max3_u32 v79, v85, v79, v116
	v_max3_u32 v85, v112, v99, v101
	v_max3_u32 v3, v78, v80, v3
	v_max3_u32 v78, v114, v86, v104
	v_max_u32_e32 v80, v82, v91
	v_min_u32_e32 v82, v82, v91
	v_max_u32_e32 v86, v0, v88
	v_min_u32_e32 v0, v0, v88
	v_max_u32_e32 v88, v2, v83
	v_min_u32_e32 v2, v2, v83
	v_max_u32_e32 v83, v1, v90
	v_min_u32_e32 v1, v1, v90
	v_max_u32_e32 v90, v81, v79
	v_min_u32_e32 v79, v81, v79
	v_max_u32_e32 v81, v87, v85
	v_min_u32_e32 v85, v87, v85
	v_max_u32_e32 v87, v84, v3
	v_min_u32_e32 v3, v84, v3
	v_max_u32_e32 v84, v89, v78
	v_min_u32_e32 v78, v89, v78
	v_max_u32_e32 v89, v80, v90
	v_min_u32_e32 v80, v80, v90
	v_max_u32_e32 v90, v86, v81
	v_min_u32_e32 v81, v86, v81
	v_max_u32_e32 v86, v88, v87
	v_min_u32_e32 v87, v88, v87
	v_max_u32_e32 v88, v83, v84
	v_min_u32_e32 v83, v83, v84
	v_max_u32_e32 v84, v82, v79
	v_min_u32_e32 v79, v82, v79
	v_max_u32_e32 v82, v0, v85
	v_min_u32_e32 v0, v0, v85
	v_max_u32_e32 v85, v2, v3
	v_min_u32_e32 v2, v2, v3
	v_max_u32_e32 v3, v1, v78
	v_min_u32_e32 v1, v1, v78
	v_max_u32_e32 v78, v89, v86
	v_min_u32_e32 v86, v89, v86
	v_max_u32_e32 v89, v90, v88
	v_min_u32_e32 v88, v90, v88
	v_max_u32_e32 v90, v80, v87
	v_min_u32_e32 v80, v80, v87
	v_max_u32_e32 v87, v81, v83
	v_min_u32_e32 v81, v81, v83
	v_max_u32_e32 v83, v84, v85
	v_min_u32_e32 v84, v84, v85
	v_max_u32_e32 v85, v82, v3
	v_min_u32_e32 v3, v82, v3
	v_max_u32_e32 v82, v79, v2
	v_min_u32_e32 v2, v79, v2
	v_max_u32_e32 v79, v0, v1
	v_min_u32_e32 v0, v0, v1
	v_max_u32_e32 v1, v78, v89
	v_min_u32_e32 v78, v78, v89
	v_max_u32_e32 v89, v86, v88
	v_min_u32_e32 v86, v86, v88
	v_max_u32_e32 v88, v90, v87
	v_min_u32_e32 v87, v90, v87
	v_max_u32_e32 v90, v80, v81
	v_min_u32_e32 v80, v80, v81
	v_max_u32_e32 v81, v83, v85
	v_min_u32_e32 v83, v83, v85
	v_max_u32_e32 v85, v84, v3
	v_min_u32_e32 v3, v84, v3
	v_max_u32_e32 v84, v82, v79
	v_min_u32_e32 v79, v82, v79
	v_max_u32_e32 v82, v2, v0
	v_min_u32_e32 v0, v2, v0
	ds_bpermute_b32 v2, v27, v1
	ds_bpermute_b32 v91, v27, v78
	ds_bpermute_b32 v92, v27, v89
	ds_bpermute_b32 v93, v27, v86
	ds_bpermute_b32 v94, v27, v88
	ds_bpermute_b32 v95, v27, v87
	ds_bpermute_b32 v96, v27, v90
	ds_bpermute_b32 v97, v27, v80
	ds_bpermute_b32 v98, v27, v81
	ds_bpermute_b32 v99, v27, v83
	ds_bpermute_b32 v100, v27, v85
	ds_bpermute_b32 v101, v27, v0
	ds_bpermute_b32 v102, v27, v82
	ds_bpermute_b32 v103, v27, v79
	ds_bpermute_b32 v104, v27, v84
	ds_bpermute_b32 v105, v27, v3
	s_waitcnt lgkmcnt(4)
	v_max_u32_e32 v1, v1, v101
	s_waitcnt lgkmcnt(3)
	v_max_u32_e32 v78, v78, v102
	s_waitcnt lgkmcnt(2)
	v_max_u32_e32 v89, v89, v103
	s_waitcnt lgkmcnt(1)
	v_max_u32_e32 v86, v86, v104
	s_waitcnt lgkmcnt(0)
; __device__ __forceinline__ unsigned f2key(float f) { const unsigned u = __float_as_uint(f); return (u & 0x80000000u) ? ~u : (u | 0x80000000u); }
; #define CE_DESC(a, b) do { const unsigned _mx = (a) > (b) ? (a) : (b), _mn = (a) > (b) ? (b) : (a); (a) = _mx; (b) = _mn; } while (0)
; __device__ __forceinline__ void merge16(unsigned (&a)[16], const unsigned (&b)[16]) {
; #pragma unroll
;     for (int i = 0; i < 16; ++i) a[i] = a[i] > b[15 - i] ? a[i] : b[15 - i];
; #pragma unroll
;     for (int stride = 8; stride > 0; stride >>= 1)
; #pragma unroll
;         for (int i = 0; i < 16; ++i) { const int j = i ^ stride; if (j > i) CE_DESC(a[i], a[j]); }
; }
; __device__ __forceinline__ void peer_tile(const Args& A, LAS unsigned char* lds, int tile) {
;     ...
;                 { const bf16_t* sp = QRY + m * 2048 + hp * 128 + 32 * g;
;                   const u32x4 s0 = *(const u32x4*)sp, s1 = *(const u32x4*)(sp + 8), s2 = *(const u32x4*)(sp + 16), s3 = *(const u32x4*)(sp + 24);
;                   const unsigned sw[16] = {s0.x, s0.y, s0.z, s0.w, s1.x, s1.y, s1.z, s1.w, s2.x, s2.y, s2.z, s2.w, s3.x, s3.y, s3.z, s3.w};
; #pragma unroll
;                   for (int i = 0; i < 16; ++i) {
;                       const float lo = (float)__builtin_bit_cast(_Float16, (unsigned short)(sw[i] & 0xffffu)), hi = (float)__builtin_bit_cast(_Float16, (unsigned short)(sw[i] >> 16));
;                       const unsigned klo = (f2key(lo) & ~127u) | (unsigned)(127 - (32 * g + 2 * i)), khi = (f2key(hi) & ~127u) | (unsigned)(127 - (32 * g + 2 * i + 1));
;                       if (i < 8) { k0[2 * i] = klo; k0[2 * i + 1] = khi; } else { k1[2 * (i - 8)] = klo; k1[2 * (i - 8) + 1] = khi; } } }
;                 sort16_desc(k0); sort16_desc(k1); merge16(k0, k1);
; #pragma unroll
;                 for (int msk = 16; msk <= 32; msk <<= 1) {
; #pragma unroll
;                     for (int i = 0; i < 16; ++i) k1[i] = (unsigned)__shfl_xor((int)k0[i], msk);
;                     merge16(k0, k1); }
	v_max_u32_e32 v88, v88, v105
	v_max_u32_e32 v87, v87, v100
	v_max_u32_e32 v90, v90, v99
	v_max_u32_e32 v80, v80, v98
	v_max_u32_e32 v81, v81, v97
	v_max_u32_e32 v83, v83, v96
	v_max_u32_e32 v85, v85, v95
	v_max_u32_e32 v3, v3, v94
	v_max_u32_e32 v84, v84, v93
	v_max_u32_e32 v79, v79, v92
	v_max_u32_e32 v82, v82, v91
	v_max_u32_e32 v0, v0, v2
	v_max_u32_e32 v2, v1, v81
	v_min_u32_e32 v1, v1, v81
	v_max_u32_e32 v81, v78, v83
	v_min_u32_e32 v78, v78, v83
	v_max_u32_e32 v83, v89, v85
	v_min_u32_e32 v85, v89, v85
	v_max_u32_e32 v89, v86, v3
	v_min_u32_e32 v3, v86, v3
	v_max_u32_e32 v86, v88, v84
	v_min_u32_e32 v84, v88, v84
	v_max_u32_e32 v88, v87, v79
	v_min_u32_e32 v79, v87, v79
	v_max_u32_e32 v87, v90, v82
	v_min_u32_e32 v82, v90, v82
	v_max_u32_e32 v90, v80, v0
	v_min_u32_e32 v0, v80, v0
	v_max_u32_e32 v80, v2, v86
	v_min_u32_e32 v2, v2, v86
	v_max_u32_e32 v86, v81, v88
	v_min_u32_e32 v81, v81, v88
	v_max_u32_e32 v88, v83, v87
	v_min_u32_e32 v83, v83, v87
	v_max_u32_e32 v87, v89, v90
	v_min_u32_e32 v89, v89, v90
	v_max_u32_e32 v90, v1, v84
	v_min_u32_e32 v1, v1, v84
	v_max_u32_e32 v84, v78, v79
	v_min_u32_e32 v78, v78, v79
	v_max_u32_e32 v79, v85, v82
	v_min_u32_e32 v82, v85, v82
	v_max_u32_e32 v85, v3, v0
	v_min_u32_e32 v0, v3, v0
	v_max_u32_e32 v3, v80, v88
	v_min_u32_e32 v80, v80, v88
	v_max_u32_e32 v88, v86, v87
	v_min_u32_e32 v86, v86, v87
	v_max_u32_e32 v87, v2, v83
	v_min_u32_e32 v2, v2, v83
	v_max_u32_e32 v83, v81, v89
	v_min_u32_e32 v81, v81, v89
	v_max_u32_e32 v89, v90, v79
	v_min_u32_e32 v79, v90, v79
	v_max_u32_e32 v90, v84, v85
	v_min_u32_e32 v84, v84, v85
	v_max_u32_e32 v85, v1, v82
	v_min_u32_e32 v1, v1, v82
	v_max_u32_e32 v82, v78, v0
	v_min_u32_e32 v0, v78, v0
	v_max_u32_e32 v78, v3, v88
	v_min_u32_e32 v3, v3, v88
	v_max_u32_e32 v88, v80, v86
	v_min_u32_e32 v80, v80, v86
	v_max_u32_e32 v86, v87, v83
	v_min_u32_e32 v83, v87, v83
	v_max_u32_e32 v87, v2, v81
	v_min_u32_e32 v2, v2, v81
	v_max_u32_e32 v81, v89, v90
	v_min_u32_e32 v89, v89, v90
	v_max_u32_e32 v90, v79, v84
	v_min_u32_e32 v79, v79, v84
	v_max_u32_e32 v84, v85, v82
	v_min_u32_e32 v82, v85, v82
	v_max_u32_e32 v85, v1, v0
	v_min_u32_e32 v0, v1, v0
	ds_bpermute_b32 v94, v29, v0
	ds_bpermute_b32 v1, v29, v78
	ds_bpermute_b32 v91, v29, v3
	ds_bpermute_b32 v92, v29, v88
	ds_bpermute_b32 v93, v29, v80
	s_waitcnt lgkmcnt(4)
	v_max_u32_e32 v78, v78, v94
	global_load_dwordx4 v[94:97], v[4:5], off offset:1040
	global_load_dwordx4 v[98:101], v[4:5], off offset:1024
	ds_bpermute_b32 v102, v29, v86
	ds_bpermute_b32 v103, v29, v83
	ds_bpermute_b32 v104, v29, v87
	ds_bpermute_b32 v105, v29, v2
	ds_bpermute_b32 v106, v29, v81
	ds_bpermute_b32 v107, v29, v89
	ds_bpermute_b32 v108, v29, v90
	ds_bpermute_b32 v109, v29, v79
	ds_bpermute_b32 v110, v29, v84
	ds_bpermute_b32 v111, v29, v85
	ds_bpermute_b32 v112, v29, v82
	s_waitcnt lgkmcnt(4)
	v_max_u32_e32 v83, v83, v108
	s_waitcnt lgkmcnt(3)
	v_max_u32_e32 v86, v86, v109
	s_waitcnt lgkmcnt(2)
	v_max_u32_e32 v80, v80, v110
	s_waitcnt lgkmcnt(1)
	v_max_u32_e32 v3, v3, v111
	s_waitcnt lgkmcnt(0)
	v_max_u32_e32 v88, v88, v112
	v_max_u32_e32 v87, v87, v107
	v_max_u32_e32 v2, v2, v106
	v_max_u32_e32 v81, v81, v105
	v_max_u32_e32 v89, v89, v104
	v_max_u32_e32 v90, v90, v103
	v_max_u32_e32 v79, v79, v102
	v_max_u32_e32 v84, v84, v93
	v_max_u32_e32 v82, v82, v92
	v_max_u32_e32 v85, v85, v91
	v_max_u32_e32 v0, v0, v1
	v_max_u32_e32 v1, v78, v81
	v_min_u32_e32 v78, v78, v81
	v_max_u32_e32 v81, v3, v89
	v_min_u32_e32 v3, v3, v89
	v_max_u32_e32 v89, v88, v90
	v_min_u32_e32 v88, v88, v90
	v_max_u32_e32 v90, v80, v79
	v_min_u32_e32 v79, v80, v79
	v_max_u32_e32 v80, v86, v84
	v_min_u32_e32 v84, v86, v84
	v_max_u32_e32 v86, v83, v82
	v_min_u32_e32 v82, v83, v82
	v_max_u32_e32 v83, v87, v85
	v_min_u32_e32 v85, v87, v85
	v_max_u32_e32 v87, v2, v0
	v_min_u32_e32 v0, v2, v0
	v_max_u32_e32 v2, v1, v80
	v_min_u32_e32 v1, v1, v80
	v_max_u32_e32 v80, v81, v86
	v_min_u32_e32 v81, v81, v86
	v_max_u32_e32 v86, v89, v83
	v_min_u32_e32 v83, v89, v83
	v_max_u32_e32 v89, v90, v87
	v_min_u32_e32 v87, v90, v87
	v_max_u32_e32 v90, v78, v84
	v_min_u32_e32 v78, v78, v84
	v_max_u32_e32 v84, v3, v82
	v_min_u32_e32 v3, v3, v82
	v_max_u32_e32 v82, v88, v85
	v_min_u32_e32 v85, v88, v85
	v_max_u32_e32 v88, v79, v0
	v_min_u32_e32 v0, v79, v0
	v_max_u32_e32 v79, v2, v86
	v_min_u32_e32 v2, v2, v86
	v_max_u32_e32 v86, v80, v89
	v_min_u32_e32 v80, v80, v89
	v_max_u32_e32 v102, v1, v83
	v_min_u32_e32 v1, v1, v83
	v_max_u32_e32 v83, v81, v87
	v_min_u32_e32 v81, v81, v87
	v_max_u32_e32 v103, v90, v82
	v_min_u32_e32 v82, v90, v82
	v_max_u32_e32 v104, v84, v88
	v_min_u32_e32 v105, v84, v88
	v_max_u32_e32 v106, v78, v85
	v_min_u32_e32 v78, v78, v85
	v_max_u32_e32 v107, v3, v0
	v_min_u32_e32 v0, v3, v0
	v_max_u32_e32 v93, v79, v86
	v_min_u32_e32 v92, v79, v86
	v_max_u32_e32 v91, v2, v80
	v_min_u32_e32 v90, v2, v80
	v_max_u32_e32 v89, v102, v83
	v_min_u32_e32 v88, v102, v83
	v_max_u32_e32 v87, v1, v81
	v_min_u32_e32 v86, v1, v81
	v_max_u32_e32 v85, v103, v104
	v_min_u32_e32 v84, v103, v104
	v_max_u32_e32 v83, v82, v105
	v_min_u32_e32 v82, v82, v105
	v_max_u32_e32 v79, v78, v0
	v_min_u32_e32 v78, v78, v0
	global_load_dwordx4 v[0:3], v[4:5], off offset:1072
	global_load_dwordx4 v[102:105], v[4:5], off offset:1056
	v_max_u32_e32 v81, v106, v107
	v_min_u32_e32 v80, v106, v107
	s_waitcnt vmcnt(2)
; __device__ __forceinline__ unsigned f2key(float f) { const unsigned u = __float_as_uint(f); return (u & 0x80000000u) ? ~u : (u | 0x80000000u); }
; __device__ __forceinline__ void peer_tile(const Args& A, LAS unsigned char* lds, int tile) {
;     ...
;                 { const bf16_t* sp = QRY + m * 2048 + hp * 128 + 32 * g;
;                   const u32x4 s0 = *(const u32x4*)sp, s1 = *(const u32x4*)(sp + 8), s2 = *(const u32x4*)(sp + 16), s3 = *(const u32x4*)(sp + 24);
;                   const unsigned sw[16] = {s0.x, s0.y, s0.z, s0.w, s1.x, s1.y, s1.z, s1.w, s2.x, s2.y, s2.z, s2.w, s3.x, s3.y, s3.z, s3.w};
; #pragma unroll
;                   for (int i = 0; i < 16; ++i) {
;                       const float lo = (float)__builtin_bit_cast(_Float16, (unsigned short)(sw[i] & 0xffffu)), hi = (float)__builtin_bit_cast(_Float16, (unsigned short)(sw[i] >> 16));
;                       const unsigned klo = (f2key(lo) & ~127u) | (unsigned)(127 - (32 * g + 2 * i)), khi = (f2key(hi) & ~127u) | (unsigned)(127 - (32 * g + 2 * i + 1));
;                       if (i < 8) { k0[2 * i] = klo; k0[2 * i + 1] = khi; } else { k1[2 * (i - 8)] = klo; k1[2 * (i - 8) + 1] = khi; } } }
;     ...
;                 for (int i = 0; i < 16; ++i) L2[p][i] = (g & 2) ? ((g & 1) ? LA[3][p][i] : LA[2][p][i]) : ((g & 1) ? LA[1][p][i] : LA[0][p][i]);
	v_cvt_f32_f16_sdwa v106, v98 dst_sel:DWORD dst_unused:UNUSED_PAD src0_sel:WORD_1
	v_cvt_f32_f16_e32 v98, v98
	v_cndmask_b32_e64 v34, v66, v34, s[0:1]
	v_cndmask_b32_e64 v33, v65, v33, s[0:1]
	v_not_b32_e32 v107, v106
	v_or_b32_e32 v108, 0x80000000, v106
	v_cmp_gt_i32_e32 vcc, 0, v106
	v_cndmask_b32_e64 v32, v64, v32, s[0:1]
	v_cndmask_b32_e64 v31, v63, v31, s[0:1]
	v_cndmask_b32_e32 v106, v108, v107, vcc
	v_not_b32_e32 v107, v98
	v_or_b32_e32 v108, 0x80000000, v98
	v_cmp_gt_i32_e32 vcc, 0, v98
	v_and_b32_e32 v106, 0xffffff80, v106
	v_sub_u32_e32 v106, v106, v15
	v_cndmask_b32_e32 v98, v108, v107, vcc
	v_cvt_f32_f16_sdwa v107, v99 dst_sel:DWORD dst_unused:UNUSED_PAD src0_sel:WORD_1
	v_cvt_f32_f16_e32 v99, v99
	v_and_b32_e32 v98, 0xffffff80, v98
	v_sub_u32_e32 v98, v98, v15
	v_not_b32_e32 v108, v107
	v_or_b32_e32 v109, 0x80000000, v107
	v_cmp_gt_i32_e32 vcc, 0, v107
	v_add_u32_e32 v106, 0x7e, v106
	v_add_u32_e32 v98, 0x7f, v98
	v_cndmask_b32_e32 v107, v109, v108, vcc
	v_not_b32_e32 v108, v99
	v_or_b32_e32 v109, 0x80000000, v99
	v_cmp_gt_i32_e32 vcc, 0, v99
	v_and_b32_e32 v107, 0xffffff80, v107
	v_sub_u32_e32 v107, v107, v14
	v_cndmask_b32_e32 v99, v109, v108, vcc
	v_cvt_f32_f16_sdwa v108, v100 dst_sel:DWORD dst_unused:UNUSED_PAD src0_sel:WORD_1
	v_cvt_f32_f16_e32 v100, v100
	v_and_b32_e32 v99, 0xffffff80, v99
	v_sub_u32_e32 v99, v99, v14
	v_not_b32_e32 v109, v108
	v_or_b32_e32 v110, 0x80000000, v108
	v_cmp_gt_i32_e32 vcc, 0, v108
	v_add_u32_e32 v107, 0x7e, v107
	v_add_u32_e32 v99, 0x7f, v99
	v_cndmask_b32_e32 v108, v110, v109, vcc
	v_not_b32_e32 v109, v100
	v_or_b32_e32 v110, 0x80000000, v100
	v_cmp_gt_i32_e32 vcc, 0, v100
	v_and_b32_e32 v108, 0xffffff80, v108
	v_sub_u32_e32 v108, v108, v12
	v_cndmask_b32_e32 v100, v110, v109, vcc
	v_cvt_f32_f16_sdwa v109, v101 dst_sel:DWORD dst_unused:UNUSED_PAD src0_sel:WORD_1
	v_cvt_f32_f16_e32 v101, v101
	v_and_b32_e32 v100, 0xffffff80, v100
	v_sub_u32_e32 v100, v100, v12
	v_not_b32_e32 v110, v109
	v_or_b32_e32 v111, 0x80000000, v109
	v_cmp_gt_i32_e32 vcc, 0, v109
	v_add_u32_e32 v108, 0x7e, v108
	v_add_u32_e32 v100, 0x7f, v100
	v_cndmask_b32_e32 v109, v111, v110, vcc
	v_not_b32_e32 v110, v101
	v_or_b32_e32 v111, 0x80000000, v101
	v_cmp_gt_i32_e32 vcc, 0, v101
	v_and_b32_e32 v109, 0xffffff80, v109
	v_sub_u32_e32 v109, v109, v10
	v_cndmask_b32_e32 v101, v111, v110, vcc
	v_cvt_f32_f16_sdwa v110, v94 dst_sel:DWORD dst_unused:UNUSED_PAD src0_sel:WORD_1
	v_cvt_f32_f16_e32 v94, v94
	v_and_b32_e32 v101, 0xffffff80, v101
	v_sub_u32_e32 v101, v101, v10
	v_not_b32_e32 v111, v110
	v_or_b32_e32 v112, 0x80000000, v110
	v_cmp_gt_i32_e32 vcc, 0, v110
	v_add_u32_e32 v109, 0x7e, v109
	v_add_u32_e32 v101, 0x7f, v101
	v_cndmask_b32_e32 v110, v112, v111, vcc
	v_not_b32_e32 v111, v94
	v_or_b32_e32 v112, 0x80000000, v94
	v_cmp_gt_i32_e32 vcc, 0, v94
	v_and_b32_e32 v110, 0xffffff80, v110
	v_sub_u32_e32 v110, v110, v8
	v_cndmask_b32_e32 v94, v112, v111, vcc
	v_cvt_f32_f16_sdwa v111, v95 dst_sel:DWORD dst_unused:UNUSED_PAD src0_sel:WORD_1
	v_cvt_f32_f16_e32 v95, v95
	v_and_b32_e32 v94, 0xffffff80, v94
	v_sub_u32_e32 v94, v94, v8
	v_not_b32_e32 v112, v111
	v_or_b32_e32 v114, 0x80000000, v111
	v_cmp_gt_i32_e32 vcc, 0, v111
	v_add_u32_e32 v110, 0x7e, v110
	v_add_u32_e32 v94, 0x7f, v94
	v_cndmask_b32_e32 v111, v114, v112, vcc
	v_not_b32_e32 v112, v95
	v_or_b32_e32 v114, 0x80000000, v95
	v_cmp_gt_i32_e32 vcc, 0, v95
	v_and_b32_e32 v111, 0xffffff80, v111
	v_sub_u32_e32 v111, v111, v16
	v_cndmask_b32_e32 v95, v114, v112, vcc
	v_cvt_f32_f16_sdwa v112, v96 dst_sel:DWORD dst_unused:UNUSED_PAD src0_sel:WORD_1
	v_cvt_f32_f16_e32 v96, v96
	v_and_b32_e32 v95, 0xffffff80, v95
	v_sub_u32_e32 v95, v95, v16
	v_not_b32_e32 v114, v112
	v_or_b32_e32 v115, 0x80000000, v112
	v_cmp_gt_i32_e32 vcc, 0, v112
	v_add_u32_e32 v111, 0x7e, v111
	v_add_u32_e32 v95, 0x7f, v95
	v_cndmask_b32_e32 v112, v115, v114, vcc
	v_not_b32_e32 v114, v96
	v_or_b32_e32 v115, 0x80000000, v96
	v_cmp_gt_i32_e32 vcc, 0, v96
	v_and_b32_e32 v112, 0xffffff80, v112
	v_sub_u32_e32 v112, v112, v17
	v_cndmask_b32_e32 v96, v115, v114, vcc
	v_cvt_f32_f16_sdwa v114, v97 dst_sel:DWORD dst_unused:UNUSED_PAD src0_sel:WORD_1
	v_cvt_f32_f16_e32 v97, v97
	v_and_b32_e32 v96, 0xffffff80, v96
	v_sub_u32_e32 v96, v96, v17
	v_not_b32_e32 v115, v114
	v_or_b32_e32 v116, 0x80000000, v114
	v_cmp_gt_i32_e32 vcc, 0, v114
	v_add_u32_e32 v112, 0x7e, v112
	v_add_u32_e32 v96, 0x7f, v96
	v_cndmask_b32_e32 v114, v116, v115, vcc
	v_not_b32_e32 v115, v97
	v_or_b32_e32 v116, 0x80000000, v97
	v_cmp_gt_i32_e32 vcc, 0, v97
	v_and_b32_e32 v114, 0xffffff80, v114
	v_sub_u32_e32 v114, v114, v18
	v_cndmask_b32_e32 v97, v116, v115, vcc
	s_waitcnt vmcnt(0)
; __device__ __forceinline__ unsigned f2key(float f) { const unsigned u = __float_as_uint(f); return (u & 0x80000000u) ? ~u : (u | 0x80000000u); }
; #define CE_DESC(a, b) do { const unsigned _mx = (a) > (b) ? (a) : (b), _mn = (a) > (b) ? (b) : (a); (a) = _mx; (b) = _mn; } while (0)
; __device__ __forceinline__ void sort16_desc(unsigned (&k)[16]) {
; #pragma unroll
;     for (int size = 2; size <= 16; size <<= 1)
; #pragma unroll
;         for (int stride = size >> 1; stride > 0; stride >>= 1)
; #pragma unroll
;             for (int i = 0; i < 16; ++i) { const int j = i ^ stride;
;                 if (j > i) { if ((i & size) == 0) CE_DESC(k[i], k[j]); else CE_DESC(k[j], k[i]); } }
; __device__ __forceinline__ void peer_tile(const Args& A, LAS unsigned char* lds, int tile) {
;     ...
;                   for (int i = 0; i < 16; ++i) {
;                       const float lo = (float)__builtin_bit_cast(_Float16, (unsigned short)(sw[i] & 0xffffu)), hi = (float)__builtin_bit_cast(_Float16, (unsigned short)(sw[i] >> 16));
;                       const unsigned klo = (f2key(lo) & ~127u) | (unsigned)(127 - (32 * g + 2 * i)), khi = (f2key(hi) & ~127u) | (unsigned)(127 - (32 * g + 2 * i + 1));
;                       if (i < 8) { k0[2 * i] = klo; k0[2 * i + 1] = khi; } else { k1[2 * (i - 8)] = klo; k1[2 * (i - 8) + 1] = khi; } } }
	v_cvt_f32_f16_sdwa v115, v102 dst_sel:DWORD dst_unused:UNUSED_PAD src0_sel:WORD_1
	v_cvt_f32_f16_e32 v102, v102
	v_and_b32_e32 v97, 0xffffff80, v97
	v_sub_u32_e32 v97, v97, v18
	v_not_b32_e32 v116, v115
	v_or_b32_e32 v117, 0x80000000, v115
	v_cmp_gt_i32_e32 vcc, 0, v115
	v_add_u32_e32 v114, 0x7e, v114
	v_add_u32_e32 v97, 0x7f, v97
	v_cndmask_b32_e32 v115, v117, v116, vcc
	v_not_b32_e32 v116, v102
	v_or_b32_e32 v117, 0x80000000, v102
	v_cmp_gt_i32_e32 vcc, 0, v102
	v_and_b32_e32 v115, 0xffffff80, v115
	v_sub_u32_e32 v115, v115, v20
	v_cndmask_b32_e32 v102, v117, v116, vcc
	v_cvt_f32_f16_sdwa v116, v103 dst_sel:DWORD dst_unused:UNUSED_PAD src0_sel:WORD_1
	v_cvt_f32_f16_e32 v103, v103
	v_and_b32_e32 v102, 0xffffff80, v102
	v_sub_u32_e32 v102, v102, v20
	v_not_b32_e32 v117, v116
	v_or_b32_e32 v118, 0x80000000, v116
	v_cmp_gt_i32_e32 vcc, 0, v116
	v_add_u32_e32 v115, 0x7e, v115
	v_add_u32_e32 v102, 0x7f, v102
	v_cndmask_b32_e32 v116, v118, v117, vcc
	v_not_b32_e32 v117, v103
	v_or_b32_e32 v118, 0x80000000, v103
	v_cmp_gt_i32_e32 vcc, 0, v103
	v_and_b32_e32 v116, 0xffffff80, v116
	v_sub_u32_e32 v116, v116, v21
	v_cndmask_b32_e32 v103, v118, v117, vcc
	v_cvt_f32_f16_sdwa v117, v104 dst_sel:DWORD dst_unused:UNUSED_PAD src0_sel:WORD_1
	v_cvt_f32_f16_e32 v104, v104
	v_and_b32_e32 v103, 0xffffff80, v103
	v_sub_u32_e32 v103, v103, v21
	v_not_b32_e32 v118, v117
	v_or_b32_e32 v119, 0x80000000, v117
	v_cmp_gt_i32_e32 vcc, 0, v117
	v_add_u32_e32 v116, 0x7e, v116
	v_add_u32_e32 v103, 0x7f, v103
	v_cndmask_b32_e32 v117, v119, v118, vcc
	v_not_b32_e32 v118, v104
	v_or_b32_e32 v119, 0x80000000, v104
	v_cmp_gt_i32_e32 vcc, 0, v104
	v_and_b32_e32 v117, 0xffffff80, v117
	v_sub_u32_e32 v117, v117, v22
	v_cndmask_b32_e32 v104, v119, v118, vcc
	v_cvt_f32_f16_sdwa v118, v105 dst_sel:DWORD dst_unused:UNUSED_PAD src0_sel:WORD_1
	v_cvt_f32_f16_e32 v105, v105
	v_and_b32_e32 v104, 0xffffff80, v104
	v_sub_u32_e32 v104, v104, v22
	v_not_b32_e32 v119, v118
	v_or_b32_e32 v120, 0x80000000, v118
	v_cmp_gt_i32_e32 vcc, 0, v118
	v_add_u32_e32 v117, 0x7e, v117
	v_add_u32_e32 v104, 0x7f, v104
	v_cndmask_b32_e32 v118, v120, v119, vcc
	v_not_b32_e32 v119, v105
	v_or_b32_e32 v120, 0x80000000, v105
	v_cmp_gt_i32_e32 vcc, 0, v105
	v_and_b32_e32 v118, 0xffffff80, v118
	v_sub_u32_e32 v118, v118, v23
	v_cndmask_b32_e32 v105, v120, v119, vcc
	v_cvt_f32_f16_sdwa v119, v0 dst_sel:DWORD dst_unused:UNUSED_PAD src0_sel:WORD_1
	v_cvt_f32_f16_e32 v0, v0
	v_and_b32_e32 v105, 0xffffff80, v105
	v_sub_u32_e32 v105, v105, v23
	v_not_b32_e32 v120, v119
	v_or_b32_e32 v121, 0x80000000, v119
	v_cmp_gt_i32_e32 vcc, 0, v119
	v_add_u32_e32 v118, 0x7e, v118
	v_add_u32_e32 v105, 0x7f, v105
	v_cndmask_b32_e32 v119, v121, v120, vcc
	v_not_b32_e32 v120, v0
	v_or_b32_e32 v121, 0x80000000, v0
	v_cmp_gt_i32_e32 vcc, 0, v0
	v_and_b32_e32 v119, 0xffffff80, v119
	v_sub_u32_e32 v119, v119, v24
	v_cndmask_b32_e32 v0, v121, v120, vcc
	v_cvt_f32_f16_sdwa v120, v1 dst_sel:DWORD dst_unused:UNUSED_PAD src0_sel:WORD_1
	v_cvt_f32_f16_e32 v1, v1
	v_and_b32_e32 v0, 0xffffff80, v0
	v_sub_u32_e32 v0, v0, v24
	v_not_b32_e32 v121, v120
	v_or_b32_e32 v122, 0x80000000, v120
	v_cmp_gt_i32_e32 vcc, 0, v120
	v_add_u32_e32 v119, 0x7e, v119
	v_add_u32_e32 v0, 0x7f, v0
	v_cndmask_b32_e32 v120, v122, v121, vcc
	v_not_b32_e32 v121, v1
	v_or_b32_e32 v122, 0x80000000, v1
	v_cmp_gt_i32_e32 vcc, 0, v1
	v_and_b32_e32 v120, 0xffffff80, v120
	v_sub_u32_e32 v120, v120, v25
	v_cndmask_b32_e32 v1, v122, v121, vcc
	v_cvt_f32_f16_sdwa v121, v2 dst_sel:DWORD dst_unused:UNUSED_PAD src0_sel:WORD_1
	v_cvt_f32_f16_e32 v2, v2
	v_and_b32_e32 v1, 0xffffff80, v1
	v_sub_u32_e32 v1, v1, v25
	v_not_b32_e32 v122, v121
	v_or_b32_e32 v123, 0x80000000, v121
	v_cmp_gt_i32_e32 vcc, 0, v121
	v_add_u32_e32 v120, 0x7e, v120
	v_add_u32_e32 v1, 0x7f, v1
	v_cndmask_b32_e32 v121, v123, v122, vcc
	v_not_b32_e32 v122, v2
	v_or_b32_e32 v123, 0x80000000, v2
	v_cmp_gt_i32_e32 vcc, 0, v2
	v_and_b32_e32 v121, 0xffffff80, v121
	v_sub_u32_e32 v121, v121, v26
	v_cndmask_b32_e32 v2, v123, v122, vcc
	v_cvt_f32_f16_sdwa v122, v3 dst_sel:DWORD dst_unused:UNUSED_PAD src0_sel:WORD_1
	v_cvt_f32_f16_e32 v3, v3
	v_and_b32_e32 v2, 0xffffff80, v2
	v_sub_u32_e32 v2, v2, v26
	v_not_b32_e32 v123, v122
	v_or_b32_e32 v124, 0x80000000, v122
	v_cmp_gt_i32_e32 vcc, 0, v122
	v_add_u32_e32 v121, 0x7e, v121
	v_add_u32_e32 v2, 0x7f, v2
	v_cndmask_b32_e32 v122, v124, v123, vcc
	v_not_b32_e32 v123, v3
	v_or_b32_e32 v124, 0x80000000, v3
	v_cmp_gt_i32_e32 vcc, 0, v3
	v_and_b32_e32 v122, 0xffffff80, v122
	v_sub_u32_e32 v122, v122, v28
	v_cndmask_b32_e32 v3, v124, v123, vcc
	v_and_b32_e32 v3, 0xffffff80, v3
	v_sub_u32_e32 v3, v3, v28
	v_add_u32_e32 v122, 0x7e, v122
	v_add_u32_e32 v3, 0x7f, v3
	v_max_u32_e32 v123, v98, v106
	v_min_u32_e32 v98, v98, v106
	v_max_u32_e32 v106, v107, v99
	v_min_u32_e32 v99, v107, v99
	v_max_u32_e32 v107, v100, v108
	v_min_u32_e32 v100, v100, v108
	v_max_u32_e32 v108, v109, v101
	v_min_u32_e32 v101, v109, v101
	v_max_u32_e32 v109, v94, v110
	v_min_u32_e32 v94, v94, v110
	v_max_u32_e32 v110, v111, v95
	v_min_u32_e32 v95, v111, v95
	v_max_u32_e32 v111, v96, v112
	v_min_u32_e32 v96, v96, v112
	v_max_u32_e32 v112, v114, v97
	v_min_u32_e32 v97, v114, v97
	v_max_u32_e32 v131, v102, v115
	v_min_u32_e32 v102, v102, v115
	v_max_u32_e32 v115, v116, v103
	v_min_u32_e32 v103, v116, v103
	v_max_u32_e32 v116, v104, v117
	v_min_u32_e32 v104, v104, v117
	v_max_u32_e32 v117, v118, v105
	v_min_u32_e32 v105, v118, v105
	v_max_u32_e32 v118, v0, v119
	v_min_u32_e32 v0, v0, v119
	v_max_u32_e32 v119, v120, v1
	v_min_u32_e32 v1, v120, v1
	v_max_u32_e32 v120, v2, v121
	v_min_u32_e32 v2, v2, v121
; #define CE_DESC(a, b) do { const unsigned _mx = (a) > (b) ? (a) : (b), _mn = (a) > (b) ? (b) : (a); (a) = _mx; (b) = _mn; } while (0)
; __device__ __forceinline__ void sort16_desc(unsigned (&k)[16]) {
; #pragma unroll
;     for (int size = 2; size <= 16; size <<= 1)
; #pragma unroll
;         for (int stride = size >> 1; stride > 0; stride >>= 1)
; #pragma unroll
;             for (int i = 0; i < 16; ++i) { const int j = i ^ stride;
;                 if (j > i) { if ((i & size) == 0) CE_DESC(k[i], k[j]); else CE_DESC(k[j], k[i]); } }
	v_max_u32_e32 v121, v122, v3
	v_min_u32_e32 v3, v122, v3
	v_max_u32_e32 v114, v123, v99
	v_min_u32_e32 v99, v123, v99
	v_max_u32_e32 v123, v98, v106
	v_min_u32_e32 v98, v98, v106
	v_max_u32_e32 v106, v101, v107
	v_min_u32_e32 v101, v101, v107
	v_max_u32_e32 v107, v108, v100
	v_min_u32_e32 v100, v108, v100
	v_max_u32_e32 v108, v109, v95
	v_min_u32_e32 v95, v109, v95
	v_max_u32_e32 v109, v94, v110
	v_min_u32_e32 v94, v94, v110
	v_max_u32_e32 v110, v97, v111
	v_min_u32_e32 v97, v97, v111
	v_max_u32_e32 v111, v112, v96
	v_min_u32_e32 v96, v112, v96
	v_max_u32_e32 v122, v131, v103
	v_min_u32_e32 v103, v131, v103
	v_max_u32_e32 v131, v102, v115
	v_min_u32_e32 v102, v102, v115
	v_max_u32_e32 v115, v105, v116
	v_min_u32_e32 v105, v105, v116
	v_max_u32_e32 v116, v117, v104
	v_min_u32_e32 v104, v117, v104
	v_max_u32_e32 v117, v118, v1
	v_min_u32_e32 v1, v118, v1
	v_max_u32_e32 v118, v0, v119
	v_min_u32_e32 v0, v0, v119
	v_max_u32_e32 v119, v3, v120
	v_min_u32_e32 v3, v3, v120
	v_max_u32_e32 v120, v121, v2
	v_min_u32_e32 v2, v121, v2
	v_max_u32_e32 v112, v114, v123
	v_min_u32_e32 v114, v114, v123
	v_max_u32_e32 v123, v99, v98
	v_min_u32_e32 v98, v99, v98
	v_max_u32_e32 v99, v100, v101
	v_min_u32_e32 v100, v100, v101
	v_max_u32_e32 v101, v107, v106
	v_min_u32_e32 v106, v107, v106
	v_max_u32_e32 v107, v108, v109
	v_min_u32_e32 v108, v108, v109
	v_max_u32_e32 v109, v95, v94
	v_min_u32_e32 v94, v95, v94
	v_max_u32_e32 v95, v96, v97
	v_min_u32_e32 v96, v96, v97
	v_max_u32_e32 v97, v111, v110
	v_min_u32_e32 v110, v111, v110
	v_max_u32_e32 v121, v122, v131
	v_min_u32_e32 v122, v122, v131
	v_max_u32_e32 v131, v103, v102
	v_min_u32_e32 v102, v103, v102
	v_max_u32_e32 v103, v104, v105
	v_min_u32_e32 v104, v104, v105
	v_max_u32_e32 v105, v116, v115
	v_min_u32_e32 v115, v116, v115
	v_max_u32_e32 v116, v117, v118
	v_min_u32_e32 v117, v117, v118
	v_max_u32_e32 v118, v1, v0
	v_min_u32_e32 v0, v1, v0
	v_max_u32_e32 v1, v2, v3
	v_min_u32_e32 v2, v2, v3
	v_max_u32_e32 v3, v120, v119
	v_min_u32_e32 v119, v120, v119
	v_max_u32_e32 v111, v112, v100
	v_min_u32_e32 v100, v112, v100
	v_max_u32_e32 v112, v114, v99
	v_min_u32_e32 v99, v114, v99
	v_max_u32_e32 v114, v123, v106
	v_min_u32_e32 v106, v123, v106
	v_max_u32_e32 v123, v98, v101
	v_min_u32_e32 v98, v98, v101
	v_max_u32_e32 v101, v96, v107
	v_min_u32_e32 v96, v96, v107
	v_max_u32_e32 v107, v95, v108
	v_min_u32_e32 v95, v95, v108
	v_max_u32_e32 v108, v110, v109
	v_min_u32_e32 v109, v110, v109
	v_max_u32_e32 v110, v97, v94
	v_min_u32_e32 v94, v97, v94
	v_max_u32_e32 v120, v121, v104
	v_min_u32_e32 v104, v121, v104
	v_max_u32_e32 v121, v122, v103
	v_min_u32_e32 v103, v122, v103
	v_max_u32_e32 v122, v131, v115
	v_min_u32_e32 v115, v131, v115
	v_max_u32_e32 v131, v102, v105
	v_min_u32_e32 v102, v102, v105
	v_max_u32_e32 v105, v2, v116
	v_min_u32_e32 v2, v2, v116
	v_max_u32_e32 v116, v1, v117
	v_min_u32_e32 v1, v1, v117
	v_max_u32_e32 v117, v119, v118
	v_min_u32_e32 v118, v119, v118
	v_max_u32_e32 v119, v3, v0
	v_min_u32_e32 v0, v3, v0
	v_max_u32_e32 v97, v111, v114
	v_min_u32_e32 v111, v111, v114
	v_max_u32_e32 v114, v112, v123
	v_min_u32_e32 v112, v112, v123
	v_max_u32_e32 v123, v100, v106
	v_min_u32_e32 v100, v100, v106
	v_max_u32_e32 v106, v99, v98
	v_min_u32_e32 v98, v99, v98
	v_max_u32_e32 v99, v109, v96
	v_min_u32_e32 v96, v109, v96
	v_max_u32_e32 v109, v94, v95
	v_min_u32_e32 v94, v94, v95
	v_max_u32_e32 v95, v108, v101
	v_min_u32_e32 v101, v108, v101
	v_max_u32_e32 v108, v110, v107
	v_min_u32_e32 v107, v110, v107
	v_max_u32_e32 v3, v120, v122
	v_min_u32_e32 v120, v120, v122
	v_max_u32_e32 v122, v121, v131
	v_min_u32_e32 v121, v121, v131
	v_max_u32_e32 v131, v104, v115
	v_min_u32_e32 v104, v104, v115
	v_max_u32_e32 v115, v103, v102
	v_min_u32_e32 v102, v103, v102
	v_max_u32_e32 v103, v118, v2
	v_min_u32_e32 v2, v118, v2
	v_max_u32_e32 v118, v0, v1
	v_min_u32_e32 v0, v0, v1
	v_max_u32_e32 v1, v117, v105
	v_min_u32_e32 v105, v117, v105
	v_max_u32_e32 v117, v119, v116
	v_min_u32_e32 v116, v119, v116
	v_max_u32_e32 v110, v97, v114
	v_min_u32_e32 v97, v97, v114
	v_max_u32_e32 v114, v111, v112
	v_min_u32_e32 v111, v111, v112
	v_max_u32_e32 v112, v123, v106
	v_min_u32_e32 v106, v123, v106
	v_max_u32_e32 v123, v100, v98
	v_min_u32_e32 v98, v100, v98
	v_max_u32_e32 v100, v94, v96
	v_min_u32_e32 v94, v94, v96
	v_max_u32_e32 v96, v109, v99
	v_min_u32_e32 v99, v109, v99
	v_max_u32_e32 v109, v107, v101
	v_min_u32_e32 v101, v107, v101
	v_max_u32_e32 v107, v108, v95
	v_min_u32_e32 v95, v108, v95
	v_max_u32_e32 v119, v3, v122
	v_min_u32_e32 v3, v3, v122
	v_max_u32_e32 v122, v120, v121
	v_min_u32_e32 v120, v120, v121
	v_max_u32_e32 v121, v131, v115
	v_min_u32_e32 v115, v131, v115
	v_max_u32_e32 v131, v104, v102
	v_min_u32_e32 v102, v104, v102
	v_max_u32_e32 v104, v0, v2
	v_min_u32_e32 v0, v0, v2
	v_max_u32_e32 v2, v118, v103
	v_min_u32_e32 v103, v118, v103
	v_max_u32_e32 v118, v116, v105
	v_min_u32_e32 v105, v116, v105
	v_max_u32_e32 v116, v117, v1
	v_min_u32_e32 v1, v117, v1
	v_max_u32_e32 v108, v110, v94
	v_min_u32_e32 v94, v110, v94
	v_max_u32_e32 v110, v97, v100
	v_min_u32_e32 v97, v97, v100
	v_max_u32_e32 v100, v114, v99
	v_min_u32_e32 v99, v114, v99
	v_max_u32_e32 v114, v111, v96
	v_min_u32_e32 v96, v111, v96
	v_max_u32_e32 v111, v112, v101
	v_min_u32_e32 v101, v112, v101
	v_max_u32_e32 v112, v106, v109
	v_min_u32_e32 v106, v106, v109
	v_max_u32_e32 v109, v123, v95
	v_min_u32_e32 v95, v123, v95
	v_max_u32_e32 v123, v98, v107
	v_min_u32_e32 v98, v98, v107
	v_max_u32_e32 v117, v119, v0
	v_min_u32_e32 v0, v119, v0
	v_max_u32_e32 v119, v3, v104
	v_min_u32_e32 v3, v3, v104
	v_max_u32_e32 v104, v122, v103
	v_min_u32_e32 v103, v122, v103
; #define CE_DESC(a, b) do { const unsigned _mx = (a) > (b) ? (a) : (b), _mn = (a) > (b) ? (b) : (a); (a) = _mx; (b) = _mn; } while (0)
; __device__ __forceinline__ void sort16_desc(unsigned (&k)[16]) {
; #pragma unroll
;     for (int size = 2; size <= 16; size <<= 1)
; #pragma unroll
;         for (int stride = size >> 1; stride > 0; stride >>= 1)
; #pragma unroll
;             for (int i = 0; i < 16; ++i) { const int j = i ^ stride;
;                 if (j > i) { if ((i & size) == 0) CE_DESC(k[i], k[j]); else CE_DESC(k[j], k[i]); } }
; }
; __device__ __forceinline__ void merge16(unsigned (&a)[16], const unsigned (&b)[16]) {
; #pragma unroll
;     for (int i = 0; i < 16; ++i) a[i] = a[i] > b[15 - i] ? a[i] : b[15 - i];
; #pragma unroll
;     for (int stride = 8; stride > 0; stride >>= 1)
; #pragma unroll
;         for (int i = 0; i < 16; ++i) { const int j = i ^ stride; if (j > i) CE_DESC(a[i], a[j]); }
; }
; __device__ __forceinline__ void peer_tile(const Args& A, LAS unsigned char* lds, int tile) {
;     ...
;                 for (int msk = 16; msk <= 32; msk <<= 1) {
; #pragma unroll
;                     for (int i = 0; i < 16; ++i) k1[i] = (unsigned)__shfl_xor((int)k0[i], msk);
;                     merge16(k0, k1); }
	v_max_u32_e32 v122, v120, v2
	v_min_u32_e32 v2, v120, v2
	v_max_u32_e32 v120, v121, v105
	v_min_u32_e32 v105, v121, v105
	v_max_u32_e32 v121, v115, v118
	v_min_u32_e32 v115, v115, v118
	v_max_u32_e32 v118, v131, v1
	v_min_u32_e32 v1, v131, v1
	v_max_u32_e32 v131, v102, v116
	v_min_u32_e32 v102, v102, v116
	v_max_u32_e32 v107, v108, v111
	v_min_u32_e32 v108, v108, v111
	v_max_u32_e32 v111, v110, v112
	v_min_u32_e32 v110, v110, v112
	v_max_u32_e32 v112, v100, v109
	v_min_u32_e32 v100, v100, v109
	v_max_u32_e32 v109, v114, v123
	v_min_u32_e32 v114, v114, v123
	v_max_u32_e32 v123, v94, v101
	v_min_u32_e32 v94, v94, v101
	v_max_u32_e32 v101, v97, v106
	v_min_u32_e32 v97, v97, v106
	v_max_u32_e32 v106, v99, v95
	v_min_u32_e32 v95, v99, v95
	v_max_u32_e32 v99, v96, v98
	v_min_u32_e32 v96, v96, v98
	v_max_u32_e32 v116, v117, v120
	v_min_u32_e32 v117, v117, v120
	v_max_u32_e32 v120, v119, v121
	v_min_u32_e32 v119, v119, v121
	v_max_u32_e32 v121, v104, v118
	v_min_u32_e32 v104, v104, v118
	v_max_u32_e32 v118, v122, v131
	v_min_u32_e32 v122, v122, v131
	v_max_u32_e32 v131, v0, v105
	v_min_u32_e32 v0, v0, v105
	v_max_u32_e32 v105, v3, v115
	v_min_u32_e32 v3, v3, v115
	v_max_u32_e32 v115, v103, v1
	v_min_u32_e32 v1, v103, v1
	v_max_u32_e32 v103, v2, v102
	v_min_u32_e32 v2, v2, v102
	v_max_u32_e32 v98, v107, v112
	v_min_u32_e32 v107, v107, v112
	v_max_u32_e32 v112, v111, v109
	v_min_u32_e32 v109, v111, v109
	v_max_u32_e32 v111, v108, v100
	v_min_u32_e32 v100, v108, v100
	v_max_u32_e32 v108, v110, v114
	v_min_u32_e32 v110, v110, v114
	v_max_u32_e32 v114, v123, v106
	v_min_u32_e32 v106, v123, v106
	v_max_u32_e32 v123, v101, v99
	v_min_u32_e32 v99, v101, v99
	v_max_u32_e32 v101, v94, v95
	v_min_u32_e32 v94, v94, v95
	v_max_u32_e32 v95, v97, v96
	v_min_u32_e32 v96, v97, v96
	v_max_u32_e32 v102, v116, v121
	v_min_u32_e32 v116, v116, v121
	v_max_u32_e32 v121, v120, v118
	v_min_u32_e32 v118, v120, v118
	v_max_u32_e32 v120, v117, v104
	v_min_u32_e32 v104, v117, v104
	v_max_u32_e32 v117, v119, v122
	v_min_u32_e32 v119, v119, v122
	v_max_u32_e32 v122, v131, v115
	v_min_u32_e32 v115, v131, v115
	v_max_u32_e32 v131, v105, v103
	v_min_u32_e32 v103, v105, v103
	v_max_u32_e32 v105, v0, v1
	v_min_u32_e32 v0, v0, v1
	v_max_u32_e32 v1, v3, v2
	v_min_u32_e32 v2, v3, v2
	v_min_u32_e32 v97, v98, v112
	v_min_u32_e32 v124, v107, v109
	v_min_u32_e32 v125, v111, v108
	v_min_u32_e32 v126, v100, v110
	v_min_u32_e32 v127, v114, v123
	v_min_u32_e32 v128, v106, v99
	v_min_u32_e32 v129, v101, v95
	v_min_u32_e32 v130, v94, v96
	v_min_u32_e32 v3, v102, v121
	v_min_u32_e32 v132, v116, v118
	v_min_u32_e32 v133, v120, v117
	v_min_u32_e32 v134, v104, v119
	v_min_u32_e32 v135, v122, v131
	v_min_u32_e32 v136, v115, v103
	v_min_u32_e32 v137, v105, v1
	v_min_u32_e32 v138, v0, v2
	v_max3_u32 v98, v98, v112, v138
	v_max3_u32 v0, v97, v0, v2
	v_max3_u32 v2, v107, v109, v137
	v_max3_u32 v1, v124, v105, v1
	v_max3_u32 v97, v111, v108, v136
	v_max3_u32 v103, v125, v115, v103
	v_max3_u32 v100, v100, v110, v135
	v_max3_u32 v105, v126, v122, v131
	v_max3_u32 v107, v114, v123, v134
	v_max3_u32 v104, v127, v104, v119
	v_max3_u32 v99, v106, v99, v133
	v_max3_u32 v106, v128, v120, v117
	v_max3_u32 v95, v101, v95, v132
	v_max3_u32 v101, v129, v116, v118
	v_max3_u32 v3, v94, v96, v3
	v_max3_u32 v94, v130, v102, v121
	v_max_u32_e32 v96, v98, v107
	v_min_u32_e32 v98, v98, v107
	v_max_u32_e32 v102, v0, v104
	v_min_u32_e32 v0, v0, v104
	v_max_u32_e32 v104, v2, v99
	v_min_u32_e32 v2, v2, v99
	v_max_u32_e32 v99, v1, v106
	v_min_u32_e32 v1, v1, v106
	v_max_u32_e32 v106, v97, v95
	v_min_u32_e32 v95, v97, v95
	v_max_u32_e32 v97, v103, v101
	v_min_u32_e32 v101, v103, v101
	v_max_u32_e32 v103, v100, v3
	v_min_u32_e32 v3, v100, v3
	v_max_u32_e32 v100, v105, v94
	v_min_u32_e32 v94, v105, v94
	v_max_u32_e32 v105, v96, v106
	v_min_u32_e32 v96, v96, v106
	v_max_u32_e32 v106, v102, v97
	v_min_u32_e32 v97, v102, v97
	v_max_u32_e32 v102, v104, v103
	v_min_u32_e32 v103, v104, v103
	v_max_u32_e32 v104, v99, v100
	v_min_u32_e32 v99, v99, v100
	v_max_u32_e32 v100, v98, v95
	v_min_u32_e32 v95, v98, v95
	v_max_u32_e32 v98, v0, v101
	v_min_u32_e32 v0, v0, v101
	v_max_u32_e32 v101, v2, v3
	v_min_u32_e32 v2, v2, v3
	v_max_u32_e32 v3, v1, v94
	v_min_u32_e32 v1, v1, v94
	v_max_u32_e32 v94, v105, v102
	v_min_u32_e32 v102, v105, v102
	v_max_u32_e32 v105, v106, v104
	v_min_u32_e32 v104, v106, v104
	v_max_u32_e32 v106, v96, v103
	v_min_u32_e32 v96, v96, v103
	v_max_u32_e32 v103, v97, v99
	v_min_u32_e32 v97, v97, v99
	v_max_u32_e32 v99, v100, v101
	v_min_u32_e32 v100, v100, v101
	v_max_u32_e32 v101, v98, v3
	v_min_u32_e32 v3, v98, v3
	v_max_u32_e32 v98, v95, v2
	v_min_u32_e32 v2, v95, v2
	v_max_u32_e32 v95, v0, v1
	v_min_u32_e32 v0, v0, v1
	v_max_u32_e32 v1, v94, v105
	v_min_u32_e32 v94, v94, v105
	v_max_u32_e32 v105, v102, v104
	v_min_u32_e32 v102, v102, v104
	v_max_u32_e32 v104, v106, v103
	v_min_u32_e32 v103, v106, v103
	v_max_u32_e32 v106, v96, v97
	v_min_u32_e32 v96, v96, v97
	v_max_u32_e32 v97, v99, v101
	v_min_u32_e32 v99, v99, v101
	v_max_u32_e32 v101, v100, v3
	v_min_u32_e32 v3, v100, v3
	v_max_u32_e32 v100, v98, v95
	v_min_u32_e32 v95, v98, v95
	v_max_u32_e32 v98, v2, v0
	v_min_u32_e32 v0, v2, v0
	ds_bpermute_b32 v2, v27, v1
	ds_bpermute_b32 v107, v27, v94
	ds_bpermute_b32 v108, v27, v105
	ds_bpermute_b32 v109, v27, v102
	ds_bpermute_b32 v110, v27, v104
	ds_bpermute_b32 v111, v27, v103
	ds_bpermute_b32 v112, v27, v106
	ds_bpermute_b32 v114, v27, v96
	ds_bpermute_b32 v115, v27, v97
	ds_bpermute_b32 v116, v27, v99
	ds_bpermute_b32 v117, v27, v101
	ds_bpermute_b32 v118, v27, v0
	ds_bpermute_b32 v119, v27, v98
	ds_bpermute_b32 v120, v27, v95
	ds_bpermute_b32 v121, v27, v100
	ds_bpermute_b32 v122, v27, v3
	s_waitcnt lgkmcnt(4)
; __device__ __forceinline__ unsigned f2key(float f) { const unsigned u = __float_as_uint(f); return (u & 0x80000000u) ? ~u : (u | 0x80000000u); }
; #define CE_DESC(a, b) do { const unsigned _mx = (a) > (b) ? (a) : (b), _mn = (a) > (b) ? (b) : (a); (a) = _mx; (b) = _mn; } while (0)
; __device__ __forceinline__ void merge16(unsigned (&a)[16], const unsigned (&b)[16]) {
; #pragma unroll
;     for (int i = 0; i < 16; ++i) a[i] = a[i] > b[15 - i] ? a[i] : b[15 - i];
; #pragma unroll
;     for (int stride = 8; stride > 0; stride >>= 1)
; #pragma unroll
;         for (int i = 0; i < 16; ++i) { const int j = i ^ stride; if (j > i) CE_DESC(a[i], a[j]); }
; }
; __device__ __forceinline__ void peer_tile(const Args& A, LAS unsigned char* lds, int tile) {
;     ...
;                 { const bf16_t* sp = QRY + m * 2048 + hp * 128 + 32 * g;
;                   const u32x4 s0 = *(const u32x4*)sp, s1 = *(const u32x4*)(sp + 8), s2 = *(const u32x4*)(sp + 16), s3 = *(const u32x4*)(sp + 24);
;                   const unsigned sw[16] = {s0.x, s0.y, s0.z, s0.w, s1.x, s1.y, s1.z, s1.w, s2.x, s2.y, s2.z, s2.w, s3.x, s3.y, s3.z, s3.w};
; #pragma unroll
;                   for (int i = 0; i < 16; ++i) {
;                       const float lo = (float)__builtin_bit_cast(_Float16, (unsigned short)(sw[i] & 0xffffu)), hi = (float)__builtin_bit_cast(_Float16, (unsigned short)(sw[i] >> 16));
;                       const unsigned klo = (f2key(lo) & ~127u) | (unsigned)(127 - (32 * g + 2 * i)), khi = (f2key(hi) & ~127u) | (unsigned)(127 - (32 * g + 2 * i + 1));
;                       if (i < 8) { k0[2 * i] = klo; k0[2 * i + 1] = khi; } else { k1[2 * (i - 8)] = klo; k1[2 * (i - 8) + 1] = khi; } } }
;                 sort16_desc(k0); sort16_desc(k1); merge16(k0, k1);
; #pragma unroll
;                 for (int msk = 16; msk <= 32; msk <<= 1) {
; #pragma unroll
;                     for (int i = 0; i < 16; ++i) k1[i] = (unsigned)__shfl_xor((int)k0[i], msk);
;                     merge16(k0, k1); }
	v_max_u32_e32 v1, v1, v118
	s_waitcnt lgkmcnt(3)
	v_max_u32_e32 v94, v94, v119
	s_waitcnt lgkmcnt(2)
	v_max_u32_e32 v105, v105, v120
	s_waitcnt lgkmcnt(1)
	v_max_u32_e32 v102, v102, v121
	s_waitcnt lgkmcnt(0)
	v_max_u32_e32 v104, v104, v122
	v_max_u32_e32 v103, v103, v117
	v_max_u32_e32 v106, v106, v116
	v_max_u32_e32 v96, v96, v115
	v_max_u32_e32 v97, v97, v114
	v_max_u32_e32 v99, v99, v112
	v_max_u32_e32 v101, v101, v111
	v_max_u32_e32 v3, v3, v110
	v_max_u32_e32 v100, v100, v109
	v_max_u32_e32 v95, v95, v108
	v_max_u32_e32 v98, v98, v107
	v_max_u32_e32 v0, v0, v2
	v_max_u32_e32 v2, v1, v97
	v_min_u32_e32 v1, v1, v97
	v_max_u32_e32 v97, v94, v99
	v_min_u32_e32 v94, v94, v99
	v_max_u32_e32 v99, v105, v101
	v_min_u32_e32 v101, v105, v101
	v_max_u32_e32 v105, v102, v3
	v_min_u32_e32 v3, v102, v3
	v_max_u32_e32 v102, v104, v100
	v_min_u32_e32 v100, v104, v100
	v_max_u32_e32 v104, v103, v95
	v_min_u32_e32 v95, v103, v95
	v_max_u32_e32 v103, v106, v98
	v_min_u32_e32 v98, v106, v98
	v_max_u32_e32 v106, v96, v0
	v_min_u32_e32 v0, v96, v0
	v_max_u32_e32 v96, v2, v102
	v_min_u32_e32 v2, v2, v102
	v_max_u32_e32 v102, v97, v104
	v_min_u32_e32 v97, v97, v104
	v_max_u32_e32 v104, v99, v103
	v_min_u32_e32 v99, v99, v103
	v_max_u32_e32 v103, v105, v106
	v_min_u32_e32 v105, v105, v106
	v_max_u32_e32 v106, v1, v100
	v_min_u32_e32 v1, v1, v100
	v_max_u32_e32 v100, v94, v95
	v_min_u32_e32 v94, v94, v95
	v_max_u32_e32 v95, v101, v98
	v_min_u32_e32 v98, v101, v98
	v_max_u32_e32 v101, v3, v0
	v_min_u32_e32 v0, v3, v0
	v_max_u32_e32 v3, v96, v104
	v_min_u32_e32 v96, v96, v104
	v_max_u32_e32 v104, v102, v103
	v_min_u32_e32 v102, v102, v103
	v_max_u32_e32 v103, v2, v99
	v_min_u32_e32 v2, v2, v99
	v_max_u32_e32 v99, v97, v105
	v_min_u32_e32 v97, v97, v105
	v_max_u32_e32 v105, v106, v95
	v_min_u32_e32 v95, v106, v95
	v_max_u32_e32 v106, v100, v101
	v_min_u32_e32 v100, v100, v101
	v_max_u32_e32 v101, v1, v98
	v_min_u32_e32 v1, v1, v98
	v_max_u32_e32 v98, v94, v0
	v_min_u32_e32 v0, v94, v0
	v_max_u32_e32 v94, v3, v104
	v_min_u32_e32 v3, v3, v104
	v_max_u32_e32 v104, v96, v102
	v_min_u32_e32 v96, v96, v102
	v_max_u32_e32 v102, v103, v99
	v_min_u32_e32 v99, v103, v99
	v_max_u32_e32 v103, v2, v97
	v_min_u32_e32 v2, v2, v97
	v_max_u32_e32 v97, v105, v106
	v_min_u32_e32 v105, v105, v106
	v_max_u32_e32 v106, v95, v100
	v_min_u32_e32 v95, v95, v100
	v_max_u32_e32 v100, v101, v98
	v_min_u32_e32 v98, v101, v98
	v_max_u32_e32 v101, v1, v0
	v_min_u32_e32 v0, v1, v0
	ds_bpermute_b32 v114, v29, v0
	ds_bpermute_b32 v1, v29, v94
	ds_bpermute_b32 v107, v29, v3
	ds_bpermute_b32 v108, v29, v104
	ds_bpermute_b32 v109, v29, v96
	s_waitcnt lgkmcnt(4)
	v_max_u32_e32 v94, v94, v114
	global_load_dwordx4 v[114:117], v[4:5], off offset:1296
	global_load_dwordx4 v[118:121], v[4:5], off offset:1280
	ds_bpermute_b32 v110, v29, v102
	ds_bpermute_b32 v111, v29, v99
	ds_bpermute_b32 v112, v29, v103
	ds_bpermute_b32 v122, v29, v2
	ds_bpermute_b32 v123, v29, v97
	ds_bpermute_b32 v124, v29, v105
	ds_bpermute_b32 v125, v29, v106
	ds_bpermute_b32 v126, v29, v95
	ds_bpermute_b32 v127, v29, v100
	ds_bpermute_b32 v128, v29, v101
	ds_bpermute_b32 v129, v29, v98
	s_waitcnt lgkmcnt(4)
	v_max_u32_e32 v99, v99, v125
	s_waitcnt lgkmcnt(3)
	v_max_u32_e32 v102, v102, v126
	s_waitcnt lgkmcnt(2)
	v_max_u32_e32 v96, v96, v127
	s_waitcnt lgkmcnt(1)
	v_max_u32_e32 v3, v3, v128
	s_waitcnt lgkmcnt(0)
	v_max_u32_e32 v104, v104, v129
	v_max_u32_e32 v103, v103, v124
	v_max_u32_e32 v2, v2, v123
	v_max_u32_e32 v97, v97, v122
	v_max_u32_e32 v105, v105, v112
	v_max_u32_e32 v106, v106, v111
	v_max_u32_e32 v95, v95, v110
	v_max_u32_e32 v100, v100, v109
	v_max_u32_e32 v98, v98, v108
	v_max_u32_e32 v101, v101, v107
	v_max_u32_e32 v0, v0, v1
	v_max_u32_e32 v1, v94, v97
	v_min_u32_e32 v94, v94, v97
	v_max_u32_e32 v97, v3, v105
	v_min_u32_e32 v3, v3, v105
	v_max_u32_e32 v105, v104, v106
	v_min_u32_e32 v104, v104, v106
	v_max_u32_e32 v106, v96, v95
	v_min_u32_e32 v95, v96, v95
	v_max_u32_e32 v96, v102, v100
	v_min_u32_e32 v100, v102, v100
	v_max_u32_e32 v102, v99, v98
	v_min_u32_e32 v98, v99, v98
	v_max_u32_e32 v99, v103, v101
	v_min_u32_e32 v101, v103, v101
	v_max_u32_e32 v103, v2, v0
	v_min_u32_e32 v0, v2, v0
	v_max_u32_e32 v2, v1, v96
	v_min_u32_e32 v1, v1, v96
	v_max_u32_e32 v96, v97, v102
	v_min_u32_e32 v97, v97, v102
	v_max_u32_e32 v102, v105, v99
	v_min_u32_e32 v99, v105, v99
	v_max_u32_e32 v105, v106, v103
	v_min_u32_e32 v103, v106, v103
	v_max_u32_e32 v106, v94, v100
	v_min_u32_e32 v94, v94, v100
	v_max_u32_e32 v100, v3, v98
	v_min_u32_e32 v3, v3, v98
	v_max_u32_e32 v98, v104, v101
	v_min_u32_e32 v101, v104, v101
	v_max_u32_e32 v104, v95, v0
	v_min_u32_e32 v0, v95, v0
	v_max_u32_e32 v95, v2, v102
	v_min_u32_e32 v2, v2, v102
	v_max_u32_e32 v102, v96, v105
	v_min_u32_e32 v96, v96, v105
	v_max_u32_e32 v110, v1, v99
	v_min_u32_e32 v1, v1, v99
	v_max_u32_e32 v99, v97, v103
	v_min_u32_e32 v97, v97, v103
	v_max_u32_e32 v111, v106, v98
	v_min_u32_e32 v98, v106, v98
	v_min_u32_e32 v122, v100, v104
	v_max_u32_e32 v123, v94, v101
	v_min_u32_e32 v94, v94, v101
	v_max_u32_e32 v124, v3, v0
	v_min_u32_e32 v0, v3, v0
	v_max_u32_e32 v112, v100, v104
	v_max_u32_e32 v109, v95, v102
	v_min_u32_e32 v108, v95, v102
	v_max_u32_e32 v107, v2, v96
	v_min_u32_e32 v106, v2, v96
	v_max_u32_e32 v105, v110, v99
	v_min_u32_e32 v104, v110, v99
	v_max_u32_e32 v103, v1, v97
	v_min_u32_e32 v102, v1, v97
	v_max_u32_e32 v99, v98, v122
	v_min_u32_e32 v98, v98, v122
	v_max_u32_e32 v97, v123, v124
	v_min_u32_e32 v96, v123, v124
	v_max_u32_e32 v95, v94, v0
	v_min_u32_e32 v94, v94, v0
	global_load_dwordx4 v[0:3], v[4:5], off offset:1328
	global_load_dwordx4 v[122:125], v[4:5], off offset:1312
	s_waitcnt vmcnt(2)
; __device__ __forceinline__ unsigned f2key(float f) { const unsigned u = __float_as_uint(f); return (u & 0x80000000u) ? ~u : (u | 0x80000000u); }
; __device__ __forceinline__ void peer_tile(const Args& A, LAS unsigned char* lds, int tile) {
;     ...
;                 { const bf16_t* sp = QRY + m * 2048 + hp * 128 + 32 * g;
;                   const u32x4 s0 = *(const u32x4*)sp, s1 = *(const u32x4*)(sp + 8), s2 = *(const u32x4*)(sp + 16), s3 = *(const u32x4*)(sp + 24);
;                   const unsigned sw[16] = {s0.x, s0.y, s0.z, s0.w, s1.x, s1.y, s1.z, s1.w, s2.x, s2.y, s2.z, s2.w, s3.x, s3.y, s3.z, s3.w};
; #pragma unroll
;                   for (int i = 0; i < 16; ++i) {
;                       const float lo = (float)__builtin_bit_cast(_Float16, (unsigned short)(sw[i] & 0xffffu)), hi = (float)__builtin_bit_cast(_Float16, (unsigned short)(sw[i] >> 16));
;                       const unsigned klo = (f2key(lo) & ~127u) | (unsigned)(127 - (32 * g + 2 * i)), khi = (f2key(hi) & ~127u) | (unsigned)(127 - (32 * g + 2 * i + 1));
;                       if (i < 8) { k0[2 * i] = klo; k0[2 * i + 1] = khi; } else { k1[2 * (i - 8)] = klo; k1[2 * (i - 8) + 1] = khi; } } }
;     ...
;                 for (int i = 0; i < 16; ++i) L2[p][i] = (g & 2) ? ((g & 1) ? LA[3][p][i] : LA[2][p][i]) : ((g & 1) ? LA[1][p][i] : LA[0][p][i]);
	v_cvt_f32_f16_sdwa v110, v118 dst_sel:DWORD dst_unused:UNUSED_PAD src0_sel:WORD_1
	v_max_u32_e32 v101, v111, v112
	v_min_u32_e32 v100, v111, v112
	v_cvt_f32_f16_e32 v111, v118
	v_not_b32_e32 v112, v110
	v_or_b32_e32 v118, 0x80000000, v110
	v_cmp_gt_i32_e32 vcc, 0, v110
	v_cndmask_b32_e64 v30, v62, v30, s[0:1]
	s_nop 0
	v_cndmask_b32_e32 v110, v118, v112, vcc
	v_not_b32_e32 v112, v111
	v_or_b32_e32 v118, 0x80000000, v111
	v_cmp_gt_i32_e32 vcc, 0, v111
	v_and_b32_e32 v110, 0xffffff80, v110
	v_sub_u32_e32 v110, v110, v15
	v_cndmask_b32_e32 v111, v118, v112, vcc
	v_cvt_f32_f16_sdwa v112, v119 dst_sel:DWORD dst_unused:UNUSED_PAD src0_sel:WORD_1
	v_cvt_f32_f16_e32 v118, v119
	v_and_b32_e32 v111, 0xffffff80, v111
	v_sub_u32_e32 v111, v111, v15
	v_not_b32_e32 v119, v112
	v_or_b32_e32 v126, 0x80000000, v112
	v_cmp_gt_i32_e32 vcc, 0, v112
	v_add_u32_e32 v110, 0x7e, v110
	v_add_u32_e32 v111, 0x7f, v111
	v_cndmask_b32_e32 v112, v126, v119, vcc
	v_not_b32_e32 v119, v118
	v_or_b32_e32 v126, 0x80000000, v118
	v_cmp_gt_i32_e32 vcc, 0, v118
	v_and_b32_e32 v112, 0xffffff80, v112
	v_sub_u32_e32 v112, v112, v14
	v_cndmask_b32_e32 v118, v126, v119, vcc
	v_cvt_f32_f16_sdwa v119, v120 dst_sel:DWORD dst_unused:UNUSED_PAD src0_sel:WORD_1
	v_cvt_f32_f16_e32 v120, v120
	v_and_b32_e32 v118, 0xffffff80, v118
	v_sub_u32_e32 v118, v118, v14
	v_not_b32_e32 v126, v119
	v_or_b32_e32 v127, 0x80000000, v119
	v_cmp_gt_i32_e32 vcc, 0, v119
	v_add_u32_e32 v112, 0x7e, v112
	v_add_u32_e32 v118, 0x7f, v118
	v_cndmask_b32_e32 v119, v127, v126, vcc
	v_not_b32_e32 v126, v120
	v_or_b32_e32 v127, 0x80000000, v120
	v_cmp_gt_i32_e32 vcc, 0, v120
	v_and_b32_e32 v119, 0xffffff80, v119
	v_sub_u32_e32 v119, v119, v12
	v_cndmask_b32_e32 v120, v127, v126, vcc
	v_cvt_f32_f16_sdwa v126, v121 dst_sel:DWORD dst_unused:UNUSED_PAD src0_sel:WORD_1
	v_cvt_f32_f16_e32 v121, v121
	v_and_b32_e32 v120, 0xffffff80, v120
	v_sub_u32_e32 v120, v120, v12
	v_not_b32_e32 v127, v126
	v_or_b32_e32 v128, 0x80000000, v126
	v_cmp_gt_i32_e32 vcc, 0, v126
	v_add_u32_e32 v119, 0x7e, v119
	v_add_u32_e32 v120, 0x7f, v120
	v_cndmask_b32_e32 v126, v128, v127, vcc
	v_not_b32_e32 v127, v121
	v_or_b32_e32 v128, 0x80000000, v121
	v_cmp_gt_i32_e32 vcc, 0, v121
	v_and_b32_e32 v126, 0xffffff80, v126
	v_sub_u32_e32 v126, v126, v10
	v_cndmask_b32_e32 v121, v128, v127, vcc
	v_cvt_f32_f16_sdwa v127, v114 dst_sel:DWORD dst_unused:UNUSED_PAD src0_sel:WORD_1
	v_cvt_f32_f16_e32 v114, v114
	v_and_b32_e32 v121, 0xffffff80, v121
	v_sub_u32_e32 v121, v121, v10
	v_not_b32_e32 v128, v127
	v_or_b32_e32 v129, 0x80000000, v127
	v_cmp_gt_i32_e32 vcc, 0, v127
	v_add_u32_e32 v126, 0x7e, v126
	v_add_u32_e32 v121, 0x7f, v121
	v_cndmask_b32_e32 v127, v129, v128, vcc
	v_not_b32_e32 v128, v114
	v_or_b32_e32 v129, 0x80000000, v114
	v_cmp_gt_i32_e32 vcc, 0, v114
	v_and_b32_e32 v127, 0xffffff80, v127
	v_sub_u32_e32 v127, v127, v8
	v_cndmask_b32_e32 v114, v129, v128, vcc
	v_cvt_f32_f16_sdwa v128, v115 dst_sel:DWORD dst_unused:UNUSED_PAD src0_sel:WORD_1
	v_cvt_f32_f16_e32 v115, v115
	v_and_b32_e32 v114, 0xffffff80, v114
	v_sub_u32_e32 v114, v114, v8
	v_not_b32_e32 v129, v128
	v_or_b32_e32 v130, 0x80000000, v128
	v_cmp_gt_i32_e32 vcc, 0, v128
	v_add_u32_e32 v127, 0x7e, v127
	v_add_u32_e32 v114, 0x7f, v114
	v_cndmask_b32_e32 v128, v130, v129, vcc
	v_not_b32_e32 v129, v115
	v_or_b32_e32 v130, 0x80000000, v115
	v_cmp_gt_i32_e32 vcc, 0, v115
	v_and_b32_e32 v128, 0xffffff80, v128
	v_sub_u32_e32 v128, v128, v16
	v_cndmask_b32_e32 v115, v130, v129, vcc
	v_cvt_f32_f16_sdwa v129, v116 dst_sel:DWORD dst_unused:UNUSED_PAD src0_sel:WORD_1
	v_cvt_f32_f16_e32 v116, v116
	v_and_b32_e32 v115, 0xffffff80, v115
	v_sub_u32_e32 v115, v115, v16
	v_not_b32_e32 v130, v129
	v_or_b32_e32 v131, 0x80000000, v129
	v_cmp_gt_i32_e32 vcc, 0, v129
	v_add_u32_e32 v128, 0x7e, v128
	v_add_u32_e32 v115, 0x7f, v115
	v_cndmask_b32_e32 v129, v131, v130, vcc
	v_not_b32_e32 v130, v116
	v_or_b32_e32 v131, 0x80000000, v116
	v_cmp_gt_i32_e32 vcc, 0, v116
	v_and_b32_e32 v129, 0xffffff80, v129
	v_sub_u32_e32 v129, v129, v17
	v_cndmask_b32_e32 v116, v131, v130, vcc
	v_cvt_f32_f16_sdwa v130, v117 dst_sel:DWORD dst_unused:UNUSED_PAD src0_sel:WORD_1
	v_cvt_f32_f16_e32 v117, v117
	v_and_b32_e32 v116, 0xffffff80, v116
	v_sub_u32_e32 v116, v116, v17
	v_not_b32_e32 v131, v130
	v_or_b32_e32 v132, 0x80000000, v130
	v_cmp_gt_i32_e32 vcc, 0, v130
	v_add_u32_e32 v129, 0x7e, v129
	v_add_u32_e32 v116, 0x7f, v116
	v_cndmask_b32_e32 v130, v132, v131, vcc
	v_not_b32_e32 v131, v117
	v_or_b32_e32 v132, 0x80000000, v117
	v_cmp_gt_i32_e32 vcc, 0, v117
	v_and_b32_e32 v130, 0xffffff80, v130
	v_sub_u32_e32 v130, v130, v18
	v_cndmask_b32_e32 v117, v132, v131, vcc
	s_waitcnt vmcnt(0)
; __device__ __forceinline__ unsigned f2key(float f) { const unsigned u = __float_as_uint(f); return (u & 0x80000000u) ? ~u : (u | 0x80000000u); }
; #define CE_DESC(a, b) do { const unsigned _mx = (a) > (b) ? (a) : (b), _mn = (a) > (b) ? (b) : (a); (a) = _mx; (b) = _mn; } while (0)
; __device__ __forceinline__ void sort16_desc(unsigned (&k)[16]) {
; #pragma unroll
;     for (int size = 2; size <= 16; size <<= 1)
; #pragma unroll
;         for (int stride = size >> 1; stride > 0; stride >>= 1)
; #pragma unroll
;             for (int i = 0; i < 16; ++i) { const int j = i ^ stride;
;                 if (j > i) { if ((i & size) == 0) CE_DESC(k[i], k[j]); else CE_DESC(k[j], k[i]); } }
; __device__ __forceinline__ void peer_tile(const Args& A, LAS unsigned char* lds, int tile) {
;     ...
;                   for (int i = 0; i < 16; ++i) {
;                       const float lo = (float)__builtin_bit_cast(_Float16, (unsigned short)(sw[i] & 0xffffu)), hi = (float)__builtin_bit_cast(_Float16, (unsigned short)(sw[i] >> 16));
;                       const unsigned klo = (f2key(lo) & ~127u) | (unsigned)(127 - (32 * g + 2 * i)), khi = (f2key(hi) & ~127u) | (unsigned)(127 - (32 * g + 2 * i + 1));
;                       if (i < 8) { k0[2 * i] = klo; k0[2 * i + 1] = khi; } else { k1[2 * (i - 8)] = klo; k1[2 * (i - 8) + 1] = khi; } } }
	v_cvt_f32_f16_sdwa v131, v122 dst_sel:DWORD dst_unused:UNUSED_PAD src0_sel:WORD_1
	v_cvt_f32_f16_e32 v122, v122
	v_and_b32_e32 v117, 0xffffff80, v117
	v_sub_u32_e32 v117, v117, v18
	v_not_b32_e32 v132, v131
	v_or_b32_e32 v133, 0x80000000, v131
	v_cmp_gt_i32_e32 vcc, 0, v131
	v_add_u32_e32 v130, 0x7e, v130
	v_add_u32_e32 v117, 0x7f, v117
	v_cndmask_b32_e32 v131, v133, v132, vcc
	v_not_b32_e32 v132, v122
	v_or_b32_e32 v133, 0x80000000, v122
	v_cmp_gt_i32_e32 vcc, 0, v122
	v_and_b32_e32 v131, 0xffffff80, v131
	v_sub_u32_e32 v131, v131, v20
	v_cndmask_b32_e32 v122, v133, v132, vcc
	v_cvt_f32_f16_sdwa v132, v123 dst_sel:DWORD dst_unused:UNUSED_PAD src0_sel:WORD_1
	v_cvt_f32_f16_e32 v123, v123
	v_and_b32_e32 v122, 0xffffff80, v122
	v_sub_u32_e32 v122, v122, v20
	v_not_b32_e32 v133, v132
	v_or_b32_e32 v134, 0x80000000, v132
	v_cmp_gt_i32_e32 vcc, 0, v132
	v_add_u32_e32 v131, 0x7e, v131
	v_add_u32_e32 v122, 0x7f, v122
	v_cndmask_b32_e32 v132, v134, v133, vcc
	v_not_b32_e32 v133, v123
	v_or_b32_e32 v134, 0x80000000, v123
	v_cmp_gt_i32_e32 vcc, 0, v123
	v_and_b32_e32 v132, 0xffffff80, v132
	v_sub_u32_e32 v132, v132, v21
	v_cndmask_b32_e32 v123, v134, v133, vcc
	v_cvt_f32_f16_sdwa v133, v124 dst_sel:DWORD dst_unused:UNUSED_PAD src0_sel:WORD_1
	v_cvt_f32_f16_e32 v124, v124
	v_and_b32_e32 v123, 0xffffff80, v123
	v_sub_u32_e32 v123, v123, v21
	v_not_b32_e32 v134, v133
	v_or_b32_e32 v135, 0x80000000, v133
	v_cmp_gt_i32_e32 vcc, 0, v133
	v_add_u32_e32 v132, 0x7e, v132
	v_add_u32_e32 v123, 0x7f, v123
	v_cndmask_b32_e32 v133, v135, v134, vcc
	v_not_b32_e32 v134, v124
	v_or_b32_e32 v135, 0x80000000, v124
	v_cmp_gt_i32_e32 vcc, 0, v124
	v_and_b32_e32 v133, 0xffffff80, v133
	v_sub_u32_e32 v133, v133, v22
	v_cndmask_b32_e32 v124, v135, v134, vcc
	v_cvt_f32_f16_sdwa v134, v125 dst_sel:DWORD dst_unused:UNUSED_PAD src0_sel:WORD_1
	v_cvt_f32_f16_e32 v125, v125
	v_and_b32_e32 v124, 0xffffff80, v124
	v_sub_u32_e32 v124, v124, v22
	v_not_b32_e32 v135, v134
	v_or_b32_e32 v136, 0x80000000, v134
	v_cmp_gt_i32_e32 vcc, 0, v134
	v_add_u32_e32 v133, 0x7e, v133
	v_add_u32_e32 v124, 0x7f, v124
	v_cndmask_b32_e32 v134, v136, v135, vcc
	v_not_b32_e32 v135, v125
	v_or_b32_e32 v136, 0x80000000, v125
	v_cmp_gt_i32_e32 vcc, 0, v125
	v_and_b32_e32 v134, 0xffffff80, v134
	v_sub_u32_e32 v134, v134, v23
	v_cndmask_b32_e32 v125, v136, v135, vcc
	v_cvt_f32_f16_sdwa v135, v0 dst_sel:DWORD dst_unused:UNUSED_PAD src0_sel:WORD_1
	v_cvt_f32_f16_e32 v0, v0
	v_and_b32_e32 v125, 0xffffff80, v125
	v_sub_u32_e32 v125, v125, v23
	v_not_b32_e32 v136, v135
	v_or_b32_e32 v137, 0x80000000, v135
	v_cmp_gt_i32_e32 vcc, 0, v135
	v_add_u32_e32 v134, 0x7e, v134
	v_add_u32_e32 v125, 0x7f, v125
	v_cndmask_b32_e32 v135, v137, v136, vcc
	v_not_b32_e32 v136, v0
	v_or_b32_e32 v137, 0x80000000, v0
	v_cmp_gt_i32_e32 vcc, 0, v0
	v_and_b32_e32 v135, 0xffffff80, v135
	v_sub_u32_e32 v135, v135, v24
	v_cndmask_b32_e32 v0, v137, v136, vcc
	v_cvt_f32_f16_sdwa v136, v1 dst_sel:DWORD dst_unused:UNUSED_PAD src0_sel:WORD_1
	v_cvt_f32_f16_e32 v1, v1
	v_and_b32_e32 v0, 0xffffff80, v0
	v_sub_u32_e32 v0, v0, v24
	v_not_b32_e32 v137, v136
	v_or_b32_e32 v138, 0x80000000, v136
	v_cmp_gt_i32_e32 vcc, 0, v136
	v_add_u32_e32 v135, 0x7e, v135
	v_add_u32_e32 v0, 0x7f, v0
	v_cndmask_b32_e32 v136, v138, v137, vcc
	v_not_b32_e32 v137, v1
	v_or_b32_e32 v138, 0x80000000, v1
	v_cmp_gt_i32_e32 vcc, 0, v1
	v_and_b32_e32 v136, 0xffffff80, v136
	v_sub_u32_e32 v136, v136, v25
	v_cndmask_b32_e32 v1, v138, v137, vcc
	v_cvt_f32_f16_sdwa v137, v2 dst_sel:DWORD dst_unused:UNUSED_PAD src0_sel:WORD_1
	v_cvt_f32_f16_e32 v2, v2
	v_and_b32_e32 v1, 0xffffff80, v1
	v_sub_u32_e32 v1, v1, v25
	v_not_b32_e32 v138, v137
	v_or_b32_e32 v139, 0x80000000, v137
	v_cmp_gt_i32_e32 vcc, 0, v137
	v_add_u32_e32 v136, 0x7e, v136
	v_add_u32_e32 v1, 0x7f, v1
	v_cndmask_b32_e32 v137, v139, v138, vcc
	v_not_b32_e32 v138, v2
	v_or_b32_e32 v139, 0x80000000, v2
	v_cmp_gt_i32_e32 vcc, 0, v2
	v_and_b32_e32 v137, 0xffffff80, v137
	v_sub_u32_e32 v137, v137, v26
	v_cndmask_b32_e32 v2, v139, v138, vcc
	v_cvt_f32_f16_sdwa v138, v3 dst_sel:DWORD dst_unused:UNUSED_PAD src0_sel:WORD_1
	v_cvt_f32_f16_e32 v3, v3
	v_and_b32_e32 v2, 0xffffff80, v2
	v_sub_u32_e32 v2, v2, v26
	v_not_b32_e32 v139, v138
	v_or_b32_e32 v140, 0x80000000, v138
	v_cmp_gt_i32_e32 vcc, 0, v138
	v_add_u32_e32 v137, 0x7e, v137
	v_add_u32_e32 v2, 0x7f, v2
	v_cndmask_b32_e32 v138, v140, v139, vcc
	v_not_b32_e32 v139, v3
	v_or_b32_e32 v140, 0x80000000, v3
	v_cmp_gt_i32_e32 vcc, 0, v3
	v_and_b32_e32 v138, 0xffffff80, v138
	v_sub_u32_e32 v138, v138, v28
	v_cndmask_b32_e32 v3, v140, v139, vcc
	v_and_b32_e32 v3, 0xffffff80, v3
	v_sub_u32_e32 v3, v3, v28
	v_add_u32_e32 v138, 0x7e, v138
	v_add_u32_e32 v3, 0x7f, v3
	v_max_u32_e32 v139, v111, v110
	v_min_u32_e32 v110, v111, v110
	v_max_u32_e32 v111, v112, v118
	v_min_u32_e32 v112, v112, v118
	v_max_u32_e32 v118, v120, v119
	v_min_u32_e32 v119, v120, v119
	v_max_u32_e32 v120, v126, v121
	v_min_u32_e32 v121, v126, v121
	v_max_u32_e32 v126, v114, v127
	v_min_u32_e32 v114, v114, v127
	v_max_u32_e32 v127, v128, v115
	v_min_u32_e32 v115, v128, v115
	v_max_u32_e32 v128, v116, v129
	v_min_u32_e32 v116, v116, v129
	v_max_u32_e32 v129, v130, v117
	v_min_u32_e32 v117, v130, v117
	v_max_u32_e32 v147, v122, v131
	v_min_u32_e32 v122, v122, v131
	v_max_u32_e32 v131, v132, v123
	v_min_u32_e32 v123, v132, v123
	v_max_u32_e32 v132, v124, v133
	v_min_u32_e32 v124, v124, v133
	v_max_u32_e32 v133, v134, v125
	v_min_u32_e32 v125, v134, v125
	v_max_u32_e32 v134, v0, v135
	v_min_u32_e32 v0, v0, v135
	v_max_u32_e32 v135, v136, v1
	v_min_u32_e32 v1, v136, v1
	v_max_u32_e32 v136, v2, v137
	v_min_u32_e32 v2, v2, v137
; #define CE_DESC(a, b) do { const unsigned _mx = (a) > (b) ? (a) : (b), _mn = (a) > (b) ? (b) : (a); (a) = _mx; (b) = _mn; } while (0)
; __device__ __forceinline__ void sort16_desc(unsigned (&k)[16]) {
; #pragma unroll
;     for (int size = 2; size <= 16; size <<= 1)
; #pragma unroll
;         for (int stride = size >> 1; stride > 0; stride >>= 1)
; #pragma unroll
;             for (int i = 0; i < 16; ++i) { const int j = i ^ stride;
;                 if (j > i) { if ((i & size) == 0) CE_DESC(k[i], k[j]); else CE_DESC(k[j], k[i]); } }
	v_max_u32_e32 v137, v138, v3
	v_min_u32_e32 v3, v138, v3
	v_max_u32_e32 v130, v139, v112
	v_min_u32_e32 v112, v139, v112
	v_max_u32_e32 v139, v110, v111
	v_min_u32_e32 v110, v110, v111
	v_max_u32_e32 v111, v121, v118
	v_min_u32_e32 v118, v121, v118
	v_max_u32_e32 v121, v120, v119
	v_min_u32_e32 v119, v120, v119
	v_max_u32_e32 v120, v126, v115
	v_min_u32_e32 v115, v126, v115
	v_max_u32_e32 v126, v114, v127
	v_min_u32_e32 v114, v114, v127
	v_max_u32_e32 v127, v117, v128
	v_min_u32_e32 v117, v117, v128
	v_max_u32_e32 v128, v129, v116
	v_min_u32_e32 v116, v129, v116
	v_max_u32_e32 v138, v147, v123
	v_min_u32_e32 v123, v147, v123
	v_max_u32_e32 v147, v122, v131
	v_min_u32_e32 v122, v122, v131
	v_max_u32_e32 v131, v125, v132
	v_min_u32_e32 v125, v125, v132
	v_max_u32_e32 v132, v133, v124
	v_min_u32_e32 v124, v133, v124
	v_max_u32_e32 v133, v134, v1
	v_min_u32_e32 v1, v134, v1
	v_max_u32_e32 v134, v0, v135
	v_min_u32_e32 v0, v0, v135
	v_max_u32_e32 v135, v3, v136
	v_min_u32_e32 v3, v3, v136
	v_max_u32_e32 v136, v137, v2
	v_min_u32_e32 v2, v137, v2
	v_max_u32_e32 v129, v130, v139
	v_min_u32_e32 v130, v130, v139
	v_max_u32_e32 v139, v112, v110
	v_min_u32_e32 v110, v112, v110
	v_max_u32_e32 v112, v119, v118
	v_min_u32_e32 v118, v119, v118
	v_max_u32_e32 v119, v121, v111
	v_min_u32_e32 v111, v121, v111
	v_max_u32_e32 v121, v120, v126
	v_min_u32_e32 v120, v120, v126
	v_max_u32_e32 v126, v115, v114
	v_min_u32_e32 v114, v115, v114
	v_max_u32_e32 v115, v116, v117
	v_min_u32_e32 v116, v116, v117
	v_max_u32_e32 v117, v128, v127
	v_min_u32_e32 v127, v128, v127
	v_max_u32_e32 v137, v138, v147
	v_min_u32_e32 v138, v138, v147
	v_max_u32_e32 v147, v123, v122
	v_min_u32_e32 v122, v123, v122
	v_max_u32_e32 v123, v124, v125
	v_min_u32_e32 v124, v124, v125
	v_max_u32_e32 v125, v132, v131
	v_min_u32_e32 v131, v132, v131
	v_max_u32_e32 v132, v133, v134
	v_min_u32_e32 v133, v133, v134
	v_max_u32_e32 v134, v1, v0
	v_min_u32_e32 v0, v1, v0
	v_max_u32_e32 v1, v2, v3
	v_min_u32_e32 v2, v2, v3
	v_max_u32_e32 v3, v136, v135
	v_min_u32_e32 v135, v136, v135
	v_max_u32_e32 v128, v129, v118
	v_min_u32_e32 v118, v129, v118
	v_max_u32_e32 v129, v130, v112
	v_min_u32_e32 v112, v130, v112
	v_max_u32_e32 v130, v139, v111
	v_min_u32_e32 v111, v139, v111
	v_max_u32_e32 v139, v110, v119
	v_min_u32_e32 v110, v110, v119
	v_max_u32_e32 v119, v116, v121
	v_min_u32_e32 v116, v116, v121
	v_max_u32_e32 v121, v115, v120
	v_min_u32_e32 v115, v115, v120
	v_max_u32_e32 v120, v127, v126
	v_min_u32_e32 v126, v127, v126
	v_max_u32_e32 v127, v117, v114
	v_min_u32_e32 v114, v117, v114
	v_max_u32_e32 v136, v137, v124
	v_min_u32_e32 v124, v137, v124
	v_max_u32_e32 v137, v138, v123
	v_min_u32_e32 v123, v138, v123
	v_max_u32_e32 v138, v147, v131
	v_min_u32_e32 v131, v147, v131
	v_max_u32_e32 v147, v122, v125
	v_min_u32_e32 v122, v122, v125
	v_max_u32_e32 v125, v2, v132
	v_min_u32_e32 v2, v2, v132
	v_max_u32_e32 v132, v1, v133
	v_min_u32_e32 v1, v1, v133
	v_max_u32_e32 v133, v135, v134
	v_min_u32_e32 v134, v135, v134
	v_max_u32_e32 v135, v3, v0
	v_min_u32_e32 v0, v3, v0
	v_max_u32_e32 v117, v128, v130
	v_min_u32_e32 v128, v128, v130
	v_max_u32_e32 v130, v129, v139
	v_min_u32_e32 v129, v129, v139
	v_max_u32_e32 v139, v118, v111
	v_min_u32_e32 v111, v118, v111
	v_max_u32_e32 v118, v112, v110
	v_min_u32_e32 v110, v112, v110
	v_max_u32_e32 v112, v126, v116
	v_min_u32_e32 v116, v126, v116
	v_max_u32_e32 v126, v114, v115
	v_min_u32_e32 v114, v114, v115
	v_max_u32_e32 v115, v120, v119
	v_min_u32_e32 v119, v120, v119
	v_max_u32_e32 v120, v127, v121
	v_min_u32_e32 v121, v127, v121
	v_max_u32_e32 v3, v136, v138
	v_min_u32_e32 v136, v136, v138
	v_max_u32_e32 v138, v137, v147
	v_min_u32_e32 v137, v137, v147
	v_max_u32_e32 v147, v124, v131
	v_min_u32_e32 v124, v124, v131
	v_max_u32_e32 v131, v123, v122
	v_min_u32_e32 v122, v123, v122
	v_max_u32_e32 v123, v134, v2
	v_min_u32_e32 v2, v134, v2
	v_max_u32_e32 v134, v0, v1
	v_min_u32_e32 v0, v0, v1
	v_max_u32_e32 v1, v133, v125
	v_min_u32_e32 v125, v133, v125
	v_max_u32_e32 v133, v135, v132
	v_min_u32_e32 v132, v135, v132
	v_max_u32_e32 v127, v117, v130
	v_min_u32_e32 v117, v117, v130
	v_max_u32_e32 v130, v128, v129
	v_min_u32_e32 v128, v128, v129
	v_max_u32_e32 v129, v139, v118
	v_min_u32_e32 v118, v139, v118
	v_max_u32_e32 v139, v111, v110
	v_min_u32_e32 v110, v111, v110
	v_max_u32_e32 v111, v114, v116
	v_min_u32_e32 v114, v114, v116
	v_max_u32_e32 v116, v126, v112
	v_min_u32_e32 v112, v126, v112
	v_max_u32_e32 v126, v121, v119
	v_min_u32_e32 v119, v121, v119
	v_max_u32_e32 v121, v120, v115
	v_min_u32_e32 v115, v120, v115
	v_max_u32_e32 v135, v3, v138
	v_min_u32_e32 v3, v3, v138
	v_max_u32_e32 v138, v136, v137
	v_min_u32_e32 v136, v136, v137
	v_max_u32_e32 v137, v147, v131
	v_min_u32_e32 v131, v147, v131
	v_max_u32_e32 v147, v124, v122
	v_min_u32_e32 v122, v124, v122
	v_max_u32_e32 v124, v0, v2
	v_min_u32_e32 v0, v0, v2
	v_max_u32_e32 v2, v134, v123
	v_min_u32_e32 v123, v134, v123
	v_max_u32_e32 v134, v132, v125
	v_min_u32_e32 v125, v132, v125
	v_max_u32_e32 v132, v133, v1
	v_min_u32_e32 v1, v133, v1
	v_max_u32_e32 v120, v127, v114
	v_min_u32_e32 v114, v127, v114
	v_max_u32_e32 v127, v117, v111
	v_min_u32_e32 v111, v117, v111
	v_max_u32_e32 v117, v130, v112
	v_min_u32_e32 v112, v130, v112
	v_max_u32_e32 v130, v128, v116
	v_min_u32_e32 v116, v128, v116
	v_max_u32_e32 v128, v129, v119
	v_min_u32_e32 v119, v129, v119
	v_max_u32_e32 v129, v118, v126
	v_min_u32_e32 v118, v118, v126
	v_max_u32_e32 v126, v139, v115
	v_min_u32_e32 v115, v139, v115
	v_max_u32_e32 v139, v110, v121
	v_min_u32_e32 v110, v110, v121
	v_max_u32_e32 v133, v135, v0
	v_min_u32_e32 v0, v135, v0
; #define CE_DESC(a, b) do { const unsigned _mx = (a) > (b) ? (a) : (b), _mn = (a) > (b) ? (b) : (a); (a) = _mx; (b) = _mn; } while (0)
; __device__ __forceinline__ void sort16_desc(unsigned (&k)[16]) {
; #pragma unroll
;     for (int size = 2; size <= 16; size <<= 1)
; #pragma unroll
;         for (int stride = size >> 1; stride > 0; stride >>= 1)
; #pragma unroll
;             for (int i = 0; i < 16; ++i) { const int j = i ^ stride;
;                 if (j > i) { if ((i & size) == 0) CE_DESC(k[i], k[j]); else CE_DESC(k[j], k[i]); } }
; }
; __device__ __forceinline__ void merge16(unsigned (&a)[16], const unsigned (&b)[16]) {
; #pragma unroll
;     for (int i = 0; i < 16; ++i) a[i] = a[i] > b[15 - i] ? a[i] : b[15 - i];
; #pragma unroll
;     for (int stride = 8; stride > 0; stride >>= 1)
; #pragma unroll
;         for (int i = 0; i < 16; ++i) { const int j = i ^ stride; if (j > i) CE_DESC(a[i], a[j]); }
; }
; __device__ __forceinline__ void peer_tile(const Args& A, LAS unsigned char* lds, int tile) {
;     ...
;                 for (int msk = 16; msk <= 32; msk <<= 1) {
; #pragma unroll
;                     for (int i = 0; i < 16; ++i) k1[i] = (unsigned)__shfl_xor((int)k0[i], msk);
;                     merge16(k0, k1); }
	v_max_u32_e32 v135, v3, v124
	v_min_u32_e32 v3, v3, v124
	v_max_u32_e32 v124, v138, v123
	v_min_u32_e32 v123, v138, v123
	v_max_u32_e32 v138, v136, v2
	v_min_u32_e32 v2, v136, v2
	v_max_u32_e32 v136, v137, v125
	v_min_u32_e32 v125, v137, v125
	v_max_u32_e32 v137, v131, v134
	v_min_u32_e32 v131, v131, v134
	v_max_u32_e32 v134, v147, v1
	v_min_u32_e32 v1, v147, v1
	v_max_u32_e32 v147, v122, v132
	v_min_u32_e32 v122, v122, v132
	v_max_u32_e32 v121, v120, v128
	v_min_u32_e32 v120, v120, v128
	v_max_u32_e32 v128, v127, v129
	v_min_u32_e32 v127, v127, v129
	v_max_u32_e32 v129, v117, v126
	v_min_u32_e32 v117, v117, v126
	v_max_u32_e32 v126, v130, v139
	v_min_u32_e32 v130, v130, v139
	v_max_u32_e32 v139, v114, v119
	v_min_u32_e32 v114, v114, v119
	v_max_u32_e32 v119, v111, v118
	v_min_u32_e32 v111, v111, v118
	v_max_u32_e32 v118, v112, v115
	v_min_u32_e32 v112, v112, v115
	v_max_u32_e32 v115, v116, v110
	v_min_u32_e32 v110, v116, v110
	v_max_u32_e32 v132, v133, v136
	v_min_u32_e32 v133, v133, v136
	v_max_u32_e32 v136, v135, v137
	v_min_u32_e32 v135, v135, v137
	v_max_u32_e32 v137, v124, v134
	v_min_u32_e32 v124, v124, v134
	v_max_u32_e32 v134, v138, v147
	v_min_u32_e32 v138, v138, v147
	v_max_u32_e32 v147, v0, v125
	v_min_u32_e32 v0, v0, v125
	v_max_u32_e32 v125, v3, v131
	v_min_u32_e32 v3, v3, v131
	v_max_u32_e32 v131, v123, v1
	v_min_u32_e32 v1, v123, v1
	v_max_u32_e32 v123, v2, v122
	v_min_u32_e32 v2, v2, v122
	v_max_u32_e32 v116, v121, v129
	v_min_u32_e32 v121, v121, v129
	v_max_u32_e32 v129, v128, v126
	v_min_u32_e32 v126, v128, v126
	v_max_u32_e32 v128, v120, v117
	v_min_u32_e32 v117, v120, v117
	v_max_u32_e32 v120, v127, v130
	v_min_u32_e32 v127, v127, v130
	v_max_u32_e32 v130, v139, v118
	v_min_u32_e32 v118, v139, v118
	v_max_u32_e32 v139, v119, v115
	v_min_u32_e32 v115, v119, v115
	v_max_u32_e32 v119, v114, v112
	v_min_u32_e32 v112, v114, v112
	v_max_u32_e32 v114, v111, v110
	v_min_u32_e32 v110, v111, v110
	v_max_u32_e32 v122, v132, v137
	v_min_u32_e32 v132, v132, v137
	v_max_u32_e32 v137, v136, v134
	v_min_u32_e32 v134, v136, v134
	v_max_u32_e32 v136, v133, v124
	v_min_u32_e32 v124, v133, v124
	v_max_u32_e32 v133, v135, v138
	v_min_u32_e32 v135, v135, v138
	v_max_u32_e32 v138, v147, v131
	v_min_u32_e32 v131, v147, v131
	v_max_u32_e32 v147, v125, v123
	v_min_u32_e32 v123, v125, v123
	v_max_u32_e32 v125, v0, v1
	v_min_u32_e32 v0, v0, v1
	v_max_u32_e32 v1, v3, v2
	v_min_u32_e32 v2, v3, v2
	v_min_u32_e32 v111, v116, v129
	v_min_u32_e32 v140, v121, v126
	v_min_u32_e32 v141, v128, v120
	v_min_u32_e32 v142, v117, v127
	v_min_u32_e32 v143, v130, v139
	v_min_u32_e32 v144, v118, v115
	v_min_u32_e32 v145, v119, v114
	v_min_u32_e32 v146, v112, v110
	v_min_u32_e32 v3, v122, v137
	v_min_u32_e32 v148, v132, v134
	v_min_u32_e32 v149, v136, v133
	v_min_u32_e32 v150, v124, v135
	v_min_u32_e32 v151, v138, v147
	v_min_u32_e32 v152, v131, v123
	v_min_u32_e32 v153, v125, v1
	v_min_u32_e32 v154, v0, v2
	v_max3_u32 v116, v116, v129, v154
	v_max3_u32 v0, v111, v0, v2
	v_max3_u32 v2, v121, v126, v153
	v_max3_u32 v1, v140, v125, v1
	v_max3_u32 v111, v128, v120, v152
	v_max3_u32 v120, v141, v131, v123
	v_max3_u32 v117, v117, v127, v151
	v_max3_u32 v121, v142, v138, v147
	v_max3_u32 v123, v130, v139, v150
	v_max3_u32 v124, v143, v124, v135
	v_max3_u32 v115, v118, v115, v149
	v_max3_u32 v118, v144, v136, v133
	v_max3_u32 v114, v119, v114, v148
	v_max3_u32 v119, v145, v132, v134
	v_max3_u32 v3, v112, v110, v3
	v_max3_u32 v110, v146, v122, v137
	v_max_u32_e32 v112, v116, v123
	v_min_u32_e32 v116, v116, v123
	v_max_u32_e32 v122, v0, v124
	v_min_u32_e32 v0, v0, v124
	v_max_u32_e32 v123, v2, v115
	v_min_u32_e32 v2, v2, v115
	v_max_u32_e32 v115, v1, v118
	v_min_u32_e32 v1, v1, v118
	v_max_u32_e32 v118, v111, v114
	v_min_u32_e32 v111, v111, v114
	v_max_u32_e32 v114, v120, v119
	v_min_u32_e32 v119, v120, v119
	v_max_u32_e32 v120, v117, v3
	v_min_u32_e32 v3, v117, v3
	v_max_u32_e32 v117, v121, v110
	v_min_u32_e32 v110, v121, v110
	v_max_u32_e32 v121, v112, v118
	v_min_u32_e32 v112, v112, v118
	v_max_u32_e32 v118, v122, v114
	v_min_u32_e32 v114, v122, v114
	v_max_u32_e32 v122, v123, v120
	v_min_u32_e32 v120, v123, v120
	v_max_u32_e32 v123, v115, v117
	v_min_u32_e32 v115, v115, v117
	v_max_u32_e32 v117, v116, v111
	v_min_u32_e32 v111, v116, v111
	v_max_u32_e32 v116, v0, v119
	v_min_u32_e32 v0, v0, v119
	v_max_u32_e32 v119, v2, v3
	v_min_u32_e32 v2, v2, v3
	v_max_u32_e32 v3, v1, v110
	v_min_u32_e32 v1, v1, v110
	v_max_u32_e32 v110, v121, v122
	v_min_u32_e32 v121, v121, v122
	v_max_u32_e32 v122, v118, v123
	v_min_u32_e32 v118, v118, v123
	v_max_u32_e32 v123, v112, v120
	v_min_u32_e32 v112, v112, v120
	v_max_u32_e32 v120, v114, v115
	v_min_u32_e32 v114, v114, v115
	v_max_u32_e32 v115, v117, v119
	v_min_u32_e32 v117, v117, v119
	v_max_u32_e32 v119, v116, v3
	v_min_u32_e32 v3, v116, v3
	v_max_u32_e32 v116, v111, v2
	v_min_u32_e32 v2, v111, v2
	v_max_u32_e32 v111, v0, v1
	v_min_u32_e32 v0, v0, v1
	v_max_u32_e32 v1, v110, v122
	v_min_u32_e32 v110, v110, v122
	v_max_u32_e32 v122, v121, v118
	v_min_u32_e32 v118, v121, v118
	v_max_u32_e32 v121, v123, v120
	v_min_u32_e32 v120, v123, v120
	v_max_u32_e32 v123, v112, v114
	v_min_u32_e32 v112, v112, v114
	v_max_u32_e32 v114, v115, v119
	v_min_u32_e32 v115, v115, v119
	v_max_u32_e32 v119, v117, v3
	v_min_u32_e32 v3, v117, v3
	v_max_u32_e32 v117, v116, v111
	v_min_u32_e32 v111, v116, v111
	v_max_u32_e32 v116, v2, v0
	v_min_u32_e32 v0, v2, v0
	ds_bpermute_b32 v2, v27, v1
	ds_bpermute_b32 v124, v27, v110
	ds_bpermute_b32 v125, v27, v122
	ds_bpermute_b32 v126, v27, v118
	ds_bpermute_b32 v127, v27, v121
	ds_bpermute_b32 v128, v27, v120
	ds_bpermute_b32 v129, v27, v123
	ds_bpermute_b32 v130, v27, v112
	ds_bpermute_b32 v131, v27, v114
	ds_bpermute_b32 v132, v27, v115
	ds_bpermute_b32 v133, v27, v119
	ds_bpermute_b32 v134, v27, v0
	ds_bpermute_b32 v135, v27, v116
	ds_bpermute_b32 v136, v27, v111
	ds_bpermute_b32 v137, v27, v117
	ds_bpermute_b32 v138, v27, v3
	s_waitcnt lgkmcnt(4)
; __device__ __forceinline__ unsigned f2key(float f) { const unsigned u = __float_as_uint(f); return (u & 0x80000000u) ? ~u : (u | 0x80000000u); }
; #define CE_DESC(a, b) do { const unsigned _mx = (a) > (b) ? (a) : (b), _mn = (a) > (b) ? (b) : (a); (a) = _mx; (b) = _mn; } while (0)
; __device__ __forceinline__ void merge16(unsigned (&a)[16], const unsigned (&b)[16]) {
; #pragma unroll
;     for (int i = 0; i < 16; ++i) a[i] = a[i] > b[15 - i] ? a[i] : b[15 - i];
; #pragma unroll
;     for (int stride = 8; stride > 0; stride >>= 1)
; #pragma unroll
;         for (int i = 0; i < 16; ++i) { const int j = i ^ stride; if (j > i) CE_DESC(a[i], a[j]); }
; }
; __device__ __forceinline__ void peer_tile(const Args& A, LAS unsigned char* lds, int tile) {
;     ...
;                 { const bf16_t* sp = QRY + m * 2048 + hp * 128 + 32 * g;
;                   const u32x4 s0 = *(const u32x4*)sp, s1 = *(const u32x4*)(sp + 8), s2 = *(const u32x4*)(sp + 16), s3 = *(const u32x4*)(sp + 24);
;                   const unsigned sw[16] = {s0.x, s0.y, s0.z, s0.w, s1.x, s1.y, s1.z, s1.w, s2.x, s2.y, s2.z, s2.w, s3.x, s3.y, s3.z, s3.w};
; #pragma unroll
;                   for (int i = 0; i < 16; ++i) {
;                       const float lo = (float)__builtin_bit_cast(_Float16, (unsigned short)(sw[i] & 0xffffu)), hi = (float)__builtin_bit_cast(_Float16, (unsigned short)(sw[i] >> 16));
;                       const unsigned klo = (f2key(lo) & ~127u) | (unsigned)(127 - (32 * g + 2 * i)), khi = (f2key(hi) & ~127u) | (unsigned)(127 - (32 * g + 2 * i + 1));
;                       if (i < 8) { k0[2 * i] = klo; k0[2 * i + 1] = khi; } else { k1[2 * (i - 8)] = klo; k1[2 * (i - 8) + 1] = khi; } } }
;                 sort16_desc(k0); sort16_desc(k1); merge16(k0, k1);
; #pragma unroll
;                 for (int msk = 16; msk <= 32; msk <<= 1) {
; #pragma unroll
;                     for (int i = 0; i < 16; ++i) k1[i] = (unsigned)__shfl_xor((int)k0[i], msk);
;                     merge16(k0, k1); }
	v_max_u32_e32 v1, v1, v134
	s_waitcnt lgkmcnt(3)
	v_max_u32_e32 v110, v110, v135
	s_waitcnt lgkmcnt(2)
	v_max_u32_e32 v122, v122, v136
	s_waitcnt lgkmcnt(1)
	v_max_u32_e32 v118, v118, v137
	s_waitcnt lgkmcnt(0)
	v_max_u32_e32 v121, v121, v138
	v_max_u32_e32 v120, v120, v133
	v_max_u32_e32 v123, v123, v132
	v_max_u32_e32 v112, v112, v131
	v_max_u32_e32 v114, v114, v130
	v_max_u32_e32 v115, v115, v129
	v_max_u32_e32 v119, v119, v128
	v_max_u32_e32 v3, v3, v127
	v_max_u32_e32 v117, v117, v126
	v_max_u32_e32 v111, v111, v125
	v_max_u32_e32 v116, v116, v124
	v_max_u32_e32 v0, v0, v2
	v_max_u32_e32 v2, v1, v114
	v_min_u32_e32 v1, v1, v114
	v_max_u32_e32 v114, v110, v115
	v_min_u32_e32 v110, v110, v115
	v_max_u32_e32 v115, v122, v119
	v_min_u32_e32 v119, v122, v119
	v_max_u32_e32 v122, v118, v3
	v_min_u32_e32 v3, v118, v3
	v_max_u32_e32 v118, v121, v117
	v_min_u32_e32 v117, v121, v117
	v_max_u32_e32 v121, v120, v111
	v_min_u32_e32 v111, v120, v111
	v_max_u32_e32 v120, v123, v116
	v_min_u32_e32 v116, v123, v116
	v_max_u32_e32 v123, v112, v0
	v_min_u32_e32 v0, v112, v0
	v_max_u32_e32 v112, v2, v118
	v_min_u32_e32 v2, v2, v118
	v_max_u32_e32 v118, v114, v121
	v_min_u32_e32 v114, v114, v121
	v_max_u32_e32 v121, v115, v120
	v_min_u32_e32 v115, v115, v120
	v_max_u32_e32 v120, v122, v123
	v_min_u32_e32 v122, v122, v123
	v_max_u32_e32 v123, v1, v117
	v_min_u32_e32 v1, v1, v117
	v_max_u32_e32 v117, v110, v111
	v_min_u32_e32 v110, v110, v111
	v_max_u32_e32 v111, v119, v116
	v_min_u32_e32 v116, v119, v116
	v_max_u32_e32 v119, v3, v0
	v_min_u32_e32 v0, v3, v0
	v_max_u32_e32 v3, v112, v121
	v_min_u32_e32 v112, v112, v121
	v_max_u32_e32 v121, v118, v120
	v_min_u32_e32 v118, v118, v120
	v_max_u32_e32 v120, v2, v115
	v_min_u32_e32 v2, v2, v115
	v_max_u32_e32 v115, v114, v122
	v_min_u32_e32 v114, v114, v122
	v_max_u32_e32 v122, v123, v111
	v_min_u32_e32 v111, v123, v111
	v_max_u32_e32 v123, v117, v119
	v_min_u32_e32 v117, v117, v119
	v_max_u32_e32 v119, v1, v116
	v_min_u32_e32 v1, v1, v116
	v_max_u32_e32 v116, v110, v0
	v_min_u32_e32 v0, v110, v0
	v_max_u32_e32 v110, v3, v121
	v_min_u32_e32 v3, v3, v121
	v_max_u32_e32 v121, v112, v118
	v_min_u32_e32 v112, v112, v118
	v_max_u32_e32 v118, v120, v115
	v_min_u32_e32 v115, v120, v115
	v_max_u32_e32 v120, v2, v114
	v_min_u32_e32 v2, v2, v114
	v_max_u32_e32 v114, v122, v123
	v_min_u32_e32 v122, v122, v123
	v_max_u32_e32 v123, v111, v117
	v_min_u32_e32 v111, v111, v117
	v_max_u32_e32 v117, v119, v116
	v_min_u32_e32 v116, v119, v116
	v_max_u32_e32 v119, v1, v0
	v_min_u32_e32 v0, v1, v0
	ds_bpermute_b32 v128, v29, v0
	ds_bpermute_b32 v1, v29, v110
	ds_bpermute_b32 v124, v29, v3
	ds_bpermute_b32 v125, v29, v121
	ds_bpermute_b32 v126, v29, v112
	s_waitcnt lgkmcnt(4)
	v_max_u32_e32 v110, v110, v128
	global_load_dwordx4 v[128:131], v[4:5], off offset:1552
	global_load_dwordx4 v[132:135], v[4:5], off offset:1536
	ds_bpermute_b32 v127, v29, v118
	ds_bpermute_b32 v136, v29, v115
	ds_bpermute_b32 v137, v29, v120
	ds_bpermute_b32 v138, v29, v2
	ds_bpermute_b32 v139, v29, v114
	ds_bpermute_b32 v140, v29, v122
	ds_bpermute_b32 v141, v29, v123
	ds_bpermute_b32 v142, v29, v111
	ds_bpermute_b32 v143, v29, v117
	ds_bpermute_b32 v144, v29, v119
	ds_bpermute_b32 v145, v29, v116
	s_waitcnt lgkmcnt(4)
	v_max_u32_e32 v115, v115, v141
	s_waitcnt lgkmcnt(3)
	v_max_u32_e32 v118, v118, v142
	s_waitcnt lgkmcnt(2)
	v_max_u32_e32 v112, v112, v143
	s_waitcnt lgkmcnt(1)
	v_max_u32_e32 v3, v3, v144
	s_waitcnt lgkmcnt(0)
	v_max_u32_e32 v121, v121, v145
	v_max_u32_e32 v120, v120, v140
	v_max_u32_e32 v2, v2, v139
	v_max_u32_e32 v114, v114, v138
	v_max_u32_e32 v122, v122, v137
	v_max_u32_e32 v123, v123, v136
	v_max_u32_e32 v111, v111, v127
	v_max_u32_e32 v117, v117, v126
	v_max_u32_e32 v116, v116, v125
	v_max_u32_e32 v119, v119, v124
	v_max_u32_e32 v0, v0, v1
	v_max_u32_e32 v1, v110, v114
	v_min_u32_e32 v110, v110, v114
	v_max_u32_e32 v114, v3, v122
	v_min_u32_e32 v3, v3, v122
	v_max_u32_e32 v122, v121, v123
	v_min_u32_e32 v121, v121, v123
	v_max_u32_e32 v123, v112, v111
	v_min_u32_e32 v111, v112, v111
	v_max_u32_e32 v112, v118, v117
	v_min_u32_e32 v117, v118, v117
	v_max_u32_e32 v118, v115, v116
	v_min_u32_e32 v115, v115, v116
	v_max_u32_e32 v116, v120, v119
	v_min_u32_e32 v119, v120, v119
	v_max_u32_e32 v120, v2, v0
	v_min_u32_e32 v0, v2, v0
	v_max_u32_e32 v2, v1, v112
	v_min_u32_e32 v1, v1, v112
	v_max_u32_e32 v112, v114, v118
	v_min_u32_e32 v114, v114, v118
	v_max_u32_e32 v118, v122, v116
	v_min_u32_e32 v116, v122, v116
	v_max_u32_e32 v122, v123, v120
	v_min_u32_e32 v120, v123, v120
	v_max_u32_e32 v123, v110, v117
	v_min_u32_e32 v110, v110, v117
	v_max_u32_e32 v117, v3, v115
	v_min_u32_e32 v3, v3, v115
	v_max_u32_e32 v115, v121, v119
	v_min_u32_e32 v119, v121, v119
	v_max_u32_e32 v121, v111, v0
	v_min_u32_e32 v0, v111, v0
	v_max_u32_e32 v111, v2, v118
	v_min_u32_e32 v2, v2, v118
	v_max_u32_e32 v118, v112, v122
	v_min_u32_e32 v112, v112, v122
	v_max_u32_e32 v127, v1, v116
	v_min_u32_e32 v1, v1, v116
	v_max_u32_e32 v116, v114, v120
	v_min_u32_e32 v114, v114, v120
	v_max_u32_e32 v136, v123, v115
	v_min_u32_e32 v115, v123, v115
	v_max_u32_e32 v137, v117, v121
	v_min_u32_e32 v138, v117, v121
	v_max_u32_e32 v139, v110, v119
	v_min_u32_e32 v110, v110, v119
	v_max_u32_e32 v140, v3, v0
	v_min_u32_e32 v0, v3, v0
	v_max_u32_e32 v126, v111, v118
	v_min_u32_e32 v125, v111, v118
	v_max_u32_e32 v124, v2, v112
	v_min_u32_e32 v123, v2, v112
	v_max_u32_e32 v122, v127, v116
	v_min_u32_e32 v121, v127, v116
	v_max_u32_e32 v120, v1, v114
	v_min_u32_e32 v119, v1, v114
	v_max_u32_e32 v118, v136, v137
	v_min_u32_e32 v117, v136, v137
	v_max_u32_e32 v116, v115, v138
	v_min_u32_e32 v115, v115, v138
	v_max_u32_e32 v114, v139, v140
	v_min_u32_e32 v112, v139, v140
	v_max_u32_e32 v111, v110, v0
	v_min_u32_e32 v110, v110, v0
	global_load_dwordx4 v[0:3], v[4:5], off offset:1584
	global_load_dwordx4 v[136:139], v[4:5], off offset:1568
	s_waitcnt vmcnt(2)
; __device__ __forceinline__ unsigned f2key(float f) { const unsigned u = __float_as_uint(f); return (u & 0x80000000u) ? ~u : (u | 0x80000000u); }
; __device__ __forceinline__ void peer_tile(const Args& A, LAS unsigned char* lds, int tile) {
;     ...
;                 { const bf16_t* sp = QRY + m * 2048 + hp * 128 + 32 * g;
;                   const u32x4 s0 = *(const u32x4*)sp, s1 = *(const u32x4*)(sp + 8), s2 = *(const u32x4*)(sp + 16), s3 = *(const u32x4*)(sp + 24);
;                   const unsigned sw[16] = {s0.x, s0.y, s0.z, s0.w, s1.x, s1.y, s1.z, s1.w, s2.x, s2.y, s2.z, s2.w, s3.x, s3.y, s3.z, s3.w};
; #pragma unroll
;                   for (int i = 0; i < 16; ++i) {
;                       const float lo = (float)__builtin_bit_cast(_Float16, (unsigned short)(sw[i] & 0xffffu)), hi = (float)__builtin_bit_cast(_Float16, (unsigned short)(sw[i] >> 16));
;                       const unsigned klo = (f2key(lo) & ~127u) | (unsigned)(127 - (32 * g + 2 * i)), khi = (f2key(hi) & ~127u) | (unsigned)(127 - (32 * g + 2 * i + 1));
;                       if (i < 8) { k0[2 * i] = klo; k0[2 * i + 1] = khi; } else { k1[2 * (i - 8)] = klo; k1[2 * (i - 8) + 1] = khi; } } }
	v_cvt_f32_f16_sdwa v127, v132 dst_sel:DWORD dst_unused:UNUSED_PAD src0_sel:WORD_1
	v_cvt_f32_f16_e32 v132, v132
	v_not_b32_e32 v140, v127
	v_or_b32_e32 v141, 0x80000000, v127
	v_cmp_gt_i32_e32 vcc, 0, v127
	s_nop 1
	v_cndmask_b32_e32 v127, v141, v140, vcc
	v_not_b32_e32 v140, v132
	v_or_b32_e32 v141, 0x80000000, v132
	v_cmp_gt_i32_e32 vcc, 0, v132
	v_and_b32_e32 v127, 0xffffff80, v127
	v_sub_u32_e32 v127, v127, v15
	v_cndmask_b32_e32 v132, v141, v140, vcc
	v_cvt_f32_f16_sdwa v140, v133 dst_sel:DWORD dst_unused:UNUSED_PAD src0_sel:WORD_1
	v_cvt_f32_f16_e32 v133, v133
	v_and_b32_e32 v132, 0xffffff80, v132
	v_sub_u32_e32 v132, v132, v15
	v_not_b32_e32 v141, v140
	v_or_b32_e32 v142, 0x80000000, v140
	v_cmp_gt_i32_e32 vcc, 0, v140
	v_add_u32_e32 v127, 0x7e, v127
	v_add_u32_e32 v132, 0x7f, v132
	v_cndmask_b32_e32 v140, v142, v141, vcc
	v_not_b32_e32 v141, v133
	v_or_b32_e32 v142, 0x80000000, v133
	v_cmp_gt_i32_e32 vcc, 0, v133
	v_and_b32_e32 v140, 0xffffff80, v140
	v_sub_u32_e32 v140, v140, v14
	v_cndmask_b32_e32 v133, v142, v141, vcc
	v_cvt_f32_f16_sdwa v141, v134 dst_sel:DWORD dst_unused:UNUSED_PAD src0_sel:WORD_1
	v_cvt_f32_f16_e32 v134, v134
	v_and_b32_e32 v133, 0xffffff80, v133
	v_sub_u32_e32 v133, v133, v14
	v_not_b32_e32 v142, v141
	v_or_b32_e32 v143, 0x80000000, v141
	v_cmp_gt_i32_e32 vcc, 0, v141
	v_add_u32_e32 v140, 0x7e, v140
	v_add_u32_e32 v133, 0x7f, v133
	v_cndmask_b32_e32 v141, v143, v142, vcc
	v_not_b32_e32 v142, v134
	v_or_b32_e32 v143, 0x80000000, v134
	v_cmp_gt_i32_e32 vcc, 0, v134
	v_and_b32_e32 v141, 0xffffff80, v141
	v_sub_u32_e32 v141, v141, v12
	v_cndmask_b32_e32 v134, v143, v142, vcc
	v_cvt_f32_f16_sdwa v142, v135 dst_sel:DWORD dst_unused:UNUSED_PAD src0_sel:WORD_1
	v_cvt_f32_f16_e32 v135, v135
	v_and_b32_e32 v134, 0xffffff80, v134
	v_sub_u32_e32 v134, v134, v12
	v_not_b32_e32 v143, v142
	v_or_b32_e32 v144, 0x80000000, v142
	v_cmp_gt_i32_e32 vcc, 0, v142
	v_add_u32_e32 v141, 0x7e, v141
	v_add_u32_e32 v134, 0x7f, v134
	v_cndmask_b32_e32 v142, v144, v143, vcc
	v_not_b32_e32 v143, v135
	v_or_b32_e32 v144, 0x80000000, v135
	v_cmp_gt_i32_e32 vcc, 0, v135
	v_and_b32_e32 v142, 0xffffff80, v142
	v_sub_u32_e32 v142, v142, v10
	v_cndmask_b32_e32 v135, v144, v143, vcc
	v_cvt_f32_f16_sdwa v143, v128 dst_sel:DWORD dst_unused:UNUSED_PAD src0_sel:WORD_1
	v_cvt_f32_f16_e32 v128, v128
	v_and_b32_e32 v135, 0xffffff80, v135
	v_sub_u32_e32 v135, v135, v10
	v_not_b32_e32 v144, v143
	v_or_b32_e32 v145, 0x80000000, v143
	v_cmp_gt_i32_e32 vcc, 0, v143
	v_add_u32_e32 v142, 0x7e, v142
	v_add_u32_e32 v135, 0x7f, v135
	v_cndmask_b32_e32 v143, v145, v144, vcc
	v_not_b32_e32 v144, v128
	v_or_b32_e32 v145, 0x80000000, v128
	v_cmp_gt_i32_e32 vcc, 0, v128
	v_and_b32_e32 v143, 0xffffff80, v143
	v_sub_u32_e32 v143, v143, v8
	v_cndmask_b32_e32 v128, v145, v144, vcc
	v_cvt_f32_f16_sdwa v144, v129 dst_sel:DWORD dst_unused:UNUSED_PAD src0_sel:WORD_1
	v_cvt_f32_f16_e32 v129, v129
	v_and_b32_e32 v128, 0xffffff80, v128
	v_sub_u32_e32 v128, v128, v8
	v_not_b32_e32 v145, v144
	v_or_b32_e32 v146, 0x80000000, v144
	v_cmp_gt_i32_e32 vcc, 0, v144
	v_add_u32_e32 v143, 0x7e, v143
	v_add_u32_e32 v128, 0x7f, v128
	v_cndmask_b32_e32 v144, v146, v145, vcc
	v_not_b32_e32 v145, v129
	v_or_b32_e32 v146, 0x80000000, v129
	v_cmp_gt_i32_e32 vcc, 0, v129
	v_and_b32_e32 v144, 0xffffff80, v144
	v_sub_u32_e32 v144, v144, v16
	v_cndmask_b32_e32 v129, v146, v145, vcc
	v_cvt_f32_f16_sdwa v145, v130 dst_sel:DWORD dst_unused:UNUSED_PAD src0_sel:WORD_1
	v_cvt_f32_f16_e32 v130, v130
	v_and_b32_e32 v129, 0xffffff80, v129
	v_sub_u32_e32 v129, v129, v16
	v_not_b32_e32 v146, v145
	v_or_b32_e32 v147, 0x80000000, v145
	v_cmp_gt_i32_e32 vcc, 0, v145
	v_add_u32_e32 v144, 0x7e, v144
	v_add_u32_e32 v129, 0x7f, v129
	v_cndmask_b32_e32 v145, v147, v146, vcc
	v_not_b32_e32 v146, v130
	v_or_b32_e32 v147, 0x80000000, v130
	v_cmp_gt_i32_e32 vcc, 0, v130
	v_and_b32_e32 v145, 0xffffff80, v145
	v_sub_u32_e32 v145, v145, v17
	v_cndmask_b32_e32 v130, v147, v146, vcc
	v_cvt_f32_f16_sdwa v146, v131 dst_sel:DWORD dst_unused:UNUSED_PAD src0_sel:WORD_1
	v_cvt_f32_f16_e32 v131, v131
	v_and_b32_e32 v130, 0xffffff80, v130
	v_sub_u32_e32 v130, v130, v17
	v_not_b32_e32 v147, v146
	v_or_b32_e32 v148, 0x80000000, v146
	v_cmp_gt_i32_e32 vcc, 0, v146
	v_add_u32_e32 v145, 0x7e, v145
	v_add_u32_e32 v130, 0x7f, v130
	v_cndmask_b32_e32 v146, v148, v147, vcc
	v_not_b32_e32 v147, v131
	v_or_b32_e32 v148, 0x80000000, v131
	v_cmp_gt_i32_e32 vcc, 0, v131
	v_and_b32_e32 v146, 0xffffff80, v146
	v_sub_u32_e32 v146, v146, v18
	v_cndmask_b32_e32 v131, v148, v147, vcc
	s_waitcnt vmcnt(0)
; __device__ __forceinline__ unsigned f2key(float f) { const unsigned u = __float_as_uint(f); return (u & 0x80000000u) ? ~u : (u | 0x80000000u); }
; #define CE_DESC(a, b) do { const unsigned _mx = (a) > (b) ? (a) : (b), _mn = (a) > (b) ? (b) : (a); (a) = _mx; (b) = _mn; } while (0)
; __device__ __forceinline__ void sort16_desc(unsigned (&k)[16]) {
; #pragma unroll
;     for (int size = 2; size <= 16; size <<= 1)
; #pragma unroll
;         for (int stride = size >> 1; stride > 0; stride >>= 1)
; #pragma unroll
;             for (int i = 0; i < 16; ++i) { const int j = i ^ stride;
;                 if (j > i) { if ((i & size) == 0) CE_DESC(k[i], k[j]); else CE_DESC(k[j], k[i]); } }
; __device__ __forceinline__ void peer_tile(const Args& A, LAS unsigned char* lds, int tile) {
;     ...
;                   for (int i = 0; i < 16; ++i) {
;                       const float lo = (float)__builtin_bit_cast(_Float16, (unsigned short)(sw[i] & 0xffffu)), hi = (float)__builtin_bit_cast(_Float16, (unsigned short)(sw[i] >> 16));
;                       const unsigned klo = (f2key(lo) & ~127u) | (unsigned)(127 - (32 * g + 2 * i)), khi = (f2key(hi) & ~127u) | (unsigned)(127 - (32 * g + 2 * i + 1));
;                       if (i < 8) { k0[2 * i] = klo; k0[2 * i + 1] = khi; } else { k1[2 * (i - 8)] = klo; k1[2 * (i - 8) + 1] = khi; } } }
	v_cvt_f32_f16_sdwa v147, v136 dst_sel:DWORD dst_unused:UNUSED_PAD src0_sel:WORD_1
	v_cvt_f32_f16_e32 v136, v136
	v_and_b32_e32 v131, 0xffffff80, v131
	v_sub_u32_e32 v131, v131, v18
	v_not_b32_e32 v148, v147
	v_or_b32_e32 v149, 0x80000000, v147
	v_cmp_gt_i32_e32 vcc, 0, v147
	v_add_u32_e32 v146, 0x7e, v146
	v_add_u32_e32 v131, 0x7f, v131
	v_cndmask_b32_e32 v147, v149, v148, vcc
	v_not_b32_e32 v148, v136
	v_or_b32_e32 v149, 0x80000000, v136
	v_cmp_gt_i32_e32 vcc, 0, v136
	v_and_b32_e32 v147, 0xffffff80, v147
	v_sub_u32_e32 v147, v147, v20
	v_cndmask_b32_e32 v136, v149, v148, vcc
	v_cvt_f32_f16_sdwa v148, v137 dst_sel:DWORD dst_unused:UNUSED_PAD src0_sel:WORD_1
	v_cvt_f32_f16_e32 v137, v137
	v_and_b32_e32 v136, 0xffffff80, v136
	v_sub_u32_e32 v136, v136, v20
	v_not_b32_e32 v149, v148
	v_or_b32_e32 v150, 0x80000000, v148
	v_cmp_gt_i32_e32 vcc, 0, v148
	v_add_u32_e32 v147, 0x7e, v147
	v_add_u32_e32 v136, 0x7f, v136
	v_cndmask_b32_e32 v148, v150, v149, vcc
	v_not_b32_e32 v149, v137
	v_or_b32_e32 v150, 0x80000000, v137
	v_cmp_gt_i32_e32 vcc, 0, v137
	v_and_b32_e32 v148, 0xffffff80, v148
	v_sub_u32_e32 v148, v148, v21
	v_cndmask_b32_e32 v137, v150, v149, vcc
	v_cvt_f32_f16_sdwa v149, v138 dst_sel:DWORD dst_unused:UNUSED_PAD src0_sel:WORD_1
	v_cvt_f32_f16_e32 v138, v138
	v_and_b32_e32 v137, 0xffffff80, v137
	v_sub_u32_e32 v137, v137, v21
	v_not_b32_e32 v150, v149
	v_or_b32_e32 v151, 0x80000000, v149
	v_cmp_gt_i32_e32 vcc, 0, v149
	v_add_u32_e32 v148, 0x7e, v148
	v_add_u32_e32 v137, 0x7f, v137
	v_cndmask_b32_e32 v149, v151, v150, vcc
	v_not_b32_e32 v150, v138
	v_or_b32_e32 v151, 0x80000000, v138
	v_cmp_gt_i32_e32 vcc, 0, v138
	v_and_b32_e32 v149, 0xffffff80, v149
	v_sub_u32_e32 v149, v149, v22
	v_cndmask_b32_e32 v138, v151, v150, vcc
	v_cvt_f32_f16_sdwa v150, v139 dst_sel:DWORD dst_unused:UNUSED_PAD src0_sel:WORD_1
	v_cvt_f32_f16_e32 v139, v139
	v_and_b32_e32 v138, 0xffffff80, v138
	v_sub_u32_e32 v138, v138, v22
	v_not_b32_e32 v151, v150
	v_or_b32_e32 v152, 0x80000000, v150
	v_cmp_gt_i32_e32 vcc, 0, v150
	v_add_u32_e32 v149, 0x7e, v149
	v_add_u32_e32 v138, 0x7f, v138
	v_cndmask_b32_e32 v150, v152, v151, vcc
	v_not_b32_e32 v151, v139
	v_or_b32_e32 v152, 0x80000000, v139
	v_cmp_gt_i32_e32 vcc, 0, v139
	v_and_b32_e32 v150, 0xffffff80, v150
	v_sub_u32_e32 v150, v150, v23
	v_cndmask_b32_e32 v139, v152, v151, vcc
	v_cvt_f32_f16_sdwa v151, v0 dst_sel:DWORD dst_unused:UNUSED_PAD src0_sel:WORD_1
	v_cvt_f32_f16_e32 v0, v0
	v_and_b32_e32 v139, 0xffffff80, v139
	v_sub_u32_e32 v139, v139, v23
	v_not_b32_e32 v152, v151
	v_or_b32_e32 v153, 0x80000000, v151
	v_cmp_gt_i32_e32 vcc, 0, v151
	v_add_u32_e32 v150, 0x7e, v150
	v_add_u32_e32 v139, 0x7f, v139
	v_cndmask_b32_e32 v151, v153, v152, vcc
	v_not_b32_e32 v152, v0
	v_or_b32_e32 v153, 0x80000000, v0
	v_cmp_gt_i32_e32 vcc, 0, v0
	v_and_b32_e32 v151, 0xffffff80, v151
	v_sub_u32_e32 v151, v151, v24
	v_cndmask_b32_e32 v0, v153, v152, vcc
	v_cvt_f32_f16_sdwa v152, v1 dst_sel:DWORD dst_unused:UNUSED_PAD src0_sel:WORD_1
	v_cvt_f32_f16_e32 v1, v1
	v_and_b32_e32 v0, 0xffffff80, v0
	v_sub_u32_e32 v0, v0, v24
	v_not_b32_e32 v153, v152
	v_or_b32_e32 v154, 0x80000000, v152
	v_cmp_gt_i32_e32 vcc, 0, v152
	v_add_u32_e32 v151, 0x7e, v151
	v_add_u32_e32 v0, 0x7f, v0
	v_cndmask_b32_e32 v152, v154, v153, vcc
	v_not_b32_e32 v153, v1
	v_or_b32_e32 v154, 0x80000000, v1
	v_cmp_gt_i32_e32 vcc, 0, v1
	v_and_b32_e32 v152, 0xffffff80, v152
	v_sub_u32_e32 v152, v152, v25
	v_cndmask_b32_e32 v1, v154, v153, vcc
	v_cvt_f32_f16_sdwa v153, v2 dst_sel:DWORD dst_unused:UNUSED_PAD src0_sel:WORD_1
	v_cvt_f32_f16_e32 v2, v2
	v_and_b32_e32 v1, 0xffffff80, v1
	v_sub_u32_e32 v1, v1, v25
	v_not_b32_e32 v154, v153
	v_or_b32_e32 v155, 0x80000000, v153
	v_cmp_gt_i32_e32 vcc, 0, v153
	v_add_u32_e32 v152, 0x7e, v152
	v_add_u32_e32 v1, 0x7f, v1
	v_cndmask_b32_e32 v153, v155, v154, vcc
	v_not_b32_e32 v154, v2
	v_or_b32_e32 v155, 0x80000000, v2
	v_cmp_gt_i32_e32 vcc, 0, v2
	v_and_b32_e32 v153, 0xffffff80, v153
	v_sub_u32_e32 v153, v153, v26
	v_cndmask_b32_e32 v2, v155, v154, vcc
	v_cvt_f32_f16_sdwa v154, v3 dst_sel:DWORD dst_unused:UNUSED_PAD src0_sel:WORD_1
	v_cvt_f32_f16_e32 v3, v3
	v_and_b32_e32 v2, 0xffffff80, v2
	v_sub_u32_e32 v2, v2, v26
	v_not_b32_e32 v155, v154
	v_or_b32_e32 v156, 0x80000000, v154
	v_cmp_gt_i32_e32 vcc, 0, v154
	v_add_u32_e32 v153, 0x7e, v153
	v_add_u32_e32 v2, 0x7f, v2
	v_cndmask_b32_e32 v154, v156, v155, vcc
	v_not_b32_e32 v155, v3
	v_or_b32_e32 v156, 0x80000000, v3
	v_cmp_gt_i32_e32 vcc, 0, v3
	v_and_b32_e32 v154, 0xffffff80, v154
	v_sub_u32_e32 v154, v154, v28
	v_cndmask_b32_e32 v3, v156, v155, vcc
	v_and_b32_e32 v3, 0xffffff80, v3
	v_sub_u32_e32 v3, v3, v28
	v_add_u32_e32 v154, 0x7e, v154
	v_add_u32_e32 v3, 0x7f, v3
	v_max_u32_e32 v155, v132, v127
	v_min_u32_e32 v127, v132, v127
	v_max_u32_e32 v132, v140, v133
	v_min_u32_e32 v133, v140, v133
	v_max_u32_e32 v140, v134, v141
	v_min_u32_e32 v134, v134, v141
	v_max_u32_e32 v141, v142, v135
	v_min_u32_e32 v135, v142, v135
	v_max_u32_e32 v142, v128, v143
	v_min_u32_e32 v128, v128, v143
	v_max_u32_e32 v143, v144, v129
	v_min_u32_e32 v129, v144, v129
	v_max_u32_e32 v144, v130, v145
	v_min_u32_e32 v130, v130, v145
	v_max_u32_e32 v145, v146, v131
	v_min_u32_e32 v131, v146, v131
	v_max_u32_e32 v163, v136, v147
	v_min_u32_e32 v136, v136, v147
	v_max_u32_e32 v147, v148, v137
	v_min_u32_e32 v137, v148, v137
	v_max_u32_e32 v148, v138, v149
	v_min_u32_e32 v138, v138, v149
	v_max_u32_e32 v149, v150, v139
	v_min_u32_e32 v139, v150, v139
	v_max_u32_e32 v150, v0, v151
	v_min_u32_e32 v0, v0, v151
	v_max_u32_e32 v151, v152, v1
	v_min_u32_e32 v1, v152, v1
	v_max_u32_e32 v152, v2, v153
	v_min_u32_e32 v2, v2, v153
; #define CE_DESC(a, b) do { const unsigned _mx = (a) > (b) ? (a) : (b), _mn = (a) > (b) ? (b) : (a); (a) = _mx; (b) = _mn; } while (0)
; __device__ __forceinline__ void sort16_desc(unsigned (&k)[16]) {
; #pragma unroll
;     for (int size = 2; size <= 16; size <<= 1)
; #pragma unroll
;         for (int stride = size >> 1; stride > 0; stride >>= 1)
; #pragma unroll
;             for (int i = 0; i < 16; ++i) { const int j = i ^ stride;
;                 if (j > i) { if ((i & size) == 0) CE_DESC(k[i], k[j]); else CE_DESC(k[j], k[i]); } }
	v_max_u32_e32 v153, v154, v3
	v_min_u32_e32 v3, v154, v3
	v_max_u32_e32 v146, v155, v133
	v_min_u32_e32 v133, v155, v133
	v_max_u32_e32 v155, v127, v132
	v_min_u32_e32 v127, v127, v132
	v_max_u32_e32 v132, v135, v140
	v_min_u32_e32 v135, v135, v140
	v_max_u32_e32 v140, v141, v134
	v_min_u32_e32 v134, v141, v134
	v_max_u32_e32 v141, v142, v129
	v_min_u32_e32 v129, v142, v129
	v_max_u32_e32 v142, v128, v143
	v_min_u32_e32 v128, v128, v143
	v_max_u32_e32 v143, v131, v144
	v_min_u32_e32 v131, v131, v144
	v_max_u32_e32 v144, v145, v130
	v_min_u32_e32 v130, v145, v130
	v_max_u32_e32 v154, v163, v137
	v_min_u32_e32 v137, v163, v137
	v_max_u32_e32 v163, v136, v147
	v_min_u32_e32 v136, v136, v147
	v_max_u32_e32 v147, v139, v148
	v_min_u32_e32 v139, v139, v148
	v_max_u32_e32 v148, v149, v138
	v_min_u32_e32 v138, v149, v138
	v_max_u32_e32 v149, v150, v1
	v_min_u32_e32 v1, v150, v1
	v_max_u32_e32 v150, v0, v151
	v_min_u32_e32 v0, v0, v151
	v_max_u32_e32 v151, v3, v152
	v_min_u32_e32 v3, v3, v152
	v_max_u32_e32 v152, v153, v2
	v_min_u32_e32 v2, v153, v2
	v_max_u32_e32 v145, v146, v155
	v_min_u32_e32 v146, v146, v155
	v_max_u32_e32 v155, v133, v127
	v_min_u32_e32 v127, v133, v127
	v_max_u32_e32 v133, v134, v135
	v_min_u32_e32 v134, v134, v135
	v_max_u32_e32 v135, v140, v132
	v_min_u32_e32 v132, v140, v132
	v_max_u32_e32 v140, v141, v142
	v_min_u32_e32 v141, v141, v142
	v_max_u32_e32 v142, v129, v128
	v_min_u32_e32 v128, v129, v128
	v_max_u32_e32 v129, v130, v131
	v_min_u32_e32 v130, v130, v131
	v_max_u32_e32 v131, v144, v143
	v_min_u32_e32 v143, v144, v143
	v_max_u32_e32 v153, v154, v163
	v_min_u32_e32 v154, v154, v163
	v_max_u32_e32 v163, v137, v136
	v_min_u32_e32 v136, v137, v136
	v_max_u32_e32 v137, v138, v139
	v_min_u32_e32 v138, v138, v139
	v_max_u32_e32 v139, v148, v147
	v_min_u32_e32 v147, v148, v147
	v_max_u32_e32 v148, v149, v150
	v_min_u32_e32 v149, v149, v150
	v_max_u32_e32 v150, v1, v0
	v_min_u32_e32 v0, v1, v0
	v_max_u32_e32 v1, v2, v3
	v_min_u32_e32 v2, v2, v3
	v_max_u32_e32 v3, v152, v151
	v_min_u32_e32 v151, v152, v151
	v_max_u32_e32 v144, v145, v134
	v_min_u32_e32 v134, v145, v134
	v_max_u32_e32 v145, v146, v133
	v_min_u32_e32 v133, v146, v133
	v_max_u32_e32 v146, v155, v132
	v_min_u32_e32 v132, v155, v132
	v_max_u32_e32 v155, v127, v135
	v_min_u32_e32 v127, v127, v135
	v_max_u32_e32 v135, v130, v140
	v_min_u32_e32 v130, v130, v140
	v_max_u32_e32 v140, v129, v141
	v_min_u32_e32 v129, v129, v141
	v_max_u32_e32 v141, v143, v142
	v_min_u32_e32 v142, v143, v142
	v_max_u32_e32 v143, v131, v128
	v_min_u32_e32 v128, v131, v128
	v_max_u32_e32 v152, v153, v138
	v_min_u32_e32 v138, v153, v138
	v_max_u32_e32 v153, v154, v137
	v_min_u32_e32 v137, v154, v137
	v_max_u32_e32 v154, v163, v147
	v_min_u32_e32 v147, v163, v147
	v_max_u32_e32 v163, v136, v139
	v_min_u32_e32 v136, v136, v139
	v_max_u32_e32 v139, v2, v148
	v_min_u32_e32 v2, v2, v148
	v_max_u32_e32 v148, v1, v149
	v_min_u32_e32 v1, v1, v149
	v_max_u32_e32 v149, v151, v150
	v_min_u32_e32 v150, v151, v150
	v_max_u32_e32 v151, v3, v0
	v_min_u32_e32 v0, v3, v0
	v_max_u32_e32 v131, v144, v146
	v_min_u32_e32 v144, v144, v146
	v_max_u32_e32 v146, v145, v155
	v_min_u32_e32 v145, v145, v155
	v_max_u32_e32 v155, v134, v132
	v_min_u32_e32 v132, v134, v132
	v_max_u32_e32 v134, v133, v127
	v_min_u32_e32 v127, v133, v127
	v_max_u32_e32 v133, v142, v130
	v_min_u32_e32 v130, v142, v130
	v_max_u32_e32 v142, v128, v129
	v_min_u32_e32 v128, v128, v129
	v_max_u32_e32 v129, v141, v135
	v_min_u32_e32 v135, v141, v135
	v_max_u32_e32 v141, v143, v140
	v_min_u32_e32 v140, v143, v140
	v_max_u32_e32 v3, v152, v154
	v_min_u32_e32 v152, v152, v154
	v_max_u32_e32 v154, v153, v163
	v_min_u32_e32 v153, v153, v163
	v_max_u32_e32 v163, v138, v147
	v_min_u32_e32 v138, v138, v147
	v_max_u32_e32 v147, v137, v136
	v_min_u32_e32 v136, v137, v136
	v_max_u32_e32 v137, v150, v2
	v_min_u32_e32 v2, v150, v2
	v_max_u32_e32 v150, v0, v1
	v_min_u32_e32 v0, v0, v1
	v_max_u32_e32 v1, v149, v139
	v_min_u32_e32 v139, v149, v139
	v_max_u32_e32 v149, v151, v148
	v_min_u32_e32 v148, v151, v148
	v_max_u32_e32 v143, v131, v146
	v_min_u32_e32 v131, v131, v146
	v_max_u32_e32 v146, v144, v145
	v_min_u32_e32 v144, v144, v145
	v_max_u32_e32 v145, v155, v134
	v_min_u32_e32 v134, v155, v134
	v_max_u32_e32 v155, v132, v127
	v_min_u32_e32 v127, v132, v127
	v_max_u32_e32 v132, v128, v130
	v_min_u32_e32 v128, v128, v130
	v_max_u32_e32 v130, v142, v133
	v_min_u32_e32 v133, v142, v133
	v_max_u32_e32 v142, v140, v135
	v_min_u32_e32 v135, v140, v135
	v_max_u32_e32 v140, v141, v129
	v_min_u32_e32 v129, v141, v129
	v_max_u32_e32 v151, v3, v154
	v_min_u32_e32 v3, v3, v154
	v_max_u32_e32 v154, v152, v153
	v_min_u32_e32 v152, v152, v153
	v_max_u32_e32 v153, v163, v147
	v_min_u32_e32 v147, v163, v147
	v_max_u32_e32 v163, v138, v136
	v_min_u32_e32 v136, v138, v136
	v_max_u32_e32 v138, v0, v2
	v_min_u32_e32 v0, v0, v2
	v_max_u32_e32 v2, v150, v137
	v_min_u32_e32 v137, v150, v137
	v_max_u32_e32 v150, v148, v139
	v_min_u32_e32 v139, v148, v139
	v_max_u32_e32 v148, v149, v1
	v_min_u32_e32 v1, v149, v1
	v_max_u32_e32 v141, v143, v128
	v_min_u32_e32 v128, v143, v128
	v_max_u32_e32 v143, v131, v132
	v_min_u32_e32 v131, v131, v132
	v_max_u32_e32 v132, v146, v133
	v_min_u32_e32 v133, v146, v133
	v_max_u32_e32 v146, v144, v130
	v_min_u32_e32 v130, v144, v130
	v_max_u32_e32 v144, v145, v135
	v_min_u32_e32 v135, v145, v135
	v_max_u32_e32 v145, v134, v142
	v_min_u32_e32 v134, v134, v142
	v_max_u32_e32 v142, v155, v129
	v_min_u32_e32 v129, v155, v129
	v_max_u32_e32 v155, v127, v140
	v_min_u32_e32 v127, v127, v140
	v_max_u32_e32 v149, v151, v0
	v_min_u32_e32 v0, v151, v0
; #define CE_DESC(a, b) do { const unsigned _mx = (a) > (b) ? (a) : (b), _mn = (a) > (b) ? (b) : (a); (a) = _mx; (b) = _mn; } while (0)
; __device__ __forceinline__ void sort16_desc(unsigned (&k)[16]) {
; #pragma unroll
;     for (int size = 2; size <= 16; size <<= 1)
; #pragma unroll
;         for (int stride = size >> 1; stride > 0; stride >>= 1)
; #pragma unroll
;             for (int i = 0; i < 16; ++i) { const int j = i ^ stride;
;                 if (j > i) { if ((i & size) == 0) CE_DESC(k[i], k[j]); else CE_DESC(k[j], k[i]); } }
; }
; __device__ __forceinline__ void merge16(unsigned (&a)[16], const unsigned (&b)[16]) {
; #pragma unroll
;     for (int i = 0; i < 16; ++i) a[i] = a[i] > b[15 - i] ? a[i] : b[15 - i];
; #pragma unroll
;     for (int stride = 8; stride > 0; stride >>= 1)
; #pragma unroll
;         for (int i = 0; i < 16; ++i) { const int j = i ^ stride; if (j > i) CE_DESC(a[i], a[j]); }
; }
; __device__ __forceinline__ void peer_tile(const Args& A, LAS unsigned char* lds, int tile) {
;     ...
;                 for (int msk = 16; msk <= 32; msk <<= 1) {
; #pragma unroll
;                     for (int i = 0; i < 16; ++i) k1[i] = (unsigned)__shfl_xor((int)k0[i], msk);
;                     merge16(k0, k1); }
	v_max_u32_e32 v151, v3, v138
	v_min_u32_e32 v3, v3, v138
	v_max_u32_e32 v138, v154, v137
	v_min_u32_e32 v137, v154, v137
	v_max_u32_e32 v154, v152, v2
	v_min_u32_e32 v2, v152, v2
	v_max_u32_e32 v152, v153, v139
	v_min_u32_e32 v139, v153, v139
	v_max_u32_e32 v153, v147, v150
	v_min_u32_e32 v147, v147, v150
	v_max_u32_e32 v150, v163, v1
	v_min_u32_e32 v1, v163, v1
	v_max_u32_e32 v163, v136, v148
	v_min_u32_e32 v136, v136, v148
	v_max_u32_e32 v140, v141, v144
	v_min_u32_e32 v141, v141, v144
	v_max_u32_e32 v144, v143, v145
	v_min_u32_e32 v143, v143, v145
	v_max_u32_e32 v145, v132, v142
	v_min_u32_e32 v132, v132, v142
	v_max_u32_e32 v142, v146, v155
	v_min_u32_e32 v146, v146, v155
	v_max_u32_e32 v155, v128, v135
	v_min_u32_e32 v128, v128, v135
	v_max_u32_e32 v135, v131, v134
	v_min_u32_e32 v131, v131, v134
	v_max_u32_e32 v134, v133, v129
	v_min_u32_e32 v129, v133, v129
	v_max_u32_e32 v133, v130, v127
	v_min_u32_e32 v127, v130, v127
	v_max_u32_e32 v148, v149, v152
	v_min_u32_e32 v149, v149, v152
	v_max_u32_e32 v152, v151, v153
	v_min_u32_e32 v151, v151, v153
	v_max_u32_e32 v153, v138, v150
	v_min_u32_e32 v138, v138, v150
	v_max_u32_e32 v150, v154, v163
	v_min_u32_e32 v154, v154, v163
	v_max_u32_e32 v163, v0, v139
	v_min_u32_e32 v0, v0, v139
	v_max_u32_e32 v139, v3, v147
	v_min_u32_e32 v3, v3, v147
	v_max_u32_e32 v147, v137, v1
	v_min_u32_e32 v1, v137, v1
	v_max_u32_e32 v137, v2, v136
	v_min_u32_e32 v2, v2, v136
	v_max_u32_e32 v130, v140, v145
	v_min_u32_e32 v140, v140, v145
	v_max_u32_e32 v145, v144, v142
	v_min_u32_e32 v142, v144, v142
	v_max_u32_e32 v144, v141, v132
	v_min_u32_e32 v132, v141, v132
	v_max_u32_e32 v141, v143, v146
	v_min_u32_e32 v143, v143, v146
	v_max_u32_e32 v146, v155, v134
	v_min_u32_e32 v134, v155, v134
	v_max_u32_e32 v155, v135, v133
	v_min_u32_e32 v133, v135, v133
	v_max_u32_e32 v135, v128, v129
	v_min_u32_e32 v128, v128, v129
	v_max_u32_e32 v129, v131, v127
	v_min_u32_e32 v127, v131, v127
	v_max_u32_e32 v136, v148, v153
	v_min_u32_e32 v148, v148, v153
	v_max_u32_e32 v153, v152, v150
	v_min_u32_e32 v150, v152, v150
	v_max_u32_e32 v152, v149, v138
	v_min_u32_e32 v138, v149, v138
	v_max_u32_e32 v149, v151, v154
	v_min_u32_e32 v151, v151, v154
	v_max_u32_e32 v154, v163, v147
	v_min_u32_e32 v147, v163, v147
	v_max_u32_e32 v163, v139, v137
	v_min_u32_e32 v137, v139, v137
	v_max_u32_e32 v139, v0, v1
	v_min_u32_e32 v0, v0, v1
	v_max_u32_e32 v1, v3, v2
	v_min_u32_e32 v2, v3, v2
	v_min_u32_e32 v131, v130, v145
	v_min_u32_e32 v156, v140, v142
	v_min_u32_e32 v157, v144, v141
	v_min_u32_e32 v158, v132, v143
	v_min_u32_e32 v159, v146, v155
	v_min_u32_e32 v160, v134, v133
	v_min_u32_e32 v161, v135, v129
	v_min_u32_e32 v162, v128, v127
	v_min_u32_e32 v3, v136, v153
	v_min_u32_e32 v164, v148, v150
	v_min_u32_e32 v165, v152, v149
	v_min_u32_e32 v166, v138, v151
	v_min_u32_e32 v167, v154, v163
	v_min_u32_e32 v168, v147, v137
	v_min_u32_e32 v169, v139, v1
	v_min_u32_e32 v170, v0, v2
	v_max3_u32 v130, v130, v145, v170
	v_max3_u32 v0, v131, v0, v2
	v_max3_u32 v2, v140, v142, v169
	v_max3_u32 v1, v156, v139, v1
	v_max3_u32 v131, v144, v141, v168
	v_max3_u32 v137, v157, v147, v137
	v_max3_u32 v132, v132, v143, v167
	v_max3_u32 v139, v158, v154, v163
	v_max3_u32 v140, v146, v155, v166
	v_max3_u32 v138, v159, v138, v151
	v_max3_u32 v133, v134, v133, v165
	v_max3_u32 v134, v160, v152, v149
	v_max3_u32 v129, v135, v129, v164
	v_max3_u32 v135, v161, v148, v150
	v_max3_u32 v3, v128, v127, v3
	v_max3_u32 v127, v162, v136, v153
	v_max_u32_e32 v128, v130, v140
	v_min_u32_e32 v130, v130, v140
	v_max_u32_e32 v136, v0, v138
	v_min_u32_e32 v0, v0, v138
	v_max_u32_e32 v138, v2, v133
	v_min_u32_e32 v2, v2, v133
	v_max_u32_e32 v133, v1, v134
	v_min_u32_e32 v1, v1, v134
	v_max_u32_e32 v134, v131, v129
	v_min_u32_e32 v129, v131, v129
	v_max_u32_e32 v131, v137, v135
	v_min_u32_e32 v135, v137, v135
	v_max_u32_e32 v137, v132, v3
	v_min_u32_e32 v3, v132, v3
	v_max_u32_e32 v132, v139, v127
	v_min_u32_e32 v127, v139, v127
	v_max_u32_e32 v139, v128, v134
	v_min_u32_e32 v128, v128, v134
	v_max_u32_e32 v134, v136, v131
	v_min_u32_e32 v131, v136, v131
	v_max_u32_e32 v136, v138, v137
	v_min_u32_e32 v137, v138, v137
	v_max_u32_e32 v138, v133, v132
	v_min_u32_e32 v132, v133, v132
	v_max_u32_e32 v133, v130, v129
	v_min_u32_e32 v129, v130, v129
	v_max_u32_e32 v130, v0, v135
	v_min_u32_e32 v0, v0, v135
	v_max_u32_e32 v135, v2, v3
	v_min_u32_e32 v2, v2, v3
	v_max_u32_e32 v3, v1, v127
	v_min_u32_e32 v1, v1, v127
	v_max_u32_e32 v127, v139, v136
	v_min_u32_e32 v136, v139, v136
	v_max_u32_e32 v139, v134, v138
	v_min_u32_e32 v134, v134, v138
	v_max_u32_e32 v138, v128, v137
	v_min_u32_e32 v128, v128, v137
	v_max_u32_e32 v137, v131, v132
	v_min_u32_e32 v131, v131, v132
	v_max_u32_e32 v132, v133, v135
	v_min_u32_e32 v133, v133, v135
	v_max_u32_e32 v135, v130, v3
	v_min_u32_e32 v3, v130, v3
	v_max_u32_e32 v130, v129, v2
	v_min_u32_e32 v2, v129, v2
	v_max_u32_e32 v129, v0, v1
	v_min_u32_e32 v0, v0, v1
	v_max_u32_e32 v1, v127, v139
	v_min_u32_e32 v127, v127, v139
	v_max_u32_e32 v139, v136, v134
	v_min_u32_e32 v134, v136, v134
	v_max_u32_e32 v136, v138, v137
	v_min_u32_e32 v137, v138, v137
	v_max_u32_e32 v138, v128, v131
	v_min_u32_e32 v128, v128, v131
	v_max_u32_e32 v131, v132, v135
	v_min_u32_e32 v132, v132, v135
	v_max_u32_e32 v135, v133, v3
	v_min_u32_e32 v3, v133, v3
	v_max_u32_e32 v133, v130, v129
	v_min_u32_e32 v129, v130, v129
	v_max_u32_e32 v130, v2, v0
	v_min_u32_e32 v0, v2, v0
	ds_bpermute_b32 v2, v27, v1
	ds_bpermute_b32 v140, v27, v127
	ds_bpermute_b32 v141, v27, v139
	ds_bpermute_b32 v142, v27, v134
	ds_bpermute_b32 v143, v27, v136
	ds_bpermute_b32 v144, v27, v137
	ds_bpermute_b32 v145, v27, v138
	ds_bpermute_b32 v146, v27, v128
	ds_bpermute_b32 v147, v27, v131
	ds_bpermute_b32 v148, v27, v132
	ds_bpermute_b32 v149, v27, v135
	ds_bpermute_b32 v150, v27, v0
	ds_bpermute_b32 v151, v27, v130
	ds_bpermute_b32 v152, v27, v129
	ds_bpermute_b32 v153, v27, v133
	ds_bpermute_b32 v154, v27, v3
	s_waitcnt lgkmcnt(4)
; __device__ __forceinline__ unsigned f2key(float f) { const unsigned u = __float_as_uint(f); return (u & 0x80000000u) ? ~u : (u | 0x80000000u); }
; #define CE_DESC(a, b) do { const unsigned _mx = (a) > (b) ? (a) : (b), _mn = (a) > (b) ? (b) : (a); (a) = _mx; (b) = _mn; } while (0)
; __device__ __forceinline__ void merge16(unsigned (&a)[16], const unsigned (&b)[16]) {
; #pragma unroll
;     for (int i = 0; i < 16; ++i) a[i] = a[i] > b[15 - i] ? a[i] : b[15 - i];
; #pragma unroll
;     for (int stride = 8; stride > 0; stride >>= 1)
; #pragma unroll
;         for (int i = 0; i < 16; ++i) { const int j = i ^ stride; if (j > i) CE_DESC(a[i], a[j]); }
; }
; __device__ __forceinline__ void peer_tile(const Args& A, LAS unsigned char* lds, int tile) {
;     ...
;                 { const bf16_t* sp = QRY + m * 2048 + hp * 128 + 32 * g;
;                   const u32x4 s0 = *(const u32x4*)sp, s1 = *(const u32x4*)(sp + 8), s2 = *(const u32x4*)(sp + 16), s3 = *(const u32x4*)(sp + 24);
;                   const unsigned sw[16] = {s0.x, s0.y, s0.z, s0.w, s1.x, s1.y, s1.z, s1.w, s2.x, s2.y, s2.z, s2.w, s3.x, s3.y, s3.z, s3.w};
; #pragma unroll
;                   for (int i = 0; i < 16; ++i) {
;                       const float lo = (float)__builtin_bit_cast(_Float16, (unsigned short)(sw[i] & 0xffffu)), hi = (float)__builtin_bit_cast(_Float16, (unsigned short)(sw[i] >> 16));
;                       const unsigned klo = (f2key(lo) & ~127u) | (unsigned)(127 - (32 * g + 2 * i)), khi = (f2key(hi) & ~127u) | (unsigned)(127 - (32 * g + 2 * i + 1));
;                       if (i < 8) { k0[2 * i] = klo; k0[2 * i + 1] = khi; } else { k1[2 * (i - 8)] = klo; k1[2 * (i - 8) + 1] = khi; } } }
;                 sort16_desc(k0); sort16_desc(k1); merge16(k0, k1);
; #pragma unroll
;                 for (int msk = 16; msk <= 32; msk <<= 1) {
; #pragma unroll
;                     for (int i = 0; i < 16; ++i) k1[i] = (unsigned)__shfl_xor((int)k0[i], msk);
;                     merge16(k0, k1); }
	v_max_u32_e32 v1, v1, v150
	s_waitcnt lgkmcnt(3)
	v_max_u32_e32 v127, v127, v151
	s_waitcnt lgkmcnt(2)
	v_max_u32_e32 v139, v139, v152
	s_waitcnt lgkmcnt(1)
	v_max_u32_e32 v134, v134, v153
	s_waitcnt lgkmcnt(0)
	v_max_u32_e32 v136, v136, v154
	v_max_u32_e32 v137, v137, v149
	v_max_u32_e32 v138, v138, v148
	v_max_u32_e32 v128, v128, v147
	v_max_u32_e32 v131, v131, v146
	v_max_u32_e32 v132, v132, v145
	v_max_u32_e32 v135, v135, v144
	v_max_u32_e32 v3, v3, v143
	v_max_u32_e32 v133, v133, v142
	v_max_u32_e32 v129, v129, v141
	v_max_u32_e32 v130, v130, v140
	v_max_u32_e32 v0, v0, v2
	v_max_u32_e32 v2, v1, v131
	v_min_u32_e32 v1, v1, v131
	v_max_u32_e32 v131, v127, v132
	v_min_u32_e32 v127, v127, v132
	v_max_u32_e32 v132, v139, v135
	v_min_u32_e32 v135, v139, v135
	v_max_u32_e32 v139, v134, v3
	v_min_u32_e32 v3, v134, v3
	v_max_u32_e32 v134, v136, v133
	v_min_u32_e32 v133, v136, v133
	v_max_u32_e32 v136, v137, v129
	v_min_u32_e32 v129, v137, v129
	v_max_u32_e32 v137, v138, v130
	v_min_u32_e32 v130, v138, v130
	v_max_u32_e32 v138, v128, v0
	v_min_u32_e32 v0, v128, v0
	v_max_u32_e32 v128, v2, v134
	v_min_u32_e32 v2, v2, v134
	v_max_u32_e32 v134, v131, v136
	v_min_u32_e32 v131, v131, v136
	v_max_u32_e32 v136, v132, v137
	v_min_u32_e32 v132, v132, v137
	v_max_u32_e32 v137, v139, v138
	v_min_u32_e32 v138, v139, v138
	v_max_u32_e32 v139, v1, v133
	v_min_u32_e32 v1, v1, v133
	v_max_u32_e32 v133, v127, v129
	v_min_u32_e32 v127, v127, v129
	v_max_u32_e32 v129, v135, v130
	v_min_u32_e32 v130, v135, v130
	v_max_u32_e32 v135, v3, v0
	v_min_u32_e32 v0, v3, v0
	v_max_u32_e32 v3, v128, v136
	v_min_u32_e32 v128, v128, v136
	v_max_u32_e32 v136, v134, v137
	v_min_u32_e32 v134, v134, v137
	v_max_u32_e32 v137, v2, v132
	v_min_u32_e32 v2, v2, v132
	v_max_u32_e32 v132, v131, v138
	v_min_u32_e32 v131, v131, v138
	v_max_u32_e32 v138, v139, v129
	v_min_u32_e32 v129, v139, v129
	v_max_u32_e32 v139, v133, v135
	v_min_u32_e32 v133, v133, v135
	v_max_u32_e32 v135, v1, v130
	v_min_u32_e32 v1, v1, v130
	v_max_u32_e32 v130, v127, v0
	v_min_u32_e32 v0, v127, v0
	v_max_u32_e32 v127, v3, v136
	v_min_u32_e32 v3, v3, v136
	v_max_u32_e32 v136, v128, v134
	v_min_u32_e32 v128, v128, v134
	v_max_u32_e32 v134, v137, v132
	v_min_u32_e32 v132, v137, v132
	v_max_u32_e32 v137, v2, v131
	v_min_u32_e32 v2, v2, v131
	v_max_u32_e32 v131, v138, v139
	v_min_u32_e32 v138, v138, v139
	v_max_u32_e32 v139, v129, v133
	v_min_u32_e32 v129, v129, v133
	v_max_u32_e32 v133, v135, v130
	v_min_u32_e32 v130, v135, v130
	v_max_u32_e32 v135, v1, v0
	v_min_u32_e32 v0, v1, v0
	ds_bpermute_b32 v144, v29, v0
	ds_bpermute_b32 v1, v29, v127
	ds_bpermute_b32 v140, v29, v3
	ds_bpermute_b32 v141, v29, v136
	ds_bpermute_b32 v142, v29, v128
	s_waitcnt lgkmcnt(4)
	v_max_u32_e32 v127, v127, v144
	global_load_dwordx4 v[144:147], v[4:5], off offset:1808
	global_load_dwordx4 v[148:151], v[4:5], off offset:1792
	ds_bpermute_b32 v143, v29, v134
	ds_bpermute_b32 v152, v29, v132
	ds_bpermute_b32 v153, v29, v137
	ds_bpermute_b32 v154, v29, v2
	ds_bpermute_b32 v155, v29, v131
	ds_bpermute_b32 v156, v29, v138
	ds_bpermute_b32 v157, v29, v139
	ds_bpermute_b32 v158, v29, v129
	ds_bpermute_b32 v159, v29, v133
	ds_bpermute_b32 v160, v29, v135
	ds_bpermute_b32 v161, v29, v130
	s_waitcnt lgkmcnt(4)
	v_max_u32_e32 v132, v132, v157
	s_waitcnt lgkmcnt(3)
	v_max_u32_e32 v134, v134, v158
	s_waitcnt lgkmcnt(2)
	v_max_u32_e32 v128, v128, v159
	s_waitcnt lgkmcnt(1)
	v_max_u32_e32 v3, v3, v160
	s_waitcnt lgkmcnt(0)
	v_max_u32_e32 v136, v136, v161
	v_max_u32_e32 v137, v137, v156
	v_max_u32_e32 v2, v2, v155
	v_max_u32_e32 v131, v131, v154
	v_max_u32_e32 v138, v138, v153
	v_max_u32_e32 v139, v139, v152
	v_max_u32_e32 v129, v129, v143
	v_max_u32_e32 v133, v133, v142
	v_max_u32_e32 v130, v130, v141
	v_max_u32_e32 v135, v135, v140
	v_max_u32_e32 v0, v0, v1
	v_max_u32_e32 v1, v127, v131
	v_min_u32_e32 v127, v127, v131
	v_max_u32_e32 v131, v3, v138
	v_min_u32_e32 v3, v3, v138
	v_max_u32_e32 v138, v136, v139
	v_min_u32_e32 v136, v136, v139
	v_max_u32_e32 v139, v128, v129
	v_min_u32_e32 v128, v128, v129
	v_max_u32_e32 v129, v134, v133
	v_min_u32_e32 v133, v134, v133
	v_max_u32_e32 v134, v132, v130
	v_min_u32_e32 v130, v132, v130
	v_max_u32_e32 v132, v137, v135
	v_min_u32_e32 v135, v137, v135
	v_max_u32_e32 v137, v2, v0
	v_min_u32_e32 v0, v2, v0
	v_max_u32_e32 v2, v1, v129
	v_min_u32_e32 v1, v1, v129
	v_max_u32_e32 v129, v131, v134
	v_min_u32_e32 v131, v131, v134
	v_max_u32_e32 v134, v138, v132
	v_min_u32_e32 v132, v138, v132
	v_max_u32_e32 v138, v139, v137
	v_min_u32_e32 v137, v139, v137
	v_max_u32_e32 v139, v127, v133
	v_min_u32_e32 v127, v127, v133
	v_max_u32_e32 v133, v3, v130
	v_min_u32_e32 v3, v3, v130
	v_max_u32_e32 v130, v136, v135
	v_min_u32_e32 v135, v136, v135
	v_max_u32_e32 v136, v128, v0
	v_min_u32_e32 v0, v128, v0
	v_max_u32_e32 v128, v2, v134
	v_min_u32_e32 v2, v2, v134
	v_max_u32_e32 v134, v129, v138
	v_min_u32_e32 v129, v129, v138
	v_max_u32_e32 v143, v1, v132
	v_min_u32_e32 v1, v1, v132
	v_max_u32_e32 v132, v131, v137
	v_min_u32_e32 v131, v131, v137
	v_max_u32_e32 v152, v139, v130
	v_min_u32_e32 v130, v139, v130
	v_max_u32_e32 v153, v133, v136
	v_min_u32_e32 v154, v133, v136
	v_max_u32_e32 v155, v127, v135
	v_min_u32_e32 v127, v127, v135
	v_max_u32_e32 v156, v3, v0
	v_min_u32_e32 v0, v3, v0
	v_max_u32_e32 v142, v128, v134
	v_min_u32_e32 v141, v128, v134
	v_max_u32_e32 v140, v2, v129
	v_min_u32_e32 v139, v2, v129
	v_max_u32_e32 v138, v143, v132
	v_min_u32_e32 v137, v143, v132
	v_max_u32_e32 v136, v1, v131
	v_min_u32_e32 v135, v1, v131
	v_max_u32_e32 v134, v152, v153
	v_min_u32_e32 v133, v152, v153
	v_max_u32_e32 v132, v130, v154
	v_min_u32_e32 v131, v130, v154
	v_max_u32_e32 v130, v155, v156
	v_min_u32_e32 v129, v155, v156
	v_max_u32_e32 v128, v127, v0
	v_min_u32_e32 v127, v127, v0
	global_load_dwordx4 v[0:3], v[4:5], off offset:1840
	global_load_dwordx4 v[152:155], v[4:5], off offset:1824
	s_waitcnt vmcnt(2)
; __device__ __forceinline__ unsigned f2key(float f) { const unsigned u = __float_as_uint(f); return (u & 0x80000000u) ? ~u : (u | 0x80000000u); }
; __device__ __forceinline__ void peer_tile(const Args& A, LAS unsigned char* lds, int tile) {
;     ...
;                 { const bf16_t* sp = QRY + m * 2048 + hp * 128 + 32 * g;
;                   const u32x4 s0 = *(const u32x4*)sp, s1 = *(const u32x4*)(sp + 8), s2 = *(const u32x4*)(sp + 16), s3 = *(const u32x4*)(sp + 24);
;                   const unsigned sw[16] = {s0.x, s0.y, s0.z, s0.w, s1.x, s1.y, s1.z, s1.w, s2.x, s2.y, s2.z, s2.w, s3.x, s3.y, s3.z, s3.w};
; #pragma unroll
;                   for (int i = 0; i < 16; ++i) {
;                       const float lo = (float)__builtin_bit_cast(_Float16, (unsigned short)(sw[i] & 0xffffu)), hi = (float)__builtin_bit_cast(_Float16, (unsigned short)(sw[i] >> 16));
;                       const unsigned klo = (f2key(lo) & ~127u) | (unsigned)(127 - (32 * g + 2 * i)), khi = (f2key(hi) & ~127u) | (unsigned)(127 - (32 * g + 2 * i + 1));
;                       if (i < 8) { k0[2 * i] = klo; k0[2 * i + 1] = khi; } else { k1[2 * (i - 8)] = klo; k1[2 * (i - 8) + 1] = khi; } } }
	v_cvt_f32_f16_sdwa v143, v148 dst_sel:DWORD dst_unused:UNUSED_PAD src0_sel:WORD_1
	v_cvt_f32_f16_e32 v4, v148
	v_not_b32_e32 v5, v143
	v_or_b32_e32 v148, 0x80000000, v143
	v_cmp_gt_i32_e32 vcc, 0, v143
	v_not_b32_e32 v143, v4
	s_nop 0
	v_cndmask_b32_e32 v5, v148, v5, vcc
	v_or_b32_e32 v148, 0x80000000, v4
	v_cmp_gt_i32_e32 vcc, 0, v4
	v_and_b32_e32 v5, 0xffffff80, v5
	v_sub_u32_e32 v5, v5, v15
	v_cndmask_b32_e32 v4, v148, v143, vcc
	v_and_b32_e32 v4, 0xffffff80, v4
	v_cvt_f32_f16_sdwa v143, v149 dst_sel:DWORD dst_unused:UNUSED_PAD src0_sel:WORD_1
	v_sub_u32_e32 v4, v4, v15
	v_cvt_f32_f16_e32 v15, v149
	v_add_u32_e32 v5, 0x7e, v5
	v_not_b32_e32 v148, v143
	v_or_b32_e32 v149, 0x80000000, v143
	v_cmp_gt_i32_e32 vcc, 0, v143
	v_add_u32_e32 v4, 0x7f, v4
	s_nop 0
	v_cndmask_b32_e32 v143, v149, v148, vcc
	v_not_b32_e32 v148, v15
	v_or_b32_e32 v149, 0x80000000, v15
	v_cmp_gt_i32_e32 vcc, 0, v15
	v_and_b32_e32 v143, 0xffffff80, v143
	v_sub_u32_e32 v143, v143, v14
	v_cndmask_b32_e32 v15, v149, v148, vcc
	v_and_b32_e32 v15, 0xffffff80, v15
	v_cvt_f32_f16_sdwa v148, v150 dst_sel:DWORD dst_unused:UNUSED_PAD src0_sel:WORD_1
	v_sub_u32_e32 v14, v15, v14
	v_cvt_f32_f16_e32 v15, v150
	v_add_u32_e32 v143, 0x7e, v143
	v_not_b32_e32 v149, v148
	v_or_b32_e32 v150, 0x80000000, v148
	v_cmp_gt_i32_e32 vcc, 0, v148
	v_add_u32_e32 v14, 0x7f, v14
	s_nop 0
	v_cndmask_b32_e32 v148, v150, v149, vcc
	v_not_b32_e32 v149, v15
	v_or_b32_e32 v150, 0x80000000, v15
	v_cmp_gt_i32_e32 vcc, 0, v15
	v_and_b32_e32 v148, 0xffffff80, v148
	v_sub_u32_e32 v148, v148, v12
	v_cndmask_b32_e32 v15, v150, v149, vcc
	v_and_b32_e32 v15, 0xffffff80, v15
	v_cvt_f32_f16_sdwa v149, v151 dst_sel:DWORD dst_unused:UNUSED_PAD src0_sel:WORD_1
	v_sub_u32_e32 v12, v15, v12
	v_cvt_f32_f16_e32 v15, v151
	v_add_u32_e32 v148, 0x7e, v148
	v_not_b32_e32 v150, v149
	v_or_b32_e32 v151, 0x80000000, v149
	v_cmp_gt_i32_e32 vcc, 0, v149
	v_add_u32_e32 v12, 0x7f, v12
	s_nop 0
	v_cndmask_b32_e32 v149, v151, v150, vcc
	v_not_b32_e32 v150, v15
	v_or_b32_e32 v151, 0x80000000, v15
	v_cmp_gt_i32_e32 vcc, 0, v15
	v_and_b32_e32 v149, 0xffffff80, v149
	v_sub_u32_e32 v149, v149, v10
	v_cndmask_b32_e32 v15, v151, v150, vcc
	v_and_b32_e32 v15, 0xffffff80, v15
	v_cvt_f32_f16_sdwa v150, v144 dst_sel:DWORD dst_unused:UNUSED_PAD src0_sel:WORD_1
	v_sub_u32_e32 v10, v15, v10
	v_cvt_f32_f16_e32 v15, v144
	v_add_u32_e32 v149, 0x7e, v149
	v_not_b32_e32 v144, v150
	v_or_b32_e32 v151, 0x80000000, v150
	v_cmp_gt_i32_e32 vcc, 0, v150
	v_not_b32_e32 v150, v15
	v_add_u32_e32 v10, 0x7f, v10
	v_cndmask_b32_e32 v144, v151, v144, vcc
	v_or_b32_e32 v151, 0x80000000, v15
	v_cmp_gt_i32_e32 vcc, 0, v15
	v_and_b32_e32 v144, 0xffffff80, v144
	v_sub_u32_e32 v144, v144, v8
	v_cndmask_b32_e32 v15, v151, v150, vcc
	v_and_b32_e32 v15, 0xffffff80, v15
	v_cvt_f32_f16_sdwa v150, v145 dst_sel:DWORD dst_unused:UNUSED_PAD src0_sel:WORD_1
	v_sub_u32_e32 v8, v15, v8
	v_cvt_f32_f16_e32 v15, v145
	v_add_u32_e32 v144, 0x7e, v144
	v_not_b32_e32 v145, v150
	v_or_b32_e32 v151, 0x80000000, v150
	v_cmp_gt_i32_e32 vcc, 0, v150
	v_not_b32_e32 v150, v15
	v_add_u32_e32 v8, 0x7f, v8
	v_cndmask_b32_e32 v145, v151, v145, vcc
	v_or_b32_e32 v151, 0x80000000, v15
	v_cmp_gt_i32_e32 vcc, 0, v15
	v_and_b32_e32 v145, 0xffffff80, v145
	v_sub_u32_e32 v145, v145, v16
	v_cndmask_b32_e32 v15, v151, v150, vcc
	v_and_b32_e32 v15, 0xffffff80, v15
	v_cvt_f32_f16_sdwa v150, v146 dst_sel:DWORD dst_unused:UNUSED_PAD src0_sel:WORD_1
	v_sub_u32_e32 v15, v15, v16
	v_cvt_f32_f16_e32 v16, v146
	v_add_u32_e32 v145, 0x7e, v145
	v_not_b32_e32 v146, v150
	v_or_b32_e32 v151, 0x80000000, v150
	v_cmp_gt_i32_e32 vcc, 0, v150
	v_not_b32_e32 v150, v16
	v_add_u32_e32 v15, 0x7f, v15
	v_cndmask_b32_e32 v146, v151, v146, vcc
	v_or_b32_e32 v151, 0x80000000, v16
	v_cmp_gt_i32_e32 vcc, 0, v16
	v_and_b32_e32 v146, 0xffffff80, v146
	v_sub_u32_e32 v146, v146, v17
	v_cndmask_b32_e32 v16, v151, v150, vcc
	v_and_b32_e32 v16, 0xffffff80, v16
	v_cvt_f32_f16_sdwa v150, v147 dst_sel:DWORD dst_unused:UNUSED_PAD src0_sel:WORD_1
	v_sub_u32_e32 v16, v16, v17
	v_cvt_f32_f16_e32 v17, v147
	v_add_u32_e32 v146, 0x7e, v146
	v_not_b32_e32 v147, v150
	v_or_b32_e32 v151, 0x80000000, v150
	v_cmp_gt_i32_e32 vcc, 0, v150
	v_not_b32_e32 v150, v17
	v_add_u32_e32 v16, 0x7f, v16
	v_cndmask_b32_e32 v147, v151, v147, vcc
	v_or_b32_e32 v151, 0x80000000, v17
	v_cmp_gt_i32_e32 vcc, 0, v17
	v_and_b32_e32 v147, 0xffffff80, v147
	v_sub_u32_e32 v147, v147, v18
	v_cndmask_b32_e32 v17, v151, v150, vcc
	v_and_b32_e32 v17, 0xffffff80, v17
	s_waitcnt vmcnt(0)
; __device__ __forceinline__ unsigned f2key(float f) { const unsigned u = __float_as_uint(f); return (u & 0x80000000u) ? ~u : (u | 0x80000000u); }
; #define CE_DESC(a, b) do { const unsigned _mx = (a) > (b) ? (a) : (b), _mn = (a) > (b) ? (b) : (a); (a) = _mx; (b) = _mn; } while (0)
; __device__ __forceinline__ void sort16_desc(unsigned (&k)[16]) {
; #pragma unroll
;     for (int size = 2; size <= 16; size <<= 1)
; #pragma unroll
;         for (int stride = size >> 1; stride > 0; stride >>= 1)
; #pragma unroll
;             for (int i = 0; i < 16; ++i) { const int j = i ^ stride;
;                 if (j > i) { if ((i & size) == 0) CE_DESC(k[i], k[j]); else CE_DESC(k[j], k[i]); } }
; __device__ __forceinline__ void peer_tile(const Args& A, LAS unsigned char* lds, int tile) {
;     ...
;                   for (int i = 0; i < 16; ++i) {
;                       const float lo = (float)__builtin_bit_cast(_Float16, (unsigned short)(sw[i] & 0xffffu)), hi = (float)__builtin_bit_cast(_Float16, (unsigned short)(sw[i] >> 16));
;                       const unsigned klo = (f2key(lo) & ~127u) | (unsigned)(127 - (32 * g + 2 * i)), khi = (f2key(hi) & ~127u) | (unsigned)(127 - (32 * g + 2 * i + 1));
;                       if (i < 8) { k0[2 * i] = klo; k0[2 * i + 1] = khi; } else { k1[2 * (i - 8)] = klo; k1[2 * (i - 8) + 1] = khi; } } }
	v_cvt_f32_f16_sdwa v150, v152 dst_sel:DWORD dst_unused:UNUSED_PAD src0_sel:WORD_1
	v_sub_u32_e32 v17, v17, v18
	v_cvt_f32_f16_e32 v18, v152
	v_add_u32_e32 v147, 0x7e, v147
	v_not_b32_e32 v151, v150
	v_or_b32_e32 v152, 0x80000000, v150
	v_cmp_gt_i32_e32 vcc, 0, v150
	v_add_u32_e32 v17, 0x7f, v17
	s_nop 0
	v_cndmask_b32_e32 v150, v152, v151, vcc
	v_not_b32_e32 v151, v18
	v_or_b32_e32 v152, 0x80000000, v18
	v_cmp_gt_i32_e32 vcc, 0, v18
	v_and_b32_e32 v150, 0xffffff80, v150
	v_sub_u32_e32 v150, v150, v20
	v_cndmask_b32_e32 v18, v152, v151, vcc
	v_and_b32_e32 v18, 0xffffff80, v18
	v_cvt_f32_f16_sdwa v151, v153 dst_sel:DWORD dst_unused:UNUSED_PAD src0_sel:WORD_1
	v_sub_u32_e32 v18, v18, v20
	v_cvt_f32_f16_e32 v20, v153
	v_add_u32_e32 v150, 0x7e, v150
	v_not_b32_e32 v152, v151
	v_or_b32_e32 v153, 0x80000000, v151
	v_cmp_gt_i32_e32 vcc, 0, v151
	v_add_u32_e32 v18, 0x7f, v18
	v_max_u32_e32 v161, v18, v150
	v_cndmask_b32_e32 v151, v153, v152, vcc
	v_not_b32_e32 v152, v20
	v_or_b32_e32 v153, 0x80000000, v20
	v_cmp_gt_i32_e32 vcc, 0, v20
	v_and_b32_e32 v151, 0xffffff80, v151
	v_sub_u32_e32 v151, v151, v21
	v_cndmask_b32_e32 v20, v153, v152, vcc
	v_and_b32_e32 v20, 0xffffff80, v20
	v_cvt_f32_f16_sdwa v152, v154 dst_sel:DWORD dst_unused:UNUSED_PAD src0_sel:WORD_1
	v_sub_u32_e32 v20, v20, v21
	v_cvt_f32_f16_e32 v21, v154
	v_add_u32_e32 v151, 0x7e, v151
	v_not_b32_e32 v153, v152
	v_or_b32_e32 v154, 0x80000000, v152
	v_cmp_gt_i32_e32 vcc, 0, v152
	v_add_u32_e32 v20, 0x7f, v20
	v_min_u32_e32 v18, v18, v150
	v_cndmask_b32_e32 v152, v154, v153, vcc
	v_not_b32_e32 v153, v21
	v_or_b32_e32 v154, 0x80000000, v21
	v_cmp_gt_i32_e32 vcc, 0, v21
	v_and_b32_e32 v152, 0xffffff80, v152
	v_sub_u32_e32 v152, v152, v22
	v_cndmask_b32_e32 v21, v154, v153, vcc
	v_and_b32_e32 v21, 0xffffff80, v21
	v_cvt_f32_f16_sdwa v153, v155 dst_sel:DWORD dst_unused:UNUSED_PAD src0_sel:WORD_1
	v_sub_u32_e32 v21, v21, v22
	v_cvt_f32_f16_e32 v22, v155
	v_add_u32_e32 v152, 0x7e, v152
	v_not_b32_e32 v154, v153
	v_or_b32_e32 v155, 0x80000000, v153
	v_cmp_gt_i32_e32 vcc, 0, v153
	v_add_u32_e32 v21, 0x7f, v21
	v_max_u32_e32 v150, v151, v20
	v_cndmask_b32_e32 v153, v155, v154, vcc
	v_not_b32_e32 v154, v22
	v_or_b32_e32 v155, 0x80000000, v22
	v_cmp_gt_i32_e32 vcc, 0, v22
	v_and_b32_e32 v153, 0xffffff80, v153
	v_sub_u32_e32 v153, v153, v23
	v_cndmask_b32_e32 v22, v155, v154, vcc
	v_cvt_f32_f16_sdwa v154, v0 dst_sel:DWORD dst_unused:UNUSED_PAD src0_sel:WORD_1
	v_cvt_f32_f16_e32 v0, v0
	v_and_b32_e32 v22, 0xffffff80, v22
	v_sub_u32_e32 v22, v22, v23
	v_not_b32_e32 v23, v154
	v_or_b32_e32 v155, 0x80000000, v154
	v_cmp_gt_i32_e32 vcc, 0, v154
	v_not_b32_e32 v154, v0
	v_add_u32_e32 v153, 0x7e, v153
	v_cndmask_b32_e32 v23, v155, v23, vcc
	v_or_b32_e32 v155, 0x80000000, v0
	v_cmp_gt_i32_e32 vcc, 0, v0
	v_and_b32_e32 v23, 0xffffff80, v23
	v_sub_u32_e32 v23, v23, v24
	v_cndmask_b32_e32 v0, v155, v154, vcc
	v_cvt_f32_f16_sdwa v154, v1 dst_sel:DWORD dst_unused:UNUSED_PAD src0_sel:WORD_1
	v_cvt_f32_f16_e32 v1, v1
	v_and_b32_e32 v0, 0xffffff80, v0
	v_sub_u32_e32 v0, v0, v24
	v_not_b32_e32 v24, v154
	v_or_b32_e32 v155, 0x80000000, v154
	v_cmp_gt_i32_e32 vcc, 0, v154
	v_not_b32_e32 v154, v1
	v_add_u32_e32 v22, 0x7f, v22
	v_cndmask_b32_e32 v24, v155, v24, vcc
	v_or_b32_e32 v155, 0x80000000, v1
	v_cmp_gt_i32_e32 vcc, 0, v1
	v_and_b32_e32 v24, 0xffffff80, v24
	v_sub_u32_e32 v24, v24, v25
	v_cndmask_b32_e32 v1, v155, v154, vcc
	v_cvt_f32_f16_sdwa v154, v2 dst_sel:DWORD dst_unused:UNUSED_PAD src0_sel:WORD_1
	v_cvt_f32_f16_e32 v2, v2
	v_and_b32_e32 v1, 0xffffff80, v1
	v_sub_u32_e32 v1, v1, v25
	v_not_b32_e32 v25, v154
	v_or_b32_e32 v155, 0x80000000, v154
	v_cmp_gt_i32_e32 vcc, 0, v154
	v_not_b32_e32 v154, v2
	v_add_u32_e32 v23, 0x7e, v23
	v_cndmask_b32_e32 v25, v155, v25, vcc
	v_or_b32_e32 v155, 0x80000000, v2
	v_cmp_gt_i32_e32 vcc, 0, v2
	v_and_b32_e32 v25, 0xffffff80, v25
	v_sub_u32_e32 v25, v25, v26
	v_cndmask_b32_e32 v2, v155, v154, vcc
	v_cvt_f32_f16_sdwa v154, v3 dst_sel:DWORD dst_unused:UNUSED_PAD src0_sel:WORD_1
	v_cvt_f32_f16_e32 v3, v3
	v_and_b32_e32 v2, 0xffffff80, v2
	v_sub_u32_e32 v2, v2, v26
	v_not_b32_e32 v26, v154
	v_or_b32_e32 v155, 0x80000000, v154
	v_cmp_gt_i32_e32 vcc, 0, v154
	v_not_b32_e32 v154, v3
	v_add_u32_e32 v0, 0x7f, v0
	v_cndmask_b32_e32 v26, v155, v26, vcc
	v_or_b32_e32 v155, 0x80000000, v3
	v_cmp_gt_i32_e32 vcc, 0, v3
	v_and_b32_e32 v26, 0xffffff80, v26
	v_sub_u32_e32 v26, v26, v28
	v_cndmask_b32_e32 v3, v155, v154, vcc
	v_and_b32_e32 v3, 0xffffff80, v3
	v_sub_u32_e32 v3, v3, v28
	v_add_u32_e32 v24, 0x7e, v24
	v_add_u32_e32 v1, 0x7f, v1
	v_add_u32_e32 v25, 0x7e, v25
	v_add_u32_e32 v2, 0x7f, v2
	v_add_u32_e32 v26, 0x7e, v26
	v_add_u32_e32 v3, 0x7f, v3
	v_max_u32_e32 v28, v4, v5
	v_min_u32_e32 v4, v4, v5
	v_max_u32_e32 v5, v143, v14
	v_min_u32_e32 v14, v143, v14
	v_max_u32_e32 v143, v12, v148
	v_min_u32_e32 v12, v12, v148
	v_max_u32_e32 v148, v149, v10
	v_min_u32_e32 v10, v149, v10
	v_max_u32_e32 v149, v8, v144
	v_min_u32_e32 v8, v8, v144
	v_max_u32_e32 v144, v145, v15
	v_min_u32_e32 v15, v145, v15
	v_max_u32_e32 v145, v16, v146
	v_min_u32_e32 v16, v16, v146
	v_max_u32_e32 v146, v147, v17
	v_min_u32_e32 v17, v147, v17
	v_min_u32_e32 v20, v151, v20
	v_max_u32_e32 v151, v21, v152
	v_min_u32_e32 v21, v21, v152
	v_max_u32_e32 v152, v153, v22
	v_min_u32_e32 v22, v153, v22
	v_max_u32_e32 v153, v0, v23
	v_min_u32_e32 v0, v0, v23
	v_max_u32_e32 v23, v24, v1
	v_min_u32_e32 v1, v24, v1
	v_max_u32_e32 v24, v2, v25
	v_min_u32_e32 v2, v2, v25
	v_max_u32_e32 v25, v26, v3
	v_min_u32_e32 v3, v26, v3
	v_max_u32_e32 v147, v28, v14
	v_min_u32_e32 v14, v28, v14
	v_max_u32_e32 v28, v4, v5
	v_min_u32_e32 v4, v4, v5
; #define CE_DESC(a, b) do { const unsigned _mx = (a) > (b) ? (a) : (b), _mn = (a) > (b) ? (b) : (a); (a) = _mx; (b) = _mn; } while (0)
; __device__ __forceinline__ void sort16_desc(unsigned (&k)[16]) {
; #pragma unroll
;     for (int size = 2; size <= 16; size <<= 1)
; #pragma unroll
;         for (int stride = size >> 1; stride > 0; stride >>= 1)
; #pragma unroll
;             for (int i = 0; i < 16; ++i) { const int j = i ^ stride;
;                 if (j > i) { if ((i & size) == 0) CE_DESC(k[i], k[j]); else CE_DESC(k[j], k[i]); } }
	v_max_u32_e32 v5, v10, v143
	v_min_u32_e32 v10, v10, v143
	v_max_u32_e32 v143, v148, v12
	v_min_u32_e32 v12, v148, v12
	v_max_u32_e32 v148, v149, v15
	v_min_u32_e32 v15, v149, v15
	v_max_u32_e32 v149, v8, v144
	v_min_u32_e32 v8, v8, v144
	v_max_u32_e32 v144, v17, v145
	v_min_u32_e32 v17, v17, v145
	v_max_u32_e32 v145, v146, v16
	v_min_u32_e32 v16, v146, v16
	v_max_u32_e32 v26, v161, v20
	v_min_u32_e32 v20, v161, v20
	v_max_u32_e32 v161, v18, v150
	v_min_u32_e32 v18, v18, v150
	v_max_u32_e32 v150, v22, v151
	v_min_u32_e32 v22, v22, v151
	v_max_u32_e32 v151, v152, v21
	v_min_u32_e32 v21, v152, v21
	v_max_u32_e32 v152, v153, v1
	v_min_u32_e32 v1, v153, v1
	v_max_u32_e32 v153, v0, v23
	v_min_u32_e32 v0, v0, v23
	v_max_u32_e32 v23, v3, v24
	v_min_u32_e32 v3, v3, v24
	v_max_u32_e32 v24, v25, v2
	v_min_u32_e32 v2, v25, v2
	v_max_u32_e32 v146, v147, v28
	v_min_u32_e32 v28, v147, v28
	v_max_u32_e32 v147, v14, v4
	v_min_u32_e32 v4, v14, v4
	v_max_u32_e32 v14, v12, v10
	v_min_u32_e32 v10, v12, v10
	v_max_u32_e32 v12, v143, v5
	v_min_u32_e32 v5, v143, v5
	v_max_u32_e32 v143, v148, v149
	v_min_u32_e32 v148, v148, v149
	v_max_u32_e32 v149, v15, v8
	v_min_u32_e32 v8, v15, v8
	v_max_u32_e32 v15, v16, v17
	v_min_u32_e32 v16, v16, v17
	v_max_u32_e32 v17, v145, v144
	v_min_u32_e32 v144, v145, v144
	v_max_u32_e32 v25, v26, v161
	v_min_u32_e32 v26, v26, v161
	v_max_u32_e32 v161, v20, v18
	v_min_u32_e32 v18, v20, v18
	v_max_u32_e32 v20, v21, v22
	v_min_u32_e32 v21, v21, v22
	v_max_u32_e32 v22, v151, v150
	v_min_u32_e32 v150, v151, v150
	v_max_u32_e32 v151, v152, v153
	v_min_u32_e32 v152, v152, v153
	v_max_u32_e32 v153, v1, v0
	v_min_u32_e32 v0, v1, v0
	v_max_u32_e32 v1, v2, v3
	v_min_u32_e32 v2, v2, v3
	v_max_u32_e32 v3, v24, v23
	v_min_u32_e32 v23, v24, v23
	v_max_u32_e32 v145, v146, v10
	v_min_u32_e32 v10, v146, v10
	v_max_u32_e32 v146, v28, v14
	v_min_u32_e32 v14, v28, v14
	v_max_u32_e32 v28, v147, v5
	v_min_u32_e32 v5, v147, v5
	v_max_u32_e32 v147, v4, v12
	v_min_u32_e32 v4, v4, v12
	v_max_u32_e32 v12, v16, v143
	v_min_u32_e32 v16, v16, v143
	v_max_u32_e32 v143, v15, v148
	v_min_u32_e32 v15, v15, v148
	v_max_u32_e32 v148, v144, v149
	v_min_u32_e32 v144, v144, v149
	v_max_u32_e32 v149, v17, v8
	v_min_u32_e32 v8, v17, v8
	v_max_u32_e32 v24, v25, v21
	v_min_u32_e32 v21, v25, v21
	v_max_u32_e32 v25, v26, v20
	v_min_u32_e32 v20, v26, v20
	v_max_u32_e32 v26, v161, v150
	v_min_u32_e32 v150, v161, v150
	v_max_u32_e32 v161, v18, v22
	v_min_u32_e32 v18, v18, v22
	v_max_u32_e32 v22, v2, v151
	v_min_u32_e32 v2, v2, v151
	v_max_u32_e32 v151, v1, v152
	v_min_u32_e32 v1, v1, v152
	v_max_u32_e32 v152, v23, v153
	v_min_u32_e32 v23, v23, v153
	v_max_u32_e32 v153, v3, v0
	v_min_u32_e32 v0, v3, v0
	v_max_u32_e32 v17, v145, v28
	v_min_u32_e32 v28, v145, v28
	v_max_u32_e32 v145, v146, v147
	v_min_u32_e32 v146, v146, v147
	v_max_u32_e32 v147, v10, v5
	v_min_u32_e32 v5, v10, v5
	v_max_u32_e32 v10, v14, v4
	v_min_u32_e32 v4, v14, v4
	v_max_u32_e32 v14, v144, v16
	v_min_u32_e32 v16, v144, v16
	v_max_u32_e32 v144, v8, v15
	v_min_u32_e32 v8, v8, v15
	v_max_u32_e32 v15, v148, v12
	v_min_u32_e32 v12, v148, v12
	v_max_u32_e32 v148, v149, v143
	v_min_u32_e32 v143, v149, v143
	v_max_u32_e32 v3, v24, v26
	v_min_u32_e32 v24, v24, v26
	v_max_u32_e32 v26, v25, v161
	v_min_u32_e32 v25, v25, v161
	v_max_u32_e32 v161, v21, v150
	v_min_u32_e32 v21, v21, v150
	v_max_u32_e32 v150, v20, v18
	v_min_u32_e32 v18, v20, v18
	v_max_u32_e32 v20, v23, v2
	v_min_u32_e32 v2, v23, v2
	v_max_u32_e32 v23, v0, v1
	v_min_u32_e32 v0, v0, v1
	v_max_u32_e32 v1, v152, v22
	v_min_u32_e32 v22, v152, v22
	v_max_u32_e32 v152, v153, v151
	v_min_u32_e32 v151, v153, v151
	v_max_u32_e32 v149, v17, v145
	v_min_u32_e32 v17, v17, v145
	v_max_u32_e32 v145, v28, v146
	v_min_u32_e32 v28, v28, v146
	v_max_u32_e32 v146, v147, v10
	v_min_u32_e32 v10, v147, v10
	v_max_u32_e32 v147, v5, v4
	v_min_u32_e32 v4, v5, v4
	v_max_u32_e32 v5, v8, v16
	v_min_u32_e32 v8, v8, v16
	v_max_u32_e32 v16, v144, v14
	v_min_u32_e32 v14, v144, v14
	v_max_u32_e32 v144, v143, v12
	v_min_u32_e32 v12, v143, v12
	v_max_u32_e32 v143, v148, v15
	v_min_u32_e32 v15, v148, v15
	v_max_u32_e32 v153, v3, v26
	v_min_u32_e32 v3, v3, v26
	v_max_u32_e32 v26, v24, v25
	v_min_u32_e32 v24, v24, v25
	v_max_u32_e32 v25, v161, v150
	v_min_u32_e32 v150, v161, v150
	v_max_u32_e32 v161, v21, v18
	v_min_u32_e32 v18, v21, v18
	v_max_u32_e32 v21, v0, v2
	v_min_u32_e32 v0, v0, v2
	v_max_u32_e32 v2, v23, v20
	v_min_u32_e32 v20, v23, v20
	v_max_u32_e32 v23, v151, v22
	v_min_u32_e32 v22, v151, v22
	v_max_u32_e32 v151, v152, v1
	v_min_u32_e32 v1, v152, v1
	v_max_u32_e32 v148, v149, v8
	v_min_u32_e32 v8, v149, v8
	v_max_u32_e32 v149, v17, v5
	v_min_u32_e32 v5, v17, v5
	v_max_u32_e32 v17, v145, v14
	v_min_u32_e32 v14, v145, v14
	v_max_u32_e32 v145, v28, v16
	v_min_u32_e32 v16, v28, v16
	v_max_u32_e32 v28, v146, v12
	v_min_u32_e32 v12, v146, v12
	v_max_u32_e32 v146, v10, v144
	v_min_u32_e32 v10, v10, v144
	v_max_u32_e32 v144, v147, v15
	v_min_u32_e32 v15, v147, v15
	v_max_u32_e32 v147, v4, v143
	v_min_u32_e32 v4, v4, v143
	v_max_u32_e32 v152, v153, v0
	v_min_u32_e32 v0, v153, v0
	v_max_u32_e32 v153, v3, v21
	v_min_u32_e32 v3, v3, v21
	v_max_u32_e32 v21, v26, v20
	v_min_u32_e32 v20, v26, v20
	v_max_u32_e32 v26, v24, v2
	v_min_u32_e32 v2, v24, v2
	v_max_u32_e32 v24, v25, v22
	v_min_u32_e32 v22, v25, v22
	v_max_u32_e32 v25, v150, v23
	v_min_u32_e32 v23, v150, v23
	v_max_u32_e32 v150, v161, v1
	v_min_u32_e32 v1, v161, v1
	v_max_u32_e32 v161, v18, v151
	v_min_u32_e32 v18, v18, v151
	v_max_u32_e32 v143, v148, v28
	v_min_u32_e32 v28, v148, v28
	v_max_u32_e32 v148, v149, v146
	v_min_u32_e32 v146, v149, v146
; #define CE_DESC(a, b) do { const unsigned _mx = (a) > (b) ? (a) : (b), _mn = (a) > (b) ? (b) : (a); (a) = _mx; (b) = _mn; } while (0)
; __device__ __forceinline__ void merge16(unsigned (&a)[16], const unsigned (&b)[16]) {
; #pragma unroll
;     for (int i = 0; i < 16; ++i) a[i] = a[i] > b[15 - i] ? a[i] : b[15 - i];
; #pragma unroll
;     for (int stride = 8; stride > 0; stride >>= 1)
; #pragma unroll
;         for (int i = 0; i < 16; ++i) { const int j = i ^ stride; if (j > i) CE_DESC(a[i], a[j]); }
; }
; __device__ __forceinline__ void peer_tile(const Args& A, LAS unsigned char* lds, int tile) {
;     ...
;                 sort16_desc(k0); sort16_desc(k1); merge16(k0, k1);
; #pragma unroll
;                 for (int msk = 16; msk <= 32; msk <<= 1) {
; #pragma unroll
;                     for (int i = 0; i < 16; ++i) k1[i] = (unsigned)__shfl_xor((int)k0[i], msk);
;                     merge16(k0, k1); }
	v_max_u32_e32 v149, v17, v144
	v_min_u32_e32 v17, v17, v144
	v_max_u32_e32 v144, v145, v147
	v_min_u32_e32 v145, v145, v147
	v_max_u32_e32 v147, v8, v12
	v_min_u32_e32 v8, v8, v12
	v_max_u32_e32 v12, v5, v10
	v_min_u32_e32 v5, v5, v10
	v_max_u32_e32 v10, v14, v15
	v_min_u32_e32 v14, v14, v15
	v_max_u32_e32 v15, v16, v4
	v_min_u32_e32 v4, v16, v4
	v_max_u32_e32 v151, v152, v24
	v_min_u32_e32 v24, v152, v24
	v_max_u32_e32 v152, v153, v25
	v_min_u32_e32 v25, v153, v25
	v_max_u32_e32 v153, v21, v150
	v_min_u32_e32 v21, v21, v150
	v_max_u32_e32 v150, v26, v161
	v_min_u32_e32 v26, v26, v161
	v_max_u32_e32 v161, v0, v22
	v_min_u32_e32 v0, v0, v22
	v_max_u32_e32 v22, v3, v23
	v_min_u32_e32 v3, v3, v23
	v_max_u32_e32 v23, v20, v1
	v_min_u32_e32 v1, v20, v1
	v_max_u32_e32 v20, v2, v18
	v_min_u32_e32 v2, v2, v18
	v_max_u32_e32 v16, v143, v149
	v_min_u32_e32 v143, v143, v149
	v_max_u32_e32 v149, v148, v144
	v_min_u32_e32 v144, v148, v144
	v_max_u32_e32 v148, v28, v17
	v_min_u32_e32 v17, v28, v17
	v_max_u32_e32 v28, v146, v145
	v_min_u32_e32 v145, v146, v145
	v_max_u32_e32 v146, v147, v10
	v_min_u32_e32 v10, v147, v10
	v_max_u32_e32 v147, v12, v15
	v_min_u32_e32 v12, v12, v15
	v_max_u32_e32 v15, v8, v14
	v_min_u32_e32 v8, v8, v14
	v_max_u32_e32 v14, v5, v4
	v_min_u32_e32 v4, v5, v4
	v_max_u32_e32 v18, v151, v153
	v_min_u32_e32 v151, v151, v153
	v_max_u32_e32 v153, v152, v150
	v_min_u32_e32 v150, v152, v150
	v_max_u32_e32 v152, v24, v21
	v_min_u32_e32 v21, v24, v21
	v_max_u32_e32 v24, v25, v26
	v_min_u32_e32 v25, v25, v26
	v_max_u32_e32 v26, v161, v23
	v_min_u32_e32 v23, v161, v23
	v_max_u32_e32 v161, v22, v20
	v_min_u32_e32 v20, v22, v20
	v_max_u32_e32 v22, v0, v1
	v_min_u32_e32 v0, v0, v1
	v_max_u32_e32 v1, v3, v2
	v_min_u32_e32 v2, v3, v2
	v_min_u32_e32 v5, v16, v149
	v_min_u32_e32 v154, v143, v144
	v_min_u32_e32 v155, v148, v28
	v_min_u32_e32 v156, v17, v145
	v_min_u32_e32 v157, v146, v147
	v_min_u32_e32 v158, v10, v12
	v_min_u32_e32 v159, v15, v14
	v_min_u32_e32 v160, v8, v4
	v_min_u32_e32 v3, v18, v153
	v_min_u32_e32 v162, v151, v150
	v_min_u32_e32 v163, v152, v24
	v_min_u32_e32 v164, v21, v25
	v_min_u32_e32 v165, v26, v161
	v_min_u32_e32 v166, v23, v20
	v_min_u32_e32 v167, v22, v1
	v_min_u32_e32 v168, v0, v2
	v_max3_u32 v16, v16, v149, v168
	v_max3_u32 v0, v5, v0, v2
	v_max3_u32 v2, v143, v144, v167
	v_max3_u32 v1, v154, v22, v1
	v_max3_u32 v5, v148, v28, v166
	v_max3_u32 v20, v155, v23, v20
	v_max3_u32 v17, v17, v145, v165
	v_max3_u32 v22, v156, v26, v161
	v_max3_u32 v23, v146, v147, v164
	v_max3_u32 v21, v157, v21, v25
	v_max3_u32 v10, v10, v12, v163
	v_max3_u32 v12, v158, v152, v24
	v_max3_u32 v14, v15, v14, v162
	v_max3_u32 v15, v159, v151, v150
	v_max3_u32 v3, v8, v4, v3
	v_max3_u32 v4, v160, v18, v153
	v_max_u32_e32 v8, v16, v23
	v_min_u32_e32 v16, v16, v23
	v_max_u32_e32 v18, v0, v21
	v_min_u32_e32 v0, v0, v21
	v_max_u32_e32 v21, v2, v10
	v_min_u32_e32 v2, v2, v10
	v_max_u32_e32 v10, v1, v12
	v_min_u32_e32 v1, v1, v12
	v_max_u32_e32 v12, v5, v14
	v_min_u32_e32 v5, v5, v14
	v_max_u32_e32 v14, v20, v15
	v_min_u32_e32 v15, v20, v15
	v_max_u32_e32 v20, v17, v3
	v_min_u32_e32 v3, v17, v3
	v_max_u32_e32 v17, v22, v4
	v_min_u32_e32 v4, v22, v4
	v_max_u32_e32 v22, v8, v12
	v_min_u32_e32 v8, v8, v12
	v_max_u32_e32 v12, v18, v14
	v_min_u32_e32 v14, v18, v14
	v_max_u32_e32 v18, v21, v20
	v_min_u32_e32 v20, v21, v20
	v_max_u32_e32 v21, v10, v17
	v_min_u32_e32 v10, v10, v17
	v_max_u32_e32 v17, v16, v5
	v_min_u32_e32 v5, v16, v5
	v_max_u32_e32 v16, v0, v15
	v_min_u32_e32 v0, v0, v15
	v_max_u32_e32 v15, v2, v3
	v_min_u32_e32 v2, v2, v3
	v_max_u32_e32 v3, v1, v4
	v_min_u32_e32 v1, v1, v4
	v_max_u32_e32 v4, v22, v18
	v_min_u32_e32 v18, v22, v18
	v_max_u32_e32 v22, v12, v21
	v_min_u32_e32 v12, v12, v21
	v_max_u32_e32 v21, v8, v20
	v_min_u32_e32 v8, v8, v20
	v_max_u32_e32 v20, v14, v10
	v_min_u32_e32 v10, v14, v10
	v_max_u32_e32 v14, v17, v15
	v_min_u32_e32 v15, v17, v15
	v_max_u32_e32 v17, v16, v3
	v_min_u32_e32 v3, v16, v3
	v_max_u32_e32 v16, v5, v2
	v_min_u32_e32 v2, v5, v2
	v_max_u32_e32 v5, v0, v1
	v_min_u32_e32 v0, v0, v1
	v_max_u32_e32 v1, v4, v22
	v_min_u32_e32 v4, v4, v22
	v_max_u32_e32 v22, v18, v12
	v_min_u32_e32 v12, v18, v12
	v_max_u32_e32 v18, v21, v20
	v_min_u32_e32 v20, v21, v20
	v_max_u32_e32 v21, v8, v10
	v_min_u32_e32 v8, v8, v10
	v_max_u32_e32 v10, v14, v17
	v_min_u32_e32 v14, v14, v17
	v_max_u32_e32 v17, v15, v3
	v_min_u32_e32 v3, v15, v3
	v_max_u32_e32 v15, v16, v5
	v_min_u32_e32 v5, v16, v5
	v_max_u32_e32 v16, v2, v0
	v_min_u32_e32 v0, v2, v0
	ds_bpermute_b32 v2, v27, v1
	ds_bpermute_b32 v23, v27, v4
	ds_bpermute_b32 v24, v27, v22
	ds_bpermute_b32 v25, v27, v12
	ds_bpermute_b32 v26, v27, v18
	ds_bpermute_b32 v28, v27, v20
	ds_bpermute_b32 v143, v27, v21
	ds_bpermute_b32 v144, v27, v8
	ds_bpermute_b32 v145, v27, v10
	ds_bpermute_b32 v146, v27, v14
	ds_bpermute_b32 v147, v27, v17
	ds_bpermute_b32 v148, v27, v0
	ds_bpermute_b32 v149, v27, v16
	ds_bpermute_b32 v150, v27, v5
	ds_bpermute_b32 v151, v27, v15
	ds_bpermute_b32 v27, v27, v3
	s_waitcnt lgkmcnt(4)
	v_max_u32_e32 v1, v1, v148
	s_waitcnt lgkmcnt(3)
	v_max_u32_e32 v4, v4, v149
	s_waitcnt lgkmcnt(2)
	v_max_u32_e32 v22, v22, v150
	s_waitcnt lgkmcnt(1)
	v_max_u32_e32 v12, v12, v151
	s_waitcnt lgkmcnt(0)
; __device__ __forceinline__ void peer_tile(const Args& A, LAS unsigned char* lds, int tile) {
;     ...
;                 for (int msk = 16; msk <= 32; msk <<= 1) {
; #pragma unroll
;                     for (int i = 0; i < 16; ++i) k1[i] = (unsigned)__shfl_xor((int)k0[i], msk);
;                     merge16(k0, k1); }
; #pragma unroll
;                 for (int i = 0; i < 16; ++i) LA[hh][p][i] = k0[i];
;             }
;         }
;         {
;             const int h = 4 * hg + g;
;             unsigned L2[2][16];
; #pragma unroll
;             for (int p = 0; p < 2; ++p)
; #pragma unroll
;                 for (int i = 0; i < 16; ++i) L2[p][i] = (g & 2) ? ((g & 1) ? LA[3][p][i] : LA[2][p][i]) : ((g & 1) ? LA[1][p][i] : LA[0][p][i]);
	v_max_u32_e32 v18, v18, v27
	v_max_u32_e32 v20, v20, v147
	v_max_u32_e32 v21, v21, v146
	v_max_u32_e32 v8, v8, v145
	v_max_u32_e32 v10, v10, v144
	v_max_u32_e32 v14, v14, v143
	v_max_u32_e32 v17, v17, v28
	v_max_u32_e32 v3, v3, v26
	v_max_u32_e32 v15, v15, v25
	v_max_u32_e32 v5, v5, v24
	v_max_u32_e32 v16, v16, v23
	v_max_u32_e32 v0, v0, v2
	v_max_u32_e32 v2, v1, v10
	v_min_u32_e32 v1, v1, v10
	v_max_u32_e32 v10, v4, v14
	v_min_u32_e32 v4, v4, v14
	v_max_u32_e32 v14, v22, v17
	v_min_u32_e32 v17, v22, v17
	v_max_u32_e32 v22, v12, v3
	v_min_u32_e32 v3, v12, v3
	v_max_u32_e32 v12, v18, v15
	v_min_u32_e32 v15, v18, v15
	v_max_u32_e32 v18, v20, v5
	v_min_u32_e32 v5, v20, v5
	v_max_u32_e32 v20, v21, v16
	v_min_u32_e32 v16, v21, v16
	v_max_u32_e32 v21, v8, v0
	v_min_u32_e32 v0, v8, v0
	v_max_u32_e32 v8, v2, v12
	v_min_u32_e32 v2, v2, v12
	v_max_u32_e32 v12, v10, v18
	v_min_u32_e32 v10, v10, v18
	v_max_u32_e32 v18, v14, v20
	v_min_u32_e32 v14, v14, v20
	v_max_u32_e32 v20, v22, v21
	v_min_u32_e32 v21, v22, v21
	v_max_u32_e32 v22, v1, v15
	v_min_u32_e32 v1, v1, v15
	v_max_u32_e32 v15, v4, v5
	v_min_u32_e32 v4, v4, v5
	v_max_u32_e32 v5, v17, v16
	v_min_u32_e32 v16, v17, v16
	v_max_u32_e32 v17, v3, v0
	v_min_u32_e32 v0, v3, v0
	v_max_u32_e32 v3, v8, v18
	v_min_u32_e32 v8, v8, v18
	v_max_u32_e32 v18, v12, v20
	v_min_u32_e32 v12, v12, v20
	v_max_u32_e32 v20, v2, v14
	v_min_u32_e32 v2, v2, v14
	v_max_u32_e32 v14, v10, v21
	v_min_u32_e32 v10, v10, v21
	v_max_u32_e32 v21, v22, v5
	v_min_u32_e32 v5, v22, v5
	v_max_u32_e32 v22, v15, v17
	v_min_u32_e32 v15, v15, v17
	v_max_u32_e32 v17, v1, v16
	v_min_u32_e32 v1, v1, v16
	v_max_u32_e32 v16, v4, v0
	v_min_u32_e32 v0, v4, v0
	v_max_u32_e32 v4, v3, v18
	v_min_u32_e32 v3, v3, v18
	v_max_u32_e32 v18, v8, v12
	v_min_u32_e32 v8, v8, v12
	v_max_u32_e32 v12, v20, v14
	v_min_u32_e32 v14, v20, v14
	v_max_u32_e32 v20, v2, v10
	v_min_u32_e32 v2, v2, v10
	v_max_u32_e32 v10, v21, v22
	v_min_u32_e32 v21, v21, v22
	v_max_u32_e32 v22, v5, v15
	v_min_u32_e32 v5, v5, v15
	v_max_u32_e32 v15, v17, v16
	v_min_u32_e32 v16, v17, v16
	v_max_u32_e32 v17, v1, v0
	v_min_u32_e32 v0, v1, v0
	ds_bpermute_b32 v1, v29, v4
	ds_bpermute_b32 v23, v29, v3
	ds_bpermute_b32 v24, v29, v18
	ds_bpermute_b32 v25, v29, v8
	ds_bpermute_b32 v26, v29, v12
	ds_bpermute_b32 v27, v29, v14
	ds_bpermute_b32 v28, v29, v20
	ds_bpermute_b32 v143, v29, v2
	ds_bpermute_b32 v144, v29, v10
	ds_bpermute_b32 v145, v29, v21
	ds_bpermute_b32 v146, v29, v22
	ds_bpermute_b32 v147, v29, v0
	ds_bpermute_b32 v148, v29, v17
	ds_bpermute_b32 v149, v29, v16
	ds_bpermute_b32 v150, v29, v15
	ds_bpermute_b32 v29, v29, v5
	s_waitcnt lgkmcnt(4)
	v_max_u32_e32 v4, v4, v147
	s_waitcnt lgkmcnt(3)
	v_max_u32_e32 v3, v3, v148
	s_waitcnt lgkmcnt(2)
	v_max_u32_e32 v18, v18, v149
	s_waitcnt lgkmcnt(1)
	v_max_u32_e32 v8, v8, v150
	s_waitcnt lgkmcnt(0)
	v_max_u32_e32 v12, v12, v29
	v_max_u32_e32 v14, v14, v146
	v_max_u32_e32 v20, v20, v145
	v_max_u32_e32 v2, v2, v144
	v_max_u32_e32 v10, v10, v143
	v_max_u32_e32 v21, v21, v28
	v_max_u32_e32 v22, v22, v27
	v_max_u32_e32 v5, v5, v26
	v_max_u32_e32 v15, v15, v25
	v_max_u32_e32 v16, v16, v24
	v_max_u32_e32 v17, v17, v23
	v_max_u32_e32 v0, v0, v1
	v_max_u32_e32 v1, v4, v10
	v_min_u32_e32 v4, v4, v10
	v_max_u32_e32 v10, v3, v21
	v_min_u32_e32 v3, v3, v21
	v_max_u32_e32 v21, v18, v22
	v_min_u32_e32 v18, v18, v22
	v_max_u32_e32 v22, v8, v5
	v_min_u32_e32 v5, v8, v5
	v_max_u32_e32 v8, v12, v15
	v_min_u32_e32 v12, v12, v15
	v_max_u32_e32 v15, v14, v16
	v_min_u32_e32 v14, v14, v16
	v_max_u32_e32 v16, v20, v17
	v_min_u32_e32 v17, v20, v17
	v_max_u32_e32 v20, v2, v0
	v_min_u32_e32 v0, v2, v0
	v_max_u32_e32 v2, v1, v8
	v_min_u32_e32 v1, v1, v8
	v_max_u32_e32 v8, v10, v15
	v_min_u32_e32 v10, v10, v15
	v_max_u32_e32 v15, v21, v16
	v_min_u32_e32 v16, v21, v16
	v_max_u32_e32 v21, v22, v20
	v_min_u32_e32 v20, v22, v20
	v_max_u32_e32 v22, v4, v12
	v_min_u32_e32 v4, v4, v12
	v_max_u32_e32 v12, v3, v14
	v_min_u32_e32 v3, v3, v14
	v_max_u32_e32 v14, v18, v17
	v_min_u32_e32 v17, v18, v17
	v_max_u32_e32 v18, v5, v0
	v_min_u32_e32 v0, v5, v0
	v_max_u32_e32 v5, v2, v15
	v_min_u32_e32 v2, v2, v15
	v_max_u32_e32 v15, v8, v21
	v_min_u32_e32 v8, v8, v21
	v_max_u32_e32 v21, v1, v16
	v_min_u32_e32 v1, v1, v16
	v_max_u32_e32 v16, v10, v20
	v_min_u32_e32 v10, v10, v20
	v_max_u32_e32 v20, v22, v14
	v_min_u32_e32 v14, v22, v14
	v_max_u32_e32 v22, v12, v18
	v_min_u32_e32 v12, v12, v18
	v_max_u32_e32 v18, v4, v17
	v_min_u32_e32 v4, v4, v17
	v_max_u32_e32 v17, v3, v0
	v_min_u32_e32 v0, v3, v0
	v_max_u32_e32 v3, v5, v15
	v_min_u32_e32 v5, v5, v15
	v_max_u32_e32 v15, v2, v8
	v_min_u32_e32 v2, v2, v8
	v_max_u32_e32 v8, v21, v16
	v_min_u32_e32 v16, v21, v16
	v_max_u32_e32 v21, v1, v10
	v_min_u32_e32 v1, v1, v10
	v_max_u32_e32 v10, v20, v22
	v_min_u32_e32 v20, v20, v22
	v_max_u32_e32 v22, v14, v12
	v_min_u32_e32 v12, v14, v12
	v_max_u32_e32 v14, v18, v17
	v_min_u32_e32 v17, v18, v17
	v_max_u32_e32 v18, v4, v0
	v_min_u32_e32 v0, v4, v0
	v_and_b32_e32 v4, 16, v19
	v_cmp_eq_u32_e32 vcc, 0, v4
	v_cndmask_b32_e64 v23, v77, v45, s[0:1]
	v_cndmask_b32_e64 v24, v76, v44, s[0:1]
	v_cndmask_b32_e32 v4, v142, v109, vcc
	v_cndmask_b32_e64 v4, v4, v23, s[4:5]
	v_cndmask_b32_e32 v23, v141, v108, vcc
	v_cndmask_b32_e64 v23, v23, v24, s[4:5]
	v_cndmask_b32_e32 v24, v140, v107, vcc
	v_cndmask_b32_e64 v25, v75, v43, s[0:1]
	v_cndmask_b32_e64 v24, v24, v25, s[4:5]
	v_cndmask_b32_e32 v25, v139, v106, vcc
	v_cndmask_b32_e64 v26, v74, v42, s[0:1]
	v_cndmask_b32_e64 v25, v25, v26, s[4:5]
	v_cndmask_b32_e32 v26, v138, v105, vcc
	v_cndmask_b32_e64 v27, v73, v41, s[0:1]
	v_cndmask_b32_e64 v26, v26, v27, s[4:5]
; __device__ __forceinline__ float key2f(unsigned k) { const unsigned u = (k & 0x80000000u) ? (k & 0x7fffffffu) : ~k; return __uint_as_float(u); }
; __device__ __forceinline__ void peer_tile(const Args& A, LAS unsigned char* lds, int tile) {
;     ...
;                 for (int i = 0; i < 16; ++i) L2[p][i] = (g & 2) ? ((g & 1) ? LA[3][p][i] : LA[2][p][i]) : ((g & 1) ? LA[1][p][i] : LA[0][p][i]);
;             float va[16], vb[16];
; #pragma unroll
;             for (int i = 0; i < 16; ++i) { va[i] = key2f(L2[0][i] & ~127u); vb[i] = key2f(L2[1][i] & ~127u); idx[i] = 127u - (L2[0][i] & 127u); idx[16 + i] = 127u - (L2[1][i] & 127u); }
	v_cndmask_b32_e32 v27, v137, v104, vcc
	v_cndmask_b32_e64 v28, v72, v40, s[0:1]
	v_cndmask_b32_e64 v27, v27, v28, s[4:5]
	v_cndmask_b32_e32 v28, v136, v103, vcc
	v_cndmask_b32_e64 v29, v71, v39, s[0:1]
	v_cndmask_b32_e64 v28, v28, v29, s[4:5]
	v_cndmask_b32_e32 v29, v135, v102, vcc
	v_cndmask_b32_e64 v29, v29, v38, s[4:5]
	v_cndmask_b32_e32 v38, v134, v101, vcc
	v_cndmask_b32_e64 v37, v38, v37, s[4:5]
	v_cndmask_b32_e32 v38, v133, v100, vcc
	v_cndmask_b32_e64 v36, v38, v36, s[4:5]
	v_cndmask_b32_e32 v38, v132, v99, vcc
	v_cndmask_b32_e64 v38, v38, v35, s[4:5]
	v_cndmask_b32_e32 v35, v131, v98, vcc
	v_cndmask_b32_e64 v39, v35, v34, s[4:5]
	v_cndmask_b32_e32 v34, v130, v97, vcc
	v_cndmask_b32_e64 v33, v34, v33, s[4:5]
	v_cndmask_b32_e32 v34, v129, v96, vcc
	v_cndmask_b32_e64 v40, v34, v32, s[4:5]
	v_cndmask_b32_e32 v32, v128, v95, vcc
	v_cndmask_b32_e64 v42, v32, v31, s[4:5]
	v_cndmask_b32_e32 v31, v127, v94, vcc
	v_cndmask_b32_e64 v43, v31, v30, s[4:5]
	v_cndmask_b32_e32 v3, v3, v126, vcc
	v_cndmask_b32_e64 v30, v93, v61, s[0:1]
	v_cndmask_b32_e64 v3, v3, v30, s[4:5]
	v_cndmask_b32_e32 v5, v5, v125, vcc
	v_cndmask_b32_e64 v30, v92, v60, s[0:1]
	v_cndmask_b32_e64 v30, v5, v30, s[4:5]
	v_cndmask_b32_e32 v5, v15, v124, vcc
	v_cndmask_b32_e64 v15, v91, v59, s[0:1]
	v_cndmask_b32_e64 v15, v5, v15, s[4:5]
	v_cndmask_b32_e32 v2, v2, v123, vcc
	v_cndmask_b32_e64 v5, v90, v58, s[0:1]
	v_cndmask_b32_e64 v31, v2, v5, s[4:5]
	v_cndmask_b32_e32 v2, v8, v122, vcc
	v_cndmask_b32_e64 v5, v89, v57, s[0:1]
	v_cndmask_b32_e64 v8, v2, v5, s[4:5]
	v_cndmask_b32_e32 v2, v16, v121, vcc
	v_cndmask_b32_e64 v5, v88, v56, s[0:1]
	v_cndmask_b32_e64 v32, v2, v5, s[4:5]
	v_cndmask_b32_e32 v2, v21, v120, vcc
	v_cndmask_b32_e64 v5, v87, v55, s[0:1]
	v_cndmask_b32_e64 v21, v2, v5, s[4:5]
	v_cndmask_b32_e32 v1, v1, v119, vcc
	v_cndmask_b32_e64 v2, v86, v54, s[0:1]
	v_cndmask_b32_e64 v34, v1, v2, s[4:5]
	v_cndmask_b32_e32 v1, v10, v118, vcc
	v_cndmask_b32_e64 v2, v85, v53, s[0:1]
	v_cndmask_b32_e64 v41, v1, v2, s[4:5]
	v_cndmask_b32_e32 v1, v20, v117, vcc
	v_cndmask_b32_e64 v2, v84, v52, s[0:1]
	v_cndmask_b32_e64 v44, v1, v2, s[4:5]
	v_cndmask_b32_e32 v1, v22, v116, vcc
	v_cndmask_b32_e64 v2, v83, v51, s[0:1]
	v_cndmask_b32_e64 v45, v1, v2, s[4:5]
	v_cndmask_b32_e32 v1, v12, v115, vcc
	v_cndmask_b32_e64 v2, v82, v50, s[0:1]
	v_cndmask_b32_e64 v50, v1, v2, s[4:5]
	v_cndmask_b32_e32 v1, v14, v114, vcc
	v_cndmask_b32_e64 v2, v81, v49, s[0:1]
	v_cndmask_b32_e64 v49, v1, v2, s[4:5]
	v_cndmask_b32_e32 v1, v17, v112, vcc
	v_cndmask_b32_e64 v2, v80, v48, s[0:1]
	v_cndmask_b32_e64 v48, v1, v2, s[4:5]
	v_cndmask_b32_e32 v1, v18, v111, vcc
	v_cndmask_b32_e64 v2, v79, v47, s[0:1]
	v_cndmask_b32_e64 v47, v1, v2, s[4:5]
	v_cndmask_b32_e32 v0, v0, v110, vcc
	v_cndmask_b32_e64 v1, v78, v46, s[0:1]
	v_cndmask_b32_e64 v46, v0, v1, s[4:5]
	v_and_b32_e32 v0, 0x7fffff80, v4
	v_bitop3_b32 v1, v4, s19, v4 bitop3:0xcf
	v_cmp_gt_i32_e32 vcc, 0, v4
	v_bitop3_b32 v2, v4, s19, v4 bitop3:0xc
	v_bitop3_b32 v4, v23, s19, v23 bitop3:0xcf
	v_cndmask_b32_e32 v20, v1, v0, vcc
	v_and_b32_e32 v0, 0x7fffff80, v3
	v_bitop3_b32 v1, v3, s19, v3 bitop3:0xcf
	v_cmp_gt_i32_e32 vcc, 0, v3
	v_add_u32_e32 v5, 0, v6
	v_bitop3_b32 v3, v3, s19, v3 bitop3:0xc
	v_cndmask_b32_e32 v1, v1, v0, vcc
	v_and_b32_e32 v0, 0x7fffff80, v23
	v_cmp_gt_i32_e32 vcc, 0, v23
	v_bitop3_b32 v14, v31, s19, v31 bitop3:0xcf
	v_bitop3_b32 v6, v24, s19, v24 bitop3:0xc
	v_cndmask_b32_e32 v18, v4, v0, vcc
	v_and_b32_e32 v0, 0x7fffff80, v30
	v_bitop3_b32 v4, v30, s19, v30 bitop3:0xcf
	v_cmp_gt_i32_e32 vcc, 0, v30
	v_bitop3_b32 v10, v15, s19, v15 bitop3:0xc
	v_bitop3_b32 v16, v32, s19, v32 bitop3:0xcf
	v_cndmask_b32_e32 v0, v4, v0, vcc
	v_bitop3_b32 v4, v23, s19, v23 bitop3:0xc
	ds_write2_b32 v5, v2, v4 offset1:1
	v_bitop3_b32 v2, v30, s19, v30 bitop3:0xc
	ds_write2_b32 v5, v3, v2 offset0:16 offset1:17
	v_and_b32_e32 v2, 0x7fffff80, v24
	v_bitop3_b32 v3, v24, s19, v24 bitop3:0xcf
	v_cmp_gt_i32_e32 vcc, 0, v24
	v_bitop3_b32 v4, v25, s19, v25 bitop3:0xcf
	v_bitop3_b32 v22, v29, s19, v29 bitop3:0xcf
	v_cndmask_b32_e32 v12, v3, v2, vcc
	v_and_b32_e32 v2, 0x7fffff80, v15
	v_bitop3_b32 v3, v15, s19, v15 bitop3:0xcf
	v_cmp_gt_i32_e32 vcc, 0, v15
	v_bitop3_b32 v15, v27, s19, v27 bitop3:0xcf
	v_bitop3_b32 v24, v34, s19, v34 bitop3:0xcf
	v_cndmask_b32_e32 v3, v3, v2, vcc
	v_and_b32_e32 v2, 0x7fffff80, v25
	v_cmp_gt_i32_e32 vcc, 0, v25
	s_nop 1
	v_cndmask_b32_e32 v4, v4, v2, vcc
	v_and_b32_e32 v2, 0x7fffff80, v31
	v_cmp_gt_i32_e32 vcc, 0, v31
	s_nop 1
	v_cndmask_b32_e32 v2, v14, v2, vcc
	v_bitop3_b32 v14, v25, s19, v25 bitop3:0xc
	ds_write2_b32 v5, v6, v14 offset0:2 offset1:3
	v_bitop3_b32 v6, v31, s19, v31 bitop3:0xc
	ds_write2_b32 v5, v10, v6 offset0:18 offset1:19
	v_and_b32_e32 v6, 0x7fffff80, v26
	v_bitop3_b32 v10, v26, s19, v26 bitop3:0xcf
	v_cmp_gt_i32_e32 vcc, 0, v26
	v_bitop3_b32 v25, v36, s19, v36 bitop3:0xcf
	s_nop 0
	v_cndmask_b32_e32 v14, v10, v6, vcc
	v_and_b32_e32 v6, 0x7fffff80, v8
	v_bitop3_b32 v10, v8, s19, v8 bitop3:0xcf
	v_cmp_gt_i32_e32 vcc, 0, v8
	v_bitop3_b32 v8, v8, s19, v8 bitop3:0xc
	s_nop 0
	v_cndmask_b32_e32 v17, v10, v6, vcc
	v_and_b32_e32 v10, 0x7fffff80, v27
	v_cmp_gt_i32_e32 vcc, 0, v27
	v_bitop3_b32 v6, v26, s19, v26 bitop3:0xc
	v_bitop3_b32 v26, v43, s19, v43 bitop3:0xcf
	v_cndmask_b32_e32 v10, v15, v10, vcc
	v_and_b32_e32 v15, 0x7fffff80, v32
	v_cmp_gt_i32_e32 vcc, 0, v32
	s_nop 1
	v_cndmask_b32_e32 v16, v16, v15, vcc
	v_bitop3_b32 v15, v27, s19, v27 bitop3:0xc
	ds_write2_b32 v5, v6, v15 offset0:4 offset1:5
	v_bitop3_b32 v6, v32, s19, v32 bitop3:0xc
	ds_write2_b32 v5, v8, v6 offset0:20 offset1:21
	v_and_b32_e32 v6, 0x7fffff80, v28
; __device__ __forceinline__ float key2f(unsigned k) { const unsigned u = (k & 0x80000000u) ? (k & 0x7fffffffu) : ~k; return __uint_as_float(u); }
; #define CK(i, j) ((f2key(va[i] + vb[j]) & ~255u) | (unsigned)(255 - (16 * (i) + (j))))
; __device__ __forceinline__ void peer_tile(const Args& A, LAS unsigned char* lds, int tile) {
;     ...
; #pragma unroll
;             for (int i = 0; i < 16; ++i) { va[i] = key2f(L2[0][i] & ~127u); vb[i] = key2f(L2[1][i] & ~127u); idx[i] = 127u - (L2[0][i] & 127u); idx[16 + i] = 127u - (L2[1][i] & 127u); }
;     ...
;             unsigned Lf[16], Bt[16];
; #pragma unroll
;             for (int j = 0; j < 16; ++j) Lf[j] = CK(0, j);
; #pragma unroll
;             for (int j = 0; j < 8; ++j) Bt[j] = CK(1, j);
; #pragma unroll
;             for (int j = 0; j < 5; ++j) Bt[8 + j] = CK(2, j);
	v_bitop3_b32 v8, v28, s19, v28 bitop3:0xcf
	v_cmp_gt_i32_e32 vcc, 0, v28
	v_bitop3_b32 v15, v21, s19, v21 bitop3:0xcf
	s_nop 0
	v_cndmask_b32_e32 v8, v8, v6, vcc
	v_and_b32_e32 v6, 0x7fffff80, v21
	v_cmp_gt_i32_e32 vcc, 0, v21
	v_bitop3_b32 v21, v21, s19, v21 bitop3:0xc
	s_nop 0
	v_cndmask_b32_e32 v23, v15, v6, vcc
	v_and_b32_e32 v6, 0x7fffff80, v29
	v_cmp_gt_i32_e32 vcc, 0, v29
	v_bitop3_b32 v15, v28, s19, v28 bitop3:0xc
	s_nop 0
	v_cndmask_b32_e32 v6, v22, v6, vcc
	v_and_b32_e32 v22, 0x7fffff80, v34
	v_cmp_gt_i32_e32 vcc, 0, v34
	s_nop 1
	v_cndmask_b32_e32 v22, v24, v22, vcc
	v_bitop3_b32 v24, v29, s19, v29 bitop3:0xc
	ds_write2_b32 v5, v15, v24 offset0:6 offset1:7
	v_bitop3_b32 v15, v34, s19, v34 bitop3:0xc
	ds_write2_b32 v5, v21, v15 offset0:22 offset1:23
	v_and_b32_e32 v15, 0x7fffff80, v37
	v_bitop3_b32 v21, v37, s19, v37 bitop3:0xcf
	v_cmp_gt_i32_e32 vcc, 0, v37
	v_and_b32_e32 v24, 0x7fffff80, v36
	s_nop 0
	v_cndmask_b32_e32 v27, v21, v15, vcc
	v_and_b32_e32 v15, 0x7fffff80, v41
	v_bitop3_b32 v21, v41, s19, v41 bitop3:0xcf
	v_cmp_gt_i32_e32 vcc, 0, v41
	s_nop 1
	v_cndmask_b32_e32 v35, v21, v15, vcc
	v_cmp_gt_i32_e32 vcc, 0, v36
	v_bitop3_b32 v15, v37, s19, v37 bitop3:0xc
	v_bitop3_b32 v21, v41, s19, v41 bitop3:0xc
	v_cndmask_b32_e32 v28, v25, v24, vcc
	v_and_b32_e32 v24, 0x7fffff80, v44
	v_bitop3_b32 v25, v44, s19, v44 bitop3:0xcf
	v_cmp_gt_i32_e32 vcc, 0, v44
	s_nop 1
	v_cndmask_b32_e32 v34, v25, v24, vcc
	v_bitop3_b32 v24, v36, s19, v36 bitop3:0xc
	ds_write2_b32 v5, v15, v24 offset0:8 offset1:9
	v_bitop3_b32 v15, v44, s19, v44 bitop3:0xc
	ds_write2_b32 v5, v21, v15 offset0:24 offset1:25
	v_and_b32_e32 v15, 0x7fffff80, v38
	v_bitop3_b32 v21, v38, s19, v38 bitop3:0xcf
	v_cmp_gt_i32_e32 vcc, 0, v38
	v_and_b32_e32 v24, 0x7fffff80, v39
	v_bitop3_b32 v25, v39, s19, v39 bitop3:0xcf
	v_cndmask_b32_e32 v29, v21, v15, vcc
	v_and_b32_e32 v15, 0x7fffff80, v45
	v_bitop3_b32 v21, v45, s19, v45 bitop3:0xcf
	v_cmp_gt_i32_e32 vcc, 0, v45
	s_nop 1
	v_cndmask_b32_e32 v37, v21, v15, vcc
	v_cmp_gt_i32_e32 vcc, 0, v39
	v_bitop3_b32 v15, v38, s19, v38 bitop3:0xc
	v_bitop3_b32 v21, v45, s19, v45 bitop3:0xc
	v_cndmask_b32_e32 v30, v25, v24, vcc
	v_and_b32_e32 v24, 0x7fffff80, v50
	v_bitop3_b32 v25, v50, s19, v50 bitop3:0xcf
	v_cmp_gt_i32_e32 vcc, 0, v50
	s_nop 1
	v_cndmask_b32_e32 v36, v25, v24, vcc
	v_bitop3_b32 v24, v39, s19, v39 bitop3:0xc
	ds_write2_b32 v5, v15, v24 offset0:10 offset1:11
	v_bitop3_b32 v15, v50, s19, v50 bitop3:0xc
	ds_write2_b32 v5, v21, v15 offset0:26 offset1:27
	v_and_b32_e32 v15, 0x7fffff80, v33
	v_bitop3_b32 v21, v33, s19, v33 bitop3:0xcf
	v_cmp_gt_i32_e32 vcc, 0, v33
	v_and_b32_e32 v24, 0x7fffff80, v40
	v_bitop3_b32 v25, v40, s19, v40 bitop3:0xcf
	v_cndmask_b32_e32 v31, v21, v15, vcc
	v_and_b32_e32 v15, 0x7fffff80, v49
	v_bitop3_b32 v21, v49, s19, v49 bitop3:0xcf
	v_cmp_gt_i32_e32 vcc, 0, v49
	s_nop 1
	v_cndmask_b32_e32 v39, v21, v15, vcc
	v_cmp_gt_i32_e32 vcc, 0, v40
	v_bitop3_b32 v15, v33, s19, v33 bitop3:0xc
	v_bitop3_b32 v21, v49, s19, v49 bitop3:0xc
	v_cndmask_b32_e32 v32, v25, v24, vcc
	v_and_b32_e32 v24, 0x7fffff80, v48
	v_bitop3_b32 v25, v48, s19, v48 bitop3:0xcf
	v_cmp_gt_i32_e32 vcc, 0, v48
	v_bitop3_b32 v33, v46, s19, v46 bitop3:0xcf
	s_nop 0
	v_cndmask_b32_e32 v38, v25, v24, vcc
	v_bitop3_b32 v24, v40, s19, v40 bitop3:0xc
	ds_write2_b32 v5, v15, v24 offset0:12 offset1:13
	v_bitop3_b32 v15, v48, s19, v48 bitop3:0xc
	ds_write2_b32 v5, v21, v15 offset0:28 offset1:29
	v_and_b32_e32 v15, 0x7fffff80, v42
	v_bitop3_b32 v21, v42, s19, v42 bitop3:0xcf
	v_cmp_gt_i32_e32 vcc, 0, v42
	v_and_b32_e32 v24, 0x7fffff80, v43
	s_nop 0
	v_cndmask_b32_e32 v25, v21, v15, vcc
	v_and_b32_e32 v15, 0x7fffff80, v47
	v_bitop3_b32 v21, v47, s19, v47 bitop3:0xcf
	v_cmp_gt_i32_e32 vcc, 0, v47
	s_nop 1
	v_cndmask_b32_e32 v41, v21, v15, vcc
	v_cmp_gt_i32_e32 vcc, 0, v43
	v_bitop3_b32 v21, v47, s19, v47 bitop3:0xc
	v_bitop3_b32 v15, v42, s19, v42 bitop3:0xc
	v_cndmask_b32_e32 v26, v26, v24, vcc
	v_and_b32_e32 v24, 0x7fffff80, v46
	v_cmp_gt_i32_e32 vcc, 0, v46
	v_pk_add_f32 v[34:35], v[20:21], v[34:35] op_sel_hi:[0,1]
	s_nop 0
	v_cndmask_b32_e32 v40, v33, v24, vcc
	v_bitop3_b32 v24, v43, s19, v43 bitop3:0xc
	v_pk_add_f32 v[42:43], v[20:21], v[0:1] op_sel_hi:[0,1]
	ds_write2_b32 v5, v15, v24 offset0:14 offset1:15
	v_not_b32_e32 v15, v43
	v_or_b32_e32 v33, 0x80000000, v43
	v_cmp_gt_i32_e32 vcc, 0, v43
	v_or_b32_e32 v43, 0x80000000, v42
	v_bitop3_b32 v24, v46, s19, v46 bitop3:0xc
	v_cndmask_b32_e32 v15, v33, v15, vcc
	v_or_b32_e32 v33, 0xff, v15
	v_not_b32_e32 v15, v42
	v_cmp_gt_i32_e32 vcc, 0, v42
	ds_write2_b32 v5, v21, v24 offset0:30 offset1:31
	s_waitcnt lgkmcnt(0)
; #define CK(i, j) ((f2key(va[i] + vb[j]) & ~255u) | (unsigned)(255 - (16 * (i) + (j))))
; __device__ __forceinline__ void peer_tile(const Args& A, LAS unsigned char* lds, int tile) {
;     ...
;             unsigned Lf[16], Bt[16];
; #pragma unroll
;             for (int j = 0; j < 16; ++j) Lf[j] = CK(0, j);
; #pragma unroll
;             for (int j = 0; j < 8; ++j) Bt[j] = CK(1, j);
; #pragma unroll
;             for (int j = 0; j < 5; ++j) Bt[8 + j] = CK(2, j);
; #pragma unroll
;             for (int j = 0; j < 3; ++j) Bt[13 + j] = CK(4, j);
;             sort16_desc(Bt); merge16(Lf, Bt);
; #pragma unroll
;             for (int j = 0; j < 4; ++j) Bt[j] = CK(3, j);
;             Bt[4] = CK(5, 0); Bt[5] = CK(5, 1); Bt[6] = CK(6, 0); Bt[7] = CK(6, 1); Bt[8] = CK(7, 0); Bt[9] = CK(7, 1);
;             Bt[10] = CK(8, 0); Bt[11] = CK(9, 0); Bt[12] = CK(10, 0); Bt[13] = CK(11, 0); Bt[14] = CK(12, 0); Bt[15] = CK(13, 0);
	s_nop 0
	v_cndmask_b32_e32 v15, v43, v15, vcc
	v_and_b32_e32 v15, 0xffffff00, v15
	v_pk_add_f32 v[42:43], v[20:21], v[2:3] op_sel_hi:[0,1]
	v_or_b32_e32 v44, 0xfe, v15
	v_not_b32_e32 v15, v43
	v_or_b32_e32 v45, 0x80000000, v43
	v_cmp_gt_i32_e32 vcc, 0, v43
	v_or_b32_e32 v43, 0x80000000, v42
	s_nop 0
	v_cndmask_b32_e32 v15, v45, v15, vcc
	v_and_b32_e32 v15, 0xffffff00, v15
	v_or_b32_e32 v45, 0xfd, v15
	v_not_b32_e32 v15, v42
	v_cmp_gt_i32_e32 vcc, 0, v42
	s_nop 1
	v_cndmask_b32_e32 v15, v43, v15, vcc
	v_and_b32_e32 v15, 0xffffff00, v15
	v_pk_add_f32 v[42:43], v[20:21], v[16:17] op_sel_hi:[0,1]
	v_or_b32_e32 v46, 0xfc, v15
	v_not_b32_e32 v15, v43
	v_or_b32_e32 v47, 0x80000000, v43
	v_cmp_gt_i32_e32 vcc, 0, v43
	v_or_b32_e32 v43, 0x80000000, v42
	s_nop 0
	v_cndmask_b32_e32 v15, v47, v15, vcc
	v_and_b32_e32 v15, 0xffffff00, v15
	v_or_b32_e32 v47, 0xfb, v15
	v_not_b32_e32 v15, v42
	v_cmp_gt_i32_e32 vcc, 0, v42
	s_nop 1
	v_cndmask_b32_e32 v15, v43, v15, vcc
	v_and_b32_e32 v15, 0xffffff00, v15
	v_pk_add_f32 v[42:43], v[20:21], v[22:23] op_sel_hi:[0,1]
	v_or_b32_e32 v48, 0xfa, v15
	v_not_b32_e32 v15, v43
	v_or_b32_e32 v49, 0x80000000, v43
	v_cmp_gt_i32_e32 vcc, 0, v43
	v_pk_add_f32 v[22:23], v[18:19], v[22:23] op_sel_hi:[0,1]
	s_nop 0
	v_cndmask_b32_e32 v15, v49, v15, vcc
	v_and_b32_e32 v15, 0xffffff00, v15
	v_or_b32_e32 v43, 0xf9, v15
	v_not_b32_e32 v15, v42
	v_or_b32_e32 v49, 0x80000000, v42
	v_cmp_gt_i32_e32 vcc, 0, v42
	s_nop 1
	v_cndmask_b32_e32 v15, v49, v15, vcc
	v_and_b32_e32 v15, 0xffffff00, v15
	v_or_b32_e32 v42, 0xf8, v15
	v_not_b32_e32 v15, v35
	v_or_b32_e32 v49, 0x80000000, v35
	v_cmp_gt_i32_e32 vcc, 0, v35
	v_or_b32_e32 v35, 0x80000000, v34
	s_nop 0
	v_cndmask_b32_e32 v15, v49, v15, vcc
	v_and_b32_e32 v15, 0xffffff00, v15
	v_or_b32_e32 v49, 0xf7, v15
	v_not_b32_e32 v15, v34
	v_cmp_gt_i32_e32 vcc, 0, v34
	s_nop 1
	v_cndmask_b32_e32 v15, v35, v15, vcc
	v_and_b32_e32 v15, 0xffffff00, v15
	v_pk_add_f32 v[34:35], v[20:21], v[36:37] op_sel_hi:[0,1]
	v_or_b32_e32 v50, 0xf6, v15
	v_not_b32_e32 v15, v35
	v_or_b32_e32 v36, 0x80000000, v35
	v_cmp_gt_i32_e32 vcc, 0, v35
	v_or_b32_e32 v35, 0x80000000, v34
	s_nop 0
	v_cndmask_b32_e32 v15, v36, v15, vcc
	v_and_b32_e32 v15, 0xffffff00, v15
	v_or_b32_e32 v36, 0xf5, v15
	v_not_b32_e32 v15, v34
	v_cmp_gt_i32_e32 vcc, 0, v34
	s_nop 1
	v_cndmask_b32_e32 v15, v35, v15, vcc
	v_and_b32_e32 v15, 0xffffff00, v15
	v_pk_add_f32 v[34:35], v[20:21], v[38:39] op_sel_hi:[0,1]
	v_or_b32_e32 v37, 0xf4, v15
	v_not_b32_e32 v15, v35
	v_or_b32_e32 v38, 0x80000000, v35
	v_cmp_gt_i32_e32 vcc, 0, v35
	v_or_b32_e32 v35, 0x80000000, v34
	s_nop 0
	v_cndmask_b32_e32 v15, v38, v15, vcc
	v_and_b32_e32 v15, 0xffffff00, v15
	v_or_b32_e32 v38, 0xf3, v15
	v_not_b32_e32 v15, v34
	v_cmp_gt_i32_e32 vcc, 0, v34
	s_nop 1
	v_cndmask_b32_e32 v15, v35, v15, vcc
	v_and_b32_e32 v15, 0xffffff00, v15
	v_pk_add_f32 v[34:35], v[20:21], v[40:41] op_sel_hi:[0,1]
	v_or_b32_e32 v39, 0xf2, v15
	v_not_b32_e32 v15, v35
	v_or_b32_e32 v20, 0x80000000, v35
	v_cmp_gt_i32_e32 vcc, 0, v35
	v_or_b32_e32 v35, 0x80000000, v34
	s_nop 0
	v_cndmask_b32_e32 v15, v20, v15, vcc
	v_and_b32_e32 v15, 0xffffff00, v15
	v_or_b32_e32 v20, 0xf1, v15
	v_not_b32_e32 v15, v34
	v_cmp_gt_i32_e32 vcc, 0, v34
	s_nop 1
	v_cndmask_b32_e32 v15, v35, v15, vcc
	v_and_b32_e32 v15, 0xffffff00, v15
	v_pk_add_f32 v[34:35], v[18:19], v[0:1] op_sel_hi:[0,1]
	v_or_b32_e32 v40, 0xf0, v15
	v_not_b32_e32 v15, v35
	v_or_b32_e32 v41, 0x80000000, v35
	v_cmp_gt_i32_e32 vcc, 0, v35
	v_or_b32_e32 v35, 0x80000000, v34
	s_nop 0
	v_cndmask_b32_e32 v15, v41, v15, vcc
	v_and_b32_e32 v15, 0xffffff00, v15
	v_or_b32_e32 v41, 0xef, v15
	v_not_b32_e32 v15, v34
	v_cmp_gt_i32_e32 vcc, 0, v34
	s_nop 1
	v_cndmask_b32_e32 v15, v35, v15, vcc
	v_and_b32_e32 v15, 0xffffff00, v15
	v_pk_add_f32 v[34:35], v[18:19], v[2:3] op_sel_hi:[0,1]
	v_or_b32_e32 v51, 0xee, v15
	v_not_b32_e32 v15, v35
	v_or_b32_e32 v52, 0x80000000, v35
	v_cmp_gt_i32_e32 vcc, 0, v35
	v_or_b32_e32 v35, 0x80000000, v34
	s_nop 0
	v_cndmask_b32_e32 v15, v52, v15, vcc
	v_and_b32_e32 v15, 0xffffff00, v15
	v_or_b32_e32 v52, 0xed, v15
	v_not_b32_e32 v15, v34
	v_cmp_gt_i32_e32 vcc, 0, v34
	s_nop 1
	v_cndmask_b32_e32 v15, v35, v15, vcc
	v_and_b32_e32 v15, 0xffffff00, v15
	v_pk_add_f32 v[34:35], v[18:19], v[16:17] op_sel_hi:[0,1]
	v_or_b32_e32 v53, 0xec, v15
	v_not_b32_e32 v15, v35
	v_or_b32_e32 v16, 0x80000000, v35
	v_cmp_gt_i32_e32 vcc, 0, v35
	s_nop 1
	v_cndmask_b32_e32 v15, v16, v15, vcc
	v_and_b32_e32 v15, 0xffffff00, v15
	v_or_b32_e32 v35, 0xeb, v15
	v_not_b32_e32 v15, v34
	v_or_b32_e32 v16, 0x80000000, v34
	v_cmp_gt_i32_e32 vcc, 0, v34
	s_nop 1
	v_cndmask_b32_e32 v15, v16, v15, vcc
	v_and_b32_e32 v15, 0xffffff00, v15
	v_or_b32_e32 v34, 0xea, v15
	v_not_b32_e32 v15, v23
	v_or_b32_e32 v16, 0x80000000, v23
	v_cmp_gt_i32_e32 vcc, 0, v23
	s_nop 1
	v_cndmask_b32_e32 v15, v16, v15, vcc
	v_and_b32_e32 v15, 0xffffff00, v15
	v_or_b32_e32 v18, 0xe9, v15
	v_not_b32_e32 v15, v22
	v_or_b32_e32 v16, 0x80000000, v22
	v_cmp_gt_i32_e32 vcc, 0, v22
	v_pk_add_f32 v[22:23], v[12:13], v[0:1] op_sel_hi:[0,1]
	s_nop 0
	v_cndmask_b32_e32 v15, v16, v15, vcc
	v_and_b32_e32 v15, 0xffffff00, v15
	v_or_b32_e32 v54, 0xe8, v15
	v_not_b32_e32 v15, v23
	v_or_b32_e32 v16, 0x80000000, v23
	v_cmp_gt_i32_e32 vcc, 0, v23
	s_nop 1
	v_cndmask_b32_e32 v15, v16, v15, vcc
	v_and_b32_e32 v15, 0xffffff00, v15
	v_or_b32_e32 v55, 0xdf, v15
	v_not_b32_e32 v15, v22
	v_or_b32_e32 v16, 0x80000000, v22
	v_cmp_gt_i32_e32 vcc, 0, v22
	v_pk_add_f32 v[22:23], v[12:13], v[2:3] op_sel_hi:[0,1]
	v_lshl_add_u32 v13, v13, 10, s35
	v_cndmask_b32_e32 v15, v16, v15, vcc
	v_and_b32_e32 v15, 0xffffff00, v15
; #define CE_DESC(a, b) do { const unsigned _mx = (a) > (b) ? (a) : (b), _mn = (a) > (b) ? (b) : (a); (a) = _mx; (b) = _mn; } while (0)
; #define CK(i, j) ((f2key(va[i] + vb[j]) & ~255u) | (unsigned)(255 - (16 * (i) + (j))))
; __device__ __forceinline__ void sort16_desc(unsigned (&k)[16]) {
; #pragma unroll
;     for (int size = 2; size <= 16; size <<= 1)
; #pragma unroll
;         for (int stride = size >> 1; stride > 0; stride >>= 1)
; #pragma unroll
;             for (int i = 0; i < 16; ++i) { const int j = i ^ stride;
;                 if (j > i) { if ((i & size) == 0) CE_DESC(k[i], k[j]); else CE_DESC(k[j], k[i]); } }
; }
; __device__ __forceinline__ void peer_tile(const Args& A, LAS unsigned char* lds, int tile) {
;     ...
;             for (int j = 0; j < 16; ++j) Lf[j] = CK(0, j);
; #pragma unroll
;             for (int j = 0; j < 8; ++j) Bt[j] = CK(1, j);
; #pragma unroll
;             for (int j = 0; j < 5; ++j) Bt[8 + j] = CK(2, j);
; #pragma unroll
;             for (int j = 0; j < 3; ++j) Bt[13 + j] = CK(4, j);
;             sort16_desc(Bt); merge16(Lf, Bt);
; #pragma unroll
;             for (int j = 0; j < 4; ++j) Bt[j] = CK(3, j);
;             Bt[4] = CK(5, 0); Bt[5] = CK(5, 1); Bt[6] = CK(6, 0); Bt[7] = CK(6, 1); Bt[8] = CK(7, 0); Bt[9] = CK(7, 1);
;             Bt[10] = CK(8, 0); Bt[11] = CK(9, 0); Bt[12] = CK(10, 0); Bt[13] = CK(11, 0); Bt[14] = CK(12, 0); Bt[15] = CK(13, 0);
;             sort16_desc(Bt); merge16(Lf, Bt);
	v_or_b32_e32 v56, 0xde, v15
	v_not_b32_e32 v15, v23
	v_or_b32_e32 v16, 0x80000000, v23
	v_cmp_gt_i32_e32 vcc, 0, v23
	s_nop 1
	v_cndmask_b32_e32 v15, v16, v15, vcc
	v_and_b32_e32 v15, 0xffffff00, v15
	v_or_b32_e32 v23, 0xdd, v15
	v_not_b32_e32 v15, v22
	v_or_b32_e32 v16, 0x80000000, v22
	v_cmp_gt_i32_e32 vcc, 0, v22
	s_nop 1
	v_cndmask_b32_e32 v15, v16, v15, vcc
	v_and_b32_e32 v15, 0xffffff00, v15
	v_or_b32_e32 v22, 0xdc, v15
	v_mov_b32_e32 v15, v12
	v_mov_b32_e32 v16, v1
	v_pk_add_f32 v[16:17], v[14:15], v[16:17]
	s_nop 0
	v_not_b32_e32 v12, v17
	v_or_b32_e32 v15, 0x80000000, v17
	v_cmp_gt_i32_e32 vcc, 0, v17
	v_or_b32_e32 v17, 0x80000000, v16
	s_nop 0
	v_cndmask_b32_e32 v12, v15, v12, vcc
	v_not_b32_e32 v15, v16
	v_cmp_gt_i32_e32 vcc, 0, v16
	v_mov_b32_e32 v16, v3
	v_and_b32_e32 v12, 0xffffff00, v12
	v_cndmask_b32_e32 v15, v17, v15, vcc
	v_and_b32_e32 v15, 0xffffff00, v15
	v_mov_b32_e32 v17, v0
	v_or_b32_e32 v57, 0xbf, v15
	v_pk_add_f32 v[14:15], v[14:15], v[16:17] op_sel_hi:[0,1]
	v_not_b32_e32 v16, v15
	v_or_b32_e32 v17, 0x80000000, v15
	v_cmp_gt_i32_e32 vcc, 0, v15
	v_or_b32_e32 v12, 0xdb, v12
	v_pk_add_f32 v[2:3], v[4:5], v[2:3] op_sel_hi:[0,1]
	v_cndmask_b32_e32 v15, v17, v16, vcc
	v_not_b32_e32 v16, v14
	v_or_b32_e32 v17, 0x80000000, v14
	v_cmp_gt_i32_e32 vcc, 0, v14
	v_and_b32_e32 v15, 0xffffff00, v15
	v_or_b32_e32 v15, 0xbe, v15
	v_cndmask_b32_e32 v14, v17, v16, vcc
	v_and_b32_e32 v14, 0xffffff00, v14
	v_or_b32_e32 v14, 0xbd, v14
	v_max_u32_e32 v16, v41, v51
	v_min_u32_e32 v17, v41, v51
	v_max_u32_e32 v41, v53, v52
	v_min_u32_e32 v51, v53, v52
	v_max_u32_e32 v52, v35, v34
	v_min_u32_e32 v34, v35, v34
	v_max_u32_e32 v35, v54, v18
	v_min_u32_e32 v18, v54, v18
	v_max_u32_e32 v53, v55, v56
	v_min_u32_e32 v54, v55, v56
	v_max_u32_e32 v55, v22, v23
	v_min_u32_e32 v22, v22, v23
	v_max_u32_e32 v23, v12, v57
	v_min_u32_e32 v12, v12, v57
	v_max_u32_e32 v56, v14, v15
	v_min_u32_e32 v14, v14, v15
	v_max_u32_e32 v15, v16, v51
	v_min_u32_e32 v16, v16, v51
	v_max_u32_e32 v51, v17, v41
	v_min_u32_e32 v17, v17, v41
	v_max_u32_e32 v41, v18, v52
	v_min_u32_e32 v18, v18, v52
	v_max_u32_e32 v52, v35, v34
	v_min_u32_e32 v34, v35, v34
	v_max_u32_e32 v35, v53, v22
	v_min_u32_e32 v22, v53, v22
	v_max_u32_e32 v53, v54, v55
	v_min_u32_e32 v54, v54, v55
	v_max_u32_e32 v55, v14, v23
	v_min_u32_e32 v14, v14, v23
	v_max_u32_e32 v23, v56, v12
	v_min_u32_e32 v12, v56, v12
	v_max_u32_e32 v56, v15, v51
	v_min_u32_e32 v15, v15, v51
	v_max_u32_e32 v51, v16, v17
	v_min_u32_e32 v16, v16, v17
	v_max_u32_e32 v17, v34, v18
	v_min_u32_e32 v18, v34, v18
	v_max_u32_e32 v34, v52, v41
	v_min_u32_e32 v41, v52, v41
	v_max_u32_e32 v52, v35, v53
	v_min_u32_e32 v35, v35, v53
	v_max_u32_e32 v53, v22, v54
	v_min_u32_e32 v22, v22, v54
	v_max_u32_e32 v54, v12, v14
	v_min_u32_e32 v12, v12, v14
	v_max_u32_e32 v14, v23, v55
	v_min_u32_e32 v23, v23, v55
	v_max_u32_e32 v55, v56, v18
	v_min_u32_e32 v18, v56, v18
	v_max_u32_e32 v56, v15, v17
	v_min_u32_e32 v15, v15, v17
	v_max_u32_e32 v17, v51, v41
	v_min_u32_e32 v41, v51, v41
	v_max_u32_e32 v51, v16, v34
	v_min_u32_e32 v16, v16, v34
	v_max_u32_e32 v34, v12, v52
	v_min_u32_e32 v12, v12, v52
	v_max_u32_e32 v52, v54, v35
	v_min_u32_e32 v35, v54, v35
	v_max_u32_e32 v54, v23, v53
	v_min_u32_e32 v23, v23, v53
	v_max_u32_e32 v53, v14, v22
	v_min_u32_e32 v14, v14, v22
	v_max_u32_e32 v22, v55, v17
	v_min_u32_e32 v17, v55, v17
	v_max_u32_e32 v55, v56, v51
	v_min_u32_e32 v51, v56, v51
	v_max_u32_e32 v56, v18, v41
	v_min_u32_e32 v18, v18, v41
	v_max_u32_e32 v41, v15, v16
	v_min_u32_e32 v15, v15, v16
	v_max_u32_e32 v16, v23, v12
	v_min_u32_e32 v12, v23, v12
	v_max_u32_e32 v23, v14, v35
	v_min_u32_e32 v14, v14, v35
	v_max_u32_e32 v35, v54, v34
	v_min_u32_e32 v34, v54, v34
	v_max_u32_e32 v54, v53, v52
	v_min_u32_e32 v52, v53, v52
	v_max_u32_e32 v53, v22, v55
	v_min_u32_e32 v22, v22, v55
	v_max_u32_e32 v55, v17, v51
	v_min_u32_e32 v17, v17, v51
	v_max_u32_e32 v51, v56, v41
	v_min_u32_e32 v41, v56, v41
	v_max_u32_e32 v56, v18, v15
	v_min_u32_e32 v15, v18, v15
	v_max_u32_e32 v18, v14, v12
	v_min_u32_e32 v12, v14, v12
	v_max_u32_e32 v14, v23, v16
	v_min_u32_e32 v16, v23, v16
	v_max_u32_e32 v23, v52, v34
	v_min_u32_e32 v34, v52, v34
	v_max_u32_e32 v52, v54, v35
	v_min_u32_e32 v35, v54, v35
	v_max_u32_e32 v54, v53, v12
	v_min_u32_e32 v12, v53, v12
	v_max_u32_e32 v53, v22, v18
	v_min_u32_e32 v18, v22, v18
	v_max_u32_e32 v22, v55, v16
	v_min_u32_e32 v16, v55, v16
	v_max_u32_e32 v55, v17, v14
	v_min_u32_e32 v14, v17, v14
	v_max_u32_e32 v17, v51, v34
	v_min_u32_e32 v34, v51, v34
	v_max_u32_e32 v51, v41, v23
	v_min_u32_e32 v23, v41, v23
	v_max_u32_e32 v41, v56, v35
	v_min_u32_e32 v35, v56, v35
	v_max_u32_e32 v56, v15, v52
	v_min_u32_e32 v15, v15, v52
	v_max_u32_e32 v52, v54, v17
	v_min_u32_e32 v17, v54, v17
	v_max_u32_e32 v54, v53, v51
	v_min_u32_e32 v51, v53, v51
	v_max_u32_e32 v53, v22, v41
	v_min_u32_e32 v22, v22, v41
	v_max_u32_e32 v41, v55, v56
	v_min_u32_e32 v55, v55, v56
	v_max_u32_e32 v56, v12, v34
	v_min_u32_e32 v12, v12, v34
	v_max_u32_e32 v34, v18, v23
	v_min_u32_e32 v18, v18, v23
	v_max_u32_e32 v23, v16, v35
	v_min_u32_e32 v16, v16, v35
	v_max_u32_e32 v35, v14, v15
	v_min_u32_e32 v14, v14, v15
	v_max_u32_e32 v15, v52, v53
	v_min_u32_e32 v52, v52, v53
	v_max_u32_e32 v53, v54, v41
	v_min_u32_e32 v41, v54, v41
	v_max_u32_e32 v54, v17, v22
	v_min_u32_e32 v17, v17, v22
	v_max_u32_e32 v22, v51, v55
	v_min_u32_e32 v51, v51, v55
	v_max_u32_e32 v55, v56, v23
	v_min_u32_e32 v23, v56, v23
	v_max_u32_e32 v56, v34, v35
	v_min_u32_e32 v34, v34, v35
	v_max_u32_e32 v35, v12, v16
	v_min_u32_e32 v12, v12, v16
	v_max_u32_e32 v16, v18, v14
	v_min_u32_e32 v14, v18, v14
; #define CK(i, j) ((f2key(va[i] + vb[j]) & ~255u) | (unsigned)(255 - (16 * (i) + (j))))
; __device__ __forceinline__ void peer_tile(const Args& A, LAS unsigned char* lds, int tile) {
;     ...
;             sort16_desc(Bt); merge16(Lf, Bt);
; #pragma unroll
;             for (int j = 0; j < 4; ++j) Bt[j] = CK(3, j);
;             Bt[4] = CK(5, 0); Bt[5] = CK(5, 1); Bt[6] = CK(6, 0); Bt[7] = CK(6, 1); Bt[8] = CK(7, 0); Bt[9] = CK(7, 1);
;             Bt[10] = CK(8, 0); Bt[11] = CK(9, 0); Bt[12] = CK(10, 0); Bt[13] = CK(11, 0); Bt[14] = CK(12, 0); Bt[15] = CK(13, 0);
;             sort16_desc(Bt); merge16(Lf, Bt);
	v_min_u32_e32 v18, v15, v53
	v_min_u32_e32 v57, v52, v41
	v_min_u32_e32 v58, v54, v22
	v_min_u32_e32 v59, v17, v51
	v_min_u32_e32 v60, v55, v56
	v_min_u32_e32 v61, v23, v34
	v_min_u32_e32 v62, v35, v16
	v_min_u32_e32 v63, v12, v14
	v_max_u32_e32 v33, v33, v63
	v_max3_u32 v12, v44, v12, v14
	v_max_u32_e32 v14, v45, v62
	v_max3_u32 v16, v46, v35, v16
	v_max_u32_e32 v35, v47, v61
	v_max3_u32 v23, v48, v23, v34
	v_max_u32_e32 v34, v43, v60
	v_max3_u32 v42, v42, v55, v56
	v_max_u32_e32 v43, v49, v59
	v_max3_u32 v17, v50, v17, v51
	v_max_u32_e32 v36, v36, v58
	v_max3_u32 v22, v37, v54, v22
	v_max_u32_e32 v37, v38, v57
	v_max3_u32 v38, v39, v52, v41
	v_max_u32_e32 v18, v20, v18
	v_max3_u32 v15, v40, v15, v53
	v_max_u32_e32 v20, v33, v43
	v_min_u32_e32 v33, v33, v43
	v_max_u32_e32 v39, v12, v17
	v_min_u32_e32 v12, v12, v17
	v_max_u32_e32 v17, v14, v36
	v_min_u32_e32 v14, v14, v36
	v_max_u32_e32 v36, v16, v22
	v_min_u32_e32 v16, v16, v22
	v_max_u32_e32 v22, v35, v37
	v_min_u32_e32 v35, v35, v37
	v_max_u32_e32 v37, v23, v38
	v_min_u32_e32 v23, v23, v38
	v_max_u32_e32 v38, v34, v18
	v_min_u32_e32 v18, v34, v18
	v_max_u32_e32 v34, v42, v15
	v_min_u32_e32 v15, v42, v15
	v_max_u32_e32 v40, v20, v22
	v_min_u32_e32 v20, v20, v22
	v_max_u32_e32 v22, v39, v37
	v_min_u32_e32 v37, v39, v37
	v_max_u32_e32 v39, v17, v38
	v_min_u32_e32 v17, v17, v38
	v_max_u32_e32 v38, v36, v34
	v_min_u32_e32 v34, v36, v34
	v_max_u32_e32 v36, v33, v35
	v_min_u32_e32 v33, v33, v35
	v_max_u32_e32 v35, v12, v23
	v_min_u32_e32 v12, v12, v23
	v_max_u32_e32 v23, v14, v18
	v_min_u32_e32 v14, v14, v18
	v_max_u32_e32 v18, v16, v15
	v_min_u32_e32 v15, v16, v15
	v_max_u32_e32 v16, v40, v39
	v_min_u32_e32 v39, v40, v39
	v_max_u32_e32 v40, v22, v38
	v_min_u32_e32 v22, v22, v38
	v_max_u32_e32 v38, v20, v17
	v_min_u32_e32 v17, v20, v17
	v_max_u32_e32 v20, v37, v34
	v_min_u32_e32 v34, v37, v34
	v_max_u32_e32 v37, v36, v23
	v_min_u32_e32 v23, v36, v23
	v_max_u32_e32 v36, v35, v18
	v_min_u32_e32 v18, v35, v18
	v_max_u32_e32 v35, v33, v14
	v_min_u32_e32 v33, v33, v14
	v_max_u32_e32 v41, v12, v15
	v_min_u32_e32 v12, v12, v15
	v_pk_add_f32 v[14:15], v[4:5], v[0:1] op_sel_hi:[0,1]
	v_not_b32_e32 v50, v15
	v_or_b32_e32 v51, 0x80000000, v15
	v_cmp_gt_i32_e32 vcc, 0, v15
	v_not_b32_e32 v4, v3
	v_min_u32_e32 v42, v16, v40
	v_cndmask_b32_e32 v15, v51, v50, vcc
	v_not_b32_e32 v50, v14
	v_or_b32_e32 v51, 0x80000000, v14
	v_cmp_gt_i32_e32 vcc, 0, v14
	v_and_b32_e32 v15, 0xffffff00, v15
	v_or_b32_e32 v15, 0xcf, v15
	v_cndmask_b32_e32 v14, v51, v50, vcc
	v_or_b32_e32 v50, 0x80000000, v3
	v_cmp_gt_i32_e32 vcc, 0, v3
	v_and_b32_e32 v14, 0xffffff00, v14
	v_or_b32_e32 v14, 0xce, v14
	v_cndmask_b32_e32 v3, v50, v4, vcc
	v_and_b32_e32 v3, 0xffffff00, v3
	v_or_b32_e32 v4, 0xcd, v3
	v_not_b32_e32 v3, v2
	v_or_b32_e32 v50, 0x80000000, v2
	v_cmp_gt_i32_e32 vcc, 0, v2
	v_min_u32_e32 v43, v39, v22
	v_min_u32_e32 v44, v38, v20
	v_cndmask_b32_e32 v2, v50, v3, vcc
	v_and_b32_e32 v2, 0xffffff00, v2
	v_or_b32_e32 v50, 0xcc, v2
	v_pk_add_f32 v[2:3], v[10:11], v[0:1] op_sel_hi:[0,1]
	v_not_b32_e32 v10, v3
	v_or_b32_e32 v51, 0x80000000, v3
	v_cmp_gt_i32_e32 vcc, 0, v3
	v_min_u32_e32 v45, v17, v34
	v_min_u32_e32 v46, v37, v36
	v_cndmask_b32_e32 v3, v51, v10, vcc
	v_and_b32_e32 v3, 0xffffff00, v3
	v_or_b32_e32 v10, 0xaf, v3
	v_not_b32_e32 v3, v2
	v_or_b32_e32 v51, 0x80000000, v2
	v_cmp_gt_i32_e32 vcc, 0, v2
	v_min_u32_e32 v47, v23, v18
	v_min_u32_e32 v48, v35, v41
	v_cndmask_b32_e32 v2, v51, v3, vcc
	v_and_b32_e32 v2, 0xffffff00, v2
	v_or_b32_e32 v51, 0xae, v2
	v_pk_add_f32 v[2:3], v[8:9], v[0:1] op_sel_hi:[0,1]
	v_not_b32_e32 v8, v3
	v_or_b32_e32 v52, 0x80000000, v3
	v_cmp_gt_i32_e32 vcc, 0, v3
	v_min_u32_e32 v49, v33, v12
	v_lshlrev_b32_e32 v11, 9, v11
	v_cndmask_b32_e32 v3, v52, v8, vcc
	v_and_b32_e32 v3, 0xffffff00, v3
	v_or_b32_e32 v8, 0x9f, v3
	v_not_b32_e32 v3, v2
	v_or_b32_e32 v52, 0x80000000, v2
	v_cmp_gt_i32_e32 vcc, 0, v2
	s_nop 1
	v_cndmask_b32_e32 v2, v52, v3, vcc
	v_and_b32_e32 v2, 0xffffff00, v2
	v_or_b32_e32 v52, 0x9e, v2
	v_pk_add_f32 v[2:3], v[6:7], v[0:1] op_sel_hi:[0,1]
	v_not_b32_e32 v0, v3
	v_or_b32_e32 v6, 0x80000000, v3
	v_cmp_gt_i32_e32 vcc, 0, v3
	v_not_b32_e32 v3, v2
	s_nop 0
	v_cndmask_b32_e32 v0, v6, v0, vcc
	v_or_b32_e32 v6, 0x80000000, v2
	v_cmp_gt_i32_e32 vcc, 0, v2
	v_and_b32_e32 v0, 0xffffff00, v0
	v_or_b32_e32 v0, 0x8f, v0
	v_cndmask_b32_e32 v2, v6, v3, vcc
	v_add_f32_e32 v3, v27, v1
	v_not_b32_e32 v6, v3
	v_or_b32_e32 v27, 0x80000000, v3
	v_cmp_gt_i32_e32 vcc, 0, v3
	v_and_b32_e32 v2, 0xffffff00, v2
	v_or_b32_e32 v2, 0x8e, v2
	v_cndmask_b32_e32 v3, v27, v6, vcc
	v_add_f32_e32 v6, v28, v1
	v_not_b32_e32 v27, v6
	v_or_b32_e32 v28, 0x80000000, v6
	v_cmp_gt_i32_e32 vcc, 0, v6
	v_and_b32_e32 v3, 0xffffff00, v3
	v_or_b32_e32 v3, 0x7f, v3
	v_cndmask_b32_e32 v6, v28, v27, vcc
	v_add_f32_e32 v27, v29, v1
	v_not_b32_e32 v28, v27
	v_or_b32_e32 v29, 0x80000000, v27
	v_cmp_gt_i32_e32 vcc, 0, v27
	v_and_b32_e32 v6, 0xffffff00, v6
	v_or_b32_e32 v6, 0x6f, v6
	v_cndmask_b32_e32 v27, v29, v28, vcc
	v_add_f32_e32 v28, v30, v1
	v_not_b32_e32 v29, v28
	v_or_b32_e32 v30, 0x80000000, v28
	v_cmp_gt_i32_e32 vcc, 0, v28
	v_and_b32_e32 v27, 0xffffff00, v27
	v_or_b32_e32 v27, 0x5f, v27
	v_cndmask_b32_e32 v28, v30, v29, vcc
	v_add_f32_e32 v29, v31, v1
	v_not_b32_e32 v30, v29
	v_or_b32_e32 v31, 0x80000000, v29
	v_cmp_gt_i32_e32 vcc, 0, v29
	v_and_b32_e32 v28, 0xffffff00, v28
	v_or_b32_e32 v28, 0x4f, v28
	v_cndmask_b32_e32 v29, v31, v30, vcc
	v_add_f32_e32 v30, v32, v1
	v_not_b32_e32 v31, v30
	v_or_b32_e32 v32, 0x80000000, v30
	v_cmp_gt_i32_e32 vcc, 0, v30
	v_and_or_b32 v29, v29, s34, 63
	s_nop 0
	v_cndmask_b32_e32 v30, v32, v31, vcc
; #define CE_DESC(a, b) do { const unsigned _mx = (a) > (b) ? (a) : (b), _mn = (a) > (b) ? (b) : (a); (a) = _mx; (b) = _mn; } while (0)
; #define CK(i, j) ((f2key(va[i] + vb[j]) & ~255u) | (unsigned)(255 - (16 * (i) + (j))))
; __device__ __forceinline__ void sort16_desc(unsigned (&k)[16]) {
; #pragma unroll
;     for (int size = 2; size <= 16; size <<= 1)
; #pragma unroll
;         for (int stride = size >> 1; stride > 0; stride >>= 1)
; #pragma unroll
;             for (int i = 0; i < 16; ++i) { const int j = i ^ stride;
;                 if (j > i) { if ((i & size) == 0) CE_DESC(k[i], k[j]); else CE_DESC(k[j], k[i]); } }
; }
; __device__ __forceinline__ void merge16(unsigned (&a)[16], const unsigned (&b)[16]) {
; #pragma unroll
;     for (int i = 0; i < 16; ++i) a[i] = a[i] > b[15 - i] ? a[i] : b[15 - i];
; #pragma unroll
;     for (int stride = 8; stride > 0; stride >>= 1)
; #pragma unroll
;         for (int i = 0; i < 16; ++i) { const int j = i ^ stride; if (j > i) CE_DESC(a[i], a[j]); }
; }
; __device__ __forceinline__ void peer_tile(const Args& A, LAS unsigned char* lds, int tile) {
;     ...
;             for (int j = 0; j < 4; ++j) Bt[j] = CK(3, j);
;             Bt[4] = CK(5, 0); Bt[5] = CK(5, 1); Bt[6] = CK(6, 0); Bt[7] = CK(6, 1); Bt[8] = CK(7, 0); Bt[9] = CK(7, 1);
;             Bt[10] = CK(8, 0); Bt[11] = CK(9, 0); Bt[12] = CK(10, 0); Bt[13] = CK(11, 0); Bt[14] = CK(12, 0); Bt[15] = CK(13, 0);
;             sort16_desc(Bt); merge16(Lf, Bt);
	v_and_or_b32 v30, v30, s34, 47
	v_max_u32_e32 v31, v15, v14
	v_min_u32_e32 v14, v15, v14
	v_max_u32_e32 v15, v50, v4
	v_min_u32_e32 v4, v50, v4
	v_max_u32_e32 v32, v10, v51
	v_min_u32_e32 v10, v10, v51
	v_max_u32_e32 v50, v52, v8
	v_min_u32_e32 v8, v52, v8
	v_max_u32_e32 v51, v0, v2
	v_min_u32_e32 v0, v0, v2
	v_max_u32_e32 v2, v6, v3
	v_min_u32_e32 v3, v6, v3
	v_max_u32_e32 v6, v27, v28
	v_min_u32_e32 v27, v27, v28
	v_max_u32_e32 v28, v30, v29
	v_min_u32_e32 v29, v30, v29
	v_max_u32_e32 v30, v31, v4
	v_min_u32_e32 v4, v31, v4
	v_max_u32_e32 v31, v14, v15
	v_min_u32_e32 v14, v14, v15
	v_max_u32_e32 v15, v8, v32
	v_min_u32_e32 v8, v8, v32
	v_max_u32_e32 v32, v50, v10
	v_min_u32_e32 v10, v50, v10
	v_max_u32_e32 v50, v51, v3
	v_min_u32_e32 v3, v51, v3
	v_max_u32_e32 v51, v0, v2
	v_min_u32_e32 v0, v0, v2
	v_max_u32_e32 v2, v29, v6
	v_min_u32_e32 v6, v29, v6
	v_max_u32_e32 v29, v28, v27
	v_min_u32_e32 v27, v28, v27
	v_max_u32_e32 v28, v30, v31
	v_min_u32_e32 v30, v30, v31
	v_max_u32_e32 v31, v4, v14
	v_min_u32_e32 v4, v4, v14
	v_max_u32_e32 v14, v10, v8
	v_min_u32_e32 v8, v10, v8
	v_max_u32_e32 v10, v32, v15
	v_min_u32_e32 v15, v32, v15
	v_max_u32_e32 v32, v50, v51
	v_min_u32_e32 v50, v50, v51
	v_max_u32_e32 v51, v3, v0
	v_min_u32_e32 v0, v3, v0
	v_max_u32_e32 v3, v27, v6
	v_min_u32_e32 v6, v27, v6
	v_max_u32_e32 v27, v29, v2
	v_min_u32_e32 v2, v29, v2
	v_max_u32_e32 v29, v28, v8
	v_min_u32_e32 v8, v28, v8
	v_max_u32_e32 v28, v30, v14
	v_min_u32_e32 v14, v30, v14
	v_max_u32_e32 v30, v31, v15
	v_min_u32_e32 v15, v31, v15
	v_max_u32_e32 v31, v4, v10
	v_min_u32_e32 v4, v4, v10
	v_max_u32_e32 v10, v6, v32
	v_min_u32_e32 v6, v6, v32
	v_max_u32_e32 v32, v3, v50
	v_min_u32_e32 v3, v3, v50
	v_max_u32_e32 v50, v2, v51
	v_min_u32_e32 v2, v2, v51
	v_max_u32_e32 v51, v27, v0
	v_min_u32_e32 v0, v27, v0
	v_max_u32_e32 v27, v29, v30
	v_min_u32_e32 v29, v29, v30
	v_max_u32_e32 v30, v28, v31
	v_min_u32_e32 v28, v28, v31
	v_max_u32_e32 v31, v8, v15
	v_min_u32_e32 v8, v8, v15
	v_max_u32_e32 v15, v14, v4
	v_min_u32_e32 v4, v14, v4
	v_max_u32_e32 v14, v2, v6
	v_min_u32_e32 v2, v2, v6
	v_max_u32_e32 v6, v0, v3
	v_min_u32_e32 v0, v0, v3
	v_max_u32_e32 v3, v50, v10
	v_min_u32_e32 v10, v50, v10
	v_max_u32_e32 v50, v51, v32
	v_min_u32_e32 v32, v51, v32
	v_max_u32_e32 v51, v27, v30
	v_min_u32_e32 v27, v27, v30
	v_max_u32_e32 v30, v29, v28
	v_min_u32_e32 v28, v29, v28
	v_max_u32_e32 v29, v31, v15
	v_min_u32_e32 v15, v31, v15
	v_max_u32_e32 v31, v8, v4
	v_min_u32_e32 v4, v8, v4
	v_max_u32_e32 v8, v0, v2
	v_min_u32_e32 v0, v0, v2
	v_max_u32_e32 v2, v6, v14
	v_min_u32_e32 v6, v6, v14
	v_max_u32_e32 v14, v32, v10
	v_min_u32_e32 v10, v32, v10
	v_max_u32_e32 v32, v50, v3
	v_min_u32_e32 v3, v50, v3
	v_max_u32_e32 v50, v51, v0
	v_min_u32_e32 v0, v51, v0
	v_max_u32_e32 v51, v27, v8
	v_min_u32_e32 v8, v27, v8
	v_max_u32_e32 v27, v30, v6
	v_min_u32_e32 v6, v30, v6
	v_max_u32_e32 v30, v28, v2
	v_min_u32_e32 v2, v28, v2
	v_max_u32_e32 v28, v29, v10
	v_min_u32_e32 v10, v29, v10
	v_max_u32_e32 v29, v15, v14
	v_min_u32_e32 v14, v15, v14
	v_max_u32_e32 v15, v31, v3
	v_min_u32_e32 v3, v31, v3
	v_max_u32_e32 v31, v4, v32
	v_min_u32_e32 v4, v4, v32
	v_max_u32_e32 v32, v50, v28
	v_min_u32_e32 v28, v50, v28
	v_max_u32_e32 v50, v51, v29
	v_min_u32_e32 v29, v51, v29
	v_max_u32_e32 v51, v27, v15
	v_min_u32_e32 v15, v27, v15
	v_max_u32_e32 v27, v30, v31
	v_min_u32_e32 v30, v30, v31
	v_max_u32_e32 v31, v0, v10
	v_min_u32_e32 v0, v0, v10
	v_max_u32_e32 v10, v8, v14
	v_min_u32_e32 v8, v8, v14
	v_max_u32_e32 v14, v6, v3
	v_min_u32_e32 v3, v6, v3
	v_max_u32_e32 v6, v2, v4
	v_min_u32_e32 v2, v2, v4
	v_max_u32_e32 v4, v32, v51
	v_min_u32_e32 v32, v32, v51
	v_max_u32_e32 v51, v50, v27
	v_min_u32_e32 v27, v50, v27
	v_max_u32_e32 v50, v28, v15
	v_min_u32_e32 v15, v28, v15
	v_max_u32_e32 v28, v29, v30
	v_min_u32_e32 v29, v29, v30
	v_max_u32_e32 v30, v31, v14
	v_min_u32_e32 v14, v31, v14
	v_max_u32_e32 v31, v10, v6
	v_min_u32_e32 v6, v10, v6
	v_max_u32_e32 v10, v0, v3
	v_min_u32_e32 v0, v0, v3
	v_max_u32_e32 v3, v8, v2
	v_min_u32_e32 v2, v8, v2
	v_min_u32_e32 v8, v4, v51
	v_min_u32_e32 v52, v32, v27
	v_min_u32_e32 v53, v50, v28
	v_min_u32_e32 v54, v15, v29
	v_min_u32_e32 v55, v30, v31
	v_min_u32_e32 v56, v14, v6
	v_min_u32_e32 v57, v10, v3
	v_min_u32_e32 v58, v0, v2
	v_max3_u32 v16, v16, v40, v58
	v_max3_u32 v0, v42, v0, v2
	v_max3_u32 v2, v39, v22, v57
	v_max3_u32 v3, v43, v10, v3
	v_max3_u32 v10, v38, v20, v56
	v_max3_u32 v6, v44, v14, v6
	v_max3_u32 v14, v17, v34, v55
	v_max3_u32 v17, v45, v30, v31
	v_max3_u32 v20, v37, v36, v54
	v_max3_u32 v15, v46, v15, v29
	v_max3_u32 v18, v23, v18, v53
	v_max3_u32 v22, v47, v50, v28
	v_max3_u32 v23, v35, v41, v52
	v_max3_u32 v27, v48, v32, v27
	v_max3_u32 v8, v33, v12, v8
	v_max3_u32 v4, v49, v4, v51
	v_max_u32_e32 v12, v16, v20
	v_min_u32_e32 v16, v16, v20
	v_max_u32_e32 v20, v0, v15
	v_min_u32_e32 v0, v0, v15
	v_max_u32_e32 v15, v2, v18
	v_min_u32_e32 v2, v2, v18
	v_max_u32_e32 v18, v3, v22
	v_min_u32_e32 v3, v3, v22
	v_max_u32_e32 v22, v10, v23
	v_min_u32_e32 v10, v10, v23
	v_max_u32_e32 v23, v6, v27
	v_min_u32_e32 v6, v6, v27
	v_max_u32_e32 v27, v14, v8
	v_min_u32_e32 v8, v14, v8
	v_max_u32_e32 v14, v17, v4
	v_min_u32_e32 v4, v17, v4
	v_max_u32_e32 v17, v12, v22
	v_min_u32_e32 v12, v12, v22
	v_max_u32_e32 v22, v20, v23
	v_min_u32_e32 v20, v20, v23
	v_max_u32_e32 v23, v15, v27
	v_min_u32_e32 v15, v15, v27
	v_max_u32_e32 v27, v18, v14
	v_min_u32_e32 v14, v18, v14
	v_max_u32_e32 v18, v16, v10
	v_min_u32_e32 v10, v16, v10
	v_max_u32_e32 v16, v0, v6
	v_min_u32_e32 v0, v0, v6
	v_max_u32_e32 v6, v2, v8
	v_min_u32_e32 v2, v2, v8
	v_max_u32_e32 v8, v3, v4
; __device__ __forceinline__ float key2f(unsigned k) { const unsigned u = (k & 0x80000000u) ? (k & 0x7fffffffu) : ~k; return __uint_as_float(u); }
; #define CE_DESC(a, b) do { const unsigned _mx = (a) > (b) ? (a) : (b), _mn = (a) > (b) ? (b) : (a); (a) = _mx; (b) = _mn; } while (0)
; #define CK(i, j) ((f2key(va[i] + vb[j]) & ~255u) | (unsigned)(255 - (16 * (i) + (j))))
; __device__ __forceinline__ void peer_tile(const Args& A, LAS unsigned char* lds, int tile) {
;     ...
;             sort16_desc(Bt); merge16(Lf, Bt);
;             { unsigned x0 = CK(14, 0), x1 = CK(15, 0);
; #pragma unroll
;               for (int i = 0; i < 16; ++i) CE_DESC(Lf[i], x0);
; #pragma unroll
;               for (int i = 0; i < 16; ++i) CE_DESC(Lf[i], x1); }
;     ...
;             float fv[16], den = 0.f; const float f0 = key2f(Lf[0] & ~255u);
; #pragma unroll
;             for (int k = 0; k < 16; ++k) { fv[k] = __expf(key2f(Lf[k] & ~255u) - f0); den += fv[k]; }
	v_min_u32_e32 v3, v3, v4
	v_max_u32_e32 v4, v17, v23
	v_min_u32_e32 v17, v17, v23
	v_max_u32_e32 v23, v22, v27
	v_min_u32_e32 v22, v22, v27
	v_max_u32_e32 v27, v12, v15
	v_min_u32_e32 v12, v12, v15
	v_max_u32_e32 v15, v20, v14
	v_min_u32_e32 v14, v20, v14
	v_max_u32_e32 v20, v18, v6
	v_min_u32_e32 v6, v18, v6
	v_max_u32_e32 v18, v16, v8
	v_min_u32_e32 v8, v16, v8
	v_max_u32_e32 v16, v10, v2
	v_min_u32_e32 v2, v10, v2
	v_max_u32_e32 v10, v0, v3
	v_min_u32_e32 v0, v0, v3
	v_max_u32_e32 v41, v2, v0
	v_min_u32_e32 v0, v2, v0
	v_add_f32_e32 v2, v25, v1
	v_not_b32_e32 v25, v2
	v_or_b32_e32 v42, 0x80000000, v2
	v_cmp_gt_i32_e32 vcc, 0, v2
	v_add_f32_e32 v1, v26, v1
	v_max_u32_e32 v3, v4, v23
	v_cndmask_b32_e32 v2, v42, v25, vcc
	v_and_or_b32 v2, v2, s34, 31
	v_not_b32_e32 v25, v1
	v_or_b32_e32 v26, 0x80000000, v1
	v_cmp_gt_i32_e32 vcc, 0, v1
	v_min_u32_e32 v28, v4, v23
	v_max_u32_e32 v29, v17, v22
	v_cndmask_b32_e32 v1, v26, v25, vcc
	v_max_u32_e32 v25, v3, v2
	v_min_u32_e32 v3, v3, v2
	v_min_u32_e32 v3, v28, v3
	v_min_u32_e32 v30, v17, v22
	v_med3_u32 v2, v4, v23, v2
	v_min_u32_e32 v23, v29, v3
	v_max_u32_e32 v31, v27, v15
	v_max_u32_e32 v4, v29, v3
	v_med3_u32 v3, v17, v22, v3
	v_min_u32_e32 v17, v30, v23
	v_min_u32_e32 v32, v27, v15
	v_min_u32_e32 v23, v31, v17
	v_max_u32_e32 v33, v12, v14
	v_max_u32_e32 v22, v31, v17
	v_med3_u32 v15, v27, v15, v17
	v_min_u32_e32 v17, v32, v23
	v_min_u32_e32 v34, v12, v14
	v_min_u32_e32 v26, v33, v17
	v_max_u32_e32 v35, v20, v18
	v_med3_u32 v12, v12, v14, v17
	v_min_u32_e32 v14, v34, v26
	v_min_u32_e32 v36, v20, v18
	v_min_u32_e32 v26, v35, v14
	v_max_u32_e32 v37, v6, v8
	v_max_u32_e32 v23, v33, v17
	v_max_u32_e32 v17, v35, v14
	v_med3_u32 v14, v20, v18, v14
	v_min_u32_e32 v18, v36, v26
	v_min_u32_e32 v38, v6, v8
	v_min_u32_e32 v26, v37, v18
	v_max_u32_e32 v39, v16, v10
	v_med3_u32 v6, v6, v8, v18
	v_min_u32_e32 v8, v38, v26
	v_min_u32_e32 v40, v16, v10
	v_min_u32_e32 v26, v39, v8
	v_and_or_b32 v1, v1, s34, 15
	v_max_u32_e32 v20, v37, v18
	v_max_u32_e32 v18, v39, v8
	v_med3_u32 v8, v16, v10, v8
	v_min_u32_e32 v10, v40, v26
	v_max_u32_e32 v26, v25, v1
	v_min_u32_e32 v1, v25, v1
	v_max_u32_e32 v25, v2, v1
	v_min_u32_e32 v1, v2, v1
	v_max_u32_e32 v2, v4, v1
	v_min_u32_e32 v1, v4, v1
	v_max_u32_e32 v4, v3, v1
	v_min_u32_e32 v1, v3, v1
	v_max_u32_e32 v3, v22, v1
	v_min_u32_e32 v1, v22, v1
	v_max_u32_e32 v22, v15, v1
	v_min_u32_e32 v1, v15, v1
	v_max_u32_e32 v15, v23, v1
	v_min_u32_e32 v1, v23, v1
	v_max_u32_e32 v23, v12, v1
	v_min_u32_e32 v1, v12, v1
	v_max_u32_e32 v12, v17, v1
	v_min_u32_e32 v1, v17, v1
	v_max_u32_e32 v17, v14, v1
	v_min_u32_e32 v1, v14, v1
	v_max_u32_e32 v14, v20, v1
	v_min_u32_e32 v1, v20, v1
	v_max_u32_e32 v20, v6, v1
	v_min_u32_e32 v1, v6, v1
	v_max_u32_e32 v6, v18, v1
	v_min_u32_e32 v1, v18, v1
	v_max_u32_e32 v16, v41, v10
	v_max_u32_e32 v18, v8, v1
	v_min_u32_e32 v1, v8, v1
	v_min_u32_e32 v10, v41, v10
	v_max_u32_e32 v8, v16, v1
	v_min_u32_e32 v1, v16, v1
	v_max3_u32 v10, v0, v10, v1
	v_and_b32_e32 v0, 0x7fffff00, v26
	v_bitop3_b32 v1, v26, s33, v26 bitop3:0xcf
	v_cmp_gt_i32_e32 vcc, 0, v26
	v_and_b32_e32 v16, 0x7fffff00, v25
	v_bitop3_b32 v27, v25, s33, v25 bitop3:0xcf
	v_cndmask_b32_e32 v0, v1, v0, vcc
	v_cmp_gt_i32_e32 vcc, 0, v25
	v_sub_f32_e32 v1, v0, v0
	v_bitop3_b32 v28, v2, s33, v2 bitop3:0xcf
	v_cndmask_b32_e32 v16, v27, v16, vcc
	v_and_b32_e32 v27, 0x7fffff00, v2
	v_cmp_gt_i32_e32 vcc, 0, v2
	v_mul_f32_e32 v1, 0x3fb8aa3b, v1
	v_sub_f32_e32 v16, v16, v0
	v_cndmask_b32_e32 v27, v28, v27, vcc
	v_and_b32_e32 v28, 0x7fffff00, v4
	v_bitop3_b32 v29, v4, s33, v4 bitop3:0xcf
	v_cmp_gt_i32_e32 vcc, 0, v4
	v_exp_f32_e32 v1, v1
	v_mul_f32_e32 v16, 0x3fb8aa3b, v16
	v_sub_f32_e32 v27, v27, v0
	v_cndmask_b32_e32 v28, v29, v28, vcc
	v_and_b32_e32 v30, 0x7fffff00, v3
	v_bitop3_b32 v31, v3, s33, v3 bitop3:0xcf
	v_cmp_gt_i32_e32 vcc, 0, v3
	v_exp_f32_e32 v16, v16
	v_mul_f32_e32 v27, 0x3fb8aa3b, v27
	v_sub_f32_e32 v28, v28, v0
	v_cndmask_b32_e32 v30, v31, v30, vcc
	v_and_b32_e32 v31, 0x7fffff00, v22
	v_bitop3_b32 v32, v22, s33, v22 bitop3:0xcf
	v_cmp_gt_i32_e32 vcc, 0, v22
	v_exp_f32_e32 v27, v27
	v_mul_f32_e32 v28, 0x3fb8aa3b, v28
	v_sub_f32_e32 v30, v30, v0
	v_cndmask_b32_e32 v31, v32, v31, vcc
	v_and_b32_e32 v32, 0x7fffff00, v15
	v_bitop3_b32 v33, v15, s33, v15 bitop3:0xcf
	v_cmp_gt_i32_e32 vcc, 0, v15
	v_exp_f32_e32 v28, v28
	v_mul_f32_e32 v30, 0x3fb8aa3b, v30
	v_sub_f32_e32 v31, v31, v0
	v_cndmask_b32_e32 v32, v33, v32, vcc
	v_and_b32_e32 v33, 0x7fffff00, v23
	v_bitop3_b32 v34, v23, s33, v23 bitop3:0xcf
	v_cmp_gt_i32_e32 vcc, 0, v23
	v_add_f32_e32 v29, 0, v1
	v_exp_f32_e32 v30, v30
	v_mul_f32_e32 v31, 0x3fb8aa3b, v31
	v_sub_f32_e32 v32, v32, v0
	v_cndmask_b32_e32 v33, v34, v33, vcc
	v_and_b32_e32 v34, 0x7fffff00, v12
	v_bitop3_b32 v35, v12, s33, v12 bitop3:0xcf
	v_cmp_gt_i32_e32 vcc, 0, v12
	v_add_f32_e32 v29, v29, v16
	v_exp_f32_e32 v31, v31
	v_mul_f32_e32 v32, 0x3fb8aa3b, v32
	v_sub_f32_e32 v33, v33, v0
	v_cndmask_b32_e32 v34, v35, v34, vcc
	v_and_b32_e32 v35, 0x7fffff00, v17
	v_bitop3_b32 v36, v17, s33, v17 bitop3:0xcf
	v_cmp_gt_i32_e32 vcc, 0, v17
	v_add_f32_e32 v29, v29, v27
	v_exp_f32_e32 v32, v32
	v_mul_f32_e32 v33, 0x3fb8aa3b, v33
	v_sub_f32_e32 v34, v34, v0
	v_cndmask_b32_e32 v35, v36, v35, vcc
	v_and_b32_e32 v36, 0x7fffff00, v14
	v_bitop3_b32 v37, v14, s33, v14 bitop3:0xcf
	v_cmp_gt_i32_e32 vcc, 0, v14
	v_add_f32_e32 v29, v29, v28
	v_exp_f32_e32 v33, v33
	v_mul_f32_e32 v34, 0x3fb8aa3b, v34
	v_sub_f32_e32 v35, v35, v0
	v_cndmask_b32_e32 v36, v37, v36, vcc
	v_and_b32_e32 v37, 0x7fffff00, v20
	v_bitop3_b32 v38, v20, s33, v20 bitop3:0xcf
	v_cmp_gt_i32_e32 vcc, 0, v20
	v_add_f32_e32 v29, v29, v30
; #define LDS_WAIT() asm volatile("s_waitcnt lgkmcnt(0)" ::: "memory")
; __device__ __forceinline__ float key2f(unsigned k) { const unsigned u = (k & 0x80000000u) ? (k & 0x7fffffffu) : ~k; return __uint_as_float(u); }
; __device__ __forceinline__ void peer_tile(const Args& A, LAS unsigned char* lds, int tile) {
;     ...
;             float fv[16], den = 0.f; const float f0 = key2f(Lf[0] & ~255u);
; #pragma unroll
;             for (int k = 0; k < 16; ++k) { fv[k] = __expf(key2f(Lf[k] & ~255u) - f0); den += fv[k]; }
;             const float rden = 1.f / den;
;             LDS_WAIT();
; #pragma unroll
;             for (int k = 0; k < 16; ++k) { const unsigned code = 255u - (Lf[k] & 255u); const unsigned e = idx[code >> 4] * 128u + idx[16 + (code & 15u)];
;                 u32x2 sv; sv.x = e; sv.y = __float_as_uint(fv[k] * rden); SEL[(tl * 8 + h) * 16 + k] = sv; }
	v_exp_f32_e32 v34, v34
	v_mul_f32_e32 v35, 0x3fb8aa3b, v35
	v_sub_f32_e32 v36, v36, v0
	v_cndmask_b32_e32 v37, v38, v37, vcc
	v_and_b32_e32 v38, 0x7fffff00, v6
	v_bitop3_b32 v39, v6, s33, v6 bitop3:0xcf
	v_cmp_gt_i32_e32 vcc, 0, v6
	v_add_f32_e32 v29, v29, v31
	v_exp_f32_e32 v35, v35
	v_mul_f32_e32 v36, 0x3fb8aa3b, v36
	v_sub_f32_e32 v37, v37, v0
	v_cndmask_b32_e32 v38, v39, v38, vcc
	v_and_b32_e32 v39, 0x7fffff00, v18
	v_bitop3_b32 v40, v18, s33, v18 bitop3:0xcf
	v_cmp_gt_i32_e32 vcc, 0, v18
	v_add_f32_e32 v29, v29, v32
	v_exp_f32_e32 v36, v36
	v_mul_f32_e32 v37, 0x3fb8aa3b, v37
	v_sub_f32_e32 v38, v38, v0
	v_cndmask_b32_e32 v39, v40, v39, vcc
	v_and_b32_e32 v40, 0x7fffff00, v8
	v_bitop3_b32 v41, v8, s33, v8 bitop3:0xcf
	v_cmp_gt_i32_e32 vcc, 0, v8
	v_add_f32_e32 v29, v29, v33
	v_exp_f32_e32 v37, v37
	v_mul_f32_e32 v38, 0x3fb8aa3b, v38
	v_sub_f32_e32 v39, v39, v0
	v_cndmask_b32_e32 v40, v41, v40, vcc
	v_and_b32_e32 v41, 0x7fffff00, v10
	v_bitop3_b32 v42, v10, s33, v10 bitop3:0xcf
	v_cmp_gt_i32_e32 vcc, 0, v10
	v_add_f32_e32 v29, v29, v34
	v_exp_f32_e32 v38, v38
	v_mul_f32_e32 v39, 0x3fb8aa3b, v39
	v_sub_f32_e32 v40, v40, v0
	v_cndmask_b32_e32 v41, v42, v41, vcc
	v_add_f32_e32 v29, v29, v35
	v_exp_f32_e32 v39, v39
	v_mul_f32_e32 v40, 0x3fb8aa3b, v40
	v_sub_f32_e32 v0, v41, v0
	v_add_f32_e32 v29, v29, v36
	v_exp_f32_e32 v40, v40
	v_mul_f32_e32 v0, 0x3fb8aa3b, v0
	v_add_f32_e32 v29, v29, v37
	v_exp_f32_e32 v41, v0
	v_add_f32_e32 v0, v29, v38
	v_add_f32_e32 v0, v0, v39
	v_add_f32_e32 v0, v0, v40
	v_add_f32_e32 v0, v0, v41
	v_div_scale_f32 v29, s[0:1], v0, v0, 1.0
	v_rcp_f32_e32 v42, v29
	v_not_b32_e32 v21, v26
	v_not_b32_e32 v24, v25
	v_fma_f32 v43, -v29, v42, 1.0
	v_fmac_f32_e32 v42, v43, v42
	v_div_scale_f32 v43, vcc, 1.0, v0, 1.0
	v_mul_f32_e32 v44, v43, v42
	v_fma_f32 v45, -v29, v44, v43
	v_fmac_f32_e32 v44, v45, v42
	v_fma_f32 v29, -v29, v44, v43
	v_div_fmas_f32 v29, v29, v42, v44
	v_div_fixup_f32 v29, v29, v0, 1.0
	v_and_b32_e32 v0, 48, v19
	v_lshrrev_b32_e32 v19, 2, v21
	v_and_b32_e32 v19, 60, v19
	v_bitop3_b32 v21, v26, 15, v26 bitop3:0xc
	v_add_u32_e32 v19, v5, v19
	v_lshl_add_u32 v21, v21, 2, v5
	ds_read_b32 v19, v19
	ds_read_b32 v21, v21 offset:64
	v_lshlrev_b32_e32 v0, 3, v0
	v_add3_u32 v11, v13, v11, v0
	v_mul_f32_e32 v1, v1, v29
	v_not_b32_e32 v13, v2
	s_waitcnt lgkmcnt(0)
	v_lshl_add_u32 v0, v19, 7, v21
	ds_write_b64 v11, v[0:1]
	v_lshrrev_b32_e32 v0, 2, v24
	v_and_b32_e32 v0, 60, v0
	v_bitop3_b32 v1, v25, 15, v25 bitop3:0xc
	v_add_u32_e32 v0, v5, v0
	v_lshl_add_u32 v1, v1, 2, v5
	ds_read_b32 v0, v0
	ds_read_b32 v1, v1 offset:64
	v_cmp_eq_u32_e32 vcc, 0, v9
	s_waitcnt lgkmcnt(0)
	v_lshl_add_u32 v0, v0, 7, v1
	v_mul_f32_e32 v1, v16, v29
	ds_write_b64 v11, v[0:1] offset:8
	v_lshrrev_b32_e32 v0, 2, v13
	v_and_b32_e32 v0, 60, v0
	v_bitop3_b32 v1, v2, 15, v2 bitop3:0xc
	v_add_u32_e32 v0, v5, v0
	v_lshl_add_u32 v1, v1, 2, v5
	ds_read_b32 v0, v0
	ds_read_b32 v1, v1 offset:64
	v_not_b32_e32 v2, v4
	s_waitcnt lgkmcnt(0)
	v_lshl_add_u32 v0, v0, 7, v1
	v_mul_f32_e32 v1, v27, v29
	ds_write_b64 v11, v[0:1] offset:16
	v_lshrrev_b32_e32 v0, 2, v2
	v_and_b32_e32 v0, 60, v0
	v_bitop3_b32 v1, v4, 15, v4 bitop3:0xc
	v_add_u32_e32 v0, v5, v0
	v_lshl_add_u32 v1, v1, 2, v5
	ds_read_b32 v0, v0
	ds_read_b32 v1, v1 offset:64
	v_not_b32_e32 v2, v3
	v_mul_lo_u32 v4, v7, s36
	s_waitcnt lgkmcnt(0)
	v_lshl_add_u32 v0, v0, 7, v1
	v_mul_f32_e32 v1, v28, v29
	ds_write_b64 v11, v[0:1] offset:24
	v_lshrrev_b32_e32 v0, 2, v2
	v_and_b32_e32 v0, 60, v0
	v_bitop3_b32 v1, v3, 15, v3 bitop3:0xc
	v_add_u32_e32 v0, v5, v0
	v_lshl_add_u32 v1, v1, 2, v5
	ds_read_b32 v0, v0
	ds_read_b32 v1, v1 offset:64
	v_not_b32_e32 v2, v22
	s_waitcnt lgkmcnt(0)
	v_lshl_add_u32 v0, v0, 7, v1
	v_mul_f32_e32 v1, v30, v29
	ds_write_b64 v11, v[0:1] offset:32
	v_lshrrev_b32_e32 v0, 2, v2
	v_and_b32_e32 v0, 60, v0
	v_bitop3_b32 v1, v22, 15, v22 bitop3:0xc
	v_add_u32_e32 v0, v5, v0
	v_lshl_add_u32 v1, v1, 2, v5
	ds_read_b32 v0, v0
	ds_read_b32 v1, v1 offset:64
	v_not_b32_e32 v2, v15
	s_waitcnt lgkmcnt(0)
	v_lshl_add_u32 v0, v0, 7, v1
	v_mul_f32_e32 v1, v31, v29
	ds_write_b64 v11, v[0:1] offset:40
	v_lshrrev_b32_e32 v0, 2, v2
	v_and_b32_e32 v0, 60, v0
	v_bitop3_b32 v1, v15, 15, v15 bitop3:0xc
	v_add_u32_e32 v0, v5, v0
	v_lshl_add_u32 v1, v1, 2, v5
	ds_read_b32 v0, v0
	ds_read_b32 v1, v1 offset:64
	v_not_b32_e32 v2, v23
	s_waitcnt lgkmcnt(0)
	v_lshl_add_u32 v0, v0, 7, v1
	v_mul_f32_e32 v1, v32, v29
	ds_write_b64 v11, v[0:1] offset:48
	v_lshrrev_b32_e32 v0, 2, v2
	v_and_b32_e32 v0, 60, v0
	v_bitop3_b32 v1, v23, 15, v23 bitop3:0xc
	v_add_u32_e32 v0, v5, v0
	v_lshl_add_u32 v1, v1, 2, v5
	ds_read_b32 v0, v0
	ds_read_b32 v1, v1 offset:64
	v_not_b32_e32 v2, v12
	s_waitcnt lgkmcnt(0)
	v_lshl_add_u32 v0, v0, 7, v1
	v_mul_f32_e32 v1, v33, v29
	ds_write_b64 v11, v[0:1] offset:56
	v_lshrrev_b32_e32 v0, 2, v2
	v_and_b32_e32 v0, 60, v0
	v_bitop3_b32 v1, v12, 15, v12 bitop3:0xc
	v_add_u32_e32 v0, v5, v0
	v_lshl_add_u32 v1, v1, 2, v5
	ds_read_b32 v0, v0
	ds_read_b32 v1, v1 offset:64
	v_not_b32_e32 v2, v17
	s_waitcnt lgkmcnt(0)
	v_lshl_add_u32 v0, v0, 7, v1
	v_mul_f32_e32 v1, v34, v29
	ds_write_b64 v11, v[0:1] offset:64
	v_lshrrev_b32_e32 v0, 2, v2
	v_and_b32_e32 v0, 60, v0
	v_bitop3_b32 v1, v17, 15, v17 bitop3:0xc
	v_add_u32_e32 v0, v5, v0
	v_lshl_add_u32 v1, v1, 2, v5
	ds_read_b32 v0, v0
	ds_read_b32 v1, v1 offset:64
	v_not_b32_e32 v2, v14
	s_waitcnt lgkmcnt(0)
	v_lshl_add_u32 v0, v0, 7, v1
	v_mul_f32_e32 v1, v35, v29
	ds_write_b64 v11, v[0:1] offset:72
	v_lshrrev_b32_e32 v0, 2, v2
	v_and_b32_e32 v0, 60, v0
	v_bitop3_b32 v1, v14, 15, v14 bitop3:0xc
	v_add_u32_e32 v0, v5, v0
	v_lshl_add_u32 v1, v1, 2, v5
	ds_read_b32 v0, v0
	ds_read_b32 v1, v1 offset:64
	v_not_b32_e32 v2, v20
	s_waitcnt lgkmcnt(0)
; __device__ __forceinline__ void peer_tile(const Args& A, LAS unsigned char* lds, int tile) {
;     ...
;     __syncthreads();
;     const unsigned char* T8 = A.ws + WS_T8; const float* SC = (const float*)(A.ws + WS_SC);
;     LAS u32x2* SORT = (LAS u32x2*)(lds + PE_IDX);
;     LAS int* OFFS = (LAS int*)(lds + PE_SEL + 65536);
;     for (int ti = 0; ti < 8; ++ti) {
;         const int tl = 8 * w + ti;
;         const u32x2 e0 = SEL[tl * 128 + lane], e1 = SEL[tl * 128 + 64 + lane];
;         const int p0 = (int)(e0.x >> 10), p1 = (int)(e1.x >> 10);
;         int off = 0;
;         for (int p = 0; p < 16; ++p) {
;             const unsigned long long m0 = __ballot(p0 == p), m1 = __ballot(p1 == p);
;             const int c0 = __popcll(m0), c1 = __popcll(m1);
;             const int r0 = __builtin_amdgcn_mbcnt_hi((unsigned)(m0 >> 32), __builtin_amdgcn_mbcnt_lo((unsigned)m0, 0u));
;             const int r1 = __builtin_amdgcn_mbcnt_hi((unsigned)(m1 >> 32), __builtin_amdgcn_mbcnt_lo((unsigned)m1, 0u));
;             if (p0 == p) SORT[tl * 128 + off + r0] = e0;
;             if (p1 == p) SORT[tl * 128 + off + c0 + r1] = e1;
;             if (lane == 0) OFFS[tl * 17 + p] = off;
;             off += c0 + c1;
;         }
;         if (lane == 0) OFFS[tl * 17 + 16] = off;
;     }
;     LDS_WAIT(); __builtin_amdgcn_wave_barrier();
;     const unsigned char* T8v = T8 + (size_t)16384 * 1024;
;     const bf16_t* A3 = (const bf16_t*)(A.ws + WS_A3); const float* RSq = (const float*)(A.ws + WS_RS);
;     for (int pass = 0; pass < 2; ++pass) {
;         const int tb = 8 * w + 4 * pass;
;         u32x4 xpa[4], xpb[4]; f32x2 oacc[4][8];
; #pragma unroll
;         for (int tk = 0; tk < 4; ++tk) { const size_t m = (size_t)tile * 64 + tb + tk;
;             { const u32x4 ra = *(const u32x4*)(A3 + m * 1024 + 16 * lane), rb = *(const u32x4*)(A3 + m * 1024 + 16 * lane + 8);
;               float xr_; { const f32x4 p0 = *(const f32x4*)(RSq + m * 16), p1 = *(const f32x4*)(RSq + m * 16 + 4), p2 = *(const f32x4*)(RSq + m * 16 + 8), p3 = *(const f32x4*)(RSq + m * 16 + 12);
;                 const f32x4 ps = (p0 + p1) + (p2 + p3); xr_ = rsqrtf(((ps[0] + ps[1]) + (ps[2] + ps[3])) * (1.f / 1024.f) + 1e-6f); }
;               const unsigned rr[8] = {ra.x, ra.y, ra.z, ra.w, rb.x, rb.y, rb.z, rb.w}; unsigned hh[8];
;               const float* sp = MOD + (int)(m >> 11) * 6144 + 3072 + 16 * lane;
	v_lshl_add_u32 v0, v0, 7, v1
	v_mul_f32_e32 v1, v36, v29
	ds_write_b64 v11, v[0:1] offset:80
	v_lshrrev_b32_e32 v0, 2, v2
	v_and_b32_e32 v0, 60, v0
	v_bitop3_b32 v1, v20, 15, v20 bitop3:0xc
	v_add_u32_e32 v0, v5, v0
	v_lshl_add_u32 v1, v1, 2, v5
	ds_read_b32 v0, v0
	ds_read_b32 v1, v1 offset:64
	v_not_b32_e32 v2, v6
	s_waitcnt lgkmcnt(0)
	v_lshl_add_u32 v0, v0, 7, v1
	v_mul_f32_e32 v1, v37, v29
	ds_write_b64 v11, v[0:1] offset:88
	v_lshrrev_b32_e32 v0, 2, v2
	v_and_b32_e32 v0, 60, v0
	v_bitop3_b32 v1, v6, 15, v6 bitop3:0xc
	v_add_u32_e32 v0, v5, v0
	v_lshl_add_u32 v1, v1, 2, v5
	ds_read_b32 v0, v0
	ds_read_b32 v1, v1 offset:64
	v_not_b32_e32 v2, v18
	s_waitcnt lgkmcnt(0)
	v_lshl_add_u32 v0, v0, 7, v1
	v_mul_f32_e32 v1, v38, v29
	ds_write_b64 v11, v[0:1] offset:96
	v_lshrrev_b32_e32 v0, 2, v2
	v_and_b32_e32 v0, 60, v0
	v_bitop3_b32 v1, v18, 15, v18 bitop3:0xc
	v_add_u32_e32 v0, v5, v0
	v_lshl_add_u32 v1, v1, 2, v5
	ds_read_b32 v0, v0
	ds_read_b32 v1, v1 offset:64
	v_not_b32_e32 v2, v8
	s_waitcnt lgkmcnt(0)
	v_lshl_add_u32 v0, v0, 7, v1
	v_mul_f32_e32 v1, v39, v29
	ds_write_b64 v11, v[0:1] offset:104
	v_lshrrev_b32_e32 v0, 2, v2
	v_and_b32_e32 v0, 60, v0
	v_bitop3_b32 v1, v8, 15, v8 bitop3:0xc
	v_add_u32_e32 v0, v5, v0
	v_lshl_add_u32 v1, v1, 2, v5
	ds_read_b32 v0, v0
	ds_read_b32 v1, v1 offset:64
	v_not_b32_e32 v2, v10
	s_waitcnt lgkmcnt(0)
	v_lshl_add_u32 v0, v0, 7, v1
	v_mul_f32_e32 v1, v40, v29
	ds_write_b64 v11, v[0:1] offset:112
	v_lshrrev_b32_e32 v0, 2, v2
	v_and_b32_e32 v0, 60, v0
	v_bitop3_b32 v1, v10, 15, v10 bitop3:0xc
	v_add_u32_e32 v0, v5, v0
	v_lshl_add_u32 v1, v1, 2, v5
	ds_read_b32 v0, v0
	ds_read_b32 v1, v1 offset:64
	v_lshlrev_b32_e32 v5, 13, v7
	v_lshl_or_b32 v6, v9, 3, v5
	s_waitcnt lgkmcnt(0)
	v_lshl_add_u32 v0, v0, 7, v1
	v_mul_f32_e32 v1, v41, v29
	ds_write_b64 v11, v[0:1] offset:120
	s_waitcnt lgkmcnt(0)
	s_barrier
	s_mov_b64 exec, -1
	v_and_b32_e32 v240, 63, v214
	v_lshrrev_b32_e32 v242, 6, v214
	v_lshlrev_b32_e32 v240, 4, v240
	v_readfirstlane_b32 s16, v242
	v_lshlrev_b32_e32 v245, 1, v240
	v_lshlrev_b32_e32 v246, 2, v240
	v_lshrrev_b32_e32 v247, 4, v240
	v_and_b32_e32 v247, 48, v247
	v_mov_b32_e32 v244, 0
	v_mov_b32_e32 v243, 0x358637bd
	v_mov_b32_e32 v242, 0xbf3a00e3
	s_add_u32 s4, s50, 0x1000000
	s_addc_u32 s5, s51, 0
	s_add_u32 s6, s50, 0x2000000
	s_addc_u32 s7, s51, 0
	s_add_u32 s8, s50, 0x3000000
	s_addc_u32 s9, s51, 0
	s_add_u32 s52, s50, 0x3010000
	s_addc_u32 s53, s51, 0
	s_add_u32 s12, s50, 0xb000000
	s_addc_u32 s13, s51, 0
	s_add_u32 s14, s50, 0xd000000
	s_addc_u32 s15, s51, 0
	s_lshr_b32 s0, s2, 5
	s_mul_i32 s0, s0, 0x6000
	s_add_u32 s10, s50, s0
	s_addc_u32 s11, s51, 0
	s_add_u32 s80, s10, 0x4000
	s_addc_u32 s81, s11, 0
	s_add_u32 s82, s10, 0x6000
	s_addc_u32 s83, s11, 0
	s_mul_i32 s22, s16, 9920
	s_cmp_eq_u32 s16, 7
	s_cselect_b32 s22, 0x21000, s22
	s_mov_b32 s85, 0xffffffff
	s_mov_b32 s72, 0x3e6d3388
	s_mov_b32 s56, s4
	s_and_b32 s57, s5, 0xffff
	s_or_b32 s57, s57, 0x04000000
	s_mov_b32 s58, 16384
	s_mov_b32 s59, 0x00027000
	s_mov_b32 s60, s6
	s_and_b32 s61, s7, 0xffff
	s_or_b32 s61, s61, 0x04000000
	s_mov_b32 s62, 16384
	s_mov_b32 s63, 0x00027000
	s_lshl_b32 s76, s16, 3
	s_lshl_b32 s0, s2, 6
	s_add_i32 s77, s0, s76
	global_load_dwordx4 v[192:195], v246, s[80:81] offset:0
	global_load_dwordx4 v[196:199], v246, s[80:81] offset:16
	global_load_dwordx4 v[200:203], v246, s[80:81] offset:32
	global_load_dwordx4 v[204:207], v246, s[80:81] offset:48
	s_add_i32 s0, s77, 0
	s_lshl_b32 s1, s0, 11
	s_add_u32 s78, s12, s1
	s_addc_u32 s79, s13, 0
	global_load_dwordx4 v[128:131], v245, s[78:79]
	global_load_dwordx4 v[132:135], v245, s[78:79] offset:16
	global_load_dwordx4 v[136:139], v245, s[78:79] offset:2048
	global_load_dwordx4 v[140:143], v245, s[78:79] offset:2064
	s_lshl_b32 s1, s0, 6
	s_add_u32 s78, s14, s1
	s_addc_u32 s79, s15, 0
	global_load_dwordx4 v[144:147], v244, s[78:79] offset:0
	global_load_dwordx4 v[148:151], v244, s[78:79] offset:16
	global_load_dwordx4 v[152:155], v244, s[78:79] offset:32
	global_load_dwordx4 v[156:159], v244, s[78:79] offset:48
	global_load_dwordx4 v[160:163], v244, s[78:79] offset:64
	global_load_dwordx4 v[164:167], v244, s[78:79] offset:80
	global_load_dwordx4 v[168:171], v244, s[78:79] offset:96
	global_load_dwordx4 v[172:175], v244, s[78:79] offset:112
	s_add_i32 s0, s77, 2
	s_lshl_b32 s1, s0, 11
	s_add_u32 s78, s12, s1
	s_addc_u32 s79, s13, 0
	global_load_dwordx4 v[176:179], v245, s[78:79]
	global_load_dwordx4 v[180:183], v245, s[78:79] offset:16
	global_load_dwordx4 v[184:187], v245, s[78:79] offset:2048
	global_load_dwordx4 v[188:191], v245, s[78:79] offset:2064
	s_lshl_b32 s1, s0, 6
	s_add_u32 s78, s14, s1
	s_addc_u32 s79, s15, 0
	global_load_dwordx4 v[216:219], v244, s[78:79] offset:0
	global_load_dwordx4 v[220:223], v244, s[78:79] offset:16
	global_load_dwordx4 v[224:227], v244, s[78:79] offset:32
	global_load_dwordx4 v[228:231], v244, s[78:79] offset:48
	global_load_dwordx4 v[232:235], v244, s[78:79] offset:64
	global_load_dwordx4 v[236:239], v244, s[78:79] offset:80
	global_load_dwordx4 v[248:251], v244, s[78:79] offset:96
	global_load_dwordx4 v[252:255], v244, s[78:79] offset:112
	s_waitcnt vmcnt(12)
; __device__ __forceinline__ unsigned pk2(float lo, float hi) { const f32x2 v = {lo, hi}; const bf16x2_t b = __builtin_convertvector(v, bf16x2_t); return __builtin_bit_cast(unsigned, b); }
; __device__ __forceinline__ float bflo(unsigned u) { return __uint_as_float(u << 16); }
; __device__ __forceinline__ float bfhi(unsigned u) { return __uint_as_float(u & 0xffff0000u); }
; __device__ __forceinline__ void peer_tile(const Args& A, LAS unsigned char* lds, int tile) {
;     ...
;         for (int tk = 0; tk < 4; ++tk) { const size_t m = (size_t)tile * 64 + tb + tk;
;             { const u32x4 ra = *(const u32x4*)(A3 + m * 1024 + 16 * lane), rb = *(const u32x4*)(A3 + m * 1024 + 16 * lane + 8);
;               float xr_; { const f32x4 p0 = *(const f32x4*)(RSq + m * 16), p1 = *(const f32x4*)(RSq + m * 16 + 4), p2 = *(const f32x4*)(RSq + m * 16 + 8), p3 = *(const f32x4*)(RSq + m * 16 + 12);
;                 const f32x4 ps = (p0 + p1) + (p2 + p3); xr_ = rsqrtf(((ps[0] + ps[1]) + (ps[2] + ps[3])) * (1.f / 1024.f) + 1e-6f); }
;               const unsigned rr[8] = {ra.x, ra.y, ra.z, ra.w, rb.x, rb.y, rb.z, rb.w}; unsigned hh[8];
;               const float* sp = MOD + (int)(m >> 11) * 6144 + 3072 + 16 * lane;
; #pragma unroll
;               for (int q = 0; q < 8; ++q) { const f32x2 sh = *(const f32x2*)(sp + 2 * q); hh[q] = pk2(bflo(rr[q]) * xr_ + sh[0], bfhi(rr[q]) * xr_ + sh[1]); }
;               xpa[tk] = (u32x4){hh[0], hh[1], hh[2], hh[3]}; xpb[tk] = (u32x4){hh[4], hh[5], hh[6], hh[7]}; }
;     ...
;                 { const unsigned xx[8] = {xpa[tk].x, xpa[tk].y, xpa[tk].z, xpa[tk].w, xpb[tk].x, xpb[tk].y, xpb[tk].z, xpb[tk].w};
; #pragma unroll
;                   for (int q = 0; q < 8; ++q) xf[q] = (f32x2){bflo(xx[q]), bfhi(xx[q])}; }
	v_pk_add_f32 v[144:145], v[144:145], v[148:149]
	v_pk_add_f32 v[146:147], v[146:147], v[150:151]
	v_pk_add_f32 v[152:153], v[152:153], v[156:157]
	v_pk_add_f32 v[154:155], v[154:155], v[158:159]
	v_pk_add_f32 v[144:145], v[144:145], v[152:153]
	v_pk_add_f32 v[146:147], v[146:147], v[154:155]
	v_add_f32_e32 v144, v144, v145
	v_add_f32_e32 v146, v146, v147
	v_add_f32_e32 v144, v144, v146
	v_fmamk_f32 v144, v144, 0x3a800000, v243
	v_rsq_f32_e32 v144, v144
	v_pk_add_f32 v[160:161], v[160:161], v[164:165]
	v_pk_add_f32 v[162:163], v[162:163], v[166:167]
	v_pk_add_f32 v[168:169], v[168:169], v[172:173]
	v_pk_add_f32 v[170:171], v[170:171], v[174:175]
	v_pk_add_f32 v[160:161], v[160:161], v[168:169]
	v_pk_add_f32 v[162:163], v[162:163], v[170:171]
	v_add_f32_e32 v160, v160, v161
	v_add_f32_e32 v162, v162, v163
	v_add_f32_e32 v160, v160, v162
	v_fmamk_f32 v160, v160, 0x3a800000, v243
	v_rsq_f32_e32 v160, v160
	v_lshlrev_b32_e32 v208, 16, v128
	v_and_b32_e32 v209, 0xffff0000, v128
	v_fma_f32 v208, v208, v144, v192
	v_fma_f32 v209, v209, v144, v193
	v_cvt_pk_bf16_f32 v210, v208, v209
	v_lshlrev_b32_e32 v0, 16, v210
	v_and_b32_e32 v1, 0xffff0000, v210
	v_lshlrev_b32_e32 v208, 16, v129
	v_and_b32_e32 v209, 0xffff0000, v129
	v_fma_f32 v208, v208, v144, v194
	v_fma_f32 v209, v209, v144, v195
	v_cvt_pk_bf16_f32 v210, v208, v209
	v_lshlrev_b32_e32 v2, 16, v210
	v_and_b32_e32 v3, 0xffff0000, v210
	v_lshlrev_b32_e32 v208, 16, v130
	v_and_b32_e32 v209, 0xffff0000, v130
	v_fma_f32 v208, v208, v144, v196
	v_fma_f32 v209, v209, v144, v197
	v_cvt_pk_bf16_f32 v210, v208, v209
	v_lshlrev_b32_e32 v4, 16, v210
	v_and_b32_e32 v5, 0xffff0000, v210
	v_lshlrev_b32_e32 v208, 16, v131
	v_and_b32_e32 v209, 0xffff0000, v131
	v_fma_f32 v208, v208, v144, v198
	v_fma_f32 v209, v209, v144, v199
	v_cvt_pk_bf16_f32 v210, v208, v209
	v_lshlrev_b32_e32 v6, 16, v210
	v_and_b32_e32 v7, 0xffff0000, v210
	v_lshlrev_b32_e32 v208, 16, v132
	v_and_b32_e32 v209, 0xffff0000, v132
	v_fma_f32 v208, v208, v144, v200
	v_fma_f32 v209, v209, v144, v201
	v_cvt_pk_bf16_f32 v210, v208, v209
	v_lshlrev_b32_e32 v8, 16, v210
	v_and_b32_e32 v9, 0xffff0000, v210
	v_lshlrev_b32_e32 v208, 16, v133
	v_and_b32_e32 v209, 0xffff0000, v133
	v_fma_f32 v208, v208, v144, v202
	v_fma_f32 v209, v209, v144, v203
	v_cvt_pk_bf16_f32 v210, v208, v209
	v_lshlrev_b32_e32 v10, 16, v210
	v_and_b32_e32 v11, 0xffff0000, v210
	v_lshlrev_b32_e32 v208, 16, v134
	v_and_b32_e32 v209, 0xffff0000, v134
	v_fma_f32 v208, v208, v144, v204
	v_fma_f32 v209, v209, v144, v205
	v_cvt_pk_bf16_f32 v210, v208, v209
	v_lshlrev_b32_e32 v12, 16, v210
	v_and_b32_e32 v13, 0xffff0000, v210
	v_lshlrev_b32_e32 v208, 16, v135
	v_and_b32_e32 v209, 0xffff0000, v135
	v_fma_f32 v208, v208, v144, v206
	v_fma_f32 v209, v209, v144, v207
	v_cvt_pk_bf16_f32 v210, v208, v209
	v_lshlrev_b32_e32 v14, 16, v210
	v_and_b32_e32 v15, 0xffff0000, v210
	v_lshlrev_b32_e32 v208, 16, v136
	v_and_b32_e32 v209, 0xffff0000, v136
	v_fma_f32 v208, v208, v160, v192
	v_fma_f32 v209, v209, v160, v193
	v_cvt_pk_bf16_f32 v210, v208, v209
	v_lshlrev_b32_e32 v16, 16, v210
	v_and_b32_e32 v17, 0xffff0000, v210
	v_lshlrev_b32_e32 v208, 16, v137
	v_and_b32_e32 v209, 0xffff0000, v137
	v_fma_f32 v208, v208, v160, v194
	v_fma_f32 v209, v209, v160, v195
	v_cvt_pk_bf16_f32 v210, v208, v209
	v_lshlrev_b32_e32 v18, 16, v210
	v_and_b32_e32 v19, 0xffff0000, v210
	v_lshlrev_b32_e32 v208, 16, v138
	v_and_b32_e32 v209, 0xffff0000, v138
	v_fma_f32 v208, v208, v160, v196
	v_fma_f32 v209, v209, v160, v197
	v_cvt_pk_bf16_f32 v210, v208, v209
	v_lshlrev_b32_e32 v20, 16, v210
	v_and_b32_e32 v21, 0xffff0000, v210
	v_lshlrev_b32_e32 v208, 16, v139
	v_and_b32_e32 v209, 0xffff0000, v139
	v_fma_f32 v208, v208, v160, v198
	v_fma_f32 v209, v209, v160, v199
	v_cvt_pk_bf16_f32 v210, v208, v209
	v_lshlrev_b32_e32 v22, 16, v210
	v_and_b32_e32 v23, 0xffff0000, v210
	v_lshlrev_b32_e32 v208, 16, v140
	v_and_b32_e32 v209, 0xffff0000, v140
	v_fma_f32 v208, v208, v160, v200
	v_fma_f32 v209, v209, v160, v201
	v_cvt_pk_bf16_f32 v210, v208, v209
	v_lshlrev_b32_e32 v24, 16, v210
	v_and_b32_e32 v25, 0xffff0000, v210
	v_lshlrev_b32_e32 v208, 16, v141
	v_and_b32_e32 v209, 0xffff0000, v141
	v_fma_f32 v208, v208, v160, v202
	v_fma_f32 v209, v209, v160, v203
	v_cvt_pk_bf16_f32 v210, v208, v209
	v_lshlrev_b32_e32 v26, 16, v210
	v_and_b32_e32 v27, 0xffff0000, v210
	v_lshlrev_b32_e32 v208, 16, v142
	v_and_b32_e32 v209, 0xffff0000, v142
	v_fma_f32 v208, v208, v160, v204
	v_fma_f32 v209, v209, v160, v205
	v_cvt_pk_bf16_f32 v210, v208, v209
	v_lshlrev_b32_e32 v28, 16, v210
	v_and_b32_e32 v29, 0xffff0000, v210
	v_lshlrev_b32_e32 v208, 16, v143
	v_and_b32_e32 v209, 0xffff0000, v143
	v_fma_f32 v208, v208, v160, v206
	v_fma_f32 v209, v209, v160, v207
	v_cvt_pk_bf16_f32 v210, v208, v209
	v_lshlrev_b32_e32 v30, 16, v210
	v_and_b32_e32 v31, 0xffff0000, v210
	s_nop 0
	s_add_i32 s0, s77, 4
	s_lshl_b32 s1, s0, 11
	s_add_u32 s78, s12, s1
	s_addc_u32 s79, s13, 0
	global_load_dwordx4 v[128:131], v245, s[78:79]
	global_load_dwordx4 v[132:135], v245, s[78:79] offset:16
	global_load_dwordx4 v[136:139], v245, s[78:79] offset:2048
	global_load_dwordx4 v[140:143], v245, s[78:79] offset:2064
	s_lshl_b32 s1, s0, 6
	s_add_u32 s78, s14, s1
	s_addc_u32 s79, s15, 0
	global_load_dwordx4 v[144:147], v244, s[78:79] offset:0
	global_load_dwordx4 v[148:151], v244, s[78:79] offset:16
	global_load_dwordx4 v[152:155], v244, s[78:79] offset:32
	global_load_dwordx4 v[156:159], v244, s[78:79] offset:48
	global_load_dwordx4 v[160:163], v244, s[78:79] offset:64
	global_load_dwordx4 v[164:167], v244, s[78:79] offset:80
	global_load_dwordx4 v[168:171], v244, s[78:79] offset:96
	global_load_dwordx4 v[172:175], v244, s[78:79] offset:112
	s_waitcnt vmcnt(12)
; __device__ __forceinline__ unsigned pk2(float lo, float hi) { const f32x2 v = {lo, hi}; const bf16x2_t b = __builtin_convertvector(v, bf16x2_t); return __builtin_bit_cast(unsigned, b); }
; __device__ __forceinline__ float bflo(unsigned u) { return __uint_as_float(u << 16); }
; __device__ __forceinline__ float bfhi(unsigned u) { return __uint_as_float(u & 0xffff0000u); }
; __device__ __forceinline__ void peer_tile(const Args& A, LAS unsigned char* lds, int tile) {
;     ...
;         for (int tk = 0; tk < 4; ++tk) { const size_t m = (size_t)tile * 64 + tb + tk;
;             { const u32x4 ra = *(const u32x4*)(A3 + m * 1024 + 16 * lane), rb = *(const u32x4*)(A3 + m * 1024 + 16 * lane + 8);
;               float xr_; { const f32x4 p0 = *(const f32x4*)(RSq + m * 16), p1 = *(const f32x4*)(RSq + m * 16 + 4), p2 = *(const f32x4*)(RSq + m * 16 + 8), p3 = *(const f32x4*)(RSq + m * 16 + 12);
;                 const f32x4 ps = (p0 + p1) + (p2 + p3); xr_ = rsqrtf(((ps[0] + ps[1]) + (ps[2] + ps[3])) * (1.f / 1024.f) + 1e-6f); }
;               const unsigned rr[8] = {ra.x, ra.y, ra.z, ra.w, rb.x, rb.y, rb.z, rb.w}; unsigned hh[8];
;               const float* sp = MOD + (int)(m >> 11) * 6144 + 3072 + 16 * lane;
; #pragma unroll
;               for (int q = 0; q < 8; ++q) { const f32x2 sh = *(const f32x2*)(sp + 2 * q); hh[q] = pk2(bflo(rr[q]) * xr_ + sh[0], bfhi(rr[q]) * xr_ + sh[1]); }
;               xpa[tk] = (u32x4){hh[0], hh[1], hh[2], hh[3]}; xpb[tk] = (u32x4){hh[4], hh[5], hh[6], hh[7]}; }
;     ...
;                 { const unsigned xx[8] = {xpa[tk].x, xpa[tk].y, xpa[tk].z, xpa[tk].w, xpb[tk].x, xpb[tk].y, xpb[tk].z, xpb[tk].w};
; #pragma unroll
;                   for (int q = 0; q < 8; ++q) xf[q] = (f32x2){bflo(xx[q]), bfhi(xx[q])}; }
	v_pk_add_f32 v[216:217], v[216:217], v[220:221]
	v_pk_add_f32 v[218:219], v[218:219], v[222:223]
	v_pk_add_f32 v[224:225], v[224:225], v[228:229]
	v_pk_add_f32 v[226:227], v[226:227], v[230:231]
	v_pk_add_f32 v[216:217], v[216:217], v[224:225]
	v_pk_add_f32 v[218:219], v[218:219], v[226:227]
	v_add_f32_e32 v216, v216, v217
	v_add_f32_e32 v218, v218, v219
	v_add_f32_e32 v216, v216, v218
	v_fmamk_f32 v216, v216, 0x3a800000, v243
	v_rsq_f32_e32 v216, v216
	v_pk_add_f32 v[232:233], v[232:233], v[236:237]
	v_pk_add_f32 v[234:235], v[234:235], v[238:239]
	v_pk_add_f32 v[248:249], v[248:249], v[252:253]
	v_pk_add_f32 v[250:251], v[250:251], v[254:255]
	v_pk_add_f32 v[232:233], v[232:233], v[248:249]
	v_pk_add_f32 v[234:235], v[234:235], v[250:251]
	v_add_f32_e32 v232, v232, v233
	v_add_f32_e32 v234, v234, v235
	v_add_f32_e32 v232, v232, v234
	v_fmamk_f32 v232, v232, 0x3a800000, v243
	v_rsq_f32_e32 v232, v232
	v_lshlrev_b32_e32 v208, 16, v176
	v_and_b32_e32 v209, 0xffff0000, v176
	v_fma_f32 v208, v208, v216, v192
	v_fma_f32 v209, v209, v216, v193
	v_cvt_pk_bf16_f32 v210, v208, v209
	v_lshlrev_b32_e32 v32, 16, v210
	v_and_b32_e32 v33, 0xffff0000, v210
	v_lshlrev_b32_e32 v208, 16, v177
	v_and_b32_e32 v209, 0xffff0000, v177
	v_fma_f32 v208, v208, v216, v194
	v_fma_f32 v209, v209, v216, v195
	v_cvt_pk_bf16_f32 v210, v208, v209
	v_lshlrev_b32_e32 v34, 16, v210
	v_and_b32_e32 v35, 0xffff0000, v210
	v_lshlrev_b32_e32 v208, 16, v178
	v_and_b32_e32 v209, 0xffff0000, v178
	v_fma_f32 v208, v208, v216, v196
	v_fma_f32 v209, v209, v216, v197
	v_cvt_pk_bf16_f32 v210, v208, v209
	v_lshlrev_b32_e32 v36, 16, v210
	v_and_b32_e32 v37, 0xffff0000, v210
	v_lshlrev_b32_e32 v208, 16, v179
	v_and_b32_e32 v209, 0xffff0000, v179
	v_fma_f32 v208, v208, v216, v198
	v_fma_f32 v209, v209, v216, v199
	v_cvt_pk_bf16_f32 v210, v208, v209
	v_lshlrev_b32_e32 v38, 16, v210
	v_and_b32_e32 v39, 0xffff0000, v210
	v_lshlrev_b32_e32 v208, 16, v180
	v_and_b32_e32 v209, 0xffff0000, v180
	v_fma_f32 v208, v208, v216, v200
	v_fma_f32 v209, v209, v216, v201
	v_cvt_pk_bf16_f32 v210, v208, v209
	v_lshlrev_b32_e32 v40, 16, v210
	v_and_b32_e32 v41, 0xffff0000, v210
	v_lshlrev_b32_e32 v208, 16, v181
	v_and_b32_e32 v209, 0xffff0000, v181
	v_fma_f32 v208, v208, v216, v202
	v_fma_f32 v209, v209, v216, v203
	v_cvt_pk_bf16_f32 v210, v208, v209
	v_lshlrev_b32_e32 v42, 16, v210
	v_and_b32_e32 v43, 0xffff0000, v210
	v_lshlrev_b32_e32 v208, 16, v182
	v_and_b32_e32 v209, 0xffff0000, v182
	v_fma_f32 v208, v208, v216, v204
	v_fma_f32 v209, v209, v216, v205
	v_cvt_pk_bf16_f32 v210, v208, v209
	v_lshlrev_b32_e32 v44, 16, v210
	v_and_b32_e32 v45, 0xffff0000, v210
	v_lshlrev_b32_e32 v208, 16, v183
	v_and_b32_e32 v209, 0xffff0000, v183
	v_fma_f32 v208, v208, v216, v206
	v_fma_f32 v209, v209, v216, v207
	v_cvt_pk_bf16_f32 v210, v208, v209
	v_lshlrev_b32_e32 v46, 16, v210
	v_and_b32_e32 v47, 0xffff0000, v210
	v_lshlrev_b32_e32 v208, 16, v184
	v_and_b32_e32 v209, 0xffff0000, v184
	v_fma_f32 v208, v208, v232, v192
	v_fma_f32 v209, v209, v232, v193
	v_cvt_pk_bf16_f32 v210, v208, v209
	v_lshlrev_b32_e32 v48, 16, v210
	v_and_b32_e32 v49, 0xffff0000, v210
	v_lshlrev_b32_e32 v208, 16, v185
	v_and_b32_e32 v209, 0xffff0000, v185
	v_fma_f32 v208, v208, v232, v194
	v_fma_f32 v209, v209, v232, v195
	v_cvt_pk_bf16_f32 v210, v208, v209
	v_lshlrev_b32_e32 v50, 16, v210
	v_and_b32_e32 v51, 0xffff0000, v210
	v_lshlrev_b32_e32 v208, 16, v186
	v_and_b32_e32 v209, 0xffff0000, v186
	v_fma_f32 v208, v208, v232, v196
	v_fma_f32 v209, v209, v232, v197
	v_cvt_pk_bf16_f32 v210, v208, v209
	v_lshlrev_b32_e32 v52, 16, v210
	v_and_b32_e32 v53, 0xffff0000, v210
	v_lshlrev_b32_e32 v208, 16, v187
	v_and_b32_e32 v209, 0xffff0000, v187
	v_fma_f32 v208, v208, v232, v198
	v_fma_f32 v209, v209, v232, v199
	v_cvt_pk_bf16_f32 v210, v208, v209
	v_lshlrev_b32_e32 v54, 16, v210
	v_and_b32_e32 v55, 0xffff0000, v210
	v_lshlrev_b32_e32 v208, 16, v188
	v_and_b32_e32 v209, 0xffff0000, v188
	v_fma_f32 v208, v208, v232, v200
	v_fma_f32 v209, v209, v232, v201
	v_cvt_pk_bf16_f32 v210, v208, v209
	v_lshlrev_b32_e32 v56, 16, v210
	v_and_b32_e32 v57, 0xffff0000, v210
	v_lshlrev_b32_e32 v208, 16, v189
	v_and_b32_e32 v209, 0xffff0000, v189
	v_fma_f32 v208, v208, v232, v202
	v_fma_f32 v209, v209, v232, v203
	v_cvt_pk_bf16_f32 v210, v208, v209
	v_lshlrev_b32_e32 v58, 16, v210
	v_and_b32_e32 v59, 0xffff0000, v210
	v_lshlrev_b32_e32 v208, 16, v190
	v_and_b32_e32 v209, 0xffff0000, v190
	v_fma_f32 v208, v208, v232, v204
	v_fma_f32 v209, v209, v232, v205
	v_cvt_pk_bf16_f32 v210, v208, v209
	v_lshlrev_b32_e32 v60, 16, v210
	v_and_b32_e32 v61, 0xffff0000, v210
	v_lshlrev_b32_e32 v208, 16, v191
	v_and_b32_e32 v209, 0xffff0000, v191
	v_fma_f32 v208, v208, v232, v206
	v_fma_f32 v209, v209, v232, v207
	v_cvt_pk_bf16_f32 v210, v208, v209
	v_lshlrev_b32_e32 v62, 16, v210
	v_and_b32_e32 v63, 0xffff0000, v210
	s_nop 0
	s_add_i32 s0, s77, 6
	s_lshl_b32 s1, s0, 11
	s_add_u32 s78, s12, s1
	s_addc_u32 s79, s13, 0
	global_load_dwordx4 v[176:179], v245, s[78:79]
	global_load_dwordx4 v[180:183], v245, s[78:79] offset:16
	global_load_dwordx4 v[184:187], v245, s[78:79] offset:2048
	global_load_dwordx4 v[188:191], v245, s[78:79] offset:2064
	s_lshl_b32 s1, s0, 6
	s_add_u32 s78, s14, s1
	s_addc_u32 s79, s15, 0
	global_load_dwordx4 v[216:219], v244, s[78:79] offset:0
	global_load_dwordx4 v[220:223], v244, s[78:79] offset:16
	global_load_dwordx4 v[224:227], v244, s[78:79] offset:32
	global_load_dwordx4 v[228:231], v244, s[78:79] offset:48
	global_load_dwordx4 v[232:235], v244, s[78:79] offset:64
	global_load_dwordx4 v[236:239], v244, s[78:79] offset:80
	global_load_dwordx4 v[248:251], v244, s[78:79] offset:96
	global_load_dwordx4 v[252:255], v244, s[78:79] offset:112
	s_waitcnt vmcnt(12)
; __device__ __forceinline__ unsigned pk2(float lo, float hi) { const f32x2 v = {lo, hi}; const bf16x2_t b = __builtin_convertvector(v, bf16x2_t); return __builtin_bit_cast(unsigned, b); }
; __device__ __forceinline__ float bflo(unsigned u) { return __uint_as_float(u << 16); }
; __device__ __forceinline__ float bfhi(unsigned u) { return __uint_as_float(u & 0xffff0000u); }
; __device__ __forceinline__ void peer_tile(const Args& A, LAS unsigned char* lds, int tile) {
;     ...
;         for (int tk = 0; tk < 4; ++tk) { const size_t m = (size_t)tile * 64 + tb + tk;
;             { const u32x4 ra = *(const u32x4*)(A3 + m * 1024 + 16 * lane), rb = *(const u32x4*)(A3 + m * 1024 + 16 * lane + 8);
;               float xr_; { const f32x4 p0 = *(const f32x4*)(RSq + m * 16), p1 = *(const f32x4*)(RSq + m * 16 + 4), p2 = *(const f32x4*)(RSq + m * 16 + 8), p3 = *(const f32x4*)(RSq + m * 16 + 12);
;                 const f32x4 ps = (p0 + p1) + (p2 + p3); xr_ = rsqrtf(((ps[0] + ps[1]) + (ps[2] + ps[3])) * (1.f / 1024.f) + 1e-6f); }
;               const unsigned rr[8] = {ra.x, ra.y, ra.z, ra.w, rb.x, rb.y, rb.z, rb.w}; unsigned hh[8];
;               const float* sp = MOD + (int)(m >> 11) * 6144 + 3072 + 16 * lane;
; #pragma unroll
;               for (int q = 0; q < 8; ++q) { const f32x2 sh = *(const f32x2*)(sp + 2 * q); hh[q] = pk2(bflo(rr[q]) * xr_ + sh[0], bfhi(rr[q]) * xr_ + sh[1]); }
;               xpa[tk] = (u32x4){hh[0], hh[1], hh[2], hh[3]}; xpb[tk] = (u32x4){hh[4], hh[5], hh[6], hh[7]}; }
;     ...
;                 { const unsigned xx[8] = {xpa[tk].x, xpa[tk].y, xpa[tk].z, xpa[tk].w, xpb[tk].x, xpb[tk].y, xpb[tk].z, xpb[tk].w};
; #pragma unroll
;                   for (int q = 0; q < 8; ++q) xf[q] = (f32x2){bflo(xx[q]), bfhi(xx[q])}; }
	v_pk_add_f32 v[144:145], v[144:145], v[148:149]
	v_pk_add_f32 v[146:147], v[146:147], v[150:151]
	v_pk_add_f32 v[152:153], v[152:153], v[156:157]
	v_pk_add_f32 v[154:155], v[154:155], v[158:159]
	v_pk_add_f32 v[144:145], v[144:145], v[152:153]
	v_pk_add_f32 v[146:147], v[146:147], v[154:155]
	v_add_f32_e32 v144, v144, v145
	v_add_f32_e32 v146, v146, v147
	v_add_f32_e32 v144, v144, v146
	v_fmamk_f32 v144, v144, 0x3a800000, v243
	v_rsq_f32_e32 v144, v144
	v_pk_add_f32 v[160:161], v[160:161], v[164:165]
	v_pk_add_f32 v[162:163], v[162:163], v[166:167]
	v_pk_add_f32 v[168:169], v[168:169], v[172:173]
	v_pk_add_f32 v[170:171], v[170:171], v[174:175]
	v_pk_add_f32 v[160:161], v[160:161], v[168:169]
	v_pk_add_f32 v[162:163], v[162:163], v[170:171]
	v_add_f32_e32 v160, v160, v161
	v_add_f32_e32 v162, v162, v163
	v_add_f32_e32 v160, v160, v162
	v_fmamk_f32 v160, v160, 0x3a800000, v243
	v_rsq_f32_e32 v160, v160
	v_lshlrev_b32_e32 v208, 16, v128
	v_and_b32_e32 v209, 0xffff0000, v128
	v_fma_f32 v208, v208, v144, v192
	v_fma_f32 v209, v209, v144, v193
	v_cvt_pk_bf16_f32 v210, v208, v209
	v_lshlrev_b32_e32 v64, 16, v210
	v_and_b32_e32 v65, 0xffff0000, v210
	v_lshlrev_b32_e32 v208, 16, v129
	v_and_b32_e32 v209, 0xffff0000, v129
	v_fma_f32 v208, v208, v144, v194
	v_fma_f32 v209, v209, v144, v195
	v_cvt_pk_bf16_f32 v210, v208, v209
	v_lshlrev_b32_e32 v66, 16, v210
	v_and_b32_e32 v67, 0xffff0000, v210
	v_lshlrev_b32_e32 v208, 16, v130
	v_and_b32_e32 v209, 0xffff0000, v130
	v_fma_f32 v208, v208, v144, v196
	v_fma_f32 v209, v209, v144, v197
	v_cvt_pk_bf16_f32 v210, v208, v209
	v_lshlrev_b32_e32 v68, 16, v210
	v_and_b32_e32 v69, 0xffff0000, v210
	v_lshlrev_b32_e32 v208, 16, v131
	v_and_b32_e32 v209, 0xffff0000, v131
	v_fma_f32 v208, v208, v144, v198
	v_fma_f32 v209, v209, v144, v199
	v_cvt_pk_bf16_f32 v210, v208, v209
	v_lshlrev_b32_e32 v70, 16, v210
	v_and_b32_e32 v71, 0xffff0000, v210
	v_lshlrev_b32_e32 v208, 16, v132
	v_and_b32_e32 v209, 0xffff0000, v132
	v_fma_f32 v208, v208, v144, v200
	v_fma_f32 v209, v209, v144, v201
	v_cvt_pk_bf16_f32 v210, v208, v209
	v_lshlrev_b32_e32 v72, 16, v210
	v_and_b32_e32 v73, 0xffff0000, v210
	v_lshlrev_b32_e32 v208, 16, v133
	v_and_b32_e32 v209, 0xffff0000, v133
	v_fma_f32 v208, v208, v144, v202
	v_fma_f32 v209, v209, v144, v203
	v_cvt_pk_bf16_f32 v210, v208, v209
	v_lshlrev_b32_e32 v74, 16, v210
	v_and_b32_e32 v75, 0xffff0000, v210
	v_lshlrev_b32_e32 v208, 16, v134
	v_and_b32_e32 v209, 0xffff0000, v134
	v_fma_f32 v208, v208, v144, v204
	v_fma_f32 v209, v209, v144, v205
	v_cvt_pk_bf16_f32 v210, v208, v209
	v_lshlrev_b32_e32 v76, 16, v210
	v_and_b32_e32 v77, 0xffff0000, v210
	v_lshlrev_b32_e32 v208, 16, v135
	v_and_b32_e32 v209, 0xffff0000, v135
	v_fma_f32 v208, v208, v144, v206
	v_fma_f32 v209, v209, v144, v207
	v_cvt_pk_bf16_f32 v210, v208, v209
	v_lshlrev_b32_e32 v78, 16, v210
	v_and_b32_e32 v79, 0xffff0000, v210
	v_lshlrev_b32_e32 v208, 16, v136
	v_and_b32_e32 v209, 0xffff0000, v136
	v_fma_f32 v208, v208, v160, v192
	v_fma_f32 v209, v209, v160, v193
	v_cvt_pk_bf16_f32 v210, v208, v209
	v_lshlrev_b32_e32 v80, 16, v210
	v_and_b32_e32 v81, 0xffff0000, v210
	v_lshlrev_b32_e32 v208, 16, v137
	v_and_b32_e32 v209, 0xffff0000, v137
	v_fma_f32 v208, v208, v160, v194
	v_fma_f32 v209, v209, v160, v195
	v_cvt_pk_bf16_f32 v210, v208, v209
	v_lshlrev_b32_e32 v82, 16, v210
	v_and_b32_e32 v83, 0xffff0000, v210
	v_lshlrev_b32_e32 v208, 16, v138
	v_and_b32_e32 v209, 0xffff0000, v138
	v_fma_f32 v208, v208, v160, v196
	v_fma_f32 v209, v209, v160, v197
	v_cvt_pk_bf16_f32 v210, v208, v209
	v_lshlrev_b32_e32 v84, 16, v210
	v_and_b32_e32 v85, 0xffff0000, v210
	v_lshlrev_b32_e32 v208, 16, v139
	v_and_b32_e32 v209, 0xffff0000, v139
	v_fma_f32 v208, v208, v160, v198
	v_fma_f32 v209, v209, v160, v199
	v_cvt_pk_bf16_f32 v210, v208, v209
	v_lshlrev_b32_e32 v86, 16, v210
	v_and_b32_e32 v87, 0xffff0000, v210
	v_lshlrev_b32_e32 v208, 16, v140
	v_and_b32_e32 v209, 0xffff0000, v140
	v_fma_f32 v208, v208, v160, v200
	v_fma_f32 v209, v209, v160, v201
	v_cvt_pk_bf16_f32 v210, v208, v209
	v_lshlrev_b32_e32 v88, 16, v210
	v_and_b32_e32 v89, 0xffff0000, v210
	v_lshlrev_b32_e32 v208, 16, v141
	v_and_b32_e32 v209, 0xffff0000, v141
	v_fma_f32 v208, v208, v160, v202
	v_fma_f32 v209, v209, v160, v203
	v_cvt_pk_bf16_f32 v210, v208, v209
	v_lshlrev_b32_e32 v90, 16, v210
	v_and_b32_e32 v91, 0xffff0000, v210
	v_lshlrev_b32_e32 v208, 16, v142
	v_and_b32_e32 v209, 0xffff0000, v142
	v_fma_f32 v208, v208, v160, v204
	v_fma_f32 v209, v209, v160, v205
	v_cvt_pk_bf16_f32 v210, v208, v209
	v_lshlrev_b32_e32 v92, 16, v210
	v_and_b32_e32 v93, 0xffff0000, v210
	v_lshlrev_b32_e32 v208, 16, v143
	v_and_b32_e32 v209, 0xffff0000, v143
	v_fma_f32 v208, v208, v160, v206
	v_fma_f32 v209, v209, v160, v207
	v_cvt_pk_bf16_f32 v210, v208, v209
	v_lshlrev_b32_e32 v94, 16, v210
	v_and_b32_e32 v95, 0xffff0000, v210
	s_nop 0
	s_waitcnt vmcnt(0)
; __device__ __forceinline__ unsigned pk2(float lo, float hi) { const f32x2 v = {lo, hi}; const bf16x2_t b = __builtin_convertvector(v, bf16x2_t); return __builtin_bit_cast(unsigned, b); }
; __device__ __forceinline__ float bflo(unsigned u) { return __uint_as_float(u << 16); }
; __device__ __forceinline__ float bfhi(unsigned u) { return __uint_as_float(u & 0xffff0000u); }
; __device__ __forceinline__ void peer_tile(const Args& A, LAS unsigned char* lds, int tile) {
;     ...
;     for (int ti = 0; ti < 8; ++ti) {
;         const int tl = 8 * w + ti;
;         const u32x2 e0 = SEL[tl * 128 + lane], e1 = SEL[tl * 128 + 64 + lane];
;         const int p0 = (int)(e0.x >> 10), p1 = (int)(e1.x >> 10);
;     ...
;         for (int tk = 0; tk < 4; ++tk) { const size_t m = (size_t)tile * 64 + tb + tk;
;             { const u32x4 ra = *(const u32x4*)(A3 + m * 1024 + 16 * lane), rb = *(const u32x4*)(A3 + m * 1024 + 16 * lane + 8);
;               float xr_; { const f32x4 p0 = *(const f32x4*)(RSq + m * 16), p1 = *(const f32x4*)(RSq + m * 16 + 4), p2 = *(const f32x4*)(RSq + m * 16 + 8), p3 = *(const f32x4*)(RSq + m * 16 + 12);
;                 const f32x4 ps = (p0 + p1) + (p2 + p3); xr_ = rsqrtf(((ps[0] + ps[1]) + (ps[2] + ps[3])) * (1.f / 1024.f) + 1e-6f); }
;               const unsigned rr[8] = {ra.x, ra.y, ra.z, ra.w, rb.x, rb.y, rb.z, rb.w}; unsigned hh[8];
;               const float* sp = MOD + (int)(m >> 11) * 6144 + 3072 + 16 * lane;
; #pragma unroll
;               for (int q = 0; q < 8; ++q) { const f32x2 sh = *(const f32x2*)(sp + 2 * q); hh[q] = pk2(bflo(rr[q]) * xr_ + sh[0], bfhi(rr[q]) * xr_ + sh[1]); }
;               xpa[tk] = (u32x4){hh[0], hh[1], hh[2], hh[3]}; xpb[tk] = (u32x4){hh[4], hh[5], hh[6], hh[7]}; }
; #pragma unroll
;             for (int q = 0; q < 8; ++q) oacc[tk][q] = (f32x2){0.f, 0.f}; }
	v_pk_add_f32 v[216:217], v[216:217], v[220:221]
	v_pk_add_f32 v[218:219], v[218:219], v[222:223]
	v_pk_add_f32 v[224:225], v[224:225], v[228:229]
	v_pk_add_f32 v[226:227], v[226:227], v[230:231]
	v_pk_add_f32 v[216:217], v[216:217], v[224:225]
	v_pk_add_f32 v[218:219], v[218:219], v[226:227]
	v_add_f32_e32 v216, v216, v217
	v_add_f32_e32 v218, v218, v219
	v_add_f32_e32 v216, v216, v218
	v_fmamk_f32 v216, v216, 0x3a800000, v243
	v_rsq_f32_e32 v216, v216
	v_pk_add_f32 v[232:233], v[232:233], v[236:237]
	v_pk_add_f32 v[234:235], v[234:235], v[238:239]
	v_pk_add_f32 v[248:249], v[248:249], v[252:253]
	v_pk_add_f32 v[250:251], v[250:251], v[254:255]
	v_pk_add_f32 v[232:233], v[232:233], v[248:249]
	v_pk_add_f32 v[234:235], v[234:235], v[250:251]
	v_add_f32_e32 v232, v232, v233
	v_add_f32_e32 v234, v234, v235
	v_add_f32_e32 v232, v232, v234
	v_fmamk_f32 v232, v232, 0x3a800000, v243
	v_rsq_f32_e32 v232, v232
	v_lshlrev_b32_e32 v208, 16, v176
	v_and_b32_e32 v209, 0xffff0000, v176
	v_fma_f32 v208, v208, v216, v192
	v_fma_f32 v209, v209, v216, v193
	v_cvt_pk_bf16_f32 v210, v208, v209
	v_lshlrev_b32_e32 v96, 16, v210
	v_and_b32_e32 v97, 0xffff0000, v210
	v_lshlrev_b32_e32 v208, 16, v177
	v_and_b32_e32 v209, 0xffff0000, v177
	v_fma_f32 v208, v208, v216, v194
	v_fma_f32 v209, v209, v216, v195
	v_cvt_pk_bf16_f32 v210, v208, v209
	v_lshlrev_b32_e32 v98, 16, v210
	v_and_b32_e32 v99, 0xffff0000, v210
	v_lshlrev_b32_e32 v208, 16, v178
	v_and_b32_e32 v209, 0xffff0000, v178
	v_fma_f32 v208, v208, v216, v196
	v_fma_f32 v209, v209, v216, v197
	v_cvt_pk_bf16_f32 v210, v208, v209
	v_lshlrev_b32_e32 v100, 16, v210
	v_and_b32_e32 v101, 0xffff0000, v210
	v_lshlrev_b32_e32 v208, 16, v179
	v_and_b32_e32 v209, 0xffff0000, v179
	v_fma_f32 v208, v208, v216, v198
	v_fma_f32 v209, v209, v216, v199
	v_cvt_pk_bf16_f32 v210, v208, v209
	v_lshlrev_b32_e32 v102, 16, v210
	v_and_b32_e32 v103, 0xffff0000, v210
	v_lshlrev_b32_e32 v208, 16, v180
	v_and_b32_e32 v209, 0xffff0000, v180
	v_fma_f32 v208, v208, v216, v200
	v_fma_f32 v209, v209, v216, v201
	v_cvt_pk_bf16_f32 v210, v208, v209
	v_lshlrev_b32_e32 v104, 16, v210
	v_and_b32_e32 v105, 0xffff0000, v210
	v_lshlrev_b32_e32 v208, 16, v181
	v_and_b32_e32 v209, 0xffff0000, v181
	v_fma_f32 v208, v208, v216, v202
	v_fma_f32 v209, v209, v216, v203
	v_cvt_pk_bf16_f32 v210, v208, v209
	v_lshlrev_b32_e32 v106, 16, v210
	v_and_b32_e32 v107, 0xffff0000, v210
	v_lshlrev_b32_e32 v208, 16, v182
	v_and_b32_e32 v209, 0xffff0000, v182
	v_fma_f32 v208, v208, v216, v204
	v_fma_f32 v209, v209, v216, v205
	v_cvt_pk_bf16_f32 v210, v208, v209
	v_lshlrev_b32_e32 v108, 16, v210
	v_and_b32_e32 v109, 0xffff0000, v210
	v_lshlrev_b32_e32 v208, 16, v183
	v_and_b32_e32 v209, 0xffff0000, v183
	v_fma_f32 v208, v208, v216, v206
	v_fma_f32 v209, v209, v216, v207
	v_cvt_pk_bf16_f32 v210, v208, v209
	v_lshlrev_b32_e32 v110, 16, v210
	v_and_b32_e32 v111, 0xffff0000, v210
	v_lshlrev_b32_e32 v208, 16, v184
	v_and_b32_e32 v209, 0xffff0000, v184
	v_fma_f32 v208, v208, v232, v192
	v_fma_f32 v209, v209, v232, v193
	v_cvt_pk_bf16_f32 v210, v208, v209
	v_lshlrev_b32_e32 v112, 16, v210
	v_and_b32_e32 v113, 0xffff0000, v210
	v_lshlrev_b32_e32 v208, 16, v185
	v_and_b32_e32 v209, 0xffff0000, v185
	v_fma_f32 v208, v208, v232, v194
	v_fma_f32 v209, v209, v232, v195
	v_cvt_pk_bf16_f32 v210, v208, v209
	v_lshlrev_b32_e32 v114, 16, v210
	v_and_b32_e32 v115, 0xffff0000, v210
	v_lshlrev_b32_e32 v208, 16, v186
	v_and_b32_e32 v209, 0xffff0000, v186
	v_fma_f32 v208, v208, v232, v196
	v_fma_f32 v209, v209, v232, v197
	v_cvt_pk_bf16_f32 v210, v208, v209
	v_lshlrev_b32_e32 v116, 16, v210
	v_and_b32_e32 v117, 0xffff0000, v210
	v_lshlrev_b32_e32 v208, 16, v187
	v_and_b32_e32 v209, 0xffff0000, v187
	v_fma_f32 v208, v208, v232, v198
	v_fma_f32 v209, v209, v232, v199
	v_cvt_pk_bf16_f32 v210, v208, v209
	v_lshlrev_b32_e32 v118, 16, v210
	v_and_b32_e32 v119, 0xffff0000, v210
	v_lshlrev_b32_e32 v208, 16, v188
	v_and_b32_e32 v209, 0xffff0000, v188
	v_fma_f32 v208, v208, v232, v200
	v_fma_f32 v209, v209, v232, v201
	v_cvt_pk_bf16_f32 v210, v208, v209
	v_lshlrev_b32_e32 v120, 16, v210
	v_and_b32_e32 v121, 0xffff0000, v210
	v_lshlrev_b32_e32 v208, 16, v189
	v_and_b32_e32 v209, 0xffff0000, v189
	v_fma_f32 v208, v208, v232, v202
	v_fma_f32 v209, v209, v232, v203
	v_cvt_pk_bf16_f32 v210, v208, v209
	v_lshlrev_b32_e32 v122, 16, v210
	v_and_b32_e32 v123, 0xffff0000, v210
	v_lshlrev_b32_e32 v208, 16, v190
	v_and_b32_e32 v209, 0xffff0000, v190
	v_fma_f32 v208, v208, v232, v204
	v_fma_f32 v209, v209, v232, v205
	v_cvt_pk_bf16_f32 v210, v208, v209
	v_lshlrev_b32_e32 v124, 16, v210
	v_and_b32_e32 v125, 0xffff0000, v210
	v_lshlrev_b32_e32 v208, 16, v191
	v_and_b32_e32 v209, 0xffff0000, v191
	v_fma_f32 v208, v208, v232, v206
	v_fma_f32 v209, v209, v232, v207
	v_cvt_pk_bf16_f32 v210, v208, v209
	v_lshlrev_b32_e32 v126, 16, v210
	v_and_b32_e32 v127, 0xffff0000, v210
	s_nop 0
	v_mov_b32_e32 v224, 0x7fffffff
	v_mov_b32_e32 v225, 0x7fffffff
	v_mov_b32_e32 v226, 0x7fffffff
	v_mov_b32_e32 v227, 0x7fffffff
	v_mov_b32_e32 v228, 0
	v_mov_b32_e32 v229, 0
	v_mov_b32_e32 v230, 0
	v_mov_b32_e32 v231, 0
	v_add_u32_e32 v232, s22, v240
	ds_write_b128 v232, v[224:227] offset:0
	ds_write_b128 v232, v[228:231] offset:4992
	ds_write_b128 v232, v[224:227] offset:1024
	ds_write_b128 v232, v[228:231] offset:6016
	ds_write_b128 v232, v[224:227] offset:2048
	ds_write_b128 v232, v[228:231] offset:7040
	ds_write_b128 v232, v[224:227] offset:3072
	ds_write_b128 v232, v[228:231] offset:8064
	s_mov_b32 exec_hi, 0x00ffffff
	ds_write_b128 v232, v[224:227] offset:4096
	s_mov_b32 exec_hi, 0x000fffff
	ds_write_b128 v232, v[228:231] offset:9088
	s_mov_b64 exec, -1
	v_lshrrev_b32_e32 v221, 2, v240
	v_add_u32_e32 v221, s22, v221
	ds_write_b32 v221, v228 offset:4224
	v_lshrrev_b32_e32 v233, 1, v240
	s_lshl_b32 s0, s76, 10
	s_add_i32 s0, s0, 0x11000
	v_add_u32_e32 v233, s0, v233
	ds_read_b64 v[128:129], v233 offset:0
	ds_read_b64 v[130:131], v233 offset:512
	ds_read_b64 v[132:133], v233 offset:1024
	ds_read_b64 v[134:135], v233 offset:1536
	ds_read_b64 v[136:137], v233 offset:2048
	ds_read_b64 v[138:139], v233 offset:2560
	ds_read_b64 v[140:141], v233 offset:3072
	ds_read_b64 v[142:143], v233 offset:3584
	ds_read_b64 v[144:145], v233 offset:4096
	ds_read_b64 v[146:147], v233 offset:4608
	ds_read_b64 v[148:149], v233 offset:5120
	ds_read_b64 v[150:151], v233 offset:5632
	ds_read_b64 v[152:153], v233 offset:6144
	ds_read_b64 v[154:155], v233 offset:6656
	ds_read_b64 v[156:157], v233 offset:7168
	ds_read_b64 v[158:159], v233 offset:7680
	v_mov_b32_e32 v220, 1
	v_lshrrev_b32_e32 v200, 4, v240
	v_lshrrev_b32_e32 v201, 3, v200
	v_and_b32_e32 v200, 7, v200
	s_add_i32 s3, s22, 4224
	s_and_b32 s1, s32, 7
	s_waitcnt lgkmcnt(0)
; __device__ __forceinline__ void peer_tile(const Args& A, LAS unsigned char* lds, int tile) {
;     ...
;     for (int ti = 0; ti < 8; ++ti) {
;         const int tl = 8 * w + ti;
;         const u32x2 e0 = SEL[tl * 128 + lane], e1 = SEL[tl * 128 + 64 + lane];
;         const int p0 = (int)(e0.x >> 10), p1 = (int)(e1.x >> 10);
;         int off = 0;
;         for (int p = 0; p < 16; ++p) {
;             const unsigned long long m0 = __ballot(p0 == p), m1 = __ballot(p1 == p);
;             const int c0 = __popcll(m0), c1 = __popcll(m1);
;             const int r0 = __builtin_amdgcn_mbcnt_hi((unsigned)(m0 >> 32), __builtin_amdgcn_mbcnt_lo((unsigned)m0, 0u));
;             const int r1 = __builtin_amdgcn_mbcnt_hi((unsigned)(m1 >> 32), __builtin_amdgcn_mbcnt_lo((unsigned)m1, 0u));
;             if (p0 == p) SORT[tl * 128 + off + r0] = e0;
;             if (p1 == p) SORT[tl * 128 + off + c0 + r1] = e1;
;             if (lane == 0) OFFS[tl * 17 + p] = off;
;             off += c0 + c1;
;         }
;         if (lane == 0) OFFS[tl * 17 + 16] = off;
;     }
	v_lshrrev_b32_e32 v160, 11, v128
	v_subrev_u32_e32 v160, s1, v160
	v_and_b32_e32 v160, 7, v160
	v_lshl_add_u32 v176, v160, 2, s3
	v_lshrrev_b32_e32 v161, 11, v130
	v_subrev_u32_e32 v161, s1, v161
	v_and_b32_e32 v161, 7, v161
	v_lshl_add_u32 v177, v161, 2, s3
	v_lshrrev_b32_e32 v162, 11, v132
	v_subrev_u32_e32 v162, s1, v162
	v_and_b32_e32 v162, 7, v162
	v_lshl_add_u32 v178, v162, 2, s3
	v_lshrrev_b32_e32 v163, 11, v134
	v_subrev_u32_e32 v163, s1, v163
	v_and_b32_e32 v163, 7, v163
	v_lshl_add_u32 v179, v163, 2, s3
	v_lshrrev_b32_e32 v164, 11, v136
	v_subrev_u32_e32 v164, s1, v164
	v_and_b32_e32 v164, 7, v164
	v_lshl_add_u32 v180, v164, 2, s3
	v_lshrrev_b32_e32 v165, 11, v138
	v_subrev_u32_e32 v165, s1, v165
	v_and_b32_e32 v165, 7, v165
	v_lshl_add_u32 v181, v165, 2, s3
	v_lshrrev_b32_e32 v166, 11, v140
	v_subrev_u32_e32 v166, s1, v166
	v_and_b32_e32 v166, 7, v166
	v_lshl_add_u32 v182, v166, 2, s3
	v_lshrrev_b32_e32 v167, 11, v142
	v_subrev_u32_e32 v167, s1, v167
	v_and_b32_e32 v167, 7, v167
	v_lshl_add_u32 v183, v167, 2, s3
	v_lshrrev_b32_e32 v168, 11, v144
	v_subrev_u32_e32 v168, s1, v168
	v_and_b32_e32 v168, 7, v168
	v_lshl_add_u32 v184, v168, 2, s3
	v_lshrrev_b32_e32 v169, 11, v146
	v_subrev_u32_e32 v169, s1, v169
	v_and_b32_e32 v169, 7, v169
	v_lshl_add_u32 v185, v169, 2, s3
	v_lshrrev_b32_e32 v170, 11, v148
	v_subrev_u32_e32 v170, s1, v170
	v_and_b32_e32 v170, 7, v170
	v_lshl_add_u32 v186, v170, 2, s3
	v_lshrrev_b32_e32 v171, 11, v150
	v_subrev_u32_e32 v171, s1, v171
	v_and_b32_e32 v171, 7, v171
	v_lshl_add_u32 v187, v171, 2, s3
	v_lshrrev_b32_e32 v172, 11, v152
	v_subrev_u32_e32 v172, s1, v172
	v_and_b32_e32 v172, 7, v172
	v_lshl_add_u32 v188, v172, 2, s3
	v_lshrrev_b32_e32 v173, 11, v154
	v_subrev_u32_e32 v173, s1, v173
	v_and_b32_e32 v173, 7, v173
	v_lshl_add_u32 v189, v173, 2, s3
	v_lshrrev_b32_e32 v174, 11, v156
	v_subrev_u32_e32 v174, s1, v174
	v_and_b32_e32 v174, 7, v174
	v_lshl_add_u32 v190, v174, 2, s3
	v_lshrrev_b32_e32 v175, 11, v158
	v_subrev_u32_e32 v175, s1, v175
	v_and_b32_e32 v175, 7, v175
	v_lshl_add_u32 v191, v175, 2, s3
	ds_add_rtn_u32 v176, v176, v220 offset:0
	ds_add_rtn_u32 v177, v177, v220 offset:0
	ds_add_rtn_u32 v178, v178, v220 offset:32
	ds_add_rtn_u32 v179, v179, v220 offset:32
	ds_add_rtn_u32 v180, v180, v220 offset:64
	ds_add_rtn_u32 v181, v181, v220 offset:64
	ds_add_rtn_u32 v182, v182, v220 offset:96
	ds_add_rtn_u32 v183, v183, v220 offset:96
	ds_add_rtn_u32 v184, v184, v220 offset:128
	ds_add_rtn_u32 v185, v185, v220 offset:128
	ds_add_rtn_u32 v186, v186, v220 offset:160
	ds_add_rtn_u32 v187, v187, v220 offset:160
	ds_add_rtn_u32 v188, v188, v220 offset:192
	ds_add_rtn_u32 v189, v189, v220 offset:192
	ds_add_rtn_u32 v190, v190, v220 offset:224
	ds_add_rtn_u32 v191, v191, v220 offset:224
	v_lshl_add_u32 v207, v201, 5, s3
	ds_read_b32 v203, v221 offset:4224
	ds_read_b128 v[192:195], v207
	ds_read_b128 v[196:199], v207 offset:16
	v_mov_b32_e32 v202, 0
	s_waitcnt lgkmcnt(0)
	v_cmp_lt_u32_e64 s[38:39], 0, v200
	v_cmp_lt_u32_e64 s[40:41], 1, v200
	v_cmp_lt_u32_e64 s[42:43], 2, v200
	v_cmp_lt_u32_e64 s[44:45], 3, v200
	v_cmp_lt_u32_e64 s[64:65], 4, v200
	v_cmp_lt_u32_e64 s[66:67], 5, v200
	v_cmp_lt_u32_e64 s[94:95], 6, v200
	v_cndmask_b32_e64 v206, 0, v192, s[38:39]
	v_add_u32_e32 v202, v202, v206
	v_cndmask_b32_e64 v206, 0, v193, s[40:41]
	v_add_u32_e32 v202, v202, v206
	v_cndmask_b32_e64 v206, 0, v194, s[42:43]
	v_add_u32_e32 v202, v202, v206
	v_cndmask_b32_e64 v206, 0, v195, s[44:45]
	v_add_u32_e32 v202, v202, v206
	v_cndmask_b32_e64 v206, 0, v196, s[64:65]
	v_add_u32_e32 v202, v202, v206
	v_cndmask_b32_e64 v206, 0, v197, s[66:67]
	v_add_u32_e32 v202, v202, v206
	v_cndmask_b32_e64 v206, 0, v198, s[94:95]
	v_add_u32_e32 v202, v202, v206
	v_add_u32_e32 v204, 3, v202
	v_add3_u32 v212, v202, v203, 3
	v_lshrrev_b32_e32 v204, 2, v204
	v_lshrrev_b32_e32 v212, 2, v212
	v_sub_u32_e32 v212, v212, v204
	v_lshl_add_u32 v207, v200, 3, v201
	v_lshl_add_u32 v207, v207, 2, s3
	ds_write_b32 v207, v212 offset:256
	v_lshl_add_u32 v208, v200, 5, s3
	ds_read_b128 v[192:195], v208 offset:256
	ds_read_b128 v[196:199], v208 offset:272
	v_mov_b32_e32 v205, 0
	s_waitcnt lgkmcnt(0)
	v_cmp_lt_u32_e64 s[38:39], 0, v201
	v_cmp_lt_u32_e64 s[40:41], 1, v201
	v_cmp_lt_u32_e64 s[42:43], 2, v201
	v_cmp_lt_u32_e64 s[44:45], 3, v201
	v_cmp_lt_u32_e64 s[64:65], 4, v201
	v_cmp_lt_u32_e64 s[66:67], 5, v201
	v_cmp_lt_u32_e64 s[94:95], 6, v201
	v_cndmask_b32_e64 v206, 0, v192, s[38:39]
	v_add_u32_e32 v205, v205, v206
	v_cndmask_b32_e64 v206, 0, v193, s[40:41]
	v_add_u32_e32 v205, v205, v206
	v_cndmask_b32_e64 v206, 0, v194, s[42:43]
	v_add_u32_e32 v205, v205, v206
	v_cndmask_b32_e64 v206, 0, v195, s[44:45]
	v_add_u32_e32 v205, v205, v206
	v_cndmask_b32_e64 v206, 0, v196, s[64:65]
	v_add_u32_e32 v205, v205, v206
	v_cndmask_b32_e64 v206, 0, v197, s[66:67]
	v_add_u32_e32 v205, v205, v206
	v_cndmask_b32_e64 v206, 0, v198, s[94:95]
	v_add_u32_e32 v205, v205, v206
	v_add_u32_e32 v206, v192, v193
	v_add_u32_e32 v206, v206, v194
	v_add_u32_e32 v206, v206, v195
	v_add_u32_e32 v206, v206, v196
	v_add_u32_e32 v206, v206, v197
	v_add_u32_e32 v206, v206, v198
	v_add_u32_e32 v206, v206, v199
	v_lshl_add_u32 v207, v200, 2, s3
	ds_write_b32 v207, v206 offset:512
	v_mov_b32_e32 v207, s3
	ds_read_b128 v[192:195], v207 offset:512
	ds_read_b128 v[196:199], v207 offset:528
	ds_write_b32 v221, v202 offset:4224
	s_waitcnt lgkmcnt(0)
; __device__ __forceinline__ void peer_tile(const Args& A, LAS unsigned char* lds, int tile) {
;     ...
;         int off = 0;
;         for (int p = 0; p < 16; ++p) {
;             const unsigned long long m0 = __ballot(p0 == p), m1 = __ballot(p1 == p);
;             const int c0 = __popcll(m0), c1 = __popcll(m1);
;             const int r0 = __builtin_amdgcn_mbcnt_hi((unsigned)(m0 >> 32), __builtin_amdgcn_mbcnt_lo((unsigned)m0, 0u));
;             const int r1 = __builtin_amdgcn_mbcnt_hi((unsigned)(m1 >> 32), __builtin_amdgcn_mbcnt_lo((unsigned)m1, 0u));
;             if (p0 == p) SORT[tl * 128 + off + r0] = e0;
;             if (p1 == p) SORT[tl * 128 + off + c0 + r1] = e1;
;             if (lane == 0) OFFS[tl * 17 + p] = off;
;             off += c0 + c1;
;         }
;         if (lane == 0) OFFS[tl * 17 + 16] = off;
	v_cmp_lt_u32_e64 s[38:39], 0, v200
	v_cmp_lt_u32_e64 s[40:41], 1, v200
	v_cmp_lt_u32_e64 s[42:43], 2, v200
	v_cmp_lt_u32_e64 s[44:45], 3, v200
	v_cmp_lt_u32_e64 s[64:65], 4, v200
	v_cmp_lt_u32_e64 s[66:67], 5, v200
	v_cmp_lt_u32_e64 s[94:95], 6, v200
	v_cndmask_b32_e64 v206, 0, v192, s[38:39]
	v_add_u32_e32 v205, v205, v206
	v_cndmask_b32_e64 v206, 0, v193, s[40:41]
	v_add_u32_e32 v205, v205, v206
	v_cndmask_b32_e64 v206, 0, v194, s[42:43]
	v_add_u32_e32 v205, v205, v206
	v_cndmask_b32_e64 v206, 0, v195, s[44:45]
	v_add_u32_e32 v205, v205, v206
	v_cndmask_b32_e64 v206, 0, v196, s[64:65]
	v_add_u32_e32 v205, v205, v206
	v_cndmask_b32_e64 v206, 0, v197, s[66:67]
	v_add_u32_e32 v205, v205, v206
	v_cndmask_b32_e64 v206, 0, v198, s[94:95]
	v_add_u32_e32 v205, v205, v206
	v_sub_u32_e32 v205, v205, v204
	v_lshrrev_b32_e32 v208, 4, v240
	v_and_b32_e32 v222, 31, v208
	v_lshrrev_b32_e32 v208, 5, v208
	v_add_u32_e32 v207, 0, v208
	v_lshl_add_u32 v206, v207, 5, s3
	ds_read_b128 v[192:195], v206
	ds_read_b128 v[196:199], v206 offset:16
	v_lshlrev_b32_e32 v206, 2, v222
	v_lshlrev_b32_e32 v223, 3, v207
	s_waitcnt lgkmcnt(0)
	v_cmp_le_u32_e64 s[38:39], v193, v206
	v_cmp_le_u32_e64 s[40:41], v194, v206
	v_cmp_le_u32_e64 s[42:43], v195, v206
	v_cmp_le_u32_e64 s[44:45], v196, v206
	v_cmp_le_u32_e64 s[64:65], v197, v206
	v_cmp_le_u32_e64 s[66:67], v198, v206
	v_cmp_le_u32_e64 s[94:95], v199, v206
	v_addc_co_u32_e64 v223, s[92:93], 0, v223, s[38:39]
	v_addc_co_u32_e64 v223, s[92:93], 0, v223, s[40:41]
	v_addc_co_u32_e64 v223, s[92:93], 0, v223, s[42:43]
	v_addc_co_u32_e64 v223, s[92:93], 0, v223, s[44:45]
	v_addc_co_u32_e64 v223, s[92:93], 0, v223, s[64:65]
	v_addc_co_u32_e64 v223, s[92:93], 0, v223, s[66:67]
	v_addc_co_u32_e64 v223, s[92:93], 0, v223, s[94:95]
	v_lshlrev_b32_e32 v223, 2, v223
	ds_bpermute_b32 v216, v223, v205
	v_add_u32_e32 v207, 2, v208
	v_lshl_add_u32 v206, v207, 5, s3
	ds_read_b128 v[192:195], v206
	ds_read_b128 v[196:199], v206 offset:16
	v_lshlrev_b32_e32 v206, 2, v222
	v_lshlrev_b32_e32 v223, 3, v207
	s_waitcnt lgkmcnt(0)
	v_cmp_le_u32_e64 s[38:39], v193, v206
	v_cmp_le_u32_e64 s[40:41], v194, v206
	v_cmp_le_u32_e64 s[42:43], v195, v206
	v_cmp_le_u32_e64 s[44:45], v196, v206
	v_cmp_le_u32_e64 s[64:65], v197, v206
	v_cmp_le_u32_e64 s[66:67], v198, v206
	v_cmp_le_u32_e64 s[94:95], v199, v206
	v_addc_co_u32_e64 v223, s[92:93], 0, v223, s[38:39]
	v_addc_co_u32_e64 v223, s[92:93], 0, v223, s[40:41]
	v_addc_co_u32_e64 v223, s[92:93], 0, v223, s[42:43]
	v_addc_co_u32_e64 v223, s[92:93], 0, v223, s[44:45]
	v_addc_co_u32_e64 v223, s[92:93], 0, v223, s[64:65]
	v_addc_co_u32_e64 v223, s[92:93], 0, v223, s[66:67]
	v_addc_co_u32_e64 v223, s[92:93], 0, v223, s[94:95]
	v_lshlrev_b32_e32 v223, 2, v223
	ds_bpermute_b32 v217, v223, v205
	v_add_u32_e32 v207, 4, v208
	v_lshl_add_u32 v206, v207, 5, s3
	ds_read_b128 v[192:195], v206
	ds_read_b128 v[196:199], v206 offset:16
	v_lshlrev_b32_e32 v206, 2, v222
	v_lshlrev_b32_e32 v223, 3, v207
	s_waitcnt lgkmcnt(0)
	v_cmp_le_u32_e64 s[38:39], v193, v206
	v_cmp_le_u32_e64 s[40:41], v194, v206
	v_cmp_le_u32_e64 s[42:43], v195, v206
	v_cmp_le_u32_e64 s[44:45], v196, v206
	v_cmp_le_u32_e64 s[64:65], v197, v206
	v_cmp_le_u32_e64 s[66:67], v198, v206
	v_cmp_le_u32_e64 s[94:95], v199, v206
	v_addc_co_u32_e64 v223, s[92:93], 0, v223, s[38:39]
	v_addc_co_u32_e64 v223, s[92:93], 0, v223, s[40:41]
	v_addc_co_u32_e64 v223, s[92:93], 0, v223, s[42:43]
	v_addc_co_u32_e64 v223, s[92:93], 0, v223, s[44:45]
	v_addc_co_u32_e64 v223, s[92:93], 0, v223, s[64:65]
	v_addc_co_u32_e64 v223, s[92:93], 0, v223, s[66:67]
	v_addc_co_u32_e64 v223, s[92:93], 0, v223, s[94:95]
	v_lshlrev_b32_e32 v223, 2, v223
	ds_bpermute_b32 v218, v223, v205
	v_add_u32_e32 v207, 6, v208
	v_lshl_add_u32 v206, v207, 5, s3
	ds_read_b128 v[192:195], v206
	ds_read_b128 v[196:199], v206 offset:16
	v_lshlrev_b32_e32 v206, 2, v222
	v_lshlrev_b32_e32 v223, 3, v207
	s_waitcnt lgkmcnt(0)
	v_cmp_le_u32_e64 s[38:39], v193, v206
	v_cmp_le_u32_e64 s[40:41], v194, v206
	v_cmp_le_u32_e64 s[42:43], v195, v206
	v_cmp_le_u32_e64 s[44:45], v196, v206
	v_cmp_le_u32_e64 s[64:65], v197, v206
	v_cmp_le_u32_e64 s[66:67], v198, v206
	v_cmp_le_u32_e64 s[94:95], v199, v206
	v_addc_co_u32_e64 v223, s[92:93], 0, v223, s[38:39]
	v_addc_co_u32_e64 v223, s[92:93], 0, v223, s[40:41]
	v_addc_co_u32_e64 v223, s[92:93], 0, v223, s[42:43]
	v_addc_co_u32_e64 v223, s[92:93], 0, v223, s[44:45]
	v_addc_co_u32_e64 v223, s[92:93], 0, v223, s[64:65]
	v_addc_co_u32_e64 v223, s[92:93], 0, v223, s[66:67]
	v_addc_co_u32_e64 v223, s[92:93], 0, v223, s[94:95]
	v_lshlrev_b32_e32 v223, 2, v223
	ds_bpermute_b32 v219, v223, v205
	s_waitcnt lgkmcnt(0)
	v_add_u32_e32 v216, v216, v222
	v_add_u32_e32 v217, v217, v222
	v_add_u32_e32 v218, v218, v222
	v_add_u32_e32 v219, v219, v222
	v_lshlrev_b32_e32 v160, 2, v160
	ds_bpermute_b32 v160, v160, v202
	v_lshlrev_b32_e32 v161, 2, v161
	ds_bpermute_b32 v161, v161, v202
	v_lshlrev_b32_e32 v162, 2, v162
	v_add_u32_e32 v162, 32, v162
	ds_bpermute_b32 v162, v162, v202
	v_lshlrev_b32_e32 v163, 2, v163
	v_add_u32_e32 v163, 32, v163
	ds_bpermute_b32 v163, v163, v202
	v_lshlrev_b32_e32 v164, 2, v164
	v_add_u32_e32 v164, 64, v164
	ds_bpermute_b32 v164, v164, v202
	v_lshlrev_b32_e32 v165, 2, v165
	v_add_u32_e32 v165, 64, v165
	ds_bpermute_b32 v165, v165, v202
	v_lshlrev_b32_e32 v166, 2, v166
	v_add_u32_e32 v166, 96, v166
	ds_bpermute_b32 v166, v166, v202
	v_lshlrev_b32_e32 v167, 2, v167
	v_add_u32_e32 v167, 96, v167
	ds_bpermute_b32 v167, v167, v202
	v_lshlrev_b32_e32 v168, 2, v168
	v_add_u32_e32 v168, 128, v168
	ds_bpermute_b32 v168, v168, v202
	v_lshlrev_b32_e32 v169, 2, v169
	v_add_u32_e32 v169, 128, v169
	ds_bpermute_b32 v169, v169, v202
	v_lshlrev_b32_e32 v170, 2, v170
	v_add_u32_e32 v170, 160, v170
	ds_bpermute_b32 v170, v170, v202
	v_lshlrev_b32_e32 v171, 2, v171
	v_add_u32_e32 v171, 160, v171
	ds_bpermute_b32 v171, v171, v202
	v_lshlrev_b32_e32 v172, 2, v172
	v_add_u32_e32 v172, 192, v172
	ds_bpermute_b32 v172, v172, v202
	v_lshlrev_b32_e32 v173, 2, v173
	v_add_u32_e32 v173, 192, v173
	ds_bpermute_b32 v173, v173, v202
	v_lshlrev_b32_e32 v174, 2, v174
	v_add_u32_e32 v174, 224, v174
	ds_bpermute_b32 v174, v174, v202
	v_lshlrev_b32_e32 v175, 2, v175
	v_add_u32_e32 v175, 224, v175
	ds_bpermute_b32 v175, v175, v202
	s_waitcnt lgkmcnt(0)
; __device__ __forceinline__ void peer_tile(const Args& A, LAS unsigned char* lds, int tile) {
;     ...
;             if (p0 == p) SORT[tl * 128 + off + r0] = e0;
;             if (p1 == p) SORT[tl * 128 + off + c0 + r1] = e1;
;             if (lane == 0) OFFS[tl * 17 + p] = off;
;             off += c0 + c1;
;         }
;         if (lane == 0) OFFS[tl * 17 + 16] = off;
	v_add_u32_e32 v176, v176, v160
	v_lshrrev_b32_e32 v160, 2, v176
	v_and_b32_e32 v176, 3, v176
	v_lshlrev_b32_e32 v160, 2, v160
	ds_bpermute_b32 v160, v160, v216
	v_add_u32_e32 v177, v177, v161
	v_lshrrev_b32_e32 v161, 2, v177
	v_and_b32_e32 v177, 3, v177
	v_lshlrev_b32_e32 v161, 2, v161
	ds_bpermute_b32 v161, v161, v216
	v_add_u32_e32 v178, v178, v162
	v_lshrrev_b32_e32 v162, 2, v178
	v_and_b32_e32 v178, 3, v178
	v_lshlrev_b32_e32 v162, 2, v162
	v_add_u32_e32 v162, 128, v162
	ds_bpermute_b32 v162, v162, v216
	v_add_u32_e32 v179, v179, v163
	v_lshrrev_b32_e32 v163, 2, v179
	v_and_b32_e32 v179, 3, v179
	v_lshlrev_b32_e32 v163, 2, v163
	v_add_u32_e32 v163, 128, v163
	ds_bpermute_b32 v163, v163, v216
	v_add_u32_e32 v180, v180, v164
	v_lshrrev_b32_e32 v164, 2, v180
	v_and_b32_e32 v180, 3, v180
	v_lshlrev_b32_e32 v164, 2, v164
	ds_bpermute_b32 v164, v164, v217
	v_add_u32_e32 v181, v181, v165
	v_lshrrev_b32_e32 v165, 2, v181
	v_and_b32_e32 v181, 3, v181
	v_lshlrev_b32_e32 v165, 2, v165
	ds_bpermute_b32 v165, v165, v217
	v_add_u32_e32 v182, v182, v166
	v_lshrrev_b32_e32 v166, 2, v182
	v_and_b32_e32 v182, 3, v182
	v_lshlrev_b32_e32 v166, 2, v166
	v_add_u32_e32 v166, 128, v166
	ds_bpermute_b32 v166, v166, v217
	v_add_u32_e32 v183, v183, v167
	v_lshrrev_b32_e32 v167, 2, v183
	v_and_b32_e32 v183, 3, v183
	v_lshlrev_b32_e32 v167, 2, v167
	v_add_u32_e32 v167, 128, v167
	ds_bpermute_b32 v167, v167, v217
	v_add_u32_e32 v184, v184, v168
	v_lshrrev_b32_e32 v168, 2, v184
	v_and_b32_e32 v184, 3, v184
	v_lshlrev_b32_e32 v168, 2, v168
	ds_bpermute_b32 v168, v168, v218
	v_add_u32_e32 v185, v185, v169
	v_lshrrev_b32_e32 v169, 2, v185
	v_and_b32_e32 v185, 3, v185
	v_lshlrev_b32_e32 v169, 2, v169
	ds_bpermute_b32 v169, v169, v218
	v_add_u32_e32 v186, v186, v170
	v_lshrrev_b32_e32 v170, 2, v186
	v_and_b32_e32 v186, 3, v186
	v_lshlrev_b32_e32 v170, 2, v170
	v_add_u32_e32 v170, 128, v170
	ds_bpermute_b32 v170, v170, v218
	v_add_u32_e32 v187, v187, v171
	v_lshrrev_b32_e32 v171, 2, v187
	v_and_b32_e32 v187, 3, v187
	v_lshlrev_b32_e32 v171, 2, v171
	v_add_u32_e32 v171, 128, v171
	ds_bpermute_b32 v171, v171, v218
	v_add_u32_e32 v188, v188, v172
	v_lshrrev_b32_e32 v172, 2, v188
	v_and_b32_e32 v188, 3, v188
	v_lshlrev_b32_e32 v172, 2, v172
	ds_bpermute_b32 v172, v172, v219
	v_add_u32_e32 v189, v189, v173
	v_lshrrev_b32_e32 v173, 2, v189
	v_and_b32_e32 v189, 3, v189
	v_lshlrev_b32_e32 v173, 2, v173
	ds_bpermute_b32 v173, v173, v219
	v_add_u32_e32 v190, v190, v174
	v_lshrrev_b32_e32 v174, 2, v190
	v_and_b32_e32 v190, 3, v190
	v_lshlrev_b32_e32 v174, 2, v174
	v_add_u32_e32 v174, 128, v174
	ds_bpermute_b32 v174, v174, v219
	v_add_u32_e32 v191, v191, v175
	v_lshrrev_b32_e32 v175, 2, v191
	v_and_b32_e32 v191, 3, v191
	v_lshlrev_b32_e32 v175, 2, v175
	v_add_u32_e32 v175, 128, v175
	ds_bpermute_b32 v175, v175, v219
	s_waitcnt lgkmcnt(0)
	v_lshl_add_u32 v160, v160, 4, s22
	v_lshl_add_u32 v160, v176, 2, v160
	ds_write_b32 v160, v128
	ds_write_b32 v160, v129 offset:4992
	v_lshl_add_u32 v161, v161, 4, s22
	v_lshl_add_u32 v161, v177, 2, v161
	ds_write_b32 v161, v130
	ds_write_b32 v161, v131 offset:4992
	v_lshl_add_u32 v162, v162, 4, s22
	v_lshl_add_u32 v162, v178, 2, v162
	ds_write_b32 v162, v132
	ds_write_b32 v162, v133 offset:4992
	v_lshl_add_u32 v163, v163, 4, s22
	v_lshl_add_u32 v163, v179, 2, v163
	ds_write_b32 v163, v134
	ds_write_b32 v163, v135 offset:4992
	v_lshl_add_u32 v164, v164, 4, s22
	v_lshl_add_u32 v164, v180, 2, v164
	ds_write_b32 v164, v136
	ds_write_b32 v164, v137 offset:4992
	v_lshl_add_u32 v165, v165, 4, s22
	v_lshl_add_u32 v165, v181, 2, v165
	ds_write_b32 v165, v138
	ds_write_b32 v165, v139 offset:4992
	v_lshl_add_u32 v166, v166, 4, s22
	v_lshl_add_u32 v166, v182, 2, v166
	ds_write_b32 v166, v140
	ds_write_b32 v166, v141 offset:4992
	v_lshl_add_u32 v167, v167, 4, s22
	v_lshl_add_u32 v167, v183, 2, v167
	ds_write_b32 v167, v142
	ds_write_b32 v167, v143 offset:4992
	v_lshl_add_u32 v168, v168, 4, s22
	v_lshl_add_u32 v168, v184, 2, v168
	ds_write_b32 v168, v144
	ds_write_b32 v168, v145 offset:4992
	v_lshl_add_u32 v169, v169, 4, s22
	v_lshl_add_u32 v169, v185, 2, v169
	ds_write_b32 v169, v146
	ds_write_b32 v169, v147 offset:4992
	v_lshl_add_u32 v170, v170, 4, s22
	v_lshl_add_u32 v170, v186, 2, v170
	ds_write_b32 v170, v148
	ds_write_b32 v170, v149 offset:4992
	v_lshl_add_u32 v171, v171, 4, s22
	v_lshl_add_u32 v171, v187, 2, v171
	ds_write_b32 v171, v150
	ds_write_b32 v171, v151 offset:4992
	v_lshl_add_u32 v172, v172, 4, s22
	v_lshl_add_u32 v172, v188, 2, v172
	ds_write_b32 v172, v152
	ds_write_b32 v172, v153 offset:4992
	v_lshl_add_u32 v173, v173, 4, s22
	v_lshl_add_u32 v173, v189, 2, v173
	ds_write_b32 v173, v154
	ds_write_b32 v173, v155 offset:4992
	v_lshl_add_u32 v174, v174, 4, s22
	v_lshl_add_u32 v174, v190, 2, v174
	ds_write_b32 v174, v156
	ds_write_b32 v174, v157 offset:4992
	v_lshl_add_u32 v175, v175, 4, s22
	v_lshl_add_u32 v175, v191, 2, v175
	ds_write_b32 v175, v158
	ds_write_b32 v175, v159 offset:4992
	v_mov_b32_e32 v206, 0x7fffffff
	ds_write_b32 v221, v206 offset:4224
	ds_write_b32 v221, v206 offset:4480
	ds_write_b32 v221, v206 offset:4736
	s_mov_b32 s91, 256
	s_add_i32 s20, s91, 3
	s_and_b32 s20, s20, -4
	s_mov_b32 s24, s8
	s_and_b32 s25, s9, 0xffff
	s_mov_b32 s26, 0x20000
	s_mov_b32 s27, 0x00027000
	s_mov_b32 s28, s52
	s_and_b32 s29, s53, 0xffff
	s_mov_b32 s30, 0x20000
	s_mov_b32 s31, 0x00027000
	s_waitcnt vmcnt(0) lgkmcnt(0)
	v_mov_b32_e32 v213, s22
	v_mov_b32_e32 v233, v240
	v_mov_b32_e32 v235, v240
	v_mov_b32_e32 v237, v240
	v_mov_b32_e32 v239, v240
	ds_read_b32 v232, v213 offset:0
	ds_read_b32 v234, v213 offset:4
	ds_read_b32 v236, v213 offset:8
	ds_read_b32 v238, v213 offset:12
	s_waitcnt lgkmcnt(0)
; __device__ __forceinline__ float bflo(unsigned u) { return __uint_as_float(u << 16); }
; __device__ __forceinline__ float bfhi(unsigned u) { return __uint_as_float(u & 0xffff0000u); }
; #define IT_ADVANCE() do { it_j += 4; while (it_j >= it_end) { if (it_done) break; ++it_tk; if (it_tk == 4) { it_tk = 0; ++it_p; if (it_p == 16) { it_done = true; it_p = 15; it_j = 0; it_end = 1; break; } } \
;             it_j = __builtin_amdgcn_readfirstlane(OFFS[(tb + it_tk) * 17 + it_p]); it_end = __builtin_amdgcn_readfirstlane(OFFS[(tb + it_tk) * 17 + it_p + 1]); } } while (0)
; __device__ __forceinline__ void peer_tile(const Args& A, LAS unsigned char* lds, int tile) {
;     ...
;         u32x4 uA[4], vA[4], uB[4], vB[4]; float cgA = 0.f, suA = 0.f, svA = 0.f, cgB = 0.f, suB = 0.f, svB = 0.f;
; #pragma unroll
;         for (int k = 0; k < 4; ++k) { uA[k] = (u32x4){0u, 0u, 0u, 0u}; vA[k] = uA[k]; uB[k] = uA[k]; vB[k] = uA[k]; }
;         IT_ADVANCE();
;         LOAD_SET(uA, vA, cgA, suA, svA);
;         for (int p = 0; p < 16; ++p) {
; #pragma unroll
;             for (int tk = 0; tk < 4; ++tk) {
;                 const int tl = tb + tk;
;                 const int beg = __builtin_amdgcn_readfirstlane(OFFS[tl * 17 + p]), end = __builtin_amdgcn_readfirstlane(OFFS[tl * 17 + p + 1]);
;                 f32x2 xf[8];
;                 { const unsigned xx[8] = {xpa[tk].x, xpa[tk].y, xpa[tk].z, xpa[tk].w, xpb[tk].x, xpb[tk].y, xpb[tk].z, xpb[tk].w};
; #pragma unroll
;                   for (int q = 0; q < 8; ++q) xf[q] = (f32x2){bflo(xx[q]), bfhi(xx[q])}; }
	buffer_load_dwordx4 v[128:131], v[232:233], s[56:59], 0 idxen offen
	buffer_load_dwordx4 v[132:135], v[234:235], s[56:59], 0 idxen offen
	buffer_load_dwordx4 v[136:139], v[236:237], s[56:59], 0 idxen offen
	buffer_load_dwordx4 v[140:143], v[238:239], s[56:59], 0 idxen offen
	ds_read_b32 v232, v213 offset:16
	ds_read_b32 v234, v213 offset:20
	ds_read_b32 v236, v213 offset:24
	ds_read_b32 v238, v213 offset:28
	s_waitcnt lgkmcnt(0)
	buffer_load_dwordx4 v[144:147], v[232:233], s[56:59], 0 idxen offen
	buffer_load_dwordx4 v[148:151], v[234:235], s[56:59], 0 idxen offen
	buffer_load_dwordx4 v[152:155], v[236:237], s[56:59], 0 idxen offen
	buffer_load_dwordx4 v[156:159], v[238:239], s[56:59], 0 idxen offen
	ds_read_b32 v232, v213 offset:32
	ds_read_b32 v234, v213 offset:36
	ds_read_b32 v236, v213 offset:40
	ds_read_b32 v238, v213 offset:44
	s_waitcnt lgkmcnt(0)
	buffer_load_dwordx4 v[160:163], v[232:233], s[56:59], 0 idxen offen
	buffer_load_dwordx4 v[164:167], v[234:235], s[56:59], 0 idxen offen
	buffer_load_dwordx4 v[168:171], v[236:237], s[56:59], 0 idxen offen
	buffer_load_dwordx4 v[172:175], v[238:239], s[56:59], 0 idxen offen
	ds_read_b32 v232, v213 offset:48
	ds_read_b32 v234, v213 offset:52
	ds_read_b32 v236, v213 offset:56
	ds_read_b32 v238, v213 offset:60
	s_mov_b32 s21, 0
	s_mov_b32 s89, -1
	s_mov_b32 s86, 0
	v_lshrrev_b32_e32 v208, 6, v240
	v_and_b32_e32 v208, 3, v208
	v_lshrrev_b32_e32 v209, 1, v208
	v_lshlrev_b32_e32 v208, 1, v208
	v_and_b32_e32 v208, 2, v208
	v_or_b32_e32 v208, v208, v209
	v_lshlrev_b32_e32 v208, 2, v208
	v_add3_u32 v211, v208, v247, s22
	ds_read_b32 v248, v211
	ds_read_b32 v249, v211 offset:4992
	s_branch .LU_sw0
.LU_t0_s0:
	s_cmp_ge_u32 s21, s20
	s_cbranch_scc1 .LU_done
	s_waitcnt lgkmcnt(0)
	v_lshlrev_b32_e32 v208, 3, v248
	buffer_load_dwordx2 v[252:253], v208, s[24:27], 0 offen
	buffer_load_dwordx4 v[176:179], v[232:233], s[56:59], 0 idxen offen
	buffer_load_dwordx4 v[180:183], v[234:235], s[56:59], 0 idxen offen
	buffer_load_dwordx4 v[184:187], v[236:237], s[56:59], 0 idxen offen
	buffer_load_dwordx4 v[188:191], v[238:239], s[56:59], 0 idxen offen
	ds_read_b32 v232, v213 offset:64
	ds_read_b32 v234, v213 offset:68
	ds_read_b32 v236, v213 offset:72
	ds_read_b32 v238, v213 offset:76
	s_waitcnt vmcnt(13)
	v_cvt_pk_f32_fp8_e32 v[224:225], v128
	v_cvt_pk_f32_fp8_e32 v[226:227], v132
	v_cvt_pk_f32_fp8_e32 v[228:229], v136
	v_cvt_pk_f32_fp8_e32 v[230:231], v140
	v_pk_mul_f32 v[216:217], v[224:225], v[0:1]
	v_pk_mul_f32 v[218:219], v[226:227], v[0:1]
	v_pk_mul_f32 v[220:221], v[228:229], v[0:1]
	v_pk_mul_f32 v[222:223], v[230:231], v[0:1]
	v_cvt_pk_f32_fp8_sdwa v[224:225], v128 src0_sel:WORD_1
	v_cvt_pk_f32_fp8_sdwa v[226:227], v132 src0_sel:WORD_1
	v_cvt_pk_f32_fp8_sdwa v[228:229], v136 src0_sel:WORD_1
	v_cvt_pk_f32_fp8_sdwa v[230:231], v140 src0_sel:WORD_1
	v_pk_fma_f32 v[216:217], v[224:225], v[2:3], v[216:217]
	v_pk_fma_f32 v[218:219], v[226:227], v[2:3], v[218:219]
	v_pk_fma_f32 v[220:221], v[228:229], v[2:3], v[220:221]
	v_pk_fma_f32 v[222:223], v[230:231], v[2:3], v[222:223]
	v_cvt_pk_f32_fp8_e32 v[224:225], v129
	v_cvt_pk_f32_fp8_e32 v[226:227], v133
	v_cvt_pk_f32_fp8_e32 v[228:229], v137
	v_cvt_pk_f32_fp8_e32 v[230:231], v141
	v_pk_fma_f32 v[216:217], v[224:225], v[4:5], v[216:217]
	v_pk_fma_f32 v[218:219], v[226:227], v[4:5], v[218:219]
	v_pk_fma_f32 v[220:221], v[228:229], v[4:5], v[220:221]
	v_pk_fma_f32 v[222:223], v[230:231], v[4:5], v[222:223]
	v_cvt_pk_f32_fp8_sdwa v[224:225], v129 src0_sel:WORD_1
	v_cvt_pk_f32_fp8_sdwa v[226:227], v133 src0_sel:WORD_1
	v_cvt_pk_f32_fp8_sdwa v[228:229], v137 src0_sel:WORD_1
	v_cvt_pk_f32_fp8_sdwa v[230:231], v141 src0_sel:WORD_1
	v_pk_fma_f32 v[216:217], v[224:225], v[6:7], v[216:217]
	v_pk_fma_f32 v[218:219], v[226:227], v[6:7], v[218:219]
	v_pk_fma_f32 v[220:221], v[228:229], v[6:7], v[220:221]
	v_pk_fma_f32 v[222:223], v[230:231], v[6:7], v[222:223]
	v_cvt_pk_f32_fp8_e32 v[224:225], v130
	v_cvt_pk_f32_fp8_e32 v[226:227], v134
	v_cvt_pk_f32_fp8_e32 v[228:229], v138
	v_cvt_pk_f32_fp8_e32 v[230:231], v142
	v_pk_fma_f32 v[216:217], v[224:225], v[8:9], v[216:217]
	v_pk_fma_f32 v[218:219], v[226:227], v[8:9], v[218:219]
	v_pk_fma_f32 v[220:221], v[228:229], v[8:9], v[220:221]
	v_pk_fma_f32 v[222:223], v[230:231], v[8:9], v[222:223]
	v_cvt_pk_f32_fp8_sdwa v[224:225], v130 src0_sel:WORD_1
	v_cvt_pk_f32_fp8_sdwa v[226:227], v134 src0_sel:WORD_1
	v_cvt_pk_f32_fp8_sdwa v[228:229], v138 src0_sel:WORD_1
	v_cvt_pk_f32_fp8_sdwa v[230:231], v142 src0_sel:WORD_1
	v_pk_fma_f32 v[216:217], v[224:225], v[10:11], v[216:217]
	v_pk_fma_f32 v[218:219], v[226:227], v[10:11], v[218:219]
	v_pk_fma_f32 v[220:221], v[228:229], v[10:11], v[220:221]
	v_pk_fma_f32 v[222:223], v[230:231], v[10:11], v[222:223]
	v_cvt_pk_f32_fp8_e32 v[224:225], v131
	v_cvt_pk_f32_fp8_e32 v[226:227], v135
	v_cvt_pk_f32_fp8_e32 v[228:229], v139
	v_cvt_pk_f32_fp8_e32 v[230:231], v143
	v_pk_fma_f32 v[216:217], v[224:225], v[12:13], v[216:217]
	v_pk_fma_f32 v[218:219], v[226:227], v[12:13], v[218:219]
	v_pk_fma_f32 v[220:221], v[228:229], v[12:13], v[220:221]
	v_pk_fma_f32 v[222:223], v[230:231], v[12:13], v[222:223]
	v_cvt_pk_f32_fp8_sdwa v[224:225], v131 src0_sel:WORD_1
	v_cvt_pk_f32_fp8_sdwa v[226:227], v135 src0_sel:WORD_1
	v_cvt_pk_f32_fp8_sdwa v[228:229], v139 src0_sel:WORD_1
	v_cvt_pk_f32_fp8_sdwa v[230:231], v143 src0_sel:WORD_1
	v_pk_fma_f32 v[216:217], v[224:225], v[14:15], v[216:217]
	v_pk_fma_f32 v[218:219], v[226:227], v[14:15], v[218:219]
	v_pk_fma_f32 v[220:221], v[228:229], v[14:15], v[220:221]
	v_pk_fma_f32 v[222:223], v[230:231], v[14:15], v[222:223]
	v_add_f32_e32 v192, v216, v217
	v_add_f32_e32 v193, v218, v219
	v_add_f32_e32 v194, v220, v221
	v_add_f32_e32 v195, v222, v223
	s_sub_i32 s90, s90, 1
	s_cmp_eq_u32 s90, 0
	s_cbranch_scc1 .LU_sw1
.LU_t0_s1:
	s_waitcnt lgkmcnt(0)
	buffer_load_dwordx4 v[128:131], v[232:233], s[56:59], 0 idxen offen
	buffer_load_dwordx4 v[132:135], v[234:235], s[56:59], 0 idxen offen
	buffer_load_dwordx4 v[136:139], v[236:237], s[56:59], 0 idxen offen
	buffer_load_dwordx4 v[140:143], v[238:239], s[56:59], 0 idxen offen
	ds_read_b32 v232, v213 offset:80
	ds_read_b32 v234, v213 offset:84
	ds_read_b32 v236, v213 offset:88
	ds_read_b32 v238, v213 offset:92
	s_waitcnt vmcnt(13)
	v_cvt_pk_f32_fp8_e32 v[224:225], v144
	v_cvt_pk_f32_fp8_e32 v[226:227], v148
	v_cvt_pk_f32_fp8_e32 v[228:229], v152
	v_cvt_pk_f32_fp8_e32 v[230:231], v156
	v_pk_mul_f32 v[216:217], v[224:225], v[0:1]
	v_pk_mul_f32 v[218:219], v[226:227], v[0:1]
	v_pk_mul_f32 v[220:221], v[228:229], v[0:1]
	v_pk_mul_f32 v[222:223], v[230:231], v[0:1]
	v_cvt_pk_f32_fp8_sdwa v[224:225], v144 src0_sel:WORD_1
	v_cvt_pk_f32_fp8_sdwa v[226:227], v148 src0_sel:WORD_1
	v_cvt_pk_f32_fp8_sdwa v[228:229], v152 src0_sel:WORD_1
	v_cvt_pk_f32_fp8_sdwa v[230:231], v156 src0_sel:WORD_1
	v_pk_fma_f32 v[216:217], v[224:225], v[2:3], v[216:217]
	v_pk_fma_f32 v[218:219], v[226:227], v[2:3], v[218:219]
	v_pk_fma_f32 v[220:221], v[228:229], v[2:3], v[220:221]
	v_pk_fma_f32 v[222:223], v[230:231], v[2:3], v[222:223]
	v_cvt_pk_f32_fp8_e32 v[224:225], v145
	v_cvt_pk_f32_fp8_e32 v[226:227], v149
	v_cvt_pk_f32_fp8_e32 v[228:229], v153
	v_cvt_pk_f32_fp8_e32 v[230:231], v157
	v_pk_fma_f32 v[216:217], v[224:225], v[4:5], v[216:217]
	v_pk_fma_f32 v[218:219], v[226:227], v[4:5], v[218:219]
	v_pk_fma_f32 v[220:221], v[228:229], v[4:5], v[220:221]
	v_pk_fma_f32 v[222:223], v[230:231], v[4:5], v[222:223]
	v_cvt_pk_f32_fp8_sdwa v[224:225], v145 src0_sel:WORD_1
	v_cvt_pk_f32_fp8_sdwa v[226:227], v149 src0_sel:WORD_1
	v_cvt_pk_f32_fp8_sdwa v[228:229], v153 src0_sel:WORD_1
	v_cvt_pk_f32_fp8_sdwa v[230:231], v157 src0_sel:WORD_1
	v_pk_fma_f32 v[216:217], v[224:225], v[6:7], v[216:217]
	v_pk_fma_f32 v[218:219], v[226:227], v[6:7], v[218:219]
	v_pk_fma_f32 v[220:221], v[228:229], v[6:7], v[220:221]
	v_pk_fma_f32 v[222:223], v[230:231], v[6:7], v[222:223]
	v_cvt_pk_f32_fp8_e32 v[224:225], v146
	v_cvt_pk_f32_fp8_e32 v[226:227], v150
	v_cvt_pk_f32_fp8_e32 v[228:229], v154
	v_cvt_pk_f32_fp8_e32 v[230:231], v158
	v_pk_fma_f32 v[216:217], v[224:225], v[8:9], v[216:217]
	v_pk_fma_f32 v[218:219], v[226:227], v[8:9], v[218:219]
	v_pk_fma_f32 v[220:221], v[228:229], v[8:9], v[220:221]
	v_pk_fma_f32 v[222:223], v[230:231], v[8:9], v[222:223]
	v_cvt_pk_f32_fp8_sdwa v[224:225], v146 src0_sel:WORD_1
	v_cvt_pk_f32_fp8_sdwa v[226:227], v150 src0_sel:WORD_1
	v_cvt_pk_f32_fp8_sdwa v[228:229], v154 src0_sel:WORD_1
	v_cvt_pk_f32_fp8_sdwa v[230:231], v158 src0_sel:WORD_1
	v_pk_fma_f32 v[216:217], v[224:225], v[10:11], v[216:217]
	v_pk_fma_f32 v[218:219], v[226:227], v[10:11], v[218:219]
	v_pk_fma_f32 v[220:221], v[228:229], v[10:11], v[220:221]
	v_pk_fma_f32 v[222:223], v[230:231], v[10:11], v[222:223]
	v_cvt_pk_f32_fp8_e32 v[224:225], v147
	v_cvt_pk_f32_fp8_e32 v[226:227], v151
	v_cvt_pk_f32_fp8_e32 v[228:229], v155
	v_cvt_pk_f32_fp8_e32 v[230:231], v159
	v_pk_fma_f32 v[216:217], v[224:225], v[12:13], v[216:217]
	v_pk_fma_f32 v[218:219], v[226:227], v[12:13], v[218:219]
	v_pk_fma_f32 v[220:221], v[228:229], v[12:13], v[220:221]
	v_pk_fma_f32 v[222:223], v[230:231], v[12:13], v[222:223]
	v_cvt_pk_f32_fp8_sdwa v[224:225], v147 src0_sel:WORD_1
	v_cvt_pk_f32_fp8_sdwa v[226:227], v151 src0_sel:WORD_1
	v_cvt_pk_f32_fp8_sdwa v[228:229], v155 src0_sel:WORD_1
	v_cvt_pk_f32_fp8_sdwa v[230:231], v159 src0_sel:WORD_1
	v_pk_fma_f32 v[216:217], v[224:225], v[14:15], v[216:217]
	v_pk_fma_f32 v[218:219], v[226:227], v[14:15], v[218:219]
	v_pk_fma_f32 v[220:221], v[228:229], v[14:15], v[220:221]
	v_pk_fma_f32 v[222:223], v[230:231], v[14:15], v[222:223]
	v_add_f32_e32 v196, v216, v217
	v_add_f32_e32 v197, v218, v219
	v_add_f32_e32 v198, v220, v221
	v_add_f32_e32 v199, v222, v223
	s_sub_i32 s90, s90, 1
	s_cmp_eq_u32 s90, 0
	s_cbranch_scc1 .LU_sw2
.LU_t0_s2:
	s_waitcnt lgkmcnt(0)
	buffer_load_dwordx4 v[144:147], v[232:233], s[56:59], 0 idxen offen
	buffer_load_dwordx4 v[148:151], v[234:235], s[56:59], 0 idxen offen
	buffer_load_dwordx4 v[152:155], v[236:237], s[56:59], 0 idxen offen
	buffer_load_dwordx4 v[156:159], v[238:239], s[56:59], 0 idxen offen
	ds_read_b32 v232, v213 offset:96
	ds_read_b32 v234, v213 offset:100
	ds_read_b32 v236, v213 offset:104
	ds_read_b32 v238, v213 offset:108
	s_waitcnt vmcnt(13)
	v_cvt_pk_f32_fp8_e32 v[224:225], v160
	v_cvt_pk_f32_fp8_e32 v[226:227], v164
	v_cvt_pk_f32_fp8_e32 v[228:229], v168
	v_cvt_pk_f32_fp8_e32 v[230:231], v172
	v_pk_mul_f32 v[216:217], v[224:225], v[0:1]
	v_pk_mul_f32 v[218:219], v[226:227], v[0:1]
	v_pk_mul_f32 v[220:221], v[228:229], v[0:1]
	v_pk_mul_f32 v[222:223], v[230:231], v[0:1]
	v_cvt_pk_f32_fp8_sdwa v[224:225], v160 src0_sel:WORD_1
	v_cvt_pk_f32_fp8_sdwa v[226:227], v164 src0_sel:WORD_1
	v_cvt_pk_f32_fp8_sdwa v[228:229], v168 src0_sel:WORD_1
	v_cvt_pk_f32_fp8_sdwa v[230:231], v172 src0_sel:WORD_1
	v_pk_fma_f32 v[216:217], v[224:225], v[2:3], v[216:217]
	v_pk_fma_f32 v[218:219], v[226:227], v[2:3], v[218:219]
	v_pk_fma_f32 v[220:221], v[228:229], v[2:3], v[220:221]
	v_pk_fma_f32 v[222:223], v[230:231], v[2:3], v[222:223]
	v_cvt_pk_f32_fp8_e32 v[224:225], v161
	v_cvt_pk_f32_fp8_e32 v[226:227], v165
	v_cvt_pk_f32_fp8_e32 v[228:229], v169
	v_cvt_pk_f32_fp8_e32 v[230:231], v173
	v_pk_fma_f32 v[216:217], v[224:225], v[4:5], v[216:217]
	v_pk_fma_f32 v[218:219], v[226:227], v[4:5], v[218:219]
	v_pk_fma_f32 v[220:221], v[228:229], v[4:5], v[220:221]
	v_pk_fma_f32 v[222:223], v[230:231], v[4:5], v[222:223]
	v_cvt_pk_f32_fp8_sdwa v[224:225], v161 src0_sel:WORD_1
	v_cvt_pk_f32_fp8_sdwa v[226:227], v165 src0_sel:WORD_1
	v_cvt_pk_f32_fp8_sdwa v[228:229], v169 src0_sel:WORD_1
	v_cvt_pk_f32_fp8_sdwa v[230:231], v173 src0_sel:WORD_1
	v_pk_fma_f32 v[216:217], v[224:225], v[6:7], v[216:217]
	v_pk_fma_f32 v[218:219], v[226:227], v[6:7], v[218:219]
	v_pk_fma_f32 v[220:221], v[228:229], v[6:7], v[220:221]
	v_pk_fma_f32 v[222:223], v[230:231], v[6:7], v[222:223]
	v_cvt_pk_f32_fp8_e32 v[224:225], v162
	v_cvt_pk_f32_fp8_e32 v[226:227], v166
	v_cvt_pk_f32_fp8_e32 v[228:229], v170
	v_cvt_pk_f32_fp8_e32 v[230:231], v174
	v_pk_fma_f32 v[216:217], v[224:225], v[8:9], v[216:217]
	v_pk_fma_f32 v[218:219], v[226:227], v[8:9], v[218:219]
	v_pk_fma_f32 v[220:221], v[228:229], v[8:9], v[220:221]
	v_pk_fma_f32 v[222:223], v[230:231], v[8:9], v[222:223]
	v_cvt_pk_f32_fp8_sdwa v[224:225], v162 src0_sel:WORD_1
	v_cvt_pk_f32_fp8_sdwa v[226:227], v166 src0_sel:WORD_1
	v_cvt_pk_f32_fp8_sdwa v[228:229], v170 src0_sel:WORD_1
	v_cvt_pk_f32_fp8_sdwa v[230:231], v174 src0_sel:WORD_1
	v_pk_fma_f32 v[216:217], v[224:225], v[10:11], v[216:217]
	v_pk_fma_f32 v[218:219], v[226:227], v[10:11], v[218:219]
	v_pk_fma_f32 v[220:221], v[228:229], v[10:11], v[220:221]
	v_pk_fma_f32 v[222:223], v[230:231], v[10:11], v[222:223]
	v_cvt_pk_f32_fp8_e32 v[224:225], v163
	v_cvt_pk_f32_fp8_e32 v[226:227], v167
	v_cvt_pk_f32_fp8_e32 v[228:229], v171
	v_cvt_pk_f32_fp8_e32 v[230:231], v175
	v_pk_fma_f32 v[216:217], v[224:225], v[12:13], v[216:217]
	v_pk_fma_f32 v[218:219], v[226:227], v[12:13], v[218:219]
	v_pk_fma_f32 v[220:221], v[228:229], v[12:13], v[220:221]
	v_pk_fma_f32 v[222:223], v[230:231], v[12:13], v[222:223]
	v_cvt_pk_f32_fp8_sdwa v[224:225], v163 src0_sel:WORD_1
	v_cvt_pk_f32_fp8_sdwa v[226:227], v167 src0_sel:WORD_1
	v_cvt_pk_f32_fp8_sdwa v[228:229], v171 src0_sel:WORD_1
	v_cvt_pk_f32_fp8_sdwa v[230:231], v175 src0_sel:WORD_1
	v_pk_fma_f32 v[216:217], v[224:225], v[14:15], v[216:217]
	v_pk_fma_f32 v[218:219], v[226:227], v[14:15], v[218:219]
	v_pk_fma_f32 v[220:221], v[228:229], v[14:15], v[220:221]
	v_pk_fma_f32 v[222:223], v[230:231], v[14:15], v[222:223]
	v_add_f32_e32 v200, v216, v217
	v_add_f32_e32 v201, v218, v219
	v_add_f32_e32 v202, v220, v221
	v_add_f32_e32 v203, v222, v223
	s_sub_i32 s90, s90, 1
	s_cmp_eq_u32 s90, 0
	s_cbranch_scc1 .LU_sw3

; __device__ __forceinline__ float bflo(unsigned u) { return __uint_as_float(u << 16); }
; __device__ __forceinline__ float bfhi(unsigned u) { return __uint_as_float(u & 0xffff0000u); }
; #define IT_ADVANCE() do { it_j += 4; while (it_j >= it_end) { if (it_done) break; ++it_tk; if (it_tk == 4) { it_tk = 0; ++it_p; if (it_p == 16) { it_done = true; it_p = 15; it_j = 0; it_end = 1; break; } } \
;             it_j = __builtin_amdgcn_readfirstlane(OFFS[(tb + it_tk) * 17 + it_p]); it_end = __builtin_amdgcn_readfirstlane(OFFS[(tb + it_tk) * 17 + it_p + 1]); } } while (0)
; __device__ __forceinline__ void peer_tile(const Args& A, LAS unsigned char* lds, int tile) {
;     ...
;         u32x4 uA[4], vA[4], uB[4], vB[4]; float cgA = 0.f, suA = 0.f, svA = 0.f, cgB = 0.f, suB = 0.f, svB = 0.f;
; #pragma unroll
;         for (int k = 0; k < 4; ++k) { uA[k] = (u32x4){0u, 0u, 0u, 0u}; vA[k] = uA[k]; uB[k] = uA[k]; vB[k] = uA[k]; }
;         IT_ADVANCE();
;         LOAD_SET(uA, vA, cgA, suA, svA);
;         for (int p = 0; p < 16; ++p) {
; #pragma unroll
;             for (int tk = 0; tk < 4; ++tk) {
;                 const int tl = tb + tk;
;                 const int beg = __builtin_amdgcn_readfirstlane(OFFS[tl * 17 + p]), end = __builtin_amdgcn_readfirstlane(OFFS[tl * 17 + p + 1]);
;                 f32x2 xf[8];
;                 { const unsigned xx[8] = {xpa[tk].x, xpa[tk].y, xpa[tk].z, xpa[tk].w, xpb[tk].x, xpb[tk].y, xpb[tk].z, xpb[tk].w};
; #pragma unroll
;                   for (int q = 0; q < 8; ++q) xf[q] = (f32x2){bflo(xx[q]), bfhi(xx[q])}; }
.LU_t1_s0:
	s_cmp_ge_u32 s21, s20
	s_cbranch_scc1 .LU_done
	s_waitcnt lgkmcnt(0)
	v_lshlrev_b32_e32 v208, 3, v248
	buffer_load_dwordx2 v[252:253], v208, s[24:27], 0 offen
	buffer_load_dwordx4 v[176:179], v[232:233], s[56:59], 0 idxen offen
	buffer_load_dwordx4 v[180:183], v[234:235], s[56:59], 0 idxen offen
	buffer_load_dwordx4 v[184:187], v[236:237], s[56:59], 0 idxen offen
	buffer_load_dwordx4 v[188:191], v[238:239], s[56:59], 0 idxen offen
	ds_read_b32 v232, v213 offset:64
	ds_read_b32 v234, v213 offset:68
	ds_read_b32 v236, v213 offset:72
	ds_read_b32 v238, v213 offset:76
	s_waitcnt vmcnt(13)
	v_cvt_pk_f32_fp8_e32 v[224:225], v128
	v_cvt_pk_f32_fp8_e32 v[226:227], v132
	v_cvt_pk_f32_fp8_e32 v[228:229], v136
	v_cvt_pk_f32_fp8_e32 v[230:231], v140
	v_pk_mul_f32 v[216:217], v[224:225], v[16:17]
	v_pk_mul_f32 v[218:219], v[226:227], v[16:17]
	v_pk_mul_f32 v[220:221], v[228:229], v[16:17]
	v_pk_mul_f32 v[222:223], v[230:231], v[16:17]
	v_cvt_pk_f32_fp8_sdwa v[224:225], v128 src0_sel:WORD_1
	v_cvt_pk_f32_fp8_sdwa v[226:227], v132 src0_sel:WORD_1
	v_cvt_pk_f32_fp8_sdwa v[228:229], v136 src0_sel:WORD_1
	v_cvt_pk_f32_fp8_sdwa v[230:231], v140 src0_sel:WORD_1
	v_pk_fma_f32 v[216:217], v[224:225], v[18:19], v[216:217]
	v_pk_fma_f32 v[218:219], v[226:227], v[18:19], v[218:219]
	v_pk_fma_f32 v[220:221], v[228:229], v[18:19], v[220:221]
	v_pk_fma_f32 v[222:223], v[230:231], v[18:19], v[222:223]
	v_cvt_pk_f32_fp8_e32 v[224:225], v129
	v_cvt_pk_f32_fp8_e32 v[226:227], v133
	v_cvt_pk_f32_fp8_e32 v[228:229], v137
	v_cvt_pk_f32_fp8_e32 v[230:231], v141
	v_pk_fma_f32 v[216:217], v[224:225], v[20:21], v[216:217]
	v_pk_fma_f32 v[218:219], v[226:227], v[20:21], v[218:219]
	v_pk_fma_f32 v[220:221], v[228:229], v[20:21], v[220:221]
	v_pk_fma_f32 v[222:223], v[230:231], v[20:21], v[222:223]
	v_cvt_pk_f32_fp8_sdwa v[224:225], v129 src0_sel:WORD_1
	v_cvt_pk_f32_fp8_sdwa v[226:227], v133 src0_sel:WORD_1
	v_cvt_pk_f32_fp8_sdwa v[228:229], v137 src0_sel:WORD_1
	v_cvt_pk_f32_fp8_sdwa v[230:231], v141 src0_sel:WORD_1
	v_pk_fma_f32 v[216:217], v[224:225], v[22:23], v[216:217]
	v_pk_fma_f32 v[218:219], v[226:227], v[22:23], v[218:219]
	v_pk_fma_f32 v[220:221], v[228:229], v[22:23], v[220:221]
	v_pk_fma_f32 v[222:223], v[230:231], v[22:23], v[222:223]
	v_cvt_pk_f32_fp8_e32 v[224:225], v130
	v_cvt_pk_f32_fp8_e32 v[226:227], v134
	v_cvt_pk_f32_fp8_e32 v[228:229], v138
	v_cvt_pk_f32_fp8_e32 v[230:231], v142
	v_pk_fma_f32 v[216:217], v[224:225], v[24:25], v[216:217]
	v_pk_fma_f32 v[218:219], v[226:227], v[24:25], v[218:219]
	v_pk_fma_f32 v[220:221], v[228:229], v[24:25], v[220:221]
	v_pk_fma_f32 v[222:223], v[230:231], v[24:25], v[222:223]
	v_cvt_pk_f32_fp8_sdwa v[224:225], v130 src0_sel:WORD_1
	v_cvt_pk_f32_fp8_sdwa v[226:227], v134 src0_sel:WORD_1
	v_cvt_pk_f32_fp8_sdwa v[228:229], v138 src0_sel:WORD_1
	v_cvt_pk_f32_fp8_sdwa v[230:231], v142 src0_sel:WORD_1
	v_pk_fma_f32 v[216:217], v[224:225], v[26:27], v[216:217]
	v_pk_fma_f32 v[218:219], v[226:227], v[26:27], v[218:219]
	v_pk_fma_f32 v[220:221], v[228:229], v[26:27], v[220:221]
	v_pk_fma_f32 v[222:223], v[230:231], v[26:27], v[222:223]
	v_cvt_pk_f32_fp8_e32 v[224:225], v131
	v_cvt_pk_f32_fp8_e32 v[226:227], v135
	v_cvt_pk_f32_fp8_e32 v[228:229], v139
	v_cvt_pk_f32_fp8_e32 v[230:231], v143
	v_pk_fma_f32 v[216:217], v[224:225], v[28:29], v[216:217]
	v_pk_fma_f32 v[218:219], v[226:227], v[28:29], v[218:219]
	v_pk_fma_f32 v[220:221], v[228:229], v[28:29], v[220:221]
	v_pk_fma_f32 v[222:223], v[230:231], v[28:29], v[222:223]
	v_cvt_pk_f32_fp8_sdwa v[224:225], v131 src0_sel:WORD_1
	v_cvt_pk_f32_fp8_sdwa v[226:227], v135 src0_sel:WORD_1
	v_cvt_pk_f32_fp8_sdwa v[228:229], v139 src0_sel:WORD_1
	v_cvt_pk_f32_fp8_sdwa v[230:231], v143 src0_sel:WORD_1
	v_pk_fma_f32 v[216:217], v[224:225], v[30:31], v[216:217]
	v_pk_fma_f32 v[218:219], v[226:227], v[30:31], v[218:219]
	v_pk_fma_f32 v[220:221], v[228:229], v[30:31], v[220:221]
	v_pk_fma_f32 v[222:223], v[230:231], v[30:31], v[222:223]
	v_add_f32_e32 v192, v216, v217
	v_add_f32_e32 v193, v218, v219
	v_add_f32_e32 v194, v220, v221
	v_add_f32_e32 v195, v222, v223
	s_sub_i32 s90, s90, 1
	s_cmp_eq_u32 s90, 0
	s_cbranch_scc1 .LU_sw1
.LU_t1_s1:
	s_waitcnt lgkmcnt(0)
	buffer_load_dwordx4 v[128:131], v[232:233], s[56:59], 0 idxen offen
	buffer_load_dwordx4 v[132:135], v[234:235], s[56:59], 0 idxen offen
	buffer_load_dwordx4 v[136:139], v[236:237], s[56:59], 0 idxen offen
	buffer_load_dwordx4 v[140:143], v[238:239], s[56:59], 0 idxen offen
	ds_read_b32 v232, v213 offset:80
	ds_read_b32 v234, v213 offset:84
	ds_read_b32 v236, v213 offset:88
	ds_read_b32 v238, v213 offset:92
	s_waitcnt vmcnt(13)
	v_cvt_pk_f32_fp8_e32 v[224:225], v144
	v_cvt_pk_f32_fp8_e32 v[226:227], v148
	v_cvt_pk_f32_fp8_e32 v[228:229], v152
	v_cvt_pk_f32_fp8_e32 v[230:231], v156
	v_pk_mul_f32 v[216:217], v[224:225], v[16:17]
	v_pk_mul_f32 v[218:219], v[226:227], v[16:17]
	v_pk_mul_f32 v[220:221], v[228:229], v[16:17]
	v_pk_mul_f32 v[222:223], v[230:231], v[16:17]
	v_cvt_pk_f32_fp8_sdwa v[224:225], v144 src0_sel:WORD_1
	v_cvt_pk_f32_fp8_sdwa v[226:227], v148 src0_sel:WORD_1
	v_cvt_pk_f32_fp8_sdwa v[228:229], v152 src0_sel:WORD_1
	v_cvt_pk_f32_fp8_sdwa v[230:231], v156 src0_sel:WORD_1
	v_pk_fma_f32 v[216:217], v[224:225], v[18:19], v[216:217]
	v_pk_fma_f32 v[218:219], v[226:227], v[18:19], v[218:219]
	v_pk_fma_f32 v[220:221], v[228:229], v[18:19], v[220:221]
	v_pk_fma_f32 v[222:223], v[230:231], v[18:19], v[222:223]
	v_cvt_pk_f32_fp8_e32 v[224:225], v145
	v_cvt_pk_f32_fp8_e32 v[226:227], v149
	v_cvt_pk_f32_fp8_e32 v[228:229], v153
	v_cvt_pk_f32_fp8_e32 v[230:231], v157
	v_pk_fma_f32 v[216:217], v[224:225], v[20:21], v[216:217]
	v_pk_fma_f32 v[218:219], v[226:227], v[20:21], v[218:219]
	v_pk_fma_f32 v[220:221], v[228:229], v[20:21], v[220:221]
	v_pk_fma_f32 v[222:223], v[230:231], v[20:21], v[222:223]
	v_cvt_pk_f32_fp8_sdwa v[224:225], v145 src0_sel:WORD_1
	v_cvt_pk_f32_fp8_sdwa v[226:227], v149 src0_sel:WORD_1
	v_cvt_pk_f32_fp8_sdwa v[228:229], v153 src0_sel:WORD_1
	v_cvt_pk_f32_fp8_sdwa v[230:231], v157 src0_sel:WORD_1
	v_pk_fma_f32 v[216:217], v[224:225], v[22:23], v[216:217]
	v_pk_fma_f32 v[218:219], v[226:227], v[22:23], v[218:219]
	v_pk_fma_f32 v[220:221], v[228:229], v[22:23], v[220:221]
	v_pk_fma_f32 v[222:223], v[230:231], v[22:23], v[222:223]
	v_cvt_pk_f32_fp8_e32 v[224:225], v146
	v_cvt_pk_f32_fp8_e32 v[226:227], v150
	v_cvt_pk_f32_fp8_e32 v[228:229], v154
	v_cvt_pk_f32_fp8_e32 v[230:231], v158
	v_pk_fma_f32 v[216:217], v[224:225], v[24:25], v[216:217]
	v_pk_fma_f32 v[218:219], v[226:227], v[24:25], v[218:219]
	v_pk_fma_f32 v[220:221], v[228:229], v[24:25], v[220:221]
	v_pk_fma_f32 v[222:223], v[230:231], v[24:25], v[222:223]
	v_cvt_pk_f32_fp8_sdwa v[224:225], v146 src0_sel:WORD_1
	v_cvt_pk_f32_fp8_sdwa v[226:227], v150 src0_sel:WORD_1
	v_cvt_pk_f32_fp8_sdwa v[228:229], v154 src0_sel:WORD_1
	v_cvt_pk_f32_fp8_sdwa v[230:231], v158 src0_sel:WORD_1
	v_pk_fma_f32 v[216:217], v[224:225], v[26:27], v[216:217]
	v_pk_fma_f32 v[218:219], v[226:227], v[26:27], v[218:219]
	v_pk_fma_f32 v[220:221], v[228:229], v[26:27], v[220:221]
	v_pk_fma_f32 v[222:223], v[230:231], v[26:27], v[222:223]
	v_cvt_pk_f32_fp8_e32 v[224:225], v147
	v_cvt_pk_f32_fp8_e32 v[226:227], v151
	v_cvt_pk_f32_fp8_e32 v[228:229], v155
	v_cvt_pk_f32_fp8_e32 v[230:231], v159
	v_pk_fma_f32 v[216:217], v[224:225], v[28:29], v[216:217]
	v_pk_fma_f32 v[218:219], v[226:227], v[28:29], v[218:219]
	v_pk_fma_f32 v[220:221], v[228:229], v[28:29], v[220:221]
	v_pk_fma_f32 v[222:223], v[230:231], v[28:29], v[222:223]
	v_cvt_pk_f32_fp8_sdwa v[224:225], v147 src0_sel:WORD_1
	v_cvt_pk_f32_fp8_sdwa v[226:227], v151 src0_sel:WORD_1
	v_cvt_pk_f32_fp8_sdwa v[228:229], v155 src0_sel:WORD_1
	v_cvt_pk_f32_fp8_sdwa v[230:231], v159 src0_sel:WORD_1
	v_pk_fma_f32 v[216:217], v[224:225], v[30:31], v[216:217]
	v_pk_fma_f32 v[218:219], v[226:227], v[30:31], v[218:219]
	v_pk_fma_f32 v[220:221], v[228:229], v[30:31], v[220:221]
	v_pk_fma_f32 v[222:223], v[230:231], v[30:31], v[222:223]
	v_add_f32_e32 v196, v216, v217
	v_add_f32_e32 v197, v218, v219
	v_add_f32_e32 v198, v220, v221
	v_add_f32_e32 v199, v222, v223
	s_sub_i32 s90, s90, 1
	s_cmp_eq_u32 s90, 0
	s_cbranch_scc1 .LU_sw2
.LU_t1_s2:
	s_waitcnt lgkmcnt(0)
	buffer_load_dwordx4 v[144:147], v[232:233], s[56:59], 0 idxen offen
	buffer_load_dwordx4 v[148:151], v[234:235], s[56:59], 0 idxen offen
	buffer_load_dwordx4 v[152:155], v[236:237], s[56:59], 0 idxen offen
	buffer_load_dwordx4 v[156:159], v[238:239], s[56:59], 0 idxen offen
	ds_read_b32 v232, v213 offset:96
	ds_read_b32 v234, v213 offset:100
	ds_read_b32 v236, v213 offset:104
	ds_read_b32 v238, v213 offset:108
	s_waitcnt vmcnt(13)
	v_cvt_pk_f32_fp8_e32 v[224:225], v160
	v_cvt_pk_f32_fp8_e32 v[226:227], v164
	v_cvt_pk_f32_fp8_e32 v[228:229], v168
	v_cvt_pk_f32_fp8_e32 v[230:231], v172
	v_pk_mul_f32 v[216:217], v[224:225], v[16:17]
	v_pk_mul_f32 v[218:219], v[226:227], v[16:17]
	v_pk_mul_f32 v[220:221], v[228:229], v[16:17]
	v_pk_mul_f32 v[222:223], v[230:231], v[16:17]
	v_cvt_pk_f32_fp8_sdwa v[224:225], v160 src0_sel:WORD_1
	v_cvt_pk_f32_fp8_sdwa v[226:227], v164 src0_sel:WORD_1
	v_cvt_pk_f32_fp8_sdwa v[228:229], v168 src0_sel:WORD_1
	v_cvt_pk_f32_fp8_sdwa v[230:231], v172 src0_sel:WORD_1
	v_pk_fma_f32 v[216:217], v[224:225], v[18:19], v[216:217]
	v_pk_fma_f32 v[218:219], v[226:227], v[18:19], v[218:219]
	v_pk_fma_f32 v[220:221], v[228:229], v[18:19], v[220:221]
	v_pk_fma_f32 v[222:223], v[230:231], v[18:19], v[222:223]
	v_cvt_pk_f32_fp8_e32 v[224:225], v161
	v_cvt_pk_f32_fp8_e32 v[226:227], v165
	v_cvt_pk_f32_fp8_e32 v[228:229], v169
	v_cvt_pk_f32_fp8_e32 v[230:231], v173
	v_pk_fma_f32 v[216:217], v[224:225], v[20:21], v[216:217]
	v_pk_fma_f32 v[218:219], v[226:227], v[20:21], v[218:219]
	v_pk_fma_f32 v[220:221], v[228:229], v[20:21], v[220:221]
	v_pk_fma_f32 v[222:223], v[230:231], v[20:21], v[222:223]
	v_cvt_pk_f32_fp8_sdwa v[224:225], v161 src0_sel:WORD_1
	v_cvt_pk_f32_fp8_sdwa v[226:227], v165 src0_sel:WORD_1
	v_cvt_pk_f32_fp8_sdwa v[228:229], v169 src0_sel:WORD_1
	v_cvt_pk_f32_fp8_sdwa v[230:231], v173 src0_sel:WORD_1
	v_pk_fma_f32 v[216:217], v[224:225], v[22:23], v[216:217]
	v_pk_fma_f32 v[218:219], v[226:227], v[22:23], v[218:219]
	v_pk_fma_f32 v[220:221], v[228:229], v[22:23], v[220:221]
	v_pk_fma_f32 v[222:223], v[230:231], v[22:23], v[222:223]
	v_cvt_pk_f32_fp8_e32 v[224:225], v162
	v_cvt_pk_f32_fp8_e32 v[226:227], v166
	v_cvt_pk_f32_fp8_e32 v[228:229], v170
	v_cvt_pk_f32_fp8_e32 v[230:231], v174
	v_pk_fma_f32 v[216:217], v[224:225], v[24:25], v[216:217]
	v_pk_fma_f32 v[218:219], v[226:227], v[24:25], v[218:219]
	v_pk_fma_f32 v[220:221], v[228:229], v[24:25], v[220:221]
	v_pk_fma_f32 v[222:223], v[230:231], v[24:25], v[222:223]
	v_cvt_pk_f32_fp8_sdwa v[224:225], v162 src0_sel:WORD_1
	v_cvt_pk_f32_fp8_sdwa v[226:227], v166 src0_sel:WORD_1
	v_cvt_pk_f32_fp8_sdwa v[228:229], v170 src0_sel:WORD_1
	v_cvt_pk_f32_fp8_sdwa v[230:231], v174 src0_sel:WORD_1
	v_pk_fma_f32 v[216:217], v[224:225], v[26:27], v[216:217]
	v_pk_fma_f32 v[218:219], v[226:227], v[26:27], v[218:219]
	v_pk_fma_f32 v[220:221], v[228:229], v[26:27], v[220:221]
	v_pk_fma_f32 v[222:223], v[230:231], v[26:27], v[222:223]
	v_cvt_pk_f32_fp8_e32 v[224:225], v163
	v_cvt_pk_f32_fp8_e32 v[226:227], v167
	v_cvt_pk_f32_fp8_e32 v[228:229], v171
	v_cvt_pk_f32_fp8_e32 v[230:231], v175
	v_pk_fma_f32 v[216:217], v[224:225], v[28:29], v[216:217]
	v_pk_fma_f32 v[218:219], v[226:227], v[28:29], v[218:219]
	v_pk_fma_f32 v[220:221], v[228:229], v[28:29], v[220:221]
	v_pk_fma_f32 v[222:223], v[230:231], v[28:29], v[222:223]
	v_cvt_pk_f32_fp8_sdwa v[224:225], v163 src0_sel:WORD_1
	v_cvt_pk_f32_fp8_sdwa v[226:227], v167 src0_sel:WORD_1
	v_cvt_pk_f32_fp8_sdwa v[228:229], v171 src0_sel:WORD_1
	v_cvt_pk_f32_fp8_sdwa v[230:231], v175 src0_sel:WORD_1
	v_pk_fma_f32 v[216:217], v[224:225], v[30:31], v[216:217]
	v_pk_fma_f32 v[218:219], v[226:227], v[30:31], v[218:219]
	v_pk_fma_f32 v[220:221], v[228:229], v[30:31], v[220:221]
	v_pk_fma_f32 v[222:223], v[230:231], v[30:31], v[222:223]
	v_add_f32_e32 v200, v216, v217
	v_add_f32_e32 v201, v218, v219
	v_add_f32_e32 v202, v220, v221
	v_add_f32_e32 v203, v222, v223
	s_sub_i32 s90, s90, 1
	s_cmp_eq_u32 s90, 0
	s_cbranch_scc1 .LU_sw3

.LU_t2_s0:
	s_cmp_ge_u32 s21, s20
	s_cbranch_scc1 .LU_done
	s_waitcnt lgkmcnt(0)
	v_lshlrev_b32_e32 v208, 3, v248
	buffer_load_dwordx2 v[252:253], v208, s[24:27], 0 offen
	buffer_load_dwordx4 v[176:179], v[232:233], s[56:59], 0 idxen offen
	buffer_load_dwordx4 v[180:183], v[234:235], s[56:59], 0 idxen offen
	buffer_load_dwordx4 v[184:187], v[236:237], s[56:59], 0 idxen offen
	buffer_load_dwordx4 v[188:191], v[238:239], s[56:59], 0 idxen offen
	ds_read_b32 v232, v213 offset:64
	ds_read_b32 v234, v213 offset:68
	ds_read_b32 v236, v213 offset:72
	ds_read_b32 v238, v213 offset:76
	s_waitcnt vmcnt(13)
	v_cvt_pk_f32_fp8_e32 v[224:225], v128
	v_cvt_pk_f32_fp8_e32 v[226:227], v132
	v_cvt_pk_f32_fp8_e32 v[228:229], v136
	v_cvt_pk_f32_fp8_e32 v[230:231], v140
	v_pk_mul_f32 v[216:217], v[224:225], v[32:33]
	v_pk_mul_f32 v[218:219], v[226:227], v[32:33]
	v_pk_mul_f32 v[220:221], v[228:229], v[32:33]
	v_pk_mul_f32 v[222:223], v[230:231], v[32:33]
	v_cvt_pk_f32_fp8_sdwa v[224:225], v128 src0_sel:WORD_1
	v_cvt_pk_f32_fp8_sdwa v[226:227], v132 src0_sel:WORD_1
	v_cvt_pk_f32_fp8_sdwa v[228:229], v136 src0_sel:WORD_1
	v_cvt_pk_f32_fp8_sdwa v[230:231], v140 src0_sel:WORD_1
	v_pk_fma_f32 v[216:217], v[224:225], v[34:35], v[216:217]
	v_pk_fma_f32 v[218:219], v[226:227], v[34:35], v[218:219]
	v_pk_fma_f32 v[220:221], v[228:229], v[34:35], v[220:221]
	v_pk_fma_f32 v[222:223], v[230:231], v[34:35], v[222:223]
	v_cvt_pk_f32_fp8_e32 v[224:225], v129
	v_cvt_pk_f32_fp8_e32 v[226:227], v133
	v_cvt_pk_f32_fp8_e32 v[228:229], v137
	v_cvt_pk_f32_fp8_e32 v[230:231], v141
	v_pk_fma_f32 v[216:217], v[224:225], v[36:37], v[216:217]
	v_pk_fma_f32 v[218:219], v[226:227], v[36:37], v[218:219]
	v_pk_fma_f32 v[220:221], v[228:229], v[36:37], v[220:221]
	v_pk_fma_f32 v[222:223], v[230:231], v[36:37], v[222:223]
	v_cvt_pk_f32_fp8_sdwa v[224:225], v129 src0_sel:WORD_1
	v_cvt_pk_f32_fp8_sdwa v[226:227], v133 src0_sel:WORD_1
	v_cvt_pk_f32_fp8_sdwa v[228:229], v137 src0_sel:WORD_1
	v_cvt_pk_f32_fp8_sdwa v[230:231], v141 src0_sel:WORD_1
	v_pk_fma_f32 v[216:217], v[224:225], v[38:39], v[216:217]
	v_pk_fma_f32 v[218:219], v[226:227], v[38:39], v[218:219]
	v_pk_fma_f32 v[220:221], v[228:229], v[38:39], v[220:221]
	v_pk_fma_f32 v[222:223], v[230:231], v[38:39], v[222:223]
	v_cvt_pk_f32_fp8_e32 v[224:225], v130
	v_cvt_pk_f32_fp8_e32 v[226:227], v134
	v_cvt_pk_f32_fp8_e32 v[228:229], v138
	v_cvt_pk_f32_fp8_e32 v[230:231], v142
	v_pk_fma_f32 v[216:217], v[224:225], v[40:41], v[216:217]
	v_pk_fma_f32 v[218:219], v[226:227], v[40:41], v[218:219]
	v_pk_fma_f32 v[220:221], v[228:229], v[40:41], v[220:221]
	v_pk_fma_f32 v[222:223], v[230:231], v[40:41], v[222:223]
	v_cvt_pk_f32_fp8_sdwa v[224:225], v130 src0_sel:WORD_1
	v_cvt_pk_f32_fp8_sdwa v[226:227], v134 src0_sel:WORD_1
	v_cvt_pk_f32_fp8_sdwa v[228:229], v138 src0_sel:WORD_1
	v_cvt_pk_f32_fp8_sdwa v[230:231], v142 src0_sel:WORD_1
	v_pk_fma_f32 v[216:217], v[224:225], v[42:43], v[216:217]
	v_pk_fma_f32 v[218:219], v[226:227], v[42:43], v[218:219]
	v_pk_fma_f32 v[220:221], v[228:229], v[42:43], v[220:221]
	v_pk_fma_f32 v[222:223], v[230:231], v[42:43], v[222:223]
	v_cvt_pk_f32_fp8_e32 v[224:225], v131
	v_cvt_pk_f32_fp8_e32 v[226:227], v135
	v_cvt_pk_f32_fp8_e32 v[228:229], v139
	v_cvt_pk_f32_fp8_e32 v[230:231], v143
	v_pk_fma_f32 v[216:217], v[224:225], v[44:45], v[216:217]
	v_pk_fma_f32 v[218:219], v[226:227], v[44:45], v[218:219]
	v_pk_fma_f32 v[220:221], v[228:229], v[44:45], v[220:221]
	v_pk_fma_f32 v[222:223], v[230:231], v[44:45], v[222:223]
	v_cvt_pk_f32_fp8_sdwa v[224:225], v131 src0_sel:WORD_1
	v_cvt_pk_f32_fp8_sdwa v[226:227], v135 src0_sel:WORD_1
	v_cvt_pk_f32_fp8_sdwa v[228:229], v139 src0_sel:WORD_1
	v_cvt_pk_f32_fp8_sdwa v[230:231], v143 src0_sel:WORD_1
	v_pk_fma_f32 v[216:217], v[224:225], v[46:47], v[216:217]
	v_pk_fma_f32 v[218:219], v[226:227], v[46:47], v[218:219]
	v_pk_fma_f32 v[220:221], v[228:229], v[46:47], v[220:221]
	v_pk_fma_f32 v[222:223], v[230:231], v[46:47], v[222:223]
	v_add_f32_e32 v192, v216, v217
	v_add_f32_e32 v193, v218, v219
	v_add_f32_e32 v194, v220, v221
	v_add_f32_e32 v195, v222, v223
	s_sub_i32 s90, s90, 1
	s_cmp_eq_u32 s90, 0
	s_cbranch_scc1 .LU_sw1
.LU_t2_s1:
	s_waitcnt lgkmcnt(0)
	buffer_load_dwordx4 v[128:131], v[232:233], s[56:59], 0 idxen offen
	buffer_load_dwordx4 v[132:135], v[234:235], s[56:59], 0 idxen offen
	buffer_load_dwordx4 v[136:139], v[236:237], s[56:59], 0 idxen offen
	buffer_load_dwordx4 v[140:143], v[238:239], s[56:59], 0 idxen offen
	ds_read_b32 v232, v213 offset:80
	ds_read_b32 v234, v213 offset:84
	ds_read_b32 v236, v213 offset:88
	ds_read_b32 v238, v213 offset:92
	s_waitcnt vmcnt(13)
	v_cvt_pk_f32_fp8_e32 v[224:225], v144
	v_cvt_pk_f32_fp8_e32 v[226:227], v148
	v_cvt_pk_f32_fp8_e32 v[228:229], v152
	v_cvt_pk_f32_fp8_e32 v[230:231], v156
	v_pk_mul_f32 v[216:217], v[224:225], v[32:33]
	v_pk_mul_f32 v[218:219], v[226:227], v[32:33]
	v_pk_mul_f32 v[220:221], v[228:229], v[32:33]
	v_pk_mul_f32 v[222:223], v[230:231], v[32:33]
	v_cvt_pk_f32_fp8_sdwa v[224:225], v144 src0_sel:WORD_1
	v_cvt_pk_f32_fp8_sdwa v[226:227], v148 src0_sel:WORD_1
	v_cvt_pk_f32_fp8_sdwa v[228:229], v152 src0_sel:WORD_1
	v_cvt_pk_f32_fp8_sdwa v[230:231], v156 src0_sel:WORD_1
	v_pk_fma_f32 v[216:217], v[224:225], v[34:35], v[216:217]
	v_pk_fma_f32 v[218:219], v[226:227], v[34:35], v[218:219]
	v_pk_fma_f32 v[220:221], v[228:229], v[34:35], v[220:221]
	v_pk_fma_f32 v[222:223], v[230:231], v[34:35], v[222:223]
	v_cvt_pk_f32_fp8_e32 v[224:225], v145
	v_cvt_pk_f32_fp8_e32 v[226:227], v149
	v_cvt_pk_f32_fp8_e32 v[228:229], v153
	v_cvt_pk_f32_fp8_e32 v[230:231], v157
	v_pk_fma_f32 v[216:217], v[224:225], v[36:37], v[216:217]
	v_pk_fma_f32 v[218:219], v[226:227], v[36:37], v[218:219]
	v_pk_fma_f32 v[220:221], v[228:229], v[36:37], v[220:221]
	v_pk_fma_f32 v[222:223], v[230:231], v[36:37], v[222:223]
	v_cvt_pk_f32_fp8_sdwa v[224:225], v145 src0_sel:WORD_1
	v_cvt_pk_f32_fp8_sdwa v[226:227], v149 src0_sel:WORD_1
	v_cvt_pk_f32_fp8_sdwa v[228:229], v153 src0_sel:WORD_1
	v_cvt_pk_f32_fp8_sdwa v[230:231], v157 src0_sel:WORD_1
	v_pk_fma_f32 v[216:217], v[224:225], v[38:39], v[216:217]
	v_pk_fma_f32 v[218:219], v[226:227], v[38:39], v[218:219]
	v_pk_fma_f32 v[220:221], v[228:229], v[38:39], v[220:221]
	v_pk_fma_f32 v[222:223], v[230:231], v[38:39], v[222:223]
	v_cvt_pk_f32_fp8_e32 v[224:225], v146
	v_cvt_pk_f32_fp8_e32 v[226:227], v150
	v_cvt_pk_f32_fp8_e32 v[228:229], v154
	v_cvt_pk_f32_fp8_e32 v[230:231], v158
	v_pk_fma_f32 v[216:217], v[224:225], v[40:41], v[216:217]
	v_pk_fma_f32 v[218:219], v[226:227], v[40:41], v[218:219]
	v_pk_fma_f32 v[220:221], v[228:229], v[40:41], v[220:221]
	v_pk_fma_f32 v[222:223], v[230:231], v[40:41], v[222:223]
	v_cvt_pk_f32_fp8_sdwa v[224:225], v146 src0_sel:WORD_1
	v_cvt_pk_f32_fp8_sdwa v[226:227], v150 src0_sel:WORD_1
	v_cvt_pk_f32_fp8_sdwa v[228:229], v154 src0_sel:WORD_1
	v_cvt_pk_f32_fp8_sdwa v[230:231], v158 src0_sel:WORD_1
	v_pk_fma_f32 v[216:217], v[224:225], v[42:43], v[216:217]
	v_pk_fma_f32 v[218:219], v[226:227], v[42:43], v[218:219]
	v_pk_fma_f32 v[220:221], v[228:229], v[42:43], v[220:221]
	v_pk_fma_f32 v[222:223], v[230:231], v[42:43], v[222:223]
	v_cvt_pk_f32_fp8_e32 v[224:225], v147
	v_cvt_pk_f32_fp8_e32 v[226:227], v151
	v_cvt_pk_f32_fp8_e32 v[228:229], v155
	v_cvt_pk_f32_fp8_e32 v[230:231], v159
	v_pk_fma_f32 v[216:217], v[224:225], v[44:45], v[216:217]
	v_pk_fma_f32 v[218:219], v[226:227], v[44:45], v[218:219]
	v_pk_fma_f32 v[220:221], v[228:229], v[44:45], v[220:221]
	v_pk_fma_f32 v[222:223], v[230:231], v[44:45], v[222:223]
	v_cvt_pk_f32_fp8_sdwa v[224:225], v147 src0_sel:WORD_1
	v_cvt_pk_f32_fp8_sdwa v[226:227], v151 src0_sel:WORD_1
	v_cvt_pk_f32_fp8_sdwa v[228:229], v155 src0_sel:WORD_1
	v_cvt_pk_f32_fp8_sdwa v[230:231], v159 src0_sel:WORD_1
	v_pk_fma_f32 v[216:217], v[224:225], v[46:47], v[216:217]
	v_pk_fma_f32 v[218:219], v[226:227], v[46:47], v[218:219]
	v_pk_fma_f32 v[220:221], v[228:229], v[46:47], v[220:221]
	v_pk_fma_f32 v[222:223], v[230:231], v[46:47], v[222:223]
	v_add_f32_e32 v196, v216, v217
	v_add_f32_e32 v197, v218, v219
	v_add_f32_e32 v198, v220, v221
	v_add_f32_e32 v199, v222, v223
	s_sub_i32 s90, s90, 1
	s_cmp_eq_u32 s90, 0
	s_cbranch_scc1 .LU_sw2
.LU_t2_s2:
	s_waitcnt lgkmcnt(0)
	buffer_load_dwordx4 v[144:147], v[232:233], s[56:59], 0 idxen offen
	buffer_load_dwordx4 v[148:151], v[234:235], s[56:59], 0 idxen offen
	buffer_load_dwordx4 v[152:155], v[236:237], s[56:59], 0 idxen offen
	buffer_load_dwordx4 v[156:159], v[238:239], s[56:59], 0 idxen offen
	ds_read_b32 v232, v213 offset:96
	ds_read_b32 v234, v213 offset:100
	ds_read_b32 v236, v213 offset:104
	ds_read_b32 v238, v213 offset:108
	s_waitcnt vmcnt(13)
	v_cvt_pk_f32_fp8_e32 v[224:225], v160
	v_cvt_pk_f32_fp8_e32 v[226:227], v164
	v_cvt_pk_f32_fp8_e32 v[228:229], v168
	v_cvt_pk_f32_fp8_e32 v[230:231], v172
	v_pk_mul_f32 v[216:217], v[224:225], v[32:33]
	v_pk_mul_f32 v[218:219], v[226:227], v[32:33]
	v_pk_mul_f32 v[220:221], v[228:229], v[32:33]
	v_pk_mul_f32 v[222:223], v[230:231], v[32:33]
	v_cvt_pk_f32_fp8_sdwa v[224:225], v160 src0_sel:WORD_1
	v_cvt_pk_f32_fp8_sdwa v[226:227], v164 src0_sel:WORD_1
	v_cvt_pk_f32_fp8_sdwa v[228:229], v168 src0_sel:WORD_1
	v_cvt_pk_f32_fp8_sdwa v[230:231], v172 src0_sel:WORD_1
	v_pk_fma_f32 v[216:217], v[224:225], v[34:35], v[216:217]
	v_pk_fma_f32 v[218:219], v[226:227], v[34:35], v[218:219]
	v_pk_fma_f32 v[220:221], v[228:229], v[34:35], v[220:221]
	v_pk_fma_f32 v[222:223], v[230:231], v[34:35], v[222:223]
	v_cvt_pk_f32_fp8_e32 v[224:225], v161
	v_cvt_pk_f32_fp8_e32 v[226:227], v165
	v_cvt_pk_f32_fp8_e32 v[228:229], v169
	v_cvt_pk_f32_fp8_e32 v[230:231], v173
	v_pk_fma_f32 v[216:217], v[224:225], v[36:37], v[216:217]
	v_pk_fma_f32 v[218:219], v[226:227], v[36:37], v[218:219]
	v_pk_fma_f32 v[220:221], v[228:229], v[36:37], v[220:221]
	v_pk_fma_f32 v[222:223], v[230:231], v[36:37], v[222:223]
	v_cvt_pk_f32_fp8_sdwa v[224:225], v161 src0_sel:WORD_1
	v_cvt_pk_f32_fp8_sdwa v[226:227], v165 src0_sel:WORD_1
	v_cvt_pk_f32_fp8_sdwa v[228:229], v169 src0_sel:WORD_1
	v_cvt_pk_f32_fp8_sdwa v[230:231], v173 src0_sel:WORD_1
	v_pk_fma_f32 v[216:217], v[224:225], v[38:39], v[216:217]
	v_pk_fma_f32 v[218:219], v[226:227], v[38:39], v[218:219]
	v_pk_fma_f32 v[220:221], v[228:229], v[38:39], v[220:221]
	v_pk_fma_f32 v[222:223], v[230:231], v[38:39], v[222:223]
	v_cvt_pk_f32_fp8_e32 v[224:225], v162
	v_cvt_pk_f32_fp8_e32 v[226:227], v166
	v_cvt_pk_f32_fp8_e32 v[228:229], v170
	v_cvt_pk_f32_fp8_e32 v[230:231], v174
	v_pk_fma_f32 v[216:217], v[224:225], v[40:41], v[216:217]
	v_pk_fma_f32 v[218:219], v[226:227], v[40:41], v[218:219]
	v_pk_fma_f32 v[220:221], v[228:229], v[40:41], v[220:221]
	v_pk_fma_f32 v[222:223], v[230:231], v[40:41], v[222:223]
	v_cvt_pk_f32_fp8_sdwa v[224:225], v162 src0_sel:WORD_1
	v_cvt_pk_f32_fp8_sdwa v[226:227], v166 src0_sel:WORD_1
	v_cvt_pk_f32_fp8_sdwa v[228:229], v170 src0_sel:WORD_1
	v_cvt_pk_f32_fp8_sdwa v[230:231], v174 src0_sel:WORD_1
	v_pk_fma_f32 v[216:217], v[224:225], v[42:43], v[216:217]
	v_pk_fma_f32 v[218:219], v[226:227], v[42:43], v[218:219]
	v_pk_fma_f32 v[220:221], v[228:229], v[42:43], v[220:221]
	v_pk_fma_f32 v[222:223], v[230:231], v[42:43], v[222:223]
	v_cvt_pk_f32_fp8_e32 v[224:225], v163
	v_cvt_pk_f32_fp8_e32 v[226:227], v167
	v_cvt_pk_f32_fp8_e32 v[228:229], v171
	v_cvt_pk_f32_fp8_e32 v[230:231], v175
	v_pk_fma_f32 v[216:217], v[224:225], v[44:45], v[216:217]
	v_pk_fma_f32 v[218:219], v[226:227], v[44:45], v[218:219]
	v_pk_fma_f32 v[220:221], v[228:229], v[44:45], v[220:221]
	v_pk_fma_f32 v[222:223], v[230:231], v[44:45], v[222:223]
	v_cvt_pk_f32_fp8_sdwa v[224:225], v163 src0_sel:WORD_1
	v_cvt_pk_f32_fp8_sdwa v[226:227], v167 src0_sel:WORD_1
	v_cvt_pk_f32_fp8_sdwa v[228:229], v171 src0_sel:WORD_1
	v_cvt_pk_f32_fp8_sdwa v[230:231], v175 src0_sel:WORD_1
	v_pk_fma_f32 v[216:217], v[224:225], v[46:47], v[216:217]
	v_pk_fma_f32 v[218:219], v[226:227], v[46:47], v[218:219]
	v_pk_fma_f32 v[220:221], v[228:229], v[46:47], v[220:221]
	v_pk_fma_f32 v[222:223], v[230:231], v[46:47], v[222:223]
	v_add_f32_e32 v200, v216, v217
	v_add_f32_e32 v201, v218, v219
	v_add_f32_e32 v202, v220, v221
	v_add_f32_e32 v203, v222, v223
	s_sub_i32 s90, s90, 1
	s_cmp_eq_u32 s90, 0
	s_cbranch_scc1 .LU_sw3

.LU_t3_s0:
	s_cmp_ge_u32 s21, s20
	s_cbranch_scc1 .LU_done
	s_waitcnt lgkmcnt(0)
	v_lshlrev_b32_e32 v208, 3, v248
	buffer_load_dwordx2 v[252:253], v208, s[24:27], 0 offen
	buffer_load_dwordx4 v[176:179], v[232:233], s[56:59], 0 idxen offen
	buffer_load_dwordx4 v[180:183], v[234:235], s[56:59], 0 idxen offen
	buffer_load_dwordx4 v[184:187], v[236:237], s[56:59], 0 idxen offen
	buffer_load_dwordx4 v[188:191], v[238:239], s[56:59], 0 idxen offen
	ds_read_b32 v232, v213 offset:64
	ds_read_b32 v234, v213 offset:68
	ds_read_b32 v236, v213 offset:72
	ds_read_b32 v238, v213 offset:76
	s_waitcnt vmcnt(13)
	v_cvt_pk_f32_fp8_e32 v[224:225], v128
	v_cvt_pk_f32_fp8_e32 v[226:227], v132
	v_cvt_pk_f32_fp8_e32 v[228:229], v136
	v_cvt_pk_f32_fp8_e32 v[230:231], v140
	v_pk_mul_f32 v[216:217], v[224:225], v[48:49]
	v_pk_mul_f32 v[218:219], v[226:227], v[48:49]
	v_pk_mul_f32 v[220:221], v[228:229], v[48:49]
	v_pk_mul_f32 v[222:223], v[230:231], v[48:49]
	v_cvt_pk_f32_fp8_sdwa v[224:225], v128 src0_sel:WORD_1
	v_cvt_pk_f32_fp8_sdwa v[226:227], v132 src0_sel:WORD_1
	v_cvt_pk_f32_fp8_sdwa v[228:229], v136 src0_sel:WORD_1
	v_cvt_pk_f32_fp8_sdwa v[230:231], v140 src0_sel:WORD_1
	v_pk_fma_f32 v[216:217], v[224:225], v[50:51], v[216:217]
	v_pk_fma_f32 v[218:219], v[226:227], v[50:51], v[218:219]
	v_pk_fma_f32 v[220:221], v[228:229], v[50:51], v[220:221]
	v_pk_fma_f32 v[222:223], v[230:231], v[50:51], v[222:223]
	v_cvt_pk_f32_fp8_e32 v[224:225], v129
	v_cvt_pk_f32_fp8_e32 v[226:227], v133
	v_cvt_pk_f32_fp8_e32 v[228:229], v137
	v_cvt_pk_f32_fp8_e32 v[230:231], v141
	v_pk_fma_f32 v[216:217], v[224:225], v[52:53], v[216:217]
	v_pk_fma_f32 v[218:219], v[226:227], v[52:53], v[218:219]
	v_pk_fma_f32 v[220:221], v[228:229], v[52:53], v[220:221]
	v_pk_fma_f32 v[222:223], v[230:231], v[52:53], v[222:223]
	v_cvt_pk_f32_fp8_sdwa v[224:225], v129 src0_sel:WORD_1
	v_cvt_pk_f32_fp8_sdwa v[226:227], v133 src0_sel:WORD_1
	v_cvt_pk_f32_fp8_sdwa v[228:229], v137 src0_sel:WORD_1
	v_cvt_pk_f32_fp8_sdwa v[230:231], v141 src0_sel:WORD_1
	v_pk_fma_f32 v[216:217], v[224:225], v[54:55], v[216:217]
	v_pk_fma_f32 v[218:219], v[226:227], v[54:55], v[218:219]
	v_pk_fma_f32 v[220:221], v[228:229], v[54:55], v[220:221]
	v_pk_fma_f32 v[222:223], v[230:231], v[54:55], v[222:223]
	v_cvt_pk_f32_fp8_e32 v[224:225], v130
	v_cvt_pk_f32_fp8_e32 v[226:227], v134
	v_cvt_pk_f32_fp8_e32 v[228:229], v138
	v_cvt_pk_f32_fp8_e32 v[230:231], v142
	v_pk_fma_f32 v[216:217], v[224:225], v[56:57], v[216:217]
	v_pk_fma_f32 v[218:219], v[226:227], v[56:57], v[218:219]
	v_pk_fma_f32 v[220:221], v[228:229], v[56:57], v[220:221]
	v_pk_fma_f32 v[222:223], v[230:231], v[56:57], v[222:223]
	v_cvt_pk_f32_fp8_sdwa v[224:225], v130 src0_sel:WORD_1
	v_cvt_pk_f32_fp8_sdwa v[226:227], v134 src0_sel:WORD_1
	v_cvt_pk_f32_fp8_sdwa v[228:229], v138 src0_sel:WORD_1
	v_cvt_pk_f32_fp8_sdwa v[230:231], v142 src0_sel:WORD_1
	v_pk_fma_f32 v[216:217], v[224:225], v[58:59], v[216:217]
	v_pk_fma_f32 v[218:219], v[226:227], v[58:59], v[218:219]
	v_pk_fma_f32 v[220:221], v[228:229], v[58:59], v[220:221]
	v_pk_fma_f32 v[222:223], v[230:231], v[58:59], v[222:223]
	v_cvt_pk_f32_fp8_e32 v[224:225], v131
	v_cvt_pk_f32_fp8_e32 v[226:227], v135
	v_cvt_pk_f32_fp8_e32 v[228:229], v139
	v_cvt_pk_f32_fp8_e32 v[230:231], v143
	v_pk_fma_f32 v[216:217], v[224:225], v[60:61], v[216:217]
	v_pk_fma_f32 v[218:219], v[226:227], v[60:61], v[218:219]
	v_pk_fma_f32 v[220:221], v[228:229], v[60:61], v[220:221]
	v_pk_fma_f32 v[222:223], v[230:231], v[60:61], v[222:223]
	v_cvt_pk_f32_fp8_sdwa v[224:225], v131 src0_sel:WORD_1
	v_cvt_pk_f32_fp8_sdwa v[226:227], v135 src0_sel:WORD_1
	v_cvt_pk_f32_fp8_sdwa v[228:229], v139 src0_sel:WORD_1
	v_cvt_pk_f32_fp8_sdwa v[230:231], v143 src0_sel:WORD_1
	v_pk_fma_f32 v[216:217], v[224:225], v[62:63], v[216:217]
	v_pk_fma_f32 v[218:219], v[226:227], v[62:63], v[218:219]
	v_pk_fma_f32 v[220:221], v[228:229], v[62:63], v[220:221]
	v_pk_fma_f32 v[222:223], v[230:231], v[62:63], v[222:223]
	v_add_f32_e32 v192, v216, v217
	v_add_f32_e32 v193, v218, v219
	v_add_f32_e32 v194, v220, v221
	v_add_f32_e32 v195, v222, v223
	s_sub_i32 s90, s90, 1
	s_cmp_eq_u32 s90, 0
	s_cbranch_scc1 .LU_sw1
.LU_t3_s1:
	s_waitcnt lgkmcnt(0)
	buffer_load_dwordx4 v[128:131], v[232:233], s[56:59], 0 idxen offen
	buffer_load_dwordx4 v[132:135], v[234:235], s[56:59], 0 idxen offen
	buffer_load_dwordx4 v[136:139], v[236:237], s[56:59], 0 idxen offen
	buffer_load_dwordx4 v[140:143], v[238:239], s[56:59], 0 idxen offen
	ds_read_b32 v232, v213 offset:80
	ds_read_b32 v234, v213 offset:84
	ds_read_b32 v236, v213 offset:88
	ds_read_b32 v238, v213 offset:92
	s_waitcnt vmcnt(13)
	v_cvt_pk_f32_fp8_e32 v[224:225], v144
	v_cvt_pk_f32_fp8_e32 v[226:227], v148
	v_cvt_pk_f32_fp8_e32 v[228:229], v152
	v_cvt_pk_f32_fp8_e32 v[230:231], v156
	v_pk_mul_f32 v[216:217], v[224:225], v[48:49]
	v_pk_mul_f32 v[218:219], v[226:227], v[48:49]
	v_pk_mul_f32 v[220:221], v[228:229], v[48:49]
	v_pk_mul_f32 v[222:223], v[230:231], v[48:49]
	v_cvt_pk_f32_fp8_sdwa v[224:225], v144 src0_sel:WORD_1
	v_cvt_pk_f32_fp8_sdwa v[226:227], v148 src0_sel:WORD_1
	v_cvt_pk_f32_fp8_sdwa v[228:229], v152 src0_sel:WORD_1
	v_cvt_pk_f32_fp8_sdwa v[230:231], v156 src0_sel:WORD_1
	v_pk_fma_f32 v[216:217], v[224:225], v[50:51], v[216:217]
	v_pk_fma_f32 v[218:219], v[226:227], v[50:51], v[218:219]
	v_pk_fma_f32 v[220:221], v[228:229], v[50:51], v[220:221]
	v_pk_fma_f32 v[222:223], v[230:231], v[50:51], v[222:223]
	v_cvt_pk_f32_fp8_e32 v[224:225], v145
	v_cvt_pk_f32_fp8_e32 v[226:227], v149
	v_cvt_pk_f32_fp8_e32 v[228:229], v153
	v_cvt_pk_f32_fp8_e32 v[230:231], v157
	v_pk_fma_f32 v[216:217], v[224:225], v[52:53], v[216:217]
	v_pk_fma_f32 v[218:219], v[226:227], v[52:53], v[218:219]
	v_pk_fma_f32 v[220:221], v[228:229], v[52:53], v[220:221]
	v_pk_fma_f32 v[222:223], v[230:231], v[52:53], v[222:223]
	v_cvt_pk_f32_fp8_sdwa v[224:225], v145 src0_sel:WORD_1
	v_cvt_pk_f32_fp8_sdwa v[226:227], v149 src0_sel:WORD_1
	v_cvt_pk_f32_fp8_sdwa v[228:229], v153 src0_sel:WORD_1
	v_cvt_pk_f32_fp8_sdwa v[230:231], v157 src0_sel:WORD_1
	v_pk_fma_f32 v[216:217], v[224:225], v[54:55], v[216:217]
	v_pk_fma_f32 v[218:219], v[226:227], v[54:55], v[218:219]
	v_pk_fma_f32 v[220:221], v[228:229], v[54:55], v[220:221]
	v_pk_fma_f32 v[222:223], v[230:231], v[54:55], v[222:223]
	v_cvt_pk_f32_fp8_e32 v[224:225], v146
	v_cvt_pk_f32_fp8_e32 v[226:227], v150
	v_cvt_pk_f32_fp8_e32 v[228:229], v154
	v_cvt_pk_f32_fp8_e32 v[230:231], v158
	v_pk_fma_f32 v[216:217], v[224:225], v[56:57], v[216:217]
	v_pk_fma_f32 v[218:219], v[226:227], v[56:57], v[218:219]
	v_pk_fma_f32 v[220:221], v[228:229], v[56:57], v[220:221]
	v_pk_fma_f32 v[222:223], v[230:231], v[56:57], v[222:223]
	v_cvt_pk_f32_fp8_sdwa v[224:225], v146 src0_sel:WORD_1
	v_cvt_pk_f32_fp8_sdwa v[226:227], v150 src0_sel:WORD_1
	v_cvt_pk_f32_fp8_sdwa v[228:229], v154 src0_sel:WORD_1
	v_cvt_pk_f32_fp8_sdwa v[230:231], v158 src0_sel:WORD_1
	v_pk_fma_f32 v[216:217], v[224:225], v[58:59], v[216:217]
	v_pk_fma_f32 v[218:219], v[226:227], v[58:59], v[218:219]
	v_pk_fma_f32 v[220:221], v[228:229], v[58:59], v[220:221]
	v_pk_fma_f32 v[222:223], v[230:231], v[58:59], v[222:223]
	v_cvt_pk_f32_fp8_e32 v[224:225], v147
	v_cvt_pk_f32_fp8_e32 v[226:227], v151
	v_cvt_pk_f32_fp8_e32 v[228:229], v155
	v_cvt_pk_f32_fp8_e32 v[230:231], v159
	v_pk_fma_f32 v[216:217], v[224:225], v[60:61], v[216:217]
	v_pk_fma_f32 v[218:219], v[226:227], v[60:61], v[218:219]
	v_pk_fma_f32 v[220:221], v[228:229], v[60:61], v[220:221]
	v_pk_fma_f32 v[222:223], v[230:231], v[60:61], v[222:223]
	v_cvt_pk_f32_fp8_sdwa v[224:225], v147 src0_sel:WORD_1
	v_cvt_pk_f32_fp8_sdwa v[226:227], v151 src0_sel:WORD_1
	v_cvt_pk_f32_fp8_sdwa v[228:229], v155 src0_sel:WORD_1
	v_cvt_pk_f32_fp8_sdwa v[230:231], v159 src0_sel:WORD_1
	v_pk_fma_f32 v[216:217], v[224:225], v[62:63], v[216:217]
	v_pk_fma_f32 v[218:219], v[226:227], v[62:63], v[218:219]
	v_pk_fma_f32 v[220:221], v[228:229], v[62:63], v[220:221]
	v_pk_fma_f32 v[222:223], v[230:231], v[62:63], v[222:223]
	v_add_f32_e32 v196, v216, v217
	v_add_f32_e32 v197, v218, v219
	v_add_f32_e32 v198, v220, v221
	v_add_f32_e32 v199, v222, v223
	s_sub_i32 s90, s90, 1
	s_cmp_eq_u32 s90, 0
	s_cbranch_scc1 .LU_sw2
.LU_t3_s2:
	s_waitcnt lgkmcnt(0)
	buffer_load_dwordx4 v[144:147], v[232:233], s[56:59], 0 idxen offen
	buffer_load_dwordx4 v[148:151], v[234:235], s[56:59], 0 idxen offen
	buffer_load_dwordx4 v[152:155], v[236:237], s[56:59], 0 idxen offen
	buffer_load_dwordx4 v[156:159], v[238:239], s[56:59], 0 idxen offen
	ds_read_b32 v232, v213 offset:96
	ds_read_b32 v234, v213 offset:100
	ds_read_b32 v236, v213 offset:104
	ds_read_b32 v238, v213 offset:108
	s_waitcnt vmcnt(13)
	v_cvt_pk_f32_fp8_e32 v[224:225], v160
	v_cvt_pk_f32_fp8_e32 v[226:227], v164
	v_cvt_pk_f32_fp8_e32 v[228:229], v168
	v_cvt_pk_f32_fp8_e32 v[230:231], v172
	v_pk_mul_f32 v[216:217], v[224:225], v[48:49]
	v_pk_mul_f32 v[218:219], v[226:227], v[48:49]
	v_pk_mul_f32 v[220:221], v[228:229], v[48:49]
	v_pk_mul_f32 v[222:223], v[230:231], v[48:49]
	v_cvt_pk_f32_fp8_sdwa v[224:225], v160 src0_sel:WORD_1
	v_cvt_pk_f32_fp8_sdwa v[226:227], v164 src0_sel:WORD_1
	v_cvt_pk_f32_fp8_sdwa v[228:229], v168 src0_sel:WORD_1
	v_cvt_pk_f32_fp8_sdwa v[230:231], v172 src0_sel:WORD_1
	v_pk_fma_f32 v[216:217], v[224:225], v[50:51], v[216:217]
	v_pk_fma_f32 v[218:219], v[226:227], v[50:51], v[218:219]
	v_pk_fma_f32 v[220:221], v[228:229], v[50:51], v[220:221]
	v_pk_fma_f32 v[222:223], v[230:231], v[50:51], v[222:223]
	v_cvt_pk_f32_fp8_e32 v[224:225], v161
	v_cvt_pk_f32_fp8_e32 v[226:227], v165
	v_cvt_pk_f32_fp8_e32 v[228:229], v169
	v_cvt_pk_f32_fp8_e32 v[230:231], v173
	v_pk_fma_f32 v[216:217], v[224:225], v[52:53], v[216:217]
	v_pk_fma_f32 v[218:219], v[226:227], v[52:53], v[218:219]
	v_pk_fma_f32 v[220:221], v[228:229], v[52:53], v[220:221]
	v_pk_fma_f32 v[222:223], v[230:231], v[52:53], v[222:223]
	v_cvt_pk_f32_fp8_sdwa v[224:225], v161 src0_sel:WORD_1
	v_cvt_pk_f32_fp8_sdwa v[226:227], v165 src0_sel:WORD_1
	v_cvt_pk_f32_fp8_sdwa v[228:229], v169 src0_sel:WORD_1
	v_cvt_pk_f32_fp8_sdwa v[230:231], v173 src0_sel:WORD_1
	v_pk_fma_f32 v[216:217], v[224:225], v[54:55], v[216:217]
	v_pk_fma_f32 v[218:219], v[226:227], v[54:55], v[218:219]
	v_pk_fma_f32 v[220:221], v[228:229], v[54:55], v[220:221]
	v_pk_fma_f32 v[222:223], v[230:231], v[54:55], v[222:223]
	v_cvt_pk_f32_fp8_e32 v[224:225], v162
	v_cvt_pk_f32_fp8_e32 v[226:227], v166
	v_cvt_pk_f32_fp8_e32 v[228:229], v170
	v_cvt_pk_f32_fp8_e32 v[230:231], v174
	v_pk_fma_f32 v[216:217], v[224:225], v[56:57], v[216:217]
	v_pk_fma_f32 v[218:219], v[226:227], v[56:57], v[218:219]
	v_pk_fma_f32 v[220:221], v[228:229], v[56:57], v[220:221]
	v_pk_fma_f32 v[222:223], v[230:231], v[56:57], v[222:223]
	v_cvt_pk_f32_fp8_sdwa v[224:225], v162 src0_sel:WORD_1
	v_cvt_pk_f32_fp8_sdwa v[226:227], v166 src0_sel:WORD_1
	v_cvt_pk_f32_fp8_sdwa v[228:229], v170 src0_sel:WORD_1
	v_cvt_pk_f32_fp8_sdwa v[230:231], v174 src0_sel:WORD_1
	v_pk_fma_f32 v[216:217], v[224:225], v[58:59], v[216:217]
	v_pk_fma_f32 v[218:219], v[226:227], v[58:59], v[218:219]
	v_pk_fma_f32 v[220:221], v[228:229], v[58:59], v[220:221]
	v_pk_fma_f32 v[222:223], v[230:231], v[58:59], v[222:223]
	v_cvt_pk_f32_fp8_e32 v[224:225], v163
	v_cvt_pk_f32_fp8_e32 v[226:227], v167
	v_cvt_pk_f32_fp8_e32 v[228:229], v171
	v_cvt_pk_f32_fp8_e32 v[230:231], v175
	v_pk_fma_f32 v[216:217], v[224:225], v[60:61], v[216:217]
	v_pk_fma_f32 v[218:219], v[226:227], v[60:61], v[218:219]
	v_pk_fma_f32 v[220:221], v[228:229], v[60:61], v[220:221]
	v_pk_fma_f32 v[222:223], v[230:231], v[60:61], v[222:223]
	v_cvt_pk_f32_fp8_sdwa v[224:225], v163 src0_sel:WORD_1
	v_cvt_pk_f32_fp8_sdwa v[226:227], v167 src0_sel:WORD_1
	v_cvt_pk_f32_fp8_sdwa v[228:229], v171 src0_sel:WORD_1
	v_cvt_pk_f32_fp8_sdwa v[230:231], v175 src0_sel:WORD_1
	v_pk_fma_f32 v[216:217], v[224:225], v[62:63], v[216:217]
	v_pk_fma_f32 v[218:219], v[226:227], v[62:63], v[218:219]
	v_pk_fma_f32 v[220:221], v[228:229], v[62:63], v[220:221]
	v_pk_fma_f32 v[222:223], v[230:231], v[62:63], v[222:223]
	v_add_f32_e32 v200, v216, v217
	v_add_f32_e32 v201, v218, v219
	v_add_f32_e32 v202, v220, v221
	v_add_f32_e32 v203, v222, v223
	s_sub_i32 s90, s90, 1
	s_cmp_eq_u32 s90, 0
	s_cbranch_scc1 .LU_sw3

.LU_t4_s0:
	s_cmp_ge_u32 s21, s20
	s_cbranch_scc1 .LU_done
	s_waitcnt lgkmcnt(0)
	v_lshlrev_b32_e32 v208, 3, v248
	buffer_load_dwordx2 v[252:253], v208, s[24:27], 0 offen
	buffer_load_dwordx4 v[176:179], v[232:233], s[56:59], 0 idxen offen
	buffer_load_dwordx4 v[180:183], v[234:235], s[56:59], 0 idxen offen
	buffer_load_dwordx4 v[184:187], v[236:237], s[56:59], 0 idxen offen
	buffer_load_dwordx4 v[188:191], v[238:239], s[56:59], 0 idxen offen
	ds_read_b32 v232, v213 offset:64
	ds_read_b32 v234, v213 offset:68
	ds_read_b32 v236, v213 offset:72
	ds_read_b32 v238, v213 offset:76
	s_waitcnt vmcnt(13)
	v_cvt_pk_f32_fp8_e32 v[224:225], v128
	v_cvt_pk_f32_fp8_e32 v[226:227], v132
	v_cvt_pk_f32_fp8_e32 v[228:229], v136
	v_cvt_pk_f32_fp8_e32 v[230:231], v140
	v_pk_mul_f32 v[216:217], v[224:225], v[64:65]
	v_pk_mul_f32 v[218:219], v[226:227], v[64:65]
	v_pk_mul_f32 v[220:221], v[228:229], v[64:65]
	v_pk_mul_f32 v[222:223], v[230:231], v[64:65]
	v_cvt_pk_f32_fp8_sdwa v[224:225], v128 src0_sel:WORD_1
	v_cvt_pk_f32_fp8_sdwa v[226:227], v132 src0_sel:WORD_1
	v_cvt_pk_f32_fp8_sdwa v[228:229], v136 src0_sel:WORD_1
	v_cvt_pk_f32_fp8_sdwa v[230:231], v140 src0_sel:WORD_1
	v_pk_fma_f32 v[216:217], v[224:225], v[66:67], v[216:217]
	v_pk_fma_f32 v[218:219], v[226:227], v[66:67], v[218:219]
	v_pk_fma_f32 v[220:221], v[228:229], v[66:67], v[220:221]
	v_pk_fma_f32 v[222:223], v[230:231], v[66:67], v[222:223]
	v_cvt_pk_f32_fp8_e32 v[224:225], v129
	v_cvt_pk_f32_fp8_e32 v[226:227], v133
	v_cvt_pk_f32_fp8_e32 v[228:229], v137
	v_cvt_pk_f32_fp8_e32 v[230:231], v141
	v_pk_fma_f32 v[216:217], v[224:225], v[68:69], v[216:217]
	v_pk_fma_f32 v[218:219], v[226:227], v[68:69], v[218:219]
	v_pk_fma_f32 v[220:221], v[228:229], v[68:69], v[220:221]
	v_pk_fma_f32 v[222:223], v[230:231], v[68:69], v[222:223]
	v_cvt_pk_f32_fp8_sdwa v[224:225], v129 src0_sel:WORD_1
	v_cvt_pk_f32_fp8_sdwa v[226:227], v133 src0_sel:WORD_1
	v_cvt_pk_f32_fp8_sdwa v[228:229], v137 src0_sel:WORD_1
	v_cvt_pk_f32_fp8_sdwa v[230:231], v141 src0_sel:WORD_1
	v_pk_fma_f32 v[216:217], v[224:225], v[70:71], v[216:217]
	v_pk_fma_f32 v[218:219], v[226:227], v[70:71], v[218:219]
	v_pk_fma_f32 v[220:221], v[228:229], v[70:71], v[220:221]
	v_pk_fma_f32 v[222:223], v[230:231], v[70:71], v[222:223]
	v_cvt_pk_f32_fp8_e32 v[224:225], v130
	v_cvt_pk_f32_fp8_e32 v[226:227], v134
	v_cvt_pk_f32_fp8_e32 v[228:229], v138
	v_cvt_pk_f32_fp8_e32 v[230:231], v142
	v_pk_fma_f32 v[216:217], v[224:225], v[72:73], v[216:217]
	v_pk_fma_f32 v[218:219], v[226:227], v[72:73], v[218:219]
	v_pk_fma_f32 v[220:221], v[228:229], v[72:73], v[220:221]
	v_pk_fma_f32 v[222:223], v[230:231], v[72:73], v[222:223]
	v_cvt_pk_f32_fp8_sdwa v[224:225], v130 src0_sel:WORD_1
	v_cvt_pk_f32_fp8_sdwa v[226:227], v134 src0_sel:WORD_1
	v_cvt_pk_f32_fp8_sdwa v[228:229], v138 src0_sel:WORD_1
	v_cvt_pk_f32_fp8_sdwa v[230:231], v142 src0_sel:WORD_1
	v_pk_fma_f32 v[216:217], v[224:225], v[74:75], v[216:217]
	v_pk_fma_f32 v[218:219], v[226:227], v[74:75], v[218:219]
	v_pk_fma_f32 v[220:221], v[228:229], v[74:75], v[220:221]
	v_pk_fma_f32 v[222:223], v[230:231], v[74:75], v[222:223]
	v_cvt_pk_f32_fp8_e32 v[224:225], v131
	v_cvt_pk_f32_fp8_e32 v[226:227], v135
	v_cvt_pk_f32_fp8_e32 v[228:229], v139
	v_cvt_pk_f32_fp8_e32 v[230:231], v143
	v_pk_fma_f32 v[216:217], v[224:225], v[76:77], v[216:217]
	v_pk_fma_f32 v[218:219], v[226:227], v[76:77], v[218:219]
	v_pk_fma_f32 v[220:221], v[228:229], v[76:77], v[220:221]
	v_pk_fma_f32 v[222:223], v[230:231], v[76:77], v[222:223]
	v_cvt_pk_f32_fp8_sdwa v[224:225], v131 src0_sel:WORD_1
	v_cvt_pk_f32_fp8_sdwa v[226:227], v135 src0_sel:WORD_1
	v_cvt_pk_f32_fp8_sdwa v[228:229], v139 src0_sel:WORD_1
	v_cvt_pk_f32_fp8_sdwa v[230:231], v143 src0_sel:WORD_1
	v_pk_fma_f32 v[216:217], v[224:225], v[78:79], v[216:217]
	v_pk_fma_f32 v[218:219], v[226:227], v[78:79], v[218:219]
	v_pk_fma_f32 v[220:221], v[228:229], v[78:79], v[220:221]
	v_pk_fma_f32 v[222:223], v[230:231], v[78:79], v[222:223]
	v_add_f32_e32 v192, v216, v217
	v_add_f32_e32 v193, v218, v219
	v_add_f32_e32 v194, v220, v221
	v_add_f32_e32 v195, v222, v223
	s_sub_i32 s90, s90, 1
	s_cmp_eq_u32 s90, 0
	s_cbranch_scc1 .LU_sw1
.LU_t4_s1:
	s_waitcnt lgkmcnt(0)
	buffer_load_dwordx4 v[128:131], v[232:233], s[56:59], 0 idxen offen
	buffer_load_dwordx4 v[132:135], v[234:235], s[56:59], 0 idxen offen
	buffer_load_dwordx4 v[136:139], v[236:237], s[56:59], 0 idxen offen
	buffer_load_dwordx4 v[140:143], v[238:239], s[56:59], 0 idxen offen
	ds_read_b32 v232, v213 offset:80
	ds_read_b32 v234, v213 offset:84
	ds_read_b32 v236, v213 offset:88
	ds_read_b32 v238, v213 offset:92
	s_waitcnt vmcnt(13)
	v_cvt_pk_f32_fp8_e32 v[224:225], v144
	v_cvt_pk_f32_fp8_e32 v[226:227], v148
	v_cvt_pk_f32_fp8_e32 v[228:229], v152
	v_cvt_pk_f32_fp8_e32 v[230:231], v156
	v_pk_mul_f32 v[216:217], v[224:225], v[64:65]
	v_pk_mul_f32 v[218:219], v[226:227], v[64:65]
	v_pk_mul_f32 v[220:221], v[228:229], v[64:65]
	v_pk_mul_f32 v[222:223], v[230:231], v[64:65]
	v_cvt_pk_f32_fp8_sdwa v[224:225], v144 src0_sel:WORD_1
	v_cvt_pk_f32_fp8_sdwa v[226:227], v148 src0_sel:WORD_1
	v_cvt_pk_f32_fp8_sdwa v[228:229], v152 src0_sel:WORD_1
	v_cvt_pk_f32_fp8_sdwa v[230:231], v156 src0_sel:WORD_1
	v_pk_fma_f32 v[216:217], v[224:225], v[66:67], v[216:217]
	v_pk_fma_f32 v[218:219], v[226:227], v[66:67], v[218:219]
	v_pk_fma_f32 v[220:221], v[228:229], v[66:67], v[220:221]
	v_pk_fma_f32 v[222:223], v[230:231], v[66:67], v[222:223]
	v_cvt_pk_f32_fp8_e32 v[224:225], v145
	v_cvt_pk_f32_fp8_e32 v[226:227], v149
	v_cvt_pk_f32_fp8_e32 v[228:229], v153
	v_cvt_pk_f32_fp8_e32 v[230:231], v157
	v_pk_fma_f32 v[216:217], v[224:225], v[68:69], v[216:217]
	v_pk_fma_f32 v[218:219], v[226:227], v[68:69], v[218:219]
	v_pk_fma_f32 v[220:221], v[228:229], v[68:69], v[220:221]
	v_pk_fma_f32 v[222:223], v[230:231], v[68:69], v[222:223]
	v_cvt_pk_f32_fp8_sdwa v[224:225], v145 src0_sel:WORD_1
	v_cvt_pk_f32_fp8_sdwa v[226:227], v149 src0_sel:WORD_1
	v_cvt_pk_f32_fp8_sdwa v[228:229], v153 src0_sel:WORD_1
	v_cvt_pk_f32_fp8_sdwa v[230:231], v157 src0_sel:WORD_1
	v_pk_fma_f32 v[216:217], v[224:225], v[70:71], v[216:217]
	v_pk_fma_f32 v[218:219], v[226:227], v[70:71], v[218:219]
	v_pk_fma_f32 v[220:221], v[228:229], v[70:71], v[220:221]
	v_pk_fma_f32 v[222:223], v[230:231], v[70:71], v[222:223]
	v_cvt_pk_f32_fp8_e32 v[224:225], v146
	v_cvt_pk_f32_fp8_e32 v[226:227], v150
	v_cvt_pk_f32_fp8_e32 v[228:229], v154
	v_cvt_pk_f32_fp8_e32 v[230:231], v158
	v_pk_fma_f32 v[216:217], v[224:225], v[72:73], v[216:217]
	v_pk_fma_f32 v[218:219], v[226:227], v[72:73], v[218:219]
	v_pk_fma_f32 v[220:221], v[228:229], v[72:73], v[220:221]
	v_pk_fma_f32 v[222:223], v[230:231], v[72:73], v[222:223]
	v_cvt_pk_f32_fp8_sdwa v[224:225], v146 src0_sel:WORD_1
	v_cvt_pk_f32_fp8_sdwa v[226:227], v150 src0_sel:WORD_1
	v_cvt_pk_f32_fp8_sdwa v[228:229], v154 src0_sel:WORD_1
	v_cvt_pk_f32_fp8_sdwa v[230:231], v158 src0_sel:WORD_1
	v_pk_fma_f32 v[216:217], v[224:225], v[74:75], v[216:217]
	v_pk_fma_f32 v[218:219], v[226:227], v[74:75], v[218:219]
	v_pk_fma_f32 v[220:221], v[228:229], v[74:75], v[220:221]
	v_pk_fma_f32 v[222:223], v[230:231], v[74:75], v[222:223]
	v_cvt_pk_f32_fp8_e32 v[224:225], v147
	v_cvt_pk_f32_fp8_e32 v[226:227], v151
	v_cvt_pk_f32_fp8_e32 v[228:229], v155
	v_cvt_pk_f32_fp8_e32 v[230:231], v159
	v_pk_fma_f32 v[216:217], v[224:225], v[76:77], v[216:217]
	v_pk_fma_f32 v[218:219], v[226:227], v[76:77], v[218:219]
	v_pk_fma_f32 v[220:221], v[228:229], v[76:77], v[220:221]
	v_pk_fma_f32 v[222:223], v[230:231], v[76:77], v[222:223]
	v_cvt_pk_f32_fp8_sdwa v[224:225], v147 src0_sel:WORD_1
	v_cvt_pk_f32_fp8_sdwa v[226:227], v151 src0_sel:WORD_1
	v_cvt_pk_f32_fp8_sdwa v[228:229], v155 src0_sel:WORD_1
	v_cvt_pk_f32_fp8_sdwa v[230:231], v159 src0_sel:WORD_1
	v_pk_fma_f32 v[216:217], v[224:225], v[78:79], v[216:217]
	v_pk_fma_f32 v[218:219], v[226:227], v[78:79], v[218:219]
	v_pk_fma_f32 v[220:221], v[228:229], v[78:79], v[220:221]
	v_pk_fma_f32 v[222:223], v[230:231], v[78:79], v[222:223]
	v_add_f32_e32 v196, v216, v217
	v_add_f32_e32 v197, v218, v219
	v_add_f32_e32 v198, v220, v221
	v_add_f32_e32 v199, v222, v223
	s_sub_i32 s90, s90, 1
	s_cmp_eq_u32 s90, 0
	s_cbranch_scc1 .LU_sw2
.LU_t4_s2:
	s_waitcnt lgkmcnt(0)
	buffer_load_dwordx4 v[144:147], v[232:233], s[56:59], 0 idxen offen
	buffer_load_dwordx4 v[148:151], v[234:235], s[56:59], 0 idxen offen
	buffer_load_dwordx4 v[152:155], v[236:237], s[56:59], 0 idxen offen
	buffer_load_dwordx4 v[156:159], v[238:239], s[56:59], 0 idxen offen
	ds_read_b32 v232, v213 offset:96
	ds_read_b32 v234, v213 offset:100
	ds_read_b32 v236, v213 offset:104
	ds_read_b32 v238, v213 offset:108
	s_waitcnt vmcnt(13)
	v_cvt_pk_f32_fp8_e32 v[224:225], v160
	v_cvt_pk_f32_fp8_e32 v[226:227], v164
	v_cvt_pk_f32_fp8_e32 v[228:229], v168
	v_cvt_pk_f32_fp8_e32 v[230:231], v172
	v_pk_mul_f32 v[216:217], v[224:225], v[64:65]
	v_pk_mul_f32 v[218:219], v[226:227], v[64:65]
	v_pk_mul_f32 v[220:221], v[228:229], v[64:65]
	v_pk_mul_f32 v[222:223], v[230:231], v[64:65]
	v_cvt_pk_f32_fp8_sdwa v[224:225], v160 src0_sel:WORD_1
	v_cvt_pk_f32_fp8_sdwa v[226:227], v164 src0_sel:WORD_1
	v_cvt_pk_f32_fp8_sdwa v[228:229], v168 src0_sel:WORD_1
	v_cvt_pk_f32_fp8_sdwa v[230:231], v172 src0_sel:WORD_1
	v_pk_fma_f32 v[216:217], v[224:225], v[66:67], v[216:217]
	v_pk_fma_f32 v[218:219], v[226:227], v[66:67], v[218:219]
	v_pk_fma_f32 v[220:221], v[228:229], v[66:67], v[220:221]
	v_pk_fma_f32 v[222:223], v[230:231], v[66:67], v[222:223]
	v_cvt_pk_f32_fp8_e32 v[224:225], v161
	v_cvt_pk_f32_fp8_e32 v[226:227], v165
	v_cvt_pk_f32_fp8_e32 v[228:229], v169
	v_cvt_pk_f32_fp8_e32 v[230:231], v173
	v_pk_fma_f32 v[216:217], v[224:225], v[68:69], v[216:217]
	v_pk_fma_f32 v[218:219], v[226:227], v[68:69], v[218:219]
	v_pk_fma_f32 v[220:221], v[228:229], v[68:69], v[220:221]
	v_pk_fma_f32 v[222:223], v[230:231], v[68:69], v[222:223]
	v_cvt_pk_f32_fp8_sdwa v[224:225], v161 src0_sel:WORD_1
	v_cvt_pk_f32_fp8_sdwa v[226:227], v165 src0_sel:WORD_1
	v_cvt_pk_f32_fp8_sdwa v[228:229], v169 src0_sel:WORD_1
	v_cvt_pk_f32_fp8_sdwa v[230:231], v173 src0_sel:WORD_1
	v_pk_fma_f32 v[216:217], v[224:225], v[70:71], v[216:217]
	v_pk_fma_f32 v[218:219], v[226:227], v[70:71], v[218:219]
	v_pk_fma_f32 v[220:221], v[228:229], v[70:71], v[220:221]
	v_pk_fma_f32 v[222:223], v[230:231], v[70:71], v[222:223]
	v_cvt_pk_f32_fp8_e32 v[224:225], v162
	v_cvt_pk_f32_fp8_e32 v[226:227], v166
	v_cvt_pk_f32_fp8_e32 v[228:229], v170
	v_cvt_pk_f32_fp8_e32 v[230:231], v174
	v_pk_fma_f32 v[216:217], v[224:225], v[72:73], v[216:217]
	v_pk_fma_f32 v[218:219], v[226:227], v[72:73], v[218:219]
	v_pk_fma_f32 v[220:221], v[228:229], v[72:73], v[220:221]
	v_pk_fma_f32 v[222:223], v[230:231], v[72:73], v[222:223]
	v_cvt_pk_f32_fp8_sdwa v[224:225], v162 src0_sel:WORD_1
	v_cvt_pk_f32_fp8_sdwa v[226:227], v166 src0_sel:WORD_1
	v_cvt_pk_f32_fp8_sdwa v[228:229], v170 src0_sel:WORD_1
	v_cvt_pk_f32_fp8_sdwa v[230:231], v174 src0_sel:WORD_1
	v_pk_fma_f32 v[216:217], v[224:225], v[74:75], v[216:217]
	v_pk_fma_f32 v[218:219], v[226:227], v[74:75], v[218:219]
	v_pk_fma_f32 v[220:221], v[228:229], v[74:75], v[220:221]
	v_pk_fma_f32 v[222:223], v[230:231], v[74:75], v[222:223]
	v_cvt_pk_f32_fp8_e32 v[224:225], v163
	v_cvt_pk_f32_fp8_e32 v[226:227], v167
	v_cvt_pk_f32_fp8_e32 v[228:229], v171
	v_cvt_pk_f32_fp8_e32 v[230:231], v175
	v_pk_fma_f32 v[216:217], v[224:225], v[76:77], v[216:217]
	v_pk_fma_f32 v[218:219], v[226:227], v[76:77], v[218:219]
	v_pk_fma_f32 v[220:221], v[228:229], v[76:77], v[220:221]
	v_pk_fma_f32 v[222:223], v[230:231], v[76:77], v[222:223]
	v_cvt_pk_f32_fp8_sdwa v[224:225], v163 src0_sel:WORD_1
	v_cvt_pk_f32_fp8_sdwa v[226:227], v167 src0_sel:WORD_1
	v_cvt_pk_f32_fp8_sdwa v[228:229], v171 src0_sel:WORD_1
	v_cvt_pk_f32_fp8_sdwa v[230:231], v175 src0_sel:WORD_1
	v_pk_fma_f32 v[216:217], v[224:225], v[78:79], v[216:217]
	v_pk_fma_f32 v[218:219], v[226:227], v[78:79], v[218:219]
	v_pk_fma_f32 v[220:221], v[228:229], v[78:79], v[220:221]
	v_pk_fma_f32 v[222:223], v[230:231], v[78:79], v[222:223]
	v_add_f32_e32 v200, v216, v217
	v_add_f32_e32 v201, v218, v219
	v_add_f32_e32 v202, v220, v221
	v_add_f32_e32 v203, v222, v223
	s_sub_i32 s90, s90, 1
	s_cmp_eq_u32 s90, 0
	s_cbranch_scc1 .LU_sw3

.LU_t5_s0:
	s_cmp_ge_u32 s21, s20
	s_cbranch_scc1 .LU_done
	s_waitcnt lgkmcnt(0)
	v_lshlrev_b32_e32 v208, 3, v248
	buffer_load_dwordx2 v[252:253], v208, s[24:27], 0 offen
	buffer_load_dwordx4 v[176:179], v[232:233], s[56:59], 0 idxen offen
	buffer_load_dwordx4 v[180:183], v[234:235], s[56:59], 0 idxen offen
	buffer_load_dwordx4 v[184:187], v[236:237], s[56:59], 0 idxen offen
	buffer_load_dwordx4 v[188:191], v[238:239], s[56:59], 0 idxen offen
	ds_read_b32 v232, v213 offset:64
	ds_read_b32 v234, v213 offset:68
	ds_read_b32 v236, v213 offset:72
	ds_read_b32 v238, v213 offset:76
	s_waitcnt vmcnt(13)
	v_cvt_pk_f32_fp8_e32 v[224:225], v128
	v_cvt_pk_f32_fp8_e32 v[226:227], v132
	v_cvt_pk_f32_fp8_e32 v[228:229], v136
	v_cvt_pk_f32_fp8_e32 v[230:231], v140
	v_pk_mul_f32 v[216:217], v[224:225], v[80:81]
	v_pk_mul_f32 v[218:219], v[226:227], v[80:81]
	v_pk_mul_f32 v[220:221], v[228:229], v[80:81]
	v_pk_mul_f32 v[222:223], v[230:231], v[80:81]
	v_cvt_pk_f32_fp8_sdwa v[224:225], v128 src0_sel:WORD_1
	v_cvt_pk_f32_fp8_sdwa v[226:227], v132 src0_sel:WORD_1
	v_cvt_pk_f32_fp8_sdwa v[228:229], v136 src0_sel:WORD_1
	v_cvt_pk_f32_fp8_sdwa v[230:231], v140 src0_sel:WORD_1
	v_pk_fma_f32 v[216:217], v[224:225], v[82:83], v[216:217]
	v_pk_fma_f32 v[218:219], v[226:227], v[82:83], v[218:219]
	v_pk_fma_f32 v[220:221], v[228:229], v[82:83], v[220:221]
	v_pk_fma_f32 v[222:223], v[230:231], v[82:83], v[222:223]
	v_cvt_pk_f32_fp8_e32 v[224:225], v129
	v_cvt_pk_f32_fp8_e32 v[226:227], v133
	v_cvt_pk_f32_fp8_e32 v[228:229], v137
	v_cvt_pk_f32_fp8_e32 v[230:231], v141
	v_pk_fma_f32 v[216:217], v[224:225], v[84:85], v[216:217]
	v_pk_fma_f32 v[218:219], v[226:227], v[84:85], v[218:219]
	v_pk_fma_f32 v[220:221], v[228:229], v[84:85], v[220:221]
	v_pk_fma_f32 v[222:223], v[230:231], v[84:85], v[222:223]
	v_cvt_pk_f32_fp8_sdwa v[224:225], v129 src0_sel:WORD_1
	v_cvt_pk_f32_fp8_sdwa v[226:227], v133 src0_sel:WORD_1
	v_cvt_pk_f32_fp8_sdwa v[228:229], v137 src0_sel:WORD_1
	v_cvt_pk_f32_fp8_sdwa v[230:231], v141 src0_sel:WORD_1
	v_pk_fma_f32 v[216:217], v[224:225], v[86:87], v[216:217]
	v_pk_fma_f32 v[218:219], v[226:227], v[86:87], v[218:219]
	v_pk_fma_f32 v[220:221], v[228:229], v[86:87], v[220:221]
	v_pk_fma_f32 v[222:223], v[230:231], v[86:87], v[222:223]
	v_cvt_pk_f32_fp8_e32 v[224:225], v130
	v_cvt_pk_f32_fp8_e32 v[226:227], v134
	v_cvt_pk_f32_fp8_e32 v[228:229], v138
	v_cvt_pk_f32_fp8_e32 v[230:231], v142
	v_pk_fma_f32 v[216:217], v[224:225], v[88:89], v[216:217]
	v_pk_fma_f32 v[218:219], v[226:227], v[88:89], v[218:219]
	v_pk_fma_f32 v[220:221], v[228:229], v[88:89], v[220:221]
	v_pk_fma_f32 v[222:223], v[230:231], v[88:89], v[222:223]
	v_cvt_pk_f32_fp8_sdwa v[224:225], v130 src0_sel:WORD_1
	v_cvt_pk_f32_fp8_sdwa v[226:227], v134 src0_sel:WORD_1
	v_cvt_pk_f32_fp8_sdwa v[228:229], v138 src0_sel:WORD_1
	v_cvt_pk_f32_fp8_sdwa v[230:231], v142 src0_sel:WORD_1
	v_pk_fma_f32 v[216:217], v[224:225], v[90:91], v[216:217]
	v_pk_fma_f32 v[218:219], v[226:227], v[90:91], v[218:219]
	v_pk_fma_f32 v[220:221], v[228:229], v[90:91], v[220:221]
	v_pk_fma_f32 v[222:223], v[230:231], v[90:91], v[222:223]
	v_cvt_pk_f32_fp8_e32 v[224:225], v131
	v_cvt_pk_f32_fp8_e32 v[226:227], v135
	v_cvt_pk_f32_fp8_e32 v[228:229], v139
	v_cvt_pk_f32_fp8_e32 v[230:231], v143
	v_pk_fma_f32 v[216:217], v[224:225], v[92:93], v[216:217]
	v_pk_fma_f32 v[218:219], v[226:227], v[92:93], v[218:219]
	v_pk_fma_f32 v[220:221], v[228:229], v[92:93], v[220:221]
	v_pk_fma_f32 v[222:223], v[230:231], v[92:93], v[222:223]
	v_cvt_pk_f32_fp8_sdwa v[224:225], v131 src0_sel:WORD_1
	v_cvt_pk_f32_fp8_sdwa v[226:227], v135 src0_sel:WORD_1
	v_cvt_pk_f32_fp8_sdwa v[228:229], v139 src0_sel:WORD_1
	v_cvt_pk_f32_fp8_sdwa v[230:231], v143 src0_sel:WORD_1
	v_pk_fma_f32 v[216:217], v[224:225], v[94:95], v[216:217]
	v_pk_fma_f32 v[218:219], v[226:227], v[94:95], v[218:219]
	v_pk_fma_f32 v[220:221], v[228:229], v[94:95], v[220:221]
	v_pk_fma_f32 v[222:223], v[230:231], v[94:95], v[222:223]
	v_add_f32_e32 v192, v216, v217
	v_add_f32_e32 v193, v218, v219
	v_add_f32_e32 v194, v220, v221
	v_add_f32_e32 v195, v222, v223
	s_sub_i32 s90, s90, 1
	s_cmp_eq_u32 s90, 0
	s_cbranch_scc1 .LU_sw1
.LU_t5_s1:
	s_waitcnt lgkmcnt(0)
	buffer_load_dwordx4 v[128:131], v[232:233], s[56:59], 0 idxen offen
	buffer_load_dwordx4 v[132:135], v[234:235], s[56:59], 0 idxen offen
	buffer_load_dwordx4 v[136:139], v[236:237], s[56:59], 0 idxen offen
	buffer_load_dwordx4 v[140:143], v[238:239], s[56:59], 0 idxen offen
	ds_read_b32 v232, v213 offset:80
	ds_read_b32 v234, v213 offset:84
	ds_read_b32 v236, v213 offset:88
	ds_read_b32 v238, v213 offset:92
	s_waitcnt vmcnt(13)
	v_cvt_pk_f32_fp8_e32 v[224:225], v144
	v_cvt_pk_f32_fp8_e32 v[226:227], v148
	v_cvt_pk_f32_fp8_e32 v[228:229], v152
	v_cvt_pk_f32_fp8_e32 v[230:231], v156
	v_pk_mul_f32 v[216:217], v[224:225], v[80:81]
	v_pk_mul_f32 v[218:219], v[226:227], v[80:81]
	v_pk_mul_f32 v[220:221], v[228:229], v[80:81]
	v_pk_mul_f32 v[222:223], v[230:231], v[80:81]
	v_cvt_pk_f32_fp8_sdwa v[224:225], v144 src0_sel:WORD_1
	v_cvt_pk_f32_fp8_sdwa v[226:227], v148 src0_sel:WORD_1
	v_cvt_pk_f32_fp8_sdwa v[228:229], v152 src0_sel:WORD_1
	v_cvt_pk_f32_fp8_sdwa v[230:231], v156 src0_sel:WORD_1
	v_pk_fma_f32 v[216:217], v[224:225], v[82:83], v[216:217]
	v_pk_fma_f32 v[218:219], v[226:227], v[82:83], v[218:219]
	v_pk_fma_f32 v[220:221], v[228:229], v[82:83], v[220:221]
	v_pk_fma_f32 v[222:223], v[230:231], v[82:83], v[222:223]
	v_cvt_pk_f32_fp8_e32 v[224:225], v145
	v_cvt_pk_f32_fp8_e32 v[226:227], v149
	v_cvt_pk_f32_fp8_e32 v[228:229], v153
	v_cvt_pk_f32_fp8_e32 v[230:231], v157
	v_pk_fma_f32 v[216:217], v[224:225], v[84:85], v[216:217]
	v_pk_fma_f32 v[218:219], v[226:227], v[84:85], v[218:219]
	v_pk_fma_f32 v[220:221], v[228:229], v[84:85], v[220:221]
	v_pk_fma_f32 v[222:223], v[230:231], v[84:85], v[222:223]
	v_cvt_pk_f32_fp8_sdwa v[224:225], v145 src0_sel:WORD_1
	v_cvt_pk_f32_fp8_sdwa v[226:227], v149 src0_sel:WORD_1
	v_cvt_pk_f32_fp8_sdwa v[228:229], v153 src0_sel:WORD_1
	v_cvt_pk_f32_fp8_sdwa v[230:231], v157 src0_sel:WORD_1
	v_pk_fma_f32 v[216:217], v[224:225], v[86:87], v[216:217]
	v_pk_fma_f32 v[218:219], v[226:227], v[86:87], v[218:219]
	v_pk_fma_f32 v[220:221], v[228:229], v[86:87], v[220:221]
	v_pk_fma_f32 v[222:223], v[230:231], v[86:87], v[222:223]
	v_cvt_pk_f32_fp8_e32 v[224:225], v146
	v_cvt_pk_f32_fp8_e32 v[226:227], v150
	v_cvt_pk_f32_fp8_e32 v[228:229], v154
	v_cvt_pk_f32_fp8_e32 v[230:231], v158
	v_pk_fma_f32 v[216:217], v[224:225], v[88:89], v[216:217]
	v_pk_fma_f32 v[218:219], v[226:227], v[88:89], v[218:219]
	v_pk_fma_f32 v[220:221], v[228:229], v[88:89], v[220:221]
	v_pk_fma_f32 v[222:223], v[230:231], v[88:89], v[222:223]
	v_cvt_pk_f32_fp8_sdwa v[224:225], v146 src0_sel:WORD_1
	v_cvt_pk_f32_fp8_sdwa v[226:227], v150 src0_sel:WORD_1
	v_cvt_pk_f32_fp8_sdwa v[228:229], v154 src0_sel:WORD_1
	v_cvt_pk_f32_fp8_sdwa v[230:231], v158 src0_sel:WORD_1
	v_pk_fma_f32 v[216:217], v[224:225], v[90:91], v[216:217]
	v_pk_fma_f32 v[218:219], v[226:227], v[90:91], v[218:219]
	v_pk_fma_f32 v[220:221], v[228:229], v[90:91], v[220:221]
	v_pk_fma_f32 v[222:223], v[230:231], v[90:91], v[222:223]
	v_cvt_pk_f32_fp8_e32 v[224:225], v147
	v_cvt_pk_f32_fp8_e32 v[226:227], v151
	v_cvt_pk_f32_fp8_e32 v[228:229], v155
	v_cvt_pk_f32_fp8_e32 v[230:231], v159
	v_pk_fma_f32 v[216:217], v[224:225], v[92:93], v[216:217]
	v_pk_fma_f32 v[218:219], v[226:227], v[92:93], v[218:219]
	v_pk_fma_f32 v[220:221], v[228:229], v[92:93], v[220:221]
	v_pk_fma_f32 v[222:223], v[230:231], v[92:93], v[222:223]
	v_cvt_pk_f32_fp8_sdwa v[224:225], v147 src0_sel:WORD_1
	v_cvt_pk_f32_fp8_sdwa v[226:227], v151 src0_sel:WORD_1
	v_cvt_pk_f32_fp8_sdwa v[228:229], v155 src0_sel:WORD_1
	v_cvt_pk_f32_fp8_sdwa v[230:231], v159 src0_sel:WORD_1
	v_pk_fma_f32 v[216:217], v[224:225], v[94:95], v[216:217]
	v_pk_fma_f32 v[218:219], v[226:227], v[94:95], v[218:219]
	v_pk_fma_f32 v[220:221], v[228:229], v[94:95], v[220:221]
	v_pk_fma_f32 v[222:223], v[230:231], v[94:95], v[222:223]
	v_add_f32_e32 v196, v216, v217
	v_add_f32_e32 v197, v218, v219
	v_add_f32_e32 v198, v220, v221
	v_add_f32_e32 v199, v222, v223
	s_sub_i32 s90, s90, 1
	s_cmp_eq_u32 s90, 0
	s_cbranch_scc1 .LU_sw2
.LU_t5_s2:
	s_waitcnt lgkmcnt(0)
	buffer_load_dwordx4 v[144:147], v[232:233], s[56:59], 0 idxen offen
	buffer_load_dwordx4 v[148:151], v[234:235], s[56:59], 0 idxen offen
	buffer_load_dwordx4 v[152:155], v[236:237], s[56:59], 0 idxen offen
	buffer_load_dwordx4 v[156:159], v[238:239], s[56:59], 0 idxen offen
	ds_read_b32 v232, v213 offset:96
	ds_read_b32 v234, v213 offset:100
	ds_read_b32 v236, v213 offset:104
	ds_read_b32 v238, v213 offset:108
	s_waitcnt vmcnt(13)
	v_cvt_pk_f32_fp8_e32 v[224:225], v160
	v_cvt_pk_f32_fp8_e32 v[226:227], v164
	v_cvt_pk_f32_fp8_e32 v[228:229], v168
	v_cvt_pk_f32_fp8_e32 v[230:231], v172
	v_pk_mul_f32 v[216:217], v[224:225], v[80:81]
	v_pk_mul_f32 v[218:219], v[226:227], v[80:81]
	v_pk_mul_f32 v[220:221], v[228:229], v[80:81]
	v_pk_mul_f32 v[222:223], v[230:231], v[80:81]
	v_cvt_pk_f32_fp8_sdwa v[224:225], v160 src0_sel:WORD_1
	v_cvt_pk_f32_fp8_sdwa v[226:227], v164 src0_sel:WORD_1
	v_cvt_pk_f32_fp8_sdwa v[228:229], v168 src0_sel:WORD_1
	v_cvt_pk_f32_fp8_sdwa v[230:231], v172 src0_sel:WORD_1
	v_pk_fma_f32 v[216:217], v[224:225], v[82:83], v[216:217]
	v_pk_fma_f32 v[218:219], v[226:227], v[82:83], v[218:219]
	v_pk_fma_f32 v[220:221], v[228:229], v[82:83], v[220:221]
	v_pk_fma_f32 v[222:223], v[230:231], v[82:83], v[222:223]
	v_cvt_pk_f32_fp8_e32 v[224:225], v161
	v_cvt_pk_f32_fp8_e32 v[226:227], v165
	v_cvt_pk_f32_fp8_e32 v[228:229], v169
	v_cvt_pk_f32_fp8_e32 v[230:231], v173
	v_pk_fma_f32 v[216:217], v[224:225], v[84:85], v[216:217]
	v_pk_fma_f32 v[218:219], v[226:227], v[84:85], v[218:219]
	v_pk_fma_f32 v[220:221], v[228:229], v[84:85], v[220:221]
	v_pk_fma_f32 v[222:223], v[230:231], v[84:85], v[222:223]
	v_cvt_pk_f32_fp8_sdwa v[224:225], v161 src0_sel:WORD_1
	v_cvt_pk_f32_fp8_sdwa v[226:227], v165 src0_sel:WORD_1
	v_cvt_pk_f32_fp8_sdwa v[228:229], v169 src0_sel:WORD_1
	v_cvt_pk_f32_fp8_sdwa v[230:231], v173 src0_sel:WORD_1
	v_pk_fma_f32 v[216:217], v[224:225], v[86:87], v[216:217]
	v_pk_fma_f32 v[218:219], v[226:227], v[86:87], v[218:219]
	v_pk_fma_f32 v[220:221], v[228:229], v[86:87], v[220:221]
	v_pk_fma_f32 v[222:223], v[230:231], v[86:87], v[222:223]
	v_cvt_pk_f32_fp8_e32 v[224:225], v162
	v_cvt_pk_f32_fp8_e32 v[226:227], v166
	v_cvt_pk_f32_fp8_e32 v[228:229], v170
	v_cvt_pk_f32_fp8_e32 v[230:231], v174
	v_pk_fma_f32 v[216:217], v[224:225], v[88:89], v[216:217]
	v_pk_fma_f32 v[218:219], v[226:227], v[88:89], v[218:219]
	v_pk_fma_f32 v[220:221], v[228:229], v[88:89], v[220:221]
	v_pk_fma_f32 v[222:223], v[230:231], v[88:89], v[222:223]
	v_cvt_pk_f32_fp8_sdwa v[224:225], v162 src0_sel:WORD_1
	v_cvt_pk_f32_fp8_sdwa v[226:227], v166 src0_sel:WORD_1
	v_cvt_pk_f32_fp8_sdwa v[228:229], v170 src0_sel:WORD_1
	v_cvt_pk_f32_fp8_sdwa v[230:231], v174 src0_sel:WORD_1
	v_pk_fma_f32 v[216:217], v[224:225], v[90:91], v[216:217]
	v_pk_fma_f32 v[218:219], v[226:227], v[90:91], v[218:219]
	v_pk_fma_f32 v[220:221], v[228:229], v[90:91], v[220:221]
	v_pk_fma_f32 v[222:223], v[230:231], v[90:91], v[222:223]
	v_cvt_pk_f32_fp8_e32 v[224:225], v163
	v_cvt_pk_f32_fp8_e32 v[226:227], v167
	v_cvt_pk_f32_fp8_e32 v[228:229], v171
	v_cvt_pk_f32_fp8_e32 v[230:231], v175
	v_pk_fma_f32 v[216:217], v[224:225], v[92:93], v[216:217]
	v_pk_fma_f32 v[218:219], v[226:227], v[92:93], v[218:219]
	v_pk_fma_f32 v[220:221], v[228:229], v[92:93], v[220:221]
	v_pk_fma_f32 v[222:223], v[230:231], v[92:93], v[222:223]
	v_cvt_pk_f32_fp8_sdwa v[224:225], v163 src0_sel:WORD_1
	v_cvt_pk_f32_fp8_sdwa v[226:227], v167 src0_sel:WORD_1
	v_cvt_pk_f32_fp8_sdwa v[228:229], v171 src0_sel:WORD_1
	v_cvt_pk_f32_fp8_sdwa v[230:231], v175 src0_sel:WORD_1
	v_pk_fma_f32 v[216:217], v[224:225], v[94:95], v[216:217]
	v_pk_fma_f32 v[218:219], v[226:227], v[94:95], v[218:219]
	v_pk_fma_f32 v[220:221], v[228:229], v[94:95], v[220:221]
	v_pk_fma_f32 v[222:223], v[230:231], v[94:95], v[222:223]
	v_add_f32_e32 v200, v216, v217
	v_add_f32_e32 v201, v218, v219
	v_add_f32_e32 v202, v220, v221
	v_add_f32_e32 v203, v222, v223
	s_sub_i32 s90, s90, 1
	s_cmp_eq_u32 s90, 0
	s_cbranch_scc1 .LU_sw3

.LU_t6_s0:
	s_cmp_ge_u32 s21, s20
	s_cbranch_scc1 .LU_done
	s_waitcnt lgkmcnt(0)
	v_lshlrev_b32_e32 v208, 3, v248
	buffer_load_dwordx2 v[252:253], v208, s[24:27], 0 offen
	buffer_load_dwordx4 v[176:179], v[232:233], s[56:59], 0 idxen offen
	buffer_load_dwordx4 v[180:183], v[234:235], s[56:59], 0 idxen offen
	buffer_load_dwordx4 v[184:187], v[236:237], s[56:59], 0 idxen offen
	buffer_load_dwordx4 v[188:191], v[238:239], s[56:59], 0 idxen offen
	ds_read_b32 v232, v213 offset:64
	ds_read_b32 v234, v213 offset:68
	ds_read_b32 v236, v213 offset:72
	ds_read_b32 v238, v213 offset:76
	s_waitcnt vmcnt(13)
	v_cvt_pk_f32_fp8_e32 v[224:225], v128
	v_cvt_pk_f32_fp8_e32 v[226:227], v132
	v_cvt_pk_f32_fp8_e32 v[228:229], v136
	v_cvt_pk_f32_fp8_e32 v[230:231], v140
	v_pk_mul_f32 v[216:217], v[224:225], v[96:97]
	v_pk_mul_f32 v[218:219], v[226:227], v[96:97]
	v_pk_mul_f32 v[220:221], v[228:229], v[96:97]
	v_pk_mul_f32 v[222:223], v[230:231], v[96:97]
	v_cvt_pk_f32_fp8_sdwa v[224:225], v128 src0_sel:WORD_1
	v_cvt_pk_f32_fp8_sdwa v[226:227], v132 src0_sel:WORD_1
	v_cvt_pk_f32_fp8_sdwa v[228:229], v136 src0_sel:WORD_1
	v_cvt_pk_f32_fp8_sdwa v[230:231], v140 src0_sel:WORD_1
	v_pk_fma_f32 v[216:217], v[224:225], v[98:99], v[216:217]
	v_pk_fma_f32 v[218:219], v[226:227], v[98:99], v[218:219]
	v_pk_fma_f32 v[220:221], v[228:229], v[98:99], v[220:221]
	v_pk_fma_f32 v[222:223], v[230:231], v[98:99], v[222:223]
	v_cvt_pk_f32_fp8_e32 v[224:225], v129
	v_cvt_pk_f32_fp8_e32 v[226:227], v133
	v_cvt_pk_f32_fp8_e32 v[228:229], v137
	v_cvt_pk_f32_fp8_e32 v[230:231], v141
	v_pk_fma_f32 v[216:217], v[224:225], v[100:101], v[216:217]
	v_pk_fma_f32 v[218:219], v[226:227], v[100:101], v[218:219]
	v_pk_fma_f32 v[220:221], v[228:229], v[100:101], v[220:221]
	v_pk_fma_f32 v[222:223], v[230:231], v[100:101], v[222:223]
	v_cvt_pk_f32_fp8_sdwa v[224:225], v129 src0_sel:WORD_1
	v_cvt_pk_f32_fp8_sdwa v[226:227], v133 src0_sel:WORD_1
	v_cvt_pk_f32_fp8_sdwa v[228:229], v137 src0_sel:WORD_1
	v_cvt_pk_f32_fp8_sdwa v[230:231], v141 src0_sel:WORD_1
	v_pk_fma_f32 v[216:217], v[224:225], v[102:103], v[216:217]
	v_pk_fma_f32 v[218:219], v[226:227], v[102:103], v[218:219]
	v_pk_fma_f32 v[220:221], v[228:229], v[102:103], v[220:221]
	v_pk_fma_f32 v[222:223], v[230:231], v[102:103], v[222:223]
	v_cvt_pk_f32_fp8_e32 v[224:225], v130
	v_cvt_pk_f32_fp8_e32 v[226:227], v134
	v_cvt_pk_f32_fp8_e32 v[228:229], v138
	v_cvt_pk_f32_fp8_e32 v[230:231], v142
	v_pk_fma_f32 v[216:217], v[224:225], v[104:105], v[216:217]
	v_pk_fma_f32 v[218:219], v[226:227], v[104:105], v[218:219]
	v_pk_fma_f32 v[220:221], v[228:229], v[104:105], v[220:221]
	v_pk_fma_f32 v[222:223], v[230:231], v[104:105], v[222:223]
	v_cvt_pk_f32_fp8_sdwa v[224:225], v130 src0_sel:WORD_1
	v_cvt_pk_f32_fp8_sdwa v[226:227], v134 src0_sel:WORD_1
	v_cvt_pk_f32_fp8_sdwa v[228:229], v138 src0_sel:WORD_1
	v_cvt_pk_f32_fp8_sdwa v[230:231], v142 src0_sel:WORD_1
	v_pk_fma_f32 v[216:217], v[224:225], v[106:107], v[216:217]
	v_pk_fma_f32 v[218:219], v[226:227], v[106:107], v[218:219]
	v_pk_fma_f32 v[220:221], v[228:229], v[106:107], v[220:221]
	v_pk_fma_f32 v[222:223], v[230:231], v[106:107], v[222:223]
	v_cvt_pk_f32_fp8_e32 v[224:225], v131
	v_cvt_pk_f32_fp8_e32 v[226:227], v135
	v_cvt_pk_f32_fp8_e32 v[228:229], v139
	v_cvt_pk_f32_fp8_e32 v[230:231], v143
	v_pk_fma_f32 v[216:217], v[224:225], v[108:109], v[216:217]
	v_pk_fma_f32 v[218:219], v[226:227], v[108:109], v[218:219]
	v_pk_fma_f32 v[220:221], v[228:229], v[108:109], v[220:221]
	v_pk_fma_f32 v[222:223], v[230:231], v[108:109], v[222:223]
	v_cvt_pk_f32_fp8_sdwa v[224:225], v131 src0_sel:WORD_1
	v_cvt_pk_f32_fp8_sdwa v[226:227], v135 src0_sel:WORD_1
	v_cvt_pk_f32_fp8_sdwa v[228:229], v139 src0_sel:WORD_1
	v_cvt_pk_f32_fp8_sdwa v[230:231], v143 src0_sel:WORD_1
	v_pk_fma_f32 v[216:217], v[224:225], v[110:111], v[216:217]
	v_pk_fma_f32 v[218:219], v[226:227], v[110:111], v[218:219]
	v_pk_fma_f32 v[220:221], v[228:229], v[110:111], v[220:221]
	v_pk_fma_f32 v[222:223], v[230:231], v[110:111], v[222:223]
	v_add_f32_e32 v192, v216, v217
	v_add_f32_e32 v193, v218, v219
	v_add_f32_e32 v194, v220, v221
	v_add_f32_e32 v195, v222, v223
	s_sub_i32 s90, s90, 1
	s_cmp_eq_u32 s90, 0
	s_cbranch_scc1 .LU_sw1
.LU_t6_s1:
	s_waitcnt lgkmcnt(0)
	buffer_load_dwordx4 v[128:131], v[232:233], s[56:59], 0 idxen offen
	buffer_load_dwordx4 v[132:135], v[234:235], s[56:59], 0 idxen offen
	buffer_load_dwordx4 v[136:139], v[236:237], s[56:59], 0 idxen offen
	buffer_load_dwordx4 v[140:143], v[238:239], s[56:59], 0 idxen offen
	ds_read_b32 v232, v213 offset:80
	ds_read_b32 v234, v213 offset:84
	ds_read_b32 v236, v213 offset:88
	ds_read_b32 v238, v213 offset:92
	s_waitcnt vmcnt(13)
	v_cvt_pk_f32_fp8_e32 v[224:225], v144
	v_cvt_pk_f32_fp8_e32 v[226:227], v148
	v_cvt_pk_f32_fp8_e32 v[228:229], v152
	v_cvt_pk_f32_fp8_e32 v[230:231], v156
	v_pk_mul_f32 v[216:217], v[224:225], v[96:97]
	v_pk_mul_f32 v[218:219], v[226:227], v[96:97]
	v_pk_mul_f32 v[220:221], v[228:229], v[96:97]
	v_pk_mul_f32 v[222:223], v[230:231], v[96:97]
	v_cvt_pk_f32_fp8_sdwa v[224:225], v144 src0_sel:WORD_1
	v_cvt_pk_f32_fp8_sdwa v[226:227], v148 src0_sel:WORD_1
	v_cvt_pk_f32_fp8_sdwa v[228:229], v152 src0_sel:WORD_1
	v_cvt_pk_f32_fp8_sdwa v[230:231], v156 src0_sel:WORD_1
	v_pk_fma_f32 v[216:217], v[224:225], v[98:99], v[216:217]
	v_pk_fma_f32 v[218:219], v[226:227], v[98:99], v[218:219]
	v_pk_fma_f32 v[220:221], v[228:229], v[98:99], v[220:221]
	v_pk_fma_f32 v[222:223], v[230:231], v[98:99], v[222:223]
	v_cvt_pk_f32_fp8_e32 v[224:225], v145
	v_cvt_pk_f32_fp8_e32 v[226:227], v149
	v_cvt_pk_f32_fp8_e32 v[228:229], v153
	v_cvt_pk_f32_fp8_e32 v[230:231], v157
	v_pk_fma_f32 v[216:217], v[224:225], v[100:101], v[216:217]
	v_pk_fma_f32 v[218:219], v[226:227], v[100:101], v[218:219]
	v_pk_fma_f32 v[220:221], v[228:229], v[100:101], v[220:221]
	v_pk_fma_f32 v[222:223], v[230:231], v[100:101], v[222:223]
	v_cvt_pk_f32_fp8_sdwa v[224:225], v145 src0_sel:WORD_1
	v_cvt_pk_f32_fp8_sdwa v[226:227], v149 src0_sel:WORD_1
	v_cvt_pk_f32_fp8_sdwa v[228:229], v153 src0_sel:WORD_1
	v_cvt_pk_f32_fp8_sdwa v[230:231], v157 src0_sel:WORD_1
	v_pk_fma_f32 v[216:217], v[224:225], v[102:103], v[216:217]
	v_pk_fma_f32 v[218:219], v[226:227], v[102:103], v[218:219]
	v_pk_fma_f32 v[220:221], v[228:229], v[102:103], v[220:221]
	v_pk_fma_f32 v[222:223], v[230:231], v[102:103], v[222:223]
	v_cvt_pk_f32_fp8_e32 v[224:225], v146
	v_cvt_pk_f32_fp8_e32 v[226:227], v150
	v_cvt_pk_f32_fp8_e32 v[228:229], v154
	v_cvt_pk_f32_fp8_e32 v[230:231], v158
	v_pk_fma_f32 v[216:217], v[224:225], v[104:105], v[216:217]
	v_pk_fma_f32 v[218:219], v[226:227], v[104:105], v[218:219]
	v_pk_fma_f32 v[220:221], v[228:229], v[104:105], v[220:221]
	v_pk_fma_f32 v[222:223], v[230:231], v[104:105], v[222:223]
	v_cvt_pk_f32_fp8_sdwa v[224:225], v146 src0_sel:WORD_1
	v_cvt_pk_f32_fp8_sdwa v[226:227], v150 src0_sel:WORD_1
	v_cvt_pk_f32_fp8_sdwa v[228:229], v154 src0_sel:WORD_1
	v_cvt_pk_f32_fp8_sdwa v[230:231], v158 src0_sel:WORD_1
	v_pk_fma_f32 v[216:217], v[224:225], v[106:107], v[216:217]
	v_pk_fma_f32 v[218:219], v[226:227], v[106:107], v[218:219]
	v_pk_fma_f32 v[220:221], v[228:229], v[106:107], v[220:221]
	v_pk_fma_f32 v[222:223], v[230:231], v[106:107], v[222:223]
	v_cvt_pk_f32_fp8_e32 v[224:225], v147
	v_cvt_pk_f32_fp8_e32 v[226:227], v151
	v_cvt_pk_f32_fp8_e32 v[228:229], v155
	v_cvt_pk_f32_fp8_e32 v[230:231], v159
	v_pk_fma_f32 v[216:217], v[224:225], v[108:109], v[216:217]
	v_pk_fma_f32 v[218:219], v[226:227], v[108:109], v[218:219]
	v_pk_fma_f32 v[220:221], v[228:229], v[108:109], v[220:221]
	v_pk_fma_f32 v[222:223], v[230:231], v[108:109], v[222:223]
	v_cvt_pk_f32_fp8_sdwa v[224:225], v147 src0_sel:WORD_1
	v_cvt_pk_f32_fp8_sdwa v[226:227], v151 src0_sel:WORD_1
	v_cvt_pk_f32_fp8_sdwa v[228:229], v155 src0_sel:WORD_1
	v_cvt_pk_f32_fp8_sdwa v[230:231], v159 src0_sel:WORD_1
	v_pk_fma_f32 v[216:217], v[224:225], v[110:111], v[216:217]
	v_pk_fma_f32 v[218:219], v[226:227], v[110:111], v[218:219]
	v_pk_fma_f32 v[220:221], v[228:229], v[110:111], v[220:221]
	v_pk_fma_f32 v[222:223], v[230:231], v[110:111], v[222:223]
	v_add_f32_e32 v196, v216, v217
	v_add_f32_e32 v197, v218, v219
	v_add_f32_e32 v198, v220, v221
	v_add_f32_e32 v199, v222, v223
	s_sub_i32 s90, s90, 1
	s_cmp_eq_u32 s90, 0
	s_cbranch_scc1 .LU_sw2
.LU_t6_s2:
	s_waitcnt lgkmcnt(0)
	buffer_load_dwordx4 v[144:147], v[232:233], s[56:59], 0 idxen offen
	buffer_load_dwordx4 v[148:151], v[234:235], s[56:59], 0 idxen offen
	buffer_load_dwordx4 v[152:155], v[236:237], s[56:59], 0 idxen offen
	buffer_load_dwordx4 v[156:159], v[238:239], s[56:59], 0 idxen offen
	ds_read_b32 v232, v213 offset:96
	ds_read_b32 v234, v213 offset:100
	ds_read_b32 v236, v213 offset:104
	ds_read_b32 v238, v213 offset:108
	s_waitcnt vmcnt(13)
	v_cvt_pk_f32_fp8_e32 v[224:225], v160
	v_cvt_pk_f32_fp8_e32 v[226:227], v164
	v_cvt_pk_f32_fp8_e32 v[228:229], v168
	v_cvt_pk_f32_fp8_e32 v[230:231], v172
	v_pk_mul_f32 v[216:217], v[224:225], v[96:97]
	v_pk_mul_f32 v[218:219], v[226:227], v[96:97]
	v_pk_mul_f32 v[220:221], v[228:229], v[96:97]
	v_pk_mul_f32 v[222:223], v[230:231], v[96:97]
	v_cvt_pk_f32_fp8_sdwa v[224:225], v160 src0_sel:WORD_1
	v_cvt_pk_f32_fp8_sdwa v[226:227], v164 src0_sel:WORD_1
	v_cvt_pk_f32_fp8_sdwa v[228:229], v168 src0_sel:WORD_1
	v_cvt_pk_f32_fp8_sdwa v[230:231], v172 src0_sel:WORD_1
	v_pk_fma_f32 v[216:217], v[224:225], v[98:99], v[216:217]
	v_pk_fma_f32 v[218:219], v[226:227], v[98:99], v[218:219]
	v_pk_fma_f32 v[220:221], v[228:229], v[98:99], v[220:221]
	v_pk_fma_f32 v[222:223], v[230:231], v[98:99], v[222:223]
	v_cvt_pk_f32_fp8_e32 v[224:225], v161
	v_cvt_pk_f32_fp8_e32 v[226:227], v165
	v_cvt_pk_f32_fp8_e32 v[228:229], v169
	v_cvt_pk_f32_fp8_e32 v[230:231], v173
	v_pk_fma_f32 v[216:217], v[224:225], v[100:101], v[216:217]
	v_pk_fma_f32 v[218:219], v[226:227], v[100:101], v[218:219]
	v_pk_fma_f32 v[220:221], v[228:229], v[100:101], v[220:221]
	v_pk_fma_f32 v[222:223], v[230:231], v[100:101], v[222:223]
	v_cvt_pk_f32_fp8_sdwa v[224:225], v161 src0_sel:WORD_1
	v_cvt_pk_f32_fp8_sdwa v[226:227], v165 src0_sel:WORD_1
	v_cvt_pk_f32_fp8_sdwa v[228:229], v169 src0_sel:WORD_1
	v_cvt_pk_f32_fp8_sdwa v[230:231], v173 src0_sel:WORD_1
	v_pk_fma_f32 v[216:217], v[224:225], v[102:103], v[216:217]
	v_pk_fma_f32 v[218:219], v[226:227], v[102:103], v[218:219]
	v_pk_fma_f32 v[220:221], v[228:229], v[102:103], v[220:221]
	v_pk_fma_f32 v[222:223], v[230:231], v[102:103], v[222:223]
	v_cvt_pk_f32_fp8_e32 v[224:225], v162
	v_cvt_pk_f32_fp8_e32 v[226:227], v166
	v_cvt_pk_f32_fp8_e32 v[228:229], v170
	v_cvt_pk_f32_fp8_e32 v[230:231], v174
	v_pk_fma_f32 v[216:217], v[224:225], v[104:105], v[216:217]
	v_pk_fma_f32 v[218:219], v[226:227], v[104:105], v[218:219]
	v_pk_fma_f32 v[220:221], v[228:229], v[104:105], v[220:221]
	v_pk_fma_f32 v[222:223], v[230:231], v[104:105], v[222:223]
	v_cvt_pk_f32_fp8_sdwa v[224:225], v162 src0_sel:WORD_1
	v_cvt_pk_f32_fp8_sdwa v[226:227], v166 src0_sel:WORD_1
	v_cvt_pk_f32_fp8_sdwa v[228:229], v170 src0_sel:WORD_1
	v_cvt_pk_f32_fp8_sdwa v[230:231], v174 src0_sel:WORD_1
	v_pk_fma_f32 v[216:217], v[224:225], v[106:107], v[216:217]
	v_pk_fma_f32 v[218:219], v[226:227], v[106:107], v[218:219]
	v_pk_fma_f32 v[220:221], v[228:229], v[106:107], v[220:221]
	v_pk_fma_f32 v[222:223], v[230:231], v[106:107], v[222:223]
	v_cvt_pk_f32_fp8_e32 v[224:225], v163
	v_cvt_pk_f32_fp8_e32 v[226:227], v167
	v_cvt_pk_f32_fp8_e32 v[228:229], v171
	v_cvt_pk_f32_fp8_e32 v[230:231], v175
	v_pk_fma_f32 v[216:217], v[224:225], v[108:109], v[216:217]
	v_pk_fma_f32 v[218:219], v[226:227], v[108:109], v[218:219]
	v_pk_fma_f32 v[220:221], v[228:229], v[108:109], v[220:221]
	v_pk_fma_f32 v[222:223], v[230:231], v[108:109], v[222:223]
	v_cvt_pk_f32_fp8_sdwa v[224:225], v163 src0_sel:WORD_1
	v_cvt_pk_f32_fp8_sdwa v[226:227], v167 src0_sel:WORD_1
	v_cvt_pk_f32_fp8_sdwa v[228:229], v171 src0_sel:WORD_1
	v_cvt_pk_f32_fp8_sdwa v[230:231], v175 src0_sel:WORD_1
	v_pk_fma_f32 v[216:217], v[224:225], v[110:111], v[216:217]
	v_pk_fma_f32 v[218:219], v[226:227], v[110:111], v[218:219]
	v_pk_fma_f32 v[220:221], v[228:229], v[110:111], v[220:221]
	v_pk_fma_f32 v[222:223], v[230:231], v[110:111], v[222:223]
	v_add_f32_e32 v200, v216, v217
	v_add_f32_e32 v201, v218, v219
	v_add_f32_e32 v202, v220, v221
	v_add_f32_e32 v203, v222, v223
	s_sub_i32 s90, s90, 1
	s_cmp_eq_u32 s90, 0
	s_cbranch_scc1 .LU_sw3

.LU_t7_s0:
	s_cmp_ge_u32 s21, s20
	s_cbranch_scc1 .LU_done
	s_waitcnt lgkmcnt(0)
	v_lshlrev_b32_e32 v208, 3, v248
	buffer_load_dwordx2 v[252:253], v208, s[24:27], 0 offen
	buffer_load_dwordx4 v[176:179], v[232:233], s[56:59], 0 idxen offen
	buffer_load_dwordx4 v[180:183], v[234:235], s[56:59], 0 idxen offen
	buffer_load_dwordx4 v[184:187], v[236:237], s[56:59], 0 idxen offen
	buffer_load_dwordx4 v[188:191], v[238:239], s[56:59], 0 idxen offen
	ds_read_b32 v232, v213 offset:64
	ds_read_b32 v234, v213 offset:68
	ds_read_b32 v236, v213 offset:72
	ds_read_b32 v238, v213 offset:76
	s_waitcnt vmcnt(13)
	v_cvt_pk_f32_fp8_e32 v[224:225], v128
	v_cvt_pk_f32_fp8_e32 v[226:227], v132
	v_cvt_pk_f32_fp8_e32 v[228:229], v136
	v_cvt_pk_f32_fp8_e32 v[230:231], v140
	v_pk_mul_f32 v[216:217], v[224:225], v[112:113]
	v_pk_mul_f32 v[218:219], v[226:227], v[112:113]
	v_pk_mul_f32 v[220:221], v[228:229], v[112:113]
	v_pk_mul_f32 v[222:223], v[230:231], v[112:113]
	v_cvt_pk_f32_fp8_sdwa v[224:225], v128 src0_sel:WORD_1
	v_cvt_pk_f32_fp8_sdwa v[226:227], v132 src0_sel:WORD_1
	v_cvt_pk_f32_fp8_sdwa v[228:229], v136 src0_sel:WORD_1
	v_cvt_pk_f32_fp8_sdwa v[230:231], v140 src0_sel:WORD_1
	v_pk_fma_f32 v[216:217], v[224:225], v[114:115], v[216:217]
	v_pk_fma_f32 v[218:219], v[226:227], v[114:115], v[218:219]
	v_pk_fma_f32 v[220:221], v[228:229], v[114:115], v[220:221]
	v_pk_fma_f32 v[222:223], v[230:231], v[114:115], v[222:223]
	v_cvt_pk_f32_fp8_e32 v[224:225], v129
	v_cvt_pk_f32_fp8_e32 v[226:227], v133
	v_cvt_pk_f32_fp8_e32 v[228:229], v137
	v_cvt_pk_f32_fp8_e32 v[230:231], v141
	v_pk_fma_f32 v[216:217], v[224:225], v[116:117], v[216:217]
	v_pk_fma_f32 v[218:219], v[226:227], v[116:117], v[218:219]
	v_pk_fma_f32 v[220:221], v[228:229], v[116:117], v[220:221]
	v_pk_fma_f32 v[222:223], v[230:231], v[116:117], v[222:223]
	v_cvt_pk_f32_fp8_sdwa v[224:225], v129 src0_sel:WORD_1
	v_cvt_pk_f32_fp8_sdwa v[226:227], v133 src0_sel:WORD_1
	v_cvt_pk_f32_fp8_sdwa v[228:229], v137 src0_sel:WORD_1
	v_cvt_pk_f32_fp8_sdwa v[230:231], v141 src0_sel:WORD_1
	v_pk_fma_f32 v[216:217], v[224:225], v[118:119], v[216:217]
	v_pk_fma_f32 v[218:219], v[226:227], v[118:119], v[218:219]
	v_pk_fma_f32 v[220:221], v[228:229], v[118:119], v[220:221]
	v_pk_fma_f32 v[222:223], v[230:231], v[118:119], v[222:223]
	v_cvt_pk_f32_fp8_e32 v[224:225], v130
	v_cvt_pk_f32_fp8_e32 v[226:227], v134
	v_cvt_pk_f32_fp8_e32 v[228:229], v138
	v_cvt_pk_f32_fp8_e32 v[230:231], v142
	v_pk_fma_f32 v[216:217], v[224:225], v[120:121], v[216:217]
	v_pk_fma_f32 v[218:219], v[226:227], v[120:121], v[218:219]
	v_pk_fma_f32 v[220:221], v[228:229], v[120:121], v[220:221]
	v_pk_fma_f32 v[222:223], v[230:231], v[120:121], v[222:223]
	v_cvt_pk_f32_fp8_sdwa v[224:225], v130 src0_sel:WORD_1
	v_cvt_pk_f32_fp8_sdwa v[226:227], v134 src0_sel:WORD_1
	v_cvt_pk_f32_fp8_sdwa v[228:229], v138 src0_sel:WORD_1
	v_cvt_pk_f32_fp8_sdwa v[230:231], v142 src0_sel:WORD_1
	v_pk_fma_f32 v[216:217], v[224:225], v[122:123], v[216:217]
	v_pk_fma_f32 v[218:219], v[226:227], v[122:123], v[218:219]
	v_pk_fma_f32 v[220:221], v[228:229], v[122:123], v[220:221]
	v_pk_fma_f32 v[222:223], v[230:231], v[122:123], v[222:223]
	v_cvt_pk_f32_fp8_e32 v[224:225], v131
	v_cvt_pk_f32_fp8_e32 v[226:227], v135
	v_cvt_pk_f32_fp8_e32 v[228:229], v139
	v_cvt_pk_f32_fp8_e32 v[230:231], v143
	v_pk_fma_f32 v[216:217], v[224:225], v[124:125], v[216:217]
	v_pk_fma_f32 v[218:219], v[226:227], v[124:125], v[218:219]
	v_pk_fma_f32 v[220:221], v[228:229], v[124:125], v[220:221]
	v_pk_fma_f32 v[222:223], v[230:231], v[124:125], v[222:223]
	v_cvt_pk_f32_fp8_sdwa v[224:225], v131 src0_sel:WORD_1
	v_cvt_pk_f32_fp8_sdwa v[226:227], v135 src0_sel:WORD_1
	v_cvt_pk_f32_fp8_sdwa v[228:229], v139 src0_sel:WORD_1
	v_cvt_pk_f32_fp8_sdwa v[230:231], v143 src0_sel:WORD_1
	v_pk_fma_f32 v[216:217], v[224:225], v[126:127], v[216:217]
	v_pk_fma_f32 v[218:219], v[226:227], v[126:127], v[218:219]
	v_pk_fma_f32 v[220:221], v[228:229], v[126:127], v[220:221]
	v_pk_fma_f32 v[222:223], v[230:231], v[126:127], v[222:223]
	v_add_f32_e32 v192, v216, v217
	v_add_f32_e32 v193, v218, v219
	v_add_f32_e32 v194, v220, v221
	v_add_f32_e32 v195, v222, v223
	s_sub_i32 s90, s90, 1
	s_cmp_eq_u32 s90, 0
	s_cbranch_scc1 .LU_sw1
.LU_t7_s1:
	s_waitcnt lgkmcnt(0)
	buffer_load_dwordx4 v[128:131], v[232:233], s[56:59], 0 idxen offen
	buffer_load_dwordx4 v[132:135], v[234:235], s[56:59], 0 idxen offen
	buffer_load_dwordx4 v[136:139], v[236:237], s[56:59], 0 idxen offen
	buffer_load_dwordx4 v[140:143], v[238:239], s[56:59], 0 idxen offen
	ds_read_b32 v232, v213 offset:80
	ds_read_b32 v234, v213 offset:84
	ds_read_b32 v236, v213 offset:88
	ds_read_b32 v238, v213 offset:92
	s_waitcnt vmcnt(13)
	v_cvt_pk_f32_fp8_e32 v[224:225], v144
	v_cvt_pk_f32_fp8_e32 v[226:227], v148
	v_cvt_pk_f32_fp8_e32 v[228:229], v152
	v_cvt_pk_f32_fp8_e32 v[230:231], v156
	v_pk_mul_f32 v[216:217], v[224:225], v[112:113]
	v_pk_mul_f32 v[218:219], v[226:227], v[112:113]
	v_pk_mul_f32 v[220:221], v[228:229], v[112:113]
	v_pk_mul_f32 v[222:223], v[230:231], v[112:113]
	v_cvt_pk_f32_fp8_sdwa v[224:225], v144 src0_sel:WORD_1
	v_cvt_pk_f32_fp8_sdwa v[226:227], v148 src0_sel:WORD_1
	v_cvt_pk_f32_fp8_sdwa v[228:229], v152 src0_sel:WORD_1
	v_cvt_pk_f32_fp8_sdwa v[230:231], v156 src0_sel:WORD_1
	v_pk_fma_f32 v[216:217], v[224:225], v[114:115], v[216:217]
	v_pk_fma_f32 v[218:219], v[226:227], v[114:115], v[218:219]
	v_pk_fma_f32 v[220:221], v[228:229], v[114:115], v[220:221]
	v_pk_fma_f32 v[222:223], v[230:231], v[114:115], v[222:223]
	v_cvt_pk_f32_fp8_e32 v[224:225], v145
	v_cvt_pk_f32_fp8_e32 v[226:227], v149
	v_cvt_pk_f32_fp8_e32 v[228:229], v153
	v_cvt_pk_f32_fp8_e32 v[230:231], v157
	v_pk_fma_f32 v[216:217], v[224:225], v[116:117], v[216:217]
	v_pk_fma_f32 v[218:219], v[226:227], v[116:117], v[218:219]
	v_pk_fma_f32 v[220:221], v[228:229], v[116:117], v[220:221]
	v_pk_fma_f32 v[222:223], v[230:231], v[116:117], v[222:223]
	v_cvt_pk_f32_fp8_sdwa v[224:225], v145 src0_sel:WORD_1
	v_cvt_pk_f32_fp8_sdwa v[226:227], v149 src0_sel:WORD_1
	v_cvt_pk_f32_fp8_sdwa v[228:229], v153 src0_sel:WORD_1
	v_cvt_pk_f32_fp8_sdwa v[230:231], v157 src0_sel:WORD_1
	v_pk_fma_f32 v[216:217], v[224:225], v[118:119], v[216:217]
	v_pk_fma_f32 v[218:219], v[226:227], v[118:119], v[218:219]
	v_pk_fma_f32 v[220:221], v[228:229], v[118:119], v[220:221]
	v_pk_fma_f32 v[222:223], v[230:231], v[118:119], v[222:223]
	v_cvt_pk_f32_fp8_e32 v[224:225], v146
	v_cvt_pk_f32_fp8_e32 v[226:227], v150
	v_cvt_pk_f32_fp8_e32 v[228:229], v154
	v_cvt_pk_f32_fp8_e32 v[230:231], v158
	v_pk_fma_f32 v[216:217], v[224:225], v[120:121], v[216:217]
	v_pk_fma_f32 v[218:219], v[226:227], v[120:121], v[218:219]
	v_pk_fma_f32 v[220:221], v[228:229], v[120:121], v[220:221]
	v_pk_fma_f32 v[222:223], v[230:231], v[120:121], v[222:223]
	v_cvt_pk_f32_fp8_sdwa v[224:225], v146 src0_sel:WORD_1
	v_cvt_pk_f32_fp8_sdwa v[226:227], v150 src0_sel:WORD_1
	v_cvt_pk_f32_fp8_sdwa v[228:229], v154 src0_sel:WORD_1
	v_cvt_pk_f32_fp8_sdwa v[230:231], v158 src0_sel:WORD_1
	v_pk_fma_f32 v[216:217], v[224:225], v[122:123], v[216:217]
	v_pk_fma_f32 v[218:219], v[226:227], v[122:123], v[218:219]
	v_pk_fma_f32 v[220:221], v[228:229], v[122:123], v[220:221]
	v_pk_fma_f32 v[222:223], v[230:231], v[122:123], v[222:223]
	v_cvt_pk_f32_fp8_e32 v[224:225], v147
	v_cvt_pk_f32_fp8_e32 v[226:227], v151
	v_cvt_pk_f32_fp8_e32 v[228:229], v155
	v_cvt_pk_f32_fp8_e32 v[230:231], v159
	v_pk_fma_f32 v[216:217], v[224:225], v[124:125], v[216:217]
	v_pk_fma_f32 v[218:219], v[226:227], v[124:125], v[218:219]
	v_pk_fma_f32 v[220:221], v[228:229], v[124:125], v[220:221]
	v_pk_fma_f32 v[222:223], v[230:231], v[124:125], v[222:223]
	v_cvt_pk_f32_fp8_sdwa v[224:225], v147 src0_sel:WORD_1
	v_cvt_pk_f32_fp8_sdwa v[226:227], v151 src0_sel:WORD_1
	v_cvt_pk_f32_fp8_sdwa v[228:229], v155 src0_sel:WORD_1
	v_cvt_pk_f32_fp8_sdwa v[230:231], v159 src0_sel:WORD_1
	v_pk_fma_f32 v[216:217], v[224:225], v[126:127], v[216:217]
	v_pk_fma_f32 v[218:219], v[226:227], v[126:127], v[218:219]
	v_pk_fma_f32 v[220:221], v[228:229], v[126:127], v[220:221]
	v_pk_fma_f32 v[222:223], v[230:231], v[126:127], v[222:223]
	v_add_f32_e32 v196, v216, v217
	v_add_f32_e32 v197, v218, v219
	v_add_f32_e32 v198, v220, v221
	v_add_f32_e32 v199, v222, v223
	s_sub_i32 s90, s90, 1
	s_cmp_eq_u32 s90, 0
	s_cbranch_scc1 .LU_sw2
.LU_t7_s2:
	s_waitcnt lgkmcnt(0)
	buffer_load_dwordx4 v[144:147], v[232:233], s[56:59], 0 idxen offen
	buffer_load_dwordx4 v[148:151], v[234:235], s[56:59], 0 idxen offen
	buffer_load_dwordx4 v[152:155], v[236:237], s[56:59], 0 idxen offen
	buffer_load_dwordx4 v[156:159], v[238:239], s[56:59], 0 idxen offen
	ds_read_b32 v232, v213 offset:96
	ds_read_b32 v234, v213 offset:100
	ds_read_b32 v236, v213 offset:104
	ds_read_b32 v238, v213 offset:108
	s_waitcnt vmcnt(13)
	v_cvt_pk_f32_fp8_e32 v[224:225], v160
	v_cvt_pk_f32_fp8_e32 v[226:227], v164
	v_cvt_pk_f32_fp8_e32 v[228:229], v168
	v_cvt_pk_f32_fp8_e32 v[230:231], v172
	v_pk_mul_f32 v[216:217], v[224:225], v[112:113]
	v_pk_mul_f32 v[218:219], v[226:227], v[112:113]
	v_pk_mul_f32 v[220:221], v[228:229], v[112:113]
	v_pk_mul_f32 v[222:223], v[230:231], v[112:113]
	v_cvt_pk_f32_fp8_sdwa v[224:225], v160 src0_sel:WORD_1
	v_cvt_pk_f32_fp8_sdwa v[226:227], v164 src0_sel:WORD_1
	v_cvt_pk_f32_fp8_sdwa v[228:229], v168 src0_sel:WORD_1
	v_cvt_pk_f32_fp8_sdwa v[230:231], v172 src0_sel:WORD_1
	v_pk_fma_f32 v[216:217], v[224:225], v[114:115], v[216:217]
	v_pk_fma_f32 v[218:219], v[226:227], v[114:115], v[218:219]
	v_pk_fma_f32 v[220:221], v[228:229], v[114:115], v[220:221]
	v_pk_fma_f32 v[222:223], v[230:231], v[114:115], v[222:223]
	v_cvt_pk_f32_fp8_e32 v[224:225], v161
	v_cvt_pk_f32_fp8_e32 v[226:227], v165
	v_cvt_pk_f32_fp8_e32 v[228:229], v169
	v_cvt_pk_f32_fp8_e32 v[230:231], v173
	v_pk_fma_f32 v[216:217], v[224:225], v[116:117], v[216:217]
	v_pk_fma_f32 v[218:219], v[226:227], v[116:117], v[218:219]
	v_pk_fma_f32 v[220:221], v[228:229], v[116:117], v[220:221]
	v_pk_fma_f32 v[222:223], v[230:231], v[116:117], v[222:223]
	v_cvt_pk_f32_fp8_sdwa v[224:225], v161 src0_sel:WORD_1
	v_cvt_pk_f32_fp8_sdwa v[226:227], v165 src0_sel:WORD_1
	v_cvt_pk_f32_fp8_sdwa v[228:229], v169 src0_sel:WORD_1
	v_cvt_pk_f32_fp8_sdwa v[230:231], v173 src0_sel:WORD_1
	v_pk_fma_f32 v[216:217], v[224:225], v[118:119], v[216:217]
	v_pk_fma_f32 v[218:219], v[226:227], v[118:119], v[218:219]
	v_pk_fma_f32 v[220:221], v[228:229], v[118:119], v[220:221]
	v_pk_fma_f32 v[222:223], v[230:231], v[118:119], v[222:223]
	v_cvt_pk_f32_fp8_e32 v[224:225], v162
	v_cvt_pk_f32_fp8_e32 v[226:227], v166
	v_cvt_pk_f32_fp8_e32 v[228:229], v170
	v_cvt_pk_f32_fp8_e32 v[230:231], v174
	v_pk_fma_f32 v[216:217], v[224:225], v[120:121], v[216:217]
	v_pk_fma_f32 v[218:219], v[226:227], v[120:121], v[218:219]
	v_pk_fma_f32 v[220:221], v[228:229], v[120:121], v[220:221]
	v_pk_fma_f32 v[222:223], v[230:231], v[120:121], v[222:223]
	v_cvt_pk_f32_fp8_sdwa v[224:225], v162 src0_sel:WORD_1
	v_cvt_pk_f32_fp8_sdwa v[226:227], v166 src0_sel:WORD_1
	v_cvt_pk_f32_fp8_sdwa v[228:229], v170 src0_sel:WORD_1
	v_cvt_pk_f32_fp8_sdwa v[230:231], v174 src0_sel:WORD_1
	v_pk_fma_f32 v[216:217], v[224:225], v[122:123], v[216:217]
	v_pk_fma_f32 v[218:219], v[226:227], v[122:123], v[218:219]
	v_pk_fma_f32 v[220:221], v[228:229], v[122:123], v[220:221]
	v_pk_fma_f32 v[222:223], v[230:231], v[122:123], v[222:223]
	v_cvt_pk_f32_fp8_e32 v[224:225], v163
	v_cvt_pk_f32_fp8_e32 v[226:227], v167
	v_cvt_pk_f32_fp8_e32 v[228:229], v171
	v_cvt_pk_f32_fp8_e32 v[230:231], v175
	v_pk_fma_f32 v[216:217], v[224:225], v[124:125], v[216:217]
	v_pk_fma_f32 v[218:219], v[226:227], v[124:125], v[218:219]
	v_pk_fma_f32 v[220:221], v[228:229], v[124:125], v[220:221]
	v_pk_fma_f32 v[222:223], v[230:231], v[124:125], v[222:223]
	v_cvt_pk_f32_fp8_sdwa v[224:225], v163 src0_sel:WORD_1
	v_cvt_pk_f32_fp8_sdwa v[226:227], v167 src0_sel:WORD_1
	v_cvt_pk_f32_fp8_sdwa v[228:229], v171 src0_sel:WORD_1
	v_cvt_pk_f32_fp8_sdwa v[230:231], v175 src0_sel:WORD_1
	v_pk_fma_f32 v[216:217], v[224:225], v[126:127], v[216:217]
	v_pk_fma_f32 v[218:219], v[226:227], v[126:127], v[218:219]
	v_pk_fma_f32 v[220:221], v[228:229], v[126:127], v[220:221]
	v_pk_fma_f32 v[222:223], v[230:231], v[126:127], v[222:223]
	v_add_f32_e32 v200, v216, v217
	v_add_f32_e32 v201, v218, v219
	v_add_f32_e32 v202, v220, v221
	v_add_f32_e32 v203, v222, v223
	s_sub_i32 s90, s90, 1
	s_cmp_eq_u32 s90, 0
	s_cbranch_scc1 .LU_sw3
